# packed f32 VALU ops (v_pk_fma/mul/add_f32) unpacked into scalar pairs kernel-wide; LN reductions and up-proj row shuffles moved from ds_bpermute to DPP
# speedup vs baseline: 1.0873x; 1.0034x over previous
.LBB0_19:
	s_or_b64 exec, exec, s[16:17]
	s_waitcnt lgkmcnt(0)
	v_add_f32_e32 v74, v76, v78
	v_add_f32_e32 v75, v77, v79
	s_mov_b32 s0, 0x3a800000
	v_mul_f32_e32 v74, s0, v74
	v_mul_f32_e32 v75, s0, v75
	s_and_b64 s[0:1], exec, vcc
	v_fma_f32 v74, -v75, v75, v74
	v_max_f32_e32 v74, 0, v74
	v_add_f32_e32 v74, 0x358637bd, v74
	v_mul_f32_e32 v76, 0x4b800000, v74
	v_cmp_gt_f32_e64 s[40:41], s58, v74
	v_sub_f32_e32 v17, v17, v75
	v_sub_f32_e32 v16, v16, v75
	v_cndmask_b32_e64 v74, v74, v76, s[40:41]
	v_rsq_f32_e32 v74, v74
	v_sub_f32_e32 v15, v15, v75
	v_sub_f32_e32 v14, v14, v75
	v_sub_f32_e32 v13, v13, v75
	v_mul_f32_e32 v76, 0x45800000, v74
	v_cndmask_b32_e64 v74, v74, v76, s[40:41]
	v_sub_f32_e32 v12, v12, v75
	v_sub_f32_e32 v11, v11, v75
	v_sub_f32_e32 v10, v10, v75
	v_mul_f32_e32 v14, v14, v74
	v_mul_f32_e32 v15, v15, v74
	v_mul_f32_e32 v16, v16, v74
	v_mul_f32_e32 v17, v17, v74
	v_mul_f32_e32 v10, v10, v74
	v_mul_f32_e32 v11, v11, v74
	v_mul_f32_e32 v12, v12, v74
	v_mul_f32_e32 v13, v13, v74
	v_sub_f32_e32 v9, v9, v75
	v_sub_f32_e32 v8, v8, v75
	v_sub_f32_e32 v7, v7, v75
	v_sub_f32_e32 v6, v6, v75
	v_sub_f32_e32 v5, v5, v75
	v_sub_f32_e32 v4, v4, v75
	v_sub_f32_e32 v3, v3, v75
	v_sub_f32_e32 v2, v2, v75
	s_waitcnt vmcnt(2)
	v_fma_f32 v16, v16, v32, v24
	v_fma_f32 v17, v17, v33, v25
	v_fma_f32 v14, v14, v30, v22
	v_fma_f32 v15, v15, v31, v23
	v_fma_f32 v12, v12, v36, v20
	v_fma_f32 v13, v13, v37, v21
	v_fma_f32 v10, v10, v34, v18
	v_fma_f32 v11, v11, v35, v19
	v_mul_f32_e32 v6, v6, v74
	v_mul_f32_e32 v7, v7, v74
	v_mul_f32_e32 v8, v8, v74
	v_mul_f32_e32 v9, v9, v74
	v_mul_f32_e32 v2, v2, v74
	v_mul_f32_e32 v3, v3, v74
	v_mul_f32_e32 v4, v4, v74
	v_mul_f32_e32 v5, v5, v74
	s_waitcnt vmcnt(0)
	v_fma_f32 v8, v8, v44, v40
	v_fma_f32 v9, v9, v45, v41
	v_fma_f32 v6, v6, v42, v38
	v_fma_f32 v7, v7, v43, v39
	v_fma_f32 v74, v4, v48, v28
	v_fma_f32 v75, v5, v49, v29
	v_fma_f32 v76, v2, v46, v26
	v_fma_f32 v77, v3, v47, v27
	v_cvt_pk_bf16_f32 v2, v14, v15
	v_cvt_pk_bf16_f32 v3, v16, v17
	v_cvt_pk_bf16_f32 v4, v10, v11
	v_cvt_pk_bf16_f32 v5, v12, v13
	global_store_dwordx4 v[70:71], v[2:5], off
	s_or_b64 s[14:15], s[0:1], s[14:15]
	s_mov_b64 s[0:1], 0x800
	v_cvt_pk_bf16_f32 v2, v6, v7
	v_cvt_pk_bf16_f32 v3, v8, v9
	v_cvt_pk_bf16_f32 v4, v76, v77
	v_cvt_pk_bf16_f32 v5, v74, v75
	global_store_dwordx4 v[70:71], v[2:5], off offset:1024
	v_mov_b64_e32 v[6:7], v[62:63]
	v_mov_b64_e32 v[10:11], v[50:51]
	v_mov_b64_e32 v[2:3], v[58:59]
	v_mov_b64_e32 v[14:15], v[54:55]
	v_lshl_add_u64 v[70:71], v[70:71], 0, s[0:1]
	v_mov_b64_e32 v[74:75], v[72:73]
	v_mov_b64_e32 v[4:5], v[60:61]
	v_mov_b64_e32 v[8:9], v[64:65]
	v_mov_b64_e32 v[12:13], v[52:53]
	v_mov_b64_e32 v[16:17], v[56:57]
	s_andn2_b64 exec, exec, s[14:15]
	s_cbranch_execz .LBB0_24

.LBB0_22:
	s_or_b64 exec, exec, s[16:17]
	v_mul_f32_e32 v78, v15, v15
	v_fmac_f32_e32 v78, v14, v14
	v_mov_b32_e32 v76, v10
	v_mov_b32_e32 v77, v17
	v_add_f32_e32 v75, 0, v14
	v_fmac_f32_e32 v78, v16, v16
	v_mul_f32_e32 v76, v76, v76
	v_mul_f32_e32 v77, v77, v77
	v_add_f32_e32 v75, v15, v75
	v_add_f32_e32 v77, v77, v78
	v_add_f32_e32 v75, v16, v75
	v_add_f32_e32 v88, v76, v77
	v_mul_f32_e32 v76, v12, v12
	v_mul_f32_e32 v77, v13, v13
	v_mul_f32_e32 v78, v10, v10
	v_mul_f32_e32 v79, v11, v11
	v_add_f32_e32 v75, v17, v75
	v_add_f32_e32 v77, v79, v88
	v_add_f32_e32 v75, v10, v75
	v_add_f32_e32 v78, v76, v77
	v_mov_b32_e32 v76, v6
	v_mov_b32_e32 v77, v13
	v_add_f32_e32 v75, v11, v75
	v_mul_f32_e32 v76, v76, v76
	v_mul_f32_e32 v77, v77, v77
	v_add_f32_e32 v75, v12, v75
	v_add_f32_e32 v77, v77, v78
	v_add_f32_e32 v75, v13, v75
	v_add_f32_e32 v88, v76, v77
	v_mul_f32_e32 v76, v8, v8
	v_mul_f32_e32 v77, v9, v9
	v_mul_f32_e32 v78, v6, v6
	v_mul_f32_e32 v79, v7, v7
	v_add_f32_e32 v75, v6, v75
	v_add_f32_e32 v77, v79, v88
	v_add_f32_e32 v75, v7, v75
	v_add_f32_e32 v78, v76, v77
	v_mov_b32_e32 v76, v2
	v_mov_b32_e32 v77, v9
	v_add_f32_e32 v75, v8, v75
	v_mul_f32_e32 v76, v76, v76
	v_mul_f32_e32 v77, v77, v77
	v_add_f32_e32 v75, v9, v75
	v_add_f32_e32 v77, v77, v78
	v_add_f32_e32 v75, v2, v75
	v_add_f32_e32 v88, v76, v77
	v_mul_f32_e32 v78, v2, v2
	v_mul_f32_e32 v79, v3, v3
	v_add_f32_e32 v75, v3, v75
	v_mul_f32_e32 v76, v4, v4
	v_mul_f32_e32 v77, v5, v5
	v_add_f32_e32 v78, v79, v88
	v_add_f32_e32 v77, v4, v75
	v_add_f32_e32 v78, v76, v78
	v_mul_f32_e32 v76, v5, v5
	v_mov_b32_e32 v79, v5
	v_add_f32_e32 v76, v78, v76
	v_add_f32_e32 v77, v79, v77
	s_nop 1
	v_add_f32_dpp v76, v76, v76 quad_perm:[1,0,3,2] row_mask:0xf bank_mask:0xf
	v_add_f32_dpp v77, v77, v77 quad_perm:[1,0,3,2] row_mask:0xf bank_mask:0xf
	s_nop 0
	v_add_f32_dpp v76, v76, v76 quad_perm:[2,3,0,1] row_mask:0xf bank_mask:0xf
	v_add_f32_dpp v77, v77, v77 quad_perm:[2,3,0,1] row_mask:0xf bank_mask:0xf
	s_nop 0
	v_add_f32_dpp v76, v76, v76 row_half_mirror row_mask:0xf bank_mask:0xf
	v_add_f32_dpp v77, v77, v77 row_half_mirror row_mask:0xf bank_mask:0xf
	s_nop 0
	v_add_f32_dpp v76, v76, v76 row_mirror row_mask:0xf bank_mask:0xf
	v_add_f32_dpp v77, v77, v77 row_mirror row_mask:0xf bank_mask:0xf
	s_nop 0
	v_add_f32_dpp v76, v76, v76 row_bcast:15 row_mask:0xa bank_mask:0xf
	v_add_f32_dpp v77, v77, v77 row_bcast:15 row_mask:0xa bank_mask:0xf
	s_nop 0
	v_add_f32_dpp v76, v76, v76 row_bcast:31 row_mask:0xc bank_mask:0xf
	v_add_f32_dpp v77, v77, v77 row_bcast:31 row_mask:0xc bank_mask:0xf
	s_nop 0
	v_readlane_b32 s98, v76, 63
	v_readlane_b32 s99, v77, 63
	s_nop 1
	v_mov_b32_e32 v76, s98
	v_mov_b32_e32 v77, s99
	v_mov_b32_e32 v78, 0
	v_mov_b32_e32 v79, 0
	v_add_u32_e32 v75, 0xfffff000, v74
	v_lshrrev_b32_e32 v75, 11, v75
	v_add_u32_e32 v75, 1, v75
	v_cmp_lt_i32_e64 s[40:41], s29, v74
	v_cndmask_b32_e64 v74, 0, v75, s[40:41]
	v_cmp_ne_u32_e64 s[40:41], v74, v87
	s_and_saveexec_b64 s[16:17], s[40:41]
	s_cbranch_execz .LBB0_19
	v_mul_u32_u24_e32 v18, 0x1800, v74
	v_mov_b32_e32 v19, v1
	v_lshlrev_b64 v[18:19], 2, v[18:19]
	v_lshl_add_u64 v[20:21], v[66:67], 0, v[18:19]
	v_lshl_add_u64 v[38:39], v[68:69], 0, v[18:19]
	global_load_dwordx4 v[30:33], v[20:21], off
	global_load_dwordx4 v[34:37], v[20:21], off offset:16
	global_load_dwordx4 v[46:49], v[20:21], off offset:2064
	global_load_dwordx4 v[42:45], v[20:21], off offset:2048
	s_nop 0
	global_load_dwordx4 v[18:21], v[38:39], off offset:16
	global_load_dwordx4 v[22:25], v[38:39], off
	global_load_dwordx4 v[26:29], v[38:39], off offset:2064
	s_nop 0
	global_load_dwordx4 v[38:41], v[38:39], off offset:2048
	v_mov_b32_e32 v87, v74
	s_waitcnt vmcnt(7)
	v_add_f32_e32 v32, 1.0, v32
	v_add_f32_e32 v33, 1.0, v33
	v_add_f32_e32 v30, 1.0, v30
	v_add_f32_e32 v31, 1.0, v31
	s_waitcnt vmcnt(6)
	v_add_f32_e32 v36, 1.0, v36
	v_add_f32_e32 v37, 1.0, v37
	v_add_f32_e32 v34, 1.0, v34
	v_add_f32_e32 v35, 1.0, v35
	s_waitcnt vmcnt(4)
	v_add_f32_e32 v44, 1.0, v44
	v_add_f32_e32 v45, 1.0, v45
	v_add_f32_e32 v42, 1.0, v42
	v_add_f32_e32 v43, 1.0, v43
	v_add_f32_e32 v48, 1.0, v48
	v_add_f32_e32 v49, 1.0, v49
	v_add_f32_e32 v46, 1.0, v46
	v_add_f32_e32 v47, 1.0, v47
	s_branch .LBB0_19

.LBB0_50:
	s_add_u32 s40, s6, 0x60000
	s_addc_u32 s41, s7, 0
	v_lshl_add_u64 v[94:95], v[12:13], 0, s[40:41]
	v_add_u32_e32 v40, 0x1000, v35
	v_add_u32_e32 v42, 0x2000, v35
	v_add_u32_e32 v44, 0x3000, v35
	v_add_u32_e32 v46, 0x4000, v35
	v_add_u32_e32 v48, 0x5000, v35
	v_add_u32_e32 v50, 0x6000, v35
	v_add_u32_e32 v52, 0x7000, v35
	v_add_u32_e32 v54, 0x8000, v35
	ds_read2_b32 v[38:39], v35 offset1:1
	ds_read2_b32 v[40:41], v40 offset1:1
	ds_read2_b32 v[42:43], v42 offset1:1
	ds_read2_b32 v[44:45], v44 offset1:1
	ds_read2_b32 v[46:47], v46 offset1:1
	ds_read2_b32 v[48:49], v48 offset1:1
	ds_read2_b32 v[50:51], v50 offset1:1
	ds_read2_b32 v[52:53], v52 offset1:1
	ds_read2_b32 v[54:55], v54 offset1:1
	s_waitcnt vmcnt(15) lgkmcnt(8)
	v_fma_f32 v32, v60, v38, v32
	v_fma_f32 v33, v61, v38, v33
	s_waitcnt lgkmcnt(7)
	v_fma_f32 v30, v60, v40, v30
	v_fma_f32 v31, v61, v40, v31
	s_waitcnt lgkmcnt(6)
	v_fma_f32 v28, v60, v42, v28
	v_fma_f32 v29, v61, v42, v29
	s_waitcnt lgkmcnt(5)
	v_fma_f32 v26, v60, v44, v26
	v_fma_f32 v27, v61, v44, v27
	s_waitcnt lgkmcnt(4)
	v_fma_f32 v24, v60, v46, v24
	v_fma_f32 v25, v61, v46, v25
	s_waitcnt lgkmcnt(3)
	v_fma_f32 v22, v60, v48, v22
	v_fma_f32 v23, v61, v48, v23
	s_waitcnt lgkmcnt(2)
	v_fma_f32 v20, v60, v50, v20
	v_fma_f32 v21, v61, v50, v21
	s_waitcnt lgkmcnt(1)
	v_fma_f32 v18, v60, v52, v18
	v_fma_f32 v19, v61, v52, v19
	s_waitcnt lgkmcnt(0)
	v_fma_f32 v16, v60, v54, v16
	v_fma_f32 v17, v61, v54, v17
	global_load_dwordx2 v[60:61], v[94:95], off
	s_waitcnt vmcnt(15)
	v_fma_f32 v32, v62, v39, v32
	v_fma_f32 v33, v63, v39, v33
	v_fma_f32 v30, v62, v41, v30
	v_fma_f32 v31, v63, v41, v31
	v_fma_f32 v28, v62, v43, v28
	v_fma_f32 v29, v63, v43, v29
	v_fma_f32 v26, v62, v45, v26
	v_fma_f32 v27, v63, v45, v27
	v_fma_f32 v24, v62, v47, v24
	v_fma_f32 v25, v63, v47, v25
	v_fma_f32 v22, v62, v49, v22
	v_fma_f32 v23, v63, v49, v23
	v_fma_f32 v20, v62, v51, v20
	v_fma_f32 v21, v63, v51, v21
	v_fma_f32 v18, v62, v53, v18
	v_fma_f32 v19, v63, v53, v19
	v_fma_f32 v16, v62, v55, v16
	v_fma_f32 v17, v63, v55, v17
	s_mov_b32 s0, 0x6000
	v_lshl_add_u64 v[92:93], v[94:95], 0, s[0:1]
	global_load_dwordx2 v[62:63], v[92:93], off
	v_add_u32_e32 v40, 0x1008, v35
	v_add_u32_e32 v42, 0x2008, v35
	v_add_u32_e32 v44, 0x3008, v35
	v_add_u32_e32 v46, 0x4008, v35
	v_add_u32_e32 v48, 0x5008, v35
	v_add_u32_e32 v50, 0x6008, v35
	v_add_u32_e32 v52, 0x7008, v35
	v_add_u32_e32 v54, 0x8008, v35
	ds_read2_b32 v[38:39], v35 offset0:2 offset1:3
	ds_read2_b32 v[40:41], v40 offset1:1
	ds_read2_b32 v[42:43], v42 offset1:1
	ds_read2_b32 v[44:45], v44 offset1:1
	ds_read2_b32 v[46:47], v46 offset1:1
	ds_read2_b32 v[48:49], v48 offset1:1
	ds_read2_b32 v[50:51], v50 offset1:1
	ds_read2_b32 v[52:53], v52 offset1:1
	ds_read2_b32 v[54:55], v54 offset1:1
	s_waitcnt vmcnt(15) lgkmcnt(8)
	v_fma_f32 v32, v64, v38, v32
	v_fma_f32 v33, v65, v38, v33
	s_waitcnt lgkmcnt(7)
	v_fma_f32 v30, v64, v40, v30
	v_fma_f32 v31, v65, v40, v31
	s_waitcnt lgkmcnt(6)
	v_fma_f32 v28, v64, v42, v28
	v_fma_f32 v29, v65, v42, v29
	s_waitcnt lgkmcnt(5)
	v_fma_f32 v26, v64, v44, v26
	v_fma_f32 v27, v65, v44, v27
	s_waitcnt lgkmcnt(4)
	v_fma_f32 v24, v64, v46, v24
	v_fma_f32 v25, v65, v46, v25
	s_waitcnt lgkmcnt(3)
	v_fma_f32 v22, v64, v48, v22
	v_fma_f32 v23, v65, v48, v23
	s_waitcnt lgkmcnt(2)
	v_fma_f32 v20, v64, v50, v20
	v_fma_f32 v21, v65, v50, v21
	s_waitcnt lgkmcnt(1)
	v_fma_f32 v18, v64, v52, v18
	v_fma_f32 v19, v65, v52, v19
	s_waitcnt lgkmcnt(0)
	v_fma_f32 v16, v64, v54, v16
	v_fma_f32 v17, v65, v54, v17
	s_mov_b32 s0, 0xc000
	v_lshl_add_u64 v[92:93], v[94:95], 0, s[0:1]
	global_load_dwordx2 v[64:65], v[92:93], off
	s_waitcnt vmcnt(15)
	v_fma_f32 v32, v66, v39, v32
	v_fma_f32 v33, v67, v39, v33
	v_fma_f32 v30, v66, v41, v30
	v_fma_f32 v31, v67, v41, v31
	v_fma_f32 v28, v66, v43, v28
	v_fma_f32 v29, v67, v43, v29
	v_fma_f32 v26, v66, v45, v26
	v_fma_f32 v27, v67, v45, v27
	v_fma_f32 v24, v66, v47, v24
	v_fma_f32 v25, v67, v47, v25
	v_fma_f32 v22, v66, v49, v22
	v_fma_f32 v23, v67, v49, v23
	v_fma_f32 v20, v66, v51, v20
	v_fma_f32 v21, v67, v51, v21
	v_fma_f32 v18, v66, v53, v18
	v_fma_f32 v19, v67, v53, v19
	v_fma_f32 v16, v66, v55, v16
	v_fma_f32 v17, v67, v55, v17
	s_mov_b32 s0, 0x12000
	v_lshl_add_u64 v[92:93], v[94:95], 0, s[0:1]
	global_load_dwordx2 v[66:67], v[92:93], off
	v_add_u32_e32 v40, 0x1010, v35
	v_add_u32_e32 v42, 0x2010, v35
	v_add_u32_e32 v44, 0x3010, v35
	v_add_u32_e32 v46, 0x4010, v35
	v_add_u32_e32 v48, 0x5010, v35
	v_add_u32_e32 v50, 0x6010, v35
	v_add_u32_e32 v52, 0x7010, v35
	v_add_u32_e32 v54, 0x8010, v35
	ds_read2_b32 v[38:39], v35 offset0:4 offset1:5
	ds_read2_b32 v[40:41], v40 offset1:1
	ds_read2_b32 v[42:43], v42 offset1:1
	ds_read2_b32 v[44:45], v44 offset1:1
	ds_read2_b32 v[46:47], v46 offset1:1
	ds_read2_b32 v[48:49], v48 offset1:1
	ds_read2_b32 v[50:51], v50 offset1:1
	ds_read2_b32 v[52:53], v52 offset1:1
	ds_read2_b32 v[54:55], v54 offset1:1
	s_waitcnt vmcnt(15) lgkmcnt(8)
	v_fma_f32 v32, v68, v38, v32
	v_fma_f32 v33, v69, v38, v33
	s_waitcnt lgkmcnt(7)
	v_fma_f32 v30, v68, v40, v30
	v_fma_f32 v31, v69, v40, v31
	s_waitcnt lgkmcnt(6)
	v_fma_f32 v28, v68, v42, v28
	v_fma_f32 v29, v69, v42, v29
	s_waitcnt lgkmcnt(5)
	v_fma_f32 v26, v68, v44, v26
	v_fma_f32 v27, v69, v44, v27
	s_waitcnt lgkmcnt(4)
	v_fma_f32 v24, v68, v46, v24
	v_fma_f32 v25, v69, v46, v25
	s_waitcnt lgkmcnt(3)
	v_fma_f32 v22, v68, v48, v22
	v_fma_f32 v23, v69, v48, v23
	s_waitcnt lgkmcnt(2)
	v_fma_f32 v20, v68, v50, v20
	v_fma_f32 v21, v69, v50, v21
	s_waitcnt lgkmcnt(1)
	v_fma_f32 v18, v68, v52, v18
	v_fma_f32 v19, v69, v52, v19
	s_waitcnt lgkmcnt(0)
	v_fma_f32 v16, v68, v54, v16
	v_fma_f32 v17, v69, v54, v17
	s_mov_b32 s0, 0x18000
	v_lshl_add_u64 v[92:93], v[94:95], 0, s[0:1]
	global_load_dwordx2 v[68:69], v[92:93], off
	s_waitcnt vmcnt(15)
	v_fma_f32 v32, v70, v39, v32
	v_fma_f32 v33, v71, v39, v33
	v_fma_f32 v30, v70, v41, v30
	v_fma_f32 v31, v71, v41, v31
	v_fma_f32 v28, v70, v43, v28
	v_fma_f32 v29, v71, v43, v29
	v_fma_f32 v26, v70, v45, v26
	v_fma_f32 v27, v71, v45, v27
	v_fma_f32 v24, v70, v47, v24
	v_fma_f32 v25, v71, v47, v25
	v_fma_f32 v22, v70, v49, v22
	v_fma_f32 v23, v71, v49, v23
	v_fma_f32 v20, v70, v51, v20
	v_fma_f32 v21, v71, v51, v21
	v_fma_f32 v18, v70, v53, v18
	v_fma_f32 v19, v71, v53, v19
	v_fma_f32 v16, v70, v55, v16
	v_fma_f32 v17, v71, v55, v17
	s_mov_b32 s0, 0x1e000
	v_lshl_add_u64 v[92:93], v[94:95], 0, s[0:1]
	global_load_dwordx2 v[70:71], v[92:93], off
	v_add_u32_e32 v40, 0x1018, v35
	v_add_u32_e32 v42, 0x2018, v35
	v_add_u32_e32 v44, 0x3018, v35
	v_add_u32_e32 v46, 0x4018, v35
	v_add_u32_e32 v48, 0x5018, v35
	v_add_u32_e32 v50, 0x6018, v35
	v_add_u32_e32 v52, 0x7018, v35
	v_add_u32_e32 v54, 0x8018, v35
	ds_read2_b32 v[38:39], v35 offset0:6 offset1:7
	ds_read2_b32 v[40:41], v40 offset1:1
	ds_read2_b32 v[42:43], v42 offset1:1
	ds_read2_b32 v[44:45], v44 offset1:1
	ds_read2_b32 v[46:47], v46 offset1:1
	ds_read2_b32 v[48:49], v48 offset1:1
	ds_read2_b32 v[50:51], v50 offset1:1
	ds_read2_b32 v[52:53], v52 offset1:1
	ds_read2_b32 v[54:55], v54 offset1:1
	s_waitcnt vmcnt(15) lgkmcnt(8)
	v_fma_f32 v32, v72, v38, v32
	v_fma_f32 v33, v73, v38, v33
	s_waitcnt lgkmcnt(7)
	v_fma_f32 v30, v72, v40, v30
	v_fma_f32 v31, v73, v40, v31
	s_waitcnt lgkmcnt(6)
	v_fma_f32 v28, v72, v42, v28
	v_fma_f32 v29, v73, v42, v29
	s_waitcnt lgkmcnt(5)
	v_fma_f32 v26, v72, v44, v26
	v_fma_f32 v27, v73, v44, v27
	s_waitcnt lgkmcnt(4)
	v_fma_f32 v24, v72, v46, v24
	v_fma_f32 v25, v73, v46, v25
	s_waitcnt lgkmcnt(3)
	v_fma_f32 v22, v72, v48, v22
	v_fma_f32 v23, v73, v48, v23
	s_waitcnt lgkmcnt(2)
	v_fma_f32 v20, v72, v50, v20
	v_fma_f32 v21, v73, v50, v21
	s_waitcnt lgkmcnt(1)
	v_fma_f32 v18, v72, v52, v18
	v_fma_f32 v19, v73, v52, v19
	s_waitcnt lgkmcnt(0)
	v_fma_f32 v16, v72, v54, v16
	v_fma_f32 v17, v73, v54, v17
	s_mov_b32 s0, 0x24000
	v_lshl_add_u64 v[92:93], v[94:95], 0, s[0:1]
	global_load_dwordx2 v[72:73], v[92:93], off
	s_waitcnt vmcnt(15)
	v_fma_f32 v32, v74, v39, v32
	v_fma_f32 v33, v75, v39, v33
	v_fma_f32 v30, v74, v41, v30
	v_fma_f32 v31, v75, v41, v31
	v_fma_f32 v28, v74, v43, v28
	v_fma_f32 v29, v75, v43, v29
	v_fma_f32 v26, v74, v45, v26
	v_fma_f32 v27, v75, v45, v27
	v_fma_f32 v24, v74, v47, v24
	v_fma_f32 v25, v75, v47, v25
	v_fma_f32 v22, v74, v49, v22
	v_fma_f32 v23, v75, v49, v23
	v_fma_f32 v20, v74, v51, v20
	v_fma_f32 v21, v75, v51, v21
	v_fma_f32 v18, v74, v53, v18
	v_fma_f32 v19, v75, v53, v19
	v_fma_f32 v16, v74, v55, v16
	v_fma_f32 v17, v75, v55, v17
	s_mov_b32 s0, 0x2a000
	v_lshl_add_u64 v[92:93], v[94:95], 0, s[0:1]
	global_load_dwordx2 v[74:75], v[92:93], off
	v_add_u32_e32 v40, 0x1020, v35
	v_add_u32_e32 v42, 0x2020, v35
	v_add_u32_e32 v44, 0x3020, v35
	v_add_u32_e32 v46, 0x4020, v35
	v_add_u32_e32 v48, 0x5020, v35
	v_add_u32_e32 v50, 0x6020, v35
	v_add_u32_e32 v52, 0x7020, v35
	v_add_u32_e32 v54, 0x8020, v35
	ds_read2_b32 v[38:39], v35 offset0:8 offset1:9
	ds_read2_b32 v[40:41], v40 offset1:1
	ds_read2_b32 v[42:43], v42 offset1:1
	ds_read2_b32 v[44:45], v44 offset1:1
	ds_read2_b32 v[46:47], v46 offset1:1
	ds_read2_b32 v[48:49], v48 offset1:1
	ds_read2_b32 v[50:51], v50 offset1:1
	ds_read2_b32 v[52:53], v52 offset1:1
	ds_read2_b32 v[54:55], v54 offset1:1
	s_waitcnt vmcnt(15) lgkmcnt(8)
	v_fma_f32 v32, v76, v38, v32
	v_fma_f32 v33, v77, v38, v33
	s_waitcnt lgkmcnt(7)
	v_fma_f32 v30, v76, v40, v30
	v_fma_f32 v31, v77, v40, v31
	s_waitcnt lgkmcnt(6)
	v_fma_f32 v28, v76, v42, v28
	v_fma_f32 v29, v77, v42, v29
	s_waitcnt lgkmcnt(5)
	v_fma_f32 v26, v76, v44, v26
	v_fma_f32 v27, v77, v44, v27
	s_waitcnt lgkmcnt(4)
	v_fma_f32 v24, v76, v46, v24
	v_fma_f32 v25, v77, v46, v25
	s_waitcnt lgkmcnt(3)
	v_fma_f32 v22, v76, v48, v22
	v_fma_f32 v23, v77, v48, v23
	s_waitcnt lgkmcnt(2)
	v_fma_f32 v20, v76, v50, v20
	v_fma_f32 v21, v77, v50, v21
	s_waitcnt lgkmcnt(1)
	v_fma_f32 v18, v76, v52, v18
	v_fma_f32 v19, v77, v52, v19
	s_waitcnt lgkmcnt(0)
	v_fma_f32 v16, v76, v54, v16
	v_fma_f32 v17, v77, v54, v17
	s_mov_b32 s0, 0x30000
	v_lshl_add_u64 v[92:93], v[94:95], 0, s[0:1]
	global_load_dwordx2 v[76:77], v[92:93], off
	s_waitcnt vmcnt(15)
	v_fma_f32 v32, v78, v39, v32
	v_fma_f32 v33, v79, v39, v33
	v_fma_f32 v30, v78, v41, v30
	v_fma_f32 v31, v79, v41, v31
	v_fma_f32 v28, v78, v43, v28
	v_fma_f32 v29, v79, v43, v29
	v_fma_f32 v26, v78, v45, v26
	v_fma_f32 v27, v79, v45, v27
	v_fma_f32 v24, v78, v47, v24
	v_fma_f32 v25, v79, v47, v25
	v_fma_f32 v22, v78, v49, v22
	v_fma_f32 v23, v79, v49, v23
	v_fma_f32 v20, v78, v51, v20
	v_fma_f32 v21, v79, v51, v21
	v_fma_f32 v18, v78, v53, v18
	v_fma_f32 v19, v79, v53, v19
	v_fma_f32 v16, v78, v55, v16
	v_fma_f32 v17, v79, v55, v17
	s_mov_b32 s0, 0x36000
	v_lshl_add_u64 v[92:93], v[94:95], 0, s[0:1]
	global_load_dwordx2 v[78:79], v[92:93], off
	v_add_u32_e32 v40, 0x1028, v35
	v_add_u32_e32 v42, 0x2028, v35
	v_add_u32_e32 v44, 0x3028, v35
	v_add_u32_e32 v46, 0x4028, v35
	v_add_u32_e32 v48, 0x5028, v35
	v_add_u32_e32 v50, 0x6028, v35
	v_add_u32_e32 v52, 0x7028, v35
	v_add_u32_e32 v54, 0x8028, v35
	ds_read2_b32 v[38:39], v35 offset0:10 offset1:11
	ds_read2_b32 v[40:41], v40 offset1:1
	ds_read2_b32 v[42:43], v42 offset1:1
	ds_read2_b32 v[44:45], v44 offset1:1
	ds_read2_b32 v[46:47], v46 offset1:1
	ds_read2_b32 v[48:49], v48 offset1:1
	ds_read2_b32 v[50:51], v50 offset1:1
	ds_read2_b32 v[52:53], v52 offset1:1
	ds_read2_b32 v[54:55], v54 offset1:1
	s_waitcnt vmcnt(15) lgkmcnt(8)
	v_fma_f32 v32, v80, v38, v32
	v_fma_f32 v33, v81, v38, v33
	s_waitcnt lgkmcnt(7)
	v_fma_f32 v30, v80, v40, v30
	v_fma_f32 v31, v81, v40, v31
	s_waitcnt lgkmcnt(6)
	v_fma_f32 v28, v80, v42, v28
	v_fma_f32 v29, v81, v42, v29
	s_waitcnt lgkmcnt(5)
	v_fma_f32 v26, v80, v44, v26
	v_fma_f32 v27, v81, v44, v27
	s_waitcnt lgkmcnt(4)
	v_fma_f32 v24, v80, v46, v24
	v_fma_f32 v25, v81, v46, v25
	s_waitcnt lgkmcnt(3)
	v_fma_f32 v22, v80, v48, v22
	v_fma_f32 v23, v81, v48, v23
	s_waitcnt lgkmcnt(2)
	v_fma_f32 v20, v80, v50, v20
	v_fma_f32 v21, v81, v50, v21
	s_waitcnt lgkmcnt(1)
	v_fma_f32 v18, v80, v52, v18
	v_fma_f32 v19, v81, v52, v19
	s_waitcnt lgkmcnt(0)
	v_fma_f32 v16, v80, v54, v16
	v_fma_f32 v17, v81, v54, v17
	s_mov_b32 s0, 0x3c000
	v_lshl_add_u64 v[92:93], v[94:95], 0, s[0:1]
	global_load_dwordx2 v[80:81], v[92:93], off
	s_waitcnt vmcnt(15)
	v_fma_f32 v32, v82, v39, v32
	v_fma_f32 v33, v83, v39, v33
	v_fma_f32 v30, v82, v41, v30
	v_fma_f32 v31, v83, v41, v31
	v_fma_f32 v28, v82, v43, v28
	v_fma_f32 v29, v83, v43, v29
	v_fma_f32 v26, v82, v45, v26
	v_fma_f32 v27, v83, v45, v27
	v_fma_f32 v24, v82, v47, v24
	v_fma_f32 v25, v83, v47, v25
	v_fma_f32 v22, v82, v49, v22
	v_fma_f32 v23, v83, v49, v23
	v_fma_f32 v20, v82, v51, v20
	v_fma_f32 v21, v83, v51, v21
	v_fma_f32 v18, v82, v53, v18
	v_fma_f32 v19, v83, v53, v19
	v_fma_f32 v16, v82, v55, v16
	v_fma_f32 v17, v83, v55, v17
	s_mov_b32 s0, 0x42000
	v_lshl_add_u64 v[92:93], v[94:95], 0, s[0:1]
	global_load_dwordx2 v[82:83], v[92:93], off
	v_add_u32_e32 v40, 0x1030, v35
	v_add_u32_e32 v42, 0x2030, v35
	v_add_u32_e32 v44, 0x3030, v35
	v_add_u32_e32 v46, 0x4030, v35
	v_add_u32_e32 v48, 0x5030, v35
	v_add_u32_e32 v50, 0x6030, v35
	v_add_u32_e32 v52, 0x7030, v35
	v_add_u32_e32 v54, 0x8030, v35
	ds_read2_b32 v[38:39], v35 offset0:12 offset1:13
	ds_read2_b32 v[40:41], v40 offset1:1
	ds_read2_b32 v[42:43], v42 offset1:1
	ds_read2_b32 v[44:45], v44 offset1:1
	ds_read2_b32 v[46:47], v46 offset1:1
	ds_read2_b32 v[48:49], v48 offset1:1
	ds_read2_b32 v[50:51], v50 offset1:1
	ds_read2_b32 v[52:53], v52 offset1:1
	ds_read2_b32 v[54:55], v54 offset1:1
	s_waitcnt vmcnt(15) lgkmcnt(8)
	v_fma_f32 v32, v84, v38, v32
	v_fma_f32 v33, v85, v38, v33
	s_waitcnt lgkmcnt(7)
	v_fma_f32 v30, v84, v40, v30
	v_fma_f32 v31, v85, v40, v31
	s_waitcnt lgkmcnt(6)
	v_fma_f32 v28, v84, v42, v28
	v_fma_f32 v29, v85, v42, v29
	s_waitcnt lgkmcnt(5)
	v_fma_f32 v26, v84, v44, v26
	v_fma_f32 v27, v85, v44, v27
	s_waitcnt lgkmcnt(4)
	v_fma_f32 v24, v84, v46, v24
	v_fma_f32 v25, v85, v46, v25
	s_waitcnt lgkmcnt(3)
	v_fma_f32 v22, v84, v48, v22
	v_fma_f32 v23, v85, v48, v23
	s_waitcnt lgkmcnt(2)
	v_fma_f32 v20, v84, v50, v20
	v_fma_f32 v21, v85, v50, v21
	s_waitcnt lgkmcnt(1)
	v_fma_f32 v18, v84, v52, v18
	v_fma_f32 v19, v85, v52, v19
	s_waitcnt lgkmcnt(0)
	v_fma_f32 v16, v84, v54, v16
	v_fma_f32 v17, v85, v54, v17
	s_mov_b32 s0, 0x48000
	v_lshl_add_u64 v[92:93], v[94:95], 0, s[0:1]
	global_load_dwordx2 v[84:85], v[92:93], off
	s_waitcnt vmcnt(15)
	v_fma_f32 v32, v86, v39, v32
	v_fma_f32 v33, v87, v39, v33
	v_fma_f32 v30, v86, v41, v30
	v_fma_f32 v31, v87, v41, v31
	v_fma_f32 v28, v86, v43, v28
	v_fma_f32 v29, v87, v43, v29
	v_fma_f32 v26, v86, v45, v26
	v_fma_f32 v27, v87, v45, v27
	v_fma_f32 v24, v86, v47, v24
	v_fma_f32 v25, v87, v47, v25
	v_fma_f32 v22, v86, v49, v22
	v_fma_f32 v23, v87, v49, v23
	v_fma_f32 v20, v86, v51, v20
	v_fma_f32 v21, v87, v51, v21
	v_fma_f32 v18, v86, v53, v18
	v_fma_f32 v19, v87, v53, v19
	v_fma_f32 v16, v86, v55, v16
	v_fma_f32 v17, v87, v55, v17
	s_mov_b32 s0, 0x4e000
	v_lshl_add_u64 v[92:93], v[94:95], 0, s[0:1]
	global_load_dwordx2 v[86:87], v[92:93], off
	v_add_u32_e32 v40, 0x1038, v35
	v_add_u32_e32 v42, 0x2038, v35
	v_add_u32_e32 v44, 0x3038, v35
	v_add_u32_e32 v46, 0x4038, v35
	v_add_u32_e32 v48, 0x5038, v35
	v_add_u32_e32 v50, 0x6038, v35
	v_add_u32_e32 v52, 0x7038, v35
	v_add_u32_e32 v54, 0x8038, v35
	ds_read2_b32 v[38:39], v35 offset0:14 offset1:15
	ds_read2_b32 v[40:41], v40 offset1:1
	ds_read2_b32 v[42:43], v42 offset1:1
	ds_read2_b32 v[44:45], v44 offset1:1
	ds_read2_b32 v[46:47], v46 offset1:1
	ds_read2_b32 v[48:49], v48 offset1:1
	ds_read2_b32 v[50:51], v50 offset1:1
	ds_read2_b32 v[52:53], v52 offset1:1
	ds_read2_b32 v[54:55], v54 offset1:1
	v_add_u32_e32 v35, 64, v35
	s_waitcnt vmcnt(15) lgkmcnt(8)
	v_fma_f32 v32, v88, v38, v32
	v_fma_f32 v33, v89, v38, v33
	s_waitcnt lgkmcnt(7)
	v_fma_f32 v30, v88, v40, v30
	v_fma_f32 v31, v89, v40, v31
	s_waitcnt lgkmcnt(6)
	v_fma_f32 v28, v88, v42, v28
	v_fma_f32 v29, v89, v42, v29
	s_waitcnt lgkmcnt(5)
	v_fma_f32 v26, v88, v44, v26
	v_fma_f32 v27, v89, v44, v27
	s_waitcnt lgkmcnt(4)
	v_fma_f32 v24, v88, v46, v24
	v_fma_f32 v25, v89, v46, v25
	s_waitcnt lgkmcnt(3)
	v_fma_f32 v22, v88, v48, v22
	v_fma_f32 v23, v89, v48, v23
	s_waitcnt lgkmcnt(2)
	v_fma_f32 v20, v88, v50, v20
	v_fma_f32 v21, v89, v50, v21
	s_waitcnt lgkmcnt(1)
	v_fma_f32 v18, v88, v52, v18
	v_fma_f32 v19, v89, v52, v19
	s_waitcnt lgkmcnt(0)
	v_fma_f32 v16, v88, v54, v16
	v_fma_f32 v17, v89, v54, v17
	s_mov_b32 s0, 0x54000
	v_lshl_add_u64 v[92:93], v[94:95], 0, s[0:1]
	global_load_dwordx2 v[88:89], v[92:93], off
	s_waitcnt vmcnt(15)
	v_fma_f32 v32, v90, v39, v32
	v_fma_f32 v33, v91, v39, v33
	v_fma_f32 v30, v90, v41, v30
	v_fma_f32 v31, v91, v41, v31
	v_fma_f32 v28, v90, v43, v28
	v_fma_f32 v29, v91, v43, v29
	v_fma_f32 v26, v90, v45, v26
	v_fma_f32 v27, v91, v45, v27
	v_fma_f32 v24, v90, v47, v24
	v_fma_f32 v25, v91, v47, v25
	v_fma_f32 v22, v90, v49, v22
	v_fma_f32 v23, v91, v49, v23
	v_fma_f32 v20, v90, v51, v20
	v_fma_f32 v21, v91, v51, v21
	v_fma_f32 v18, v90, v53, v18
	v_fma_f32 v19, v91, v53, v19
	v_fma_f32 v16, v90, v55, v16
	v_fma_f32 v17, v91, v55, v17
	s_mov_b32 s0, 0x5a000
	v_lshl_add_u64 v[92:93], v[94:95], 0, s[0:1]
	global_load_dwordx2 v[90:91], v[92:93], off
	s_mov_b64 s[6:7], s[40:41]
	s_cmp_eq_u32 s6, 0x2a0000
	s_cbranch_scc0 .LBB0_50
	v_add_u32_e32 v40, 0x1000, v35
	v_add_u32_e32 v42, 0x2000, v35
	v_add_u32_e32 v44, 0x3000, v35
	v_add_u32_e32 v46, 0x4000, v35
	v_add_u32_e32 v48, 0x5000, v35
	v_add_u32_e32 v50, 0x6000, v35
	v_add_u32_e32 v52, 0x7000, v35
	v_add_u32_e32 v54, 0x8000, v35
	ds_read2_b32 v[38:39], v35 offset1:1
	ds_read2_b32 v[40:41], v40 offset1:1
	ds_read2_b32 v[42:43], v42 offset1:1
	ds_read2_b32 v[44:45], v44 offset1:1
	ds_read2_b32 v[46:47], v46 offset1:1
	ds_read2_b32 v[48:49], v48 offset1:1
	ds_read2_b32 v[50:51], v50 offset1:1
	ds_read2_b32 v[52:53], v52 offset1:1
	ds_read2_b32 v[54:55], v54 offset1:1
	s_waitcnt vmcnt(15) lgkmcnt(8)
	v_fma_f32 v32, v60, v38, v32
	v_fma_f32 v33, v61, v38, v33
	s_waitcnt lgkmcnt(7)
	v_fma_f32 v30, v60, v40, v30
	v_fma_f32 v31, v61, v40, v31
	s_waitcnt lgkmcnt(6)
	v_fma_f32 v28, v60, v42, v28
	v_fma_f32 v29, v61, v42, v29
	s_waitcnt lgkmcnt(5)
	v_fma_f32 v26, v60, v44, v26
	v_fma_f32 v27, v61, v44, v27
	s_waitcnt lgkmcnt(4)
	v_fma_f32 v24, v60, v46, v24
	v_fma_f32 v25, v61, v46, v25
	s_waitcnt lgkmcnt(3)
	v_fma_f32 v22, v60, v48, v22
	v_fma_f32 v23, v61, v48, v23
	s_waitcnt lgkmcnt(2)
	v_fma_f32 v20, v60, v50, v20
	v_fma_f32 v21, v61, v50, v21
	s_waitcnt lgkmcnt(1)
	v_fma_f32 v18, v60, v52, v18
	v_fma_f32 v19, v61, v52, v19
	s_waitcnt lgkmcnt(0)
	v_fma_f32 v16, v60, v54, v16
	v_fma_f32 v17, v61, v54, v17
	s_waitcnt vmcnt(14)
	v_fma_f32 v32, v62, v39, v32
	v_fma_f32 v33, v63, v39, v33
	v_fma_f32 v30, v62, v41, v30
	v_fma_f32 v31, v63, v41, v31
	v_fma_f32 v28, v62, v43, v28
	v_fma_f32 v29, v63, v43, v29
	v_fma_f32 v26, v62, v45, v26
	v_fma_f32 v27, v63, v45, v27
	v_fma_f32 v24, v62, v47, v24
	v_fma_f32 v25, v63, v47, v25
	v_fma_f32 v22, v62, v49, v22
	v_fma_f32 v23, v63, v49, v23
	v_fma_f32 v20, v62, v51, v20
	v_fma_f32 v21, v63, v51, v21
	v_fma_f32 v18, v62, v53, v18
	v_fma_f32 v19, v63, v53, v19
	v_fma_f32 v16, v62, v55, v16
	v_fma_f32 v17, v63, v55, v17
	v_add_u32_e32 v40, 0x1008, v35
	v_add_u32_e32 v42, 0x2008, v35
	v_add_u32_e32 v44, 0x3008, v35
	v_add_u32_e32 v46, 0x4008, v35
	v_add_u32_e32 v48, 0x5008, v35
	v_add_u32_e32 v50, 0x6008, v35
	v_add_u32_e32 v52, 0x7008, v35
	v_add_u32_e32 v54, 0x8008, v35
	ds_read2_b32 v[38:39], v35 offset0:2 offset1:3
	ds_read2_b32 v[40:41], v40 offset1:1
	ds_read2_b32 v[42:43], v42 offset1:1
	ds_read2_b32 v[44:45], v44 offset1:1
	ds_read2_b32 v[46:47], v46 offset1:1
	ds_read2_b32 v[48:49], v48 offset1:1
	ds_read2_b32 v[50:51], v50 offset1:1
	ds_read2_b32 v[52:53], v52 offset1:1
	ds_read2_b32 v[54:55], v54 offset1:1
	s_waitcnt vmcnt(13) lgkmcnt(8)
	v_fma_f32 v32, v64, v38, v32
	v_fma_f32 v33, v65, v38, v33
	s_waitcnt lgkmcnt(7)
	v_fma_f32 v30, v64, v40, v30
	v_fma_f32 v31, v65, v40, v31
	s_waitcnt lgkmcnt(6)
	v_fma_f32 v28, v64, v42, v28
	v_fma_f32 v29, v65, v42, v29
	s_waitcnt lgkmcnt(5)
	v_fma_f32 v26, v64, v44, v26
	v_fma_f32 v27, v65, v44, v27
	s_waitcnt lgkmcnt(4)
	v_fma_f32 v24, v64, v46, v24
	v_fma_f32 v25, v65, v46, v25
	s_waitcnt lgkmcnt(3)
	v_fma_f32 v22, v64, v48, v22
	v_fma_f32 v23, v65, v48, v23
	s_waitcnt lgkmcnt(2)
	v_fma_f32 v20, v64, v50, v20
	v_fma_f32 v21, v65, v50, v21
	s_waitcnt lgkmcnt(1)
	v_fma_f32 v18, v64, v52, v18
	v_fma_f32 v19, v65, v52, v19
	s_waitcnt lgkmcnt(0)
	v_fma_f32 v16, v64, v54, v16
	v_fma_f32 v17, v65, v54, v17
	s_waitcnt vmcnt(12)
	v_fma_f32 v32, v66, v39, v32
	v_fma_f32 v33, v67, v39, v33
	v_fma_f32 v30, v66, v41, v30
	v_fma_f32 v31, v67, v41, v31
	v_fma_f32 v28, v66, v43, v28
	v_fma_f32 v29, v67, v43, v29
	v_fma_f32 v26, v66, v45, v26
	v_fma_f32 v27, v67, v45, v27
	v_fma_f32 v24, v66, v47, v24
	v_fma_f32 v25, v67, v47, v25
	v_fma_f32 v22, v66, v49, v22
	v_fma_f32 v23, v67, v49, v23
	v_fma_f32 v20, v66, v51, v20
	v_fma_f32 v21, v67, v51, v21
	v_fma_f32 v18, v66, v53, v18
	v_fma_f32 v19, v67, v53, v19
	v_fma_f32 v16, v66, v55, v16
	v_fma_f32 v17, v67, v55, v17
	v_add_u32_e32 v40, 0x1010, v35
	v_add_u32_e32 v42, 0x2010, v35
	v_add_u32_e32 v44, 0x3010, v35
	v_add_u32_e32 v46, 0x4010, v35
	v_add_u32_e32 v48, 0x5010, v35
	v_add_u32_e32 v50, 0x6010, v35
	v_add_u32_e32 v52, 0x7010, v35
	v_add_u32_e32 v54, 0x8010, v35
	ds_read2_b32 v[38:39], v35 offset0:4 offset1:5
	ds_read2_b32 v[40:41], v40 offset1:1
	ds_read2_b32 v[42:43], v42 offset1:1
	ds_read2_b32 v[44:45], v44 offset1:1
	ds_read2_b32 v[46:47], v46 offset1:1
	ds_read2_b32 v[48:49], v48 offset1:1
	ds_read2_b32 v[50:51], v50 offset1:1
	ds_read2_b32 v[52:53], v52 offset1:1
	ds_read2_b32 v[54:55], v54 offset1:1
	s_waitcnt vmcnt(11) lgkmcnt(8)
	v_fma_f32 v32, v68, v38, v32
	v_fma_f32 v33, v69, v38, v33
	s_waitcnt lgkmcnt(7)
	v_fma_f32 v30, v68, v40, v30
	v_fma_f32 v31, v69, v40, v31
	s_waitcnt lgkmcnt(6)
	v_fma_f32 v28, v68, v42, v28
	v_fma_f32 v29, v69, v42, v29
	s_waitcnt lgkmcnt(5)
	v_fma_f32 v26, v68, v44, v26
	v_fma_f32 v27, v69, v44, v27
	s_waitcnt lgkmcnt(4)
	v_fma_f32 v24, v68, v46, v24
	v_fma_f32 v25, v69, v46, v25
	s_waitcnt lgkmcnt(3)
	v_fma_f32 v22, v68, v48, v22
	v_fma_f32 v23, v69, v48, v23
	s_waitcnt lgkmcnt(2)
	v_fma_f32 v20, v68, v50, v20
	v_fma_f32 v21, v69, v50, v21
	s_waitcnt lgkmcnt(1)
	v_fma_f32 v18, v68, v52, v18
	v_fma_f32 v19, v69, v52, v19
	s_waitcnt lgkmcnt(0)
	v_fma_f32 v16, v68, v54, v16
	v_fma_f32 v17, v69, v54, v17
	s_waitcnt vmcnt(10)
	v_fma_f32 v32, v70, v39, v32
	v_fma_f32 v33, v71, v39, v33
	v_fma_f32 v30, v70, v41, v30
	v_fma_f32 v31, v71, v41, v31
	v_fma_f32 v28, v70, v43, v28
	v_fma_f32 v29, v71, v43, v29
	v_fma_f32 v26, v70, v45, v26
	v_fma_f32 v27, v71, v45, v27
	v_fma_f32 v24, v70, v47, v24
	v_fma_f32 v25, v71, v47, v25
	v_fma_f32 v22, v70, v49, v22
	v_fma_f32 v23, v71, v49, v23
	v_fma_f32 v20, v70, v51, v20
	v_fma_f32 v21, v71, v51, v21
	v_fma_f32 v18, v70, v53, v18
	v_fma_f32 v19, v71, v53, v19
	v_fma_f32 v16, v70, v55, v16
	v_fma_f32 v17, v71, v55, v17
	v_add_u32_e32 v40, 0x1018, v35
	v_add_u32_e32 v42, 0x2018, v35
	v_add_u32_e32 v44, 0x3018, v35
	v_add_u32_e32 v46, 0x4018, v35
	v_add_u32_e32 v48, 0x5018, v35
	v_add_u32_e32 v50, 0x6018, v35
	v_add_u32_e32 v52, 0x7018, v35
	v_add_u32_e32 v54, 0x8018, v35
	ds_read2_b32 v[38:39], v35 offset0:6 offset1:7
	ds_read2_b32 v[40:41], v40 offset1:1
	ds_read2_b32 v[42:43], v42 offset1:1
	ds_read2_b32 v[44:45], v44 offset1:1
	ds_read2_b32 v[46:47], v46 offset1:1
	ds_read2_b32 v[48:49], v48 offset1:1
	ds_read2_b32 v[50:51], v50 offset1:1
	ds_read2_b32 v[52:53], v52 offset1:1
	ds_read2_b32 v[54:55], v54 offset1:1
	s_waitcnt vmcnt(9) lgkmcnt(8)
	v_fma_f32 v32, v72, v38, v32
	v_fma_f32 v33, v73, v38, v33
	s_waitcnt lgkmcnt(7)
	v_fma_f32 v30, v72, v40, v30
	v_fma_f32 v31, v73, v40, v31
	s_waitcnt lgkmcnt(6)
	v_fma_f32 v28, v72, v42, v28
	v_fma_f32 v29, v73, v42, v29
	s_waitcnt lgkmcnt(5)
	v_fma_f32 v26, v72, v44, v26
	v_fma_f32 v27, v73, v44, v27
	s_waitcnt lgkmcnt(4)
	v_fma_f32 v24, v72, v46, v24
	v_fma_f32 v25, v73, v46, v25
	s_waitcnt lgkmcnt(3)
	v_fma_f32 v22, v72, v48, v22
	v_fma_f32 v23, v73, v48, v23
	s_waitcnt lgkmcnt(2)
	v_fma_f32 v20, v72, v50, v20
	v_fma_f32 v21, v73, v50, v21
	s_waitcnt lgkmcnt(1)
	v_fma_f32 v18, v72, v52, v18
	v_fma_f32 v19, v73, v52, v19
	s_waitcnt lgkmcnt(0)
	v_fma_f32 v16, v72, v54, v16
	v_fma_f32 v17, v73, v54, v17
	s_waitcnt vmcnt(8)
	v_fma_f32 v32, v74, v39, v32
	v_fma_f32 v33, v75, v39, v33
	v_fma_f32 v30, v74, v41, v30
	v_fma_f32 v31, v75, v41, v31
	v_fma_f32 v28, v74, v43, v28
	v_fma_f32 v29, v75, v43, v29
	v_fma_f32 v26, v74, v45, v26
	v_fma_f32 v27, v75, v45, v27
	v_fma_f32 v24, v74, v47, v24
	v_fma_f32 v25, v75, v47, v25
	v_fma_f32 v22, v74, v49, v22
	v_fma_f32 v23, v75, v49, v23
	v_fma_f32 v20, v74, v51, v20
	v_fma_f32 v21, v75, v51, v21
	v_fma_f32 v18, v74, v53, v18
	v_fma_f32 v19, v75, v53, v19
	v_fma_f32 v16, v74, v55, v16
	v_fma_f32 v17, v75, v55, v17
	v_add_u32_e32 v40, 0x1020, v35
	v_add_u32_e32 v42, 0x2020, v35
	v_add_u32_e32 v44, 0x3020, v35
	v_add_u32_e32 v46, 0x4020, v35
	v_add_u32_e32 v48, 0x5020, v35
	v_add_u32_e32 v50, 0x6020, v35
	v_add_u32_e32 v52, 0x7020, v35
	v_add_u32_e32 v54, 0x8020, v35
	ds_read2_b32 v[38:39], v35 offset0:8 offset1:9
	ds_read2_b32 v[40:41], v40 offset1:1
	ds_read2_b32 v[42:43], v42 offset1:1
	ds_read2_b32 v[44:45], v44 offset1:1
	ds_read2_b32 v[46:47], v46 offset1:1
	ds_read2_b32 v[48:49], v48 offset1:1
	ds_read2_b32 v[50:51], v50 offset1:1
	ds_read2_b32 v[52:53], v52 offset1:1
	ds_read2_b32 v[54:55], v54 offset1:1
	s_waitcnt vmcnt(7) lgkmcnt(8)
	v_fma_f32 v32, v76, v38, v32
	v_fma_f32 v33, v77, v38, v33
	s_waitcnt lgkmcnt(7)
	v_fma_f32 v30, v76, v40, v30
	v_fma_f32 v31, v77, v40, v31
	s_waitcnt lgkmcnt(6)
	v_fma_f32 v28, v76, v42, v28
	v_fma_f32 v29, v77, v42, v29
	s_waitcnt lgkmcnt(5)
	v_fma_f32 v26, v76, v44, v26
	v_fma_f32 v27, v77, v44, v27
	s_waitcnt lgkmcnt(4)
	v_fma_f32 v24, v76, v46, v24
	v_fma_f32 v25, v77, v46, v25
	s_waitcnt lgkmcnt(3)
	v_fma_f32 v22, v76, v48, v22
	v_fma_f32 v23, v77, v48, v23
	s_waitcnt lgkmcnt(2)
	v_fma_f32 v20, v76, v50, v20
	v_fma_f32 v21, v77, v50, v21
	s_waitcnt lgkmcnt(1)
	v_fma_f32 v18, v76, v52, v18
	v_fma_f32 v19, v77, v52, v19
	s_waitcnt lgkmcnt(0)
	v_fma_f32 v16, v76, v54, v16
	v_fma_f32 v17, v77, v54, v17
	s_waitcnt vmcnt(6)
	v_fma_f32 v32, v78, v39, v32
	v_fma_f32 v33, v79, v39, v33
	v_fma_f32 v30, v78, v41, v30
	v_fma_f32 v31, v79, v41, v31
	v_fma_f32 v28, v78, v43, v28
	v_fma_f32 v29, v79, v43, v29
	v_fma_f32 v26, v78, v45, v26
	v_fma_f32 v27, v79, v45, v27
	v_fma_f32 v24, v78, v47, v24
	v_fma_f32 v25, v79, v47, v25
	v_fma_f32 v22, v78, v49, v22
	v_fma_f32 v23, v79, v49, v23
	v_fma_f32 v20, v78, v51, v20
	v_fma_f32 v21, v79, v51, v21
	v_fma_f32 v18, v78, v53, v18
	v_fma_f32 v19, v79, v53, v19
	v_fma_f32 v16, v78, v55, v16
	v_fma_f32 v17, v79, v55, v17
	v_add_u32_e32 v40, 0x1028, v35
	v_add_u32_e32 v42, 0x2028, v35
	v_add_u32_e32 v44, 0x3028, v35
	v_add_u32_e32 v46, 0x4028, v35
	v_add_u32_e32 v48, 0x5028, v35
	v_add_u32_e32 v50, 0x6028, v35
	v_add_u32_e32 v52, 0x7028, v35
	v_add_u32_e32 v54, 0x8028, v35
	ds_read2_b32 v[38:39], v35 offset0:10 offset1:11
	ds_read2_b32 v[40:41], v40 offset1:1
	ds_read2_b32 v[42:43], v42 offset1:1
	ds_read2_b32 v[44:45], v44 offset1:1
	ds_read2_b32 v[46:47], v46 offset1:1
	ds_read2_b32 v[48:49], v48 offset1:1
	ds_read2_b32 v[50:51], v50 offset1:1
	ds_read2_b32 v[52:53], v52 offset1:1
	ds_read2_b32 v[54:55], v54 offset1:1
	s_waitcnt vmcnt(5) lgkmcnt(8)
	v_fma_f32 v32, v80, v38, v32
	v_fma_f32 v33, v81, v38, v33
	s_waitcnt lgkmcnt(7)
	v_fma_f32 v30, v80, v40, v30
	v_fma_f32 v31, v81, v40, v31
	s_waitcnt lgkmcnt(6)
	v_fma_f32 v28, v80, v42, v28
	v_fma_f32 v29, v81, v42, v29
	s_waitcnt lgkmcnt(5)
	v_fma_f32 v26, v80, v44, v26
	v_fma_f32 v27, v81, v44, v27
	s_waitcnt lgkmcnt(4)
	v_fma_f32 v24, v80, v46, v24
	v_fma_f32 v25, v81, v46, v25
	s_waitcnt lgkmcnt(3)
	v_fma_f32 v22, v80, v48, v22
	v_fma_f32 v23, v81, v48, v23
	s_waitcnt lgkmcnt(2)
	v_fma_f32 v20, v80, v50, v20
	v_fma_f32 v21, v81, v50, v21
	s_waitcnt lgkmcnt(1)
	v_fma_f32 v18, v80, v52, v18
	v_fma_f32 v19, v81, v52, v19
	s_waitcnt lgkmcnt(0)
	v_fma_f32 v16, v80, v54, v16
	v_fma_f32 v17, v81, v54, v17
	s_waitcnt vmcnt(4)
	v_fma_f32 v32, v82, v39, v32
	v_fma_f32 v33, v83, v39, v33
	v_fma_f32 v30, v82, v41, v30
	v_fma_f32 v31, v83, v41, v31
	v_fma_f32 v28, v82, v43, v28
	v_fma_f32 v29, v83, v43, v29
	v_fma_f32 v26, v82, v45, v26
	v_fma_f32 v27, v83, v45, v27
	v_fma_f32 v24, v82, v47, v24
	v_fma_f32 v25, v83, v47, v25
	v_fma_f32 v22, v82, v49, v22
	v_fma_f32 v23, v83, v49, v23
	v_fma_f32 v20, v82, v51, v20
	v_fma_f32 v21, v83, v51, v21
	v_fma_f32 v18, v82, v53, v18
	v_fma_f32 v19, v83, v53, v19
	v_fma_f32 v16, v82, v55, v16
	v_fma_f32 v17, v83, v55, v17
	v_add_u32_e32 v40, 0x1030, v35
	v_add_u32_e32 v42, 0x2030, v35
	v_add_u32_e32 v44, 0x3030, v35
	v_add_u32_e32 v46, 0x4030, v35
	v_add_u32_e32 v48, 0x5030, v35
	v_add_u32_e32 v50, 0x6030, v35
	v_add_u32_e32 v52, 0x7030, v35
	v_add_u32_e32 v54, 0x8030, v35
	ds_read2_b32 v[38:39], v35 offset0:12 offset1:13
	ds_read2_b32 v[40:41], v40 offset1:1
	ds_read2_b32 v[42:43], v42 offset1:1
	ds_read2_b32 v[44:45], v44 offset1:1
	ds_read2_b32 v[46:47], v46 offset1:1
	ds_read2_b32 v[48:49], v48 offset1:1
	ds_read2_b32 v[50:51], v50 offset1:1
	ds_read2_b32 v[52:53], v52 offset1:1
	ds_read2_b32 v[54:55], v54 offset1:1
	s_waitcnt vmcnt(3) lgkmcnt(8)
	v_fma_f32 v32, v84, v38, v32
	v_fma_f32 v33, v85, v38, v33
	s_waitcnt lgkmcnt(7)
	v_fma_f32 v30, v84, v40, v30
	v_fma_f32 v31, v85, v40, v31
	s_waitcnt lgkmcnt(6)
	v_fma_f32 v28, v84, v42, v28
	v_fma_f32 v29, v85, v42, v29
	s_waitcnt lgkmcnt(5)
	v_fma_f32 v26, v84, v44, v26
	v_fma_f32 v27, v85, v44, v27
	s_waitcnt lgkmcnt(4)
	v_fma_f32 v24, v84, v46, v24
	v_fma_f32 v25, v85, v46, v25
	s_waitcnt lgkmcnt(3)
	v_fma_f32 v22, v84, v48, v22
	v_fma_f32 v23, v85, v48, v23
	s_waitcnt lgkmcnt(2)
	v_fma_f32 v20, v84, v50, v20
	v_fma_f32 v21, v85, v50, v21
	s_waitcnt lgkmcnt(1)
	v_fma_f32 v18, v84, v52, v18
	v_fma_f32 v19, v85, v52, v19
	s_waitcnt lgkmcnt(0)
	v_fma_f32 v16, v84, v54, v16
	v_fma_f32 v17, v85, v54, v17
	s_waitcnt vmcnt(2)
	v_fma_f32 v32, v86, v39, v32
	v_fma_f32 v33, v87, v39, v33
	v_fma_f32 v30, v86, v41, v30
	v_fma_f32 v31, v87, v41, v31
	v_fma_f32 v28, v86, v43, v28
	v_fma_f32 v29, v87, v43, v29
	v_fma_f32 v26, v86, v45, v26
	v_fma_f32 v27, v87, v45, v27
	v_fma_f32 v24, v86, v47, v24
	v_fma_f32 v25, v87, v47, v25
	v_fma_f32 v22, v86, v49, v22
	v_fma_f32 v23, v87, v49, v23
	v_fma_f32 v20, v86, v51, v20
	v_fma_f32 v21, v87, v51, v21
	v_fma_f32 v18, v86, v53, v18
	v_fma_f32 v19, v87, v53, v19
	v_fma_f32 v16, v86, v55, v16
	v_fma_f32 v17, v87, v55, v17
	v_add_u32_e32 v40, 0x1038, v35
	v_add_u32_e32 v42, 0x2038, v35
	v_add_u32_e32 v44, 0x3038, v35
	v_add_u32_e32 v46, 0x4038, v35
	v_add_u32_e32 v48, 0x5038, v35
	v_add_u32_e32 v50, 0x6038, v35
	v_add_u32_e32 v52, 0x7038, v35
	v_add_u32_e32 v54, 0x8038, v35
	ds_read2_b32 v[38:39], v35 offset0:14 offset1:15
	ds_read2_b32 v[40:41], v40 offset1:1
	ds_read2_b32 v[42:43], v42 offset1:1
	ds_read2_b32 v[44:45], v44 offset1:1
	ds_read2_b32 v[46:47], v46 offset1:1
	ds_read2_b32 v[48:49], v48 offset1:1
	ds_read2_b32 v[50:51], v50 offset1:1
	ds_read2_b32 v[52:53], v52 offset1:1
	ds_read2_b32 v[54:55], v54 offset1:1
	v_add_u32_e32 v35, 64, v35
	s_waitcnt vmcnt(1) lgkmcnt(8)
	v_fma_f32 v32, v88, v38, v32
	v_fma_f32 v33, v89, v38, v33
	s_waitcnt lgkmcnt(7)
	v_fma_f32 v30, v88, v40, v30
	v_fma_f32 v31, v89, v40, v31
	s_waitcnt lgkmcnt(6)
	v_fma_f32 v28, v88, v42, v28
	v_fma_f32 v29, v89, v42, v29
	s_waitcnt lgkmcnt(5)
	v_fma_f32 v26, v88, v44, v26
	v_fma_f32 v27, v89, v44, v27
	s_waitcnt lgkmcnt(4)
	v_fma_f32 v24, v88, v46, v24
	v_fma_f32 v25, v89, v46, v25
	s_waitcnt lgkmcnt(3)
	v_fma_f32 v22, v88, v48, v22
	v_fma_f32 v23, v89, v48, v23
	s_waitcnt lgkmcnt(2)
	v_fma_f32 v20, v88, v50, v20
	v_fma_f32 v21, v89, v50, v21
	s_waitcnt lgkmcnt(1)
	v_fma_f32 v18, v88, v52, v18
	v_fma_f32 v19, v89, v52, v19
	s_waitcnt lgkmcnt(0)
	v_fma_f32 v16, v88, v54, v16
	v_fma_f32 v17, v89, v54, v17
	s_waitcnt vmcnt(0)
	v_fma_f32 v32, v90, v39, v32
	v_fma_f32 v33, v91, v39, v33
	v_fma_f32 v30, v90, v41, v30
	v_fma_f32 v31, v91, v41, v31
	v_fma_f32 v28, v90, v43, v28
	v_fma_f32 v29, v91, v43, v29
	v_fma_f32 v26, v90, v45, v26
	v_fma_f32 v27, v91, v45, v27
	v_fma_f32 v24, v90, v47, v24
	v_fma_f32 v25, v91, v47, v25
	v_fma_f32 v22, v90, v49, v22
	v_fma_f32 v23, v91, v49, v23
	v_fma_f32 v20, v90, v51, v20
	v_fma_f32 v21, v91, v51, v21
	v_fma_f32 v18, v90, v53, v18
	v_fma_f32 v19, v91, v53, v19
	v_fma_f32 v16, v90, v55, v16
	v_fma_f32 v17, v91, v55, v17
	ds_write2st64_b64 v7, v[32:33], v[30:31] offset0:72 offset1:73
	ds_write2st64_b64 v7, v[28:29], v[26:27] offset0:74 offset1:75
	ds_write2st64_b64 v7, v[24:25], v[22:23] offset0:76 offset1:77
	ds_write2st64_b64 v7, v[20:21], v[18:19] offset0:78 offset1:79
	ds_write_b64 v7, v[16:17] offset:40960
	s_waitcnt lgkmcnt(0)
	s_barrier
	s_and_saveexec_b64 s[6:7], vcc
	s_cbranch_execz .LBB0_48
	s_load_dwordx2 s[0:1], s[76:77], 0x38
	s_mul_i32 s10, s4, 0x6000
	s_mul_hi_i32 s8, s4, 0x6000
	s_mul_hi_i32 s15, s4, 9
	s_mul_i32 s14, s4, 9
	s_waitcnt lgkmcnt(0)
	s_add_u32 s0, s0, s10
	s_addc_u32 s1, s1, s8
	s_add_u32 s0, s0, s2
	s_addc_u32 s1, s1, s3
	v_lshl_add_u64 v[12:13], s[0:1], 0, v[0:1]
	v_lshl_add_u64 v[14:15], v[8:9], 0, s[2:3]
	s_mov_b64 s[2:3], 0
	v_mov_b32_e32 v16, v200

.LBB0_192:
	v_lshl_add_u64 v[22:23], v[16:17], 0, s[2:3]
	v_add_co_u32_e64 v28, s[40:41], s33, v22
	global_load_dword v24, v[22:23], off
	global_load_dword v26, v[22:23], off offset:2048
	v_addc_co_u32_e64 v29, s[40:41], 0, v23, s[40:41]
	v_add_co_u32_e64 v30, s[40:41], s97, v22
	v_mov_b32_e32 v3, s6
	s_nop 0
	v_addc_co_u32_e64 v31, s[40:41], 0, v23, s[40:41]
	v_add_co_u32_e64 v32, s[40:41], s39, v22
	s_add_u32 s2, s2, 0x8000
	s_nop 0
	v_addc_co_u32_e64 v33, s[40:41], 0, v23, s[40:41]
	v_add_co_u32_e64 v34, s[40:41], s9, v22
	s_addc_u32 s3, s3, 0
	s_nop 0
	v_addc_co_u32_e64 v35, s[40:41], 0, v23, s[40:41]
	v_add_co_u32_e64 v36, s[40:41], s31, v22
	s_add_i32 s6, s6, 32
	s_nop 0
	v_addc_co_u32_e64 v37, s[40:41], 0, v23, s[40:41]
	v_add_co_u32_e64 v38, s[40:41], s57, v22
	s_cmp_eq_u32 s2, 0x80000
	s_nop 0
	v_addc_co_u32_e64 v39, s[40:41], 0, v23, s[40:41]
	v_add_co_u32_e64 v22, s[40:41], s91, v22
	s_nop 1
	v_addc_co_u32_e64 v23, s[40:41], 0, v23, s[40:41]
	global_load_dword v40, v[30:31], off offset:-4096
	s_nop 0
	global_load_dword v28, v[28:29], off offset:2048
	s_nop 0
	global_load_dword v42, v[30:31], off
	s_nop 0
	global_load_dword v30, v[30:31], off offset:2048
	s_nop 0
	global_load_dword v44, v[34:35], off offset:-4096
	s_nop 0
	global_load_dword v32, v[32:33], off offset:2048
	s_nop 0
	global_load_dword v46, v[34:35], off
	s_nop 0
	global_load_dword v34, v[34:35], off offset:2048
	s_nop 0
	global_load_dword v48, v[38:39], off offset:-4096
	s_nop 0
	global_load_dword v36, v[36:37], off offset:2048
	s_nop 0
	global_load_dword v50, v[38:39], off
	s_nop 0
	global_load_dword v38, v[38:39], off offset:2048
	s_nop 0
	global_load_dword v52, v[22:23], off
	s_nop 0
	global_load_dword v22, v[22:23], off offset:2048
	ds_read2_b32 v[54:55], v3 offset1:1
	ds_read2_b32 v[56:57], v3 offset0:2 offset1:3
	ds_read2_b32 v[58:59], v3 offset0:4 offset1:5
	ds_read2_b32 v[60:61], v3 offset0:6 offset1:7
	ds_read2_b32 v[62:63], v3 offset0:128 offset1:129
	ds_read2_b32 v[64:65], v3 offset0:130 offset1:131
	ds_read2_b32 v[66:67], v3 offset0:132 offset1:133
	ds_read2_b32 v[68:69], v3 offset0:134 offset1:135
	s_waitcnt lgkmcnt(7)
	v_mov_b32_e32 v70, v54
	s_waitcnt lgkmcnt(3)
	v_mov_b32_e32 v71, v62
	v_mov_b32_e32 v62, v55
	v_mov_b32_e32 v54, v56
	s_waitcnt lgkmcnt(2)
	v_mov_b32_e32 v55, v64
	v_mov_b32_e32 v64, v57
	v_mov_b32_e32 v56, v58
	s_waitcnt lgkmcnt(1)
	v_mov_b32_e32 v57, v66
	v_mov_b32_e32 v66, v59
	v_mov_b32_e32 v58, v60
	s_waitcnt lgkmcnt(0)
	v_mov_b32_e32 v59, v68
	v_mov_b32_e32 v68, v61
	s_waitcnt vmcnt(15)
	v_fma_f32 v20, v24, v70, v20
	v_fma_f32 v21, v24, v71, v21
	s_waitcnt vmcnt(14)
	v_fma_f32 v18, v26, v70, v18
	v_fma_f32 v19, v26, v71, v19
	s_waitcnt vmcnt(13)
	v_fma_f32 v20, v40, v62, v20
	v_fma_f32 v21, v40, v63, v21
	s_waitcnt vmcnt(12)
	v_fma_f32 v18, v28, v62, v18
	v_fma_f32 v19, v28, v63, v19
	s_waitcnt vmcnt(11)
	v_fma_f32 v20, v42, v54, v20
	v_fma_f32 v21, v42, v55, v21
	s_waitcnt vmcnt(10)
	v_fma_f32 v18, v30, v54, v18
	v_fma_f32 v19, v30, v55, v19
	s_waitcnt vmcnt(9)
	v_fma_f32 v20, v44, v64, v20
	v_fma_f32 v21, v44, v65, v21
	s_waitcnt vmcnt(8)
	v_fma_f32 v18, v32, v64, v18
	v_fma_f32 v19, v32, v65, v19
	s_waitcnt vmcnt(7)
	v_fma_f32 v20, v46, v56, v20
	v_fma_f32 v21, v46, v57, v21
	s_waitcnt vmcnt(6)
	v_fma_f32 v18, v34, v56, v18
	v_fma_f32 v19, v34, v57, v19
	s_waitcnt vmcnt(5)
	v_fma_f32 v20, v48, v66, v20
	v_fma_f32 v21, v48, v67, v21
	s_waitcnt vmcnt(4)
	v_fma_f32 v18, v36, v66, v18
	v_fma_f32 v19, v36, v67, v19
	s_waitcnt vmcnt(3)
	v_fma_f32 v20, v50, v58, v20
	v_fma_f32 v21, v50, v59, v21
	s_waitcnt vmcnt(2)
	v_fma_f32 v18, v38, v58, v18
	v_fma_f32 v19, v38, v59, v19
	s_waitcnt vmcnt(1)
	v_fma_f32 v20, v52, v68, v20
	v_fma_f32 v21, v52, v69, v21
	s_waitcnt vmcnt(0)
	v_fma_f32 v18, v22, v68, v18
	v_fma_f32 v19, v22, v69, v19
	s_cbranch_scc0 .LBB0_192
	v_lshlrev_b64 v[14:15], 1, v[14:15]
	v_lshl_add_u64 v[16:17], v[10:11], 0, v[14:15]
	s_lshl_b32 s86, s86, 1
	v_cvt_pk_bf16_f32 v3, v20, v21
	v_lshl_add_u64 v[16:17], v[16:17], 0, s[86:87]
	v_lshl_add_u64 v[14:15], v[12:13], 0, v[14:15]
	s_add_i32 s4, s4, s5
	global_store_dword v[16:17], v3, off offset:1024
	v_cvt_pk_bf16_f32 v3, v18, v19
	v_lshl_add_u64 v[14:15], v[14:15], 0, s[86:87]
	s_cmpk_gt_i32 s4, 0xff
	global_store_dword v[14:15], v3, off offset:1024
	s_cbranch_scc0 .LBB0_187
	v_readlane_b32 s0, v254, 1
	s_mov_b32 s4, s0
	v_readlane_b32 s1, v254, 2

.LBB0_197:
	v_ashrrev_i32_e32 v10, 10, v7
	v_mul_lo_u32 v9, v10, v3
	v_add_u32_e32 v12, v9, v10
	v_and_b32_e32 v9, 0x7fe, v9
	v_and_b32_e32 v12, 0x7ff, v12
	v_cvt_f32_u32_e32 v14, v9
	v_cvt_f32_u32_e32 v15, v12
	v_ashrrev_i32_e32 v11, 31, v10
	v_and_b32_e32 v0, 0x7fe, v3
	v_lshlrev_b64 v[10:11], 13, v[10:11]
	v_add_u32_e32 v7, s2, v7
	v_lshlrev_b32_e32 v0, 1, v0
	s_mov_b32 s0, 0x1fffff
	v_lshl_add_u64 v[10:11], s[14:15], 0, v[10:11]
	v_cmp_lt_i32_e32 vcc, s0, v7
	v_lshl_add_u64 v[10:11], v[10:11], 0, v[0:1]
	v_mul_f32_e32 v14, s18, v14
	v_mul_f32_e32 v15, s18, v15
	s_or_b64 s[16:17], vcc, s[16:17]
	v_add_co_u32_e32 v12, vcc, 0x1000, v10
	v_mul_f32_e32 v16, 0.5, v14
	v_mul_f32_e32 v17, 0.5, v15
	s_nop 0
	v_addc_co_u32_e32 v13, vcc, 0, v11, vcc
	v_fract_f32_e32 v18, v16
	v_fract_f32_e32 v19, v17
	v_add_f32_e32 v18, v18, v18
	v_add_f32_e32 v19, v19, v19
	v_cmp_neq_f32_e32 vcc, s27, v17
	v_cmp_neq_f32_e64 s[40:41], s27, v16
	s_mov_b32 s0, 0x3b3504f3
	v_cndmask_b32_e32 v9, 0, v19, vcc
	v_cndmask_b32_e64 v0, 0, v18, s[40:41]
	v_cmp_lt_f32_e32 vcc, 1.0, v14
	v_cmp_lt_f32_e64 s[40:41], 1.0, v15
	v_add_u32_e32 v3, s3, v3
	v_cndmask_b32_e32 v16, v14, v0, vcc
	v_cndmask_b32_e64 v17, v15, v9, s[40:41]
	v_add_f32_e32 v0, v16, v16
	v_add_f32_e32 v9, v17, v17
	v_rndne_f32_e32 v18, v0
	v_rndne_f32_e32 v19, v9
	v_fma_f32 v16, v18, -0.5, v16
	v_fma_f32 v17, v19, -0.5, v17
	v_cvt_i32_f32_e32 v0, v19
	v_cvt_i32_f32_e32 v9, v18
	v_mul_f32_e32 v18, v16, v16
	v_mul_f32_e32 v19, v17, v17
	v_and_b32_e32 v26, 1, v0
	v_fma_f32 v20, v18, s74, v190
	v_fma_f32 v21, v19, s74, v190
	v_fma_f32 v24, v18, s92, v192
	v_fma_f32 v25, v19, s92, v192
	v_fma_f32 v20, v18, v20, s94
	v_fma_f32 v21, v19, v21, s94
	v_fma_f32 v24, v18, v24, s20
	v_fma_f32 v25, v19, v25, s20
	v_mul_f32_e32 v22, v16, v18
	v_mul_f32_e32 v23, v17, v19
	v_fma_f32 v20, v18, v20, s80
	v_fma_f32 v21, v19, v21, s80
	v_fma_f32 v24, v18, v24, s36
	v_fma_f32 v25, v19, v25, s36
	v_and_b32_e32 v27, 1, v9
	v_mul_f32_e32 v20, v22, v20
	v_mul_f32_e32 v21, v23, v21
	v_fma_f32 v22, v18, v24, s38
	v_fma_f32 v23, v19, v25, s38
	v_lshlrev_b32_e32 v0, 30, v0
	v_lshlrev_b32_e32 v9, 30, v9
	v_fma_f32 v16, v16, s72, v20
	v_fma_f32 v17, v17, s72, v21
	v_fma_f32 v18, v18, v22, 1.0
	v_fma_f32 v19, v19, v23, 1.0
	v_cmp_eq_u32_e32 vcc, 0, v27
	v_cmp_eq_u32_e64 s[40:41], 0, v26
	v_and_b32_e32 v0, 0x80000000, v0
	v_and_b32_e32 v9, 0x80000000, v9
	v_cndmask_b32_e64 v20, -v17, v19, s[40:41]
	v_cndmask_b32_e64 v21, -v16, v18, vcc
	v_cndmask_b32_e64 v19, v19, v17, s[40:41]
	v_cndmask_b32_e32 v18, v18, v16, vcc
	v_xor_b32_e32 v17, v0, v20
	v_xor_b32_e32 v16, v9, v21
	v_xor_b32_e32 v19, v0, v19
	v_xor_b32_e32 v18, v9, v18
	v_mul_f32_e32 v16, s0, v16
	v_mul_f32_e32 v17, s0, v17
	v_cmp_lg_f32_e32 vcc, s27, v14
	s_mov_b32 s0, 0xbb3504f3
	v_cmp_lg_f32_e64 s[40:41], s27, v15
	v_mul_f32_e32 v18, s0, v18
	v_mul_f32_e32 v19, s0, v19
	v_cndmask_b32_e32 v9, v230, v16, vcc
	v_cndmask_b32_e64 v0, v230, v17, s[40:41]
	v_cndmask_b32_e64 v14, v230, v19, s[40:41]
	v_cndmask_b32_e32 v15, v230, v18, vcc
	v_cvt_pk_bf16_f32 v0, v9, v0
	v_cvt_pk_bf16_f32 v9, v15, v14
	global_store_dword v[10:11], v0, off
	global_store_dword v[12:13], v9, off
	s_andn2_b64 exec, exec, s[16:17]
	s_cbranch_execnz .LBB0_197

.LBB0_200:
	v_ashrrev_i32_e32 v10, 7, v5
	v_mul_lo_u32 v7, v10, v3
	v_add_u32_e32 v9, v7, v10
	v_and_b32_e32 v7, 0xfe, v7
	v_cvt_f32_ubyte0_e32 v13, v9
	v_cvt_f32_ubyte0_e32 v12, v7
	v_mul_f32_e32 v12, s64, v12
	v_mul_f32_e32 v13, s64, v13
	v_add_u32_e32 v5, s2, v5
	v_ashrrev_i32_e32 v11, 31, v10
	s_movk_i32 s0, 0x7fff
	v_mul_f32_e32 v14, 0.5, v12
	v_mul_f32_e32 v15, 0.5, v13
	v_and_b32_e32 v0, 0xfe, v3
	v_cmp_lt_i32_e32 vcc, s0, v5
	v_lshlrev_b64 v[10:11], 10, v[10:11]
	v_fract_f32_e32 v16, v14
	v_fract_f32_e32 v17, v15
	v_lshlrev_b32_e32 v0, 1, v0
	s_or_b64 s[16:17], vcc, s[16:17]
	v_lshl_add_u64 v[10:11], s[14:15], 0, v[10:11]
	v_add_f32_e32 v16, v16, v16
	v_add_f32_e32 v17, v17, v17
	v_cmp_neq_f32_e32 vcc, s27, v15
	v_cmp_neq_f32_e64 s[40:41], s27, v14
	v_lshl_add_u64 v[10:11], v[10:11], 0, v[0:1]
	v_cndmask_b32_e32 v7, 0, v17, vcc
	v_cndmask_b32_e64 v0, 0, v16, s[40:41]
	v_cmp_lt_f32_e32 vcc, 1.0, v12
	v_cmp_lt_f32_e64 s[40:41], 1.0, v13
	s_brev_b32 s0, 61
	v_cndmask_b32_e32 v14, v12, v0, vcc
	v_cndmask_b32_e64 v15, v13, v7, s[40:41]
	v_add_f32_e32 v0, v14, v14
	v_add_f32_e32 v7, v15, v15
	v_rndne_f32_e32 v16, v0
	v_rndne_f32_e32 v17, v7
	v_fma_f32 v14, v16, -0.5, v14
	v_fma_f32 v15, v17, -0.5, v15
	v_cvt_i32_f32_e32 v0, v17
	v_cvt_i32_f32_e32 v7, v16
	v_mul_f32_e32 v16, v14, v14
	v_mul_f32_e32 v17, v15, v15
	v_add_u32_e32 v3, s3, v3
	v_fma_f32 v18, v16, s74, v190
	v_fma_f32 v19, v17, s74, v190
	v_fma_f32 v22, v16, s92, v192
	v_fma_f32 v23, v17, s92, v192
	v_fma_f32 v18, v16, v18, s94
	v_fma_f32 v19, v17, v19, s94
	v_fma_f32 v22, v16, v22, s4
	v_fma_f32 v23, v17, v23, s4
	v_mul_f32_e32 v20, v14, v16
	v_mul_f32_e32 v21, v15, v17
	v_fma_f32 v18, v16, v18, s80
	v_fma_f32 v19, v17, v19, s80
	v_fma_f32 v22, v16, v22, s18
	v_fma_f32 v23, v17, v23, s18
	v_and_b32_e32 v9, 1, v0
	v_and_b32_e32 v24, 1, v7
	v_mul_f32_e32 v18, v20, v18
	v_mul_f32_e32 v19, v21, v19
	v_fma_f32 v20, v16, v22, s20
	v_fma_f32 v21, v17, v23, s20
	v_lshlrev_b32_e32 v0, 30, v0
	v_lshlrev_b32_e32 v7, 30, v7
	v_fma_f32 v14, v14, s72, v18
	v_fma_f32 v15, v15, s72, v19
	v_fma_f32 v16, v16, v20, 1.0
	v_fma_f32 v17, v17, v21, 1.0
	v_cmp_eq_u32_e32 vcc, 0, v24
	v_cmp_eq_u32_e64 s[40:41], 0, v9
	v_and_b32_e32 v0, 0x80000000, v0
	v_and_b32_e32 v7, 0x80000000, v7
	v_cndmask_b32_e64 v9, -v15, v17, s[40:41]
	v_cndmask_b32_e64 v18, -v14, v16, vcc
	v_cndmask_b32_e64 v17, v17, v15, s[40:41]
	v_cndmask_b32_e32 v16, v16, v14, vcc
	v_xor_b32_e32 v15, v0, v9
	v_xor_b32_e32 v14, v7, v18
	v_xor_b32_e32 v17, v0, v17
	v_xor_b32_e32 v16, v7, v16
	v_mul_f32_e32 v14, s64, v14
	v_mul_f32_e32 v15, s64, v15
	v_cmp_lg_f32_e32 vcc, s27, v12
	v_cmp_lg_f32_e64 s[40:41], s27, v13
	v_mul_f32_e32 v16, s0, v16
	v_mul_f32_e32 v17, s0, v17
	v_cndmask_b32_e32 v7, v230, v14, vcc
	v_cndmask_b32_e64 v0, v230, v15, s[40:41]
	v_cndmask_b32_e64 v9, v230, v17, s[40:41]
	v_cndmask_b32_e32 v12, v230, v16, vcc
	v_cvt_pk_bf16_f32 v0, v7, v0
	v_cvt_pk_bf16_f32 v7, v12, v9
	global_store_dword v[10:11], v0, off
	global_store_dword v[10:11], v7, off offset:512
	s_andn2_b64 exec, exec, s[16:17]
	s_cbranch_execnz .LBB0_200
.LBB0_201:
	s_or_b64 exec, exec, s[6:7]
	s_mov_b32 s0, 0x10000
	v_cmp_gt_i32_e32 vcc, s0, v6
	s_and_saveexec_b64 s[6:7], vcc
	s_cbranch_execz .LBB0_212
	v_and_b32_e32 v0, 15, v200
	v_cvt_f32_ubyte0_e32 v0, v0
	v_mul_f32_e32 v0, 0x3d800000, v0
	v_cmp_eq_f32_e32 vcc, 0, v0
	v_mov_b32_e32 v3, 0x461c4000
	s_mov_b32 s0, 0x3f2aaaab
	v_cndmask_b32_e64 v3, v3, 1.0, vcc
	v_frexp_mant_f32_e32 v5, v3
	v_cmp_gt_f32_e32 vcc, s0, v5
	s_mov_b32 s0, 0x3f317218
	s_movk_i32 s1, 0x204
	v_cndmask_b32_e64 v7, 1.0, 2.0, vcc
	v_mul_f32_e32 v5, v5, v7
	v_add_f32_e32 v7, 1.0, v5
	v_rcp_f32_e32 v9, v7
	v_add_f32_e32 v10, -1.0, v7
	v_add_f32_e32 v11, -1.0, v5
	v_sub_f32_e32 v10, v5, v10
	v_mul_f32_e32 v5, v11, v9
	v_mul_f32_e32 v12, v7, v5
	v_fma_f32 v14, v5, v7, -v12
	v_fmac_f32_e32 v14, v5, v10
	v_add_f32_e32 v10, v12, v14
	v_sub_f32_e32 v13, v11, v10
	v_add_f32_e64 v16, v10, -v12
	v_add_f32_e64 v17, v11, -v13
	v_mov_b32_e32 v15, v10
	v_add_f32_e64 v10, v16, -v14
	v_add_f32_e64 v11, v17, -v15
	s_mov_b32 s3, 0x42b17218
	v_add_f32_e32 v7, v10, v11
	v_add_f32_e32 v7, v13, v7
	v_mul_f32_e32 v7, v9, v7
	v_add_f32_e32 v10, v5, v7
	v_sub_f32_e32 v5, v10, v5
	v_sub_f32_e32 v5, v7, v5
	v_mul_f32_e32 v7, v10, v10
	v_fma_f32 v9, v10, v10, -v7
	v_add_f32_e32 v11, v5, v5
	v_fmac_f32_e32 v9, v10, v11
	v_add_f32_e32 v12, v7, v9
	v_mov_b32_e32 v11, 0x3e91f4c4
	v_fmamk_f32 v11, v12, 0x3e76c4e1, v11
	v_fmaak_f32 v11, v12, v11, 0x3ecccdef
	v_sub_f32_e32 v7, v12, v7
	v_sub_f32_e32 v7, v9, v7
	v_mul_f32_e32 v9, v12, v11
	v_fma_f32 v13, v12, v11, -v9
	v_fmac_f32_e32 v13, v7, v11
	v_add_f32_e32 v14, v9, v13
	v_sub_f32_e32 v9, v14, v9
	v_add_f32_e32 v15, 0x3f2aaaaa, v14
	v_sub_f32_e32 v9, v13, v9
	v_add_f32_e32 v11, 0x31739010, v9
	v_add_f32_e32 v9, 0xbf2aaaaa, v15
	v_sub_f32_e32 v13, v14, v9
	v_mul_f32_e32 v16, v10, v12
	v_mul_f32_e32 v17, v11, v13
	v_add_f32_e32 v18, v10, v12
	v_add_f32_e32 v19, v11, v13
	v_fma_f32 v14, v12, v10, -v16
	v_fmac_f32_e32 v14, v12, v5
	v_mov_b32_e32 v17, v19
	v_fmac_f32_e32 v14, v7, v10
	v_add_f32_e32 v12, v16, v14
	v_add_f32_e32 v13, v17, v15
	s_add_u32 s14, s12, 0x14a00000
	v_sub_f32_e32 v7, v12, v16
	v_cvt_f64_f32_e32 v[16:17], v3
	v_frexp_exp_i32_f64_e32 v3, v[16:17]
	v_subbrev_co_u32_e32 v3, vcc, 0, v3, vcc
	v_cvt_f32_i32_e32 v3, v3
	v_sub_f32_e32 v7, v14, v7
	v_sub_f32_e32 v9, v15, v13
	v_mul_f32_e32 v14, v12, v13
	v_mul_f32_e32 v15, v13, v12
	v_add_f32_e32 v9, v19, v9
	v_fma_f32 v16, v12, v13, -v14
	v_fmac_f32_e32 v16, v12, v9
	v_mul_f32_e32 v12, 0x3f317218, v3
	v_fmac_f32_e32 v16, v7, v13
	v_fma_f32 v18, v3, s0, -v12
	v_fmac_f32_e32 v18, 0xb102e308, v3
	v_ldexp_f32 v19, v10, 1
	v_add_f32_e32 v13, v14, v16
	v_add_f32_e32 v10, v12, v18
	v_add_f32_e32 v11, v13, v19
	v_mov_b32_e32 v20, v13
	v_mov_b32_e32 v21, v11
	v_mov_b32_e32 v15, v19
	v_add_f32_e64 v14, v20, -v14
	v_add_f32_e64 v15, v21, -v15
	v_mov_b32_e32 v17, v13
	v_ldexp_f32 v3, v5, 1
	v_add_f32_e64 v14, v16, -v14
	v_add_f32_e64 v15, v17, -v15
	v_mov_b32_e32 v19, v10
	v_add_f32_e32 v3, v3, v14
	v_add_f32_e32 v13, v3, v15
	v_add_f32_e64 v14, v10, -v12
	v_add_f32_e64 v15, v11, -v13
	v_add_f32_e32 v16, v10, v12
	v_add_f32_e32 v17, v11, v13
	v_mov_b32_e32 v12, v13
	v_mov_b32_e32 v15, v17
	v_add_f32_e64 v20, v18, -v14
	v_add_f32_e64 v21, v19, -v15
	v_add_f32_e32 v14, v18, v14
	v_add_f32_e32 v15, v19, v15
	v_mov_b32_e32 v13, v10
	v_add_f32_e64 v18, v15, -v10
	v_add_f32_e64 v19, v14, -v11
	v_add_f32_e64 v22, v16, -v18
	v_add_f32_e64 v23, v17, -v18
	v_mov_b32_e32 v16, v17
	v_mov_b32_e32 v17, v15
	v_pk_mov_b32 v[18:19], v[10:11], v[18:19] op_sel:[1,0]
	v_mov_b32_e32 v22, v20
	v_add_f32_e64 v16, v16, -v18
	v_add_f32_e64 v17, v17, -v19
	v_mov_b32_e32 v21, v15
	v_add_f32_e64 v10, v12, -v16
	v_add_f32_e64 v11, v13, -v17
	s_mov_b32 s0, 0x3fb8aa3b
	v_add_f32_e32 v12, v22, v10
	v_add_f32_e32 v13, v23, v11
	s_addc_u32 s15, s13, 0
	v_add_f32_e32 v16, v12, v13
	v_add_f32_e32 v17, v13, v12
	s_mov_b64 s[16:17], 0
	v_pk_add_f32 v[14:15], v[14:15], v[16:17] op_sel:[1,0] op_sel_hi:[0,1]
	v_mov_b32_e32 v13, v14
	v_add_f32_e64 v18, v12, -v20
	v_add_f32_e64 v19, v13, -v21
	v_mov_b32_e32 v11, v16
	v_sub_f32_e32 v3, v12, v18
	v_add_f32_e64 v10, v10, -v18
	v_add_f32_e64 v11, v11, -v19
	v_sub_f32_e32 v3, v20, v3
	v_add_f32_e32 v3, v10, v3
	v_add_f32_e32 v3, v3, v11
	v_add_f32_e32 v5, v14, v3
	v_sub_f32_e32 v7, v5, v14
	v_sub_f32_e32 v3, v3, v7
	v_mul_f32_e32 v7, v0, v5
	v_fma_f32 v5, v0, v5, -v7
	v_fmac_f32_e32 v5, v0, v3
	v_add_f32_e32 v3, v7, v5
	v_cmp_class_f32_e64 vcc, v7, s1
	v_sub_f32_e32 v9, v3, v7
	v_sub_f32_e32 v5, v5, v9
	v_cndmask_b32_e32 v3, v3, v7, vcc
	v_cmp_eq_f32_e32 vcc, s3, v3
	v_mov_b32_e32 v7, 0x37000000
	s_nop 0
	v_cndmask_b32_e32 v7, 0, v7, vcc
	v_sub_f32_e32 v9, v3, v7
	v_mul_f32_e32 v10, 0x3fb8aa3b, v9
	v_fma_f32 v11, v9, s0, -v10
	v_rndne_f32_e32 v12, v10
	v_fmac_f32_e32 v11, 0x32a5705f, v9
	v_sub_f32_e32 v10, v10, v12
	v_add_f32_e32 v10, v10, v11
	v_exp_f32_e32 v10, v10
	v_cvt_i32_f32_e32 v11, v12
	v_cmp_neq_f32_e64 vcc, |v3|, s27
	s_mov_b32 s0, 0xc2ce8ed0
	s_nop 0
	v_cndmask_b32_e32 v3, 0, v5, vcc
	v_ldexp_f32 v5, v10, v11
	v_cmp_ngt_f32_e32 vcc, s0, v9
	v_add_f32_e32 v3, v7, v3
	v_mov_b32_e32 v7, 0x7f800000
	v_cndmask_b32_e32 v5, 0, v5, vcc
	v_cmp_nlt_f32_e32 vcc, s3, v9
	s_lshl_b32 s3, s5, 10
	s_nop 0
	v_cndmask_b32_e32 v5, v7, v5, vcc
	v_fma_f32 v3, v5, v3, v5
	v_cmp_class_f32_e64 vcc, v5, s1
	s_nop 1
	v_cndmask_b32_e32 v3, v3, v5, vcc
	v_and_b32_e32 v5, 0x7fffffff, v3
	v_div_scale_f32 v7, s[0:1], v5, v5, 1.0
	v_rcp_f32_e32 v9, v7
	v_div_scale_f32 v5, vcc, 1.0, v5, 1.0
	v_fma_f32 v10, -v7, v9, 1.0
	v_fmac_f32_e32 v9, v10, v9
	v_mul_f32_e32 v10, v5, v9
	v_fma_f32 v11, -v7, v10, v5
	v_fmac_f32_e32 v10, v11, v9
	v_fma_f32 v5, -v7, v10, v5
	v_div_fmas_f32 v5, v5, v9, v10
	v_div_fixup_f32 v3, v5, |v3|, 1.0
	v_cmp_neq_f32_e32 vcc, s27, v0
	v_mov_b32_e32 v5, v6
	s_nop 0
	v_cndmask_b32_e32 v3, 0, v3, vcc
	s_branch .LBB0_204

.LBB0_216:
	s_or_b64 exec, exec, s[34:35]
	s_and_b64 s[0:1], exec, vcc
	s_or_b64 s[20:21], s[0:1], s[20:21]
	s_waitcnt lgkmcnt(0)
	v_add_f32_e32 v102, v102, v104
	v_add_f32_e32 v103, v103, v105
	s_mov_b32 s0, 0x3a800000
	v_mul_f32_e32 v102, s0, v102
	v_mul_f32_e32 v103, s0, v103
	s_mov_b32 s0, 0x5000000
	v_fma_f32 v0, -v103, v103, v102
	v_max_f32_e32 v0, 0, v0
	v_add_f32_e32 v0, 0x358637bd, v0
	v_cmp_gt_f32_e32 vcc, s58, v0
	v_mul_f32_e32 v102, 0x4b800000, v0
	v_sub_f32_e32 v75, v75, v103
	v_cndmask_b32_e32 v0, v0, v102, vcc
	v_rsq_f32_e32 v0, v0
	v_sub_f32_e32 v74, v74, v103
	v_sub_f32_e32 v81, v81, v103
	v_sub_f32_e32 v80, v80, v103
	v_mul_f32_e32 v102, 0x45800000, v0
	v_cndmask_b32_e32 v0, v0, v102, vcc
	v_mul_f32_e32 v74, v74, v0
	v_mul_f32_e32 v75, v75, v0
	v_sub_f32_e32 v77, v77, v103
	s_waitcnt vmcnt(3)
	v_fma_f32 v104, v74, v58, v42
	v_fma_f32 v105, v75, v59, v43
	v_sub_f32_e32 v75, v97, v103
	v_sub_f32_e32 v74, v96, v103
	v_sub_f32_e32 v76, v76, v103
	v_mul_f32_e32 v74, v74, v0
	v_mul_f32_e32 v75, v75, v0
	v_sub_f32_e32 v101, v101, v103
	v_sub_f32_e32 v100, v100, v103
	v_mul_f32_e32 v80, v80, v0
	v_mul_f32_e32 v81, v81, v0
	v_sub_f32_e32 v95, v95, v103
	v_sub_f32_e32 v94, v94, v103
	v_mul_f32_e32 v76, v76, v0
	v_mul_f32_e32 v77, v77, v0
	s_waitcnt vmcnt(0)
	v_fma_f32 v96, v74, v68, v64
	v_fma_f32 v97, v75, v69, v65
	v_sub_f32_e32 v75, v99, v103
	v_sub_f32_e32 v74, v98, v103
	v_mul_f32_e32 v100, v100, v0
	v_mul_f32_e32 v101, v101, v0
	v_fma_f32 v80, v80, v54, v46
	v_fma_f32 v81, v81, v55, v47
	v_mul_f32_e32 v94, v94, v0
	v_mul_f32_e32 v95, v95, v0
	v_fma_f32 v106, v76, v66, v62
	v_fma_f32 v107, v77, v67, v63
	v_sub_f32_e32 v77, v79, v103
	v_sub_f32_e32 v76, v78, v103
	v_mul_f32_e32 v74, v74, v0
	v_mul_f32_e32 v75, v75, v0
	v_fma_f32 v100, v100, v56, v48
	v_fma_f32 v101, v101, v57, v49
	v_fma_f32 v94, v94, v60, v44
	v_fma_f32 v95, v95, v61, v45
	v_mul_f32_e32 v76, v76, v0
	v_mul_f32_e32 v77, v77, v0
	v_fma_f32 v78, v74, v72, v52
	v_fma_f32 v79, v75, v73, v53
	v_cvt_pk_bf16_f32 v74, v80, v81
	v_add_co_u32_e32 v80, vcc, s0, v92
	v_fma_f32 v98, v76, v70, v50
	v_fma_f32 v99, v77, v71, v51
	v_cvt_pk_bf16_f32 v75, v100, v101
	v_cvt_pk_bf16_f32 v76, v104, v105
	v_cvt_pk_bf16_f32 v77, v94, v95
	v_addc_co_u32_e32 v81, vcc, 0, v93, vcc
	global_store_dwordx4 v[80:81], v[74:77], off
	s_mov_b64 s[0:1], 0x800
	v_lshl_add_u64 v[88:89], v[88:89], 0, 8
	v_cvt_pk_bf16_f32 v74, v106, v107
	v_cvt_pk_bf16_f32 v75, v96, v97
	v_cvt_pk_bf16_f32 v76, v98, v99
	v_cvt_pk_bf16_f32 v77, v78, v79
	global_store_dwordx4 v[80:81], v[74:77], off offset:1024
	v_mov_b64_e32 v[80:81], v[36:37]
	v_lshl_add_u64 v[90:91], v[90:91], 0, s[0:1]
	v_mov_b64_e32 v[76:77], v[40:41]
	v_mov_b64_e32 v[74:75], v[38:39]
	v_mov_b64_e32 v[78:79], v[34:35]
	v_mov_b32_e32 v119, v83
	s_andn2_b64 exec, exec, s[20:21]
	s_cbranch_execz .LBB0_223

.LBB0_219:
	s_or_b64 exec, exec, s[34:35]
	v_lshlrev_b32_e32 v100, 16, v78
	v_and_b32_e32 v101, 0xffff0000, v78
	v_lshlrev_b32_e32 v120, 16, v79
	v_and_b32_e32 v94, 0xffff0000, v79
	v_lshlrev_b32_e32 v79, 16, v76
	v_and_b32_e32 v98, 0xffff0000, v76
	v_add_f32_e32 v0, 0, v100
	v_mul_f32_e32 v76, v101, v101
	v_lshlrev_b32_e32 v95, 16, v80
	v_add_f32_e32 v0, v0, v101
	v_fmac_f32_e32 v76, v100, v100
	v_lshlrev_b32_e32 v96, 16, v74
	v_lshlrev_b32_e32 v105, 16, v75
	v_and_b32_e32 v104, 0xffff0000, v74
	v_and_b32_e32 v78, 0xffff0000, v75
	v_add_f32_e32 v0, v0, v120
	v_fmac_f32_e32 v76, v120, v120
	v_mul_f32_e32 v74, v94, v94
	v_mul_f32_e32 v75, v95, v95
	v_lshlrev_b32_e32 v107, 16, v81
	v_and_b32_e32 v106, 0xffff0000, v80
	v_add_f32_e32 v0, v0, v94
	v_add_f32_e32 v74, v74, v76
	v_add_f32_e32 v0, v0, v95
	v_add_f32_e32 v76, v75, v74
	v_mul_f32_e32 v74, v106, v106
	v_mul_f32_e32 v75, v107, v107
	v_and_b32_e32 v97, 0xffff0000, v81
	v_add_f32_e32 v0, v0, v106
	v_add_f32_e32 v74, v74, v76
	v_add_f32_e32 v0, v0, v107
	v_add_f32_e32 v76, v75, v74
	v_mul_f32_e32 v74, v96, v96
	v_mul_f32_e32 v75, v97, v97
	v_add_f32_e32 v0, v0, v97
	v_add_f32_e32 v75, v75, v76
	v_add_f32_e32 v0, v0, v96
	v_add_f32_e32 v76, v74, v75
	v_mul_f32_e32 v74, v104, v104
	v_mul_f32_e32 v75, v105, v105
	v_add_f32_e32 v0, v0, v104
	v_add_f32_e32 v74, v74, v76
	v_add_f32_e32 v0, v0, v105
	v_add_f32_e32 v76, v75, v74
	v_mul_f32_e32 v74, v78, v78
	v_mul_f32_e32 v75, v79, v79
	v_lshlrev_b32_e32 v99, 16, v77
	v_add_f32_e32 v0, v0, v78
	v_add_f32_e32 v74, v74, v76
	v_add_f32_e32 v0, v0, v79
	v_add_f32_e32 v76, v75, v74
	v_mul_f32_e32 v74, v98, v98
	v_mul_f32_e32 v75, v99, v99
	v_and_b32_e32 v103, 0xffff0000, v77
	v_add_f32_e32 v0, v0, v98
	v_add_f32_e32 v74, v74, v76
	v_add_f32_e32 v77, v0, v99
	v_add_f32_e32 v102, v75, v74
	v_mul_f32_e32 v76, v103, v103
	v_add_f32_e32 v74, v76, v102
	v_add_f32_e32 v75, v77, v103
	s_nop 1
	v_add_f32_dpp v74, v74, v74 quad_perm:[1,0,3,2] row_mask:0xf bank_mask:0xf
	v_add_f32_dpp v75, v75, v75 quad_perm:[1,0,3,2] row_mask:0xf bank_mask:0xf
	s_nop 0
	v_add_f32_dpp v74, v74, v74 quad_perm:[2,3,0,1] row_mask:0xf bank_mask:0xf
	v_add_f32_dpp v75, v75, v75 quad_perm:[2,3,0,1] row_mask:0xf bank_mask:0xf
	s_nop 0
	v_add_f32_dpp v74, v74, v74 row_half_mirror row_mask:0xf bank_mask:0xf
	v_add_f32_dpp v75, v75, v75 row_half_mirror row_mask:0xf bank_mask:0xf
	s_nop 0
	v_add_f32_dpp v74, v74, v74 row_mirror row_mask:0xf bank_mask:0xf
	v_add_f32_dpp v75, v75, v75 row_mirror row_mask:0xf bank_mask:0xf
	s_nop 0
	v_add_f32_dpp v74, v74, v74 row_bcast:15 row_mask:0xa bank_mask:0xf
	v_add_f32_dpp v75, v75, v75 row_bcast:15 row_mask:0xa bank_mask:0xf
	s_nop 0
	v_add_f32_dpp v74, v74, v74 row_bcast:31 row_mask:0xc bank_mask:0xf
	v_add_f32_dpp v75, v75, v75 row_bcast:31 row_mask:0xc bank_mask:0xf
	s_nop 0
	v_readlane_b32 s98, v74, 63
	v_readlane_b32 s99, v75, 63
	s_nop 1
	v_mov_b32_e32 v74, s98
	v_mov_b32_e32 v75, s99
	v_mov_b32_e32 v76, 0
	v_mov_b32_e32 v77, 0
	s_mov_b32 s0, 0x3a800000
	s_waitcnt lgkmcnt(0)
	v_add_f32_e32 v74, v74, v76
	v_add_f32_e32 v75, v75, v77
	s_nop 0
	v_mul_f32_e32 v108, s0, v74
	v_mul_f32_e32 v109, s0, v75
	s_nop 0
	v_fma_f32 v0, -v109, v109, v108
	v_max_f32_e32 v0, 0, v0
	v_add_f32_e32 v0, 0x358637bd, v0
	v_mul_f32_e32 v74, 0x4b800000, v0
	v_cmp_gt_f32_e64 s[42:43], s58, v0
	s_nop 1
	v_cndmask_b32_e64 v0, v0, v74, s[42:43]
	v_rsq_f32_e32 v0, v0
	s_nop 0
	v_mul_f32_e32 v74, 0x45800000, v0
	v_cndmask_b32_e64 v0, v0, v74, s[42:43]
	s_and_saveexec_b64 s[34:35], s[40:41]
	s_cbranch_execz .LBB0_221
	v_mov_b32_e32 v74, v109
	v_mov_b32_e32 v75, v0
	v_lshl_add_u64 v[76:77], s[12:13], 0, v[88:89]
	global_store_dwordx2 v[76:77], v[74:75], off
.LBB0_221:
	s_or_b64 exec, exec, s[34:35]
	v_sub_f32_e32 v75, v94, v109
	v_sub_f32_e32 v74, v120, v109
	v_sub_f32_e32 v77, v101, v109
	v_sub_f32_e32 v76, v100, v109
	v_mul_f32_e32 v76, v76, v0
	v_mul_f32_e32 v77, v77, v0
	v_mul_f32_e32 v74, v74, v0
	v_mul_f32_e32 v75, v75, v0
	v_fma_f32 v80, v6, v76, v14
	v_fma_f32 v81, v7, v77, v15
	v_fma_f32 v100, v8, v74, v16
	v_fma_f32 v101, v9, v75, v17
	v_sub_f32_e32 v75, v97, v109
	v_sub_f32_e32 v74, v107, v109
	v_sub_f32_e32 v77, v106, v109
	v_sub_f32_e32 v76, v95, v109
	v_mul_f32_e32 v76, v76, v0
	v_mul_f32_e32 v77, v77, v0
	v_mul_f32_e32 v74, v74, v0
	v_mul_f32_e32 v75, v75, v0
	v_sub_f32_e32 v97, v104, v109
	v_fma_f32 v94, v4, v74, v12
	v_fma_f32 v95, v5, v75, v13
	v_fma_f32 v74, v2, v76, v10
	v_fma_f32 v75, v3, v77, v11
	v_sub_f32_e32 v77, v78, v109
	v_sub_f32_e32 v76, v105, v109
	v_sub_f32_e32 v96, v96, v109
	v_mul_f32_e32 v104, v96, v0
	v_mul_f32_e32 v105, v97, v0
	v_mul_f32_e32 v76, v76, v0
	v_mul_f32_e32 v77, v77, v0
	v_sub_f32_e32 v103, v103, v109
	v_fma_f32 v96, v24, v76, v32
	v_fma_f32 v97, v25, v77, v33
	v_fma_f32 v76, v22, v104, v30
	v_fma_f32 v77, v23, v105, v31
	v_sub_f32_e32 v102, v99, v109
	v_sub_f32_e32 v99, v98, v109
	v_sub_f32_e32 v98, v79, v109
	v_mul_f32_e32 v104, v81, v81
	v_mul_f32_e32 v78, v98, v0
	v_mul_f32_e32 v79, v99, v0
	v_mul_f32_e32 v98, v102, v0
	v_mul_f32_e32 v99, v103, v0
	v_add_f32_e32 v0, 0, v80
	v_fmac_f32_e32 v104, v80, v80
	v_mov_b32_e32 v102, v74
	v_mov_b32_e32 v103, v101
	v_add_f32_e32 v0, v81, v0
	v_fmac_f32_e32 v104, v100, v100
	v_mul_f32_e32 v102, v102, v102
	v_mul_f32_e32 v103, v103, v103
	v_add_f32_e32 v0, v100, v0
	v_add_f32_e32 v103, v103, v104
	v_add_f32_e32 v0, v101, v0
	v_add_f32_e32 v106, v102, v103
	v_mul_f32_e32 v102, v94, v94
	v_mul_f32_e32 v103, v95, v95
	v_mul_f32_e32 v104, v74, v74
	v_mul_f32_e32 v105, v75, v75
	v_add_f32_e32 v0, v74, v0
	v_add_f32_e32 v103, v105, v106
	v_add_f32_e32 v0, v75, v0
	v_add_f32_e32 v104, v102, v103
	v_mov_b32_e32 v102, v76
	v_mov_b32_e32 v103, v95
	v_add_f32_e32 v0, v94, v0
	v_mul_f32_e32 v102, v102, v102
	v_mul_f32_e32 v103, v103, v103
	v_add_f32_e32 v0, v95, v0
	v_add_f32_e32 v103, v103, v104
	v_add_f32_e32 v0, v76, v0
	v_add_f32_e32 v106, v102, v103
	v_mul_f32_e32 v102, v96, v96
	v_mul_f32_e32 v103, v97, v97
	v_mul_f32_e32 v104, v76, v76
	v_mul_f32_e32 v105, v77, v77
	v_fma_f32 v78, v18, v78, v26
	v_fma_f32 v79, v19, v79, v27
	v_add_f32_e32 v0, v77, v0
	v_add_f32_e32 v103, v105, v106
	v_add_f32_e32 v0, v96, v0
	v_add_f32_e32 v104, v102, v103
	v_mov_b32_e32 v102, v78
	v_mov_b32_e32 v103, v97
	v_add_f32_e32 v0, v97, v0
	v_mul_f32_e32 v102, v102, v102
	v_mul_f32_e32 v103, v103, v103
	v_add_f32_e32 v0, v78, v0
	v_add_f32_e32 v103, v103, v104
	v_fma_f32 v98, v20, v98, v28
	v_fma_f32 v99, v21, v99, v29
	v_add_f32_e32 v102, v102, v103
	v_add_f32_e32 v0, v79, v0
	v_mul_f32_e32 v106, v78, v78
	v_mul_f32_e32 v107, v79, v79
	v_add_f32_e32 v103, v98, v0
	v_mul_f32_e32 v104, v98, v98
	v_mul_f32_e32 v105, v99, v99
	v_add_f32_e32 v0, v107, v102
	v_add_f32_e32 v104, v104, v0
	v_mul_f32_e32 v102, v99, v99
	v_mov_b32_e32 v105, v99
	v_add_f32_e32 v102, v104, v102
	v_add_f32_e32 v103, v105, v103
	s_nop 1
	v_add_f32_dpp v102, v102, v102 quad_perm:[1,0,3,2] row_mask:0xf bank_mask:0xf
	v_add_f32_dpp v103, v103, v103 quad_perm:[1,0,3,2] row_mask:0xf bank_mask:0xf
	s_nop 0
	v_add_f32_dpp v102, v102, v102 quad_perm:[2,3,0,1] row_mask:0xf bank_mask:0xf
	v_add_f32_dpp v103, v103, v103 quad_perm:[2,3,0,1] row_mask:0xf bank_mask:0xf
	s_nop 0
	v_add_f32_dpp v102, v102, v102 row_half_mirror row_mask:0xf bank_mask:0xf
	v_add_f32_dpp v103, v103, v103 row_half_mirror row_mask:0xf bank_mask:0xf
	s_nop 0
	v_add_f32_dpp v102, v102, v102 row_mirror row_mask:0xf bank_mask:0xf
	v_add_f32_dpp v103, v103, v103 row_mirror row_mask:0xf bank_mask:0xf
	s_nop 0
	v_add_f32_dpp v102, v102, v102 row_bcast:15 row_mask:0xa bank_mask:0xf
	v_add_f32_dpp v103, v103, v103 row_bcast:15 row_mask:0xa bank_mask:0xf
	s_nop 0
	v_add_f32_dpp v102, v102, v102 row_bcast:31 row_mask:0xc bank_mask:0xf
	v_add_f32_dpp v103, v103, v103 row_bcast:31 row_mask:0xc bank_mask:0xf
	s_nop 0
	v_readlane_b32 s98, v102, 63
	v_readlane_b32 s99, v103, 63
	s_nop 1
	v_mov_b32_e32 v102, s98
	v_mov_b32_e32 v103, s99
	v_mov_b32_e32 v104, 0
	v_mov_b32_e32 v105, 0
	v_add_u32_e32 v0, 0xfffff000, v119
	v_lshrrev_b32_e32 v0, 11, v0
	v_add_u32_e32 v0, 1, v0
	v_cmp_lt_i32_e64 s[42:43], s29, v119
	v_cndmask_b32_e64 v106, 0, v0, s[42:43]
	v_cmp_ne_u32_e64 s[42:43], v106, v118
	s_and_saveexec_b64 s[34:35], s[42:43]
	s_cbranch_execz .LBB0_216
	v_mul_u32_u24_e32 v0, 0x1800, v106
	v_lshlrev_b64 v[42:43], 2, v[0:1]
	v_lshl_add_u64 v[44:45], v[84:85], 0, v[42:43]
	v_lshl_add_u64 v[62:63], v[86:87], 0, v[42:43]
	global_load_dwordx4 v[54:57], v[44:45], off
	global_load_dwordx4 v[58:61], v[44:45], off offset:16
	global_load_dwordx4 v[70:73], v[44:45], off offset:2064
	global_load_dwordx4 v[66:69], v[44:45], off offset:2048
	s_nop 0
	global_load_dwordx4 v[42:45], v[62:63], off offset:16
	global_load_dwordx4 v[46:49], v[62:63], off
	global_load_dwordx4 v[50:53], v[62:63], off offset:2064
	s_nop 0
	global_load_dwordx4 v[62:65], v[62:63], off offset:2048
	v_mov_b32_e32 v118, v106
	s_waitcnt vmcnt(7)
	v_add_f32_e32 v56, 1.0, v56
	v_add_f32_e32 v57, 1.0, v57
	v_add_f32_e32 v54, 1.0, v54
	v_add_f32_e32 v55, 1.0, v55
	s_waitcnt vmcnt(6)
	v_add_f32_e32 v60, 1.0, v60
	v_add_f32_e32 v61, 1.0, v61
	v_add_f32_e32 v58, 1.0, v58
	v_add_f32_e32 v59, 1.0, v59
	s_waitcnt vmcnt(4)
	v_add_f32_e32 v68, 1.0, v68
	v_add_f32_e32 v69, 1.0, v69
	v_add_f32_e32 v66, 1.0, v66
	v_add_f32_e32 v67, 1.0, v67
	v_add_f32_e32 v72, 1.0, v72
	v_add_f32_e32 v73, 1.0, v73
	v_add_f32_e32 v70, 1.0, v70
	v_add_f32_e32 v71, 1.0, v71
	s_branch .LBB0_216

.LBB0_229:
	s_or_b64 exec, exec, s[16:17]
	v_lshlrev_b32_e32 v72, 16, v46
	v_and_b32_e32 v73, 0xffff0000, v46
	v_lshlrev_b32_e32 v61, 16, v48
	v_and_b32_e32 v46, 0xffff0000, v48
	v_lshlrev_b32_e32 v48, 16, v42
	v_and_b32_e32 v62, 0xffff0000, v42
	v_add_f32_e32 v42, 0, v72
	v_lshlrev_b32_e32 v74, 16, v47
	v_lshlrev_b32_e32 v65, 16, v44
	v_and_b32_e32 v66, 0xffff0000, v44
	v_add_f32_e32 v42, v42, v73
	v_mul_f32_e32 v44, v73, v73
	v_and_b32_e32 v60, 0xffff0000, v47
	v_fmac_f32_e32 v44, v72, v72
	v_add_f32_e32 v42, v42, v74
	v_lshlrev_b32_e32 v63, 16, v43
	v_and_b32_e32 v64, 0xffff0000, v43
	v_lshlrev_b32_e32 v67, 16, v45
	v_and_b32_e32 v69, 0xffff0000, v45
	v_fmac_f32_e32 v44, v74, v74
	v_add_f32_e32 v45, v42, v60
	v_mul_f32_e32 v42, v60, v60
	v_mul_f32_e32 v43, v61, v61
	v_lshlrev_b32_e32 v47, 16, v49
	v_add_f32_e32 v42, v42, v44
	v_add_f32_e32 v44, v45, v61
	v_add_f32_e32 v45, v43, v42
	v_mul_f32_e32 v42, v46, v46
	v_mul_f32_e32 v43, v47, v47
	v_and_b32_e32 v49, 0xffff0000, v49
	v_add_f32_e32 v44, v44, v46
	v_add_f32_e32 v42, v42, v45
	v_add_f32_e32 v44, v44, v47
	v_add_f32_e32 v45, v43, v42
	v_mul_f32_e32 v42, v48, v48
	v_mul_f32_e32 v43, v49, v49
	v_add_f32_e32 v44, v44, v49
	v_add_f32_e32 v43, v43, v45
	v_add_f32_e32 v44, v44, v48
	v_add_f32_e32 v45, v42, v43
	v_mul_f32_e32 v42, v62, v62
	v_mul_f32_e32 v43, v63, v63
	v_add_f32_e32 v44, v44, v62
	v_add_f32_e32 v42, v42, v45
	v_add_f32_e32 v44, v44, v63
	v_add_f32_e32 v45, v43, v42
	v_mul_f32_e32 v42, v64, v64
	v_mul_f32_e32 v43, v65, v65
	v_add_f32_e32 v44, v44, v64
	v_add_f32_e32 v42, v42, v45
	v_add_f32_e32 v44, v44, v65
	v_add_f32_e32 v45, v43, v42
	v_mul_f32_e32 v42, v66, v66
	v_mul_f32_e32 v43, v67, v67
	v_add_f32_e32 v44, v44, v66
	v_add_f32_e32 v42, v42, v45
	v_add_f32_e32 v45, v44, v67
	v_add_f32_e32 v68, v43, v42
	v_mul_f32_e32 v44, v69, v69
	v_add_f32_e32 v42, v44, v68
	v_add_f32_e32 v43, v45, v69
	s_nop 1
	v_add_f32_dpp v42, v42, v42 quad_perm:[1,0,3,2] row_mask:0xf bank_mask:0xf
	v_add_f32_dpp v43, v43, v43 quad_perm:[1,0,3,2] row_mask:0xf bank_mask:0xf
	s_nop 0
	v_add_f32_dpp v42, v42, v42 quad_perm:[2,3,0,1] row_mask:0xf bank_mask:0xf
	v_add_f32_dpp v43, v43, v43 quad_perm:[2,3,0,1] row_mask:0xf bank_mask:0xf
	s_nop 0
	v_add_f32_dpp v42, v42, v42 row_half_mirror row_mask:0xf bank_mask:0xf
	v_add_f32_dpp v43, v43, v43 row_half_mirror row_mask:0xf bank_mask:0xf
	s_nop 0
	v_add_f32_dpp v42, v42, v42 row_mirror row_mask:0xf bank_mask:0xf
	v_add_f32_dpp v43, v43, v43 row_mirror row_mask:0xf bank_mask:0xf
	s_nop 0
	v_add_f32_dpp v42, v42, v42 row_bcast:15 row_mask:0xa bank_mask:0xf
	v_add_f32_dpp v43, v43, v43 row_bcast:15 row_mask:0xa bank_mask:0xf
	s_nop 0
	v_add_f32_dpp v42, v42, v42 row_bcast:31 row_mask:0xc bank_mask:0xf
	v_add_f32_dpp v43, v43, v43 row_bcast:31 row_mask:0xc bank_mask:0xf
	s_nop 0
	v_readlane_b32 s98, v42, 63
	v_readlane_b32 s99, v43, 63
	s_nop 1
	v_mov_b32_e32 v42, s98
	v_mov_b32_e32 v43, s99
	v_mov_b32_e32 v44, 0
	v_mov_b32_e32 v45, 0
	s_and_b64 s[0:1], exec, vcc
	s_or_b64 s[14:15], s[0:1], s[14:15]
	s_mov_b32 s0, 0x3a800000
	s_waitcnt lgkmcnt(0)
	v_add_f32_e32 v42, v42, v44
	v_add_f32_e32 v43, v43, v45
	s_nop 0
	v_mul_f32_e32 v70, s0, v42
	v_mul_f32_e32 v71, s0, v43
	s_mov_b64 s[0:1], 0x1000
	v_fma_f32 v42, -v71, v71, v70
	v_max_f32_e32 v42, 0, v42
	v_add_f32_e32 v42, 0x358637bd, v42
	v_cmp_gt_f32_e32 vcc, s58, v42
	v_mul_f32_e32 v43, 0x4b800000, v42
	v_sub_f32_e32 v45, v73, v71
	v_cndmask_b32_e32 v42, v42, v43, vcc
	v_rsq_f32_e32 v42, v42
	v_sub_f32_e32 v44, v72, v71
	v_mul_f32_e32 v43, 0x45800000, v42
	v_cndmask_b32_e32 v68, v42, v43, vcc
	v_sub_f32_e32 v43, v60, v71
	v_sub_f32_e32 v42, v74, v71
	v_mul_f32_e32 v72, v44, v68
	v_mul_f32_e32 v73, v45, v68
	v_mul_f32_e32 v42, v42, v68
	v_mul_f32_e32 v43, v43, v68
	s_nop 0
	v_fma_f32 v44, v8, v42, v16
	v_fma_f32 v45, v9, v43, v17
	v_fma_f32 v42, v6, v72, v14
	v_fma_f32 v43, v7, v73, v15
	global_store_dwordx4 v[50:51], v[42:45], off
	s_nop 1
	v_sub_f32_e32 v43, v49, v71
	v_sub_f32_e32 v42, v47, v71
	v_sub_f32_e32 v45, v46, v71
	v_sub_f32_e32 v44, v61, v71
	v_mul_f32_e32 v46, v44, v68
	v_mul_f32_e32 v47, v45, v68
	v_mul_f32_e32 v42, v42, v68
	v_mul_f32_e32 v43, v43, v68
	s_nop 0
	v_fma_f32 v44, v4, v42, v12
	v_fma_f32 v45, v5, v43, v13
	v_fma_f32 v42, v2, v46, v10
	v_fma_f32 v43, v3, v47, v11
	global_store_dwordx4 v[50:51], v[42:45], off offset:16
	s_nop 1
	v_sub_f32_e32 v43, v64, v71
	v_sub_f32_e32 v42, v63, v71
	v_sub_f32_e32 v45, v62, v71
	v_sub_f32_e32 v44, v48, v71
	v_mul_f32_e32 v46, v44, v68
	v_mul_f32_e32 v47, v45, v68
	v_mul_f32_e32 v42, v42, v68
	v_mul_f32_e32 v43, v43, v68
	s_nop 0
	v_fma_f32 v44, v24, v42, v32
	v_fma_f32 v45, v25, v43, v33
	v_fma_f32 v42, v22, v46, v30
	v_fma_f32 v43, v23, v47, v31
	global_store_dwordx4 v[50:51], v[42:45], off offset:2048
	s_nop 1
	v_sub_f32_e32 v43, v69, v71
	v_sub_f32_e32 v42, v67, v71
	v_sub_f32_e32 v45, v66, v71
	v_sub_f32_e32 v44, v65, v71
	v_mul_f32_e32 v46, v44, v68
	v_mul_f32_e32 v47, v45, v68
	v_mul_f32_e32 v42, v42, v68
	v_mul_f32_e32 v43, v43, v68
	s_nop 0
	v_fma_f32 v44, v20, v42, v28
	v_fma_f32 v45, v21, v43, v29
	v_fma_f32 v42, v18, v46, v26
	v_fma_f32 v43, v19, v47, v27
	global_store_dwordx4 v[50:51], v[42:45], off offset:2064
	v_lshl_add_u64 v[50:51], v[50:51], 0, s[0:1]
	s_mov_b64 s[0:1], 0x800
	s_waitcnt vmcnt(4)
	v_mov_b64_e32 v[44:45], v[40:41]
	v_mov_b64_e32 v[48:49], v[36:37]
	v_lshl_add_u64 v[52:53], v[52:53], 0, s[0:1]
	v_mov_b64_e32 v[42:43], v[38:39]
	v_mov_b64_e32 v[46:47], v[34:35]
	s_andn2_b64 exec, exec, s[14:15]
	s_cbranch_execz .LBB0_232

.LBB0_267:
	s_or_b64 exec, exec, s[68:69]
	s_mul_i32 s1, s18, 0x1600
	s_mul_hi_u32 s0, s18, 0x1600
	s_add_u32 s54, s22, s1
	s_addc_u32 s55, s23, s0
	s_or_b32 s0, s18, 0xff
	s_mul_hi_u32 s1, s0, 0x1600
	s_mulk_i32 s0, 0x1600
	s_add_u32 s52, s22, s0
	s_addc_u32 s53, s23, s1
	s_and_saveexec_b64 s[60:61], s[42:43]
	s_cbranch_execz .LBB0_272
	s_and_b64 vcc, exec, s[48:49]
	s_cbranch_vccnz .LBB0_270
	s_waitcnt vmcnt(0)
	v_fma_f32 v2, v12, v18, v30
	v_fma_f32 v3, v13, v19, v31
	v_mul_f32_e32 v0, 0xbfb8aa3b, v2
	v_exp_f32_e32 v0, v0
	v_mul_f32_e32 v4, 0xbfb8aa3b, v3
	v_exp_f32_e32 v5, v4
	v_add_f32_e32 v0, 1.0, v0
	v_rcp_f32_e32 v4, v0
	v_add_f32_e32 v0, 1.0, v5
	v_rcp_f32_e32 v5, v0
	s_nop 0
	v_mul_f32_e32 v2, v2, v4
	v_mul_f32_e32 v3, v3, v5
	s_nop 0
	v_mul_f32_e32 v2, v24, v2
	v_mul_f32_e32 v3, v25, v3
	s_nop 0
	v_cvt_pk_bf16_f32 v0, v2, v3
	v_lshl_add_u64 v[2:3], v[202:203], 1, s[54:55]
	global_store_dword v[2:3], v0, off
.LBB0_270:
	s_andn2_b64 vcc, exec, s[50:51]
	s_cbranch_vccnz .LBB0_272
	s_waitcnt vmcnt(0)
	v_fma_f32 v2, v74, v76, v36
	v_fma_f32 v3, v75, v77, v37
	s_nop 0
	v_mul_f32_e32 v0, 0xbfb8aa3b, v2
	v_mul_f32_e32 v4, 0xbfb8aa3b, v3
	v_exp_f32_e32 v0, v0
	v_exp_f32_e32 v4, v4
	v_add_f32_e32 v0, 1.0, v0
	v_add_f32_e32 v5, 1.0, v4
	v_rcp_f32_e32 v4, v0
	v_rcp_f32_e32 v5, v5
	s_nop 0
	v_mul_f32_e32 v2, v2, v4
	v_mul_f32_e32 v3, v3, v5
	s_nop 0
	v_mul_f32_e32 v2, v68, v2
	v_mul_f32_e32 v3, v69, v3
	s_nop 0
	v_cvt_pk_bf16_f32 v0, v2, v3
	v_lshl_add_u64 v[2:3], v[202:203], 1, s[52:53]
	global_store_dword v[2:3], v0, off
.LBB0_272:
	s_or_b64 exec, exec, s[60:61]
	s_and_saveexec_b64 s[60:61], s[44:45]
	s_cbranch_execz .LBB0_277
	s_and_b64 vcc, exec, s[48:49]
	s_cbranch_vccnz .LBB0_275
	s_waitcnt vmcnt(0)
	v_fma_f32 v2, v14, v20, v32
	v_fma_f32 v3, v15, v21, v33
	v_mul_f32_e32 v0, 0xbfb8aa3b, v2
	v_exp_f32_e32 v0, v0
	v_mul_f32_e32 v4, 0xbfb8aa3b, v3
	v_exp_f32_e32 v5, v4
	v_add_f32_e32 v0, 1.0, v0
	v_rcp_f32_e32 v4, v0
	v_add_f32_e32 v0, 1.0, v5
	v_rcp_f32_e32 v5, v0
	s_nop 0
	v_mul_f32_e32 v2, v2, v4
	v_mul_f32_e32 v3, v3, v5
	s_nop 0
	v_mul_f32_e32 v2, v26, v2
	v_mul_f32_e32 v3, v27, v3
	s_nop 0
	v_cvt_pk_bf16_f32 v0, v2, v3
	v_lshl_add_u64 v[2:3], v[202:203], 1, s[54:55]
	global_store_dword v[2:3], v0, off offset:2048
.LBB0_275:
	s_andn2_b64 vcc, exec, s[50:51]
	s_cbranch_vccnz .LBB0_277
	s_waitcnt vmcnt(0)
	v_fma_f32 v2, v66, v70, v38
	v_fma_f32 v3, v67, v71, v39
	s_nop 0
	v_mul_f32_e32 v0, 0xbfb8aa3b, v2
	v_mul_f32_e32 v4, 0xbfb8aa3b, v3
	v_exp_f32_e32 v0, v0
	v_exp_f32_e32 v4, v4
	v_add_f32_e32 v0, 1.0, v0
	v_add_f32_e32 v5, 1.0, v4
	v_rcp_f32_e32 v4, v0
	v_rcp_f32_e32 v5, v5
	s_nop 0
	v_mul_f32_e32 v2, v2, v4
	v_mul_f32_e32 v3, v3, v5
	s_nop 0
	v_mul_f32_e32 v2, v64, v2
	v_mul_f32_e32 v3, v65, v3
	s_nop 0
	v_cvt_pk_bf16_f32 v0, v2, v3
	v_lshl_add_u64 v[2:3], v[202:203], 1, s[52:53]
	global_store_dword v[2:3], v0, off offset:2048
.LBB0_277:
	s_or_b64 exec, exec, s[60:61]
	s_and_saveexec_b64 s[60:61], s[46:47]
	s_cbranch_execz .LBB0_236
	s_and_b64 vcc, exec, s[48:49]
	s_cbranch_vccnz .LBB0_280
	s_waitcnt vmcnt(0)
	v_fma_f32 v2, v16, v22, v34
	v_fma_f32 v3, v17, v23, v35
	v_mul_f32_e32 v0, 0xbfb8aa3b, v2
	v_exp_f32_e32 v0, v0
	v_mul_f32_e32 v4, 0xbfb8aa3b, v3
	v_exp_f32_e32 v5, v4
	v_add_f32_e32 v0, 1.0, v0
	v_rcp_f32_e32 v4, v0
	v_add_f32_e32 v0, 1.0, v5
	v_rcp_f32_e32 v5, v0
	s_nop 0
	v_mul_f32_e32 v2, v2, v4
	v_mul_f32_e32 v3, v3, v5
	s_nop 0
	v_mul_f32_e32 v2, v28, v2
	v_mul_f32_e32 v3, v29, v3
	s_nop 0
	v_cvt_pk_bf16_f32 v0, v2, v3
	v_lshl_add_u64 v[2:3], v[54:55], 1, s[54:55]
	global_store_dword v[2:3], v0, off
.LBB0_280:
	s_andn2_b64 vcc, exec, s[50:51]
	s_cbranch_vccnz .LBB0_236
	s_waitcnt vmcnt(0)
	v_fma_f32 v2, v72, v78, v40
	v_fma_f32 v3, v73, v79, v41
	s_nop 0
	v_mul_f32_e32 v0, 0xbfb8aa3b, v2
	v_mul_f32_e32 v4, 0xbfb8aa3b, v3
	v_exp_f32_e32 v0, v0
	v_exp_f32_e32 v4, v4
	v_add_f32_e32 v0, 1.0, v0
	v_add_f32_e32 v5, 1.0, v4
	v_rcp_f32_e32 v4, v0
	v_rcp_f32_e32 v5, v5
	s_nop 0
	v_mul_f32_e32 v2, v2, v4
	v_mul_f32_e32 v3, v3, v5
	s_nop 0
	v_mul_f32_e32 v2, v62, v2
	v_mul_f32_e32 v3, v63, v3
	s_nop 0
	v_cvt_pk_bf16_f32 v0, v2, v3
	v_lshl_add_u64 v[2:3], v[54:55], 1, s[52:53]
	global_store_dword v[2:3], v0, off
	s_branch .LBB0_236

.LBB0_321:
	s_ashr_i32 s51, s50, 31
	s_lshl_b64 s[0:1], s[50:51], 18
	v_readlane_b32 s10, v254, 21
	v_readlane_b32 s11, v254, 22
	s_add_u32 s0, s10, s0
	s_addc_u32 s1, s11, s1
	v_lshl_or_b32 v216, s8, 8, v243
	s_lshl_b32 s8, s4, 8
	s_add_i32 s10, s8, 0xfffff000
	s_lshr_b32 s10, s10, 11
	s_mulk_i32 s10, 0x1800
	s_addk_i32 s10, 0x1800
	s_cmp_gt_i32 s4, 15
	s_cselect_b32 s86, s10, 0
	s_lshl_b64 s[10:11], s[86:87], 2
	s_add_u32 s10, s38, s10
	v_readlane_b32 s4, v254, 26
	s_addc_u32 s11, s4, s11
	s_andn2_b64 vcc, exec, s[14:15]
	s_cbranch_vccnz .Ldn_noadd
	v_lshl_add_u64 v[214:215], s[0:1], 0, v[206:207]
	s_mov_b64 s[0:1], 0x2000
	global_load_dwordx4 v[130:133], v[214:215], off
	v_lshl_add_u64 v[214:215], v[214:215], 0, s[0:1]
	global_load_dwordx4 v[134:137], v[214:215], off
	v_lshl_add_u64 v[214:215], v[214:215], 0, s[0:1]
	global_load_dwordx4 v[138:141], v[214:215], off
	v_lshl_add_u64 v[214:215], v[214:215], 0, s[0:1]
	global_load_dwordx4 v[142:145], v[214:215], off
	v_lshl_add_u64 v[214:215], v[214:215], 0, s[0:1]
	global_load_dwordx4 v[146:149], v[214:215], off
	v_lshl_add_u64 v[214:215], v[214:215], 0, s[0:1]
	global_load_dwordx4 v[150:153], v[214:215], off
	v_lshl_add_u64 v[214:215], v[214:215], 0, s[0:1]
	global_load_dwordx4 v[154:157], v[214:215], off
	v_lshl_add_u64 v[214:215], v[214:215], 0, s[0:1]
	global_load_dwordx4 v[158:161], v[214:215], off
	v_lshl_add_u64 v[214:215], v[214:215], 0, s[0:1]
	global_load_dwordx4 v[162:165], v[214:215], off
	v_lshl_add_u64 v[214:215], v[214:215], 0, s[0:1]
	global_load_dwordx4 v[166:169], v[214:215], off
	v_lshl_add_u64 v[214:215], v[214:215], 0, s[0:1]
	global_load_dwordx4 v[170:173], v[214:215], off
	v_lshl_add_u64 v[214:215], v[214:215], 0, s[0:1]
	global_load_dwordx4 v[174:177], v[214:215], off
	v_lshl_add_u64 v[214:215], v[214:215], 0, s[0:1]
	global_load_dwordx4 v[178:181], v[214:215], off
	v_lshl_add_u64 v[214:215], v[214:215], 0, s[0:1]
	global_load_dwordx4 v[182:185], v[214:215], off
	v_lshl_add_u64 v[214:215], v[214:215], 0, s[0:1]
	global_load_dwordx4 v[186:189], v[214:215], off
	v_lshl_add_u64 v[214:215], v[214:215], 0, s[0:1]
	global_load_dwordx4 v[194:197], v[214:215], off
	v_lshl_add_u64 v[214:215], v[214:215], 0, s[0:1]
	s_waitcnt vmcnt(15)
	v_add_f32_e32 v126, v126, v130
	v_add_f32_e32 v127, v127, v131
	v_add_f32_e32 v128, v128, v132
	v_add_f32_e32 v129, v129, v133
	global_load_dwordx4 v[130:133], v[214:215], off
	v_lshl_add_u64 v[214:215], v[214:215], 0, s[0:1]
	s_waitcnt vmcnt(15)
	v_add_f32_e32 v122, v122, v134
	v_add_f32_e32 v123, v123, v135
	v_add_f32_e32 v124, v124, v136
	v_add_f32_e32 v125, v125, v137
	global_load_dwordx4 v[134:137], v[214:215], off
	v_lshl_add_u64 v[214:215], v[214:215], 0, s[0:1]
	s_waitcnt vmcnt(15)
	v_add_f32_e32 v118, v118, v138
	v_add_f32_e32 v119, v119, v139
	v_add_f32_e32 v120, v120, v140
	v_add_f32_e32 v121, v121, v141
	global_load_dwordx4 v[138:141], v[214:215], off
	v_lshl_add_u64 v[214:215], v[214:215], 0, s[0:1]
	s_waitcnt vmcnt(15)
	v_add_f32_e32 v114, v114, v142
	v_add_f32_e32 v115, v115, v143
	v_add_f32_e32 v116, v116, v144
	v_add_f32_e32 v117, v117, v145
	global_load_dwordx4 v[142:145], v[214:215], off
	v_lshl_add_u64 v[214:215], v[214:215], 0, s[0:1]
	s_waitcnt vmcnt(15)
	v_add_f32_e32 v110, v110, v146
	v_add_f32_e32 v111, v111, v147
	v_add_f32_e32 v112, v112, v148
	v_add_f32_e32 v113, v113, v149
	global_load_dwordx4 v[146:149], v[214:215], off
	v_lshl_add_u64 v[214:215], v[214:215], 0, s[0:1]
	s_waitcnt vmcnt(15)
	v_add_f32_e32 v106, v106, v150
	v_add_f32_e32 v107, v107, v151
	v_add_f32_e32 v108, v108, v152
	v_add_f32_e32 v109, v109, v153
	global_load_dwordx4 v[150:153], v[214:215], off
	v_lshl_add_u64 v[214:215], v[214:215], 0, s[0:1]
	s_waitcnt vmcnt(15)
	v_add_f32_e32 v102, v102, v154
	v_add_f32_e32 v103, v103, v155
	v_add_f32_e32 v104, v104, v156
	v_add_f32_e32 v105, v105, v157
	global_load_dwordx4 v[154:157], v[214:215], off
	v_lshl_add_u64 v[214:215], v[214:215], 0, s[0:1]
	s_waitcnt vmcnt(15)
	v_add_f32_e32 v98, v98, v158
	v_add_f32_e32 v99, v99, v159
	v_add_f32_e32 v100, v100, v160
	v_add_f32_e32 v101, v101, v161
	global_load_dwordx4 v[158:161], v[214:215], off
	v_lshl_add_u64 v[214:215], v[214:215], 0, s[0:1]
	s_waitcnt vmcnt(15)
	v_add_f32_e32 v94, v94, v162
	v_add_f32_e32 v95, v95, v163
	v_add_f32_e32 v96, v96, v164
	v_add_f32_e32 v97, v97, v165
	global_load_dwordx4 v[162:165], v[214:215], off
	v_lshl_add_u64 v[214:215], v[214:215], 0, s[0:1]
	s_waitcnt vmcnt(15)
	v_add_f32_e32 v90, v90, v166
	v_add_f32_e32 v91, v91, v167
	v_add_f32_e32 v92, v92, v168
	v_add_f32_e32 v93, v93, v169
	global_load_dwordx4 v[166:169], v[214:215], off
	v_lshl_add_u64 v[214:215], v[214:215], 0, s[0:1]
	s_waitcnt vmcnt(15)
	v_add_f32_e32 v86, v86, v170
	v_add_f32_e32 v87, v87, v171
	v_add_f32_e32 v88, v88, v172
	v_add_f32_e32 v89, v89, v173
	global_load_dwordx4 v[170:173], v[214:215], off
	v_lshl_add_u64 v[214:215], v[214:215], 0, s[0:1]
	s_waitcnt vmcnt(15)
	v_add_f32_e32 v82, v82, v174
	v_add_f32_e32 v83, v83, v175
	v_add_f32_e32 v84, v84, v176
	v_add_f32_e32 v85, v85, v177
	global_load_dwordx4 v[174:177], v[214:215], off
	v_lshl_add_u64 v[214:215], v[214:215], 0, s[0:1]
	s_waitcnt vmcnt(15)
	v_add_f32_e32 v78, v78, v178
	v_add_f32_e32 v79, v79, v179
	v_add_f32_e32 v80, v80, v180
	v_add_f32_e32 v81, v81, v181
	global_load_dwordx4 v[178:181], v[214:215], off
	v_lshl_add_u64 v[214:215], v[214:215], 0, s[0:1]
	s_waitcnt vmcnt(15)
	v_add_f32_e32 v74, v74, v182
	v_add_f32_e32 v75, v75, v183
	v_add_f32_e32 v76, v76, v184
	v_add_f32_e32 v77, v77, v185
	global_load_dwordx4 v[182:185], v[214:215], off
	v_lshl_add_u64 v[214:215], v[214:215], 0, s[0:1]
	s_waitcnt vmcnt(15)
	v_add_f32_e32 v70, v70, v186
	v_add_f32_e32 v71, v71, v187
	v_add_f32_e32 v72, v72, v188
	v_add_f32_e32 v73, v73, v189
	global_load_dwordx4 v[186:189], v[214:215], off
	v_lshl_add_u64 v[214:215], v[214:215], 0, s[0:1]
	s_waitcnt vmcnt(15)
	v_add_f32_e32 v66, v66, v194
	v_add_f32_e32 v67, v67, v195
	v_add_f32_e32 v68, v68, v196
	v_add_f32_e32 v69, v69, v197
	global_load_dwordx4 v[194:197], v[214:215], off
	s_waitcnt vmcnt(15)
	v_add_f32_e32 v62, v62, v130
	v_add_f32_e32 v63, v63, v131
	v_add_f32_e32 v64, v64, v132
	v_add_f32_e32 v65, v65, v133
	s_waitcnt vmcnt(14)
	v_add_f32_e32 v58, v58, v134
	v_add_f32_e32 v59, v59, v135
	v_add_f32_e32 v60, v60, v136
	v_add_f32_e32 v61, v61, v137
	s_waitcnt vmcnt(13)
	v_add_f32_e32 v54, v54, v138
	v_add_f32_e32 v55, v55, v139
	v_add_f32_e32 v56, v56, v140
	v_add_f32_e32 v57, v57, v141
	s_waitcnt vmcnt(12)
	v_add_f32_e32 v50, v50, v142
	v_add_f32_e32 v51, v51, v143
	v_add_f32_e32 v52, v52, v144
	v_add_f32_e32 v53, v53, v145
	s_waitcnt vmcnt(11)
	v_add_f32_e32 v46, v46, v146
	v_add_f32_e32 v47, v47, v147
	v_add_f32_e32 v48, v48, v148
	v_add_f32_e32 v49, v49, v149
	s_waitcnt vmcnt(10)
	v_add_f32_e32 v42, v42, v150
	v_add_f32_e32 v43, v43, v151
	v_add_f32_e32 v44, v44, v152
	v_add_f32_e32 v45, v45, v153
	s_waitcnt vmcnt(9)
	v_add_f32_e32 v38, v38, v154
	v_add_f32_e32 v39, v39, v155
	v_add_f32_e32 v40, v40, v156
	v_add_f32_e32 v41, v41, v157
	s_waitcnt vmcnt(8)
	v_add_f32_e32 v34, v34, v158
	v_add_f32_e32 v35, v35, v159
	v_add_f32_e32 v36, v36, v160
	v_add_f32_e32 v37, v37, v161
	s_waitcnt vmcnt(7)
	v_add_f32_e32 v30, v30, v162
	v_add_f32_e32 v31, v31, v163
	v_add_f32_e32 v32, v32, v164
	v_add_f32_e32 v33, v33, v165
	s_waitcnt vmcnt(6)
	v_add_f32_e32 v26, v26, v166
	v_add_f32_e32 v27, v27, v167
	v_add_f32_e32 v28, v28, v168
	v_add_f32_e32 v29, v29, v169
	s_waitcnt vmcnt(5)
	v_add_f32_e32 v22, v22, v170
	v_add_f32_e32 v23, v23, v171
	v_add_f32_e32 v24, v24, v172
	v_add_f32_e32 v25, v25, v173
	s_waitcnt vmcnt(4)
	v_add_f32_e32 v18, v18, v174
	v_add_f32_e32 v19, v19, v175
	v_add_f32_e32 v20, v20, v176
	v_add_f32_e32 v21, v21, v177
	s_waitcnt vmcnt(3)
	v_add_f32_e32 v14, v14, v178
	v_add_f32_e32 v15, v15, v179
	v_add_f32_e32 v16, v16, v180
	v_add_f32_e32 v17, v17, v181
	s_waitcnt vmcnt(2)
	v_add_f32_e32 v10, v10, v182
	v_add_f32_e32 v11, v11, v183
	v_add_f32_e32 v12, v12, v184
	v_add_f32_e32 v13, v13, v185
	s_waitcnt vmcnt(1)
	v_add_f32_e32 v6, v6, v186
	v_add_f32_e32 v7, v7, v187
	v_add_f32_e32 v8, v8, v188
	v_add_f32_e32 v9, v9, v189
	s_waitcnt vmcnt(0)
	v_add_f32_e32 v2, v2, v194
	v_add_f32_e32 v3, v3, v195
	v_add_f32_e32 v4, v4, v196
	v_add_f32_e32 v5, v5, v197
.Ldn_noadd:
	v_ashrrev_i32_e32 v217, 31, v216
	v_lshlrev_b64 v[152:153], 2, v[216:217]
	v_lshl_add_u64 v[220:221], s[48:49], 0, v[152:153]
	v_lshl_add_u64 v[222:223], s[46:47], 0, v[152:153]
	v_lshl_add_u64 v[218:219], s[10:11], 0, v[152:153]
	global_load_dwordx4 v[154:157], v[220:221], off offset:16
	global_load_dwordx4 v[166:169], v[220:221], off
	global_load_dwordx4 v[162:165], v[222:223], off offset:16
	global_load_dwordx4 v[170:173], v[222:223], off
	global_load_dwordx4 v[158:161], v[218:219], off offset:16
	global_load_dwordx4 v[174:177], v[218:219], off
	v_add_u32_e32 v218, s8, v201
	v_ashrrev_i32_e32 v219, 31, v218
	v_lshlrev_b64 v[220:221], 11, v[218:219]
	v_lshl_add_u64 v[220:221], s[12:13], 0, v[220:221]
	v_lshl_add_u64 v[214:215], v[218:219], 3, s[6:7]
	v_lshl_add_u64 v[216:217], v[216:217], 1, v[220:221]
	v_mov_b64_e32 v[218:219], v[216:217]
	global_load_dwordx2 v[194:195], v[214:215], off
	global_load_dwordx4 v[178:181], v[216:217], off
	s_mov_b32 s0, 0x8000
	s_mov_b32 s1, 0
	v_lshl_add_u64 v[216:217], v[216:217], 0, s[0:1]
	global_load_dwordx2 v[196:197], v[214:215], off offset:128
	global_load_dwordx4 v[182:185], v[216:217], off
	v_lshl_add_u64 v[216:217], v[216:217], 0, s[0:1]
	global_load_dwordx2 v[232:233], v[214:215], off offset:256
	global_load_dwordx4 v[186:189], v[216:217], off
	v_lshl_add_u64 v[216:217], v[216:217], 0, s[0:1]
	global_load_dwordx2 v[248:249], v[214:215], off offset:384
	global_load_dwordx4 v[130:133], v[216:217], off
	s_mov_b32 s0, 0x28000
	s_mov_b32 s1, 0
	v_lshl_add_u64 v[216:217], v[216:217], 0, s[0:1]
	global_load_dwordx2 v[146:147], v[214:215], off offset:1024
	global_load_dwordx4 v[134:137], v[216:217], off
	s_mov_b32 s0, 0x8000
	s_mov_b32 s1, 0
	v_lshl_add_u64 v[216:217], v[216:217], 0, s[0:1]
	global_load_dwordx2 v[148:149], v[214:215], off offset:1152
	global_load_dwordx4 v[138:141], v[216:217], off
	v_lshl_add_u64 v[216:217], v[216:217], 0, s[0:1]
	global_load_dwordx2 v[150:151], v[214:215], off offset:1280
	global_load_dwordx4 v[142:145], v[216:217], off
	v_lshl_add_u64 v[216:217], v[216:217], 0, s[0:1]
	s_waitcnt vmcnt(12)
	v_lshlrev_b32_e32 v220, 16, v178
	v_and_b32_e32 v221, 0xffff0000, v178
	v_lshlrev_b32_e32 v178, 16, v179
	v_and_b32_e32 v179, 0xffff0000, v179
	v_lshlrev_b32_e32 v222, 16, v180
	v_and_b32_e32 v223, 0xffff0000, v180
	v_lshlrev_b32_e32 v180, 16, v181
	v_and_b32_e32 v181, 0xffff0000, v181
	v_sub_f32_e32 v221, v221, v194
	v_sub_f32_e32 v220, v220, v194
	v_sub_f32_e32 v179, v179, v194
	v_sub_f32_e32 v178, v178, v194
	v_mul_f32_e32 v178, v195, v178
	v_mul_f32_e32 v179, v195, v179
	v_mul_f32_e32 v220, v195, v220
	v_mul_f32_e32 v221, v195, v221
	v_sub_f32_e32 v223, v223, v194
	v_sub_f32_e32 v222, v222, v194
	v_sub_f32_e32 v181, v181, v194
	v_sub_f32_e32 v180, v180, v194
	v_fma_f32 v220, v166, v220, v170
	v_fma_f32 v221, v167, v221, v171
	v_fma_f32 v178, v168, v178, v172
	v_fma_f32 v179, v169, v179, v173
	v_mul_f32_e32 v180, v195, v180
	v_mul_f32_e32 v181, v195, v181
	v_mul_f32_e32 v222, v195, v222
	v_mul_f32_e32 v223, v195, v223
	v_mul_f32_e32 v128, v176, v128
	v_mul_f32_e32 v129, v177, v129
	v_mul_f32_e32 v126, v174, v126
	v_mul_f32_e32 v127, v175, v127
	v_fma_f32 v222, v154, v222, v162
	v_fma_f32 v223, v155, v223, v163
	v_fma_f32 v180, v156, v180, v164
	v_fma_f32 v181, v157, v181, v165
	v_fma_f32 v128, v178, s56, v128
	v_fma_f32 v129, v179, s56, v129
	v_fma_f32 v126, v220, s56, v126
	v_fma_f32 v127, v221, s56, v127
	v_mul_f32_e32 v124, v160, v124
	v_mul_f32_e32 v125, v161, v125
	v_mul_f32_e32 v122, v158, v122
	v_mul_f32_e32 v123, v159, v123
	v_fma_f32 v124, v180, s56, v124
	v_fma_f32 v125, v181, s56, v125
	v_fma_f32 v122, v222, s56, v122
	v_fma_f32 v123, v223, s56, v123
	v_cvt_pk_bf16_f32 v126, v126, v127
	v_cvt_pk_bf16_f32 v127, v128, v129
	v_cvt_pk_bf16_f32 v128, v122, v123
	v_cvt_pk_bf16_f32 v129, v124, v125
	global_store_dwordx4 v[218:219], v[126:129], off
	global_load_dwordx2 v[194:195], v[214:215], off
	global_load_dwordx4 v[178:181], v[218:219], off offset:256
	v_lshl_add_u64 v[220:221], s[10:11], 0, v[152:153]
	s_nop 1
	global_load_dwordx4 v[126:129], v[220:221], off offset:512
	global_load_dwordx4 v[122:125], v[220:221], off offset:528
	v_lshl_add_u64 v[218:219], v[218:219], 0, s[0:1]
	s_waitcnt vmcnt(15)
	v_lshlrev_b32_e32 v220, 16, v182
	v_and_b32_e32 v221, 0xffff0000, v182
	v_lshlrev_b32_e32 v182, 16, v183
	v_and_b32_e32 v183, 0xffff0000, v183
	v_lshlrev_b32_e32 v222, 16, v184
	v_and_b32_e32 v223, 0xffff0000, v184
	v_lshlrev_b32_e32 v184, 16, v185
	v_and_b32_e32 v185, 0xffff0000, v185
	v_sub_f32_e32 v221, v221, v196
	v_sub_f32_e32 v220, v220, v196
	v_sub_f32_e32 v183, v183, v196
	v_sub_f32_e32 v182, v182, v196
	v_mul_f32_e32 v182, v197, v182
	v_mul_f32_e32 v183, v197, v183
	v_mul_f32_e32 v220, v197, v220
	v_mul_f32_e32 v221, v197, v221
	v_sub_f32_e32 v223, v223, v196
	v_sub_f32_e32 v222, v222, v196
	v_sub_f32_e32 v185, v185, v196
	v_sub_f32_e32 v184, v184, v196
	v_fma_f32 v220, v166, v220, v170
	v_fma_f32 v221, v167, v221, v171
	v_fma_f32 v182, v168, v182, v172
	v_fma_f32 v183, v169, v183, v173
	v_mul_f32_e32 v184, v197, v184
	v_mul_f32_e32 v185, v197, v185
	v_mul_f32_e32 v222, v197, v222
	v_mul_f32_e32 v223, v197, v223
	v_mul_f32_e32 v120, v176, v120
	v_mul_f32_e32 v121, v177, v121
	v_mul_f32_e32 v118, v174, v118
	v_mul_f32_e32 v119, v175, v119
	v_fma_f32 v222, v154, v222, v162
	v_fma_f32 v223, v155, v223, v163
	v_fma_f32 v184, v156, v184, v164
	v_fma_f32 v185, v157, v185, v165
	v_fma_f32 v120, v182, s56, v120
	v_fma_f32 v121, v183, s56, v121
	v_fma_f32 v118, v220, s56, v118
	v_fma_f32 v119, v221, s56, v119
	v_mul_f32_e32 v116, v160, v116
	v_mul_f32_e32 v117, v161, v117
	v_mul_f32_e32 v114, v158, v114
	v_mul_f32_e32 v115, v159, v115
	v_fma_f32 v116, v184, s56, v116
	v_fma_f32 v117, v185, s56, v117
	v_fma_f32 v114, v222, s56, v114
	v_fma_f32 v115, v223, s56, v115
	v_cvt_pk_bf16_f32 v118, v118, v119
	v_cvt_pk_bf16_f32 v119, v120, v121
	v_cvt_pk_bf16_f32 v120, v114, v115
	v_cvt_pk_bf16_f32 v121, v116, v117
	global_store_dwordx4 v[218:219], v[118:121], off
	global_load_dwordx2 v[196:197], v[214:215], off offset:128
	global_load_dwordx4 v[182:185], v[218:219], off offset:256
	v_lshl_add_u64 v[220:221], s[48:49], 0, v[152:153]
	s_nop 1
	global_load_dwordx4 v[118:121], v[220:221], off offset:512
	global_load_dwordx4 v[114:117], v[220:221], off offset:528
	v_lshl_add_u64 v[218:219], v[218:219], 0, s[0:1]
	s_waitcnt vmcnt(18)
	v_lshlrev_b32_e32 v220, 16, v186
	v_and_b32_e32 v221, 0xffff0000, v186
	v_lshlrev_b32_e32 v186, 16, v187
	v_and_b32_e32 v187, 0xffff0000, v187
	v_lshlrev_b32_e32 v222, 16, v188
	v_and_b32_e32 v223, 0xffff0000, v188
	v_lshlrev_b32_e32 v188, 16, v189
	v_and_b32_e32 v189, 0xffff0000, v189
	v_sub_f32_e32 v221, v221, v232
	v_sub_f32_e32 v220, v220, v232
	v_sub_f32_e32 v187, v187, v232
	v_sub_f32_e32 v186, v186, v232
	v_mul_f32_e32 v186, v233, v186
	v_mul_f32_e32 v187, v233, v187
	v_mul_f32_e32 v220, v233, v220
	v_mul_f32_e32 v221, v233, v221
	v_sub_f32_e32 v223, v223, v232
	v_sub_f32_e32 v222, v222, v232
	v_sub_f32_e32 v189, v189, v232
	v_sub_f32_e32 v188, v188, v232
	v_fma_f32 v220, v166, v220, v170
	v_fma_f32 v221, v167, v221, v171
	v_fma_f32 v186, v168, v186, v172
	v_fma_f32 v187, v169, v187, v173
	v_mul_f32_e32 v188, v233, v188
	v_mul_f32_e32 v189, v233, v189
	v_mul_f32_e32 v222, v233, v222
	v_mul_f32_e32 v223, v233, v223
	v_mul_f32_e32 v112, v176, v112
	v_mul_f32_e32 v113, v177, v113
	v_mul_f32_e32 v110, v174, v110
	v_mul_f32_e32 v111, v175, v111
	v_fma_f32 v222, v154, v222, v162
	v_fma_f32 v223, v155, v223, v163
	v_fma_f32 v188, v156, v188, v164
	v_fma_f32 v189, v157, v189, v165
	v_fma_f32 v112, v186, s56, v112
	v_fma_f32 v113, v187, s56, v113
	v_fma_f32 v110, v220, s56, v110
	v_fma_f32 v111, v221, s56, v111
	v_mul_f32_e32 v108, v160, v108
	v_mul_f32_e32 v109, v161, v109
	v_mul_f32_e32 v106, v158, v106
	v_mul_f32_e32 v107, v159, v107
	v_fma_f32 v108, v188, s56, v108
	v_fma_f32 v109, v189, s56, v109
	v_fma_f32 v106, v222, s56, v106
	v_fma_f32 v107, v223, s56, v107
	v_cvt_pk_bf16_f32 v110, v110, v111
	v_cvt_pk_bf16_f32 v111, v112, v113
	v_cvt_pk_bf16_f32 v112, v106, v107
	v_cvt_pk_bf16_f32 v113, v108, v109
	global_store_dwordx4 v[218:219], v[110:113], off
	global_load_dwordx2 v[232:233], v[214:215], off offset:256
	global_load_dwordx4 v[186:189], v[218:219], off offset:256
	v_lshl_add_u64 v[220:221], s[46:47], 0, v[152:153]
	s_nop 1
	global_load_dwordx4 v[110:113], v[220:221], off offset:512
	global_load_dwordx4 v[106:109], v[220:221], off offset:528
	v_lshl_add_u64 v[218:219], v[218:219], 0, s[0:1]
	s_waitcnt vmcnt(21)
	v_lshlrev_b32_e32 v220, 16, v130
	v_and_b32_e32 v221, 0xffff0000, v130
	v_lshlrev_b32_e32 v130, 16, v131
	v_and_b32_e32 v131, 0xffff0000, v131
	v_lshlrev_b32_e32 v222, 16, v132
	v_and_b32_e32 v223, 0xffff0000, v132
	v_lshlrev_b32_e32 v132, 16, v133
	v_and_b32_e32 v133, 0xffff0000, v133
	v_sub_f32_e32 v221, v221, v248
	v_sub_f32_e32 v220, v220, v248
	v_sub_f32_e32 v131, v131, v248
	v_sub_f32_e32 v130, v130, v248
	v_mul_f32_e32 v130, v249, v130
	v_mul_f32_e32 v131, v249, v131
	v_mul_f32_e32 v220, v249, v220
	v_mul_f32_e32 v221, v249, v221
	v_sub_f32_e32 v223, v223, v248
	v_sub_f32_e32 v222, v222, v248
	v_sub_f32_e32 v133, v133, v248
	v_sub_f32_e32 v132, v132, v248
	v_fma_f32 v220, v166, v220, v170
	v_fma_f32 v221, v167, v221, v171
	v_fma_f32 v130, v168, v130, v172
	v_fma_f32 v131, v169, v131, v173
	v_mul_f32_e32 v132, v249, v132
	v_mul_f32_e32 v133, v249, v133
	v_mul_f32_e32 v222, v249, v222
	v_mul_f32_e32 v223, v249, v223
	v_mul_f32_e32 v104, v176, v104
	v_mul_f32_e32 v105, v177, v105
	v_mul_f32_e32 v102, v174, v102
	v_mul_f32_e32 v103, v175, v103
	v_fma_f32 v222, v154, v222, v162
	v_fma_f32 v223, v155, v223, v163
	v_fma_f32 v132, v156, v132, v164
	v_fma_f32 v133, v157, v133, v165
	v_fma_f32 v104, v130, s56, v104
	v_fma_f32 v105, v131, s56, v105
	v_fma_f32 v102, v220, s56, v102
	v_fma_f32 v103, v221, s56, v103
	v_mul_f32_e32 v100, v160, v100
	v_mul_f32_e32 v101, v161, v101
	v_mul_f32_e32 v98, v158, v98
	v_mul_f32_e32 v99, v159, v99
	v_fma_f32 v100, v132, s56, v100
	v_fma_f32 v101, v133, s56, v101
	v_fma_f32 v98, v222, s56, v98
	v_fma_f32 v99, v223, s56, v99
	v_cvt_pk_bf16_f32 v102, v102, v103
	v_cvt_pk_bf16_f32 v103, v104, v105
	v_cvt_pk_bf16_f32 v104, v98, v99
	v_cvt_pk_bf16_f32 v105, v100, v101
	global_store_dwordx4 v[218:219], v[102:105], off
	s_nop 0
	global_load_dwordx2 v[102:103], v[214:215], off offset:384
	global_load_dwordx4 v[98:101], v[218:219], off offset:256
	global_load_dwordx2 v[248:249], v[214:215], off offset:1408
	global_load_dwordx4 v[130:133], v[216:217], off
	s_mov_b32 s0, 0x28000
	s_mov_b32 s1, 0
	v_lshl_add_u64 v[218:219], v[218:219], 0, s[0:1]
	s_waitcnt vmcnt(24)
	v_lshlrev_b32_e32 v220, 16, v134
	v_and_b32_e32 v221, 0xffff0000, v134
	v_lshlrev_b32_e32 v134, 16, v135
	v_and_b32_e32 v135, 0xffff0000, v135
	v_lshlrev_b32_e32 v222, 16, v136
	v_and_b32_e32 v223, 0xffff0000, v136
	v_lshlrev_b32_e32 v136, 16, v137
	v_and_b32_e32 v137, 0xffff0000, v137
	v_sub_f32_e32 v221, v221, v146
	v_sub_f32_e32 v220, v220, v146
	v_sub_f32_e32 v135, v135, v146
	v_sub_f32_e32 v134, v134, v146
	v_mul_f32_e32 v134, v147, v134
	v_mul_f32_e32 v135, v147, v135
	v_mul_f32_e32 v220, v147, v220
	v_mul_f32_e32 v221, v147, v221
	v_sub_f32_e32 v223, v223, v146
	v_sub_f32_e32 v222, v222, v146
	v_sub_f32_e32 v137, v137, v146
	v_sub_f32_e32 v136, v136, v146
	v_fma_f32 v220, v166, v220, v170
	v_fma_f32 v221, v167, v221, v171
	v_fma_f32 v134, v168, v134, v172
	v_fma_f32 v135, v169, v135, v173
	v_mul_f32_e32 v136, v147, v136
	v_mul_f32_e32 v137, v147, v137
	v_mul_f32_e32 v222, v147, v222
	v_mul_f32_e32 v223, v147, v223
	v_mul_f32_e32 v64, v176, v64
	v_mul_f32_e32 v65, v177, v65
	v_mul_f32_e32 v62, v174, v62
	v_mul_f32_e32 v63, v175, v63
	v_fma_f32 v222, v154, v222, v162
	v_fma_f32 v223, v155, v223, v163
	v_fma_f32 v136, v156, v136, v164
	v_fma_f32 v137, v157, v137, v165
	v_fma_f32 v64, v134, s56, v64
	v_fma_f32 v65, v135, s56, v65
	v_fma_f32 v62, v220, s56, v62
	v_fma_f32 v63, v221, s56, v63
	v_mul_f32_e32 v60, v160, v60
	v_mul_f32_e32 v61, v161, v61
	v_mul_f32_e32 v58, v158, v58
	v_mul_f32_e32 v59, v159, v59
	v_fma_f32 v60, v136, s56, v60
	v_fma_f32 v61, v137, s56, v61
	v_fma_f32 v58, v222, s56, v58
	v_fma_f32 v59, v223, s56, v59
	v_cvt_pk_bf16_f32 v62, v62, v63
	v_cvt_pk_bf16_f32 v63, v64, v65
	v_cvt_pk_bf16_f32 v64, v58, v59
	v_cvt_pk_bf16_f32 v65, v60, v61
	global_store_dwordx4 v[218:219], v[62:65], off
	s_nop 0
	global_load_dwordx2 v[62:63], v[214:215], off offset:1024
	global_load_dwordx4 v[58:61], v[218:219], off offset:256
	s_mov_b32 s0, 0x8000
	s_mov_b32 s1, 0
	v_lshl_add_u64 v[218:219], v[218:219], 0, s[0:1]
	s_waitcnt vmcnt(25)
	v_lshlrev_b32_e32 v220, 16, v138
	v_and_b32_e32 v221, 0xffff0000, v138
	v_lshlrev_b32_e32 v138, 16, v139
	v_and_b32_e32 v139, 0xffff0000, v139
	v_lshlrev_b32_e32 v222, 16, v140
	v_and_b32_e32 v223, 0xffff0000, v140
	v_lshlrev_b32_e32 v140, 16, v141
	v_and_b32_e32 v141, 0xffff0000, v141
	v_sub_f32_e32 v221, v221, v148
	v_sub_f32_e32 v220, v220, v148
	v_sub_f32_e32 v139, v139, v148
	v_sub_f32_e32 v138, v138, v148
	v_mul_f32_e32 v138, v149, v138
	v_mul_f32_e32 v139, v149, v139
	v_mul_f32_e32 v220, v149, v220
	v_mul_f32_e32 v221, v149, v221
	v_sub_f32_e32 v223, v223, v148
	v_sub_f32_e32 v222, v222, v148
	v_sub_f32_e32 v141, v141, v148
	v_sub_f32_e32 v140, v140, v148
	v_fma_f32 v220, v166, v220, v170
	v_fma_f32 v221, v167, v221, v171
	v_fma_f32 v138, v168, v138, v172
	v_fma_f32 v139, v169, v139, v173
	v_mul_f32_e32 v140, v149, v140
	v_mul_f32_e32 v141, v149, v141
	v_mul_f32_e32 v222, v149, v222
	v_mul_f32_e32 v223, v149, v223
	v_mul_f32_e32 v56, v176, v56
	v_mul_f32_e32 v57, v177, v57
	v_mul_f32_e32 v54, v174, v54
	v_mul_f32_e32 v55, v175, v55
	v_fma_f32 v222, v154, v222, v162
	v_fma_f32 v223, v155, v223, v163
	v_fma_f32 v140, v156, v140, v164
	v_fma_f32 v141, v157, v141, v165
	v_fma_f32 v56, v138, s56, v56
	v_fma_f32 v57, v139, s56, v57
	v_fma_f32 v54, v220, s56, v54
	v_fma_f32 v55, v221, s56, v55
	v_mul_f32_e32 v52, v160, v52
	v_mul_f32_e32 v53, v161, v53
	v_mul_f32_e32 v50, v158, v50
	v_mul_f32_e32 v51, v159, v51
	v_fma_f32 v52, v140, s56, v52
	v_fma_f32 v53, v141, s56, v53
	v_fma_f32 v50, v222, s56, v50
	v_fma_f32 v51, v223, s56, v51
	v_cvt_pk_bf16_f32 v54, v54, v55
	v_cvt_pk_bf16_f32 v55, v56, v57
	v_cvt_pk_bf16_f32 v56, v50, v51
	v_cvt_pk_bf16_f32 v57, v52, v53
	global_store_dwordx4 v[218:219], v[54:57], off
	s_nop 0
	global_load_dwordx2 v[54:55], v[214:215], off offset:1152
	global_load_dwordx4 v[50:53], v[218:219], off offset:256
	v_lshl_add_u64 v[218:219], v[218:219], 0, s[0:1]
	s_waitcnt vmcnt(26)
	v_lshlrev_b32_e32 v220, 16, v142
	v_and_b32_e32 v221, 0xffff0000, v142
	v_lshlrev_b32_e32 v142, 16, v143
	v_and_b32_e32 v143, 0xffff0000, v143
	v_lshlrev_b32_e32 v222, 16, v144
	v_and_b32_e32 v223, 0xffff0000, v144
	v_lshlrev_b32_e32 v144, 16, v145
	v_and_b32_e32 v145, 0xffff0000, v145
	v_sub_f32_e32 v221, v221, v150
	v_sub_f32_e32 v220, v220, v150
	v_sub_f32_e32 v143, v143, v150
	v_sub_f32_e32 v142, v142, v150
	v_mul_f32_e32 v142, v151, v142
	v_mul_f32_e32 v143, v151, v143
	v_mul_f32_e32 v220, v151, v220
	v_mul_f32_e32 v221, v151, v221
	v_sub_f32_e32 v223, v223, v150
	v_sub_f32_e32 v222, v222, v150
	v_sub_f32_e32 v145, v145, v150
	v_sub_f32_e32 v144, v144, v150
	v_fma_f32 v220, v166, v220, v170
	v_fma_f32 v221, v167, v221, v171
	v_fma_f32 v142, v168, v142, v172
	v_fma_f32 v143, v169, v143, v173
	v_mul_f32_e32 v144, v151, v144
	v_mul_f32_e32 v145, v151, v145
	v_mul_f32_e32 v222, v151, v222
	v_mul_f32_e32 v223, v151, v223
	v_mul_f32_e32 v48, v176, v48
	v_mul_f32_e32 v49, v177, v49
	v_mul_f32_e32 v46, v174, v46
	v_mul_f32_e32 v47, v175, v47
	v_fma_f32 v222, v154, v222, v162
	v_fma_f32 v223, v155, v223, v163
	v_fma_f32 v144, v156, v144, v164
	v_fma_f32 v145, v157, v145, v165
	v_fma_f32 v48, v142, s56, v48
	v_fma_f32 v49, v143, s56, v49
	v_fma_f32 v46, v220, s56, v46
	v_fma_f32 v47, v221, s56, v47
	v_mul_f32_e32 v44, v160, v44
	v_mul_f32_e32 v45, v161, v45
	v_mul_f32_e32 v42, v158, v42
	v_mul_f32_e32 v43, v159, v43
	v_fma_f32 v44, v144, s56, v44
	v_fma_f32 v45, v145, s56, v45
	v_fma_f32 v42, v222, s56, v42
	v_fma_f32 v43, v223, s56, v43
	v_cvt_pk_bf16_f32 v46, v46, v47
	v_cvt_pk_bf16_f32 v47, v48, v49
	v_cvt_pk_bf16_f32 v48, v42, v43
	v_cvt_pk_bf16_f32 v49, v44, v45
	global_store_dwordx4 v[218:219], v[46:49], off
	s_nop 0
	global_load_dwordx2 v[46:47], v[214:215], off offset:1280
	global_load_dwordx4 v[42:45], v[218:219], off offset:256
	v_lshl_add_u64 v[218:219], v[218:219], 0, s[0:1]
	s_waitcnt vmcnt(9)
	v_lshlrev_b32_e32 v220, 16, v130
	v_and_b32_e32 v221, 0xffff0000, v130
	v_lshlrev_b32_e32 v130, 16, v131
	v_and_b32_e32 v131, 0xffff0000, v131
	v_lshlrev_b32_e32 v222, 16, v132
	v_and_b32_e32 v223, 0xffff0000, v132
	v_lshlrev_b32_e32 v132, 16, v133
	v_and_b32_e32 v133, 0xffff0000, v133
	v_sub_f32_e32 v221, v221, v248
	v_sub_f32_e32 v220, v220, v248
	v_sub_f32_e32 v131, v131, v248
	v_sub_f32_e32 v130, v130, v248
	v_mul_f32_e32 v130, v249, v130
	v_mul_f32_e32 v131, v249, v131
	v_mul_f32_e32 v220, v249, v220
	v_mul_f32_e32 v221, v249, v221
	v_sub_f32_e32 v223, v223, v248
	v_sub_f32_e32 v222, v222, v248
	v_sub_f32_e32 v133, v133, v248
	v_sub_f32_e32 v132, v132, v248
	v_fma_f32 v220, v166, v220, v170
	v_fma_f32 v221, v167, v221, v171
	v_fma_f32 v130, v168, v130, v172
	v_fma_f32 v131, v169, v131, v173
	v_mul_f32_e32 v132, v249, v132
	v_mul_f32_e32 v133, v249, v133
	v_mul_f32_e32 v222, v249, v222
	v_mul_f32_e32 v223, v249, v223
	v_mul_f32_e32 v40, v176, v40
	v_mul_f32_e32 v41, v177, v41
	v_mul_f32_e32 v38, v174, v38
	v_mul_f32_e32 v39, v175, v39
	v_fma_f32 v222, v154, v222, v162
	v_fma_f32 v223, v155, v223, v163
	v_fma_f32 v132, v156, v132, v164
	v_fma_f32 v133, v157, v133, v165
	v_fma_f32 v40, v130, s56, v40
	v_fma_f32 v41, v131, s56, v41
	v_fma_f32 v38, v220, s56, v38
	v_fma_f32 v39, v221, s56, v39
	v_mul_f32_e32 v36, v160, v36
	v_mul_f32_e32 v37, v161, v37
	v_mul_f32_e32 v34, v158, v34
	v_mul_f32_e32 v35, v159, v35
	v_fma_f32 v36, v132, s56, v36
	v_fma_f32 v37, v133, s56, v37
	v_fma_f32 v34, v222, s56, v34
	v_fma_f32 v35, v223, s56, v35
	v_cvt_pk_bf16_f32 v38, v38, v39
	v_cvt_pk_bf16_f32 v39, v40, v41
	v_cvt_pk_bf16_f32 v40, v34, v35
	v_cvt_pk_bf16_f32 v41, v36, v37
	global_store_dwordx4 v[218:219], v[38:41], off
	s_nop 0
	global_load_dwordx2 v[38:39], v[214:215], off offset:1408
	global_load_dwordx4 v[34:37], v[218:219], off offset:256
	s_mov_b32 s0, 0xfffa8000
	s_mov_b32 s1, 0xffffffff
	v_lshl_add_u64 v[216:217], v[216:217], 0, s[0:1]
	s_waitcnt vmcnt(17)
	v_lshlrev_b32_e32 v220, 16, v178
	v_and_b32_e32 v221, 0xffff0000, v178
	v_lshlrev_b32_e32 v178, 16, v179
	v_and_b32_e32 v179, 0xffff0000, v179
	v_lshlrev_b32_e32 v222, 16, v180
	v_and_b32_e32 v223, 0xffff0000, v180
	v_lshlrev_b32_e32 v180, 16, v181
	v_and_b32_e32 v181, 0xffff0000, v181
	v_sub_f32_e32 v221, v221, v194
	v_sub_f32_e32 v220, v220, v194
	v_sub_f32_e32 v179, v179, v194
	v_sub_f32_e32 v178, v178, v194
	v_mul_f32_e32 v178, v195, v178
	v_mul_f32_e32 v179, v195, v179
	v_mul_f32_e32 v220, v195, v220
	v_mul_f32_e32 v221, v195, v221
	v_sub_f32_e32 v223, v223, v194
	v_sub_f32_e32 v222, v222, v194
	v_sub_f32_e32 v181, v181, v194
	v_sub_f32_e32 v180, v180, v194
	v_fma_f32 v220, v118, v220, v110
	v_fma_f32 v221, v119, v221, v111
	v_fma_f32 v178, v120, v178, v112
	v_fma_f32 v179, v121, v179, v113
	v_mul_f32_e32 v180, v195, v180
	v_mul_f32_e32 v181, v195, v181
	v_mul_f32_e32 v222, v195, v222
	v_mul_f32_e32 v223, v195, v223
	v_mul_f32_e32 v96, v128, v96
	v_mul_f32_e32 v97, v129, v97
	v_mul_f32_e32 v94, v126, v94
	v_mul_f32_e32 v95, v127, v95
	v_fma_f32 v222, v114, v222, v106
	v_fma_f32 v223, v115, v223, v107
	v_fma_f32 v180, v116, v180, v108
	v_fma_f32 v181, v117, v181, v109
	v_fma_f32 v96, v178, s56, v96
	v_fma_f32 v97, v179, s56, v97
	v_fma_f32 v94, v220, s56, v94
	v_fma_f32 v95, v221, s56, v95
	v_mul_f32_e32 v92, v124, v92
	v_mul_f32_e32 v93, v125, v93
	v_mul_f32_e32 v90, v122, v90
	v_mul_f32_e32 v91, v123, v91
	v_fma_f32 v92, v180, s56, v92
	v_fma_f32 v93, v181, s56, v93
	v_fma_f32 v90, v222, s56, v90
	v_fma_f32 v91, v223, s56, v91
	v_cvt_pk_bf16_f32 v94, v94, v95
	v_cvt_pk_bf16_f32 v95, v96, v97
	v_cvt_pk_bf16_f32 v96, v90, v91
	v_cvt_pk_bf16_f32 v97, v92, v93
	global_store_dwordx4 v[216:217], v[94:97], off offset:256
	s_mov_b32 s0, 0x8000
	s_mov_b32 s1, 0
	v_lshl_add_u64 v[216:217], v[216:217], 0, s[0:1]
	s_waitcnt vmcnt(18)
	v_lshlrev_b32_e32 v220, 16, v182
	v_and_b32_e32 v221, 0xffff0000, v182
	v_lshlrev_b32_e32 v182, 16, v183
	v_and_b32_e32 v183, 0xffff0000, v183
	v_lshlrev_b32_e32 v222, 16, v184
	v_and_b32_e32 v223, 0xffff0000, v184
	v_lshlrev_b32_e32 v184, 16, v185
	v_and_b32_e32 v185, 0xffff0000, v185
	v_sub_f32_e32 v221, v221, v196
	v_sub_f32_e32 v220, v220, v196
	v_sub_f32_e32 v183, v183, v196
	v_sub_f32_e32 v182, v182, v196
	v_mul_f32_e32 v182, v197, v182
	v_mul_f32_e32 v183, v197, v183
	v_mul_f32_e32 v220, v197, v220
	v_mul_f32_e32 v221, v197, v221
	v_sub_f32_e32 v223, v223, v196
	v_sub_f32_e32 v222, v222, v196
	v_sub_f32_e32 v185, v185, v196
	v_sub_f32_e32 v184, v184, v196
	v_fma_f32 v220, v118, v220, v110
	v_fma_f32 v221, v119, v221, v111
	v_fma_f32 v182, v120, v182, v112
	v_fma_f32 v183, v121, v183, v113
	v_mul_f32_e32 v184, v197, v184
	v_mul_f32_e32 v185, v197, v185
	v_mul_f32_e32 v222, v197, v222
	v_mul_f32_e32 v223, v197, v223
	v_mul_f32_e32 v88, v128, v88
	v_mul_f32_e32 v89, v129, v89
	v_mul_f32_e32 v86, v126, v86
	v_mul_f32_e32 v87, v127, v87
	v_fma_f32 v222, v114, v222, v106
	v_fma_f32 v223, v115, v223, v107
	v_fma_f32 v184, v116, v184, v108
	v_fma_f32 v185, v117, v185, v109
	v_fma_f32 v88, v182, s56, v88
	v_fma_f32 v89, v183, s56, v89
	v_fma_f32 v86, v220, s56, v86
	v_fma_f32 v87, v221, s56, v87
	v_mul_f32_e32 v84, v124, v84
	v_mul_f32_e32 v85, v125, v85
	v_mul_f32_e32 v82, v122, v82
	v_mul_f32_e32 v83, v123, v83
	v_fma_f32 v84, v184, s56, v84
	v_fma_f32 v85, v185, s56, v85
	v_fma_f32 v82, v222, s56, v82
	v_fma_f32 v83, v223, s56, v83
	v_cvt_pk_bf16_f32 v86, v86, v87
	v_cvt_pk_bf16_f32 v87, v88, v89
	v_cvt_pk_bf16_f32 v88, v82, v83
	v_cvt_pk_bf16_f32 v89, v84, v85
	global_store_dwordx4 v[216:217], v[86:89], off offset:256
	v_lshl_add_u64 v[216:217], v[216:217], 0, s[0:1]
	s_waitcnt vmcnt(19)
	v_lshlrev_b32_e32 v220, 16, v186
	v_and_b32_e32 v221, 0xffff0000, v186
	v_lshlrev_b32_e32 v186, 16, v187
	v_and_b32_e32 v187, 0xffff0000, v187
	v_lshlrev_b32_e32 v222, 16, v188
	v_and_b32_e32 v223, 0xffff0000, v188
	v_lshlrev_b32_e32 v188, 16, v189
	v_and_b32_e32 v189, 0xffff0000, v189
	v_sub_f32_e32 v221, v221, v232
	v_sub_f32_e32 v220, v220, v232
	v_sub_f32_e32 v187, v187, v232
	v_sub_f32_e32 v186, v186, v232
	v_mul_f32_e32 v186, v233, v186
	v_mul_f32_e32 v187, v233, v187
	v_mul_f32_e32 v220, v233, v220
	v_mul_f32_e32 v221, v233, v221
	v_sub_f32_e32 v223, v223, v232
	v_sub_f32_e32 v222, v222, v232
	v_sub_f32_e32 v189, v189, v232
	v_sub_f32_e32 v188, v188, v232
	v_fma_f32 v220, v118, v220, v110
	v_fma_f32 v221, v119, v221, v111
	v_fma_f32 v186, v120, v186, v112
	v_fma_f32 v187, v121, v187, v113
	v_mul_f32_e32 v188, v233, v188
	v_mul_f32_e32 v189, v233, v189
	v_mul_f32_e32 v222, v233, v222
	v_mul_f32_e32 v223, v233, v223
	v_mul_f32_e32 v80, v128, v80
	v_mul_f32_e32 v81, v129, v81
	v_mul_f32_e32 v78, v126, v78
	v_mul_f32_e32 v79, v127, v79
	v_fma_f32 v222, v114, v222, v106
	v_fma_f32 v223, v115, v223, v107
	v_fma_f32 v188, v116, v188, v108
	v_fma_f32 v189, v117, v189, v109
	v_fma_f32 v80, v186, s56, v80
	v_fma_f32 v81, v187, s56, v81
	v_fma_f32 v78, v220, s56, v78
	v_fma_f32 v79, v221, s56, v79
	v_mul_f32_e32 v76, v124, v76
	v_mul_f32_e32 v77, v125, v77
	v_mul_f32_e32 v74, v122, v74
	v_mul_f32_e32 v75, v123, v75
	v_fma_f32 v76, v188, s56, v76
	v_fma_f32 v77, v189, s56, v77
	v_fma_f32 v74, v222, s56, v74
	v_fma_f32 v75, v223, s56, v75
	v_cvt_pk_bf16_f32 v78, v78, v79
	v_cvt_pk_bf16_f32 v79, v80, v81
	v_cvt_pk_bf16_f32 v80, v74, v75
	v_cvt_pk_bf16_f32 v81, v76, v77
	global_store_dwordx4 v[216:217], v[78:81], off offset:256
	v_lshl_add_u64 v[216:217], v[216:217], 0, s[0:1]
	s_waitcnt vmcnt(17)
	v_lshlrev_b32_e32 v220, 16, v98
	v_and_b32_e32 v221, 0xffff0000, v98
	v_lshlrev_b32_e32 v98, 16, v99
	v_and_b32_e32 v99, 0xffff0000, v99
	v_lshlrev_b32_e32 v222, 16, v100
	v_and_b32_e32 v223, 0xffff0000, v100
	v_lshlrev_b32_e32 v100, 16, v101
	v_and_b32_e32 v101, 0xffff0000, v101
	v_sub_f32_e32 v221, v221, v102
	v_sub_f32_e32 v220, v220, v102
	v_sub_f32_e32 v99, v99, v102
	v_sub_f32_e32 v98, v98, v102
	v_mul_f32_e32 v98, v103, v98
	v_mul_f32_e32 v99, v103, v99
	v_mul_f32_e32 v220, v103, v220
	v_mul_f32_e32 v221, v103, v221
	v_sub_f32_e32 v223, v223, v102
	v_sub_f32_e32 v222, v222, v102
	v_sub_f32_e32 v101, v101, v102
	v_sub_f32_e32 v100, v100, v102
	v_fma_f32 v220, v118, v220, v110
	v_fma_f32 v221, v119, v221, v111
	v_fma_f32 v98, v120, v98, v112
	v_fma_f32 v99, v121, v99, v113
	v_mul_f32_e32 v100, v103, v100
	v_mul_f32_e32 v101, v103, v101
	v_mul_f32_e32 v222, v103, v222
	v_mul_f32_e32 v223, v103, v223
	v_mul_f32_e32 v72, v128, v72
	v_mul_f32_e32 v73, v129, v73
	v_mul_f32_e32 v70, v126, v70
	v_mul_f32_e32 v71, v127, v71
	v_fma_f32 v222, v114, v222, v106
	v_fma_f32 v223, v115, v223, v107
	v_fma_f32 v100, v116, v100, v108
	v_fma_f32 v101, v117, v101, v109
	v_fma_f32 v72, v98, s56, v72
	v_fma_f32 v73, v99, s56, v73
	v_fma_f32 v70, v220, s56, v70
	v_fma_f32 v71, v221, s56, v71
	v_mul_f32_e32 v68, v124, v68
	v_mul_f32_e32 v69, v125, v69
	v_mul_f32_e32 v66, v122, v66
	v_mul_f32_e32 v67, v123, v67
	v_fma_f32 v68, v100, s56, v68
	v_fma_f32 v69, v101, s56, v69
	v_fma_f32 v66, v222, s56, v66
	v_fma_f32 v67, v223, s56, v67
	v_cvt_pk_bf16_f32 v70, v70, v71
	v_cvt_pk_bf16_f32 v71, v72, v73
	v_cvt_pk_bf16_f32 v72, v66, v67
	v_cvt_pk_bf16_f32 v73, v68, v69
	global_store_dwordx4 v[216:217], v[70:73], off offset:256
	s_mov_b32 s0, 0x28000
	s_mov_b32 s1, 0
	v_lshl_add_u64 v[216:217], v[216:217], 0, s[0:1]
	s_waitcnt vmcnt(13)
	v_lshlrev_b32_e32 v220, 16, v58
	v_and_b32_e32 v221, 0xffff0000, v58
	v_lshlrev_b32_e32 v58, 16, v59
	v_and_b32_e32 v59, 0xffff0000, v59
	v_lshlrev_b32_e32 v222, 16, v60
	v_and_b32_e32 v223, 0xffff0000, v60
	v_lshlrev_b32_e32 v60, 16, v61
	v_and_b32_e32 v61, 0xffff0000, v61
	v_sub_f32_e32 v221, v221, v62
	v_sub_f32_e32 v220, v220, v62
	v_sub_f32_e32 v59, v59, v62
	v_sub_f32_e32 v58, v58, v62
	v_mul_f32_e32 v58, v63, v58
	v_mul_f32_e32 v59, v63, v59
	v_mul_f32_e32 v220, v63, v220
	v_mul_f32_e32 v221, v63, v221
	v_sub_f32_e32 v223, v223, v62
	v_sub_f32_e32 v222, v222, v62
	v_sub_f32_e32 v61, v61, v62
	v_sub_f32_e32 v60, v60, v62
	v_fma_f32 v220, v118, v220, v110
	v_fma_f32 v221, v119, v221, v111
	v_fma_f32 v58, v120, v58, v112
	v_fma_f32 v59, v121, v59, v113
	v_mul_f32_e32 v60, v63, v60
	v_mul_f32_e32 v61, v63, v61
	v_mul_f32_e32 v222, v63, v222
	v_mul_f32_e32 v223, v63, v223
	v_mul_f32_e32 v32, v128, v32
	v_mul_f32_e32 v33, v129, v33
	v_mul_f32_e32 v30, v126, v30
	v_mul_f32_e32 v31, v127, v31
	v_fma_f32 v222, v114, v222, v106
	v_fma_f32 v223, v115, v223, v107
	v_fma_f32 v60, v116, v60, v108
	v_fma_f32 v61, v117, v61, v109
	v_fma_f32 v32, v58, s56, v32
	v_fma_f32 v33, v59, s56, v33
	v_fma_f32 v30, v220, s56, v30
	v_fma_f32 v31, v221, s56, v31
	v_mul_f32_e32 v28, v124, v28
	v_mul_f32_e32 v29, v125, v29
	v_mul_f32_e32 v26, v122, v26
	v_mul_f32_e32 v27, v123, v27
	v_fma_f32 v28, v60, s56, v28
	v_fma_f32 v29, v61, s56, v29
	v_fma_f32 v26, v222, s56, v26
	v_fma_f32 v27, v223, s56, v27
	v_cvt_pk_bf16_f32 v30, v30, v31
	v_cvt_pk_bf16_f32 v31, v32, v33
	v_cvt_pk_bf16_f32 v32, v26, v27
	v_cvt_pk_bf16_f32 v33, v28, v29
	global_store_dwordx4 v[216:217], v[30:33], off offset:256
	s_mov_b32 s0, 0x8000
	s_mov_b32 s1, 0
	v_lshl_add_u64 v[216:217], v[216:217], 0, s[0:1]
	s_waitcnt vmcnt(11)
	v_lshlrev_b32_e32 v220, 16, v50
	v_and_b32_e32 v221, 0xffff0000, v50
	v_lshlrev_b32_e32 v50, 16, v51
	v_and_b32_e32 v51, 0xffff0000, v51
	v_lshlrev_b32_e32 v222, 16, v52
	v_and_b32_e32 v223, 0xffff0000, v52
	v_lshlrev_b32_e32 v52, 16, v53
	v_and_b32_e32 v53, 0xffff0000, v53
	v_sub_f32_e32 v221, v221, v54
	v_sub_f32_e32 v220, v220, v54
	v_sub_f32_e32 v51, v51, v54
	v_sub_f32_e32 v50, v50, v54
	v_mul_f32_e32 v50, v55, v50
	v_mul_f32_e32 v51, v55, v51
	v_mul_f32_e32 v220, v55, v220
	v_mul_f32_e32 v221, v55, v221
	v_sub_f32_e32 v223, v223, v54
	v_sub_f32_e32 v222, v222, v54
	v_sub_f32_e32 v53, v53, v54
	v_sub_f32_e32 v52, v52, v54
	v_fma_f32 v220, v118, v220, v110
	v_fma_f32 v221, v119, v221, v111
	v_fma_f32 v50, v120, v50, v112
	v_fma_f32 v51, v121, v51, v113
	v_mul_f32_e32 v52, v55, v52
	v_mul_f32_e32 v53, v55, v53
	v_mul_f32_e32 v222, v55, v222
	v_mul_f32_e32 v223, v55, v223
	v_mul_f32_e32 v24, v128, v24
	v_mul_f32_e32 v25, v129, v25
	v_mul_f32_e32 v22, v126, v22
	v_mul_f32_e32 v23, v127, v23
	v_fma_f32 v222, v114, v222, v106
	v_fma_f32 v223, v115, v223, v107
	v_fma_f32 v52, v116, v52, v108
	v_fma_f32 v53, v117, v53, v109
	v_fma_f32 v24, v50, s56, v24
	v_fma_f32 v25, v51, s56, v25
	v_fma_f32 v22, v220, s56, v22
	v_fma_f32 v23, v221, s56, v23
	v_mul_f32_e32 v20, v124, v20
	v_mul_f32_e32 v21, v125, v21
	v_mul_f32_e32 v18, v122, v18
	v_mul_f32_e32 v19, v123, v19
	v_fma_f32 v20, v52, s56, v20
	v_fma_f32 v21, v53, s56, v21
	v_fma_f32 v18, v222, s56, v18
	v_fma_f32 v19, v223, s56, v19
	v_cvt_pk_bf16_f32 v22, v22, v23
	v_cvt_pk_bf16_f32 v23, v24, v25
	v_cvt_pk_bf16_f32 v24, v18, v19
	v_cvt_pk_bf16_f32 v25, v20, v21
	global_store_dwordx4 v[216:217], v[22:25], off offset:256
	v_lshl_add_u64 v[216:217], v[216:217], 0, s[0:1]
	s_waitcnt vmcnt(9)
	v_lshlrev_b32_e32 v220, 16, v42
	v_and_b32_e32 v221, 0xffff0000, v42
	v_lshlrev_b32_e32 v42, 16, v43
	v_and_b32_e32 v43, 0xffff0000, v43
	v_lshlrev_b32_e32 v222, 16, v44
	v_and_b32_e32 v223, 0xffff0000, v44
	v_lshlrev_b32_e32 v44, 16, v45
	v_and_b32_e32 v45, 0xffff0000, v45
	v_sub_f32_e32 v221, v221, v46
	v_sub_f32_e32 v220, v220, v46
	v_sub_f32_e32 v43, v43, v46
	v_sub_f32_e32 v42, v42, v46
	v_mul_f32_e32 v42, v47, v42
	v_mul_f32_e32 v43, v47, v43
	v_mul_f32_e32 v220, v47, v220
	v_mul_f32_e32 v221, v47, v221
	v_sub_f32_e32 v223, v223, v46
	v_sub_f32_e32 v222, v222, v46
	v_sub_f32_e32 v45, v45, v46
	v_sub_f32_e32 v44, v44, v46
	v_fma_f32 v220, v118, v220, v110
	v_fma_f32 v221, v119, v221, v111
	v_fma_f32 v42, v120, v42, v112
	v_fma_f32 v43, v121, v43, v113
	v_mul_f32_e32 v44, v47, v44
	v_mul_f32_e32 v45, v47, v45
	v_mul_f32_e32 v222, v47, v222
	v_mul_f32_e32 v223, v47, v223
	v_mul_f32_e32 v16, v128, v16
	v_mul_f32_e32 v17, v129, v17
	v_mul_f32_e32 v14, v126, v14
	v_mul_f32_e32 v15, v127, v15
	v_fma_f32 v222, v114, v222, v106
	v_fma_f32 v223, v115, v223, v107
	v_fma_f32 v44, v116, v44, v108
	v_fma_f32 v45, v117, v45, v109
	v_fma_f32 v16, v42, s56, v16
	v_fma_f32 v17, v43, s56, v17
	v_fma_f32 v14, v220, s56, v14
	v_fma_f32 v15, v221, s56, v15
	v_mul_f32_e32 v12, v124, v12
	v_mul_f32_e32 v13, v125, v13
	v_mul_f32_e32 v10, v122, v10
	v_mul_f32_e32 v11, v123, v11
	v_fma_f32 v12, v44, s56, v12
	v_fma_f32 v13, v45, s56, v13
	v_fma_f32 v10, v222, s56, v10
	v_fma_f32 v11, v223, s56, v11
	v_cvt_pk_bf16_f32 v14, v14, v15
	v_cvt_pk_bf16_f32 v15, v16, v17
	v_cvt_pk_bf16_f32 v16, v10, v11
	v_cvt_pk_bf16_f32 v17, v12, v13
	global_store_dwordx4 v[216:217], v[14:17], off offset:256
	v_lshl_add_u64 v[216:217], v[216:217], 0, s[0:1]
	s_waitcnt vmcnt(7)
	v_lshlrev_b32_e32 v220, 16, v34
	v_and_b32_e32 v221, 0xffff0000, v34
	v_lshlrev_b32_e32 v34, 16, v35
	v_and_b32_e32 v35, 0xffff0000, v35
	v_lshlrev_b32_e32 v222, 16, v36
	v_and_b32_e32 v223, 0xffff0000, v36
	v_lshlrev_b32_e32 v36, 16, v37
	v_and_b32_e32 v37, 0xffff0000, v37
	v_sub_f32_e32 v221, v221, v38
	v_sub_f32_e32 v220, v220, v38
	v_sub_f32_e32 v35, v35, v38
	v_sub_f32_e32 v34, v34, v38
	v_mul_f32_e32 v34, v39, v34
	v_mul_f32_e32 v35, v39, v35
	v_mul_f32_e32 v220, v39, v220
	v_mul_f32_e32 v221, v39, v221
	v_sub_f32_e32 v223, v223, v38
	v_sub_f32_e32 v222, v222, v38
	v_sub_f32_e32 v37, v37, v38
	v_sub_f32_e32 v36, v36, v38
	v_fma_f32 v220, v118, v220, v110
	v_fma_f32 v221, v119, v221, v111
	v_fma_f32 v34, v120, v34, v112
	v_fma_f32 v35, v121, v35, v113
	v_mul_f32_e32 v36, v39, v36
	v_mul_f32_e32 v37, v39, v37
	v_mul_f32_e32 v222, v39, v222
	v_mul_f32_e32 v223, v39, v223
	v_mul_f32_e32 v8, v128, v8
	v_mul_f32_e32 v9, v129, v9
	v_mul_f32_e32 v6, v126, v6
	v_mul_f32_e32 v7, v127, v7
	v_fma_f32 v222, v114, v222, v106
	v_fma_f32 v223, v115, v223, v107
	v_fma_f32 v36, v116, v36, v108
	v_fma_f32 v37, v117, v37, v109
	v_fma_f32 v8, v34, s56, v8
	v_fma_f32 v9, v35, s56, v9
	v_fma_f32 v6, v220, s56, v6
	v_fma_f32 v7, v221, s56, v7
	v_mul_f32_e32 v4, v124, v4
	v_mul_f32_e32 v5, v125, v5
	v_mul_f32_e32 v2, v122, v2
	v_mul_f32_e32 v3, v123, v3
	v_fma_f32 v4, v36, s56, v4
	v_fma_f32 v5, v37, s56, v5
	v_fma_f32 v2, v222, s56, v2
	v_fma_f32 v3, v223, s56, v3
	v_cvt_pk_bf16_f32 v6, v6, v7
	v_cvt_pk_bf16_f32 v7, v8, v9
	v_cvt_pk_bf16_f32 v8, v2, v3
	v_cvt_pk_bf16_f32 v9, v4, v5
	global_store_dwordx4 v[216:217], v[6:9], off offset:256
	s_mov_b64 s[14:15], 0

.LBB0_513:
	v_add_u32_e32 v0, s40, v10
	v_mad_i64_i32 v[6:7], s[0:1], v0, s4, v[2:3]
	s_barrier
	global_load_dword v0, v[6:7], off
	v_add_u32_e32 v7, 0x420, v13
	v_add_u32_e32 v77, 0x400, v13
	s_ashr_i32 s41, s40, 31
	s_add_i32 s3, s3, s5
	s_waitcnt vmcnt(0)
	ds_write_b32 v11, v0
	s_waitcnt lgkmcnt(0)
	s_barrier
	ds_read_b32 v0, v12 offset:2048
	ds_read_b32 v6, v14 offset:2048
	ds_read_b32 v8, v15 offset:2048
	ds_read_b32 v78, v16 offset:2048
	ds_read_b32 v80, v17 offset:2048
	ds_read_b32 v82, v18 offset:2048
	ds_read_b32 v84, v19 offset:2048
	ds_read_b32 v86, v20 offset:2048
	ds_read_b32 v88, v21 offset:2048
	ds_read2_b32 v[90:91], v13 offset0:8 offset1:9
	ds_read2_b32 v[92:93], v7 offset1:1
	ds_read2_b32 v[94:95], v13 offset1:1
	ds_read2_b32 v[96:97], v77 offset1:1
	s_waitcnt lgkmcnt(1)
	v_mov_b32_e32 v98, v94
	s_waitcnt lgkmcnt(0)
	v_mov_b32_e32 v99, v96
	v_fma_f32 v98, v0, v98, 0
	v_fma_f32 v99, v0, v99, 0
	v_mov_b32_e32 v96, v95
	v_add_u32_e32 v0, 0x408, v13
	v_fma_f32 v7, v6, v97, v99
	v_fma_f32 v6, v6, v96, v98
	ds_read2_b32 v[94:95], v13 offset0:2 offset1:3
	ds_read2_b32 v[96:97], v0 offset1:1
	v_add_u32_e32 v0, 0x410, v13
	s_waitcnt lgkmcnt(1)
	v_mov_b32_e32 v98, v94
	s_waitcnt lgkmcnt(0)
	v_mov_b32_e32 v99, v96
	v_fma_f32 v6, v8, v98, v6
	v_fma_f32 v7, v8, v99, v7
	v_mov_b32_e32 v96, v95
	v_fma_f32 v6, v78, v96, v6
	v_fma_f32 v7, v78, v97, v7
	ds_read2_b32 v[8:9], v13 offset0:4 offset1:5
	ds_read2_b32 v[78:79], v0 offset1:1
	v_add_u32_e32 v0, 0x418, v13
	s_waitcnt lgkmcnt(1)
	v_mov_b32_e32 v94, v8
	s_waitcnt lgkmcnt(0)
	v_mov_b32_e32 v95, v78
	v_fma_f32 v6, v80, v94, v6
	v_fma_f32 v7, v80, v95, v7
	v_mov_b32_e32 v78, v9
	v_fma_f32 v6, v82, v78, v6
	v_fma_f32 v7, v82, v79, v7
	ds_read2_b32 v[8:9], v13 offset0:6 offset1:7
	ds_read2_b32 v[78:79], v0 offset1:1
	s_waitcnt lgkmcnt(1)
	v_mov_b32_e32 v80, v8
	s_waitcnt lgkmcnt(0)
	v_mov_b32_e32 v81, v78
	v_fma_f32 v6, v84, v80, v6
	v_fma_f32 v7, v84, v81, v7
	v_mov_b32_e32 v78, v9
	v_fma_f32 v6, v86, v78, v6
	v_fma_f32 v7, v86, v79, v7
	ds_read_b32 v78, v22 offset:2048
	v_mov_b32_e32 v8, v90
	v_mov_b32_e32 v9, v92
	v_fma_f32 v8, v88, v8, v6
	v_fma_f32 v9, v88, v9, v7
	v_mov_b32_e32 v92, v91
	v_add_u32_e32 v7, 0x428, v13
	ds_read_b32 v80, v23 offset:2048
	ds_read_b32 v82, v24 offset:2048
	ds_read_b32 v84, v25 offset:2048
	ds_read_b32 v86, v26 offset:2048
	ds_read_b32 v88, v27 offset:2048
	ds_read_b32 v90, v28 offset:2048
	ds_read_b32 v94, v29 offset:2048
	ds_read_b32 v96, v30 offset:2048
	ds_read_b32 v6, v31 offset:2048
	ds_read_b32 v0, v32 offset:2048
	s_waitcnt lgkmcnt(10)
	v_fma_f32 v8, v78, v92, v8
	v_fma_f32 v9, v78, v93, v9
	ds_read2_b32 v[78:79], v13 offset0:10 offset1:11
	ds_read2_b32 v[92:93], v7 offset1:1
	v_add_u32_e32 v7, 0x430, v13
	s_waitcnt lgkmcnt(1)
	v_mov_b32_e32 v98, v78
	s_waitcnt lgkmcnt(0)
	v_mov_b32_e32 v99, v92
	v_fma_f32 v8, v80, v98, v8
	v_fma_f32 v9, v80, v99, v9
	v_mov_b32_e32 v92, v79
	ds_read2_b32 v[78:79], v13 offset0:12 offset1:13
	ds_read2_b32 v[80:81], v7 offset1:1
	v_fma_f32 v8, v82, v92, v8
	v_fma_f32 v9, v82, v93, v9
	v_add_u32_e32 v7, 0x438, v13
	s_waitcnt lgkmcnt(1)
	v_mov_b32_e32 v82, v78
	s_waitcnt lgkmcnt(0)
	v_mov_b32_e32 v83, v80
	v_fma_f32 v8, v84, v82, v8
	v_fma_f32 v9, v84, v83, v9
	v_mov_b32_e32 v80, v79
	v_fma_f32 v8, v86, v80, v8
	v_fma_f32 v9, v86, v81, v9
	ds_read2_b32 v[78:79], v13 offset0:14 offset1:15
	ds_read2_b32 v[80:81], v7 offset1:1
	v_add_u32_e32 v7, 0x440, v13
	s_waitcnt lgkmcnt(1)
	v_mov_b32_e32 v82, v78
	s_waitcnt lgkmcnt(0)
	v_mov_b32_e32 v83, v80
	v_fma_f32 v8, v88, v82, v8
	v_fma_f32 v9, v88, v83, v9
	v_mov_b32_e32 v80, v79
	v_fma_f32 v8, v90, v80, v8
	v_fma_f32 v9, v90, v81, v9
	ds_read2_b32 v[78:79], v13 offset0:16 offset1:17
	ds_read2_b32 v[80:81], v7 offset1:1
	v_add_u32_e32 v7, 0x448, v13
	s_waitcnt lgkmcnt(1)
	v_mov_b32_e32 v82, v78
	s_waitcnt lgkmcnt(0)
	v_mov_b32_e32 v83, v80
	v_fma_f32 v8, v94, v82, v8
	v_fma_f32 v9, v94, v83, v9
	v_mov_b32_e32 v80, v79
	v_fma_f32 v8, v96, v80, v8
	v_fma_f32 v9, v96, v81, v9
	ds_read2_b32 v[78:79], v13 offset0:18 offset1:19
	ds_read2_b32 v[80:81], v7 offset1:1
	s_waitcnt lgkmcnt(1)
	v_mov_b32_e32 v82, v78
	s_waitcnt lgkmcnt(0)
	v_mov_b32_e32 v83, v80
	v_fma_f32 v7, v6, v83, v9
	v_fma_f32 v6, v6, v82, v8
	v_mov_b32_e32 v80, v79
	v_fma_f32 v78, v0, v80, v6
	v_fma_f32 v79, v0, v81, v7
	ds_read_b32 v80, v33 offset:2048
	ds_read2_b32 v[6:7], v77 offset0:20 offset1:31
	ds_read2_b32 v[8:9], v13 offset0:20 offset1:31
	s_waitcnt lgkmcnt(1)
	v_mov_b32_e32 v83, v6
	s_waitcnt lgkmcnt(0)
	v_mov_b32_e32 v82, v8
	v_fma_f32 v78, v80, v82, v78
	v_fma_f32 v79, v80, v83, v79
	v_add_u32_e32 v82, 0x454, v13
	ds_read_b32 v8, v34 offset:2048
	ds_read_b32 v84, v35 offset:2048
	ds_read_b32 v86, v36 offset:2048
	ds_read_b32 v88, v37 offset:2048
	ds_read_b32 v90, v38 offset:2048
	ds_read_b32 v92, v39 offset:2048
	ds_read_b32 v94, v40 offset:2048
	ds_read_b32 v96, v41 offset:2048
	ds_read_b32 v6, v42 offset:2048
	ds_read_b32 v0, v43 offset:2048
	ds_read2_b32 v[80:81], v13 offset0:21 offset1:22
	ds_read2_b32 v[82:83], v82 offset1:1
	s_waitcnt lgkmcnt(1)
	v_mov_b32_e32 v98, v80
	s_waitcnt lgkmcnt(0)
	v_mov_b32_e32 v99, v82
	v_fma_f32 v78, v8, v98, v78
	v_fma_f32 v79, v8, v99, v79
	v_mov_b32_e32 v82, v81
	v_add_u32_e32 v8, 0x45c, v13
	v_fma_f32 v78, v84, v82, v78
	v_fma_f32 v79, v84, v83, v79
	ds_read2_b32 v[80:81], v13 offset0:23 offset1:24
	ds_read2_b32 v[82:83], v8 offset1:1
	v_add_u32_e32 v8, 0x464, v13
	s_waitcnt lgkmcnt(1)
	v_mov_b32_e32 v84, v80
	s_waitcnt lgkmcnt(0)
	v_mov_b32_e32 v85, v82
	v_fma_f32 v78, v86, v84, v78
	v_fma_f32 v79, v86, v85, v79
	v_mov_b32_e32 v82, v81
	v_fma_f32 v78, v88, v82, v78
	v_fma_f32 v79, v88, v83, v79
	ds_read2_b32 v[80:81], v13 offset0:25 offset1:26
	ds_read2_b32 v[82:83], v8 offset1:1
	v_add_u32_e32 v8, 0x46c, v13
	s_waitcnt lgkmcnt(1)
	v_mov_b32_e32 v84, v80
	s_waitcnt lgkmcnt(0)
	v_mov_b32_e32 v85, v82
	v_fma_f32 v78, v90, v84, v78
	v_fma_f32 v79, v90, v85, v79
	v_mov_b32_e32 v82, v81
	v_fma_f32 v78, v92, v82, v78
	v_fma_f32 v79, v92, v83, v79
	ds_read2_b32 v[80:81], v13 offset0:27 offset1:28
	ds_read2_b32 v[82:83], v8 offset1:1
	v_add_u32_e32 v8, 0x474, v13
	s_waitcnt lgkmcnt(1)
	v_mov_b32_e32 v84, v80
	s_waitcnt lgkmcnt(0)
	v_mov_b32_e32 v85, v82
	v_mov_b32_e32 v82, v81
	ds_read2_b32 v[80:81], v13 offset0:29 offset1:30
	v_fma_f32 v78, v94, v84, v78
	v_fma_f32 v79, v94, v85, v79
	v_fma_f32 v78, v96, v82, v78
	v_fma_f32 v79, v96, v83, v79
	ds_read2_b32 v[82:83], v8 offset1:1
	s_waitcnt lgkmcnt(1)
	v_mov_b32_e32 v84, v80
	ds_read_b32 v80, v44 offset:2048
	s_waitcnt lgkmcnt(1)
	v_mov_b32_e32 v85, v82
	v_fma_f32 v78, v6, v84, v78
	v_fma_f32 v79, v6, v85, v79
	v_mov_b32_e32 v82, v81
	v_fma_f32 v78, v0, v82, v78
	v_fma_f32 v79, v0, v83, v79
	v_mov_b32_e32 v6, v9
	v_add_u32_e32 v9, 0x480, v13
	ds_read_b32 v82, v45 offset:2048
	ds_read_b32 v84, v46 offset:2048
	ds_read_b32 v86, v47 offset:2048
	ds_read_b32 v88, v48 offset:2048
	ds_read_b32 v90, v49 offset:2048
	ds_read_b32 v92, v50 offset:2048
	ds_read_b32 v94, v51 offset:2048
	ds_read_b32 v96, v52 offset:2048
	ds_read_b32 v8, v53 offset:2048
	ds_read_b32 v0, v54 offset:2048
	s_waitcnt lgkmcnt(10)
	v_fma_f32 v6, v80, v6, v78
	v_fma_f32 v7, v80, v7, v79
	ds_read2_b32 v[78:79], v13 offset0:32 offset1:33
	ds_read2_b32 v[80:81], v9 offset1:1
	v_add_u32_e32 v9, 0x488, v13
	s_waitcnt lgkmcnt(1)
	v_mov_b32_e32 v98, v78
	s_waitcnt lgkmcnt(0)
	v_mov_b32_e32 v99, v80
	v_fma_f32 v6, v82, v98, v6
	v_fma_f32 v7, v82, v99, v7
	v_mov_b32_e32 v80, v79
	v_fma_f32 v6, v84, v80, v6
	v_fma_f32 v7, v84, v81, v7
	ds_read2_b32 v[78:79], v13 offset0:34 offset1:35
	ds_read2_b32 v[80:81], v9 offset1:1
	v_add_u32_e32 v9, 0x490, v13
	s_waitcnt lgkmcnt(1)
	v_mov_b32_e32 v82, v78
	s_waitcnt lgkmcnt(0)
	v_mov_b32_e32 v83, v80
	v_fma_f32 v6, v86, v82, v6
	v_fma_f32 v7, v86, v83, v7
	v_mov_b32_e32 v80, v79
	v_fma_f32 v6, v88, v80, v6
	v_fma_f32 v7, v88, v81, v7
	ds_read2_b32 v[78:79], v13 offset0:36 offset1:37
	ds_read2_b32 v[80:81], v9 offset1:1
	v_add_u32_e32 v9, 0x498, v13
	s_waitcnt lgkmcnt(1)
	v_mov_b32_e32 v82, v78
	s_waitcnt lgkmcnt(0)
	v_mov_b32_e32 v83, v80
	v_fma_f32 v6, v90, v82, v6
	v_fma_f32 v7, v90, v83, v7
	v_mov_b32_e32 v80, v79
	v_fma_f32 v6, v92, v80, v6
	v_fma_f32 v7, v92, v81, v7
	ds_read2_b32 v[78:79], v13 offset0:38 offset1:39
	ds_read2_b32 v[80:81], v9 offset1:1
	v_add_u32_e32 v9, 0x4a0, v13
	s_waitcnt lgkmcnt(1)
	v_mov_b32_e32 v82, v78
	s_waitcnt lgkmcnt(0)
	v_mov_b32_e32 v83, v80
	v_fma_f32 v6, v94, v82, v6
	v_fma_f32 v7, v94, v83, v7
	v_mov_b32_e32 v80, v79
	v_fma_f32 v6, v96, v80, v6
	v_fma_f32 v7, v96, v81, v7
	ds_read2_b32 v[78:79], v13 offset0:40 offset1:41
	ds_read2_b32 v[80:81], v9 offset1:1
	s_waitcnt lgkmcnt(1)
	v_mov_b32_e32 v82, v78
	s_waitcnt lgkmcnt(0)
	v_mov_b32_e32 v83, v80
	v_fma_f32 v6, v8, v82, v6
	v_fma_f32 v7, v8, v83, v7
	v_mov_b32_e32 v80, v79
	v_fma_f32 v78, v0, v80, v6
	v_fma_f32 v79, v0, v81, v7
	ds_read_b32 v80, v55 offset:2048
	ds_read2_b32 v[8:9], v13 offset0:42 offset1:53
	ds_read2_b32 v[6:7], v77 offset0:42 offset1:53
	v_add_u32_e32 v77, 0x4ac, v13
	s_waitcnt lgkmcnt(1)
	v_mov_b32_e32 v82, v8
	s_waitcnt lgkmcnt(0)
	v_mov_b32_e32 v83, v6
	ds_read_b32 v8, v56 offset:2048
	ds_read_b32 v84, v57 offset:2048
	ds_read_b32 v86, v58 offset:2048
	ds_read_b32 v88, v59 offset:2048
	ds_read_b32 v90, v60 offset:2048
	ds_read_b32 v92, v61 offset:2048
	ds_read_b32 v94, v62 offset:2048
	ds_read_b32 v96, v63 offset:2048
	ds_read_b32 v6, v64 offset:2048
	ds_read_b32 v0, v65 offset:2048
	v_fma_f32 v78, v80, v82, v78
	v_fma_f32 v79, v80, v83, v79
	ds_read2_b32 v[80:81], v13 offset0:43 offset1:44
	ds_read2_b32 v[82:83], v77 offset1:1
	s_waitcnt lgkmcnt(1)
	v_mov_b32_e32 v98, v80
	s_waitcnt lgkmcnt(0)
	v_mov_b32_e32 v99, v82
	v_fma_f32 v78, v8, v98, v78
	v_fma_f32 v79, v8, v99, v79
	v_mov_b32_e32 v82, v81
	v_add_u32_e32 v8, 0x4b4, v13
	v_fma_f32 v78, v84, v82, v78
	v_fma_f32 v79, v84, v83, v79
	ds_read2_b32 v[80:81], v13 offset0:45 offset1:46
	ds_read2_b32 v[82:83], v8 offset1:1
	v_add_u32_e32 v8, 0x4bc, v13
	s_waitcnt lgkmcnt(1)
	v_mov_b32_e32 v84, v80
	s_waitcnt lgkmcnt(0)
	v_mov_b32_e32 v85, v82
	v_fma_f32 v78, v86, v84, v78
	v_fma_f32 v79, v86, v85, v79
	v_mov_b32_e32 v82, v81
	v_fma_f32 v78, v88, v82, v78
	v_fma_f32 v79, v88, v83, v79
	ds_read2_b32 v[80:81], v13 offset0:47 offset1:48
	ds_read2_b32 v[82:83], v8 offset1:1
	v_add_u32_e32 v8, 0x4c4, v13
	s_waitcnt lgkmcnt(1)
	v_mov_b32_e32 v84, v80
	s_waitcnt lgkmcnt(0)
	v_mov_b32_e32 v85, v82
	v_fma_f32 v78, v90, v84, v78
	v_fma_f32 v79, v90, v85, v79
	v_mov_b32_e32 v82, v81
	v_fma_f32 v78, v92, v82, v78
	v_fma_f32 v79, v92, v83, v79
	ds_read2_b32 v[80:81], v13 offset0:49 offset1:50
	ds_read2_b32 v[82:83], v8 offset1:1
	v_add_u32_e32 v8, 0x4cc, v13
	s_waitcnt lgkmcnt(1)
	v_mov_b32_e32 v84, v80
	s_waitcnt lgkmcnt(0)
	v_mov_b32_e32 v85, v82
	v_mov_b32_e32 v82, v81
	ds_read2_b32 v[80:81], v13 offset0:51 offset1:52
	v_fma_f32 v78, v94, v84, v78
	v_fma_f32 v79, v94, v85, v79
	v_fma_f32 v78, v96, v82, v78
	v_fma_f32 v79, v96, v83, v79
	ds_read2_b32 v[82:83], v8 offset1:1
	s_waitcnt lgkmcnt(1)
	v_mov_b32_e32 v84, v80
	ds_read_b32 v80, v66 offset:2048
	s_waitcnt lgkmcnt(1)
	v_mov_b32_e32 v85, v82
	v_fma_f32 v78, v6, v84, v78
	v_fma_f32 v79, v6, v85, v79
	v_mov_b32_e32 v82, v81
	v_fma_f32 v78, v0, v82, v78
	v_fma_f32 v79, v0, v83, v79
	v_mov_b32_e32 v6, v9
	v_add_u32_e32 v9, 0x4d8, v13
	ds_read_b32 v82, v67 offset:2048
	ds_read_b32 v84, v68 offset:2048
	ds_read_b32 v86, v69 offset:2048
	ds_read_b32 v88, v70 offset:2048
	ds_read_b32 v90, v71 offset:2048
	ds_read_b32 v92, v72 offset:2048
	ds_read_b32 v94, v73 offset:2048
	ds_read_b32 v96, v74 offset:2048
	ds_read_b32 v8, v75 offset:2048
	ds_read_b32 v0, v76 offset:2048
	s_waitcnt lgkmcnt(10)
	v_fma_f32 v6, v80, v6, v78
	v_fma_f32 v7, v80, v7, v79
	ds_read2_b32 v[78:79], v13 offset0:54 offset1:55
	ds_read2_b32 v[80:81], v9 offset1:1
	v_add_u32_e32 v9, 0x4e0, v13
	s_waitcnt lgkmcnt(1)
	v_mov_b32_e32 v98, v78
	s_waitcnt lgkmcnt(0)
	v_mov_b32_e32 v99, v80
	v_fma_f32 v6, v82, v98, v6
	v_fma_f32 v7, v82, v99, v7
	v_mov_b32_e32 v80, v79
	v_fma_f32 v6, v84, v80, v6
	v_fma_f32 v7, v84, v81, v7
	ds_read2_b32 v[78:79], v13 offset0:56 offset1:57
	ds_read2_b32 v[80:81], v9 offset1:1
	v_add_u32_e32 v9, 0x4e8, v13
	s_waitcnt lgkmcnt(1)
	v_mov_b32_e32 v82, v78
	s_waitcnt lgkmcnt(0)
	v_mov_b32_e32 v83, v80
	v_fma_f32 v6, v86, v82, v6
	v_fma_f32 v7, v86, v83, v7
	v_mov_b32_e32 v80, v79
	v_fma_f32 v6, v88, v80, v6
	v_fma_f32 v7, v88, v81, v7
	ds_read2_b32 v[78:79], v13 offset0:58 offset1:59
	ds_read2_b32 v[80:81], v9 offset1:1
	v_add_u32_e32 v9, 0x4f0, v13
	s_waitcnt lgkmcnt(1)
	v_mov_b32_e32 v82, v78
	s_waitcnt lgkmcnt(0)
	v_mov_b32_e32 v83, v80
	v_fma_f32 v6, v90, v82, v6
	v_fma_f32 v7, v90, v83, v7
	v_mov_b32_e32 v80, v79
	v_fma_f32 v6, v92, v80, v6
	v_fma_f32 v7, v92, v81, v7
	ds_read2_b32 v[78:79], v13 offset0:60 offset1:61
	ds_read2_b32 v[80:81], v9 offset1:1
	v_add_u32_e32 v9, 0x4f8, v13
	s_waitcnt lgkmcnt(1)
	v_mov_b32_e32 v82, v78
	s_waitcnt lgkmcnt(0)
	v_mov_b32_e32 v83, v80
	v_fma_f32 v6, v94, v82, v6
	v_fma_f32 v7, v94, v83, v7
	v_mov_b32_e32 v80, v79
	v_fma_f32 v6, v96, v80, v6
	v_fma_f32 v7, v96, v81, v7
	ds_read2_b32 v[78:79], v13 offset0:62 offset1:63
	ds_read2_b32 v[80:81], v9 offset1:1
	s_waitcnt lgkmcnt(1)
	v_mov_b32_e32 v82, v78
	s_waitcnt lgkmcnt(0)
	v_mov_b32_e32 v83, v80
	v_fma_f32 v6, v8, v82, v6
	v_fma_f32 v7, v8, v83, v7
	v_mov_b32_e32 v80, v79
	v_fma_f32 v6, v0, v80, v6
	v_fma_f32 v7, v0, v81, v7
	v_cvt_pk_bf16_f32 v0, v6, v7
	v_lshl_add_u64 v[6:7], s[40:41], 1, v[4:5]
	s_add_i32 s40, s40, s2
	s_cmpk_gt_i32 s3, 0x1ff
	global_store_dword v[6:7], v0, off
	s_cbranch_scc0 .LBB0_513

.LBB0_523:
	v_lshl_add_u64 v[16:17], v[14:15], 0, s[14:15]
	v_add_co_u32_e32 v24, vcc, 0x400000, v16
	v_mov_b32_e32 v23, s8
	s_nop 0
	v_addc_co_u32_e32 v25, vcc, 0, v17, vcc
	global_load_dword v26, v[24:25], off
	s_nop 0
	global_load_dword v24, v[24:25], off offset:2048
	ds_read2_b32 v[28:29], v23 offset1:1
	ds_read2_b32 v[30:31], v23 offset0:128 offset1:129
	s_add_u32 s14, s14, 0x8000
	s_addc_u32 s15, s15, 0
	s_add_i32 s8, s8, 32
	s_waitcnt lgkmcnt(1)
	v_mov_b32_e32 v32, v28
	s_waitcnt lgkmcnt(0)
	v_mov_b32_e32 v33, v30
	v_mov_b32_e32 v30, v29
	s_cmp_eq_u32 s14, 0x80000
	s_waitcnt vmcnt(1)
	v_fma_f32 v20, v26, v32, v20
	v_fma_f32 v21, v26, v33, v21
	s_waitcnt vmcnt(0)
	v_fma_f32 v18, v24, v32, v18
	v_fma_f32 v19, v24, v33, v19
	v_add_co_u32_e32 v24, vcc, s20, v16
	s_nop 1
	v_addc_co_u32_e32 v25, vcc, 0, v17, vcc
	v_add_co_u32_e32 v26, vcc, s21, v16
	s_nop 1
	v_addc_co_u32_e32 v27, vcc, 0, v17, vcc
	global_load_dword v28, v[26:27], off offset:-4096
	s_nop 0
	global_load_dword v24, v[24:25], off offset:2048
	s_waitcnt vmcnt(1)
	v_fma_f32 v20, v28, v30, v20
	v_fma_f32 v21, v28, v31, v21
	s_waitcnt vmcnt(0)
	v_fma_f32 v18, v24, v30, v18
	v_fma_f32 v19, v24, v31, v19
	global_load_dword v24, v[26:27], off
	s_nop 0
	global_load_dword v26, v[26:27], off offset:2048
	ds_read2_b32 v[28:29], v23 offset0:2 offset1:3
	ds_read2_b32 v[30:31], v23 offset0:130 offset1:131
	s_waitcnt lgkmcnt(1)
	v_mov_b32_e32 v32, v28
	s_waitcnt lgkmcnt(0)
	v_mov_b32_e32 v33, v30
	v_mov_b32_e32 v30, v29
	s_waitcnt vmcnt(1)
	v_fma_f32 v20, v24, v32, v20
	v_fma_f32 v21, v24, v33, v21
	v_add_co_u32_e32 v24, vcc, s24, v16
	s_waitcnt vmcnt(0)
	v_fma_f32 v18, v26, v32, v18
	v_fma_f32 v19, v26, v33, v19
	v_addc_co_u32_e32 v25, vcc, 0, v17, vcc
	v_add_co_u32_e32 v26, vcc, s25, v16
	s_nop 1
	v_addc_co_u32_e32 v27, vcc, 0, v17, vcc
	global_load_dword v28, v[26:27], off offset:-4096
	s_nop 0
	global_load_dword v24, v[24:25], off offset:2048
	s_waitcnt vmcnt(1)
	v_fma_f32 v20, v28, v30, v20
	v_fma_f32 v21, v28, v31, v21
	s_waitcnt vmcnt(0)
	v_fma_f32 v18, v24, v30, v18
	v_fma_f32 v19, v24, v31, v19
	global_load_dword v24, v[26:27], off
	s_nop 0
	global_load_dword v26, v[26:27], off offset:2048
	ds_read2_b32 v[28:29], v23 offset0:4 offset1:5
	ds_read2_b32 v[30:31], v23 offset0:132 offset1:133
	s_waitcnt lgkmcnt(1)
	v_mov_b32_e32 v32, v28
	s_waitcnt lgkmcnt(0)
	v_mov_b32_e32 v33, v30
	v_mov_b32_e32 v30, v29
	s_waitcnt vmcnt(1)
	v_fma_f32 v20, v24, v32, v20
	v_fma_f32 v21, v24, v33, v21
	v_add_co_u32_e32 v24, vcc, s26, v16
	s_waitcnt vmcnt(0)
	v_fma_f32 v18, v26, v32, v18
	v_fma_f32 v19, v26, v33, v19
	v_addc_co_u32_e32 v25, vcc, 0, v17, vcc
	v_add_co_u32_e32 v26, vcc, s28, v16
	s_nop 1
	v_addc_co_u32_e32 v27, vcc, 0, v17, vcc
	global_load_dword v28, v[26:27], off offset:-4096
	s_nop 0
	global_load_dword v24, v[24:25], off offset:2048
	v_add_co_u32_e32 v16, vcc, s30, v16
	s_waitcnt vmcnt(1)
	v_fma_f32 v20, v28, v30, v20
	v_fma_f32 v21, v28, v31, v21
	s_waitcnt vmcnt(0)
	v_fma_f32 v18, v24, v30, v18
	v_fma_f32 v19, v24, v31, v19
	global_load_dword v24, v[26:27], off
	s_nop 0
	global_load_dword v26, v[26:27], off offset:2048
	ds_read2_b32 v[28:29], v23 offset0:6 offset1:7
	ds_read2_b32 v[30:31], v23 offset0:134 offset1:135
	v_addc_co_u32_e32 v17, vcc, 0, v17, vcc
	s_waitcnt lgkmcnt(1)
	v_mov_b32_e32 v32, v28
	s_waitcnt lgkmcnt(0)
	v_mov_b32_e32 v33, v30
	v_mov_b32_e32 v30, v29
	s_waitcnt vmcnt(1)
	v_fma_f32 v20, v24, v32, v20
	v_fma_f32 v21, v24, v33, v21
	global_load_dword v24, v[16:17], off
	s_nop 0
	global_load_dword v16, v[16:17], off offset:2048
	s_waitcnt vmcnt(2)
	v_fma_f32 v18, v26, v32, v18
	v_fma_f32 v19, v26, v33, v19
	s_waitcnt vmcnt(1)
	v_fma_f32 v20, v24, v30, v20
	v_fma_f32 v21, v24, v31, v21
	s_waitcnt vmcnt(0)
	v_fma_f32 v18, v16, v30, v18
	v_fma_f32 v19, v16, v31, v19
	s_cbranch_scc0 .LBB0_523
	v_lshlrev_b64 v[12:13], 1, v[12:13]
	v_lshl_add_u64 v[14:15], v[6:7], 0, v[12:13]
	s_lshl_b32 s86, s86, 1
	v_cvt_pk_bf16_f32 v16, v20, v21
	v_lshl_add_u64 v[14:15], v[14:15], 0, s[86:87]
	v_lshl_add_u64 v[12:13], v[8:9], 0, v[12:13]
	s_add_i32 s4, s4, s5
	global_store_dword v[14:15], v16, off offset:1024
	v_cvt_pk_bf16_f32 v14, v18, v19
	v_lshl_add_u64 v[12:13], v[12:13], 0, s[86:87]
	s_cmpk_gt_i32 s4, 0xff
	global_store_dword v[12:13], v14, off offset:1024
	s_cbranch_scc0 .LBB0_518

.LBB0_680:
	v_add_u32_e32 v0, s40, v10
	v_mad_i64_i32 v[6:7], s[0:1], v0, s4, v[2:3]
	s_barrier
	global_load_dword v0, v[6:7], off
	v_add_u32_e32 v7, 0x420, v13
	v_add_u32_e32 v77, 0x400, v13
	s_ashr_i32 s41, s40, 31
	s_add_i32 s3, s3, s30
	s_waitcnt vmcnt(0)
	ds_write_b32 v11, v0
	s_waitcnt lgkmcnt(0)
	s_barrier
	ds_read_b32 v0, v12 offset:2048
	ds_read_b32 v6, v14 offset:2048
	ds_read_b32 v8, v15 offset:2048
	ds_read_b32 v78, v16 offset:2048
	ds_read_b32 v80, v17 offset:2048
	ds_read_b32 v82, v18 offset:2048
	ds_read_b32 v84, v19 offset:2048
	ds_read_b32 v86, v20 offset:2048
	ds_read_b32 v88, v21 offset:2048
	ds_read2_b32 v[90:91], v13 offset0:8 offset1:9
	ds_read2_b32 v[92:93], v7 offset1:1
	ds_read2_b32 v[94:95], v13 offset1:1
	ds_read2_b32 v[96:97], v77 offset1:1
	s_waitcnt lgkmcnt(1)
	v_mov_b32_e32 v98, v94
	s_waitcnt lgkmcnt(0)
	v_mov_b32_e32 v99, v96
	v_fma_f32 v98, v0, v98, 0
	v_fma_f32 v99, v0, v99, 0
	v_mov_b32_e32 v96, v95
	v_add_u32_e32 v0, 0x408, v13
	v_fma_f32 v7, v6, v97, v99
	v_fma_f32 v6, v6, v96, v98
	ds_read2_b32 v[94:95], v13 offset0:2 offset1:3
	ds_read2_b32 v[96:97], v0 offset1:1
	v_add_u32_e32 v0, 0x410, v13
	s_waitcnt lgkmcnt(1)
	v_mov_b32_e32 v98, v94
	s_waitcnt lgkmcnt(0)
	v_mov_b32_e32 v99, v96
	v_fma_f32 v6, v8, v98, v6
	v_fma_f32 v7, v8, v99, v7
	v_mov_b32_e32 v96, v95
	v_fma_f32 v6, v78, v96, v6
	v_fma_f32 v7, v78, v97, v7
	ds_read2_b32 v[8:9], v13 offset0:4 offset1:5
	ds_read2_b32 v[78:79], v0 offset1:1
	v_add_u32_e32 v0, 0x418, v13
	s_waitcnt lgkmcnt(1)
	v_mov_b32_e32 v94, v8
	s_waitcnt lgkmcnt(0)
	v_mov_b32_e32 v95, v78
	v_fma_f32 v6, v80, v94, v6
	v_fma_f32 v7, v80, v95, v7
	v_mov_b32_e32 v78, v9
	v_fma_f32 v6, v82, v78, v6
	v_fma_f32 v7, v82, v79, v7
	ds_read2_b32 v[8:9], v13 offset0:6 offset1:7
	ds_read2_b32 v[78:79], v0 offset1:1
	s_waitcnt lgkmcnt(1)
	v_mov_b32_e32 v80, v8
	s_waitcnt lgkmcnt(0)
	v_mov_b32_e32 v81, v78
	v_fma_f32 v6, v84, v80, v6
	v_fma_f32 v7, v84, v81, v7
	v_mov_b32_e32 v78, v9
	v_fma_f32 v6, v86, v78, v6
	v_fma_f32 v7, v86, v79, v7
	ds_read_b32 v78, v22 offset:2048
	v_mov_b32_e32 v8, v90
	v_mov_b32_e32 v9, v92
	v_fma_f32 v8, v88, v8, v6
	v_fma_f32 v9, v88, v9, v7
	v_mov_b32_e32 v92, v91
	v_add_u32_e32 v7, 0x428, v13
	ds_read_b32 v80, v23 offset:2048
	ds_read_b32 v82, v24 offset:2048
	ds_read_b32 v84, v25 offset:2048
	ds_read_b32 v86, v26 offset:2048
	ds_read_b32 v88, v27 offset:2048
	ds_read_b32 v90, v28 offset:2048
	ds_read_b32 v94, v29 offset:2048
	ds_read_b32 v96, v30 offset:2048
	ds_read_b32 v6, v31 offset:2048
	ds_read_b32 v0, v32 offset:2048
	s_waitcnt lgkmcnt(10)
	v_fma_f32 v8, v78, v92, v8
	v_fma_f32 v9, v78, v93, v9
	ds_read2_b32 v[78:79], v13 offset0:10 offset1:11
	ds_read2_b32 v[92:93], v7 offset1:1
	v_add_u32_e32 v7, 0x430, v13
	s_waitcnt lgkmcnt(1)
	v_mov_b32_e32 v98, v78
	s_waitcnt lgkmcnt(0)
	v_mov_b32_e32 v99, v92
	v_fma_f32 v8, v80, v98, v8
	v_fma_f32 v9, v80, v99, v9
	v_mov_b32_e32 v92, v79
	ds_read2_b32 v[78:79], v13 offset0:12 offset1:13
	ds_read2_b32 v[80:81], v7 offset1:1
	v_fma_f32 v8, v82, v92, v8
	v_fma_f32 v9, v82, v93, v9
	v_add_u32_e32 v7, 0x438, v13
	s_waitcnt lgkmcnt(1)
	v_mov_b32_e32 v82, v78
	s_waitcnt lgkmcnt(0)
	v_mov_b32_e32 v83, v80
	v_fma_f32 v8, v84, v82, v8
	v_fma_f32 v9, v84, v83, v9
	v_mov_b32_e32 v80, v79
	v_fma_f32 v8, v86, v80, v8
	v_fma_f32 v9, v86, v81, v9
	ds_read2_b32 v[78:79], v13 offset0:14 offset1:15
	ds_read2_b32 v[80:81], v7 offset1:1
	v_add_u32_e32 v7, 0x440, v13
	s_waitcnt lgkmcnt(1)
	v_mov_b32_e32 v82, v78
	s_waitcnt lgkmcnt(0)
	v_mov_b32_e32 v83, v80
	v_fma_f32 v8, v88, v82, v8
	v_fma_f32 v9, v88, v83, v9
	v_mov_b32_e32 v80, v79
	v_fma_f32 v8, v90, v80, v8
	v_fma_f32 v9, v90, v81, v9
	ds_read2_b32 v[78:79], v13 offset0:16 offset1:17
	ds_read2_b32 v[80:81], v7 offset1:1
	v_add_u32_e32 v7, 0x448, v13
	s_waitcnt lgkmcnt(1)
	v_mov_b32_e32 v82, v78
	s_waitcnt lgkmcnt(0)
	v_mov_b32_e32 v83, v80
	v_fma_f32 v8, v94, v82, v8
	v_fma_f32 v9, v94, v83, v9
	v_mov_b32_e32 v80, v79
	v_fma_f32 v8, v96, v80, v8
	v_fma_f32 v9, v96, v81, v9
	ds_read2_b32 v[78:79], v13 offset0:18 offset1:19
	ds_read2_b32 v[80:81], v7 offset1:1
	s_waitcnt lgkmcnt(1)
	v_mov_b32_e32 v82, v78
	s_waitcnt lgkmcnt(0)
	v_mov_b32_e32 v83, v80
	v_fma_f32 v7, v6, v83, v9
	v_fma_f32 v6, v6, v82, v8
	v_mov_b32_e32 v80, v79
	v_fma_f32 v78, v0, v80, v6
	v_fma_f32 v79, v0, v81, v7
	ds_read_b32 v80, v33 offset:2048
	ds_read2_b32 v[6:7], v77 offset0:20 offset1:31
	ds_read2_b32 v[8:9], v13 offset0:20 offset1:31
	s_waitcnt lgkmcnt(1)
	v_mov_b32_e32 v83, v6
	s_waitcnt lgkmcnt(0)
	v_mov_b32_e32 v82, v8
	v_fma_f32 v78, v80, v82, v78
	v_fma_f32 v79, v80, v83, v79
	v_add_u32_e32 v82, 0x454, v13
	ds_read_b32 v8, v34 offset:2048
	ds_read_b32 v84, v35 offset:2048
	ds_read_b32 v86, v36 offset:2048
	ds_read_b32 v88, v37 offset:2048
	ds_read_b32 v90, v38 offset:2048
	ds_read_b32 v92, v39 offset:2048
	ds_read_b32 v94, v40 offset:2048
	ds_read_b32 v96, v41 offset:2048
	ds_read_b32 v6, v42 offset:2048
	ds_read_b32 v0, v43 offset:2048
	ds_read2_b32 v[80:81], v13 offset0:21 offset1:22
	ds_read2_b32 v[82:83], v82 offset1:1
	s_waitcnt lgkmcnt(1)
	v_mov_b32_e32 v98, v80
	s_waitcnt lgkmcnt(0)
	v_mov_b32_e32 v99, v82
	v_fma_f32 v78, v8, v98, v78
	v_fma_f32 v79, v8, v99, v79
	v_mov_b32_e32 v82, v81
	v_add_u32_e32 v8, 0x45c, v13
	v_fma_f32 v78, v84, v82, v78
	v_fma_f32 v79, v84, v83, v79
	ds_read2_b32 v[80:81], v13 offset0:23 offset1:24
	ds_read2_b32 v[82:83], v8 offset1:1
	v_add_u32_e32 v8, 0x464, v13
	s_waitcnt lgkmcnt(1)
	v_mov_b32_e32 v84, v80
	s_waitcnt lgkmcnt(0)
	v_mov_b32_e32 v85, v82
	v_fma_f32 v78, v86, v84, v78
	v_fma_f32 v79, v86, v85, v79
	v_mov_b32_e32 v82, v81
	v_fma_f32 v78, v88, v82, v78
	v_fma_f32 v79, v88, v83, v79
	ds_read2_b32 v[80:81], v13 offset0:25 offset1:26
	ds_read2_b32 v[82:83], v8 offset1:1
	v_add_u32_e32 v8, 0x46c, v13
	s_waitcnt lgkmcnt(1)
	v_mov_b32_e32 v84, v80
	s_waitcnt lgkmcnt(0)
	v_mov_b32_e32 v85, v82
	v_fma_f32 v78, v90, v84, v78
	v_fma_f32 v79, v90, v85, v79
	v_mov_b32_e32 v82, v81
	v_fma_f32 v78, v92, v82, v78
	v_fma_f32 v79, v92, v83, v79
	ds_read2_b32 v[80:81], v13 offset0:27 offset1:28
	ds_read2_b32 v[82:83], v8 offset1:1
	v_add_u32_e32 v8, 0x474, v13
	s_waitcnt lgkmcnt(1)
	v_mov_b32_e32 v84, v80
	s_waitcnt lgkmcnt(0)
	v_mov_b32_e32 v85, v82
	v_mov_b32_e32 v82, v81
	ds_read2_b32 v[80:81], v13 offset0:29 offset1:30
	v_fma_f32 v78, v94, v84, v78
	v_fma_f32 v79, v94, v85, v79
	v_fma_f32 v78, v96, v82, v78
	v_fma_f32 v79, v96, v83, v79
	ds_read2_b32 v[82:83], v8 offset1:1
	s_waitcnt lgkmcnt(1)
	v_mov_b32_e32 v84, v80
	ds_read_b32 v80, v44 offset:2048
	s_waitcnt lgkmcnt(1)
	v_mov_b32_e32 v85, v82
	v_fma_f32 v78, v6, v84, v78
	v_fma_f32 v79, v6, v85, v79
	v_mov_b32_e32 v82, v81
	v_fma_f32 v78, v0, v82, v78
	v_fma_f32 v79, v0, v83, v79
	v_mov_b32_e32 v6, v9
	v_add_u32_e32 v9, 0x480, v13
	ds_read_b32 v82, v45 offset:2048
	ds_read_b32 v84, v46 offset:2048
	ds_read_b32 v86, v47 offset:2048
	ds_read_b32 v88, v48 offset:2048
	ds_read_b32 v90, v49 offset:2048
	ds_read_b32 v92, v50 offset:2048
	ds_read_b32 v94, v51 offset:2048
	ds_read_b32 v96, v52 offset:2048
	ds_read_b32 v8, v53 offset:2048
	ds_read_b32 v0, v54 offset:2048
	s_waitcnt lgkmcnt(10)
	v_fma_f32 v6, v80, v6, v78
	v_fma_f32 v7, v80, v7, v79
	ds_read2_b32 v[78:79], v13 offset0:32 offset1:33
	ds_read2_b32 v[80:81], v9 offset1:1
	v_add_u32_e32 v9, 0x488, v13
	s_waitcnt lgkmcnt(1)
	v_mov_b32_e32 v98, v78
	s_waitcnt lgkmcnt(0)
	v_mov_b32_e32 v99, v80
	v_fma_f32 v6, v82, v98, v6
	v_fma_f32 v7, v82, v99, v7
	v_mov_b32_e32 v80, v79
	v_fma_f32 v6, v84, v80, v6
	v_fma_f32 v7, v84, v81, v7
	ds_read2_b32 v[78:79], v13 offset0:34 offset1:35
	ds_read2_b32 v[80:81], v9 offset1:1
	v_add_u32_e32 v9, 0x490, v13
	s_waitcnt lgkmcnt(1)
	v_mov_b32_e32 v82, v78
	s_waitcnt lgkmcnt(0)
	v_mov_b32_e32 v83, v80
	v_fma_f32 v6, v86, v82, v6
	v_fma_f32 v7, v86, v83, v7
	v_mov_b32_e32 v80, v79
	v_fma_f32 v6, v88, v80, v6
	v_fma_f32 v7, v88, v81, v7
	ds_read2_b32 v[78:79], v13 offset0:36 offset1:37
	ds_read2_b32 v[80:81], v9 offset1:1
	v_add_u32_e32 v9, 0x498, v13
	s_waitcnt lgkmcnt(1)
	v_mov_b32_e32 v82, v78
	s_waitcnt lgkmcnt(0)
	v_mov_b32_e32 v83, v80
	v_fma_f32 v6, v90, v82, v6
	v_fma_f32 v7, v90, v83, v7
	v_mov_b32_e32 v80, v79
	v_fma_f32 v6, v92, v80, v6
	v_fma_f32 v7, v92, v81, v7
	ds_read2_b32 v[78:79], v13 offset0:38 offset1:39
	ds_read2_b32 v[80:81], v9 offset1:1
	v_add_u32_e32 v9, 0x4a0, v13
	s_waitcnt lgkmcnt(1)
	v_mov_b32_e32 v82, v78
	s_waitcnt lgkmcnt(0)
	v_mov_b32_e32 v83, v80
	v_fma_f32 v6, v94, v82, v6
	v_fma_f32 v7, v94, v83, v7
	v_mov_b32_e32 v80, v79
	v_fma_f32 v6, v96, v80, v6
	v_fma_f32 v7, v96, v81, v7
	ds_read2_b32 v[78:79], v13 offset0:40 offset1:41
	ds_read2_b32 v[80:81], v9 offset1:1
	s_waitcnt lgkmcnt(1)
	v_mov_b32_e32 v82, v78
	s_waitcnt lgkmcnt(0)
	v_mov_b32_e32 v83, v80
	v_fma_f32 v6, v8, v82, v6
	v_fma_f32 v7, v8, v83, v7
	v_mov_b32_e32 v80, v79
	v_fma_f32 v78, v0, v80, v6
	v_fma_f32 v79, v0, v81, v7
	ds_read_b32 v80, v55 offset:2048
	ds_read2_b32 v[8:9], v13 offset0:42 offset1:53
	ds_read2_b32 v[6:7], v77 offset0:42 offset1:53
	v_add_u32_e32 v77, 0x4ac, v13
	s_waitcnt lgkmcnt(1)
	v_mov_b32_e32 v82, v8
	s_waitcnt lgkmcnt(0)
	v_mov_b32_e32 v83, v6
	ds_read_b32 v8, v56 offset:2048
	ds_read_b32 v84, v57 offset:2048
	ds_read_b32 v86, v58 offset:2048
	ds_read_b32 v88, v59 offset:2048
	ds_read_b32 v90, v60 offset:2048
	ds_read_b32 v92, v61 offset:2048
	ds_read_b32 v94, v62 offset:2048
	ds_read_b32 v96, v63 offset:2048
	ds_read_b32 v6, v64 offset:2048
	ds_read_b32 v0, v65 offset:2048
	v_fma_f32 v78, v80, v82, v78
	v_fma_f32 v79, v80, v83, v79
	ds_read2_b32 v[80:81], v13 offset0:43 offset1:44
	ds_read2_b32 v[82:83], v77 offset1:1
	s_waitcnt lgkmcnt(1)
	v_mov_b32_e32 v98, v80
	s_waitcnt lgkmcnt(0)
	v_mov_b32_e32 v99, v82
	v_fma_f32 v78, v8, v98, v78
	v_fma_f32 v79, v8, v99, v79
	v_mov_b32_e32 v82, v81
	v_add_u32_e32 v8, 0x4b4, v13
	v_fma_f32 v78, v84, v82, v78
	v_fma_f32 v79, v84, v83, v79
	ds_read2_b32 v[80:81], v13 offset0:45 offset1:46
	ds_read2_b32 v[82:83], v8 offset1:1
	v_add_u32_e32 v8, 0x4bc, v13
	s_waitcnt lgkmcnt(1)
	v_mov_b32_e32 v84, v80
	s_waitcnt lgkmcnt(0)
	v_mov_b32_e32 v85, v82
	v_fma_f32 v78, v86, v84, v78
	v_fma_f32 v79, v86, v85, v79
	v_mov_b32_e32 v82, v81
	v_fma_f32 v78, v88, v82, v78
	v_fma_f32 v79, v88, v83, v79
	ds_read2_b32 v[80:81], v13 offset0:47 offset1:48
	ds_read2_b32 v[82:83], v8 offset1:1
	v_add_u32_e32 v8, 0x4c4, v13
	s_waitcnt lgkmcnt(1)
	v_mov_b32_e32 v84, v80
	s_waitcnt lgkmcnt(0)
	v_mov_b32_e32 v85, v82
	v_fma_f32 v78, v90, v84, v78
	v_fma_f32 v79, v90, v85, v79
	v_mov_b32_e32 v82, v81
	v_fma_f32 v78, v92, v82, v78
	v_fma_f32 v79, v92, v83, v79
	ds_read2_b32 v[80:81], v13 offset0:49 offset1:50
	ds_read2_b32 v[82:83], v8 offset1:1
	v_add_u32_e32 v8, 0x4cc, v13
	s_waitcnt lgkmcnt(1)
	v_mov_b32_e32 v84, v80
	s_waitcnt lgkmcnt(0)
	v_mov_b32_e32 v85, v82
	v_mov_b32_e32 v82, v81
	ds_read2_b32 v[80:81], v13 offset0:51 offset1:52
	v_fma_f32 v78, v94, v84, v78
	v_fma_f32 v79, v94, v85, v79
	v_fma_f32 v78, v96, v82, v78
	v_fma_f32 v79, v96, v83, v79
	ds_read2_b32 v[82:83], v8 offset1:1
	s_waitcnt lgkmcnt(1)
	v_mov_b32_e32 v84, v80
	ds_read_b32 v80, v66 offset:2048
	s_waitcnt lgkmcnt(1)
	v_mov_b32_e32 v85, v82
	v_fma_f32 v78, v6, v84, v78
	v_fma_f32 v79, v6, v85, v79
	v_mov_b32_e32 v82, v81
	v_fma_f32 v78, v0, v82, v78
	v_fma_f32 v79, v0, v83, v79
	v_mov_b32_e32 v6, v9
	v_add_u32_e32 v9, 0x4d8, v13
	ds_read_b32 v82, v67 offset:2048
	ds_read_b32 v84, v68 offset:2048
	ds_read_b32 v86, v69 offset:2048
	ds_read_b32 v88, v70 offset:2048
	ds_read_b32 v90, v71 offset:2048
	ds_read_b32 v92, v72 offset:2048
	ds_read_b32 v94, v73 offset:2048
	ds_read_b32 v96, v74 offset:2048
	ds_read_b32 v8, v75 offset:2048
	ds_read_b32 v0, v76 offset:2048
	s_waitcnt lgkmcnt(10)
	v_fma_f32 v6, v80, v6, v78
	v_fma_f32 v7, v80, v7, v79
	ds_read2_b32 v[78:79], v13 offset0:54 offset1:55
	ds_read2_b32 v[80:81], v9 offset1:1
	v_add_u32_e32 v9, 0x4e0, v13
	s_waitcnt lgkmcnt(1)
	v_mov_b32_e32 v98, v78
	s_waitcnt lgkmcnt(0)
	v_mov_b32_e32 v99, v80
	v_fma_f32 v6, v82, v98, v6
	v_fma_f32 v7, v82, v99, v7
	v_mov_b32_e32 v80, v79
	v_fma_f32 v6, v84, v80, v6
	v_fma_f32 v7, v84, v81, v7
	ds_read2_b32 v[78:79], v13 offset0:56 offset1:57
	ds_read2_b32 v[80:81], v9 offset1:1
	v_add_u32_e32 v9, 0x4e8, v13
	s_waitcnt lgkmcnt(1)
	v_mov_b32_e32 v82, v78
	s_waitcnt lgkmcnt(0)
	v_mov_b32_e32 v83, v80
	v_fma_f32 v6, v86, v82, v6
	v_fma_f32 v7, v86, v83, v7
	v_mov_b32_e32 v80, v79
	v_fma_f32 v6, v88, v80, v6
	v_fma_f32 v7, v88, v81, v7
	ds_read2_b32 v[78:79], v13 offset0:58 offset1:59
	ds_read2_b32 v[80:81], v9 offset1:1
	v_add_u32_e32 v9, 0x4f0, v13
	s_waitcnt lgkmcnt(1)
	v_mov_b32_e32 v82, v78
	s_waitcnt lgkmcnt(0)
	v_mov_b32_e32 v83, v80
	v_fma_f32 v6, v90, v82, v6
	v_fma_f32 v7, v90, v83, v7
	v_mov_b32_e32 v80, v79
	v_fma_f32 v6, v92, v80, v6
	v_fma_f32 v7, v92, v81, v7
	ds_read2_b32 v[78:79], v13 offset0:60 offset1:61
	ds_read2_b32 v[80:81], v9 offset1:1
	v_add_u32_e32 v9, 0x4f8, v13
	s_waitcnt lgkmcnt(1)
	v_mov_b32_e32 v82, v78
	s_waitcnt lgkmcnt(0)
	v_mov_b32_e32 v83, v80
	v_fma_f32 v6, v94, v82, v6
	v_fma_f32 v7, v94, v83, v7
	v_mov_b32_e32 v80, v79
	v_fma_f32 v6, v96, v80, v6
	v_fma_f32 v7, v96, v81, v7
	ds_read2_b32 v[78:79], v13 offset0:62 offset1:63
	ds_read2_b32 v[80:81], v9 offset1:1
	s_waitcnt lgkmcnt(1)
	v_mov_b32_e32 v82, v78
	s_waitcnt lgkmcnt(0)
	v_mov_b32_e32 v83, v80
	v_fma_f32 v6, v8, v82, v6
	v_fma_f32 v7, v8, v83, v7
	v_mov_b32_e32 v80, v79
	v_fma_f32 v6, v0, v80, v6
	v_fma_f32 v7, v0, v81, v7
	v_cvt_pk_bf16_f32 v0, v6, v7
	v_lshl_add_u64 v[6:7], s[40:41], 1, v[4:5]
	s_add_i32 s40, s40, s2
	s_cmpk_gt_i32 s3, 0x1ff
	global_store_dword v[6:7], v0, off
	s_cbranch_scc0 .LBB0_680

.LBB0_690:
	v_lshl_add_u64 v[16:17], v[14:15], 0, s[14:15]
	v_add_co_u32_e32 v24, vcc, 0x400000, v16
	v_mov_b32_e32 v23, s4
	s_nop 0
	v_addc_co_u32_e32 v25, vcc, 0, v17, vcc
	global_load_dword v26, v[24:25], off
	s_nop 0
	global_load_dword v24, v[24:25], off offset:2048
	ds_read2_b32 v[28:29], v23 offset1:1
	ds_read2_b32 v[30:31], v23 offset0:128 offset1:129
	s_add_u32 s14, s14, 0x8000
	s_addc_u32 s15, s15, 0
	s_add_i32 s4, s4, 32
	s_waitcnt lgkmcnt(1)
	v_mov_b32_e32 v32, v28
	s_waitcnt lgkmcnt(0)
	v_mov_b32_e32 v33, v30
	v_mov_b32_e32 v30, v29
	s_cmp_eq_u32 s14, 0x80000
	s_waitcnt vmcnt(1)
	v_fma_f32 v20, v26, v32, v20
	v_fma_f32 v21, v26, v33, v21
	s_waitcnt vmcnt(0)
	v_fma_f32 v18, v24, v32, v18
	v_fma_f32 v19, v24, v33, v19
	v_add_co_u32_e32 v24, vcc, s8, v16
	s_nop 1
	v_addc_co_u32_e32 v25, vcc, 0, v17, vcc
	v_add_co_u32_e32 v26, vcc, s20, v16
	s_nop 1
	v_addc_co_u32_e32 v27, vcc, 0, v17, vcc
	global_load_dword v28, v[26:27], off offset:-4096
	s_nop 0
	global_load_dword v24, v[24:25], off offset:2048
	s_waitcnt vmcnt(1)
	v_fma_f32 v20, v28, v30, v20
	v_fma_f32 v21, v28, v31, v21
	s_waitcnt vmcnt(0)
	v_fma_f32 v18, v24, v30, v18
	v_fma_f32 v19, v24, v31, v19
	global_load_dword v24, v[26:27], off
	s_nop 0
	global_load_dword v26, v[26:27], off offset:2048
	ds_read2_b32 v[28:29], v23 offset0:2 offset1:3
	ds_read2_b32 v[30:31], v23 offset0:130 offset1:131
	s_waitcnt lgkmcnt(1)
	v_mov_b32_e32 v32, v28
	s_waitcnt lgkmcnt(0)
	v_mov_b32_e32 v33, v30
	v_mov_b32_e32 v30, v29
	s_waitcnt vmcnt(1)
	v_fma_f32 v20, v24, v32, v20
	v_fma_f32 v21, v24, v33, v21
	v_add_co_u32_e32 v24, vcc, s21, v16
	s_waitcnt vmcnt(0)
	v_fma_f32 v18, v26, v32, v18
	v_fma_f32 v19, v26, v33, v19
	v_addc_co_u32_e32 v25, vcc, 0, v17, vcc
	v_add_co_u32_e32 v26, vcc, s24, v16
	s_nop 1
	v_addc_co_u32_e32 v27, vcc, 0, v17, vcc
	global_load_dword v28, v[26:27], off offset:-4096
	s_nop 0
	global_load_dword v24, v[24:25], off offset:2048
	s_waitcnt vmcnt(1)
	v_fma_f32 v20, v28, v30, v20
	v_fma_f32 v21, v28, v31, v21
	s_waitcnt vmcnt(0)
	v_fma_f32 v18, v24, v30, v18
	v_fma_f32 v19, v24, v31, v19
	global_load_dword v24, v[26:27], off
	s_nop 0
	global_load_dword v26, v[26:27], off offset:2048
	ds_read2_b32 v[28:29], v23 offset0:4 offset1:5
	ds_read2_b32 v[30:31], v23 offset0:132 offset1:133
	s_waitcnt lgkmcnt(1)
	v_mov_b32_e32 v32, v28
	s_waitcnt lgkmcnt(0)
	v_mov_b32_e32 v33, v30
	v_mov_b32_e32 v30, v29
	s_waitcnt vmcnt(1)
	v_fma_f32 v20, v24, v32, v20
	v_fma_f32 v21, v24, v33, v21
	v_add_co_u32_e32 v24, vcc, s25, v16
	s_waitcnt vmcnt(0)
	v_fma_f32 v18, v26, v32, v18
	v_fma_f32 v19, v26, v33, v19
	v_addc_co_u32_e32 v25, vcc, 0, v17, vcc
	v_add_co_u32_e32 v26, vcc, s26, v16
	s_nop 1
	v_addc_co_u32_e32 v27, vcc, 0, v17, vcc
	global_load_dword v28, v[26:27], off offset:-4096
	s_nop 0
	global_load_dword v24, v[24:25], off offset:2048
	v_add_co_u32_e32 v16, vcc, s28, v16
	s_waitcnt vmcnt(1)
	v_fma_f32 v20, v28, v30, v20
	v_fma_f32 v21, v28, v31, v21
	s_waitcnt vmcnt(0)
	v_fma_f32 v18, v24, v30, v18
	v_fma_f32 v19, v24, v31, v19
	global_load_dword v24, v[26:27], off
	s_nop 0
	global_load_dword v26, v[26:27], off offset:2048
	ds_read2_b32 v[28:29], v23 offset0:6 offset1:7
	ds_read2_b32 v[30:31], v23 offset0:134 offset1:135
	v_addc_co_u32_e32 v17, vcc, 0, v17, vcc
	s_waitcnt lgkmcnt(1)
	v_mov_b32_e32 v32, v28
	s_waitcnt lgkmcnt(0)
	v_mov_b32_e32 v33, v30
	v_mov_b32_e32 v30, v29
	s_waitcnt vmcnt(1)
	v_fma_f32 v20, v24, v32, v20
	v_fma_f32 v21, v24, v33, v21
	global_load_dword v24, v[16:17], off
	s_nop 0
	global_load_dword v16, v[16:17], off offset:2048
	s_waitcnt vmcnt(2)
	v_fma_f32 v18, v26, v32, v18
	v_fma_f32 v19, v26, v33, v19
	s_waitcnt vmcnt(1)
	v_fma_f32 v20, v24, v30, v20
	v_fma_f32 v21, v24, v31, v21
	s_waitcnt vmcnt(0)
	v_fma_f32 v18, v16, v30, v18
	v_fma_f32 v19, v16, v31, v19
	s_cbranch_scc0 .LBB0_690
	v_lshlrev_b64 v[12:13], 1, v[12:13]
	v_lshl_add_u64 v[14:15], v[6:7], 0, v[12:13]
	s_lshl_b32 s86, s86, 1
	v_cvt_pk_bf16_f32 v16, v20, v21
	v_lshl_add_u64 v[14:15], v[14:15], 0, s[86:87]
	v_lshl_add_u64 v[12:13], v[8:9], 0, v[12:13]
	s_add_i32 s34, s34, s30
	global_store_dword v[14:15], v16, off offset:1024
	v_cvt_pk_bf16_f32 v14, v18, v19
	v_lshl_add_u64 v[12:13], v[12:13], 0, s[86:87]
	s_cmpk_gt_i32 s34, 0xff
	global_store_dword v[12:13], v14, off offset:1024
	s_cbranch_scc0 .LBB0_685

.LBB0_731:
	v_mov_b32_dpp v242, v126 row_ror:1 row_mask:0xf bank_mask:0xf
	v_mov_b32_dpp v243, v127 row_ror:1 row_mask:0xf bank_mask:0xf
	v_mov_b32_dpp v178, v126 row_ror:15 row_mask:0xf bank_mask:0xf
	v_mov_b32_dpp v179, v127 row_ror:15 row_mask:0xf bank_mask:0xf
	v_mov_b32_dpp v244, v128 row_ror:1 row_mask:0xf bank_mask:0xf
	v_mov_b32_dpp v245, v129 row_ror:1 row_mask:0xf bank_mask:0xf
	v_mov_b32_dpp v246, v138 row_ror:15 row_mask:0xf bank_mask:0xf
	v_mov_b32_dpp v248, v139 row_ror:15 row_mask:0xf bank_mask:0xf
	v_mov_b32_dpp v194, v128 row_ror:15 row_mask:0xf bank_mask:0xf
	v_mov_b32_dpp v195, v129 row_ror:15 row_mask:0xf bank_mask:0xf
	v_mov_b32_dpp v247, v140 row_ror:15 row_mask:0xf bank_mask:0xf
	v_mov_b32_dpp v249, v141 row_ror:15 row_mask:0xf bank_mask:0xf
	s_waitcnt lgkmcnt(0)
	v_cndmask_b32_e64 v167, v243, v167, s[40:41]
	v_cndmask_b32_e64 v166, v242, v166, s[40:41]
	s_waitcnt vmcnt(0)
	v_fma_f32 v166, v154, v166, v158
	v_fma_f32 v167, v155, v167, v159
	v_cndmask_b32_e64 v169, v245, v169, s[40:41]
	v_cndmask_b32_e64 v168, v244, v168, s[40:41]
	v_cndmask_b32_e64 v179, v179, v248, s[42:43]
	v_cndmask_b32_e64 v178, v178, v246, s[42:43]
	v_fma_f32 v166, v126, v150, v166
	v_fma_f32 v167, v127, v151, v167
	v_fma_f32 v168, v156, v168, v160
	v_fma_f32 v169, v157, v169, v161
	v_fma_f32 v166, v146, v178, v166
	v_fma_f32 v167, v147, v179, v167
	v_cndmask_b32_e64 v195, v195, v249, s[42:43]
	v_cndmask_b32_e64 v194, v194, v247, s[42:43]
	v_fma_f32 v168, v128, v152, v168
	v_fma_f32 v169, v129, v153, v169
	v_mul_f32_e32 v178, s100, v166
	v_mul_f32_e32 v179, s100, v167
	v_exp_f32_e32 v178, v178
	v_exp_f32_e32 v179, v179
	v_fma_f32 v168, v148, v194, v168
	v_fma_f32 v169, v149, v195, v169
	s_mul_i32 s0, s52, 0x10800
	v_mul_f32_e32 v194, s100, v168
	v_mul_f32_e32 v195, s100, v169
	v_exp_f32_e32 v194, v194
	v_exp_f32_e32 v195, v195
	v_add_f32_e32 v178, 1.0, v178
	v_add_f32_e32 v179, 1.0, v179
	v_rcp_f32_e32 v178, v178
	v_rcp_f32_e32 v179, v179
	v_add_f32_e32 v194, 1.0, v194
	v_add_f32_e32 v195, 1.0, v195
	v_rcp_f32_e32 v194, v194
	v_rcp_f32_e32 v195, v195
	s_mul_hi_i32 s1, s52, 0x10800
	s_add_u32 s0, s82, s0
	v_mov_b32_dpp v213, v138 row_ror:1 row_mask:0xf bank_mask:0xf
	v_mov_b32_dpp v215, v139 row_ror:1 row_mask:0xf bank_mask:0xf
	v_mov_b32_dpp v216, v140 row_ror:1 row_mask:0xf bank_mask:0xf
	v_mov_b32_dpp v218, v141 row_ror:1 row_mask:0xf bank_mask:0xf
	v_mov_b32_dpp v205, v130 row_ror:1 row_mask:0xf bank_mask:0xf
	v_mov_b32_dpp v214, v130 row_ror:15 row_mask:0xf bank_mask:0xf
	v_mov_b32_dpp v207, v131 row_ror:1 row_mask:0xf bank_mask:0xf
	v_mov_b32_dpp v219, v131 row_ror:15 row_mask:0xf bank_mask:0xf
	v_mov_b32_dpp v206, v132 row_ror:1 row_mask:0xf bank_mask:0xf
	v_mov_b32_dpp v217, v132 row_ror:15 row_mask:0xf bank_mask:0xf
	v_mov_b32_dpp v208, v133 row_ror:1 row_mask:0xf bank_mask:0xf
	v_mov_b32_dpp v220, v133 row_ror:15 row_mask:0xf bank_mask:0xf
	v_mov_b32_dpp v209, v114 row_ror:1 row_mask:0xf bank_mask:0xf
	v_mov_b32_dpp v221, v114 row_ror:15 row_mask:0xf bank_mask:0xf
	v_mov_b32_dpp v211, v115 row_ror:1 row_mask:0xf bank_mask:0xf
	v_mov_b32_dpp v223, v115 row_ror:15 row_mask:0xf bank_mask:0xf
	v_mov_b32_dpp v210, v116 row_ror:1 row_mask:0xf bank_mask:0xf
	v_mov_b32_dpp v222, v116 row_ror:15 row_mask:0xf bank_mask:0xf
	v_mov_b32_dpp v212, v117 row_ror:1 row_mask:0xf bank_mask:0xf
	v_mov_b32_dpp v250, v117 row_ror:15 row_mask:0xf bank_mask:0xf
	v_mul_f32_e32 v178, v166, v178
	v_mul_f32_e32 v179, v167, v179
	s_addc_u32 s1, s83, s1
	v_mul_f32_e32 v178, v142, v178
	v_mul_f32_e32 v179, v143, v179
	v_lshl_add_u64 v[176:177], v[180:181], 2, s[0:1]
	v_lshl_add_u32 v204, s52, 8, v183
	v_mul_f32_e32 v194, v168, v194
	v_mul_f32_e32 v195, v169, v195
	v_cvt_pk_bf16_f32 v196, v178, v179
	v_mov_b64_e32 v[178:179], s[22:23]
	s_movk_i32 s0, 0x1600
	v_mul_f32_e32 v194, v144, v194
	v_mul_f32_e32 v195, v145, v195
	v_mad_i64_i32 v[178:179], s[0:1], v204, s0, v[178:179]
	v_cvt_pk_bf16_f32 v197, v194, v195
	v_lshl_add_u64 v[178:179], v[180:181], 1, v[178:179]
	global_store_dwordx2 v[178:179], v[196:197], off
	s_and_saveexec_b64 s[20:21], s[44:45]
	s_cbranch_execz .LBB0_733
	global_store_dwordx4 v[176:177], v[166:169], off
	s_nop 1
	v_add_co_u32_e32 v166, vcc, 0x2000, v176
	s_nop 1
	v_addc_co_u32_e32 v167, vcc, 0, v177, vcc
	global_store_dwordx4 v[166:167], v[142:145], off offset:3072
	s_nop 1
	v_add_co_u32_e32 v142, vcc, 0x5000, v176
	s_nop 1
	v_addc_co_u32_e32 v143, vcc, 0, v177, vcc
	global_store_dwordx4 v[142:143], v[126:129], off offset:2048
.LBB0_733:
	s_or_b64 exec, exec, s[20:21]
	s_waitcnt lgkmcnt(0)
	v_cndmask_b32_e64 v126, v213, v242, s[40:41]
	v_cndmask_b32_e64 v127, v215, v243, s[40:41]
	v_cndmask_b32_e64 v128, v216, v244, s[40:41]
	v_cndmask_b32_e64 v129, v218, v245, s[40:41]
	v_fma_f32 v128, v156, v128, v160
	v_fma_f32 v129, v157, v129, v161
	v_fma_f32 v126, v154, v126, v158
	v_fma_f32 v127, v155, v127, v159
	s_waitcnt lgkmcnt(0)
	v_cndmask_b32_e64 v143, v248, v219, s[42:43]
	v_cndmask_b32_e64 v142, v246, v214, s[42:43]
	s_waitcnt lgkmcnt(0)
	v_cndmask_b32_e64 v145, v249, v220, s[42:43]
	v_cndmask_b32_e64 v144, v247, v217, s[42:43]
	v_fma_f32 v126, v138, v150, v126
	v_fma_f32 v127, v139, v151, v127
	v_fma_f32 v128, v140, v152, v128
	v_fma_f32 v129, v141, v153, v129
	v_fma_f32 v126, v146, v142, v126
	v_fma_f32 v127, v147, v143, v127
	v_fma_f32 v128, v148, v144, v128
	v_fma_f32 v129, v149, v145, v129
	v_mul_f32_e32 v138, s100, v126
	v_mul_f32_e32 v139, s100, v127
	v_mul_f32_e32 v140, s100, v128
	v_mul_f32_e32 v141, s100, v129
	v_exp_f32_e32 v138, v138
	v_exp_f32_e32 v139, v139
	v_exp_f32_e32 v140, v140
	v_exp_f32_e32 v141, v141
	v_add_f32_e32 v138, 1.0, v138
	v_add_f32_e32 v139, 1.0, v139
	v_add_f32_e32 v140, 1.0, v140
	v_add_f32_e32 v141, 1.0, v141
	v_rcp_f32_e32 v138, v138
	v_rcp_f32_e32 v139, v139
	v_rcp_f32_e32 v140, v140
	v_rcp_f32_e32 v141, v141
	v_or_b32_e32 v142, 16, v204
	v_mul_f32_e32 v126, v126, v138
	v_mul_f32_e32 v127, v127, v139
	s_movk_i32 s18, 0x1600
	v_mul_f32_e32 v128, v128, v140
	v_mul_f32_e32 v129, v129, v141
	v_mul_f32_e32 v126, v134, v126
	v_mul_f32_e32 v127, v135, v127
	v_mul_f32_e32 v128, v136, v128
	v_mul_f32_e32 v129, v137, v129
	v_mov_b64_e32 v[136:137], s[22:23]
	v_cvt_pk_bf16_f32 v134, v126, v127
	v_cvt_pk_bf16_f32 v135, v128, v129
	v_mad_i64_i32 v[126:127], s[0:1], v142, s18, v[136:137]
	v_lshlrev_b64 v[128:129], 1, v[180:181]
	v_lshl_add_u64 v[126:127], v[126:127], 0, v[128:129]
	global_store_dwordx2 v[126:127], v[134:135], off
	v_cndmask_b32_e64 v134, v205, v213, s[40:41]
	v_cndmask_b32_e64 v135, v207, v215, s[40:41]
	v_cndmask_b32_e64 v138, v206, v216, s[40:41]
	v_cndmask_b32_e64 v139, v208, v218, s[40:41]
	v_fma_f32 v134, v154, v134, v158
	v_fma_f32 v135, v155, v135, v159
	s_waitcnt lgkmcnt(0)
	v_cndmask_b32_e64 v145, v219, v223, s[42:43]
	v_cndmask_b32_e64 v144, v214, v221, s[42:43]
	v_fma_f32 v138, v156, v138, v160
	v_fma_f32 v139, v157, v139, v161
	v_fma_f32 v130, v130, v150, v134
	v_fma_f32 v131, v131, v151, v135
	v_cndmask_b32_e64 v141, v223, v163, s[42:43]
	v_cndmask_b32_e64 v140, v221, v162, s[42:43]
	s_waitcnt lgkmcnt(0)
	v_cndmask_b32_e64 v163, v220, v250, s[42:43]
	v_cndmask_b32_e64 v162, v217, v222, s[42:43]
	v_fma_f32 v132, v132, v152, v138
	v_fma_f32 v133, v133, v153, v139
	v_fma_f32 v130, v146, v144, v130
	v_fma_f32 v131, v147, v145, v131
	v_fma_f32 v132, v148, v162, v132
	v_fma_f32 v133, v149, v163, v133
	v_mul_f32_e32 v134, s100, v130
	v_mul_f32_e32 v135, s100, v131
	v_exp_f32_e32 v134, v134
	v_exp_f32_e32 v135, v135
	v_mul_f32_e32 v138, s100, v132
	v_mul_f32_e32 v139, s100, v133
	v_exp_f32_e32 v138, v138
	v_exp_f32_e32 v139, v139
	v_add_f32_e32 v134, 1.0, v134
	v_add_f32_e32 v135, 1.0, v135
	v_rcp_f32_e32 v134, v134
	v_rcp_f32_e32 v135, v135
	v_add_f32_e32 v138, 1.0, v138
	v_add_f32_e32 v139, 1.0, v139
	v_rcp_f32_e32 v138, v138
	v_rcp_f32_e32 v139, v139
	v_mul_f32_e32 v130, v130, v134
	v_mul_f32_e32 v131, v131, v135
	v_or_b32_e32 v144, 32, v204
	v_mul_f32_e32 v122, v122, v130
	v_mul_f32_e32 v123, v123, v131
	v_mul_f32_e32 v130, v132, v138
	v_mul_f32_e32 v131, v133, v139
	v_cndmask_b32_e64 v143, v250, v165, s[42:43]
	v_mul_f32_e32 v124, v124, v130
	v_mul_f32_e32 v125, v125, v131
	v_cvt_pk_bf16_f32 v130, v122, v123
	v_mad_i64_i32 v[122:123], s[0:1], v144, s18, v[136:137]
	v_cvt_pk_bf16_f32 v131, v124, v125
	v_lshl_add_u64 v[122:123], v[122:123], 0, v[128:129]
	global_store_dwordx2 v[122:123], v[130:131], off
	v_cndmask_b32_e64 v125, v211, v207, s[40:41]
	v_cndmask_b32_e64 v124, v209, v205, s[40:41]
	v_cndmask_b32_e64 v131, v212, v208, s[40:41]
	v_cndmask_b32_e64 v130, v210, v206, s[40:41]
	v_fma_f32 v130, v156, v130, v160
	v_fma_f32 v131, v157, v131, v161
	v_fma_f32 v124, v154, v124, v158
	v_fma_f32 v125, v155, v125, v159
	v_cndmask_b32_e64 v142, v222, v164, s[42:43]
	v_fma_f32 v114, v114, v150, v124
	v_fma_f32 v115, v115, v151, v125
	v_fma_f32 v116, v116, v152, v130
	v_fma_f32 v117, v117, v153, v131
	v_fma_f32 v114, v146, v140, v114
	v_fma_f32 v115, v147, v141, v115
	v_fma_f32 v116, v148, v142, v116
	v_fma_f32 v117, v149, v143, v117
	v_mul_f32_e32 v124, s100, v114
	v_mul_f32_e32 v125, s100, v115
	v_mul_f32_e32 v130, s100, v116
	v_mul_f32_e32 v131, s100, v117
	v_exp_f32_e32 v124, v124
	v_exp_f32_e32 v125, v125
	v_exp_f32_e32 v130, v130
	v_exp_f32_e32 v131, v131
	v_add_f32_e32 v124, 1.0, v124
	v_add_f32_e32 v125, 1.0, v125
	v_add_f32_e32 v130, 1.0, v130
	v_add_f32_e32 v131, 1.0, v131
	v_rcp_f32_e32 v124, v124
	v_rcp_f32_e32 v125, v125
	v_rcp_f32_e32 v130, v130
	v_rcp_f32_e32 v131, v131
	v_or_b32_e32 v132, 48, v204
	v_mul_f32_e32 v114, v114, v124
	v_mul_f32_e32 v115, v115, v125
	s_andn2_b64 vcc, exec, s[70:71]
	v_mul_f32_e32 v116, v116, v130
	v_mul_f32_e32 v117, v117, v131
	v_mul_f32_e32 v114, v118, v114
	v_mul_f32_e32 v115, v119, v115
	v_mul_f32_e32 v116, v120, v116
	v_mul_f32_e32 v117, v121, v117
	v_cvt_pk_bf16_f32 v114, v114, v115
	v_cvt_pk_bf16_f32 v115, v116, v117
	v_mad_i64_i32 v[116:117], s[0:1], v132, s18, v[136:137]
	v_lshl_add_u64 v[124:125], v[116:117], 0, v[128:129]
	global_store_dwordx2 v[124:125], v[114:115], off
	v_cndmask_b32_e64 v115, 0, 1, s[70:71]
	v_mov_b32_e32 v114, 0
	v_cmp_ne_u32_e64 s[52:53], 1, v115
	v_mov_b32_e32 v118, 0
	v_mov_b32_e32 v119, 0
	v_mov_b32_e32 v120, 0
	v_mov_b32_e32 v121, 0
	s_cbranch_vccnz .LBB0_735
	ds_read_b128 v[118:121], v187 offset:1536

.LBB0_737:
	v_mov_b32_dpp v136, v108 row_ror:1 row_mask:0xf bank_mask:0xf
	v_mov_b32_dpp v137, v109 row_ror:1 row_mask:0xf bank_mask:0xf
	v_mov_b32_dpp v134, v106 row_ror:1 row_mask:0xf bank_mask:0xf
	v_mov_b32_dpp v135, v107 row_ror:1 row_mask:0xf bank_mask:0xf
	v_mov_b32_dpp v132, v108 row_ror:15 row_mask:0xf bank_mask:0xf
	v_mov_b32_dpp v133, v109 row_ror:15 row_mask:0xf bank_mask:0xf
	v_mov_b32_dpp v143, v104 row_ror:15 row_mask:0xf bank_mask:0xf
	v_mov_b32_dpp v145, v105 row_ror:15 row_mask:0xf bank_mask:0xf
	v_mov_b32_dpp v130, v106 row_ror:15 row_mask:0xf bank_mask:0xf
	v_mov_b32_dpp v131, v107 row_ror:15 row_mask:0xf bank_mask:0xf
	v_mov_b32_dpp v139, v102 row_ror:15 row_mask:0xf bank_mask:0xf
	v_mov_b32_dpp v141, v103 row_ror:15 row_mask:0xf bank_mask:0xf
	s_waitcnt lgkmcnt(0)
	v_cndmask_b32_e64 v121, v137, v121, s[40:41]
	v_cndmask_b32_e64 v120, v136, v120, s[40:41]
	s_waitcnt lgkmcnt(0)
	v_cndmask_b32_e64 v119, v135, v119, s[40:41]
	v_cndmask_b32_e64 v118, v134, v118, s[40:41]
	v_fma_f32 v120, v156, v120, v160
	v_fma_f32 v121, v157, v121, v161
	s_waitcnt lgkmcnt(0)
	v_cndmask_b32_e64 v133, v133, v145, s[42:43]
	v_cndmask_b32_e64 v132, v132, v143, s[42:43]
	v_fma_f32 v118, v154, v118, v158
	v_fma_f32 v119, v155, v119, v159
	v_fma_f32 v108, v108, v152, v120
	v_fma_f32 v109, v109, v153, v121
	s_waitcnt lgkmcnt(0)
	v_cndmask_b32_e64 v131, v131, v141, s[42:43]
	v_cndmask_b32_e64 v130, v130, v139, s[42:43]
	v_fma_f32 v106, v106, v150, v118
	v_fma_f32 v107, v107, v151, v119
	v_fma_f32 v108, v148, v132, v108
	v_fma_f32 v109, v149, v133, v109
	v_fma_f32 v106, v146, v130, v106
	v_fma_f32 v107, v147, v131, v107
	v_mul_f32_e32 v120, s100, v108
	v_mul_f32_e32 v121, s100, v109
	v_mul_f32_e32 v118, s100, v106
	v_mul_f32_e32 v119, s100, v107
	v_exp_f32_e32 v120, v120
	v_exp_f32_e32 v121, v121
	v_exp_f32_e32 v118, v118
	v_exp_f32_e32 v119, v119
	v_add_f32_e32 v120, 1.0, v120
	v_add_f32_e32 v121, 1.0, v121
	v_add_f32_e32 v118, 1.0, v118
	v_add_f32_e32 v119, 1.0, v119
	v_rcp_f32_e32 v120, v120
	v_rcp_f32_e32 v121, v121
	v_rcp_f32_e32 v118, v118
	v_rcp_f32_e32 v119, v119
	v_mov_b32_dpp v138, v102 row_ror:1 row_mask:0xf bank_mask:0xf
	v_mov_b32_dpp v140, v103 row_ror:1 row_mask:0xf bank_mask:0xf
	v_mul_f32_e32 v108, v108, v120
	v_mul_f32_e32 v109, v109, v121
	v_mov_b32_dpp v142, v104 row_ror:1 row_mask:0xf bank_mask:0xf
	v_mov_b32_dpp v144, v105 row_ror:1 row_mask:0xf bank_mask:0xf
	v_mul_f32_e32 v106, v106, v118
	v_mul_f32_e32 v107, v107, v119
	v_mul_f32_e32 v108, v112, v108
	v_mul_f32_e32 v109, v113, v109
	v_mov_b32_dpp v163, v94 row_ror:15 row_mask:0xf bank_mask:0xf
	v_mov_b32_dpp v165, v95 row_ror:15 row_mask:0xf bank_mask:0xf
	v_add_u32_e32 v130, 0x80, v204
	v_mul_f32_e32 v106, v110, v106
	v_mul_f32_e32 v107, v111, v107
	v_cvt_pk_bf16_f32 v111, v108, v109
	v_mov_b64_e32 v[108:109], s[22:23]
	v_mov_b32_dpp v167, v96 row_ror:15 row_mask:0xf bank_mask:0xf
	v_mov_b32_dpp v169, v97 row_ror:15 row_mask:0xf bank_mask:0xf
	v_cvt_pk_bf16_f32 v110, v106, v107
	v_mad_i64_i32 v[106:107], s[0:1], v130, s18, v[108:109]
	v_lshl_add_u64 v[106:107], v[106:107], 0, v[128:129]
	global_store_dwordx2 v[106:107], v[110:111], off
	s_waitcnt lgkmcnt(0)
	v_cndmask_b32_e64 v111, v140, v135, s[40:41]
	v_cndmask_b32_e64 v110, v138, v134, s[40:41]
	s_waitcnt lgkmcnt(0)
	v_cndmask_b32_e64 v113, v144, v137, s[40:41]
	v_cndmask_b32_e64 v112, v142, v136, s[40:41]
	v_fma_f32 v110, v154, v110, v158
	v_fma_f32 v111, v155, v111, v159
	s_waitcnt lgkmcnt(0)
	v_cndmask_b32_e64 v118, v139, v163, s[42:43]
	s_waitcnt lgkmcnt(0)
	v_cndmask_b32_e64 v119, v141, v165, s[42:43]
	v_fma_f32 v112, v156, v112, v160
	v_fma_f32 v113, v157, v113, v161
	v_fma_f32 v102, v102, v150, v110
	v_fma_f32 v103, v103, v151, v111
	s_waitcnt lgkmcnt(0)
	v_cndmask_b32_e64 v120, v143, v167, s[42:43]
	s_waitcnt lgkmcnt(0)
	v_cndmask_b32_e64 v121, v145, v169, s[42:43]
	v_fma_f32 v104, v104, v152, v112
	v_fma_f32 v105, v105, v153, v113
	v_fma_f32 v102, v146, v118, v102
	v_fma_f32 v103, v147, v119, v103
	v_fma_f32 v104, v148, v120, v104
	v_fma_f32 v105, v149, v121, v105
	v_mul_f32_e32 v110, s100, v102
	v_mul_f32_e32 v111, s100, v103
	v_exp_f32_e32 v110, v110
	v_exp_f32_e32 v111, v111
	v_mul_f32_e32 v112, s100, v104
	v_mul_f32_e32 v113, s100, v105
	v_exp_f32_e32 v112, v112
	v_exp_f32_e32 v113, v113
	v_add_f32_e32 v110, 1.0, v110
	v_add_f32_e32 v111, 1.0, v111
	v_rcp_f32_e32 v110, v110
	v_rcp_f32_e32 v111, v111
	v_add_f32_e32 v112, 1.0, v112
	v_add_f32_e32 v113, 1.0, v113
	v_rcp_f32_e32 v112, v112
	v_rcp_f32_e32 v113, v113
	v_mov_b32_dpp v162, v94 row_ror:1 row_mask:0xf bank_mask:0xf
	v_mov_b32_dpp v164, v95 row_ror:1 row_mask:0xf bank_mask:0xf
	v_mov_b32_dpp v166, v96 row_ror:1 row_mask:0xf bank_mask:0xf
	v_mov_b32_dpp v168, v97 row_ror:1 row_mask:0xf bank_mask:0xf
	v_mov_b32_dpp v181, v66 row_ror:15 row_mask:0xf bank_mask:0xf
	v_mov_b32_dpp v195, v67 row_ror:15 row_mask:0xf bank_mask:0xf
	v_mul_f32_e32 v102, v102, v110
	v_mul_f32_e32 v103, v103, v111
	v_mov_b32_dpp v197, v68 row_ror:15 row_mask:0xf bank_mask:0xf
	v_mov_b32_dpp v206, v69 row_ror:15 row_mask:0xf bank_mask:0xf
	v_add_u32_e32 v118, 0x90, v204
	v_mul_f32_e32 v98, v98, v102
	v_mul_f32_e32 v99, v99, v103
	v_mul_f32_e32 v102, v104, v112
	v_mul_f32_e32 v103, v105, v113
	s_waitcnt lgkmcnt(0)
	v_cndmask_b32_e64 v104, v163, v181, s[42:43]
	v_mul_f32_e32 v100, v100, v102
	v_mul_f32_e32 v101, v101, v103
	v_cvt_pk_bf16_f32 v102, v98, v99
	v_mad_i64_i32 v[98:99], s[0:1], v118, s18, v[108:109]
	v_cvt_pk_bf16_f32 v103, v100, v101
	v_lshl_add_u64 v[98:99], v[98:99], 0, v[128:129]
	v_cndmask_b32_e64 v101, v164, v140, s[40:41]
	v_cndmask_b32_e64 v100, v162, v138, s[40:41]
	global_store_dwordx2 v[98:99], v[102:103], off
	v_cndmask_b32_e64 v103, v168, v144, s[40:41]
	v_cndmask_b32_e64 v102, v166, v142, s[40:41]
	v_fma_f32 v100, v154, v100, v158
	v_fma_f32 v101, v155, v101, v159
	s_waitcnt lgkmcnt(0)
	v_cndmask_b32_e64 v105, v165, v195, s[42:43]
	v_fma_f32 v102, v156, v102, v160
	v_fma_f32 v103, v157, v103, v161
	v_fma_f32 v94, v94, v150, v100
	v_fma_f32 v95, v95, v151, v101
	s_waitcnt lgkmcnt(0)
	v_cndmask_b32_e64 v110, v167, v197, s[42:43]
	s_waitcnt lgkmcnt(0)
	v_cndmask_b32_e64 v111, v169, v206, s[42:43]
	v_fma_f32 v96, v96, v152, v102
	v_fma_f32 v97, v97, v153, v103
	v_fma_f32 v94, v146, v104, v94
	v_fma_f32 v95, v147, v105, v95
	v_fma_f32 v96, v148, v110, v96
	v_fma_f32 v97, v149, v111, v97
	v_mul_f32_e32 v100, s100, v94
	v_mul_f32_e32 v101, s100, v95
	v_exp_f32_e32 v100, v100
	v_exp_f32_e32 v101, v101
	v_mul_f32_e32 v102, s100, v96
	v_mul_f32_e32 v103, s100, v97
	v_exp_f32_e32 v102, v102
	v_exp_f32_e32 v103, v103
	v_add_f32_e32 v100, 1.0, v100
	v_add_f32_e32 v101, 1.0, v101
	v_rcp_f32_e32 v100, v100
	v_rcp_f32_e32 v101, v101
	v_add_f32_e32 v102, 1.0, v102
	v_add_f32_e32 v103, 1.0, v103
	v_rcp_f32_e32 v102, v102
	v_rcp_f32_e32 v103, v103
	v_mov_b32_dpp v180, v66 row_ror:1 row_mask:0xf bank_mask:0xf
	v_mov_b32_dpp v194, v67 row_ror:1 row_mask:0xf bank_mask:0xf
	v_mul_f32_e32 v94, v94, v100
	v_mul_f32_e32 v95, v95, v101
	v_mov_b32_dpp v196, v68 row_ror:1 row_mask:0xf bank_mask:0xf
	v_mov_b32_dpp v205, v69 row_ror:1 row_mask:0xf bank_mask:0xf
	v_mul_f32_e32 v90, v90, v94
	v_mul_f32_e32 v91, v91, v95
	v_mul_f32_e32 v94, v96, v102
	v_mul_f32_e32 v95, v97, v103
	v_add_u32_e32 v104, 0xa0, v204
	v_mul_f32_e32 v92, v92, v94
	v_mul_f32_e32 v93, v93, v95
	v_cvt_pk_bf16_f32 v90, v90, v91
	v_cvt_pk_bf16_f32 v91, v92, v93
	v_mad_i64_i32 v[92:93], s[0:1], v104, s18, v[108:109]
	v_lshl_add_u64 v[94:95], v[92:93], 0, v[128:129]
	global_store_dwordx2 v[94:95], v[90:91], off
	s_waitcnt lgkmcnt(0)
	v_cndmask_b32_e64 v91, v194, v164, s[40:41]
	v_cndmask_b32_e64 v90, v180, v162, s[40:41]
	s_waitcnt lgkmcnt(0)
	v_cndmask_b32_e64 v93, v205, v168, s[40:41]
	v_cndmask_b32_e64 v92, v196, v166, s[40:41]
	v_fma_f32 v90, v154, v90, v158
	v_fma_f32 v91, v155, v91, v159
	v_cndmask_b32_e64 v97, v195, v115, s[42:43]
	v_cndmask_b32_e64 v96, v181, v114, s[42:43]
	v_fma_f32 v92, v156, v92, v160
	v_fma_f32 v93, v157, v93, v161
	v_fma_f32 v90, v66, v150, v90
	v_fma_f32 v91, v67, v151, v91
	v_cndmask_b32_e64 v101, v206, v117, s[42:43]
	v_cndmask_b32_e64 v100, v197, v116, s[42:43]
	v_fma_f32 v92, v68, v152, v92
	v_fma_f32 v93, v69, v153, v93
	v_fma_f32 v90, v146, v96, v90
	v_fma_f32 v91, v147, v97, v91
	v_fma_f32 v92, v148, v100, v92
	v_fma_f32 v93, v149, v101, v93
	v_mul_f32_e32 v96, s100, v90
	v_mul_f32_e32 v97, s100, v91
	v_exp_f32_e32 v96, v96
	v_exp_f32_e32 v97, v97
	v_mul_f32_e32 v100, s100, v92
	v_mul_f32_e32 v101, s100, v93
	v_exp_f32_e32 v100, v100
	v_exp_f32_e32 v101, v101
	v_add_f32_e32 v96, 1.0, v96
	v_add_f32_e32 v97, 1.0, v97
	v_rcp_f32_e32 v96, v96
	v_rcp_f32_e32 v97, v97
	v_add_f32_e32 v100, 1.0, v100
	v_add_f32_e32 v101, 1.0, v101
	v_rcp_f32_e32 v100, v100
	v_rcp_f32_e32 v101, v101
	v_mul_f32_e32 v96, v90, v96
	v_mul_f32_e32 v97, v91, v97
	v_add_u32_e32 v104, 0xb0, v204
	v_mul_f32_e32 v96, v70, v96
	v_mul_f32_e32 v97, v71, v97
	v_mul_f32_e32 v100, v92, v100
	v_mul_f32_e32 v101, v93, v101
	v_cvt_pk_bf16_f32 v102, v96, v97
	v_mul_f32_e32 v100, v72, v100
	v_mul_f32_e32 v101, v73, v101
	v_mad_i64_i32 v[96:97], s[0:1], v104, s18, v[108:109]
	v_cvt_pk_bf16_f32 v103, v100, v101
	v_lshl_add_u64 v[96:97], v[96:97], 0, v[128:129]
	global_store_dwordx2 v[96:97], v[102:103], off
	s_and_saveexec_b64 s[20:21], s[74:75]
	s_cbranch_execz .LBB0_739
	v_add_co_u32_e32 v100, vcc, 0x8000, v176
	s_nop 1
	v_addc_co_u32_e32 v101, vcc, 0, v177, vcc
	global_store_dwordx4 v[100:101], v[90:93], off offset:1024
	s_nop 1
	v_add_co_u32_e32 v90, vcc, 0xb000, v176
	s_nop 1
	v_addc_co_u32_e32 v91, vcc, 0, v177, vcc
	global_store_dwordx4 v[90:91], v[70:73], off
	s_nop 1
	v_add_co_u32_e32 v70, vcc, 0xd000, v176
	s_nop 1
	v_addc_co_u32_e32 v71, vcc, 0, v177, vcc
	global_store_dwordx4 v[70:71], v[66:69], off offset:3072

.LBB0_743:
	v_mov_b32_dpp v117, v46 row_ror:1 row_mask:0xf bank_mask:0xf
	v_mov_b32_dpp v118, v47 row_ror:1 row_mask:0xf bank_mask:0xf
	v_mov_b32_dpp v131, v46 row_ror:15 row_mask:0xf bank_mask:0xf
	v_mov_b32_dpp v132, v47 row_ror:15 row_mask:0xf bank_mask:0xf
	v_mov_b32_dpp v121, v58 row_ror:15 row_mask:0xf bank_mask:0xf
	v_mov_b32_dpp v129, v59 row_ror:15 row_mask:0xf bank_mask:0xf
	s_waitcnt lgkmcnt(0)
	v_cndmask_b32_e64 v71, v118, v71, s[40:41]
	v_cndmask_b32_e64 v70, v117, v70, s[40:41]
	v_mov_b32_dpp v119, v48 row_ror:1 row_mask:0xf bank_mask:0xf
	v_mov_b32_dpp v120, v49 row_ror:1 row_mask:0xf bank_mask:0xf
	v_fma_f32 v70, v82, v70, v86
	v_fma_f32 v71, v83, v71, v87
	s_waitcnt lgkmcnt(0)
	v_cndmask_b32_e64 v133, v132, v129, s[42:43]
	v_cndmask_b32_e64 v132, v131, v121, s[42:43]
	v_fma_f32 v70, v46, v78, v70
	v_fma_f32 v71, v47, v79, v71
	v_mov_b32_dpp v134, v48 row_ror:15 row_mask:0xf bank_mask:0xf
	v_mov_b32_dpp v135, v49 row_ror:15 row_mask:0xf bank_mask:0xf
	v_mov_b32_dpp v128, v60 row_ror:15 row_mask:0xf bank_mask:0xf
	v_mov_b32_dpp v130, v61 row_ror:15 row_mask:0xf bank_mask:0xf
	v_fma_f32 v70, v74, v132, v70
	v_fma_f32 v71, v75, v133, v71
	s_waitcnt lgkmcnt(0)
	v_cndmask_b32_e64 v73, v120, v73, s[40:41]
	v_mul_f32_e32 v131, 0xbfb8aa3b, v70
	v_exp_f32_e32 v131, v131
	v_mul_f32_e32 v132, 0xbfb8aa3b, v71
	v_cndmask_b32_e64 v72, v119, v72, s[40:41]
	v_exp_f32_e32 v133, v132
	v_fma_f32 v72, v84, v72, v88
	v_fma_f32 v73, v85, v73, v89
	s_waitcnt lgkmcnt(0)
	v_cndmask_b32_e64 v135, v135, v130, s[42:43]
	v_cndmask_b32_e64 v134, v134, v128, s[42:43]
	v_fma_f32 v72, v48, v80, v72
	v_fma_f32 v73, v49, v81, v73
	v_add_f32_e32 v131, 1.0, v131
	v_fma_f32 v72, v76, v134, v72
	v_fma_f32 v73, v77, v135, v73
	v_rcp_f32_e32 v132, v131
	v_add_f32_e32 v131, 1.0, v133
	v_mul_f32_e32 v133, 0xbfb8aa3b, v72
	v_exp_f32_e32 v134, v133
	v_mul_f32_e32 v133, 0xbfb8aa3b, v73
	v_exp_f32_e32 v135, v133
	v_rcp_f32_e32 v133, v131
	v_add_f32_e32 v131, 1.0, v134
	v_rcp_f32_e32 v134, v131
	v_add_f32_e32 v131, 1.0, v135
	v_rcp_f32_e32 v135, v131
	v_mov_b32_dpp v105, v58 row_ror:1 row_mask:0xf bank_mask:0xf
	v_mov_b32_dpp v109, v59 row_ror:1 row_mask:0xf bank_mask:0xf
	v_mov_b32_dpp v110, v60 row_ror:1 row_mask:0xf bank_mask:0xf
	v_mov_b32_dpp v112, v61 row_ror:1 row_mask:0xf bank_mask:0xf
	v_mov_b32_dpp v90, v50 row_ror:1 row_mask:0xf bank_mask:0xf
	v_mov_b32_dpp v108, v50 row_ror:15 row_mask:0xf bank_mask:0xf
	v_mov_b32_dpp v92, v51 row_ror:1 row_mask:0xf bank_mask:0xf
	v_mov_b32_dpp v113, v51 row_ror:15 row_mask:0xf bank_mask:0xf
	v_mov_b32_dpp v91, v52 row_ror:1 row_mask:0xf bank_mask:0xf
	v_mov_b32_dpp v111, v52 row_ror:15 row_mask:0xf bank_mask:0xf
	v_mov_b32_dpp v93, v53 row_ror:1 row_mask:0xf bank_mask:0xf
	v_mov_b32_dpp v114, v53 row_ror:15 row_mask:0xf bank_mask:0xf
	v_mov_b32_dpp v100, v34 row_ror:1 row_mask:0xf bank_mask:0xf
	v_mov_b32_dpp v115, v34 row_ror:15 row_mask:0xf bank_mask:0xf
	v_mov_b32_dpp v102, v35 row_ror:1 row_mask:0xf bank_mask:0xf
	v_mov_b32_dpp v116, v35 row_ror:15 row_mask:0xf bank_mask:0xf
	v_mov_b32_dpp v101, v36 row_ror:1 row_mask:0xf bank_mask:0xf
	v_mov_b32_dpp v104, v36 row_ror:15 row_mask:0xf bank_mask:0xf
	v_mov_b32_dpp v103, v37 row_ror:1 row_mask:0xf bank_mask:0xf
	v_mov_b32_dpp v131, v37 row_ror:15 row_mask:0xf bank_mask:0xf
	v_mul_f32_e32 v132, v70, v132
	v_mul_f32_e32 v133, v71, v133
	v_mul_f32_e32 v134, v72, v134
	v_mul_f32_e32 v135, v73, v135
	v_mul_f32_e32 v132, v62, v132
	v_mul_f32_e32 v133, v63, v133
	v_mul_f32_e32 v134, v64, v134
	v_mul_f32_e32 v135, v65, v135
	v_cvt_pk_bf16_f32 v132, v132, v133
	v_cvt_pk_bf16_f32 v133, v134, v135
	global_store_dwordx2 v[178:179], v[132:133], off offset:8
	s_and_saveexec_b64 s[20:21], s[44:45]
	s_cbranch_execz .LBB0_745
	global_store_dwordx4 v[176:177], v[70:73], off offset:16
	s_nop 1
	v_add_co_u32_e32 v70, vcc, 0x2000, v176
	s_nop 1
	v_addc_co_u32_e32 v71, vcc, 0, v177, vcc
	global_store_dwordx4 v[70:71], v[62:65], off offset:3088
	s_nop 1
	v_add_co_u32_e32 v62, vcc, 0x5000, v176
	s_nop 1
	v_addc_co_u32_e32 v63, vcc, 0, v177, vcc
	global_store_dwordx4 v[62:63], v[46:49], off offset:2064
.LBB0_745:
	s_or_b64 exec, exec, s[20:21]
	s_waitcnt lgkmcnt(0)
	v_cndmask_b32_e64 v46, v105, v117, s[40:41]
	v_cndmask_b32_e64 v47, v109, v118, s[40:41]
	v_cndmask_b32_e64 v48, v110, v119, s[40:41]
	v_cndmask_b32_e64 v49, v112, v120, s[40:41]
	v_fma_f32 v48, v84, v48, v88
	v_fma_f32 v49, v85, v49, v89
	v_fma_f32 v46, v82, v46, v86
	v_fma_f32 v47, v83, v47, v87
	s_waitcnt lgkmcnt(0)
	v_cndmask_b32_e64 v63, v129, v113, s[42:43]
	v_cndmask_b32_e64 v62, v121, v108, s[42:43]
	s_waitcnt lgkmcnt(0)
	v_cndmask_b32_e64 v65, v130, v114, s[42:43]
	v_cndmask_b32_e64 v64, v128, v111, s[42:43]
	v_fma_f32 v46, v58, v78, v46
	v_fma_f32 v47, v59, v79, v47
	v_fma_f32 v48, v60, v80, v48
	v_fma_f32 v49, v61, v81, v49
	v_fma_f32 v46, v74, v62, v46
	v_fma_f32 v47, v75, v63, v47
	v_fma_f32 v48, v76, v64, v48
	v_fma_f32 v49, v77, v65, v49
	v_mul_f32_e32 v58, s100, v46
	v_mul_f32_e32 v59, s100, v47
	v_mul_f32_e32 v60, s100, v48
	v_mul_f32_e32 v61, s100, v49
	v_exp_f32_e32 v58, v58
	v_exp_f32_e32 v59, v59
	v_exp_f32_e32 v60, v60
	v_exp_f32_e32 v61, v61
	v_add_f32_e32 v58, 1.0, v58
	v_add_f32_e32 v59, 1.0, v59
	v_add_f32_e32 v60, 1.0, v60
	v_add_f32_e32 v61, 1.0, v61
	v_rcp_f32_e32 v58, v58
	v_rcp_f32_e32 v59, v59
	v_rcp_f32_e32 v60, v60
	v_rcp_f32_e32 v61, v61
	s_and_b64 vcc, exec, s[52:53]
	v_mul_f32_e32 v46, v46, v58
	v_mul_f32_e32 v47, v47, v59
	s_waitcnt lgkmcnt(0)
	v_cndmask_b32_e64 v59, v113, v116, s[42:43]
	v_mul_f32_e32 v48, v48, v60
	v_mul_f32_e32 v49, v49, v61
	v_mul_f32_e32 v46, v54, v46
	v_mul_f32_e32 v47, v55, v47
	v_mul_f32_e32 v48, v56, v48
	v_mul_f32_e32 v49, v57, v49
	v_cvt_pk_bf16_f32 v46, v46, v47
	v_cvt_pk_bf16_f32 v47, v48, v49
	global_store_dwordx2 v[126:127], v[46:47], off offset:8
	v_cndmask_b32_e64 v46, v90, v105, s[40:41]
	v_cndmask_b32_e64 v47, v92, v109, s[40:41]
	v_cndmask_b32_e64 v48, v91, v110, s[40:41]
	v_cndmask_b32_e64 v49, v93, v112, s[40:41]
	v_fma_f32 v46, v82, v46, v86
	v_fma_f32 v47, v83, v47, v87
	v_cndmask_b32_e64 v58, v108, v115, s[42:43]
	v_fma_f32 v48, v84, v48, v88
	v_fma_f32 v49, v85, v49, v89
	v_fma_f32 v46, v50, v78, v46
	v_fma_f32 v47, v51, v79, v47
	s_waitcnt lgkmcnt(0)
	v_cndmask_b32_e64 v61, v114, v131, s[42:43]
	v_cndmask_b32_e64 v60, v111, v104, s[42:43]
	v_fma_f32 v48, v52, v80, v48
	v_fma_f32 v49, v53, v81, v49
	v_fma_f32 v46, v74, v58, v46
	v_fma_f32 v47, v75, v59, v47
	v_fma_f32 v48, v76, v60, v48
	v_fma_f32 v49, v77, v61, v49
	v_mul_f32_e32 v50, s100, v46
	v_mul_f32_e32 v51, s100, v47
	v_exp_f32_e32 v50, v50
	v_exp_f32_e32 v51, v51
	v_mul_f32_e32 v52, s100, v48
	v_mul_f32_e32 v53, s100, v49
	v_exp_f32_e32 v52, v52
	v_exp_f32_e32 v53, v53
	v_add_f32_e32 v50, 1.0, v50
	v_add_f32_e32 v51, 1.0, v51
	v_rcp_f32_e32 v50, v50
	v_rcp_f32_e32 v51, v51
	v_add_f32_e32 v52, 1.0, v52
	v_add_f32_e32 v53, 1.0, v53
	v_rcp_f32_e32 v52, v52
	v_rcp_f32_e32 v53, v53
	v_mul_f32_e32 v46, v46, v50
	v_mul_f32_e32 v47, v47, v51
	v_cndmask_b32_e64 v55, v116, v67, s[42:43]
	v_mul_f32_e32 v42, v42, v46
	v_mul_f32_e32 v43, v43, v47
	v_mul_f32_e32 v46, v48, v52
	v_mul_f32_e32 v47, v49, v53
	v_cvt_pk_bf16_f32 v42, v42, v43
	v_mul_f32_e32 v44, v44, v46
	v_mul_f32_e32 v45, v45, v47
	v_cndmask_b32_e64 v47, v103, v93, s[40:41]
	v_cvt_pk_bf16_f32 v43, v44, v45
	v_cndmask_b32_e64 v45, v102, v92, s[40:41]
	v_cndmask_b32_e64 v44, v100, v90, s[40:41]
	v_cndmask_b32_e64 v46, v101, v91, s[40:41]
	v_fma_f32 v46, v84, v46, v88
	v_fma_f32 v47, v85, v47, v89
	v_fma_f32 v44, v82, v44, v86
	v_fma_f32 v45, v83, v45, v87
	v_cndmask_b32_e64 v54, v115, v66, s[42:43]
	v_cndmask_b32_e64 v57, v131, v69, s[42:43]
	v_cndmask_b32_e64 v56, v104, v68, s[42:43]
	v_fma_f32 v34, v34, v78, v44
	v_fma_f32 v35, v35, v79, v45
	v_fma_f32 v36, v36, v80, v46
	v_fma_f32 v37, v37, v81, v47
	v_fma_f32 v34, v74, v54, v34
	v_fma_f32 v35, v75, v55, v35
	v_fma_f32 v36, v76, v56, v36
	v_fma_f32 v37, v77, v57, v37
	v_mul_f32_e32 v44, s100, v34
	v_mul_f32_e32 v45, s100, v35
	v_mul_f32_e32 v46, s100, v36
	v_mul_f32_e32 v47, s100, v37
	v_exp_f32_e32 v44, v44
	v_exp_f32_e32 v45, v45
	v_exp_f32_e32 v46, v46
	v_exp_f32_e32 v47, v47
	v_add_f32_e32 v44, 1.0, v44
	v_add_f32_e32 v45, 1.0, v45
	v_add_f32_e32 v46, 1.0, v46
	v_add_f32_e32 v47, 1.0, v47
	v_rcp_f32_e32 v44, v44
	v_rcp_f32_e32 v45, v45
	v_rcp_f32_e32 v46, v46
	v_rcp_f32_e32 v47, v47
	global_store_dwordx2 v[122:123], v[42:43], off offset:8
	v_mul_f32_e32 v34, v34, v44
	v_mul_f32_e32 v35, v35, v45
	v_mul_f32_e32 v36, v36, v46
	v_mul_f32_e32 v37, v37, v47
	v_mul_f32_e32 v34, v38, v34
	v_mul_f32_e32 v35, v39, v35
	v_mul_f32_e32 v36, v40, v36
	v_mul_f32_e32 v37, v41, v37
	v_cvt_pk_bf16_f32 v34, v34, v35
	v_cvt_pk_bf16_f32 v35, v36, v37
	global_store_dwordx2 v[124:125], v[34:35], off offset:8
	v_mov_b32_e32 v34, 0
	v_mov_b32_e32 v38, 0
	v_mov_b32_e32 v39, 0
	v_mov_b32_e32 v40, 0
	v_mov_b32_e32 v41, 0
	s_cbranch_vccnz .LBB0_747
	ds_read_b128 v[38:41], v187 offset:1552

.LBB0_749:
	v_mov_b32_dpp v46, v30 row_ror:1 row_mask:0xf bank_mask:0xf
	v_mov_b32_dpp v47, v31 row_ror:1 row_mask:0xf bank_mask:0xf
	v_mov_b32_dpp v48, v32 row_ror:1 row_mask:0xf bank_mask:0xf
	v_mov_b32_dpp v49, v33 row_ror:1 row_mask:0xf bank_mask:0xf
	v_mov_b32_dpp v42, v30 row_ror:15 row_mask:0xf bank_mask:0xf
	v_mov_b32_dpp v43, v31 row_ror:15 row_mask:0xf bank_mask:0xf
	v_mov_b32_dpp v51, v22 row_ror:15 row_mask:0xf bank_mask:0xf
	v_mov_b32_dpp v53, v23 row_ror:15 row_mask:0xf bank_mask:0xf
	v_mov_b32_dpp v44, v32 row_ror:15 row_mask:0xf bank_mask:0xf
	v_mov_b32_dpp v45, v33 row_ror:15 row_mask:0xf bank_mask:0xf
	v_mov_b32_dpp v55, v24 row_ror:15 row_mask:0xf bank_mask:0xf
	v_mov_b32_dpp v57, v25 row_ror:15 row_mask:0xf bank_mask:0xf
	s_waitcnt lgkmcnt(0)
	v_cndmask_b32_e64 v39, v47, v39, s[40:41]
	v_cndmask_b32_e64 v38, v46, v38, s[40:41]
	s_waitcnt lgkmcnt(0)
	v_cndmask_b32_e64 v41, v49, v41, s[40:41]
	v_cndmask_b32_e64 v40, v48, v40, s[40:41]
	v_fma_f32 v38, v82, v38, v86
	v_fma_f32 v39, v83, v39, v87
	s_waitcnt lgkmcnt(0)
	v_cndmask_b32_e64 v43, v43, v53, s[42:43]
	v_cndmask_b32_e64 v42, v42, v51, s[42:43]
	v_fma_f32 v40, v84, v40, v88
	v_fma_f32 v41, v85, v41, v89
	v_fma_f32 v30, v30, v78, v38
	v_fma_f32 v31, v31, v79, v39
	s_waitcnt lgkmcnt(0)
	v_cndmask_b32_e64 v45, v45, v57, s[42:43]
	v_cndmask_b32_e64 v44, v44, v55, s[42:43]
	v_fma_f32 v32, v32, v80, v40
	v_fma_f32 v33, v33, v81, v41
	v_fma_f32 v30, v74, v42, v30
	v_fma_f32 v31, v75, v43, v31
	v_fma_f32 v32, v76, v44, v32
	v_fma_f32 v33, v77, v45, v33
	v_mul_f32_e32 v38, s100, v30
	v_mul_f32_e32 v39, s100, v31
	v_exp_f32_e32 v38, v38
	v_exp_f32_e32 v39, v39
	v_mul_f32_e32 v40, s100, v32
	v_mul_f32_e32 v41, s100, v33
	v_exp_f32_e32 v40, v40
	v_exp_f32_e32 v41, v41
	v_add_f32_e32 v38, 1.0, v38
	v_add_f32_e32 v39, 1.0, v39
	v_rcp_f32_e32 v38, v38
	v_rcp_f32_e32 v39, v39
	v_add_f32_e32 v40, 1.0, v40
	v_add_f32_e32 v41, 1.0, v41
	v_rcp_f32_e32 v40, v40
	v_rcp_f32_e32 v41, v41
	v_mov_b32_dpp v50, v22 row_ror:1 row_mask:0xf bank_mask:0xf
	v_mov_b32_dpp v52, v23 row_ror:1 row_mask:0xf bank_mask:0xf
	v_mov_b32_dpp v54, v24 row_ror:1 row_mask:0xf bank_mask:0xf
	v_mov_b32_dpp v56, v25 row_ror:1 row_mask:0xf bank_mask:0xf
	v_mov_b32_dpp v59, v14 row_ror:15 row_mask:0xf bank_mask:0xf
	v_mov_b32_dpp v61, v15 row_ror:15 row_mask:0xf bank_mask:0xf
	v_mul_f32_e32 v30, v30, v38
	v_mul_f32_e32 v31, v31, v39
	v_mov_b32_dpp v63, v16 row_ror:15 row_mask:0xf bank_mask:0xf
	v_mov_b32_dpp v65, v17 row_ror:15 row_mask:0xf bank_mask:0xf
	v_mul_f32_e32 v26, v26, v30
	v_mul_f32_e32 v27, v27, v31
	v_mul_f32_e32 v30, v32, v40
	v_mul_f32_e32 v31, v33, v41
	v_cvt_pk_bf16_f32 v26, v26, v27
	v_mul_f32_e32 v28, v28, v30
	v_mul_f32_e32 v29, v29, v31
	s_waitcnt lgkmcnt(0)
	v_cndmask_b32_e64 v31, v56, v49, s[40:41]
	v_cvt_pk_bf16_f32 v27, v28, v29
	v_cndmask_b32_e64 v29, v52, v47, s[40:41]
	v_cndmask_b32_e64 v28, v50, v46, s[40:41]
	v_cndmask_b32_e64 v30, v54, v48, s[40:41]
	v_fma_f32 v28, v82, v28, v86
	v_fma_f32 v29, v83, v29, v87
	s_waitcnt lgkmcnt(0)
	v_cndmask_b32_e64 v32, v51, v59, s[42:43]
	s_waitcnt lgkmcnt(0)
	v_cndmask_b32_e64 v33, v53, v61, s[42:43]
	v_fma_f32 v30, v84, v30, v88
	v_fma_f32 v31, v85, v31, v89
	v_fma_f32 v22, v22, v78, v28
	v_fma_f32 v23, v23, v79, v29
	s_waitcnt lgkmcnt(0)
	v_cndmask_b32_e64 v38, v55, v63, s[42:43]
	s_waitcnt lgkmcnt(0)
	v_cndmask_b32_e64 v39, v57, v65, s[42:43]
	v_fma_f32 v24, v24, v80, v30
	v_fma_f32 v25, v25, v81, v31
	v_fma_f32 v22, v74, v32, v22
	v_fma_f32 v23, v75, v33, v23
	v_fma_f32 v24, v76, v38, v24
	v_fma_f32 v25, v77, v39, v25
	v_mul_f32_e32 v28, s100, v22
	v_mul_f32_e32 v29, s100, v23
	v_exp_f32_e32 v28, v28
	v_exp_f32_e32 v29, v29
	v_mul_f32_e32 v30, s100, v24
	v_mul_f32_e32 v31, s100, v25
	v_exp_f32_e32 v30, v30
	v_exp_f32_e32 v31, v31
	v_add_f32_e32 v28, 1.0, v28
	v_add_f32_e32 v29, 1.0, v29
	v_rcp_f32_e32 v28, v28
	v_rcp_f32_e32 v29, v29
	v_add_f32_e32 v30, 1.0, v30
	v_add_f32_e32 v31, 1.0, v31
	v_rcp_f32_e32 v30, v30
	v_rcp_f32_e32 v31, v31
	v_mov_b32_dpp v58, v14 row_ror:1 row_mask:0xf bank_mask:0xf
	v_mov_b32_dpp v60, v15 row_ror:1 row_mask:0xf bank_mask:0xf
	v_mov_b32_dpp v62, v16 row_ror:1 row_mask:0xf bank_mask:0xf
	v_mov_b32_dpp v64, v17 row_ror:1 row_mask:0xf bank_mask:0xf
	v_mov_b32_dpp v67, v2 row_ror:15 row_mask:0xf bank_mask:0xf
	v_mov_b32_dpp v69, v3 row_ror:15 row_mask:0xf bank_mask:0xf
	v_mul_f32_e32 v22, v22, v28
	v_mul_f32_e32 v23, v23, v29
	v_mov_b32_dpp v71, v4 row_ror:15 row_mask:0xf bank_mask:0xf
	v_mov_b32_dpp v42, v5 row_ror:15 row_mask:0xf bank_mask:0xf
	v_mul_f32_e32 v18, v18, v22
	v_mul_f32_e32 v19, v19, v23
	v_mul_f32_e32 v22, v24, v30
	v_mul_f32_e32 v23, v25, v31
	v_cvt_pk_bf16_f32 v18, v18, v19
	v_mul_f32_e32 v20, v20, v22
	v_mul_f32_e32 v21, v21, v23
	s_waitcnt lgkmcnt(0)
	v_cndmask_b32_e64 v23, v64, v56, s[40:41]
	v_cvt_pk_bf16_f32 v19, v20, v21
	v_cndmask_b32_e64 v21, v60, v52, s[40:41]
	v_cndmask_b32_e64 v20, v58, v50, s[40:41]
	v_cndmask_b32_e64 v22, v62, v54, s[40:41]
	v_fma_f32 v20, v82, v20, v86
	v_fma_f32 v21, v83, v21, v87
	s_waitcnt lgkmcnt(0)
	v_cndmask_b32_e64 v24, v59, v67, s[42:43]
	s_waitcnt lgkmcnt(0)
	v_cndmask_b32_e64 v25, v61, v69, s[42:43]
	v_fma_f32 v22, v84, v22, v88
	v_fma_f32 v23, v85, v23, v89
	v_fma_f32 v14, v14, v78, v20
	v_fma_f32 v15, v15, v79, v21
	global_store_dwordx2 v[106:107], v[26:27], off offset:8
	s_waitcnt lgkmcnt(0)
	v_cndmask_b32_e64 v26, v63, v71, s[42:43]
	s_waitcnt lgkmcnt(0)
	v_cndmask_b32_e64 v27, v65, v42, s[42:43]
	v_fma_f32 v16, v16, v80, v22
	v_fma_f32 v17, v17, v81, v23
	v_fma_f32 v14, v74, v24, v14
	v_fma_f32 v15, v75, v25, v15
	v_fma_f32 v16, v76, v26, v16
	v_fma_f32 v17, v77, v27, v17
	v_mul_f32_e32 v20, s100, v14
	v_mul_f32_e32 v21, s100, v15
	v_exp_f32_e32 v20, v20
	v_exp_f32_e32 v21, v21
	v_mul_f32_e32 v22, s100, v16
	v_mul_f32_e32 v23, s100, v17
	v_exp_f32_e32 v22, v22
	v_exp_f32_e32 v23, v23
	v_add_f32_e32 v20, 1.0, v20
	v_add_f32_e32 v21, 1.0, v21
	v_rcp_f32_e32 v20, v20
	v_rcp_f32_e32 v21, v21
	v_add_f32_e32 v22, 1.0, v22
	v_add_f32_e32 v23, 1.0, v23
	v_rcp_f32_e32 v22, v22
	v_rcp_f32_e32 v23, v23
	v_mov_b32_dpp v66, v2 row_ror:1 row_mask:0xf bank_mask:0xf
	v_mov_b32_dpp v68, v3 row_ror:1 row_mask:0xf bank_mask:0xf
	v_mov_b32_dpp v70, v4 row_ror:1 row_mask:0xf bank_mask:0xf
	v_mov_b32_dpp v72, v5 row_ror:1 row_mask:0xf bank_mask:0xf
	v_mul_f32_e32 v14, v14, v20
	v_mul_f32_e32 v15, v15, v21
	global_store_dwordx2 v[98:99], v[18:19], off offset:8
	v_mul_f32_e32 v10, v10, v14
	v_mul_f32_e32 v11, v11, v15
	v_mul_f32_e32 v14, v16, v22
	v_mul_f32_e32 v15, v17, v23
	v_cndmask_b32_e64 v17, v69, v35, s[42:43]
	v_mul_f32_e32 v12, v12, v14
	v_mul_f32_e32 v13, v13, v15
	v_cvt_pk_bf16_f32 v14, v10, v11
	v_cvt_pk_bf16_f32 v15, v12, v13
	s_waitcnt lgkmcnt(0)
	v_cndmask_b32_e64 v11, v68, v60, s[40:41]
	v_cndmask_b32_e64 v10, v66, v58, s[40:41]
	s_waitcnt lgkmcnt(0)
	v_cndmask_b32_e64 v13, v72, v64, s[40:41]
	v_cndmask_b32_e64 v12, v70, v62, s[40:41]
	v_fma_f32 v12, v84, v12, v88
	v_fma_f32 v13, v85, v13, v89
	v_fma_f32 v10, v82, v10, v86
	v_fma_f32 v11, v83, v11, v87
	v_cndmask_b32_e64 v16, v67, v34, s[42:43]
	v_cndmask_b32_e64 v19, v42, v37, s[42:43]
	v_cndmask_b32_e64 v18, v71, v36, s[42:43]
	v_fma_f32 v10, v2, v78, v10
	v_fma_f32 v11, v3, v79, v11
	v_fma_f32 v12, v4, v80, v12
	v_fma_f32 v13, v5, v81, v13
	v_fma_f32 v10, v74, v16, v10
	v_fma_f32 v11, v75, v17, v11
	v_fma_f32 v12, v76, v18, v12
	v_fma_f32 v13, v77, v19, v13
	v_mul_f32_e32 v16, s100, v10
	v_mul_f32_e32 v17, s100, v11
	v_mul_f32_e32 v18, s100, v12
	v_mul_f32_e32 v19, s100, v13
	v_exp_f32_e32 v16, v16
	v_exp_f32_e32 v17, v17
	v_exp_f32_e32 v18, v18
	v_exp_f32_e32 v19, v19
	v_add_f32_e32 v16, 1.0, v16
	v_add_f32_e32 v17, 1.0, v17
	v_add_f32_e32 v18, 1.0, v18
	v_add_f32_e32 v19, 1.0, v19
	v_rcp_f32_e32 v16, v16
	v_rcp_f32_e32 v17, v17
	v_rcp_f32_e32 v18, v18
	v_rcp_f32_e32 v19, v19
	global_store_dwordx2 v[94:95], v[14:15], off offset:8
	v_mul_f32_e32 v14, v10, v16
	v_mul_f32_e32 v15, v11, v17
	v_mul_f32_e32 v16, v12, v18
	v_mul_f32_e32 v17, v13, v19
	v_mul_f32_e32 v14, v6, v14
	v_mul_f32_e32 v15, v7, v15
	v_mul_f32_e32 v16, v8, v16
	v_mul_f32_e32 v17, v9, v17
	v_cvt_pk_bf16_f32 v14, v14, v15
	v_cvt_pk_bf16_f32 v15, v16, v17
	global_store_dwordx2 v[96:97], v[14:15], off offset:8
	s_and_saveexec_b64 s[20:21], s[74:75]
	s_cbranch_execz .LBB0_701
	v_add_co_u32_e32 v14, vcc, 0x8000, v176
	s_nop 1
	v_addc_co_u32_e32 v15, vcc, 0, v177, vcc
	global_store_dwordx4 v[14:15], v[10:13], off offset:1040
	s_nop 1
	v_add_co_u32_e32 v10, vcc, 0xb000, v176
	s_nop 1
	v_addc_co_u32_e32 v11, vcc, 0, v177, vcc
	global_store_dwordx4 v[10:11], v[6:9], off offset:16
	s_nop 1
	v_add_co_u32_e32 v6, vcc, 0xd000, v176
	s_nop 1
	v_addc_co_u32_e32 v7, vcc, 0, v177, vcc
	global_store_dwordx4 v[6:7], v[2:5], off offset:3088
	s_branch .LBB0_701

.LBB0_760:
	s_or_b64 exec, exec, s[16:17]
	s_and_b64 s[0:1], exec, vcc
	s_or_b64 s[14:15], s[0:1], s[14:15]
	s_waitcnt lgkmcnt(0)
	v_add_f32_e32 v102, v102, v104
	v_add_f32_e32 v103, v103, v105
	s_mov_b32 s0, 0x3a800000
	v_mul_f32_e32 v102, s0, v102
	v_mul_f32_e32 v103, s0, v103
	s_mov_b32 s0, 0xbe00000
	v_fma_f32 v0, -v103, v103, v102
	v_max_f32_e32 v0, 0, v0
	v_add_f32_e32 v0, 0x358637bd, v0
	v_cmp_gt_f32_e32 vcc, s58, v0
	v_mul_f32_e32 v92, 0x4b800000, v0
	v_sub_f32_e32 v75, v75, v103
	v_cndmask_b32_e32 v0, v0, v92, vcc
	v_rsq_f32_e32 v0, v0
	v_sub_f32_e32 v74, v74, v103
	v_sub_f32_e32 v81, v81, v103
	v_sub_f32_e32 v80, v80, v103
	v_mul_f32_e32 v92, 0x45800000, v0
	v_cndmask_b32_e32 v0, v0, v92, vcc
	v_mul_f32_e32 v74, v74, v0
	v_mul_f32_e32 v75, v75, v0
	v_sub_f32_e32 v77, v77, v103
	s_waitcnt vmcnt(3)
	v_fma_f32 v104, v74, v58, v42
	v_fma_f32 v105, v75, v59, v43
	v_sub_f32_e32 v75, v97, v103
	v_sub_f32_e32 v74, v96, v103
	v_sub_f32_e32 v76, v76, v103
	v_mul_f32_e32 v74, v74, v0
	v_mul_f32_e32 v75, v75, v0
	v_sub_f32_e32 v101, v101, v103
	v_sub_f32_e32 v100, v100, v103
	v_mul_f32_e32 v80, v80, v0
	v_mul_f32_e32 v81, v81, v0
	v_sub_f32_e32 v95, v95, v103
	v_sub_f32_e32 v94, v94, v103
	v_mul_f32_e32 v76, v76, v0
	v_mul_f32_e32 v77, v77, v0
	s_waitcnt vmcnt(0)
	v_fma_f32 v96, v74, v68, v64
	v_fma_f32 v97, v75, v69, v65
	v_sub_f32_e32 v75, v99, v103
	v_sub_f32_e32 v74, v98, v103
	v_mul_f32_e32 v100, v100, v0
	v_mul_f32_e32 v101, v101, v0
	v_fma_f32 v80, v80, v54, v46
	v_fma_f32 v81, v81, v55, v47
	v_mul_f32_e32 v94, v94, v0
	v_mul_f32_e32 v95, v95, v0
	v_fma_f32 v106, v76, v66, v62
	v_fma_f32 v107, v77, v67, v63
	v_sub_f32_e32 v77, v79, v103
	v_sub_f32_e32 v76, v78, v103
	v_mul_f32_e32 v74, v74, v0
	v_mul_f32_e32 v75, v75, v0
	v_fma_f32 v100, v100, v56, v48
	v_fma_f32 v101, v101, v57, v49
	v_fma_f32 v94, v94, v60, v44
	v_fma_f32 v95, v95, v61, v45
	v_mul_f32_e32 v76, v76, v0
	v_mul_f32_e32 v77, v77, v0
	v_fma_f32 v78, v74, v72, v52
	v_fma_f32 v79, v75, v73, v53
	v_cvt_pk_bf16_f32 v74, v80, v81
	v_add_co_u32_e32 v80, vcc, s0, v90
	v_fma_f32 v98, v76, v70, v50
	v_fma_f32 v99, v77, v71, v51
	v_cvt_pk_bf16_f32 v75, v100, v101
	v_cvt_pk_bf16_f32 v76, v104, v105
	v_cvt_pk_bf16_f32 v77, v94, v95
	v_addc_co_u32_e32 v81, vcc, 0, v91, vcc
	global_store_dwordx4 v[80:81], v[74:77], off
	s_mov_b64 s[0:1], 0x800
	v_lshl_add_u64 v[86:87], v[86:87], 0, 8
	v_cvt_pk_bf16_f32 v74, v106, v107
	v_cvt_pk_bf16_f32 v75, v96, v97
	v_cvt_pk_bf16_f32 v76, v98, v99
	v_cvt_pk_bf16_f32 v77, v78, v79
	global_store_dwordx4 v[80:81], v[74:77], off offset:1024
	v_mov_b64_e32 v[80:81], v[36:37]
	v_lshl_add_u64 v[88:89], v[88:89], 0, s[0:1]
	v_mov_b64_e32 v[76:77], v[40:41]
	v_mov_b64_e32 v[74:75], v[38:39]
	v_mov_b64_e32 v[78:79], v[34:35]
	v_mov_b32_e32 v92, v93
	s_andn2_b64 exec, exec, s[14:15]
	s_cbranch_execz .LBB0_767

.LBB0_763:
	s_or_b64 exec, exec, s[16:17]
	v_lshlrev_b32_e32 v100, 16, v78
	v_and_b32_e32 v101, 0xffff0000, v78
	v_lshlrev_b32_e32 v118, 16, v79
	v_and_b32_e32 v94, 0xffff0000, v79
	v_lshlrev_b32_e32 v79, 16, v76
	v_and_b32_e32 v98, 0xffff0000, v76
	v_add_f32_e32 v0, 0, v100
	v_mul_f32_e32 v76, v101, v101
	v_lshlrev_b32_e32 v95, 16, v80
	v_add_f32_e32 v0, v0, v101
	v_fmac_f32_e32 v76, v100, v100
	v_lshlrev_b32_e32 v96, 16, v74
	v_lshlrev_b32_e32 v105, 16, v75
	v_and_b32_e32 v104, 0xffff0000, v74
	v_and_b32_e32 v78, 0xffff0000, v75
	v_add_f32_e32 v0, v0, v118
	v_fmac_f32_e32 v76, v118, v118
	v_mul_f32_e32 v74, v94, v94
	v_mul_f32_e32 v75, v95, v95
	v_lshlrev_b32_e32 v107, 16, v81
	v_and_b32_e32 v106, 0xffff0000, v80
	v_add_f32_e32 v0, v0, v94
	v_add_f32_e32 v74, v74, v76
	v_add_f32_e32 v0, v0, v95
	v_add_f32_e32 v76, v75, v74
	v_mul_f32_e32 v74, v106, v106
	v_mul_f32_e32 v75, v107, v107
	v_and_b32_e32 v97, 0xffff0000, v81
	v_add_f32_e32 v0, v0, v106
	v_add_f32_e32 v74, v74, v76
	v_add_f32_e32 v0, v0, v107
	v_add_f32_e32 v76, v75, v74
	v_mul_f32_e32 v74, v96, v96
	v_mul_f32_e32 v75, v97, v97
	v_add_f32_e32 v0, v0, v97
	v_add_f32_e32 v75, v75, v76
	v_add_f32_e32 v0, v0, v96
	v_add_f32_e32 v76, v74, v75
	v_mul_f32_e32 v74, v104, v104
	v_mul_f32_e32 v75, v105, v105
	v_add_f32_e32 v0, v0, v104
	v_add_f32_e32 v74, v74, v76
	v_add_f32_e32 v0, v0, v105
	v_add_f32_e32 v76, v75, v74
	v_mul_f32_e32 v74, v78, v78
	v_mul_f32_e32 v75, v79, v79
	v_lshlrev_b32_e32 v99, 16, v77
	v_add_f32_e32 v0, v0, v78
	v_add_f32_e32 v74, v74, v76
	v_add_f32_e32 v0, v0, v79
	v_add_f32_e32 v76, v75, v74
	v_mul_f32_e32 v74, v98, v98
	v_mul_f32_e32 v75, v99, v99
	v_and_b32_e32 v103, 0xffff0000, v77
	v_add_f32_e32 v0, v0, v98
	v_add_f32_e32 v74, v74, v76
	v_add_f32_e32 v77, v0, v99
	v_add_f32_e32 v102, v75, v74
	v_mul_f32_e32 v76, v103, v103
	v_add_f32_e32 v74, v76, v102
	v_add_f32_e32 v75, v77, v103
	s_nop 1
	v_add_f32_dpp v74, v74, v74 quad_perm:[1,0,3,2] row_mask:0xf bank_mask:0xf
	v_add_f32_dpp v75, v75, v75 quad_perm:[1,0,3,2] row_mask:0xf bank_mask:0xf
	s_nop 0
	v_add_f32_dpp v74, v74, v74 quad_perm:[2,3,0,1] row_mask:0xf bank_mask:0xf
	v_add_f32_dpp v75, v75, v75 quad_perm:[2,3,0,1] row_mask:0xf bank_mask:0xf
	s_nop 0
	v_add_f32_dpp v74, v74, v74 row_half_mirror row_mask:0xf bank_mask:0xf
	v_add_f32_dpp v75, v75, v75 row_half_mirror row_mask:0xf bank_mask:0xf
	s_nop 0
	v_add_f32_dpp v74, v74, v74 row_mirror row_mask:0xf bank_mask:0xf
	v_add_f32_dpp v75, v75, v75 row_mirror row_mask:0xf bank_mask:0xf
	s_nop 0
	v_add_f32_dpp v74, v74, v74 row_bcast:15 row_mask:0xa bank_mask:0xf
	v_add_f32_dpp v75, v75, v75 row_bcast:15 row_mask:0xa bank_mask:0xf
	s_nop 0
	v_add_f32_dpp v74, v74, v74 row_bcast:31 row_mask:0xc bank_mask:0xf
	v_add_f32_dpp v75, v75, v75 row_bcast:31 row_mask:0xc bank_mask:0xf
	s_nop 0
	v_readlane_b32 s98, v74, 63
	v_readlane_b32 s99, v75, 63
	s_nop 1
	v_mov_b32_e32 v74, s98
	v_mov_b32_e32 v75, s99
	v_mov_b32_e32 v76, 0
	v_mov_b32_e32 v77, 0
	s_mov_b32 s0, 0x3a800000
	s_waitcnt lgkmcnt(0)
	v_add_f32_e32 v74, v74, v76
	v_add_f32_e32 v75, v75, v77
	s_nop 0
	v_mul_f32_e32 v108, s0, v74
	v_mul_f32_e32 v109, s0, v75
	s_nop 0
	v_fma_f32 v0, -v109, v109, v108
	v_max_f32_e32 v0, 0, v0
	v_add_f32_e32 v0, 0x358637bd, v0
	v_mul_f32_e32 v74, 0x4b800000, v0
	v_cmp_gt_f32_e64 s[42:43], s58, v0
	s_nop 1
	v_cndmask_b32_e64 v0, v0, v74, s[42:43]
	v_rsq_f32_e32 v0, v0
	s_nop 0
	v_mul_f32_e32 v74, 0x45800000, v0
	v_cndmask_b32_e64 v0, v0, v74, s[42:43]
	s_and_saveexec_b64 s[16:17], s[40:41]
	s_cbranch_execz .LBB0_765
	v_mov_b32_e32 v74, v109
	v_mov_b32_e32 v75, v0
	v_lshl_add_u64 v[76:77], s[12:13], 0, v[86:87]
	global_store_dwordx2 v[76:77], v[74:75], off
.LBB0_765:
	s_or_b64 exec, exec, s[16:17]
	v_sub_f32_e32 v75, v94, v109
	v_sub_f32_e32 v74, v118, v109
	v_sub_f32_e32 v77, v101, v109
	v_sub_f32_e32 v76, v100, v109
	v_mul_f32_e32 v76, v76, v0
	v_mul_f32_e32 v77, v77, v0
	v_mul_f32_e32 v74, v74, v0
	v_mul_f32_e32 v75, v75, v0
	v_fma_f32 v80, v6, v76, v14
	v_fma_f32 v81, v7, v77, v15
	v_fma_f32 v100, v8, v74, v16
	v_fma_f32 v101, v9, v75, v17
	v_sub_f32_e32 v75, v97, v109
	v_sub_f32_e32 v74, v107, v109
	v_sub_f32_e32 v77, v106, v109
	v_sub_f32_e32 v76, v95, v109
	v_mul_f32_e32 v76, v76, v0
	v_mul_f32_e32 v77, v77, v0
	v_mul_f32_e32 v74, v74, v0
	v_mul_f32_e32 v75, v75, v0
	v_sub_f32_e32 v97, v104, v109
	v_fma_f32 v94, v4, v74, v12
	v_fma_f32 v95, v5, v75, v13
	v_fma_f32 v74, v2, v76, v10
	v_fma_f32 v75, v3, v77, v11
	v_sub_f32_e32 v77, v78, v109
	v_sub_f32_e32 v76, v105, v109
	v_sub_f32_e32 v96, v96, v109
	v_mul_f32_e32 v104, v96, v0
	v_mul_f32_e32 v105, v97, v0
	v_mul_f32_e32 v76, v76, v0
	v_mul_f32_e32 v77, v77, v0
	v_sub_f32_e32 v103, v103, v109
	v_fma_f32 v96, v24, v76, v32
	v_fma_f32 v97, v25, v77, v33
	v_fma_f32 v76, v22, v104, v30
	v_fma_f32 v77, v23, v105, v31
	v_sub_f32_e32 v102, v99, v109
	v_sub_f32_e32 v99, v98, v109
	v_sub_f32_e32 v98, v79, v109
	v_mul_f32_e32 v104, v81, v81
	v_mul_f32_e32 v78, v98, v0
	v_mul_f32_e32 v79, v99, v0
	v_mul_f32_e32 v98, v102, v0
	v_mul_f32_e32 v99, v103, v0
	v_add_f32_e32 v0, 0, v80
	v_fmac_f32_e32 v104, v80, v80
	v_mov_b32_e32 v102, v74
	v_mov_b32_e32 v103, v101
	v_add_f32_e32 v0, v81, v0
	v_fmac_f32_e32 v104, v100, v100
	v_mul_f32_e32 v102, v102, v102
	v_mul_f32_e32 v103, v103, v103
	v_add_f32_e32 v0, v100, v0
	v_add_f32_e32 v103, v103, v104
	v_add_f32_e32 v0, v101, v0
	v_add_f32_e32 v106, v102, v103
	v_mul_f32_e32 v102, v94, v94
	v_mul_f32_e32 v103, v95, v95
	v_mul_f32_e32 v104, v74, v74
	v_mul_f32_e32 v105, v75, v75
	v_add_f32_e32 v0, v74, v0
	v_add_f32_e32 v103, v105, v106
	v_add_f32_e32 v0, v75, v0
	v_add_f32_e32 v104, v102, v103
	v_mov_b32_e32 v102, v76
	v_mov_b32_e32 v103, v95
	v_add_f32_e32 v0, v94, v0
	v_mul_f32_e32 v102, v102, v102
	v_mul_f32_e32 v103, v103, v103
	v_add_f32_e32 v0, v95, v0
	v_add_f32_e32 v103, v103, v104
	v_add_f32_e32 v0, v76, v0
	v_add_f32_e32 v106, v102, v103
	v_mul_f32_e32 v102, v96, v96
	v_mul_f32_e32 v103, v97, v97
	v_mul_f32_e32 v104, v76, v76
	v_mul_f32_e32 v105, v77, v77
	v_fma_f32 v78, v18, v78, v26
	v_fma_f32 v79, v19, v79, v27
	v_add_f32_e32 v0, v77, v0
	v_add_f32_e32 v103, v105, v106
	v_add_f32_e32 v0, v96, v0
	v_add_f32_e32 v104, v102, v103
	v_mov_b32_e32 v102, v78
	v_mov_b32_e32 v103, v97
	v_add_f32_e32 v0, v97, v0
	v_mul_f32_e32 v102, v102, v102
	v_mul_f32_e32 v103, v103, v103
	v_add_f32_e32 v0, v78, v0
	v_add_f32_e32 v103, v103, v104
	v_fma_f32 v98, v20, v98, v28
	v_fma_f32 v99, v21, v99, v29
	v_add_f32_e32 v102, v102, v103
	v_add_f32_e32 v0, v79, v0
	v_mul_f32_e32 v106, v78, v78
	v_mul_f32_e32 v107, v79, v79
	v_add_f32_e32 v103, v98, v0
	v_mul_f32_e32 v104, v98, v98
	v_mul_f32_e32 v105, v99, v99
	v_add_f32_e32 v0, v107, v102
	v_add_f32_e32 v104, v104, v0
	v_mul_f32_e32 v102, v99, v99
	v_mov_b32_e32 v105, v99
	v_add_f32_e32 v102, v104, v102
	v_add_f32_e32 v103, v105, v103
	s_nop 1
	v_add_f32_dpp v102, v102, v102 quad_perm:[1,0,3,2] row_mask:0xf bank_mask:0xf
	v_add_f32_dpp v103, v103, v103 quad_perm:[1,0,3,2] row_mask:0xf bank_mask:0xf
	s_nop 0
	v_add_f32_dpp v102, v102, v102 quad_perm:[2,3,0,1] row_mask:0xf bank_mask:0xf
	v_add_f32_dpp v103, v103, v103 quad_perm:[2,3,0,1] row_mask:0xf bank_mask:0xf
	s_nop 0
	v_add_f32_dpp v102, v102, v102 row_half_mirror row_mask:0xf bank_mask:0xf
	v_add_f32_dpp v103, v103, v103 row_half_mirror row_mask:0xf bank_mask:0xf
	s_nop 0
	v_add_f32_dpp v102, v102, v102 row_mirror row_mask:0xf bank_mask:0xf
	v_add_f32_dpp v103, v103, v103 row_mirror row_mask:0xf bank_mask:0xf
	s_nop 0
	v_add_f32_dpp v102, v102, v102 row_bcast:15 row_mask:0xa bank_mask:0xf
	v_add_f32_dpp v103, v103, v103 row_bcast:15 row_mask:0xa bank_mask:0xf
	s_nop 0
	v_add_f32_dpp v102, v102, v102 row_bcast:31 row_mask:0xc bank_mask:0xf
	v_add_f32_dpp v103, v103, v103 row_bcast:31 row_mask:0xc bank_mask:0xf
	s_nop 0
	v_readlane_b32 s98, v102, 63
	v_readlane_b32 s99, v103, 63
	s_nop 1
	v_mov_b32_e32 v102, s98
	v_mov_b32_e32 v103, s99
	v_mov_b32_e32 v104, 0
	v_mov_b32_e32 v105, 0
	v_add_u32_e32 v0, 0xfffff000, v92
	v_lshrrev_b32_e32 v0, 11, v0
	v_add_u32_e32 v0, 1, v0
	v_cmp_lt_i32_e64 s[42:43], s29, v92
	v_cndmask_b32_e64 v92, 0, v0, s[42:43]
	v_cmp_ne_u32_e64 s[42:43], v92, v117
	s_and_saveexec_b64 s[16:17], s[42:43]
	s_cbranch_execz .LBB0_760
	v_mul_u32_u24_e32 v0, 0x1800, v92
	v_lshlrev_b64 v[42:43], 2, v[0:1]
	v_lshl_add_u64 v[44:45], v[82:83], 0, v[42:43]
	v_lshl_add_u64 v[62:63], v[84:85], 0, v[42:43]
	global_load_dwordx4 v[54:57], v[44:45], off
	global_load_dwordx4 v[58:61], v[44:45], off offset:16
	global_load_dwordx4 v[70:73], v[44:45], off offset:2064
	global_load_dwordx4 v[66:69], v[44:45], off offset:2048
	s_nop 0
	global_load_dwordx4 v[42:45], v[62:63], off offset:16
	global_load_dwordx4 v[46:49], v[62:63], off
	global_load_dwordx4 v[50:53], v[62:63], off offset:2064
	s_nop 0
	global_load_dwordx4 v[62:65], v[62:63], off offset:2048
	v_mov_b32_e32 v117, v92
	s_waitcnt vmcnt(7)
	v_add_f32_e32 v56, 1.0, v56
	v_add_f32_e32 v57, 1.0, v57
	v_add_f32_e32 v54, 1.0, v54
	v_add_f32_e32 v55, 1.0, v55
	s_waitcnt vmcnt(6)
	v_add_f32_e32 v60, 1.0, v60
	v_add_f32_e32 v61, 1.0, v61
	v_add_f32_e32 v58, 1.0, v58
	v_add_f32_e32 v59, 1.0, v59
	s_waitcnt vmcnt(4)
	v_add_f32_e32 v68, 1.0, v68
	v_add_f32_e32 v69, 1.0, v69
	v_add_f32_e32 v66, 1.0, v66
	v_add_f32_e32 v67, 1.0, v67
	v_add_f32_e32 v72, 1.0, v72
	v_add_f32_e32 v73, 1.0, v73
	v_add_f32_e32 v70, 1.0, v70
	v_add_f32_e32 v71, 1.0, v71
	s_branch .LBB0_760

.Lrl_e0_780:
	v_lshl_or_b32 v184, s4, 8, v203
	s_lshl_b32 s4, s14, 8
	s_add_i32 s0, s4, 0xfffff000
	s_lshr_b32 s0, s0, 11
	s_mulk_i32 s0, 0x1800
	s_addk_i32 s0, 0x1800
	s_cmp_gt_i32 s14, 15
	s_cselect_b32 s86, s0, 0
	v_add_u32_e32 v186, s4, v201
	s_lshl_b64 s[0:1], s[86:87], 2
	v_ashrrev_i32_e32 v187, 31, v186
	s_add_u32 s0, s70, s0
	v_ashrrev_i32_e32 v185, 31, v184
	v_lshlrev_b64 v[188:189], 11, v[186:187]
	s_addc_u32 s1, s71, s1
	v_lshlrev_b64 v[18:19], 2, v[184:185]
	v_lshl_add_u64 v[188:189], s[12:13], 0, v[188:189]
	v_lshlrev_b64 v[184:185], 1, v[184:185]
	v_lshl_add_u64 v[22:23], s[0:1], 0, v[18:19]
	v_lshl_add_u64 v[30:31], s[2:3], 0, v[18:19]
	v_lshl_add_u64 v[38:39], s[16:17], 0, v[18:19]
	v_lshl_add_u64 v[194:195], v[186:187], 3, s[6:7]
	v_lshl_add_u64 v[188:189], v[188:189], 0, v[184:185]
	v_mov_b64_e32 v[184:185], v[188:189]
	global_load_dwordx4 v[58:61], v[22:23], off offset:16
	global_load_dwordx4 v[62:65], v[22:23], off
	global_load_dwordx4 v[66:69], v[30:31], off offset:16
	global_load_dwordx4 v[74:77], v[30:31], off
	global_load_dwordx4 v[70:73], v[38:39], off offset:16
	global_load_dwordx4 v[78:81], v[38:39], off
	global_load_dwordx4 v[18:21], v[22:23], off offset:528
	s_nop 0
	global_load_dwordx4 v[22:25], v[22:23], off offset:512
	s_nop 0
	global_load_dwordx4 v[26:29], v[30:31], off offset:528
	global_load_dwordx4 v[34:37], v[30:31], off offset:512
	s_nop 0
	global_load_dwordx4 v[30:33], v[38:39], off offset:528
	s_nop 0
	global_load_dwordx4 v[38:41], v[38:39], off offset:512
	s_and_b64 vcc, exec, s[40:41]
	global_load_dwordx2 v[232:233], v[194:195], off
	global_load_dwordx4 v[210:213], v[188:189], off
	global_load_dwordx4 v[214:217], v[188:189], off offset:256
	s_mov_b32 s0, 0x8000
	s_mov_b32 s1, 0
	v_lshl_add_u64 v[188:189], v[188:189], 0, s[0:1]
	global_load_dwordx2 v[250:251], v[194:195], off offset:128
	global_load_dwordx4 v[242:245], v[188:189], off
	global_load_dwordx4 v[246:249], v[188:189], off offset:256
	v_lshl_add_u64 v[188:189], v[188:189], 0, s[0:1]
	global_load_dwordx2 v[222:223], v[194:195], off offset:256
	global_load_dwordx4 v[218:221], v[188:189], off
	global_load_dwordx4 v[206:209], v[188:189], off offset:256
	v_lshl_add_u64 v[188:189], v[188:189], 0, s[0:1]
	s_mov_b32 s4, s42
	s_mov_b32 s14, s44
	s_mov_b64 s[34:35], s[48:49]
	s_mov_b64 s[20:21], s[46:47]
	s_waitcnt vmcnt(7)
	v_lshlrev_b32_e32 v196, 16, v210
	v_and_b32_e32 v197, 0xffff0000, v210
	v_lshlrev_b32_e32 v210, 16, v211
	v_and_b32_e32 v211, 0xffff0000, v211
	v_lshlrev_b32_e32 v186, 16, v212
	v_and_b32_e32 v187, 0xffff0000, v212
	v_lshlrev_b32_e32 v212, 16, v213
	v_and_b32_e32 v213, 0xffff0000, v213
	v_sub_f32_e32 v211, v211, v232
	v_sub_f32_e32 v210, v210, v232
	v_sub_f32_e32 v197, v197, v232
	v_sub_f32_e32 v196, v196, v232
	v_mul_f32_e32 v196, v233, v196
	v_mul_f32_e32 v197, v233, v197
	v_mul_f32_e32 v210, v233, v210
	v_mul_f32_e32 v211, v233, v211
	v_sub_f32_e32 v213, v213, v232
	v_sub_f32_e32 v212, v212, v232
	v_sub_f32_e32 v187, v187, v232
	v_sub_f32_e32 v186, v186, v232
	v_fma_f32 v210, v76, v210, v80
	v_fma_f32 v211, v77, v211, v81
	v_fma_f32 v196, v74, v196, v78
	v_fma_f32 v197, v75, v197, v79
	v_mul_f32_e32 v186, v233, v186
	v_mul_f32_e32 v187, v233, v187
	v_mul_f32_e32 v212, v233, v212
	v_mul_f32_e32 v213, v233, v213
	v_fma_f32 v186, v66, v186, v70
	v_fma_f32 v187, v67, v187, v71
	v_fma_f32 v212, v68, v212, v72
	v_fma_f32 v213, v69, v213, v73
	v_mul_f32_e32 v210, s56, v210
	v_mul_f32_e32 v211, s56, v211
	v_mul_f32_e32 v196, s56, v196
	v_mul_f32_e32 v197, s56, v197
	v_mul_f32_e32 v212, s56, v212
	v_mul_f32_e32 v213, s56, v213
	v_mul_f32_e32 v186, s56, v186
	v_mul_f32_e32 v187, s56, v187
	v_fma_f32 v176, v176, v64, v210
	v_fma_f32 v177, v177, v65, v211
	v_fma_f32 v174, v174, v62, v196
	v_fma_f32 v175, v175, v63, v197
	v_fma_f32 v172, v172, v60, v212
	v_fma_f32 v173, v173, v61, v213
	v_fma_f32 v170, v170, v58, v186
	v_fma_f32 v171, v171, v59, v187
	v_cvt_pk_bf16_f32 v174, v174, v175
	v_cvt_pk_bf16_f32 v175, v176, v177
	v_cvt_pk_bf16_f32 v176, v170, v171
	v_cvt_pk_bf16_f32 v177, v172, v173
	global_store_dwordx4 v[184:185], v[174:177], off
	s_waitcnt vmcnt(7)
	v_lshlrev_b32_e32 v196, 16, v214
	v_and_b32_e32 v197, 0xffff0000, v214
	v_lshlrev_b32_e32 v214, 16, v215
	v_and_b32_e32 v215, 0xffff0000, v215
	v_lshlrev_b32_e32 v186, 16, v216
	v_and_b32_e32 v187, 0xffff0000, v216
	v_lshlrev_b32_e32 v216, 16, v217
	v_and_b32_e32 v217, 0xffff0000, v217
	v_sub_f32_e32 v215, v215, v232
	v_sub_f32_e32 v214, v214, v232
	v_sub_f32_e32 v197, v197, v232
	v_sub_f32_e32 v196, v196, v232
	v_mul_f32_e32 v196, v233, v196
	v_mul_f32_e32 v197, v233, v197
	v_mul_f32_e32 v214, v233, v214
	v_mul_f32_e32 v215, v233, v215
	v_sub_f32_e32 v217, v217, v232
	v_sub_f32_e32 v216, v216, v232
	v_sub_f32_e32 v187, v187, v232
	v_sub_f32_e32 v186, v186, v232
	v_fma_f32 v214, v36, v214, v40
	v_fma_f32 v215, v37, v215, v41
	v_fma_f32 v196, v34, v196, v38
	v_fma_f32 v197, v35, v197, v39
	v_mul_f32_e32 v186, v233, v186
	v_mul_f32_e32 v187, v233, v187
	v_mul_f32_e32 v216, v233, v216
	v_mul_f32_e32 v217, v233, v217
	v_fma_f32 v186, v26, v186, v30
	v_fma_f32 v187, v27, v187, v31
	v_fma_f32 v216, v28, v216, v32
	v_fma_f32 v217, v29, v217, v33
	v_mul_f32_e32 v214, s56, v214
	v_mul_f32_e32 v215, s56, v215
	v_mul_f32_e32 v196, s56, v196
	v_mul_f32_e32 v197, s56, v197
	v_mul_f32_e32 v216, s56, v216
	v_mul_f32_e32 v217, s56, v217
	v_mul_f32_e32 v186, s56, v186
	v_mul_f32_e32 v187, s56, v187
	v_fma_f32 v168, v168, v24, v214
	v_fma_f32 v169, v169, v25, v215
	v_fma_f32 v166, v166, v22, v196
	v_fma_f32 v167, v167, v23, v197
	v_fma_f32 v164, v164, v20, v216
	v_fma_f32 v165, v165, v21, v217
	v_fma_f32 v162, v162, v18, v186
	v_fma_f32 v163, v163, v19, v187
	v_cvt_pk_bf16_f32 v166, v166, v167
	v_cvt_pk_bf16_f32 v167, v168, v169
	v_cvt_pk_bf16_f32 v168, v162, v163
	v_cvt_pk_bf16_f32 v169, v164, v165
	global_store_dwordx4 v[184:185], v[166:169], off offset:256
	v_lshl_add_u64 v[184:185], v[184:185], 0, s[0:1]
	global_load_dwordx2 v[232:233], v[194:195], off offset:384
	global_load_dwordx4 v[210:213], v[188:189], off
	global_load_dwordx4 v[214:217], v[188:189], off offset:256
	s_mov_b32 s0, 0x28000
	v_lshl_add_u64 v[188:189], v[188:189], 0, s[0:1]
	s_waitcnt vmcnt(9)
	v_lshlrev_b32_e32 v196, 16, v242
	v_and_b32_e32 v197, 0xffff0000, v242
	v_lshlrev_b32_e32 v242, 16, v243
	v_and_b32_e32 v243, 0xffff0000, v243
	v_lshlrev_b32_e32 v186, 16, v244
	v_and_b32_e32 v187, 0xffff0000, v244
	v_lshlrev_b32_e32 v244, 16, v245
	v_and_b32_e32 v245, 0xffff0000, v245
	v_sub_f32_e32 v243, v243, v250
	v_sub_f32_e32 v242, v242, v250
	v_sub_f32_e32 v197, v197, v250
	v_sub_f32_e32 v196, v196, v250
	v_mul_f32_e32 v196, v251, v196
	v_mul_f32_e32 v197, v251, v197
	v_mul_f32_e32 v242, v251, v242
	v_mul_f32_e32 v243, v251, v243
	v_sub_f32_e32 v245, v245, v250
	v_sub_f32_e32 v244, v244, v250
	v_sub_f32_e32 v187, v187, v250
	v_sub_f32_e32 v186, v186, v250
	v_fma_f32 v242, v76, v242, v80
	v_fma_f32 v243, v77, v243, v81
	v_fma_f32 v196, v74, v196, v78
	v_fma_f32 v197, v75, v197, v79
	v_mul_f32_e32 v186, v251, v186
	v_mul_f32_e32 v187, v251, v187
	v_mul_f32_e32 v244, v251, v244
	v_mul_f32_e32 v245, v251, v245
	v_fma_f32 v186, v66, v186, v70
	v_fma_f32 v187, v67, v187, v71
	v_fma_f32 v244, v68, v244, v72
	v_fma_f32 v245, v69, v245, v73
	v_mul_f32_e32 v242, s56, v242
	v_mul_f32_e32 v243, s56, v243
	v_mul_f32_e32 v196, s56, v196
	v_mul_f32_e32 v197, s56, v197
	v_mul_f32_e32 v244, s56, v244
	v_mul_f32_e32 v245, s56, v245
	v_mul_f32_e32 v186, s56, v186
	v_mul_f32_e32 v187, s56, v187
	v_fma_f32 v160, v160, v64, v242
	v_fma_f32 v161, v161, v65, v243
	v_fma_f32 v158, v158, v62, v196
	v_fma_f32 v159, v159, v63, v197
	v_fma_f32 v156, v156, v60, v244
	v_fma_f32 v157, v157, v61, v245
	v_fma_f32 v154, v154, v58, v186
	v_fma_f32 v155, v155, v59, v187
	v_cvt_pk_bf16_f32 v158, v158, v159
	v_cvt_pk_bf16_f32 v159, v160, v161
	v_cvt_pk_bf16_f32 v160, v154, v155
	v_cvt_pk_bf16_f32 v161, v156, v157
	global_store_dwordx4 v[184:185], v[158:161], off
	s_waitcnt vmcnt(9)
	v_lshlrev_b32_e32 v196, 16, v246
	v_and_b32_e32 v197, 0xffff0000, v246
	v_lshlrev_b32_e32 v246, 16, v247
	v_and_b32_e32 v247, 0xffff0000, v247
	v_lshlrev_b32_e32 v186, 16, v248
	v_and_b32_e32 v187, 0xffff0000, v248
	v_lshlrev_b32_e32 v248, 16, v249
	v_and_b32_e32 v249, 0xffff0000, v249
	v_sub_f32_e32 v247, v247, v250
	v_sub_f32_e32 v246, v246, v250
	v_sub_f32_e32 v197, v197, v250
	v_sub_f32_e32 v196, v196, v250
	v_mul_f32_e32 v196, v251, v196
	v_mul_f32_e32 v197, v251, v197
	v_mul_f32_e32 v246, v251, v246
	v_mul_f32_e32 v247, v251, v247
	v_sub_f32_e32 v249, v249, v250
	v_sub_f32_e32 v248, v248, v250
	v_sub_f32_e32 v187, v187, v250
	v_sub_f32_e32 v186, v186, v250
	v_fma_f32 v246, v36, v246, v40
	v_fma_f32 v247, v37, v247, v41
	v_fma_f32 v196, v34, v196, v38
	v_fma_f32 v197, v35, v197, v39
	v_mul_f32_e32 v186, v251, v186
	v_mul_f32_e32 v187, v251, v187
	v_mul_f32_e32 v248, v251, v248
	v_mul_f32_e32 v249, v251, v249
	v_fma_f32 v186, v26, v186, v30
	v_fma_f32 v187, v27, v187, v31
	v_fma_f32 v248, v28, v248, v32
	v_fma_f32 v249, v29, v249, v33
	v_mul_f32_e32 v246, s56, v246
	v_mul_f32_e32 v247, s56, v247
	v_mul_f32_e32 v196, s56, v196
	v_mul_f32_e32 v197, s56, v197
	v_mul_f32_e32 v248, s56, v248
	v_mul_f32_e32 v249, s56, v249
	v_mul_f32_e32 v186, s56, v186
	v_mul_f32_e32 v187, s56, v187
	v_fma_f32 v152, v152, v24, v246
	v_fma_f32 v153, v153, v25, v247
	v_fma_f32 v150, v150, v22, v196
	v_fma_f32 v151, v151, v23, v197
	v_fma_f32 v148, v148, v20, v248
	v_fma_f32 v149, v149, v21, v249
	v_fma_f32 v146, v146, v18, v186
	v_fma_f32 v147, v147, v19, v187
	v_cvt_pk_bf16_f32 v150, v150, v151
	v_cvt_pk_bf16_f32 v151, v152, v153
	v_cvt_pk_bf16_f32 v152, v146, v147
	v_cvt_pk_bf16_f32 v153, v148, v149
	global_store_dwordx4 v[184:185], v[150:153], off offset:256
	s_mov_b32 s0, 0x8000
	v_lshl_add_u64 v[184:185], v[184:185], 0, s[0:1]
	global_load_dwordx2 v[250:251], v[194:195], off offset:1024
	global_load_dwordx4 v[242:245], v[188:189], off
	global_load_dwordx4 v[246:249], v[188:189], off offset:256
	v_lshl_add_u64 v[188:189], v[188:189], 0, s[0:1]
	s_waitcnt vmcnt(11)
	v_lshlrev_b32_e32 v196, 16, v218
	v_and_b32_e32 v197, 0xffff0000, v218
	v_lshlrev_b32_e32 v218, 16, v219
	v_and_b32_e32 v219, 0xffff0000, v219
	v_lshlrev_b32_e32 v186, 16, v220
	v_and_b32_e32 v187, 0xffff0000, v220
	v_lshlrev_b32_e32 v220, 16, v221
	v_and_b32_e32 v221, 0xffff0000, v221
	v_sub_f32_e32 v219, v219, v222
	v_sub_f32_e32 v218, v218, v222
	v_sub_f32_e32 v197, v197, v222
	v_sub_f32_e32 v196, v196, v222
	v_mul_f32_e32 v196, v223, v196
	v_mul_f32_e32 v197, v223, v197
	v_mul_f32_e32 v218, v223, v218
	v_mul_f32_e32 v219, v223, v219
	v_sub_f32_e32 v221, v221, v222
	v_sub_f32_e32 v220, v220, v222
	v_sub_f32_e32 v187, v187, v222
	v_sub_f32_e32 v186, v186, v222
	v_fma_f32 v218, v76, v218, v80
	v_fma_f32 v219, v77, v219, v81
	v_fma_f32 v196, v74, v196, v78
	v_fma_f32 v197, v75, v197, v79
	v_mul_f32_e32 v186, v223, v186
	v_mul_f32_e32 v187, v223, v187
	v_mul_f32_e32 v220, v223, v220
	v_mul_f32_e32 v221, v223, v221
	v_fma_f32 v186, v66, v186, v70
	v_fma_f32 v187, v67, v187, v71
	v_fma_f32 v220, v68, v220, v72
	v_fma_f32 v221, v69, v221, v73
	v_mul_f32_e32 v218, s56, v218
	v_mul_f32_e32 v219, s56, v219
	v_mul_f32_e32 v196, s56, v196
	v_mul_f32_e32 v197, s56, v197
	v_mul_f32_e32 v220, s56, v220
	v_mul_f32_e32 v221, s56, v221
	v_mul_f32_e32 v186, s56, v186
	v_mul_f32_e32 v187, s56, v187
	v_fma_f32 v144, v144, v64, v218
	v_fma_f32 v145, v145, v65, v219
	v_fma_f32 v142, v142, v62, v196
	v_fma_f32 v143, v143, v63, v197
	v_fma_f32 v140, v140, v60, v220
	v_fma_f32 v141, v141, v61, v221
	v_fma_f32 v138, v138, v58, v186
	v_fma_f32 v139, v139, v59, v187
	v_cvt_pk_bf16_f32 v142, v142, v143
	v_cvt_pk_bf16_f32 v143, v144, v145
	v_cvt_pk_bf16_f32 v144, v138, v139
	v_cvt_pk_bf16_f32 v145, v140, v141
	global_store_dwordx4 v[184:185], v[142:145], off
	s_waitcnt vmcnt(11)
	v_lshlrev_b32_e32 v196, 16, v206
	v_and_b32_e32 v197, 0xffff0000, v206
	v_lshlrev_b32_e32 v206, 16, v207
	v_and_b32_e32 v207, 0xffff0000, v207
	v_lshlrev_b32_e32 v186, 16, v208
	v_and_b32_e32 v187, 0xffff0000, v208
	v_lshlrev_b32_e32 v208, 16, v209
	v_and_b32_e32 v209, 0xffff0000, v209
	v_sub_f32_e32 v207, v207, v222
	v_sub_f32_e32 v206, v206, v222
	v_sub_f32_e32 v197, v197, v222
	v_sub_f32_e32 v196, v196, v222
	v_mul_f32_e32 v196, v223, v196
	v_mul_f32_e32 v197, v223, v197
	v_mul_f32_e32 v206, v223, v206
	v_mul_f32_e32 v207, v223, v207
	v_sub_f32_e32 v209, v209, v222
	v_sub_f32_e32 v208, v208, v222
	v_sub_f32_e32 v187, v187, v222
	v_sub_f32_e32 v186, v186, v222
	v_fma_f32 v206, v36, v206, v40
	v_fma_f32 v207, v37, v207, v41
	v_fma_f32 v196, v34, v196, v38
	v_fma_f32 v197, v35, v197, v39
	v_mul_f32_e32 v186, v223, v186
	v_mul_f32_e32 v187, v223, v187
	v_mul_f32_e32 v208, v223, v208
	v_mul_f32_e32 v209, v223, v209
	v_fma_f32 v186, v26, v186, v30
	v_fma_f32 v187, v27, v187, v31
	v_fma_f32 v208, v28, v208, v32
	v_fma_f32 v209, v29, v209, v33
	v_mul_f32_e32 v206, s56, v206
	v_mul_f32_e32 v207, s56, v207
	v_mul_f32_e32 v196, s56, v196
	v_mul_f32_e32 v197, s56, v197
	v_mul_f32_e32 v208, s56, v208
	v_mul_f32_e32 v209, s56, v209
	v_mul_f32_e32 v186, s56, v186
	v_mul_f32_e32 v187, s56, v187
	v_fma_f32 v136, v136, v24, v206
	v_fma_f32 v137, v137, v25, v207
	v_fma_f32 v134, v134, v22, v196
	v_fma_f32 v135, v135, v23, v197
	v_fma_f32 v132, v132, v20, v208
	v_fma_f32 v133, v133, v21, v209
	v_fma_f32 v130, v130, v18, v186
	v_fma_f32 v131, v131, v19, v187
	v_cvt_pk_bf16_f32 v134, v134, v135
	v_cvt_pk_bf16_f32 v135, v136, v137
	v_cvt_pk_bf16_f32 v136, v130, v131
	v_cvt_pk_bf16_f32 v137, v132, v133
	global_store_dwordx4 v[184:185], v[134:137], off offset:256
	v_lshl_add_u64 v[184:185], v[184:185], 0, s[0:1]
	global_load_dwordx2 v[222:223], v[194:195], off offset:1152
	global_load_dwordx4 v[218:221], v[188:189], off
	global_load_dwordx4 v[206:209], v[188:189], off offset:256
	v_lshl_add_u64 v[188:189], v[188:189], 0, s[0:1]
	s_waitcnt vmcnt(11)
	v_lshlrev_b32_e32 v196, 16, v210
	v_and_b32_e32 v197, 0xffff0000, v210
	v_lshlrev_b32_e32 v210, 16, v211
	v_and_b32_e32 v211, 0xffff0000, v211
	v_lshlrev_b32_e32 v186, 16, v212
	v_and_b32_e32 v187, 0xffff0000, v212
	v_lshlrev_b32_e32 v212, 16, v213
	v_and_b32_e32 v213, 0xffff0000, v213
	v_sub_f32_e32 v211, v211, v232
	v_sub_f32_e32 v210, v210, v232
	v_sub_f32_e32 v197, v197, v232
	v_sub_f32_e32 v196, v196, v232
	v_mul_f32_e32 v196, v233, v196
	v_mul_f32_e32 v197, v233, v197
	v_mul_f32_e32 v210, v233, v210
	v_mul_f32_e32 v211, v233, v211
	v_sub_f32_e32 v213, v213, v232
	v_sub_f32_e32 v212, v212, v232
	v_sub_f32_e32 v187, v187, v232
	v_sub_f32_e32 v186, v186, v232
	v_fma_f32 v210, v76, v210, v80
	v_fma_f32 v211, v77, v211, v81
	v_fma_f32 v196, v74, v196, v78
	v_fma_f32 v197, v75, v197, v79
	v_mul_f32_e32 v186, v233, v186
	v_mul_f32_e32 v187, v233, v187
	v_mul_f32_e32 v212, v233, v212
	v_mul_f32_e32 v213, v233, v213
	v_fma_f32 v186, v66, v186, v70
	v_fma_f32 v187, v67, v187, v71
	v_fma_f32 v212, v68, v212, v72
	v_fma_f32 v213, v69, v213, v73
	v_mul_f32_e32 v210, s56, v210
	v_mul_f32_e32 v211, s56, v211
	v_mul_f32_e32 v196, s56, v196
	v_mul_f32_e32 v197, s56, v197
	v_mul_f32_e32 v212, s56, v212
	v_mul_f32_e32 v213, s56, v213
	v_mul_f32_e32 v186, s56, v186
	v_mul_f32_e32 v187, s56, v187
	v_fma_f32 v128, v128, v64, v210
	v_fma_f32 v129, v129, v65, v211
	v_fma_f32 v126, v126, v62, v196
	v_fma_f32 v127, v127, v63, v197
	v_fma_f32 v124, v124, v60, v212
	v_fma_f32 v125, v125, v61, v213
	v_fma_f32 v122, v122, v58, v186
	v_fma_f32 v123, v123, v59, v187
	v_cvt_pk_bf16_f32 v126, v126, v127
	v_cvt_pk_bf16_f32 v127, v128, v129
	v_cvt_pk_bf16_f32 v128, v122, v123
	v_cvt_pk_bf16_f32 v129, v124, v125
	global_store_dwordx4 v[184:185], v[126:129], off
	s_waitcnt vmcnt(11)
	v_lshlrev_b32_e32 v196, 16, v214
	v_and_b32_e32 v197, 0xffff0000, v214
	v_lshlrev_b32_e32 v214, 16, v215
	v_and_b32_e32 v215, 0xffff0000, v215
	v_lshlrev_b32_e32 v186, 16, v216
	v_and_b32_e32 v187, 0xffff0000, v216
	v_lshlrev_b32_e32 v216, 16, v217
	v_and_b32_e32 v217, 0xffff0000, v217
	v_sub_f32_e32 v215, v215, v232
	v_sub_f32_e32 v214, v214, v232
	v_sub_f32_e32 v197, v197, v232
	v_sub_f32_e32 v196, v196, v232
	v_mul_f32_e32 v196, v233, v196
	v_mul_f32_e32 v197, v233, v197
	v_mul_f32_e32 v214, v233, v214
	v_mul_f32_e32 v215, v233, v215
	v_sub_f32_e32 v217, v217, v232
	v_sub_f32_e32 v216, v216, v232
	v_sub_f32_e32 v187, v187, v232
	v_sub_f32_e32 v186, v186, v232
	v_fma_f32 v214, v36, v214, v40
	v_fma_f32 v215, v37, v215, v41
	v_fma_f32 v196, v34, v196, v38
	v_fma_f32 v197, v35, v197, v39
	v_mul_f32_e32 v186, v233, v186
	v_mul_f32_e32 v187, v233, v187
	v_mul_f32_e32 v216, v233, v216
	v_mul_f32_e32 v217, v233, v217
	v_fma_f32 v186, v26, v186, v30
	v_fma_f32 v187, v27, v187, v31
	v_fma_f32 v216, v28, v216, v32
	v_fma_f32 v217, v29, v217, v33
	v_mul_f32_e32 v214, s56, v214
	v_mul_f32_e32 v215, s56, v215
	v_mul_f32_e32 v196, s56, v196
	v_mul_f32_e32 v197, s56, v197
	v_mul_f32_e32 v216, s56, v216
	v_mul_f32_e32 v217, s56, v217
	v_mul_f32_e32 v186, s56, v186
	v_mul_f32_e32 v187, s56, v187
	v_fma_f32 v120, v120, v24, v214
	v_fma_f32 v121, v121, v25, v215
	v_fma_f32 v118, v118, v22, v196
	v_fma_f32 v119, v119, v23, v197
	v_fma_f32 v116, v116, v20, v216
	v_fma_f32 v117, v117, v21, v217
	v_fma_f32 v114, v114, v18, v186
	v_fma_f32 v115, v115, v19, v187
	v_cvt_pk_bf16_f32 v118, v118, v119
	v_cvt_pk_bf16_f32 v119, v120, v121
	v_cvt_pk_bf16_f32 v120, v114, v115
	v_cvt_pk_bf16_f32 v121, v116, v117
	global_store_dwordx4 v[184:185], v[118:121], off offset:256
	s_mov_b32 s0, 0x28000
	v_lshl_add_u64 v[184:185], v[184:185], 0, s[0:1]
	global_load_dwordx2 v[232:233], v[194:195], off offset:1280
	global_load_dwordx4 v[210:213], v[188:189], off
	global_load_dwordx4 v[214:217], v[188:189], off offset:256
	s_mov_b32 s0, 0x8000
	v_lshl_add_u64 v[188:189], v[188:189], 0, s[0:1]
	s_waitcnt vmcnt(11)
	v_lshlrev_b32_e32 v196, 16, v242
	v_and_b32_e32 v197, 0xffff0000, v242
	v_lshlrev_b32_e32 v242, 16, v243
	v_and_b32_e32 v243, 0xffff0000, v243
	v_lshlrev_b32_e32 v186, 16, v244
	v_and_b32_e32 v187, 0xffff0000, v244
	v_lshlrev_b32_e32 v244, 16, v245
	v_and_b32_e32 v245, 0xffff0000, v245
	v_sub_f32_e32 v243, v243, v250
	v_sub_f32_e32 v242, v242, v250
	v_sub_f32_e32 v197, v197, v250
	v_sub_f32_e32 v196, v196, v250
	v_mul_f32_e32 v196, v251, v196
	v_mul_f32_e32 v197, v251, v197
	v_mul_f32_e32 v242, v251, v242
	v_mul_f32_e32 v243, v251, v243
	v_sub_f32_e32 v245, v245, v250
	v_sub_f32_e32 v244, v244, v250
	v_sub_f32_e32 v187, v187, v250
	v_sub_f32_e32 v186, v186, v250
	v_fma_f32 v242, v76, v242, v80
	v_fma_f32 v243, v77, v243, v81
	v_fma_f32 v196, v74, v196, v78
	v_fma_f32 v197, v75, v197, v79
	v_mul_f32_e32 v186, v251, v186
	v_mul_f32_e32 v187, v251, v187
	v_mul_f32_e32 v244, v251, v244
	v_mul_f32_e32 v245, v251, v245
	v_fma_f32 v186, v66, v186, v70
	v_fma_f32 v187, v67, v187, v71
	v_fma_f32 v244, v68, v244, v72
	v_fma_f32 v245, v69, v245, v73
	v_mul_f32_e32 v242, s56, v242
	v_mul_f32_e32 v243, s56, v243
	v_mul_f32_e32 v196, s56, v196
	v_mul_f32_e32 v197, s56, v197
	v_mul_f32_e32 v244, s56, v244
	v_mul_f32_e32 v245, s56, v245
	v_mul_f32_e32 v186, s56, v186
	v_mul_f32_e32 v187, s56, v187
	v_fma_f32 v112, v112, v64, v242
	v_fma_f32 v113, v113, v65, v243
	v_fma_f32 v110, v110, v62, v196
	v_fma_f32 v111, v111, v63, v197
	v_fma_f32 v108, v108, v60, v244
	v_fma_f32 v109, v109, v61, v245
	v_fma_f32 v106, v106, v58, v186
	v_fma_f32 v107, v107, v59, v187
	v_cvt_pk_bf16_f32 v110, v110, v111
	v_cvt_pk_bf16_f32 v111, v112, v113
	v_cvt_pk_bf16_f32 v112, v106, v107
	v_cvt_pk_bf16_f32 v113, v108, v109
	global_store_dwordx4 v[184:185], v[110:113], off
	s_waitcnt vmcnt(11)
	v_lshlrev_b32_e32 v196, 16, v246
	v_and_b32_e32 v197, 0xffff0000, v246
	v_lshlrev_b32_e32 v246, 16, v247
	v_and_b32_e32 v247, 0xffff0000, v247
	v_lshlrev_b32_e32 v186, 16, v248
	v_and_b32_e32 v187, 0xffff0000, v248
	v_lshlrev_b32_e32 v248, 16, v249
	v_and_b32_e32 v249, 0xffff0000, v249
	v_sub_f32_e32 v247, v247, v250
	v_sub_f32_e32 v246, v246, v250
	v_sub_f32_e32 v197, v197, v250
	v_sub_f32_e32 v196, v196, v250
	v_mul_f32_e32 v196, v251, v196
	v_mul_f32_e32 v197, v251, v197
	v_mul_f32_e32 v246, v251, v246
	v_mul_f32_e32 v247, v251, v247
	v_sub_f32_e32 v249, v249, v250
	v_sub_f32_e32 v248, v248, v250
	v_sub_f32_e32 v187, v187, v250
	v_sub_f32_e32 v186, v186, v250
	v_fma_f32 v246, v36, v246, v40
	v_fma_f32 v247, v37, v247, v41
	v_fma_f32 v196, v34, v196, v38
	v_fma_f32 v197, v35, v197, v39
	v_mul_f32_e32 v186, v251, v186
	v_mul_f32_e32 v187, v251, v187
	v_mul_f32_e32 v248, v251, v248
	v_mul_f32_e32 v249, v251, v249
	v_fma_f32 v186, v26, v186, v30
	v_fma_f32 v187, v27, v187, v31
	v_fma_f32 v248, v28, v248, v32
	v_fma_f32 v249, v29, v249, v33
	v_mul_f32_e32 v246, s56, v246
	v_mul_f32_e32 v247, s56, v247
	v_mul_f32_e32 v196, s56, v196
	v_mul_f32_e32 v197, s56, v197
	v_mul_f32_e32 v248, s56, v248
	v_mul_f32_e32 v249, s56, v249
	v_mul_f32_e32 v186, s56, v186
	v_mul_f32_e32 v187, s56, v187
	v_fma_f32 v104, v104, v24, v246
	v_fma_f32 v105, v105, v25, v247
	v_fma_f32 v102, v102, v22, v196
	v_fma_f32 v103, v103, v23, v197
	v_fma_f32 v100, v100, v20, v248
	v_fma_f32 v101, v101, v21, v249
	v_fma_f32 v98, v98, v18, v186
	v_fma_f32 v99, v99, v19, v187
	v_cvt_pk_bf16_f32 v102, v102, v103
	v_cvt_pk_bf16_f32 v103, v104, v105
	v_cvt_pk_bf16_f32 v104, v98, v99
	v_cvt_pk_bf16_f32 v105, v100, v101
	global_store_dwordx4 v[184:185], v[102:105], off offset:256
	v_lshl_add_u64 v[184:185], v[184:185], 0, s[0:1]
	global_load_dwordx2 v[250:251], v[194:195], off offset:1408
	global_load_dwordx4 v[242:245], v[188:189], off
	global_load_dwordx4 v[246:249], v[188:189], off offset:256
	s_waitcnt vmcnt(11)
	v_lshlrev_b32_e32 v196, 16, v218
	v_and_b32_e32 v197, 0xffff0000, v218
	v_lshlrev_b32_e32 v218, 16, v219
	v_and_b32_e32 v219, 0xffff0000, v219
	v_lshlrev_b32_e32 v186, 16, v220
	v_and_b32_e32 v187, 0xffff0000, v220
	v_lshlrev_b32_e32 v220, 16, v221
	v_and_b32_e32 v221, 0xffff0000, v221
	v_sub_f32_e32 v219, v219, v222
	v_sub_f32_e32 v218, v218, v222
	v_sub_f32_e32 v197, v197, v222
	v_sub_f32_e32 v196, v196, v222
	v_mul_f32_e32 v196, v223, v196
	v_mul_f32_e32 v197, v223, v197
	v_mul_f32_e32 v218, v223, v218
	v_mul_f32_e32 v219, v223, v219
	v_sub_f32_e32 v221, v221, v222
	v_sub_f32_e32 v220, v220, v222
	v_sub_f32_e32 v187, v187, v222
	v_sub_f32_e32 v186, v186, v222
	v_fma_f32 v218, v76, v218, v80
	v_fma_f32 v219, v77, v219, v81
	v_fma_f32 v196, v74, v196, v78
	v_fma_f32 v197, v75, v197, v79
	v_mul_f32_e32 v186, v223, v186
	v_mul_f32_e32 v187, v223, v187
	v_mul_f32_e32 v220, v223, v220
	v_mul_f32_e32 v221, v223, v221
	v_fma_f32 v186, v66, v186, v70
	v_fma_f32 v187, v67, v187, v71
	v_fma_f32 v220, v68, v220, v72
	v_fma_f32 v221, v69, v221, v73
	v_mul_f32_e32 v218, s56, v218
	v_mul_f32_e32 v219, s56, v219
	v_mul_f32_e32 v196, s56, v196
	v_mul_f32_e32 v197, s56, v197
	v_mul_f32_e32 v220, s56, v220
	v_mul_f32_e32 v221, s56, v221
	v_mul_f32_e32 v186, s56, v186
	v_mul_f32_e32 v187, s56, v187
	v_fma_f32 v96, v96, v64, v218
	v_fma_f32 v97, v97, v65, v219
	v_fma_f32 v94, v94, v62, v196
	v_fma_f32 v95, v95, v63, v197
	v_fma_f32 v92, v92, v60, v220
	v_fma_f32 v93, v93, v61, v221
	v_fma_f32 v90, v90, v58, v186
	v_fma_f32 v91, v91, v59, v187
	v_cvt_pk_bf16_f32 v94, v94, v95
	v_cvt_pk_bf16_f32 v95, v96, v97
	v_cvt_pk_bf16_f32 v96, v90, v91
	v_cvt_pk_bf16_f32 v97, v92, v93
	global_store_dwordx4 v[184:185], v[94:97], off
	s_waitcnt vmcnt(11)
	v_lshlrev_b32_e32 v196, 16, v206
	v_and_b32_e32 v197, 0xffff0000, v206
	v_lshlrev_b32_e32 v206, 16, v207
	v_and_b32_e32 v207, 0xffff0000, v207
	v_lshlrev_b32_e32 v186, 16, v208
	v_and_b32_e32 v187, 0xffff0000, v208
	v_lshlrev_b32_e32 v208, 16, v209
	v_and_b32_e32 v209, 0xffff0000, v209
	v_sub_f32_e32 v207, v207, v222
	v_sub_f32_e32 v206, v206, v222
	v_sub_f32_e32 v197, v197, v222
	v_sub_f32_e32 v196, v196, v222
	v_mul_f32_e32 v196, v223, v196
	v_mul_f32_e32 v197, v223, v197
	v_mul_f32_e32 v206, v223, v206
	v_mul_f32_e32 v207, v223, v207
	v_sub_f32_e32 v209, v209, v222
	v_sub_f32_e32 v208, v208, v222
	v_sub_f32_e32 v187, v187, v222
	v_sub_f32_e32 v186, v186, v222
	v_fma_f32 v206, v36, v206, v40
	v_fma_f32 v207, v37, v207, v41
	v_fma_f32 v196, v34, v196, v38
	v_fma_f32 v197, v35, v197, v39
	v_mul_f32_e32 v186, v223, v186
	v_mul_f32_e32 v187, v223, v187
	v_mul_f32_e32 v208, v223, v208
	v_mul_f32_e32 v209, v223, v209
	v_fma_f32 v186, v26, v186, v30
	v_fma_f32 v187, v27, v187, v31
	v_fma_f32 v208, v28, v208, v32
	v_fma_f32 v209, v29, v209, v33
	v_mul_f32_e32 v206, s56, v206
	v_mul_f32_e32 v207, s56, v207
	v_mul_f32_e32 v196, s56, v196
	v_mul_f32_e32 v197, s56, v197
	v_mul_f32_e32 v208, s56, v208
	v_mul_f32_e32 v209, s56, v209
	v_mul_f32_e32 v186, s56, v186
	v_mul_f32_e32 v187, s56, v187
	v_fma_f32 v88, v88, v24, v206
	v_fma_f32 v89, v89, v25, v207
	v_fma_f32 v86, v86, v22, v196
	v_fma_f32 v87, v87, v23, v197
	v_fma_f32 v84, v84, v20, v208
	v_fma_f32 v85, v85, v21, v209
	v_fma_f32 v82, v82, v18, v186
	v_fma_f32 v83, v83, v19, v187
	v_cvt_pk_bf16_f32 v86, v86, v87
	v_cvt_pk_bf16_f32 v87, v88, v89
	v_cvt_pk_bf16_f32 v88, v82, v83
	v_cvt_pk_bf16_f32 v89, v84, v85
	global_store_dwordx4 v[184:185], v[86:89], off offset:256
	v_lshl_add_u64 v[184:185], v[184:185], 0, s[0:1]
	s_waitcnt vmcnt(8)
	v_lshlrev_b32_e32 v196, 16, v210
	v_and_b32_e32 v197, 0xffff0000, v210
	v_lshlrev_b32_e32 v210, 16, v211
	v_and_b32_e32 v211, 0xffff0000, v211
	v_lshlrev_b32_e32 v186, 16, v212
	v_and_b32_e32 v187, 0xffff0000, v212
	v_lshlrev_b32_e32 v212, 16, v213
	v_and_b32_e32 v213, 0xffff0000, v213
	v_sub_f32_e32 v211, v211, v232
	v_sub_f32_e32 v210, v210, v232
	v_sub_f32_e32 v197, v197, v232
	v_sub_f32_e32 v196, v196, v232
	v_mul_f32_e32 v196, v233, v196
	v_mul_f32_e32 v197, v233, v197
	v_mul_f32_e32 v210, v233, v210
	v_mul_f32_e32 v211, v233, v211
	v_sub_f32_e32 v213, v213, v232
	v_sub_f32_e32 v212, v212, v232
	v_sub_f32_e32 v187, v187, v232
	v_sub_f32_e32 v186, v186, v232
	v_fma_f32 v210, v76, v210, v80
	v_fma_f32 v211, v77, v211, v81
	v_fma_f32 v196, v74, v196, v78
	v_fma_f32 v197, v75, v197, v79
	v_mul_f32_e32 v186, v233, v186
	v_mul_f32_e32 v187, v233, v187
	v_mul_f32_e32 v212, v233, v212
	v_mul_f32_e32 v213, v233, v213
	v_fma_f32 v186, v66, v186, v70
	v_fma_f32 v187, v67, v187, v71
	v_fma_f32 v212, v68, v212, v72
	v_fma_f32 v213, v69, v213, v73
	v_mul_f32_e32 v210, s56, v210
	v_mul_f32_e32 v211, s56, v211
	v_mul_f32_e32 v196, s56, v196
	v_mul_f32_e32 v197, s56, v197
	v_mul_f32_e32 v212, s56, v212
	v_mul_f32_e32 v213, s56, v213
	v_mul_f32_e32 v186, s56, v186
	v_mul_f32_e32 v187, s56, v187
	v_fma_f32 v56, v56, v64, v210
	v_fma_f32 v57, v57, v65, v211
	v_fma_f32 v54, v54, v62, v196
	v_fma_f32 v55, v55, v63, v197
	v_fma_f32 v52, v52, v60, v212
	v_fma_f32 v53, v53, v61, v213
	v_fma_f32 v50, v50, v58, v186
	v_fma_f32 v51, v51, v59, v187
	v_cvt_pk_bf16_f32 v54, v54, v55
	v_cvt_pk_bf16_f32 v55, v56, v57
	v_cvt_pk_bf16_f32 v56, v50, v51
	v_cvt_pk_bf16_f32 v57, v52, v53
	global_store_dwordx4 v[184:185], v[54:57], off
	s_waitcnt vmcnt(8)
	v_lshlrev_b32_e32 v196, 16, v214
	v_and_b32_e32 v197, 0xffff0000, v214
	v_lshlrev_b32_e32 v214, 16, v215
	v_and_b32_e32 v215, 0xffff0000, v215
	v_lshlrev_b32_e32 v186, 16, v216
	v_and_b32_e32 v187, 0xffff0000, v216
	v_lshlrev_b32_e32 v216, 16, v217
	v_and_b32_e32 v217, 0xffff0000, v217
	v_sub_f32_e32 v215, v215, v232
	v_sub_f32_e32 v214, v214, v232
	v_sub_f32_e32 v197, v197, v232
	v_sub_f32_e32 v196, v196, v232
	v_mul_f32_e32 v196, v233, v196
	v_mul_f32_e32 v197, v233, v197
	v_mul_f32_e32 v214, v233, v214
	v_mul_f32_e32 v215, v233, v215
	v_sub_f32_e32 v217, v217, v232
	v_sub_f32_e32 v216, v216, v232
	v_sub_f32_e32 v187, v187, v232
	v_sub_f32_e32 v186, v186, v232
	v_fma_f32 v214, v36, v214, v40
	v_fma_f32 v215, v37, v215, v41
	v_fma_f32 v196, v34, v196, v38
	v_fma_f32 v197, v35, v197, v39
	v_mul_f32_e32 v186, v233, v186
	v_mul_f32_e32 v187, v233, v187
	v_mul_f32_e32 v216, v233, v216
	v_mul_f32_e32 v217, v233, v217
	v_fma_f32 v186, v26, v186, v30
	v_fma_f32 v187, v27, v187, v31
	v_fma_f32 v216, v28, v216, v32
	v_fma_f32 v217, v29, v217, v33
	v_mul_f32_e32 v214, s56, v214
	v_mul_f32_e32 v215, s56, v215
	v_mul_f32_e32 v196, s56, v196
	v_mul_f32_e32 v197, s56, v197
	v_mul_f32_e32 v216, s56, v216
	v_mul_f32_e32 v217, s56, v217
	v_mul_f32_e32 v186, s56, v186
	v_mul_f32_e32 v187, s56, v187
	v_fma_f32 v48, v48, v24, v214
	v_fma_f32 v49, v49, v25, v215
	v_fma_f32 v46, v46, v22, v196
	v_fma_f32 v47, v47, v23, v197
	v_fma_f32 v44, v44, v20, v216
	v_fma_f32 v45, v45, v21, v217
	v_fma_f32 v42, v42, v18, v186
	v_fma_f32 v43, v43, v19, v187
	v_cvt_pk_bf16_f32 v46, v46, v47
	v_cvt_pk_bf16_f32 v47, v48, v49
	v_cvt_pk_bf16_f32 v48, v42, v43
	v_cvt_pk_bf16_f32 v49, v44, v45
	global_store_dwordx4 v[184:185], v[46:49], off offset:256
	v_lshl_add_u64 v[184:185], v[184:185], 0, s[0:1]
	s_waitcnt vmcnt(5)
	v_lshlrev_b32_e32 v196, 16, v242
	v_and_b32_e32 v197, 0xffff0000, v242
	v_lshlrev_b32_e32 v242, 16, v243
	v_and_b32_e32 v243, 0xffff0000, v243
	v_lshlrev_b32_e32 v186, 16, v244
	v_and_b32_e32 v187, 0xffff0000, v244
	v_lshlrev_b32_e32 v244, 16, v245
	v_and_b32_e32 v245, 0xffff0000, v245
	v_sub_f32_e32 v243, v243, v250
	v_sub_f32_e32 v242, v242, v250
	v_sub_f32_e32 v197, v197, v250
	v_sub_f32_e32 v196, v196, v250
	v_mul_f32_e32 v196, v251, v196
	v_mul_f32_e32 v197, v251, v197
	v_mul_f32_e32 v242, v251, v242
	v_mul_f32_e32 v243, v251, v243
	v_sub_f32_e32 v245, v245, v250
	v_sub_f32_e32 v244, v244, v250
	v_sub_f32_e32 v187, v187, v250
	v_sub_f32_e32 v186, v186, v250
	v_fma_f32 v242, v76, v242, v80
	v_fma_f32 v243, v77, v243, v81
	v_fma_f32 v196, v74, v196, v78
	v_fma_f32 v197, v75, v197, v79
	v_mul_f32_e32 v186, v251, v186
	v_mul_f32_e32 v187, v251, v187
	v_mul_f32_e32 v244, v251, v244
	v_mul_f32_e32 v245, v251, v245
	v_fma_f32 v186, v66, v186, v70
	v_fma_f32 v187, v67, v187, v71
	v_fma_f32 v244, v68, v244, v72
	v_fma_f32 v245, v69, v245, v73
	v_mul_f32_e32 v242, s56, v242
	v_mul_f32_e32 v243, s56, v243
	v_mul_f32_e32 v196, s56, v196
	v_mul_f32_e32 v197, s56, v197
	v_mul_f32_e32 v244, s56, v244
	v_mul_f32_e32 v245, s56, v245
	v_mul_f32_e32 v186, s56, v186
	v_mul_f32_e32 v187, s56, v187
	v_fma_f32 v16, v16, v64, v242
	v_fma_f32 v17, v17, v65, v243
	v_fma_f32 v14, v14, v62, v196
	v_fma_f32 v15, v15, v63, v197
	v_fma_f32 v12, v12, v60, v244
	v_fma_f32 v13, v13, v61, v245
	v_fma_f32 v10, v10, v58, v186
	v_fma_f32 v11, v11, v59, v187
	v_cvt_pk_bf16_f32 v14, v14, v15
	v_cvt_pk_bf16_f32 v15, v16, v17
	v_cvt_pk_bf16_f32 v16, v10, v11
	v_cvt_pk_bf16_f32 v17, v12, v13
	global_store_dwordx4 v[184:185], v[14:17], off
	s_waitcnt vmcnt(5)
	v_lshlrev_b32_e32 v196, 16, v246
	v_and_b32_e32 v197, 0xffff0000, v246
	v_lshlrev_b32_e32 v246, 16, v247
	v_and_b32_e32 v247, 0xffff0000, v247
	v_lshlrev_b32_e32 v186, 16, v248
	v_and_b32_e32 v187, 0xffff0000, v248
	v_lshlrev_b32_e32 v248, 16, v249
	v_and_b32_e32 v249, 0xffff0000, v249
	v_sub_f32_e32 v247, v247, v250
	v_sub_f32_e32 v246, v246, v250
	v_sub_f32_e32 v197, v197, v250
	v_sub_f32_e32 v196, v196, v250
	v_mul_f32_e32 v196, v251, v196
	v_mul_f32_e32 v197, v251, v197
	v_mul_f32_e32 v246, v251, v246
	v_mul_f32_e32 v247, v251, v247
	v_sub_f32_e32 v249, v249, v250
	v_sub_f32_e32 v248, v248, v250
	v_sub_f32_e32 v187, v187, v250
	v_sub_f32_e32 v186, v186, v250
	v_fma_f32 v246, v36, v246, v40
	v_fma_f32 v247, v37, v247, v41
	v_fma_f32 v196, v34, v196, v38
	v_fma_f32 v197, v35, v197, v39
	v_mul_f32_e32 v186, v251, v186
	v_mul_f32_e32 v187, v251, v187
	v_mul_f32_e32 v248, v251, v248
	v_mul_f32_e32 v249, v251, v249
	v_fma_f32 v186, v26, v186, v30
	v_fma_f32 v187, v27, v187, v31
	v_fma_f32 v248, v28, v248, v32
	v_fma_f32 v249, v29, v249, v33
	v_mul_f32_e32 v246, s56, v246
	v_mul_f32_e32 v247, s56, v247
	v_mul_f32_e32 v196, s56, v196
	v_mul_f32_e32 v197, s56, v197
	v_mul_f32_e32 v248, s56, v248
	v_mul_f32_e32 v249, s56, v249
	v_mul_f32_e32 v186, s56, v186
	v_mul_f32_e32 v187, s56, v187
	v_fma_f32 v8, v8, v24, v246
	v_fma_f32 v9, v9, v25, v247
	v_fma_f32 v6, v6, v22, v196
	v_fma_f32 v7, v7, v23, v197
	v_fma_f32 v4, v4, v20, v248
	v_fma_f32 v5, v5, v21, v249
	v_fma_f32 v2, v2, v18, v186
	v_fma_f32 v3, v3, v19, v187
	v_cvt_pk_bf16_f32 v6, v6, v7
	v_cvt_pk_bf16_f32 v7, v8, v9
	v_cvt_pk_bf16_f32 v8, v2, v3
	v_cvt_pk_bf16_f32 v9, v4, v5
	global_store_dwordx4 v[184:185], v[6:9], off offset:256
	v_readfirstlane_b32 s98, v191
	s_cmpk_lt_u32 s98, 0x100
	s_cbranch_scc1 .Lrl_e1_780
	s_barrier

.Lrl_e0_794:
	s_lshl_b32 s3, s42, 8
	s_add_i32 s0, s3, 0xfffff000
	s_lshr_b32 s0, s0, 11
	s_mulk_i32 s0, 0x1800
	s_addk_i32 s0, 0x1800
	v_add_u32_e32 v158, s3, v160
	s_cmp_gt_i32 s42, 15
	v_ashrrev_i32_e32 v159, 31, v158
	v_add_u32_e32 v0, 0xfffff000, v158
	v_lshl_or_b32 v194, s66, 8, v162
	s_cselect_b32 s86, s0, 0
	v_lshlrev_b64 v[218:219], 12, v[0:1]
	v_lshlrev_b64 v[220:221], 12, v[158:159]
	s_lshl_b64 s[0:1], s[86:87], 2
	v_ashrrev_i32_e32 v195, 31, v194
	v_lshl_add_u64 v[220:221], s[44:45], 0, v[220:221]
	v_lshl_add_u64 v[218:219], s[46:47], 0, v[218:219]
	v_cmp_gt_i32_e32 vcc, s33, v158
	v_lshlrev_b64 v[196:197], 2, v[194:195]
	s_add_u32 s0, s37, s0
	v_cndmask_b32_e32 v219, v219, v221, vcc
	v_cndmask_b32_e32 v218, v218, v220, vcc
	v_lshl_add_u64 v[154:155], v[218:219], 0, v[196:197]
	s_addc_u32 s1, s38, s1
	v_lshl_add_u64 v[218:219], s[0:1], 0, v[196:197]
	global_load_dwordx4 v[134:137], v[218:219], off
	global_load_dwordx4 v[130:133], v[218:219], off offset:16
	global_load_dwordx4 v[122:125], v[218:219], off offset:528
	global_load_dwordx4 v[126:129], v[218:219], off offset:512
	v_lshlrev_b64 v[196:197], 1, v[194:195]
	v_lshlrev_b64 v[156:157], 11, v[158:159]
	v_lshl_add_u64 v[156:157], s[12:13], 0, v[156:157]
	v_lshl_add_u64 v[156:157], v[156:157], 0, v[196:197]
	s_mov_b32 s66, s2
	s_mov_b64 s[34:35], s[16:17]
	s_mov_b64 s[20:21], s[14:15]
	s_mov_b32 s42, s6
	global_load_dwordx4 v[164:167], v[154:155], off
	global_load_dwordx4 v[168:171], v[154:155], off offset:16
	global_load_dwordx4 v[172:175], v[154:155], off offset:512
	global_load_dwordx4 v[176:179], v[154:155], off offset:528
	s_mov_b32 s0, 0x10000
	s_mov_b32 s1, 0
	v_lshl_add_u64 v[154:155], v[154:155], 0, s[0:1]
	global_load_dwordx4 v[180:183], v[154:155], off
	global_load_dwordx4 v[184:187], v[154:155], off offset:16
	global_load_dwordx4 v[202:205], v[154:155], off offset:512
	global_load_dwordx4 v[206:209], v[154:155], off offset:528
	v_lshl_add_u64 v[154:155], v[154:155], 0, s[0:1]
	global_load_dwordx4 v[210:213], v[154:155], off
	global_load_dwordx4 v[214:217], v[154:155], off offset:16
	global_load_dwordx4 v[194:197], v[154:155], off offset:512
	global_load_dwordx4 v[218:221], v[154:155], off offset:528
	v_lshl_add_u64 v[154:155], v[154:155], 0, s[0:1]
	s_waitcnt vmcnt(10)
	v_mul_f32_e32 v166, s56, v166
	v_mul_f32_e32 v167, s56, v167
	v_mul_f32_e32 v164, s56, v164
	v_mul_f32_e32 v165, s56, v165
	v_mul_f32_e32 v170, s56, v170
	v_mul_f32_e32 v171, s56, v171
	v_mul_f32_e32 v168, s56, v168
	v_mul_f32_e32 v169, s56, v169
	v_fma_f32 v144, v144, v136, v166
	v_fma_f32 v145, v145, v137, v167
	v_fma_f32 v142, v142, v134, v164
	v_fma_f32 v143, v143, v135, v165
	v_fma_f32 v140, v140, v132, v170
	v_fma_f32 v141, v141, v133, v171
	v_fma_f32 v138, v138, v130, v168
	v_fma_f32 v139, v139, v131, v169
	v_cvt_pk_bf16_f32 v164, v142, v143
	v_cvt_pk_bf16_f32 v165, v144, v145
	v_cvt_pk_bf16_f32 v166, v138, v139
	v_cvt_pk_bf16_f32 v167, v140, v141
	global_store_dwordx4 v[156:157], v[164:167], off
	s_nop 0
	global_load_dwordx4 v[164:167], v[154:155], off
	global_load_dwordx4 v[168:171], v[154:155], off offset:16
	s_waitcnt vmcnt(11)
	v_mul_f32_e32 v174, s56, v174
	v_mul_f32_e32 v175, s56, v175
	v_mul_f32_e32 v172, s56, v172
	v_mul_f32_e32 v173, s56, v173
	v_mul_f32_e32 v178, s56, v178
	v_mul_f32_e32 v179, s56, v179
	v_mul_f32_e32 v176, s56, v176
	v_mul_f32_e32 v177, s56, v177
	v_fma_f32 v120, v120, v128, v174
	v_fma_f32 v121, v121, v129, v175
	v_fma_f32 v118, v118, v126, v172
	v_fma_f32 v119, v119, v127, v173
	v_fma_f32 v116, v116, v124, v178
	v_fma_f32 v117, v117, v125, v179
	v_fma_f32 v114, v114, v122, v176
	v_fma_f32 v115, v115, v123, v177
	v_cvt_pk_bf16_f32 v172, v118, v119
	v_cvt_pk_bf16_f32 v173, v120, v121
	v_cvt_pk_bf16_f32 v174, v114, v115
	v_cvt_pk_bf16_f32 v175, v116, v117
	global_store_dwordx4 v[156:157], v[172:175], off offset:256
	s_mov_b32 s0, 0x8000
	v_lshl_add_u64 v[156:157], v[156:157], 0, s[0:1]
	global_load_dwordx4 v[172:175], v[154:155], off offset:512
	global_load_dwordx4 v[176:179], v[154:155], off offset:528
	s_mov_b32 s0, 0x50000
	v_lshl_add_u64 v[154:155], v[154:155], 0, s[0:1]
	s_waitcnt vmcnt(12)
	v_mul_f32_e32 v182, s56, v182
	v_mul_f32_e32 v183, s56, v183
	v_mul_f32_e32 v180, s56, v180
	v_mul_f32_e32 v181, s56, v181
	v_mul_f32_e32 v186, s56, v186
	v_mul_f32_e32 v187, s56, v187
	v_mul_f32_e32 v184, s56, v184
	v_mul_f32_e32 v185, s56, v185
	v_fma_f32 v112, v112, v136, v182
	v_fma_f32 v113, v113, v137, v183
	v_fma_f32 v110, v110, v134, v180
	v_fma_f32 v111, v111, v135, v181
	v_fma_f32 v108, v108, v132, v186
	v_fma_f32 v109, v109, v133, v187
	v_fma_f32 v106, v106, v130, v184
	v_fma_f32 v107, v107, v131, v185
	v_cvt_pk_bf16_f32 v180, v110, v111
	v_cvt_pk_bf16_f32 v181, v112, v113
	v_cvt_pk_bf16_f32 v182, v106, v107
	v_cvt_pk_bf16_f32 v183, v108, v109
	global_store_dwordx4 v[156:157], v[180:183], off
	s_nop 0
	global_load_dwordx4 v[180:183], v[154:155], off
	global_load_dwordx4 v[184:187], v[154:155], off offset:16
	s_waitcnt vmcnt(13)
	v_mul_f32_e32 v204, s56, v204
	v_mul_f32_e32 v205, s56, v205
	v_mul_f32_e32 v202, s56, v202
	v_mul_f32_e32 v203, s56, v203
	v_mul_f32_e32 v208, s56, v208
	v_mul_f32_e32 v209, s56, v209
	v_mul_f32_e32 v206, s56, v206
	v_mul_f32_e32 v207, s56, v207
	v_fma_f32 v104, v104, v128, v204
	v_fma_f32 v105, v105, v129, v205
	v_fma_f32 v102, v102, v126, v202
	v_fma_f32 v103, v103, v127, v203
	v_fma_f32 v100, v100, v124, v208
	v_fma_f32 v101, v101, v125, v209
	v_fma_f32 v98, v98, v122, v206
	v_fma_f32 v99, v99, v123, v207
	v_cvt_pk_bf16_f32 v202, v102, v103
	v_cvt_pk_bf16_f32 v203, v104, v105
	v_cvt_pk_bf16_f32 v204, v98, v99
	v_cvt_pk_bf16_f32 v205, v100, v101
	global_store_dwordx4 v[156:157], v[202:205], off offset:256
	s_mov_b32 s0, 0x8000
	v_lshl_add_u64 v[156:157], v[156:157], 0, s[0:1]
	global_load_dwordx4 v[202:205], v[154:155], off offset:512
	global_load_dwordx4 v[206:209], v[154:155], off offset:528
	s_mov_b32 s0, 0x10000
	v_lshl_add_u64 v[154:155], v[154:155], 0, s[0:1]
	s_waitcnt vmcnt(14)
	v_mul_f32_e32 v212, s56, v212
	v_mul_f32_e32 v213, s56, v213
	v_mul_f32_e32 v210, s56, v210
	v_mul_f32_e32 v211, s56, v211
	v_mul_f32_e32 v216, s56, v216
	v_mul_f32_e32 v217, s56, v217
	v_mul_f32_e32 v214, s56, v214
	v_mul_f32_e32 v215, s56, v215
	v_fma_f32 v96, v96, v136, v212
	v_fma_f32 v97, v97, v137, v213
	v_fma_f32 v94, v94, v134, v210
	v_fma_f32 v95, v95, v135, v211
	v_fma_f32 v92, v92, v132, v216
	v_fma_f32 v93, v93, v133, v217
	v_fma_f32 v90, v90, v130, v214
	v_fma_f32 v91, v91, v131, v215
	v_cvt_pk_bf16_f32 v210, v94, v95
	v_cvt_pk_bf16_f32 v211, v96, v97
	v_cvt_pk_bf16_f32 v212, v90, v91
	v_cvt_pk_bf16_f32 v213, v92, v93
	global_store_dwordx4 v[156:157], v[210:213], off
	s_nop 0
	global_load_dwordx4 v[210:213], v[154:155], off
	global_load_dwordx4 v[214:217], v[154:155], off offset:16
	s_waitcnt vmcnt(15)
	v_mul_f32_e32 v196, s56, v196
	v_mul_f32_e32 v197, s56, v197
	v_mul_f32_e32 v194, s56, v194
	v_mul_f32_e32 v195, s56, v195
	v_mul_f32_e32 v220, s56, v220
	v_mul_f32_e32 v221, s56, v221
	v_mul_f32_e32 v218, s56, v218
	v_mul_f32_e32 v219, s56, v219
	v_fma_f32 v88, v88, v128, v196
	v_fma_f32 v89, v89, v129, v197
	v_fma_f32 v86, v86, v126, v194
	v_fma_f32 v87, v87, v127, v195
	v_fma_f32 v84, v84, v124, v220
	v_fma_f32 v85, v85, v125, v221
	v_fma_f32 v82, v82, v122, v218
	v_fma_f32 v83, v83, v123, v219
	v_cvt_pk_bf16_f32 v194, v86, v87
	v_cvt_pk_bf16_f32 v195, v88, v89
	v_cvt_pk_bf16_f32 v196, v82, v83
	v_cvt_pk_bf16_f32 v197, v84, v85
	global_store_dwordx4 v[156:157], v[194:197], off offset:256
	s_mov_b32 s0, 0x8000
	v_lshl_add_u64 v[156:157], v[156:157], 0, s[0:1]
	global_load_dwordx4 v[194:197], v[154:155], off offset:512
	global_load_dwordx4 v[218:221], v[154:155], off offset:528
	s_mov_b32 s0, 0x10000
	v_lshl_add_u64 v[154:155], v[154:155], 0, s[0:1]
	s_waitcnt vmcnt(15)
	v_mul_f32_e32 v166, s56, v166
	v_mul_f32_e32 v167, s56, v167
	v_mul_f32_e32 v164, s56, v164
	v_mul_f32_e32 v165, s56, v165
	v_mul_f32_e32 v170, s56, v170
	v_mul_f32_e32 v171, s56, v171
	v_mul_f32_e32 v168, s56, v168
	v_mul_f32_e32 v169, s56, v169
	v_fma_f32 v80, v80, v136, v166
	v_fma_f32 v81, v81, v137, v167
	v_fma_f32 v78, v78, v134, v164
	v_fma_f32 v79, v79, v135, v165
	v_fma_f32 v76, v76, v132, v170
	v_fma_f32 v77, v77, v133, v171
	v_fma_f32 v74, v74, v130, v168
	v_fma_f32 v75, v75, v131, v169
	v_cvt_pk_bf16_f32 v164, v78, v79
	v_cvt_pk_bf16_f32 v165, v80, v81
	v_cvt_pk_bf16_f32 v166, v74, v75
	v_cvt_pk_bf16_f32 v167, v76, v77
	global_store_dwordx4 v[156:157], v[164:167], off
	s_nop 0
	global_load_dwordx4 v[164:167], v[154:155], off
	global_load_dwordx4 v[168:171], v[154:155], off offset:16
	s_waitcnt vmcnt(15)
	v_mul_f32_e32 v174, s56, v174
	v_mul_f32_e32 v175, s56, v175
	v_mul_f32_e32 v172, s56, v172
	v_mul_f32_e32 v173, s56, v173
	v_mul_f32_e32 v178, s56, v178
	v_mul_f32_e32 v179, s56, v179
	v_mul_f32_e32 v176, s56, v176
	v_mul_f32_e32 v177, s56, v177
	v_fma_f32 v72, v72, v128, v174
	v_fma_f32 v73, v73, v129, v175
	v_fma_f32 v70, v70, v126, v172
	v_fma_f32 v71, v71, v127, v173
	v_fma_f32 v68, v68, v124, v178
	v_fma_f32 v69, v69, v125, v179
	v_fma_f32 v66, v66, v122, v176
	v_fma_f32 v67, v67, v123, v177
	v_cvt_pk_bf16_f32 v172, v70, v71
	v_cvt_pk_bf16_f32 v173, v72, v73
	v_cvt_pk_bf16_f32 v174, v66, v67
	v_cvt_pk_bf16_f32 v175, v68, v69
	global_store_dwordx4 v[156:157], v[172:175], off offset:256
	s_mov_b32 s0, 0x28000
	v_lshl_add_u64 v[156:157], v[156:157], 0, s[0:1]
	global_load_dwordx4 v[172:175], v[154:155], off offset:512
	global_load_dwordx4 v[176:179], v[154:155], off offset:528
	s_mov_b32 s0, 0x10000
	v_lshl_add_u64 v[154:155], v[154:155], 0, s[0:1]
	s_waitcnt vmcnt(15)
	v_mul_f32_e32 v182, s56, v182
	v_mul_f32_e32 v183, s56, v183
	v_mul_f32_e32 v180, s56, v180
	v_mul_f32_e32 v181, s56, v181
	v_mul_f32_e32 v186, s56, v186
	v_mul_f32_e32 v187, s56, v187
	v_mul_f32_e32 v184, s56, v184
	v_mul_f32_e32 v185, s56, v185
	v_fma_f32 v64, v64, v136, v182
	v_fma_f32 v65, v65, v137, v183
	v_fma_f32 v62, v62, v134, v180
	v_fma_f32 v63, v63, v135, v181
	v_fma_f32 v60, v60, v132, v186
	v_fma_f32 v61, v61, v133, v187
	v_fma_f32 v58, v58, v130, v184
	v_fma_f32 v59, v59, v131, v185
	v_cvt_pk_bf16_f32 v180, v62, v63
	v_cvt_pk_bf16_f32 v181, v64, v65
	v_cvt_pk_bf16_f32 v182, v58, v59
	v_cvt_pk_bf16_f32 v183, v60, v61
	global_store_dwordx4 v[156:157], v[180:183], off
	s_nop 0
	global_load_dwordx4 v[180:183], v[154:155], off
	global_load_dwordx4 v[184:187], v[154:155], off offset:16
	s_waitcnt vmcnt(15)
	v_mul_f32_e32 v204, s56, v204
	v_mul_f32_e32 v205, s56, v205
	v_mul_f32_e32 v202, s56, v202
	v_mul_f32_e32 v203, s56, v203
	v_mul_f32_e32 v208, s56, v208
	v_mul_f32_e32 v209, s56, v209
	v_mul_f32_e32 v206, s56, v206
	v_mul_f32_e32 v207, s56, v207
	v_fma_f32 v56, v56, v128, v204
	v_fma_f32 v57, v57, v129, v205
	v_fma_f32 v54, v54, v126, v202
	v_fma_f32 v55, v55, v127, v203
	v_fma_f32 v52, v52, v124, v208
	v_fma_f32 v53, v53, v125, v209
	v_fma_f32 v50, v50, v122, v206
	v_fma_f32 v51, v51, v123, v207
	v_cvt_pk_bf16_f32 v202, v54, v55
	v_cvt_pk_bf16_f32 v203, v56, v57
	v_cvt_pk_bf16_f32 v204, v50, v51
	v_cvt_pk_bf16_f32 v205, v52, v53
	global_store_dwordx4 v[156:157], v[202:205], off offset:256
	s_mov_b32 s0, 0x8000
	v_lshl_add_u64 v[156:157], v[156:157], 0, s[0:1]
	global_load_dwordx4 v[202:205], v[154:155], off offset:512
	global_load_dwordx4 v[206:209], v[154:155], off offset:528
	s_waitcnt vmcnt(15)
	v_mul_f32_e32 v212, s56, v212
	v_mul_f32_e32 v213, s56, v213
	v_mul_f32_e32 v210, s56, v210
	v_mul_f32_e32 v211, s56, v211
	v_mul_f32_e32 v216, s56, v216
	v_mul_f32_e32 v217, s56, v217
	v_mul_f32_e32 v214, s56, v214
	v_mul_f32_e32 v215, s56, v215
	v_fma_f32 v48, v48, v136, v212
	v_fma_f32 v49, v49, v137, v213
	v_fma_f32 v46, v46, v134, v210
	v_fma_f32 v47, v47, v135, v211
	v_fma_f32 v44, v44, v132, v216
	v_fma_f32 v45, v45, v133, v217
	v_fma_f32 v42, v42, v130, v214
	v_fma_f32 v43, v43, v131, v215
	v_cvt_pk_bf16_f32 v210, v46, v47
	v_cvt_pk_bf16_f32 v211, v48, v49
	v_cvt_pk_bf16_f32 v212, v42, v43
	v_cvt_pk_bf16_f32 v213, v44, v45
	global_store_dwordx4 v[156:157], v[210:213], off
	s_nop 0
	s_waitcnt vmcnt(13)
	v_mul_f32_e32 v196, s56, v196
	v_mul_f32_e32 v197, s56, v197
	v_mul_f32_e32 v194, s56, v194
	v_mul_f32_e32 v195, s56, v195
	v_mul_f32_e32 v220, s56, v220
	v_mul_f32_e32 v221, s56, v221
	v_mul_f32_e32 v218, s56, v218
	v_mul_f32_e32 v219, s56, v219
	v_fma_f32 v40, v40, v128, v196
	v_fma_f32 v41, v41, v129, v197
	v_fma_f32 v38, v38, v126, v194
	v_fma_f32 v39, v39, v127, v195
	v_fma_f32 v36, v36, v124, v220
	v_fma_f32 v37, v37, v125, v221
	v_fma_f32 v34, v34, v122, v218
	v_fma_f32 v35, v35, v123, v219
	v_cvt_pk_bf16_f32 v194, v38, v39
	v_cvt_pk_bf16_f32 v195, v40, v41
	v_cvt_pk_bf16_f32 v196, v34, v35
	v_cvt_pk_bf16_f32 v197, v36, v37
	global_store_dwordx4 v[156:157], v[194:197], off offset:256
	v_lshl_add_u64 v[156:157], v[156:157], 0, s[0:1]
	s_waitcnt vmcnt(11)
	v_mul_f32_e32 v166, s56, v166
	v_mul_f32_e32 v167, s56, v167
	v_mul_f32_e32 v164, s56, v164
	v_mul_f32_e32 v165, s56, v165
	v_mul_f32_e32 v170, s56, v170
	v_mul_f32_e32 v171, s56, v171
	v_mul_f32_e32 v168, s56, v168
	v_mul_f32_e32 v169, s56, v169
	v_fma_f32 v32, v32, v136, v166
	v_fma_f32 v33, v33, v137, v167
	v_fma_f32 v30, v30, v134, v164
	v_fma_f32 v31, v31, v135, v165
	v_fma_f32 v28, v28, v132, v170
	v_fma_f32 v29, v29, v133, v171
	v_fma_f32 v26, v26, v130, v168
	v_fma_f32 v27, v27, v131, v169
	v_cvt_pk_bf16_f32 v164, v30, v31
	v_cvt_pk_bf16_f32 v165, v32, v33
	v_cvt_pk_bf16_f32 v166, v26, v27
	v_cvt_pk_bf16_f32 v167, v28, v29
	global_store_dwordx4 v[156:157], v[164:167], off
	s_nop 0
	s_waitcnt vmcnt(9)
	v_mul_f32_e32 v174, s56, v174
	v_mul_f32_e32 v175, s56, v175
	v_mul_f32_e32 v172, s56, v172
	v_mul_f32_e32 v173, s56, v173
	v_mul_f32_e32 v178, s56, v178
	v_mul_f32_e32 v179, s56, v179
	v_mul_f32_e32 v176, s56, v176
	v_mul_f32_e32 v177, s56, v177
	v_fma_f32 v24, v24, v128, v174
	v_fma_f32 v25, v25, v129, v175
	v_fma_f32 v22, v22, v126, v172
	v_fma_f32 v23, v23, v127, v173
	v_fma_f32 v20, v20, v124, v178
	v_fma_f32 v21, v21, v125, v179
	v_fma_f32 v18, v18, v122, v176
	v_fma_f32 v19, v19, v123, v177
	v_cvt_pk_bf16_f32 v172, v22, v23
	v_cvt_pk_bf16_f32 v173, v24, v25
	v_cvt_pk_bf16_f32 v174, v18, v19
	v_cvt_pk_bf16_f32 v175, v20, v21
	global_store_dwordx4 v[156:157], v[172:175], off offset:256
	v_lshl_add_u64 v[156:157], v[156:157], 0, s[0:1]
	s_waitcnt vmcnt(7)
	v_mul_f32_e32 v182, s56, v182
	v_mul_f32_e32 v183, s56, v183
	v_mul_f32_e32 v180, s56, v180
	v_mul_f32_e32 v181, s56, v181
	v_mul_f32_e32 v186, s56, v186
	v_mul_f32_e32 v187, s56, v187
	v_mul_f32_e32 v184, s56, v184
	v_mul_f32_e32 v185, s56, v185
	v_fma_f32 v16, v16, v136, v182
	v_fma_f32 v17, v17, v137, v183
	v_fma_f32 v14, v14, v134, v180
	v_fma_f32 v15, v15, v135, v181
	v_fma_f32 v12, v12, v132, v186
	v_fma_f32 v13, v13, v133, v187
	v_fma_f32 v10, v10, v130, v184
	v_fma_f32 v11, v11, v131, v185
	v_cvt_pk_bf16_f32 v180, v14, v15
	v_cvt_pk_bf16_f32 v181, v16, v17
	v_cvt_pk_bf16_f32 v182, v10, v11
	v_cvt_pk_bf16_f32 v183, v12, v13
	global_store_dwordx4 v[156:157], v[180:183], off
	s_nop 0
	s_waitcnt vmcnt(5)
	v_mul_f32_e32 v204, s56, v204
	v_mul_f32_e32 v205, s56, v205
	v_mul_f32_e32 v202, s56, v202
	v_mul_f32_e32 v203, s56, v203
	v_mul_f32_e32 v208, s56, v208
	v_mul_f32_e32 v209, s56, v209
	v_mul_f32_e32 v206, s56, v206
	v_mul_f32_e32 v207, s56, v207
	v_fma_f32 v8, v8, v128, v204
	v_fma_f32 v9, v9, v129, v205
	v_fma_f32 v6, v6, v126, v202
	v_fma_f32 v7, v7, v127, v203
	v_fma_f32 v4, v4, v124, v208
	v_fma_f32 v5, v5, v125, v209
	v_fma_f32 v2, v2, v122, v206
	v_fma_f32 v3, v3, v123, v207
	v_cvt_pk_bf16_f32 v202, v6, v7
	v_cvt_pk_bf16_f32 v203, v8, v9
	v_cvt_pk_bf16_f32 v204, v2, v3
	v_cvt_pk_bf16_f32 v205, v4, v5
	global_store_dwordx4 v[156:157], v[202:205], off offset:256
	s_nop 0
	s_and_b64 vcc, exec, s[40:41]
	v_readfirstlane_b32 s98, v191
	s_cmpk_lt_u32 s98, 0x100
	s_cbranch_scc1 .Lrl_e1_794
	s_barrier

.LBB0_828:
	s_lshl_b32 s2, s48, 8
	v_add_u32_e32 v152, s2, v161
	v_ashrrev_i32_e32 v153, 31, v152
	v_lshlrev_b64 v[162:163], 11, v[152:153]
	v_lshl_add_u64 v[162:163], s[6:7], 0, v[162:163]
	s_lshl_b32 s86, s47, 6
	s_waitcnt vmcnt(0)
	v_add_f32_e32 v164, v128, v132
	v_add_f32_e32 v165, v129, v133
	v_add_f32_e32 v166, v126, v130
	v_add_f32_e32 v167, v127, v131
	v_lshl_add_u64 v[162:163], v[162:163], 0, s[86:87]
	v_lshlrev_b32_e32 v0, 1, v146
	v_cndmask_b32_e64 v153, v129, v165, s[42:43]
	v_cndmask_b32_e64 v165, v128, v164, s[42:43]
	v_cndmask_b32_e64 v164, v127, v167, s[42:43]
	v_cndmask_b32_e64 v166, v126, v166, s[42:43]
	v_lshl_add_u64 v[162:163], v[162:163], 0, v[0:1]
	v_cvt_pk_bf16_f32 v164, v166, v164
	v_cvt_pk_bf16_f32 v165, v165, v153
	global_store_dwordx2 v[162:163], v[164:165], off
	v_add_f32_e32 v164, v124, v136
	v_add_f32_e32 v165, v125, v137
	v_add_f32_e32 v166, v122, v134
	v_add_f32_e32 v167, v123, v135
	v_cndmask_b32_e64 v153, v125, v165, s[42:43]
	v_cndmask_b32_e64 v165, v124, v164, s[42:43]
	v_cndmask_b32_e64 v164, v123, v167, s[42:43]
	v_cndmask_b32_e64 v166, v122, v166, s[42:43]
	v_cvt_pk_bf16_f32 v164, v166, v164
	v_cvt_pk_bf16_f32 v165, v165, v153
	global_store_dwordx2 v[162:163], v[164:165], off offset:32
	v_add_f32_e32 v164, v96, v140
	v_add_f32_e32 v165, v97, v141
	v_add_f32_e32 v166, v94, v138
	v_add_f32_e32 v167, v95, v139
	v_cndmask_b32_e64 v153, v97, v165, s[42:43]
	v_cndmask_b32_e64 v165, v96, v164, s[42:43]
	v_cndmask_b32_e64 v164, v95, v167, s[42:43]
	v_cndmask_b32_e64 v166, v94, v166, s[42:43]
	v_cvt_pk_bf16_f32 v164, v166, v164
	v_cvt_pk_bf16_f32 v165, v165, v153
	global_store_dwordx2 v[162:163], v[164:165], off offset:256
	v_add_f32_e32 v164, v92, v144
	v_add_f32_e32 v165, v93, v145
	v_add_f32_e32 v166, v90, v142
	v_add_f32_e32 v167, v91, v143
	v_cndmask_b32_e64 v153, v93, v165, s[42:43]
	v_cndmask_b32_e64 v165, v92, v164, s[42:43]
	v_cndmask_b32_e64 v164, v91, v167, s[42:43]
	v_cndmask_b32_e64 v166, v90, v166, s[42:43]
	v_cvt_pk_bf16_f32 v164, v166, v164
	v_cvt_pk_bf16_f32 v165, v165, v153
	s_and_b64 vcc, exec, s[44:45]
	global_store_dwordx2 v[162:163], v[164:165], off offset:288
	s_cbranch_vccnz .LBB0_830
	v_add_co_u32_e32 v130, vcc, 0x4000, v150
	s_nop 1
	v_addc_co_u32_e32 v131, vcc, 0, v151, vcc
	v_add_co_u32_e32 v134, vcc, 0x6000, v150
	s_nop 1
	v_addc_co_u32_e32 v135, vcc, 0, v151, vcc
	v_add_co_u32_e32 v138, vcc, 0x14000, v150
	global_load_dwordx4 v[130:133], v[130:131], off
	s_nop 0
	global_load_dwordx4 v[134:137], v[134:135], off
	v_addc_co_u32_e32 v139, vcc, 0, v151, vcc
	v_add_co_u32_e32 v142, vcc, 0x16000, v150
	s_nop 1
	v_addc_co_u32_e32 v143, vcc, 0, v151, vcc
	global_load_dwordx4 v[138:141], v[138:139], off
	s_nop 0
	global_load_dwordx4 v[142:145], v[142:143], off
.LBB0_830:
	v_add3_u32 v162, v161, s2, 16
	v_ashrrev_i32_e32 v163, 31, v162
	s_lshl_b32 s0, s47, 5
	v_lshlrev_b64 v[162:163], 11, v[162:163]
	v_lshl_add_u64 v[162:163], s[6:7], 0, v[162:163]
	s_lshl_b32 s86, s0, 1
	s_waitcnt vmcnt(0)
	v_add_f32_e32 v164, v120, v132
	v_add_f32_e32 v165, v121, v133
	v_add_f32_e32 v166, v118, v130
	v_add_f32_e32 v167, v119, v131
	v_lshl_add_u64 v[162:163], v[162:163], 0, s[86:87]
	v_cndmask_b32_e64 v153, v121, v165, s[42:43]
	v_cndmask_b32_e64 v165, v120, v164, s[42:43]
	v_cndmask_b32_e64 v164, v119, v167, s[42:43]
	v_cndmask_b32_e64 v166, v118, v166, s[42:43]
	v_lshl_add_u64 v[162:163], v[162:163], 0, v[0:1]
	v_cvt_pk_bf16_f32 v164, v166, v164
	v_cvt_pk_bf16_f32 v165, v165, v153
	global_store_dwordx2 v[162:163], v[164:165], off
	v_add_f32_e32 v164, v116, v136
	v_add_f32_e32 v165, v117, v137
	v_add_f32_e32 v166, v114, v134
	v_add_f32_e32 v167, v115, v135
	v_cndmask_b32_e64 v153, v117, v165, s[42:43]
	v_cndmask_b32_e64 v165, v116, v164, s[42:43]
	v_cndmask_b32_e64 v164, v115, v167, s[42:43]
	v_cndmask_b32_e64 v166, v114, v166, s[42:43]
	v_cvt_pk_bf16_f32 v164, v166, v164
	v_cvt_pk_bf16_f32 v165, v165, v153
	global_store_dwordx2 v[162:163], v[164:165], off offset:32
	v_add_f32_e32 v164, v88, v140
	v_add_f32_e32 v165, v89, v141
	v_add_f32_e32 v166, v86, v138
	v_add_f32_e32 v167, v87, v139
	v_cndmask_b32_e64 v153, v89, v165, s[42:43]
	v_cndmask_b32_e64 v165, v88, v164, s[42:43]
	v_cndmask_b32_e64 v164, v87, v167, s[42:43]
	v_cndmask_b32_e64 v166, v86, v166, s[42:43]
	v_cvt_pk_bf16_f32 v164, v166, v164
	v_cvt_pk_bf16_f32 v165, v165, v153
	global_store_dwordx2 v[162:163], v[164:165], off offset:256
	v_add_f32_e32 v164, v84, v144
	v_add_f32_e32 v165, v85, v145
	v_add_f32_e32 v166, v82, v142
	v_add_f32_e32 v167, v83, v143
	v_cndmask_b32_e64 v153, v85, v165, s[42:43]
	v_cndmask_b32_e64 v165, v84, v164, s[42:43]
	v_cndmask_b32_e64 v164, v83, v167, s[42:43]
	v_cndmask_b32_e64 v166, v82, v166, s[42:43]
	v_cvt_pk_bf16_f32 v164, v166, v164
	v_cvt_pk_bf16_f32 v165, v165, v153
	s_and_b64 vcc, exec, s[44:45]
	global_store_dwordx2 v[162:163], v[164:165], off offset:288
	s_cbranch_vccnz .LBB0_832
	v_add_co_u32_e32 v130, vcc, 0x8000, v150
	s_nop 1
	v_addc_co_u32_e32 v131, vcc, 0, v151, vcc
	v_add_co_u32_e32 v134, vcc, 0xa000, v150
	s_nop 1
	v_addc_co_u32_e32 v135, vcc, 0, v151, vcc
	v_add_co_u32_e32 v138, vcc, 0x18000, v150
	global_load_dwordx4 v[130:133], v[130:131], off
	s_nop 0
	global_load_dwordx4 v[134:137], v[134:135], off
	v_addc_co_u32_e32 v139, vcc, 0, v151, vcc
	v_add_co_u32_e32 v142, vcc, 0x1a000, v150
	s_nop 1
	v_addc_co_u32_e32 v143, vcc, 0, v151, vcc
	global_load_dwordx4 v[138:141], v[138:139], off
	s_nop 0
	global_load_dwordx4 v[142:145], v[142:143], off
.LBB0_832:
	v_add3_u32 v162, v161, s2, 32
	v_ashrrev_i32_e32 v163, 31, v162
	v_lshlrev_b64 v[162:163], 11, v[162:163]
	v_lshl_add_u64 v[162:163], s[6:7], 0, v[162:163]
	s_waitcnt vmcnt(0)
	v_add_f32_e32 v164, v112, v132
	v_add_f32_e32 v165, v113, v133
	v_add_f32_e32 v166, v110, v130
	v_add_f32_e32 v167, v111, v131
	v_lshl_add_u64 v[162:163], v[162:163], 0, s[86:87]
	v_cndmask_b32_e64 v153, v113, v165, s[42:43]
	v_cndmask_b32_e64 v165, v112, v164, s[42:43]
	v_cndmask_b32_e64 v164, v111, v167, s[42:43]
	v_cndmask_b32_e64 v166, v110, v166, s[42:43]
	v_lshl_add_u64 v[162:163], v[162:163], 0, v[0:1]
	v_cvt_pk_bf16_f32 v164, v166, v164
	v_cvt_pk_bf16_f32 v165, v165, v153
	global_store_dwordx2 v[162:163], v[164:165], off
	v_add_f32_e32 v164, v108, v136
	v_add_f32_e32 v165, v109, v137
	v_add_f32_e32 v166, v106, v134
	v_add_f32_e32 v167, v107, v135
	v_cndmask_b32_e64 v153, v109, v165, s[42:43]
	v_cndmask_b32_e64 v165, v108, v164, s[42:43]
	v_cndmask_b32_e64 v164, v107, v167, s[42:43]
	v_cndmask_b32_e64 v166, v106, v166, s[42:43]
	v_cvt_pk_bf16_f32 v164, v166, v164
	v_cvt_pk_bf16_f32 v165, v165, v153
	global_store_dwordx2 v[162:163], v[164:165], off offset:32
	v_add_f32_e32 v164, v80, v140
	v_add_f32_e32 v165, v81, v141
	v_add_f32_e32 v166, v78, v138
	v_add_f32_e32 v167, v79, v139
	v_cndmask_b32_e64 v153, v81, v165, s[42:43]
	v_cndmask_b32_e64 v165, v80, v164, s[42:43]
	v_cndmask_b32_e64 v164, v79, v167, s[42:43]
	v_cndmask_b32_e64 v166, v78, v166, s[42:43]
	v_cvt_pk_bf16_f32 v164, v166, v164
	v_cvt_pk_bf16_f32 v165, v165, v153
	global_store_dwordx2 v[162:163], v[164:165], off offset:256
	v_add_f32_e32 v164, v76, v144
	v_add_f32_e32 v165, v77, v145
	v_add_f32_e32 v166, v74, v142
	v_add_f32_e32 v167, v75, v143
	v_cndmask_b32_e64 v153, v77, v165, s[42:43]
	v_cndmask_b32_e64 v165, v76, v164, s[42:43]
	v_cndmask_b32_e64 v164, v75, v167, s[42:43]
	v_cndmask_b32_e64 v166, v74, v166, s[42:43]
	v_cvt_pk_bf16_f32 v164, v166, v164
	v_cvt_pk_bf16_f32 v165, v165, v153
	s_and_b64 vcc, exec, s[44:45]
	global_store_dwordx2 v[162:163], v[164:165], off offset:288
	s_cbranch_vccnz .LBB0_834
	v_add_co_u32_e32 v130, vcc, 0xc000, v150
	s_nop 1
	v_addc_co_u32_e32 v131, vcc, 0, v151, vcc
	v_add_co_u32_e32 v134, vcc, 0xe000, v150
	s_nop 1
	v_addc_co_u32_e32 v135, vcc, 0, v151, vcc
	v_add_co_u32_e32 v138, vcc, 0x1c000, v150
	global_load_dwordx4 v[130:133], v[130:131], off
	s_nop 0
	global_load_dwordx4 v[134:137], v[134:135], off
	v_addc_co_u32_e32 v139, vcc, 0, v151, vcc
	v_add_co_u32_e32 v142, vcc, 0x1e000, v150
	s_nop 1
	v_addc_co_u32_e32 v143, vcc, 0, v151, vcc
	global_load_dwordx4 v[138:141], v[138:139], off
	s_nop 0
	global_load_dwordx4 v[142:145], v[142:143], off
.LBB0_834:
	v_add3_u32 v162, v161, s2, 48
	v_ashrrev_i32_e32 v163, 31, v162
	v_lshlrev_b64 v[162:163], 11, v[162:163]
	v_lshl_add_u64 v[162:163], s[6:7], 0, v[162:163]
	s_waitcnt vmcnt(0)
	v_add_f32_e32 v164, v104, v132
	v_add_f32_e32 v165, v105, v133
	v_add_f32_e32 v166, v102, v130
	v_add_f32_e32 v167, v103, v131
	v_lshl_add_u64 v[162:163], v[162:163], 0, s[86:87]
	v_cndmask_b32_e64 v153, v105, v165, s[42:43]
	v_cndmask_b32_e64 v161, v104, v164, s[42:43]
	v_cndmask_b32_e64 v164, v103, v167, s[42:43]
	v_cndmask_b32_e64 v165, v102, v166, s[42:43]
	v_lshl_add_u64 v[162:163], v[162:163], 0, v[0:1]
	v_cvt_pk_bf16_f32 v164, v165, v164
	v_cvt_pk_bf16_f32 v165, v161, v153
	global_store_dwordx2 v[162:163], v[164:165], off
	v_add_f32_e32 v164, v100, v136
	v_add_f32_e32 v165, v101, v137
	v_add_f32_e32 v166, v98, v134
	v_add_f32_e32 v167, v99, v135
	v_cndmask_b32_e64 v153, v101, v165, s[42:43]
	v_cndmask_b32_e64 v161, v100, v164, s[42:43]
	v_cndmask_b32_e64 v164, v99, v167, s[42:43]
	v_cndmask_b32_e64 v165, v98, v166, s[42:43]
	v_cvt_pk_bf16_f32 v164, v165, v164
	v_cvt_pk_bf16_f32 v165, v161, v153
	global_store_dwordx2 v[162:163], v[164:165], off offset:32
	v_add_f32_e32 v164, v72, v140
	v_add_f32_e32 v165, v73, v141
	v_add_f32_e32 v166, v70, v138
	v_add_f32_e32 v167, v71, v139
	v_cndmask_b32_e64 v153, v73, v165, s[42:43]
	v_cndmask_b32_e64 v161, v72, v164, s[42:43]
	v_cndmask_b32_e64 v164, v71, v167, s[42:43]
	v_cndmask_b32_e64 v165, v70, v166, s[42:43]
	v_cvt_pk_bf16_f32 v164, v165, v164
	v_cvt_pk_bf16_f32 v165, v161, v153
	global_store_dwordx2 v[162:163], v[164:165], off offset:256
	v_add_f32_e32 v164, v68, v144
	v_add_f32_e32 v165, v69, v145
	v_add_f32_e32 v166, v66, v142
	v_add_f32_e32 v167, v67, v143
	v_cndmask_b32_e64 v153, v69, v165, s[42:43]
	v_cndmask_b32_e64 v161, v68, v164, s[42:43]
	v_cndmask_b32_e64 v164, v67, v167, s[42:43]
	v_cndmask_b32_e64 v165, v66, v166, s[42:43]
	v_cvt_pk_bf16_f32 v164, v165, v164
	v_cvt_pk_bf16_f32 v165, v161, v153
	s_and_b64 vcc, exec, s[44:45]
	global_store_dwordx2 v[162:163], v[164:165], off offset:288
	s_cbranch_vccnz .LBB0_836
	v_add_co_u32_e32 v130, vcc, 0x20000, v150
	s_nop 1
	v_addc_co_u32_e32 v131, vcc, 0, v151, vcc
	v_add_co_u32_e32 v134, vcc, 0x22000, v150
	s_nop 1
	v_addc_co_u32_e32 v135, vcc, 0, v151, vcc
	v_add_co_u32_e32 v138, vcc, 0x30000, v150
	global_load_dwordx4 v[130:133], v[130:131], off
	s_nop 0
	global_load_dwordx4 v[134:137], v[134:135], off
	v_addc_co_u32_e32 v139, vcc, 0, v151, vcc
	v_add_co_u32_e32 v142, vcc, 0x32000, v150
	s_nop 1
	v_addc_co_u32_e32 v143, vcc, 0, v151, vcc
	global_load_dwordx4 v[138:141], v[138:139], off
	s_nop 0
	global_load_dwordx4 v[142:145], v[142:143], off
.LBB0_836:
	v_add_u32_e32 v162, 0x80, v152
	v_ashrrev_i32_e32 v163, 31, v162
	v_lshlrev_b64 v[162:163], 11, v[162:163]
	v_lshl_add_u64 v[162:163], s[6:7], 0, v[162:163]
	s_waitcnt vmcnt(0)
	v_add_f32_e32 v164, v64, v132
	v_add_f32_e32 v165, v65, v133
	v_add_f32_e32 v166, v62, v130
	v_add_f32_e32 v167, v63, v131
	v_lshl_add_u64 v[162:163], v[162:163], 0, s[86:87]
	v_cndmask_b32_e64 v153, v65, v165, s[42:43]
	v_cndmask_b32_e64 v161, v64, v164, s[42:43]
	v_cndmask_b32_e64 v164, v63, v167, s[42:43]
	v_cndmask_b32_e64 v165, v62, v166, s[42:43]
	v_lshl_add_u64 v[162:163], v[162:163], 0, v[0:1]
	v_cvt_pk_bf16_f32 v164, v165, v164
	v_cvt_pk_bf16_f32 v165, v161, v153
	global_store_dwordx2 v[162:163], v[164:165], off
	v_add_f32_e32 v164, v60, v136
	v_add_f32_e32 v165, v61, v137
	v_add_f32_e32 v166, v58, v134
	v_add_f32_e32 v167, v59, v135
	v_cndmask_b32_e64 v153, v61, v165, s[42:43]
	v_cndmask_b32_e64 v161, v60, v164, s[42:43]
	v_cndmask_b32_e64 v164, v59, v167, s[42:43]
	v_cndmask_b32_e64 v165, v58, v166, s[42:43]
	v_cvt_pk_bf16_f32 v164, v165, v164
	v_cvt_pk_bf16_f32 v165, v161, v153
	global_store_dwordx2 v[162:163], v[164:165], off offset:32
	v_add_f32_e32 v164, v32, v140
	v_add_f32_e32 v165, v33, v141
	v_add_f32_e32 v166, v30, v138
	v_add_f32_e32 v167, v31, v139
	v_cndmask_b32_e64 v153, v33, v165, s[42:43]
	v_cndmask_b32_e64 v161, v32, v164, s[42:43]
	v_cndmask_b32_e64 v164, v31, v167, s[42:43]
	v_cndmask_b32_e64 v165, v30, v166, s[42:43]
	v_cvt_pk_bf16_f32 v164, v165, v164
	v_cvt_pk_bf16_f32 v165, v161, v153
	global_store_dwordx2 v[162:163], v[164:165], off offset:256
	v_add_f32_e32 v164, v28, v144
	v_add_f32_e32 v165, v29, v145
	v_add_f32_e32 v166, v26, v142
	v_add_f32_e32 v167, v27, v143
	v_cndmask_b32_e64 v153, v29, v165, s[42:43]
	v_cndmask_b32_e64 v161, v28, v164, s[42:43]
	v_cndmask_b32_e64 v164, v27, v167, s[42:43]
	v_cndmask_b32_e64 v165, v26, v166, s[42:43]
	v_cvt_pk_bf16_f32 v164, v165, v164
	v_cvt_pk_bf16_f32 v165, v161, v153
	s_and_b64 vcc, exec, s[44:45]
	global_store_dwordx2 v[162:163], v[164:165], off offset:288
	s_cbranch_vccnz .LBB0_838
	v_add_co_u32_e32 v130, vcc, 0x24000, v150
	s_nop 1
	v_addc_co_u32_e32 v131, vcc, 0, v151, vcc
	v_add_co_u32_e32 v134, vcc, 0x26000, v150
	s_nop 1
	v_addc_co_u32_e32 v135, vcc, 0, v151, vcc
	v_add_co_u32_e32 v138, vcc, 0x34000, v150
	global_load_dwordx4 v[130:133], v[130:131], off
	s_nop 0
	global_load_dwordx4 v[134:137], v[134:135], off
	v_addc_co_u32_e32 v139, vcc, 0, v151, vcc
	v_add_co_u32_e32 v142, vcc, 0x36000, v150
	s_nop 1
	v_addc_co_u32_e32 v143, vcc, 0, v151, vcc
	global_load_dwordx4 v[138:141], v[138:139], off
	s_nop 0
	global_load_dwordx4 v[142:145], v[142:143], off
.LBB0_838:
	v_add_u32_e32 v162, 0x90, v152
	v_ashrrev_i32_e32 v163, 31, v162
	v_lshlrev_b64 v[162:163], 11, v[162:163]
	v_lshl_add_u64 v[162:163], s[6:7], 0, v[162:163]
	s_waitcnt vmcnt(0)
	v_add_f32_e32 v164, v56, v132
	v_add_f32_e32 v165, v57, v133
	v_add_f32_e32 v166, v54, v130
	v_add_f32_e32 v167, v55, v131
	v_lshl_add_u64 v[162:163], v[162:163], 0, s[86:87]
	v_cndmask_b32_e64 v153, v57, v165, s[42:43]
	v_cndmask_b32_e64 v161, v56, v164, s[42:43]
	v_cndmask_b32_e64 v164, v55, v167, s[42:43]
	v_cndmask_b32_e64 v165, v54, v166, s[42:43]
	v_lshl_add_u64 v[162:163], v[162:163], 0, v[0:1]
	v_cvt_pk_bf16_f32 v164, v165, v164
	v_cvt_pk_bf16_f32 v165, v161, v153
	global_store_dwordx2 v[162:163], v[164:165], off
	v_add_f32_e32 v164, v52, v136
	v_add_f32_e32 v165, v53, v137
	v_add_f32_e32 v166, v50, v134
	v_add_f32_e32 v167, v51, v135
	v_cndmask_b32_e64 v153, v53, v165, s[42:43]
	v_cndmask_b32_e64 v161, v52, v164, s[42:43]
	v_cndmask_b32_e64 v164, v51, v167, s[42:43]
	v_cndmask_b32_e64 v165, v50, v166, s[42:43]
	v_cvt_pk_bf16_f32 v164, v165, v164
	v_cvt_pk_bf16_f32 v165, v161, v153
	global_store_dwordx2 v[162:163], v[164:165], off offset:32
	v_add_f32_e32 v164, v24, v140
	v_add_f32_e32 v165, v25, v141
	v_add_f32_e32 v166, v22, v138
	v_add_f32_e32 v167, v23, v139
	v_cndmask_b32_e64 v153, v25, v165, s[42:43]
	v_cndmask_b32_e64 v161, v24, v164, s[42:43]
	v_cndmask_b32_e64 v164, v23, v167, s[42:43]
	v_cndmask_b32_e64 v165, v22, v166, s[42:43]
	v_cvt_pk_bf16_f32 v164, v165, v164
	v_cvt_pk_bf16_f32 v165, v161, v153
	global_store_dwordx2 v[162:163], v[164:165], off offset:256
	v_add_f32_e32 v164, v20, v144
	v_add_f32_e32 v165, v21, v145
	v_add_f32_e32 v166, v18, v142
	v_add_f32_e32 v167, v19, v143
	v_cndmask_b32_e64 v153, v21, v165, s[42:43]
	v_cndmask_b32_e64 v161, v20, v164, s[42:43]
	v_cndmask_b32_e64 v164, v19, v167, s[42:43]
	v_cndmask_b32_e64 v165, v18, v166, s[42:43]
	v_cvt_pk_bf16_f32 v164, v165, v164
	v_cvt_pk_bf16_f32 v165, v161, v153
	s_and_b64 vcc, exec, s[44:45]
	global_store_dwordx2 v[162:163], v[164:165], off offset:288
	s_cbranch_vccnz .LBB0_840
	v_add_co_u32_e32 v130, vcc, 0x28000, v150
	s_nop 1
	v_addc_co_u32_e32 v131, vcc, 0, v151, vcc
	v_add_co_u32_e32 v134, vcc, 0x2a000, v150
	s_nop 1
	v_addc_co_u32_e32 v135, vcc, 0, v151, vcc
	v_add_co_u32_e32 v138, vcc, 0x38000, v150
	global_load_dwordx4 v[130:133], v[130:131], off
	s_nop 0
	global_load_dwordx4 v[134:137], v[134:135], off
	v_addc_co_u32_e32 v139, vcc, 0, v151, vcc
	v_add_co_u32_e32 v142, vcc, 0x3a000, v150
	s_nop 1
	v_addc_co_u32_e32 v143, vcc, 0, v151, vcc
	global_load_dwordx4 v[138:141], v[138:139], off
	s_nop 0
	global_load_dwordx4 v[142:145], v[142:143], off
.LBB0_840:
	v_add_u32_e32 v162, 0xa0, v152
	v_ashrrev_i32_e32 v163, 31, v162
	v_lshlrev_b64 v[162:163], 11, v[162:163]
	v_lshl_add_u64 v[162:163], s[6:7], 0, v[162:163]
	s_waitcnt vmcnt(0)
	v_add_f32_e32 v164, v48, v132
	v_add_f32_e32 v165, v49, v133
	v_add_f32_e32 v166, v46, v130
	v_add_f32_e32 v167, v47, v131
	v_lshl_add_u64 v[162:163], v[162:163], 0, s[86:87]
	v_cndmask_b32_e64 v153, v49, v165, s[42:43]
	v_cndmask_b32_e64 v161, v48, v164, s[42:43]
	v_cndmask_b32_e64 v164, v47, v167, s[42:43]
	v_cndmask_b32_e64 v165, v46, v166, s[42:43]
	v_lshl_add_u64 v[162:163], v[162:163], 0, v[0:1]
	v_cvt_pk_bf16_f32 v164, v165, v164
	v_cvt_pk_bf16_f32 v165, v161, v153
	global_store_dwordx2 v[162:163], v[164:165], off
	v_add_f32_e32 v164, v44, v136
	v_add_f32_e32 v165, v45, v137
	v_add_f32_e32 v166, v42, v134
	v_add_f32_e32 v167, v43, v135
	v_cndmask_b32_e64 v153, v45, v165, s[42:43]
	v_cndmask_b32_e64 v161, v44, v164, s[42:43]
	v_cndmask_b32_e64 v164, v43, v167, s[42:43]
	v_cndmask_b32_e64 v165, v42, v166, s[42:43]
	v_cvt_pk_bf16_f32 v164, v165, v164
	v_cvt_pk_bf16_f32 v165, v161, v153
	global_store_dwordx2 v[162:163], v[164:165], off offset:32
	v_add_f32_e32 v164, v16, v140
	v_add_f32_e32 v165, v17, v141
	v_add_f32_e32 v166, v14, v138
	v_add_f32_e32 v167, v15, v139
	v_cndmask_b32_e64 v153, v17, v165, s[42:43]
	v_cndmask_b32_e64 v161, v16, v164, s[42:43]
	v_cndmask_b32_e64 v164, v15, v167, s[42:43]
	v_cndmask_b32_e64 v165, v14, v166, s[42:43]
	v_cvt_pk_bf16_f32 v164, v165, v164
	v_cvt_pk_bf16_f32 v165, v161, v153
	global_store_dwordx2 v[162:163], v[164:165], off offset:256
	v_add_f32_e32 v164, v12, v144
	v_add_f32_e32 v165, v13, v145
	v_add_f32_e32 v166, v10, v142
	v_add_f32_e32 v167, v11, v143
	v_cndmask_b32_e64 v153, v13, v165, s[42:43]
	v_cndmask_b32_e64 v161, v12, v164, s[42:43]
	v_cndmask_b32_e64 v164, v11, v167, s[42:43]
	v_cndmask_b32_e64 v165, v10, v166, s[42:43]
	v_cvt_pk_bf16_f32 v164, v165, v164
	v_cvt_pk_bf16_f32 v165, v161, v153
	s_and_b64 vcc, exec, s[44:45]
	global_store_dwordx2 v[162:163], v[164:165], off offset:288
	s_cbranch_vccnz .LBB0_842
	v_add_co_u32_e32 v130, vcc, 0x2c000, v150
	s_nop 1
	v_addc_co_u32_e32 v131, vcc, 0, v151, vcc
	v_add_co_u32_e32 v134, vcc, 0x2e000, v150
	s_nop 1
	v_addc_co_u32_e32 v135, vcc, 0, v151, vcc
	v_add_co_u32_e32 v138, vcc, 0x3c000, v150
	global_load_dwordx4 v[130:133], v[130:131], off
	s_nop 0
	global_load_dwordx4 v[134:137], v[134:135], off
	v_addc_co_u32_e32 v139, vcc, 0, v151, vcc
	v_add_co_u32_e32 v142, vcc, 0x3e000, v150
	s_nop 1
	v_addc_co_u32_e32 v143, vcc, 0, v151, vcc
	global_load_dwordx4 v[138:141], v[138:139], off
	s_nop 0
	global_load_dwordx4 v[142:145], v[142:143], off
.LBB0_842:
	v_add_u32_e32 v150, 0xb0, v152
	v_ashrrev_i32_e32 v151, 31, v150
	v_lshlrev_b64 v[150:151], 11, v[150:151]
	v_lshl_add_u64 v[150:151], s[6:7], 0, v[150:151]
	v_lshl_add_u64 v[150:151], v[150:151], 0, s[86:87]
	s_waitcnt vmcnt(0)
	v_add_f32_e32 v132, v40, v132
	v_add_f32_e32 v133, v41, v133
	v_add_f32_e32 v130, v38, v130
	v_add_f32_e32 v131, v39, v131
	v_lshl_add_u64 v[150:151], v[150:151], 0, v[0:1]
	v_cndmask_b32_e64 v0, v41, v133, s[42:43]
	v_cndmask_b32_e64 v132, v40, v132, s[42:43]
	v_cndmask_b32_e64 v131, v39, v131, s[42:43]
	v_cndmask_b32_e64 v130, v38, v130, s[42:43]
	v_cvt_pk_bf16_f32 v130, v130, v131
	v_cvt_pk_bf16_f32 v131, v132, v0
	global_store_dwordx2 v[150:151], v[130:131], off
	v_add_f32_e32 v130, v36, v136
	v_add_f32_e32 v131, v37, v137
	v_add_f32_e32 v132, v34, v134
	v_add_f32_e32 v133, v35, v135
	v_cndmask_b32_e64 v0, v37, v131, s[42:43]
	v_cndmask_b32_e64 v131, v36, v130, s[42:43]
	v_cndmask_b32_e64 v130, v35, v133, s[42:43]
	v_cndmask_b32_e64 v132, v34, v132, s[42:43]
	v_cvt_pk_bf16_f32 v130, v132, v130
	v_cvt_pk_bf16_f32 v131, v131, v0
	global_store_dwordx2 v[150:151], v[130:131], off offset:32
	v_add_f32_e32 v130, v8, v140
	v_add_f32_e32 v131, v9, v141
	v_add_f32_e32 v132, v6, v138
	v_add_f32_e32 v133, v7, v139
	v_cndmask_b32_e64 v0, v9, v131, s[42:43]
	v_cndmask_b32_e64 v131, v8, v130, s[42:43]
	v_cndmask_b32_e64 v130, v7, v133, s[42:43]
	v_cndmask_b32_e64 v132, v6, v132, s[42:43]
	v_cvt_pk_bf16_f32 v130, v132, v130
	v_cvt_pk_bf16_f32 v131, v131, v0
	global_store_dwordx2 v[150:151], v[130:131], off offset:256
	v_add_f32_e32 v130, v4, v144
	v_add_f32_e32 v131, v5, v145
	v_add_f32_e32 v132, v2, v142
	v_add_f32_e32 v133, v3, v143
	v_cndmask_b32_e64 v0, v5, v131, s[42:43]
	v_cndmask_b32_e64 v131, v4, v130, s[42:43]
	v_cndmask_b32_e64 v130, v3, v133, s[42:43]
	v_cndmask_b32_e64 v132, v2, v132, s[42:43]
	v_cvt_pk_bf16_f32 v130, v132, v130
	v_cvt_pk_bf16_f32 v131, v131, v0
	s_mov_b64 s[16:17], 0
	global_store_dwordx2 v[150:151], v[130:131], off offset:288

.LBB0_869:
	s_or_b64 exec, exec, s[46:47]
	v_lshl_add_u64 v[12:13], v[12:13], 1, s[6:7]
	v_lshlrev_b64 v[50:51], 2, v[32:33]
	v_lshl_add_u64 v[12:13], v[2:3], 1, v[12:13]
	v_lshl_add_u64 v[58:59], s[14:15], 0, v[50:51]
	v_lshl_add_u64 v[62:63], s[20:21], 0, v[50:51]
	v_lshl_add_u64 v[50:51], s[16:17], 0, v[50:51]
	global_load_dwordx2 v[12:13], v[12:13], off
	s_nop 0
	global_load_dwordx4 v[54:57], v[58:59], off
	s_nop 0
	global_load_dwordx4 v[58:61], v[58:59], off offset:3072
	v_ashrrev_i32_e32 v41, 31, v40
	global_load_dwordx4 v[66:69], v[50:51], off
	s_waitcnt vmcnt(10)
	v_lshlrev_b32_e32 v50, 16, v46
	global_load_dwordx4 v[62:65], v[62:63], off
	v_and_b32_e32 v51, 0xffff0000, v46
	v_lshlrev_b32_e32 v46, 16, v47
	v_and_b32_e32 v47, 0xffff0000, v47
	v_lshlrev_b64 v[40:41], 11, v[40:41]
	v_lshl_add_u64 v[40:41], s[22:23], 0, v[40:41]
	v_lshl_add_u64 v[32:33], v[32:33], 1, v[40:41]
	s_waitcnt vmcnt(1)
	v_fma_f32 v46, v56, v46, v68
	v_fma_f32 v47, v57, v47, v69
	v_fma_f32 v50, v54, v50, v66
	v_fma_f32 v51, v55, v51, v67
	v_lshlrev_b32_e32 v54, 16, v44
	v_and_b32_e32 v55, 0xffff0000, v44
	v_lshlrev_b32_e32 v44, 16, v45
	v_and_b32_e32 v45, 0xffff0000, v45
	v_fma_f32 v44, v60, v44, v46
	v_fma_f32 v45, v61, v45, v47
	v_fma_f32 v46, v58, v54, v50
	v_fma_f32 v47, v59, v55, v51
	v_lshlrev_b32_e32 v50, 16, v42
	v_and_b32_e32 v51, 0xffff0000, v42
	v_lshlrev_b32_e32 v42, 16, v43
	v_and_b32_e32 v43, 0xffff0000, v43
	s_waitcnt vmcnt(0)
	v_fma_f32 v42, v64, v42, v44
	v_fma_f32 v43, v65, v43, v45
	v_fma_f32 v44, v62, v50, v46
	v_fma_f32 v45, v63, v51, v47
	v_lshlrev_b32_e32 v46, 16, v48
	v_and_b32_e32 v47, 0xffff0000, v48
	v_lshlrev_b32_e32 v48, 16, v49
	v_and_b32_e32 v49, 0xffff0000, v49
	v_mul_f32_e32 v42, v42, v48
	v_mul_f32_e32 v43, v43, v49
	v_mul_f32_e32 v44, v44, v46
	v_mul_f32_e32 v45, v45, v47
	s_nop 0
	v_cvt_pk_bf16_f32 v44, v44, v45
	v_cvt_pk_bf16_f32 v45, v42, v43
	global_store_dwordx2 v[32:33], v[44:45], off
	s_and_saveexec_b64 s[44:45], s[42:43]
	s_cbranch_execz .LBB0_872
	v_lshlrev_b64 v[32:33], 2, v[20:21]
	v_lshl_add_u64 v[44:45], s[14:15], 0, v[32:33]
	v_lshl_add_u64 v[48:49], s[20:21], 0, v[32:33]
	v_lshl_add_u64 v[32:33], s[16:17], 0, v[32:33]
	global_load_dwordx4 v[40:43], v[44:45], off
	s_nop 0
	global_load_dwordx4 v[44:47], v[44:45], off offset:3072
	v_ashrrev_i32_e32 v29, 31, v28
	global_load_dwordx4 v[54:57], v[32:33], off
	v_lshlrev_b32_e32 v32, 16, v36
	global_load_dwordx4 v[48:51], v[48:49], off
	v_and_b32_e32 v33, 0xffff0000, v36
	v_lshlrev_b32_e32 v36, 16, v37
	v_and_b32_e32 v37, 0xffff0000, v37
	v_lshlrev_b64 v[28:29], 11, v[28:29]
	v_lshl_add_u64 v[28:29], s[22:23], 0, v[28:29]
	v_lshl_add_u64 v[20:21], v[20:21], 1, v[28:29]
	s_waitcnt vmcnt(1)
	v_fma_f32 v36, v42, v36, v56
	v_fma_f32 v37, v43, v37, v57
	v_fma_f32 v32, v40, v32, v54
	v_fma_f32 v33, v41, v33, v55
	v_lshlrev_b32_e32 v40, 16, v34
	v_and_b32_e32 v41, 0xffff0000, v34
	v_lshlrev_b32_e32 v34, 16, v35
	v_and_b32_e32 v35, 0xffff0000, v35
	v_fma_f32 v34, v46, v34, v36
	v_fma_f32 v35, v47, v35, v37
	v_fma_f32 v32, v44, v40, v32
	v_fma_f32 v33, v45, v41, v33
	v_lshlrev_b32_e32 v36, 16, v30
	v_and_b32_e32 v37, 0xffff0000, v30
	v_lshlrev_b32_e32 v30, 16, v31
	v_and_b32_e32 v31, 0xffff0000, v31
	s_waitcnt vmcnt(0)
	v_fma_f32 v30, v50, v30, v34
	v_fma_f32 v31, v51, v31, v35
	v_fma_f32 v32, v48, v36, v32
	v_fma_f32 v33, v49, v37, v33
	v_lshlrev_b32_e32 v34, 16, v38
	v_and_b32_e32 v35, 0xffff0000, v38
	v_lshlrev_b32_e32 v36, 16, v39
	v_and_b32_e32 v37, 0xffff0000, v39
	v_mul_f32_e32 v30, v30, v36
	v_mul_f32_e32 v31, v31, v37
	v_mul_f32_e32 v32, v32, v34
	v_mul_f32_e32 v33, v33, v35
	s_nop 0
	v_cvt_pk_bf16_f32 v32, v32, v33
	v_cvt_pk_bf16_f32 v33, v30, v31
	global_store_dwordx2 v[20:21], v[32:33], off
	s_or_b64 exec, exec, s[44:45]
	s_and_saveexec_b64 s[42:43], s[40:41]
	s_cbranch_execnz .LBB0_873

.LBB0_873:
	v_lshlrev_b64 v[20:21], 2, v[8:9]
	v_lshl_add_u64 v[32:33], s[14:15], 0, v[20:21]
	v_lshl_add_u64 v[36:37], s[20:21], 0, v[20:21]
	v_lshl_add_u64 v[20:21], s[16:17], 0, v[20:21]
	global_load_dwordx4 v[28:31], v[32:33], off
	s_nop 0
	global_load_dwordx4 v[32:35], v[32:33], off offset:3072
	v_ashrrev_i32_e32 v17, 31, v16
	global_load_dwordx4 v[40:43], v[20:21], off
	v_lshlrev_b32_e32 v20, 16, v24
	global_load_dwordx4 v[36:39], v[36:37], off
	v_and_b32_e32 v21, 0xffff0000, v24
	v_lshlrev_b32_e32 v24, 16, v25
	v_and_b32_e32 v25, 0xffff0000, v25
	v_lshlrev_b64 v[16:17], 11, v[16:17]
	v_lshl_add_u64 v[16:17], s[22:23], 0, v[16:17]
	v_lshl_add_u64 v[8:9], v[8:9], 1, v[16:17]
	s_waitcnt vmcnt(1)
	v_fma_f32 v24, v30, v24, v42
	v_fma_f32 v25, v31, v25, v43
	v_fma_f32 v20, v28, v20, v40
	v_fma_f32 v21, v29, v21, v41
	v_lshlrev_b32_e32 v28, 16, v22
	v_and_b32_e32 v29, 0xffff0000, v22
	v_lshlrev_b32_e32 v22, 16, v23
	v_and_b32_e32 v23, 0xffff0000, v23
	v_fma_f32 v22, v34, v22, v24
	v_fma_f32 v23, v35, v23, v25
	v_fma_f32 v20, v32, v28, v20
	v_fma_f32 v21, v33, v29, v21
	v_lshlrev_b32_e32 v24, 16, v18
	v_and_b32_e32 v25, 0xffff0000, v18
	v_lshlrev_b32_e32 v18, 16, v19
	v_and_b32_e32 v19, 0xffff0000, v19
	s_waitcnt vmcnt(0)
	v_fma_f32 v18, v38, v18, v22
	v_fma_f32 v19, v39, v19, v23
	v_fma_f32 v20, v36, v24, v20
	v_fma_f32 v21, v37, v25, v21
	v_lshlrev_b32_e32 v22, 16, v26
	v_and_b32_e32 v23, 0xffff0000, v26
	v_lshlrev_b32_e32 v24, 16, v27
	v_and_b32_e32 v25, 0xffff0000, v27
	v_mul_f32_e32 v18, v18, v24
	v_mul_f32_e32 v19, v19, v25
	v_mul_f32_e32 v20, v20, v22
	v_mul_f32_e32 v21, v21, v23
	s_nop 0
	v_cvt_pk_bf16_f32 v20, v20, v21
	v_cvt_pk_bf16_f32 v21, v18, v19
	global_store_dwordx2 v[8:9], v[20:21], off
	s_or_b64 exec, exec, s[42:43]
	s_and_saveexec_b64 s[40:41], vcc
	s_cbranch_execz .LBB0_852
.LBB0_874:
	v_lshlrev_b64 v[8:9], 2, v[2:3]
	v_lshl_add_u64 v[20:21], s[14:15], 0, v[8:9]
	v_lshl_add_u64 v[24:25], s[20:21], 0, v[8:9]
	v_lshl_add_u64 v[8:9], s[16:17], 0, v[8:9]
	global_load_dwordx4 v[16:19], v[20:21], off
	s_nop 0
	global_load_dwordx4 v[20:23], v[20:21], off offset:3072
	v_ashrrev_i32_e32 v5, 31, v4
	global_load_dwordx4 v[28:31], v[8:9], off
	v_lshlrev_b32_e32 v8, 16, v14
	global_load_dwordx4 v[24:27], v[24:25], off
	v_and_b32_e32 v9, 0xffff0000, v14
	v_lshlrev_b32_e32 v14, 16, v15
	v_and_b32_e32 v15, 0xffff0000, v15
	v_lshlrev_b64 v[4:5], 11, v[4:5]
	v_lshl_add_u64 v[4:5], s[22:23], 0, v[4:5]
	v_lshl_add_u64 v[2:3], v[2:3], 1, v[4:5]
	s_waitcnt vmcnt(1)
	v_fma_f32 v14, v18, v14, v30
	v_fma_f32 v15, v19, v15, v31
	v_fma_f32 v8, v16, v8, v28
	v_fma_f32 v9, v17, v9, v29
	v_lshlrev_b32_e32 v16, 16, v10
	v_and_b32_e32 v17, 0xffff0000, v10
	v_lshlrev_b32_e32 v10, 16, v11
	v_and_b32_e32 v11, 0xffff0000, v11
	v_fma_f32 v10, v22, v10, v14
	v_fma_f32 v11, v23, v11, v15
	v_fma_f32 v8, v20, v16, v8
	v_fma_f32 v9, v21, v17, v9
	v_lshlrev_b32_e32 v14, 16, v6
	v_and_b32_e32 v15, 0xffff0000, v6
	v_lshlrev_b32_e32 v6, 16, v7
	v_and_b32_e32 v7, 0xffff0000, v7
	s_waitcnt vmcnt(0)
	v_fma_f32 v6, v26, v6, v10
	v_fma_f32 v7, v27, v7, v11
	v_fma_f32 v8, v24, v14, v8
	v_fma_f32 v9, v25, v15, v9
	v_lshlrev_b32_e32 v10, 16, v12
	v_and_b32_e32 v11, 0xffff0000, v12
	v_lshlrev_b32_e32 v12, 16, v13
	v_and_b32_e32 v13, 0xffff0000, v13
	v_mul_f32_e32 v6, v6, v12
	v_mul_f32_e32 v7, v7, v13
	v_mul_f32_e32 v8, v8, v10
	v_mul_f32_e32 v9, v9, v11
	s_nop 0
	v_cvt_pk_bf16_f32 v8, v8, v9
	v_cvt_pk_bf16_f32 v9, v6, v7
	global_store_dwordx2 v[2:3], v[8:9], off
	s_branch .LBB0_852

.LBB0_880:
	ds_bpermute_b32 v36, v170, v153
	v_lshlrev_b64 v[34:35], 11, v[156:157]
	v_lshlrev_b32_e32 v0, 1, v154
	v_lshl_add_u64 v[34:35], s[22:23], 0, v[34:35]
	v_lshl_add_u64 v[34:35], v[34:35], 0, v[0:1]
	s_waitcnt lgkmcnt(0)
	v_add_f32_e32 v36, v153, v36
	v_div_scale_f32 v37, s[0:1], v36, v36, 1.0
	v_rcp_f32_e32 v38, v37
	v_div_scale_f32 v39, vcc, 1.0, v36, 1.0
	v_mov_b32_e32 v153, v1
	v_fma_f32 v40, -v37, v38, 1.0
	v_fmac_f32_e32 v38, v40, v38
	v_mul_f32_e32 v40, v39, v38
	v_fma_f32 v41, -v37, v40, v39
	v_fmac_f32_e32 v40, v41, v38
	v_fma_f32 v37, -v37, v40, v39
	v_div_fmas_f32 v37, v37, v38, v40
	v_div_fixup_f32 v36, v37, v36, 1.0
	v_mul_f32_e32 v2, v2, v36
	v_mul_f32_e32 v3, v3, v36
	v_mul_f32_e32 v4, v4, v36
	v_mul_f32_e32 v5, v5, v36
	v_lshl_add_u64 v[34:35], v[34:35], 0, v[152:153]
	v_cvt_pk_bf16_f32 v2, v2, v3
	v_cvt_pk_bf16_f32 v3, v4, v5
	global_store_dwordx2 v[34:35], v[2:3], off
	v_mul_f32_e32 v2, v6, v36
	v_mul_f32_e32 v3, v7, v36
	v_mul_f32_e32 v4, v8, v36
	v_mul_f32_e32 v5, v9, v36
	v_cvt_pk_bf16_f32 v2, v2, v3
	v_cvt_pk_bf16_f32 v3, v4, v5
	global_store_dwordx2 v[34:35], v[2:3], off offset:16
	v_mul_f32_e32 v2, v10, v36
	v_mul_f32_e32 v3, v11, v36
	v_mul_f32_e32 v4, v12, v36
	v_mul_f32_e32 v5, v13, v36
	v_cvt_pk_bf16_f32 v2, v2, v3
	v_cvt_pk_bf16_f32 v3, v4, v5
	global_store_dwordx2 v[34:35], v[2:3], off offset:32
	v_mul_f32_e32 v2, v14, v36
	v_mul_f32_e32 v3, v15, v36
	v_mul_f32_e32 v4, v16, v36
	v_mul_f32_e32 v5, v17, v36
	v_cvt_pk_bf16_f32 v2, v2, v3
	v_cvt_pk_bf16_f32 v3, v4, v5
	global_store_dwordx2 v[34:35], v[2:3], off offset:48
	v_mul_f32_e32 v2, v18, v36
	v_mul_f32_e32 v3, v19, v36
	v_mul_f32_e32 v4, v20, v36
	v_mul_f32_e32 v5, v21, v36
	v_cvt_pk_bf16_f32 v2, v2, v3
	v_cvt_pk_bf16_f32 v3, v4, v5
	global_store_dwordx2 v[34:35], v[2:3], off offset:64
	v_mul_f32_e32 v2, v22, v36
	v_mul_f32_e32 v3, v23, v36
	v_mul_f32_e32 v4, v24, v36
	v_mul_f32_e32 v5, v25, v36
	v_cvt_pk_bf16_f32 v2, v2, v3
	v_cvt_pk_bf16_f32 v3, v4, v5
	global_store_dwordx2 v[34:35], v[2:3], off offset:80
	v_mul_f32_e32 v2, v26, v36
	v_mul_f32_e32 v3, v27, v36
	v_mul_f32_e32 v4, v28, v36
	v_mul_f32_e32 v5, v29, v36
	v_cvt_pk_bf16_f32 v2, v2, v3
	v_cvt_pk_bf16_f32 v3, v4, v5
	global_store_dwordx2 v[34:35], v[2:3], off offset:96
	v_mul_f32_e32 v2, v30, v36
	v_mul_f32_e32 v3, v31, v36
	v_mul_f32_e32 v4, v32, v36
	v_mul_f32_e32 v5, v33, v36
	s_add_i32 s16, s16, s5
	v_cvt_pk_bf16_f32 v2, v2, v3
	v_cvt_pk_bf16_f32 v3, v4, v5
	s_cmpk_gt_i32 s16, 0x1ff
	global_store_dwordx2 v[34:35], v[2:3], off offset:112
	s_cbranch_scc1 .LBB0_893

.LBB0_885:
	ds_read_b128 v[34:37], v172
	ds_read_b128 v[38:41], v172 offset:32
	ds_read_b128 v[42:45], v172 offset:64
	ds_read_b128 v[46:49], v172 offset:96
	ds_read_b128 v[98:101], v172 offset:4608
	ds_read_b128 v[102:105], v172 offset:4640
	ds_read_b128 v[106:109], v172 offset:4672
	ds_read_b128 v[110:113], v172 offset:4704
	s_waitcnt vmcnt(5) lgkmcnt(7)
	v_mfma_f32_32x32x16_bf16 v[50:65], v[34:37], v[66:69], 0
	v_add_u32_e32 v0, 0x2000, v173
	ds_read2_b64 v[126:129], v0 offset0:128 offset1:130
	ds_read2_b64 v[114:117], v0 offset0:132 offset1:134
	s_waitcnt vmcnt(4) lgkmcnt(8)
	v_mfma_f32_32x32x16_bf16 v[50:65], v[38:41], v[70:73], v[50:65]
	s_waitcnt vmcnt(1) lgkmcnt(7)
	v_mfma_f32_32x32x16_bf16 v[50:65], v[42:45], v[78:81], v[50:65]
	s_waitcnt vmcnt(0) lgkmcnt(6)
	v_mfma_f32_32x32x16_bf16 v[50:65], v[46:49], v[82:85], v[50:65]
	s_waitcnt lgkmcnt(5)
	v_mfma_f32_32x32x16_bf16 v[34:49], v[98:101], v[66:69], 0
	v_add_u32_e32 v98, 0x3000, v173
	s_waitcnt lgkmcnt(4)
	v_mfma_f32_32x32x16_bf16 v[34:49], v[102:105], v[70:73], v[34:49]
	s_waitcnt lgkmcnt(3)
	v_mfma_f32_32x32x16_bf16 v[34:49], v[106:109], v[78:81], v[34:49]
	s_waitcnt lgkmcnt(2)
	v_mfma_f32_32x32x16_bf16 v[34:49], v[110:113], v[82:85], v[34:49]
	ds_read2_b64 v[122:125], v98 offset0:160 offset1:162
	ds_read2_b64 v[118:121], v98 offset0:164 offset1:166
	ds_read2_b64 v[110:113], v0 offset0:136 offset1:138
	ds_read2_b64 v[106:109], v98 offset0:168 offset1:170
	ds_read2_b64 v[102:105], v0 offset0:140 offset1:142
	ds_read2_b64 v[98:101], v98 offset0:172 offset1:174
	v_max_f32_e32 v0, v51, v51
	v_max_f32_e32 v174, v50, v50
	v_max_f32_e32 v0, v174, v0
	v_max3_f32 v0, v0, v52, v53
	v_max3_f32 v0, v0, v54, v55
	v_max3_f32 v0, v0, v56, v57
	v_max3_f32 v0, v0, v58, v59
	v_max3_f32 v0, v0, v60, v61
	v_max3_f32 v0, v0, v62, v63
	v_max3_f32 v0, v0, v64, v65
	v_max3_f32 v0, v0, v34, v35
	v_max3_f32 v0, v0, v36, v37
	v_max3_f32 v0, v0, v38, v39
	v_max3_f32 v0, v0, v40, v41
	v_max3_f32 v0, v0, v42, v43
	v_max3_f32 v0, v0, v44, v45
	v_max3_f32 v0, v0, v46, v47
	v_max3_f32 v0, v0, v48, v49
	ds_bpermute_b32 v174, v170, v0
	s_waitcnt lgkmcnt(0)
	v_max_f32_e32 v174, v174, v174
	v_max_f32_e32 v0, v0, v174
	v_cmp_gt_f32_e32 vcc, v0, v151
	s_cbranch_vccz .LBB0_887
	v_max_f32_e32 v0, v0, v0
	v_max_f32_e32 v174, v151, v151
	v_max_f32_e32 v174, v174, v0
	v_sub_f32_e32 v0, v151, v174
	v_exp_f32_e32 v0, v0
	v_mov_b32_e32 v151, v174
	v_mul_f32_e32 v153, v153, v0
	v_mul_f32_e32 v32, v32, v0
	v_mul_f32_e32 v33, v33, v0
	v_mul_f32_e32 v30, v30, v0
	v_mul_f32_e32 v31, v31, v0
	v_mul_f32_e32 v28, v28, v0
	v_mul_f32_e32 v29, v29, v0
	v_mul_f32_e32 v26, v26, v0
	v_mul_f32_e32 v27, v27, v0
	v_mul_f32_e32 v24, v24, v0
	v_mul_f32_e32 v25, v25, v0
	v_mul_f32_e32 v22, v22, v0
	v_mul_f32_e32 v23, v23, v0
	v_mul_f32_e32 v20, v20, v0
	v_mul_f32_e32 v21, v21, v0
	v_mul_f32_e32 v18, v18, v0
	v_mul_f32_e32 v19, v19, v0
	v_mul_f32_e32 v16, v16, v0
	v_mul_f32_e32 v17, v17, v0
	v_mul_f32_e32 v14, v14, v0
	v_mul_f32_e32 v15, v15, v0
	v_mul_f32_e32 v12, v12, v0
	v_mul_f32_e32 v13, v13, v0
	v_mul_f32_e32 v10, v10, v0
	v_mul_f32_e32 v11, v11, v0
	v_mul_f32_e32 v8, v8, v0
	v_mul_f32_e32 v9, v9, v0
	v_mul_f32_e32 v6, v6, v0
	v_mul_f32_e32 v7, v7, v0
	v_mul_f32_e32 v4, v4, v0
	v_mul_f32_e32 v5, v5, v0
	v_mul_f32_e32 v2, v2, v0
	v_mul_f32_e32 v3, v3, v0

.LBB0_889:
	v_add_f32_e32 v0, 0, v0
	v_add_f32_e32 v0, v50, v0
	v_add_f32_e32 v0, v51, v0
	v_add_f32_e32 v0, v52, v0
	v_add_f32_e32 v0, v53, v0
	v_add_f32_e32 v0, v54, v0
	v_add_f32_e32 v0, v55, v0
	v_add_f32_e32 v0, v56, v0
	v_add_f32_e32 v0, v57, v0
	v_add_f32_e32 v0, v58, v0
	v_add_f32_e32 v0, v59, v0
	v_add_f32_e32 v0, v60, v0
	v_add_f32_e32 v0, v61, v0
	v_add_f32_e32 v0, v62, v0
	v_add_f32_e32 v0, v63, v0
	v_add_f32_e32 v0, v64, v0
	v_add_f32_e32 v0, v34, v0
	v_add_f32_e32 v0, v35, v0
	v_add_f32_e32 v0, v36, v0
	v_add_f32_e32 v0, v37, v0
	v_add_f32_e32 v0, v38, v0
	v_add_f32_e32 v0, v39, v0
	v_add_f32_e32 v0, v40, v0
	v_add_f32_e32 v0, v41, v0
	v_add_f32_e32 v0, v42, v0
	v_add_f32_e32 v0, v43, v0
	v_add_f32_e32 v0, v44, v0
	v_add_f32_e32 v0, v45, v0
	v_add_f32_e32 v0, v46, v0
	v_add_f32_e32 v0, v47, v0
	v_add_f32_e32 v0, v48, v0
	v_add_f32_e32 v0, v49, v0
	ds_read_b128 v[34:37], v172 offset:17920
	ds_read_b128 v[38:41], v172 offset:17952
	ds_read_b128 v[42:45], v172 offset:17984
	ds_read_b128 v[46:49], v172 offset:18016
	ds_read_b128 v[98:101], v172 offset:22528
	ds_read_b128 v[102:105], v172 offset:22560
	ds_read_b128 v[106:109], v172 offset:22592
	ds_read_b128 v[110:113], v172 offset:22624
	v_add_f32_e32 v0, v153, v0
	s_waitcnt lgkmcnt(7)
	v_mfma_f32_32x32x16_bf16 v[50:65], v[34:37], v[66:69], 0
	s_waitcnt lgkmcnt(6)
	v_mfma_f32_32x32x16_bf16 v[50:65], v[38:41], v[70:73], v[50:65]
	s_waitcnt lgkmcnt(5)
	v_mfma_f32_32x32x16_bf16 v[50:65], v[42:45], v[78:81], v[50:65]
	s_waitcnt lgkmcnt(4)
	v_mfma_f32_32x32x16_bf16 v[50:65], v[46:49], v[82:85], v[50:65]
	s_waitcnt lgkmcnt(3)
	v_mfma_f32_32x32x16_bf16 v[34:49], v[98:101], v[66:69], 0
	v_add_u32_e32 v98, 0x6800, v173
	v_add_u32_e32 v99, 0x7800, v173
	ds_read2_b64 v[126:129], v98 offset0:64 offset1:66
	ds_read2_b64 v[114:117], v98 offset0:68 offset1:70
	s_waitcnt lgkmcnt(4)
	v_mfma_f32_32x32x16_bf16 v[34:49], v[102:105], v[70:73], v[34:49]
	s_waitcnt lgkmcnt(3)
	v_mfma_f32_32x32x16_bf16 v[34:49], v[106:109], v[78:81], v[34:49]
	s_waitcnt lgkmcnt(2)
	v_mfma_f32_32x32x16_bf16 v[34:49], v[110:113], v[82:85], v[34:49]
	ds_read2_b64 v[122:125], v99 offset0:96 offset1:98
	ds_read2_b64 v[118:121], v99 offset0:100 offset1:102
	ds_read2_b64 v[110:113], v98 offset0:72 offset1:74
	ds_read2_b64 v[106:109], v99 offset0:104 offset1:106
	ds_read2_b64 v[102:105], v98 offset0:76 offset1:78
	ds_read2_b64 v[98:101], v99 offset0:108 offset1:110
	v_max_f32_e32 v153, v51, v51
	v_max_f32_e32 v162, v50, v50
	v_max_f32_e32 v153, v162, v153
	v_max3_f32 v153, v153, v52, v53
	v_max3_f32 v153, v153, v54, v55
	v_max3_f32 v153, v153, v56, v57
	v_max3_f32 v153, v153, v58, v59
	v_max3_f32 v153, v153, v60, v61
	v_max3_f32 v153, v153, v62, v63
	v_max3_f32 v153, v153, v64, v65
	v_max3_f32 v153, v153, v34, v35
	v_max3_f32 v153, v153, v36, v37
	v_max3_f32 v153, v153, v38, v39
	v_max3_f32 v153, v153, v40, v41
	v_max3_f32 v153, v153, v42, v43
	v_max3_f32 v153, v153, v44, v45
	v_max3_f32 v153, v153, v46, v47
	v_max3_f32 v153, v153, v48, v49
	ds_bpermute_b32 v162, v170, v153
	s_waitcnt lgkmcnt(0)
	v_max_f32_e32 v162, v162, v162
	v_max_f32_e32 v153, v153, v162
	v_cmp_gt_f32_e32 vcc, v153, v151
	s_cbranch_vccz .LBB0_891
	v_max_f32_e32 v153, v153, v153
	v_max_f32_e32 v162, v151, v151
	v_max_f32_e32 v153, v162, v153
	v_sub_f32_e32 v151, v151, v153
	v_exp_f32_e32 v162, v151
	v_mov_b32_e32 v151, v153
	v_mul_f32_e32 v0, v0, v162
	v_mul_f32_e32 v32, v32, v162
	v_mul_f32_e32 v33, v33, v162
	v_mul_f32_e32 v30, v30, v162
	v_mul_f32_e32 v31, v31, v162
	v_mul_f32_e32 v28, v28, v162
	v_mul_f32_e32 v29, v29, v162
	v_mul_f32_e32 v26, v26, v162
	v_mul_f32_e32 v27, v27, v162
	v_mul_f32_e32 v24, v24, v162
	v_mul_f32_e32 v25, v25, v162
	v_mul_f32_e32 v22, v22, v162
	v_mul_f32_e32 v23, v23, v162
	v_mul_f32_e32 v20, v20, v162
	v_mul_f32_e32 v21, v21, v162
	v_mul_f32_e32 v18, v18, v162
	v_mul_f32_e32 v19, v19, v162
	v_mul_f32_e32 v16, v16, v162
	v_mul_f32_e32 v17, v17, v162
	v_mul_f32_e32 v14, v14, v162
	v_mul_f32_e32 v15, v15, v162
	v_mul_f32_e32 v12, v12, v162
	v_mul_f32_e32 v13, v13, v162
	v_mul_f32_e32 v10, v10, v162
	v_mul_f32_e32 v11, v11, v162
	v_mul_f32_e32 v8, v8, v162
	v_mul_f32_e32 v9, v9, v162
	v_mul_f32_e32 v6, v6, v162
	v_mul_f32_e32 v7, v7, v162
	v_mul_f32_e32 v4, v4, v162
	v_mul_f32_e32 v5, v5, v162
	v_mul_f32_e32 v2, v2, v162
	v_mul_f32_e32 v3, v3, v162

.LBB0_895:
	v_sub_f32_e32 v50, v50, v125
	v_exp_f32_e32 v50, v50
	v_sub_f32_e32 v51, v51, v125
	v_exp_f32_e32 v51, v51
	v_sub_f32_e32 v52, v52, v125
	v_exp_f32_e32 v52, v52
	v_sub_f32_e32 v53, v53, v125
	v_exp_f32_e32 v53, v53
	v_sub_f32_e32 v54, v54, v125
	v_add_f32_e32 v98, 0, v50
	v_exp_f32_e32 v54, v54
	v_sub_f32_e32 v55, v55, v125
	v_add_f32_e32 v98, v51, v98
	v_exp_f32_e32 v55, v55
	v_sub_f32_e32 v56, v56, v125
	v_add_f32_e32 v98, v52, v98
	v_exp_f32_e32 v56, v56
	v_sub_f32_e32 v57, v57, v125
	v_add_f32_e32 v98, v53, v98
	v_exp_f32_e32 v57, v57
	v_sub_f32_e32 v58, v58, v125
	v_add_f32_e32 v98, v54, v98
	v_exp_f32_e32 v58, v58
	v_sub_f32_e32 v59, v59, v125
	v_add_f32_e32 v98, v55, v98
	v_exp_f32_e32 v59, v59
	v_sub_f32_e32 v60, v60, v125
	v_add_f32_e32 v98, v56, v98
	v_exp_f32_e32 v60, v60
	v_sub_f32_e32 v61, v61, v125
	v_add_f32_e32 v98, v57, v98
	v_exp_f32_e32 v61, v61
	v_sub_f32_e32 v62, v62, v125
	v_add_f32_e32 v98, v58, v98
	v_exp_f32_e32 v62, v62
	v_sub_f32_e32 v63, v63, v125
	v_add_f32_e32 v98, v59, v98
	v_exp_f32_e32 v63, v63
	v_sub_f32_e32 v64, v64, v125
	v_add_f32_e32 v98, v60, v98
	v_exp_f32_e32 v64, v64
	v_sub_f32_e32 v65, v65, v125
	v_add_f32_e32 v98, v61, v98
	v_exp_f32_e32 v65, v65
	v_sub_f32_e32 v34, v34, v125
	v_add_f32_e32 v98, v62, v98
	v_exp_f32_e32 v99, v34
	v_sub_f32_e32 v34, v35, v125
	v_add_f32_e32 v98, v63, v98
	v_exp_f32_e32 v100, v34
	v_sub_f32_e32 v34, v36, v125
	v_add_f32_e32 v98, v64, v98
	v_exp_f32_e32 v101, v34
	v_sub_f32_e32 v34, v37, v125
	v_add_f32_e32 v98, v65, v98
	v_exp_f32_e32 v102, v34
	v_sub_f32_e32 v35, v38, v125
	v_add_f32_e32 v34, v99, v98
	v_exp_f32_e32 v98, v35
	v_sub_f32_e32 v35, v39, v125
	v_add_f32_e32 v34, v100, v34
	v_exp_f32_e32 v103, v35
	v_sub_f32_e32 v35, v40, v125
	v_add_f32_e32 v34, v101, v34
	v_exp_f32_e32 v104, v35
	v_sub_f32_e32 v35, v41, v125
	v_add_f32_e32 v34, v102, v34
	v_exp_f32_e32 v105, v35
	v_sub_f32_e32 v35, v42, v125
	v_add_f32_e32 v34, v98, v34
	v_exp_f32_e32 v106, v35
	v_sub_f32_e32 v35, v43, v125
	v_add_f32_e32 v34, v103, v34
	v_exp_f32_e32 v107, v35
	v_sub_f32_e32 v35, v44, v125
	v_add_f32_e32 v34, v104, v34
	v_exp_f32_e32 v108, v35
	v_sub_f32_e32 v35, v45, v125
	v_add_f32_e32 v34, v105, v34
	v_exp_f32_e32 v109, v35
	v_sub_f32_e32 v35, v46, v125
	v_add_f32_e32 v34, v106, v34
	v_exp_f32_e32 v110, v35
	v_sub_f32_e32 v35, v47, v125
	v_add_f32_e32 v34, v107, v34
	v_exp_f32_e32 v111, v35
	v_sub_f32_e32 v35, v48, v125
	v_add_f32_e32 v34, v108, v34
	v_exp_f32_e32 v112, v35
	v_sub_f32_e32 v35, v49, v125
	v_add_f32_e32 v34, v109, v34
	v_exp_f32_e32 v49, v35
	v_add_f32_e32 v34, v110, v34
	v_add_f32_e32 v34, v111, v34
	v_add_f32_e32 v34, v112, v34
	v_add_f32_e32 v34, v49, v34
	v_add_f32_e32 v113, v140, v34
	v_cvt_pk_bf16_f32 v34, v50, v51
	v_cvt_pk_bf16_f32 v35, v52, v53
	v_cvt_pk_bf16_f32 v36, v54, v55
	v_cvt_pk_bf16_f32 v37, v56, v57
	v_cvt_pk_bf16_f32 v38, v58, v59
	v_cvt_pk_bf16_f32 v39, v60, v61
	v_cvt_pk_bf16_f32 v40, v62, v63
	v_cvt_pk_bf16_f32 v41, v64, v65
	v_cvt_pk_bf16_f32 v42, v99, v100
	v_cvt_pk_bf16_f32 v43, v101, v102
	v_cvt_pk_bf16_f32 v44, v98, v103
	v_cvt_pk_bf16_f32 v45, v104, v105
	v_cvt_pk_bf16_f32 v46, v106, v107
	v_cvt_pk_bf16_f32 v47, v108, v109
	v_cvt_pk_bf16_f32 v48, v110, v111
	v_cvt_pk_bf16_f32 v49, v112, v49
	v_mfma_f32_32x32x16_bf16 v[18:33], v[94:97], v[34:37], v[18:33]
	v_mfma_f32_32x32x16_bf16 v[2:17], v[90:93], v[34:37], v[2:17]
	v_mfma_f32_32x32x16_bf16 v[18:33], v[86:89], v[38:41], v[18:33]
	v_mfma_f32_32x32x16_bf16 v[2:17], v[82:85], v[38:41], v[2:17]
	v_mfma_f32_32x32x16_bf16 v[18:33], v[78:81], v[42:45], v[18:33]
	v_mfma_f32_32x32x16_bf16 v[2:17], v[74:77], v[42:45], v[2:17]
	v_mfma_f32_32x32x16_bf16 v[18:33], v[70:73], v[46:49], v[18:33]
	v_mfma_f32_32x32x16_bf16 v[2:17], v[66:69], v[46:49], v[2:17]
	ds_bpermute_b32 v36, v131, v113
	v_lshlrev_b64 v[34:35], 11, v[132:133]
	v_lshl_add_u64 v[34:35], s[22:23], 0, v[34:35]
	v_lshl_add_u64 v[34:35], v[34:35], 0, v[0:1]
	v_mov_b32_e32 v129, v1
	s_waitcnt lgkmcnt(0)
	v_add_f32_e32 v36, v113, v36
	v_div_scale_f32 v37, s[0:1], v36, v36, 1.0
	v_rcp_f32_e32 v38, v37
	v_div_scale_f32 v0, vcc, 1.0, v36, 1.0
	v_lshl_add_u64 v[34:35], v[34:35], 0, v[128:129]
	v_fma_f32 v39, -v37, v38, 1.0
	v_fmac_f32_e32 v38, v39, v38
	v_mul_f32_e32 v39, v0, v38
	v_fma_f32 v40, -v37, v39, v0
	v_fmac_f32_e32 v39, v40, v38
	v_fma_f32 v0, -v37, v39, v0
	v_div_fmas_f32 v0, v0, v38, v39
	v_div_fixup_f32 v0, v0, v36, 1.0
	v_mul_f32_e32 v18, v18, v0
	v_mul_f32_e32 v19, v19, v0
	v_mul_f32_e32 v20, v20, v0
	v_mul_f32_e32 v21, v21, v0
	v_mul_f32_e32 v2, v2, v0
	v_mul_f32_e32 v3, v3, v0
	v_mul_f32_e32 v4, v4, v0
	v_mul_f32_e32 v5, v5, v0
	v_cvt_pk_bf16_f32 v18, v18, v19
	v_cvt_pk_bf16_f32 v19, v20, v21
	v_cvt_pk_bf16_f32 v2, v2, v3
	v_cvt_pk_bf16_f32 v3, v4, v5
	global_store_dwordx2 v[34:35], v[18:19], off
	v_mul_f32_e32 v18, v22, v0
	v_mul_f32_e32 v19, v23, v0
	v_mul_f32_e32 v20, v24, v0
	v_mul_f32_e32 v21, v25, v0
	global_store_dwordx2 v[34:35], v[2:3], off offset:64
	v_mul_f32_e32 v2, v6, v0
	v_mul_f32_e32 v3, v7, v0
	v_mul_f32_e32 v4, v8, v0
	v_mul_f32_e32 v5, v9, v0
	v_cvt_pk_bf16_f32 v18, v18, v19
	v_cvt_pk_bf16_f32 v19, v20, v21
	v_cvt_pk_bf16_f32 v2, v2, v3
	v_cvt_pk_bf16_f32 v3, v4, v5
	global_store_dwordx2 v[34:35], v[18:19], off offset:16
	v_mul_f32_e32 v18, v26, v0
	v_mul_f32_e32 v19, v27, v0
	v_mul_f32_e32 v20, v28, v0
	v_mul_f32_e32 v21, v29, v0
	global_store_dwordx2 v[34:35], v[2:3], off offset:80
	v_mul_f32_e32 v2, v10, v0
	v_mul_f32_e32 v3, v11, v0
	v_mul_f32_e32 v4, v12, v0
	v_mul_f32_e32 v5, v13, v0
	v_cvt_pk_bf16_f32 v18, v18, v19
	v_cvt_pk_bf16_f32 v19, v20, v21
	v_cvt_pk_bf16_f32 v2, v2, v3
	v_cvt_pk_bf16_f32 v3, v4, v5
	global_store_dwordx2 v[34:35], v[18:19], off offset:32
	v_mul_f32_e32 v18, v30, v0
	v_mul_f32_e32 v19, v31, v0
	v_mul_f32_e32 v20, v32, v0
	v_mul_f32_e32 v21, v33, v0
	global_store_dwordx2 v[34:35], v[2:3], off offset:96
	v_mul_f32_e32 v2, v14, v0
	v_mul_f32_e32 v3, v15, v0
	v_mul_f32_e32 v4, v16, v0
	v_mul_f32_e32 v5, v17, v0
	s_add_i32 s7, s7, s5
	s_add_i32 s4, s4, s6
	v_cvt_pk_bf16_f32 v18, v18, v19
	v_cvt_pk_bf16_f32 v19, v20, v21
	v_cvt_pk_bf16_f32 v2, v2, v3
	v_cvt_pk_bf16_f32 v3, v4, v5
	s_cmpk_gt_i32 s7, 0x7f
	global_store_dwordx2 v[34:35], v[18:19], off offset:48
	global_store_dwordx2 v[34:35], v[2:3], off offset:112
	s_cbranch_scc1 .LBB0_902
.LBB0_896:
	s_ashr_i32 s0, s7, 3
	s_ashr_i32 s1, s0, 31
	s_bfe_u32 s8, s7, 0x10002
	s_lshl_b64 s[10:11], s[0:1], 16
	s_add_u32 s1, s2, s10
	s_addc_u32 s11, s3, s11
	s_lshl_b32 s10, s8, 7
	s_add_u32 s10, s1, s10
	s_addc_u32 s11, s11, 0
	s_lshl_b32 s1, s0, 1
	s_or_b32 s14, s1, s8
	s_lshl_b32 s0, s0, 8
	s_and_b32 s1, s4, 0xc0
	s_or_b32 s0, s0, s1
	v_add_u32_e32 v132, s0, v137
	v_ashrrev_i32_e32 v133, 31, v132
	v_readlane_b32 s0, v254, 21
	v_lshl_or_b32 v0, s8, 8, v135
	v_lshlrev_b64 v[2:3], 10, v[132:133]
	v_readlane_b32 s1, v254, 22
	v_lshlrev_b32_e32 v0, 1, v0
	v_mov_b32_e32 v125, v1
	v_lshl_add_u64 v[2:3], s[0:1], 0, v[2:3]
	v_lshl_add_u64 v[2:3], v[2:3], 0, v[0:1]
	v_mov_b32_e32 v127, v1
	s_ashr_i32 s15, s14, 31
	v_lshl_add_u64 v[2:3], v[2:3], 0, v[124:125]
	v_lshl_add_u64 v[26:27], s[10:11], 0, v[126:127]
	s_lshl_b64 s[14:15], s[14:15], 15
	global_load_dwordx4 v[78:81], v[2:3], off
	global_load_dwordx4 v[74:77], v[2:3], off offset:32
	global_load_dwordx4 v[66:69], v[2:3], off offset:64
	global_load_dwordx4 v[70:73], v[2:3], off offset:96
	v_lshl_add_u64 v[2:3], v[26:27], 0, v[114:115]
	global_load_dwordx4 v[2:5], v[2:3], off
	v_lshl_add_u64 v[30:31], v[116:117], 0, s[14:15]
	global_load_dwordx4 v[6:9], v[30:31], off
	v_lshl_add_u64 v[10:11], v[26:27], 0, v[118:119]
	global_load_dwordx4 v[10:13], v[10:11], off
	s_nop 0
	global_load_dwordx4 v[14:17], v[30:31], off offset:128
	v_lshl_add_u64 v[18:19], v[26:27], 0, v[120:121]
	global_load_dwordx4 v[18:21], v[18:19], off
	s_nop 0
	global_load_dwordx4 v[22:25], v[30:31], off offset:256
	v_lshl_add_u64 v[26:27], v[26:27], 0, v[122:123]
	global_load_dwordx4 v[26:29], v[26:27], off
	s_nop 0
	global_load_dwordx4 v[30:33], v[30:31], off offset:384
	s_waitcnt lgkmcnt(0)
	s_barrier
	s_waitcnt vmcnt(7)
	ds_write_b128 v134, v[2:5]
	v_add_u32_e32 v2, 0x9000, v136
	s_waitcnt vmcnt(6)
	ds_write2_b64 v2, v[6:7], v[8:9] offset1:1
	s_waitcnt vmcnt(5)
	ds_write_b128 v134, v[10:13] offset:9216
	v_add_u32_e32 v2, 0x9080, v136
	s_waitcnt vmcnt(4)
	ds_write2_b64 v2, v[14:15], v[16:17] offset1:1
	s_waitcnt vmcnt(3)
	ds_write_b128 v134, v[18:21] offset:18432
	v_add_u32_e32 v2, 0x9100, v136
	s_waitcnt vmcnt(2)
	ds_write2_b64 v2, v[22:23], v[24:25] offset1:1
	s_waitcnt vmcnt(1)
	ds_write_b128 v134, v[26:29] offset:27648
	v_add_u32_e32 v2, 0x9180, v136
	s_waitcnt vmcnt(0)
	ds_write2_b64 v2, v[30:31], v[32:33] offset1:1
	s_waitcnt lgkmcnt(0)
	s_barrier
	ds_read_b128 v[2:5], v138
	ds_read_b128 v[6:9], v138 offset:32
	ds_read_b128 v[10:13], v138 offset:64
	ds_read_b128 v[14:17], v138 offset:96
	ds_read_b128 v[36:39], v138 offset:4608
	ds_read_b128 v[40:43], v138 offset:4640
	ds_read_b128 v[44:47], v138 offset:4672
	ds_read_b128 v[48:51], v138 offset:4704
	s_waitcnt lgkmcnt(7)
	v_mfma_f32_32x32x16_bf16 v[20:35], v[2:5], v[78:81], 0
	v_add_u32_e32 v127, 0x9000, v139
	v_add_u32_e32 v129, 0xd000, v139
	ds_read2_b64 v[60:63], v127 offset1:2
	ds_read2_b64 v[52:55], v127 offset0:4 offset1:6
	s_waitcnt lgkmcnt(8)
	v_mfma_f32_32x32x16_bf16 v[20:35], v[6:9], v[74:77], v[20:35]
	s_waitcnt lgkmcnt(7)
	v_mfma_f32_32x32x16_bf16 v[20:35], v[10:13], v[66:69], v[20:35]
	s_waitcnt lgkmcnt(6)
	v_mfma_f32_32x32x16_bf16 v[20:35], v[14:17], v[70:73], v[20:35]
	s_waitcnt lgkmcnt(5)
	v_mfma_f32_32x32x16_bf16 v[4:19], v[36:39], v[78:81], 0
	s_waitcnt lgkmcnt(4)
	v_mfma_f32_32x32x16_bf16 v[4:19], v[40:43], v[74:77], v[4:19]
	s_waitcnt lgkmcnt(3)
	v_mfma_f32_32x32x16_bf16 v[4:19], v[44:47], v[66:69], v[4:19]
	s_waitcnt lgkmcnt(2)
	v_mfma_f32_32x32x16_bf16 v[4:19], v[48:51], v[70:73], v[4:19]
	ds_read2_b64 v[82:85], v129 offset0:32 offset1:34
	ds_read2_b64 v[56:59], v129 offset0:36 offset1:38
	ds_read2_b64 v[48:51], v127 offset0:8 offset1:10
	ds_read2_b64 v[44:47], v129 offset0:40 offset1:42
	ds_read2_b64 v[40:43], v127 offset0:12 offset1:14
	ds_read2_b64 v[36:39], v129 offset0:44 offset1:46
	v_max_f32_e32 v2, v21, v21
	v_max_f32_e32 v3, v20, v20
	v_max_f32_e32 v2, v3, v2
	v_max3_f32 v2, v2, v22, v23
	v_max3_f32 v2, v2, v24, v25
	v_max3_f32 v2, v2, v26, v27
	v_max3_f32 v2, v2, v28, v29
	v_max3_f32 v2, v2, v30, v31
	v_max3_f32 v2, v2, v32, v33
	v_max3_f32 v2, v2, v34, v35
	v_max3_f32 v2, v2, v4, v5
	v_max3_f32 v2, v2, v6, v7
	v_max3_f32 v2, v2, v8, v9
	v_max3_f32 v2, v2, v10, v11
	v_max3_f32 v2, v2, v12, v13
	v_max3_f32 v2, v2, v14, v15
	v_max3_f32 v2, v2, v16, v17
	v_max3_f32 v2, v2, v18, v19
	ds_bpermute_b32 v3, v131, v2
	s_mov_b32 s0, 0xf149f2ca
	v_mov_b32_e32 v64, 0xf149f2ca
	s_waitcnt lgkmcnt(0)
	v_max_f32_e32 v3, v3, v3
	v_max_f32_e32 v2, v2, v3
	v_cmp_lt_f32_e32 vcc, s0, v2
	v_max_f32_e32 v2, 0xf149f2ca, v2
	v_sub_f32_e32 v3, 0xf149f2ca, v2
	s_cmp_eq_u64 vcc, 0
	v_exp_f32_e32 v3, v3
	s_cselect_b64 vcc, -1, 0
	v_cndmask_b32_e32 v125, v2, v64, vcc
	v_sub_f32_e32 v2, v20, v125
	v_exp_f32_e32 v20, v2
	v_mul_f32_e32 v2, 0, v3
	v_sub_f32_e32 v3, v21, v125
	v_exp_f32_e32 v3, v3
	v_sub_f32_e32 v21, v22, v125
	v_exp_f32_e32 v21, v21
	v_sub_f32_e32 v22, v23, v125
	v_exp_f32_e32 v22, v22
	v_sub_f32_e32 v24, v24, v125
	v_add_f32_e32 v23, 0, v20
	v_exp_f32_e32 v24, v24
	v_sub_f32_e32 v25, v25, v125
	v_add_f32_e32 v23, v3, v23
	v_exp_f32_e32 v25, v25
	v_sub_f32_e32 v26, v26, v125
	v_add_f32_e32 v23, v21, v23
	v_exp_f32_e32 v26, v26
	v_sub_f32_e32 v27, v27, v125
	v_add_f32_e32 v23, v22, v23
	v_exp_f32_e32 v27, v27
	v_sub_f32_e32 v28, v28, v125
	v_add_f32_e32 v23, v24, v23
	v_exp_f32_e32 v28, v28
	v_sub_f32_e32 v29, v29, v125
	v_add_f32_e32 v23, v25, v23
	v_exp_f32_e32 v29, v29
	v_sub_f32_e32 v30, v30, v125
	v_add_f32_e32 v23, v26, v23
	v_exp_f32_e32 v30, v30
	v_sub_f32_e32 v31, v31, v125
	v_add_f32_e32 v23, v27, v23
	v_exp_f32_e32 v31, v31
	v_sub_f32_e32 v32, v32, v125
	v_add_f32_e32 v23, v28, v23
	v_exp_f32_e32 v32, v32
	v_sub_f32_e32 v33, v33, v125
	v_add_f32_e32 v23, v29, v23
	v_exp_f32_e32 v33, v33
	v_sub_f32_e32 v34, v34, v125
	v_add_f32_e32 v23, v30, v23
	v_exp_f32_e32 v34, v34
	v_sub_f32_e32 v35, v35, v125
	v_add_f32_e32 v23, v31, v23
	v_exp_f32_e32 v35, v35
	v_sub_f32_e32 v4, v4, v125
	v_add_f32_e32 v23, v32, v23
	v_exp_f32_e32 v4, v4
	v_sub_f32_e32 v5, v5, v125
	v_add_f32_e32 v23, v33, v23
	v_exp_f32_e32 v5, v5
	v_sub_f32_e32 v6, v6, v125
	v_add_f32_e32 v23, v34, v23
	v_exp_f32_e32 v6, v6
	v_sub_f32_e32 v7, v7, v125
	v_add_f32_e32 v23, v35, v23
	v_exp_f32_e32 v7, v7
	v_sub_f32_e32 v8, v8, v125
	v_add_f32_e32 v23, v4, v23
	v_exp_f32_e32 v8, v8
	v_sub_f32_e32 v9, v9, v125
	v_add_f32_e32 v23, v5, v23
	v_exp_f32_e32 v9, v9
	v_sub_f32_e32 v10, v10, v125
	v_add_f32_e32 v23, v6, v23
	v_exp_f32_e32 v10, v10
	v_sub_f32_e32 v11, v11, v125
	v_add_f32_e32 v23, v7, v23
	v_exp_f32_e32 v11, v11
	v_sub_f32_e32 v12, v12, v125
	v_add_f32_e32 v23, v8, v23
	v_exp_f32_e32 v12, v12
	v_sub_f32_e32 v13, v13, v125
	v_add_f32_e32 v23, v9, v23
	v_exp_f32_e32 v13, v13
	v_sub_f32_e32 v14, v14, v125
	v_add_f32_e32 v23, v10, v23
	v_exp_f32_e32 v14, v14
	v_sub_f32_e32 v15, v15, v125
	v_add_f32_e32 v23, v11, v23
	v_exp_f32_e32 v15, v15
	v_sub_f32_e32 v16, v16, v125
	v_add_f32_e32 v23, v12, v23
	v_exp_f32_e32 v16, v16
	v_sub_f32_e32 v17, v17, v125
	v_add_f32_e32 v23, v13, v23
	v_exp_f32_e32 v17, v17
	v_sub_f32_e32 v18, v18, v125
	v_add_f32_e32 v23, v14, v23
	v_exp_f32_e32 v18, v18
	v_sub_f32_e32 v19, v19, v125
	v_add_f32_e32 v23, v15, v23
	v_exp_f32_e32 v19, v19
	v_add_f32_e32 v23, v16, v23
	v_add_f32_e32 v23, v17, v23
	v_add_f32_e32 v23, v18, v23
	v_cndmask_b32_e64 v2, v2, 0, vcc
	v_add_f32_e32 v23, v19, v23
	v_add_f32_e32 v140, v2, v23
	v_cvt_pk_bf16_f32 v86, v20, v3
	v_cvt_pk_bf16_f32 v87, v21, v22
	v_cvt_pk_bf16_f32 v88, v24, v25
	v_cvt_pk_bf16_f32 v89, v26, v27
	v_cvt_pk_bf16_f32 v90, v28, v29
	v_cvt_pk_bf16_f32 v91, v30, v31
	v_cvt_pk_bf16_f32 v92, v32, v33
	v_cvt_pk_bf16_f32 v93, v34, v35
	v_cvt_pk_bf16_f32 v94, v4, v5
	v_cvt_pk_bf16_f32 v95, v6, v7
	v_cvt_pk_bf16_f32 v96, v8, v9
	v_cvt_pk_bf16_f32 v97, v10, v11
	v_cvt_pk_bf16_f32 v98, v12, v13
	v_cvt_pk_bf16_f32 v99, v14, v15
	v_cvt_pk_bf16_f32 v100, v16, v17
	v_cvt_pk_bf16_f32 v101, v18, v19
	v_mov_b32_e32 v3, v2
	v_mov_b32_e32 v4, v2
	v_mov_b32_e32 v5, v2
	v_mov_b32_e32 v6, v2
	v_mov_b32_e32 v7, v2
	v_mov_b32_e32 v8, v2
	v_mov_b32_e32 v9, v2
	v_mov_b32_e32 v10, v2
	v_mov_b32_e32 v11, v2
	v_mov_b32_e32 v12, v2
	v_mov_b32_e32 v13, v2
	v_mov_b32_e32 v14, v2
	v_mov_b32_e32 v15, v2
	v_mov_b32_e32 v16, v2
	v_mov_b32_e32 v17, v2
	s_nop 1
	v_mfma_f32_32x32x16_bf16 v[18:33], v[60:63], v[86:89], v[2:17]
	v_mfma_f32_32x32x16_bf16 v[2:17], v[82:85], v[86:89], v[2:17]
	v_mfma_f32_32x32x16_bf16 v[18:33], v[52:55], v[90:93], v[18:33]
	v_mfma_f32_32x32x16_bf16 v[2:17], v[56:59], v[90:93], v[2:17]
	v_mfma_f32_32x32x16_bf16 v[18:33], v[48:51], v[94:97], v[18:33]
	v_mfma_f32_32x32x16_bf16 v[2:17], v[44:47], v[94:97], v[2:17]
	v_mfma_f32_32x32x16_bf16 v[18:33], v[40:43], v[98:101], v[18:33]
	v_mfma_f32_32x32x16_bf16 v[2:17], v[36:39], v[98:101], v[2:17]
	ds_read_b128 v[34:37], v138 offset:9216
	ds_read_b128 v[38:41], v138 offset:9248
	ds_read_b128 v[42:45], v138 offset:9280
	ds_read_b128 v[46:49], v138 offset:9312
	ds_read_b128 v[82:85], v138 offset:13824
	ds_read_b128 v[86:89], v138 offset:13856
	ds_read_b128 v[90:93], v138 offset:13888
	ds_read_b128 v[94:97], v138 offset:13920
	s_waitcnt lgkmcnt(7)
	v_mfma_f32_32x32x16_bf16 v[50:65], v[34:37], v[78:81], 0
	s_waitcnt lgkmcnt(6)
	v_mfma_f32_32x32x16_bf16 v[50:65], v[38:41], v[74:77], v[50:65]
	s_waitcnt lgkmcnt(5)
	v_mfma_f32_32x32x16_bf16 v[50:65], v[42:45], v[66:69], v[50:65]
	s_waitcnt lgkmcnt(4)
	v_mfma_f32_32x32x16_bf16 v[50:65], v[46:49], v[70:73], v[50:65]
	s_waitcnt lgkmcnt(3)
	v_mfma_f32_32x32x16_bf16 v[34:49], v[82:85], v[78:81], 0
	s_waitcnt lgkmcnt(2)
	v_mfma_f32_32x32x16_bf16 v[34:49], v[86:89], v[74:77], v[34:49]
	s_waitcnt lgkmcnt(1)
	v_mfma_f32_32x32x16_bf16 v[34:49], v[90:93], v[66:69], v[34:49]
	s_waitcnt lgkmcnt(0)
	v_mfma_f32_32x32x16_bf16 v[34:49], v[94:97], v[70:73], v[34:49]
	ds_read2_b64 v[110:113], v127 offset0:16 offset1:18
	ds_read2_b64 v[102:105], v127 offset0:20 offset1:22
	ds_read2_b64 v[106:109], v129 offset0:48 offset1:50
	ds_read2_b64 v[98:101], v129 offset0:52 offset1:54
	ds_read2_b64 v[94:97], v127 offset0:24 offset1:26
	ds_read2_b64 v[90:93], v129 offset0:56 offset1:58
	ds_read2_b64 v[86:89], v127 offset0:28 offset1:30
	ds_read2_b64 v[82:85], v129 offset0:60 offset1:62
	v_max_f32_e32 v141, v51, v51
	v_max_f32_e32 v142, v50, v50
	v_max_f32_e32 v141, v142, v141
	v_max3_f32 v141, v141, v52, v53
	v_max3_f32 v141, v141, v54, v55
	v_max3_f32 v141, v141, v56, v57
	v_max3_f32 v141, v141, v58, v59
	v_max3_f32 v141, v141, v60, v61
	v_max3_f32 v141, v141, v62, v63
	v_max3_f32 v141, v141, v64, v65
	v_max3_f32 v141, v141, v34, v35
	v_max3_f32 v141, v141, v36, v37
	v_max3_f32 v141, v141, v38, v39
	v_max3_f32 v141, v141, v40, v41
	v_max3_f32 v141, v141, v42, v43
	v_max3_f32 v141, v141, v44, v45
	v_max3_f32 v141, v141, v46, v47
	v_max3_f32 v141, v141, v48, v49
	ds_bpermute_b32 v142, v131, v141
	s_waitcnt lgkmcnt(0)
	v_max_f32_e32 v142, v142, v142
	v_max_f32_e32 v141, v141, v142
	v_cmp_gt_f32_e32 vcc, v141, v125
	s_cbranch_vccz .LBB0_898
	v_max_f32_e32 v141, v141, v141
	v_max_f32_e32 v142, v125, v125
	v_max_f32_e32 v141, v142, v141
	v_sub_f32_e32 v125, v125, v141
	v_exp_f32_e32 v142, v125
	v_mov_b32_e32 v125, v141
	v_mul_f32_e32 v140, v140, v142
	v_mul_f32_e32 v16, v16, v142
	v_mul_f32_e32 v17, v17, v142
	v_mul_f32_e32 v14, v14, v142
	v_mul_f32_e32 v15, v15, v142
	v_mul_f32_e32 v12, v12, v142
	v_mul_f32_e32 v13, v13, v142
	v_mul_f32_e32 v10, v10, v142
	v_mul_f32_e32 v11, v11, v142
	v_mul_f32_e32 v8, v8, v142
	v_mul_f32_e32 v9, v9, v142
	v_mul_f32_e32 v6, v6, v142
	v_mul_f32_e32 v7, v7, v142
	v_mul_f32_e32 v4, v4, v142
	v_mul_f32_e32 v5, v5, v142
	v_mul_f32_e32 v2, v2, v142
	v_mul_f32_e32 v3, v3, v142
	v_mul_f32_e32 v32, v32, v142
	v_mul_f32_e32 v33, v33, v142
	v_mul_f32_e32 v30, v30, v142
	v_mul_f32_e32 v31, v31, v142
	v_mul_f32_e32 v28, v28, v142
	v_mul_f32_e32 v29, v29, v142
	v_mul_f32_e32 v26, v26, v142
	v_mul_f32_e32 v27, v27, v142
	v_mul_f32_e32 v24, v24, v142
	v_mul_f32_e32 v25, v25, v142
	v_mul_f32_e32 v22, v22, v142
	v_mul_f32_e32 v23, v23, v142
	v_mul_f32_e32 v20, v20, v142
	v_mul_f32_e32 v21, v21, v142
	v_mul_f32_e32 v18, v18, v142
	v_mul_f32_e32 v19, v19, v142
.LBB0_898:
	v_sub_f32_e32 v50, v50, v125
	v_exp_f32_e32 v50, v50
	v_sub_f32_e32 v51, v51, v125
	v_exp_f32_e32 v51, v51
	v_sub_f32_e32 v52, v52, v125
	v_exp_f32_e32 v52, v52
	v_sub_f32_e32 v53, v53, v125
	v_exp_f32_e32 v53, v53
	v_sub_f32_e32 v54, v54, v125
	v_add_f32_e32 v141, 0, v50
	v_exp_f32_e32 v54, v54
	v_sub_f32_e32 v55, v55, v125
	v_add_f32_e32 v141, v51, v141
	v_exp_f32_e32 v55, v55
	v_sub_f32_e32 v56, v56, v125
	v_add_f32_e32 v141, v52, v141
	v_exp_f32_e32 v56, v56
	v_sub_f32_e32 v57, v57, v125
	v_add_f32_e32 v141, v53, v141
	v_exp_f32_e32 v57, v57
	v_sub_f32_e32 v58, v58, v125
	v_add_f32_e32 v141, v54, v141
	v_exp_f32_e32 v58, v58
	v_sub_f32_e32 v59, v59, v125
	v_add_f32_e32 v141, v55, v141
	v_exp_f32_e32 v59, v59
	v_sub_f32_e32 v60, v60, v125
	v_add_f32_e32 v141, v56, v141
	v_exp_f32_e32 v60, v60
	v_sub_f32_e32 v61, v61, v125
	v_add_f32_e32 v141, v57, v141
	v_exp_f32_e32 v61, v61
	v_sub_f32_e32 v62, v62, v125
	v_add_f32_e32 v141, v58, v141
	v_exp_f32_e32 v62, v62
	v_sub_f32_e32 v63, v63, v125
	v_add_f32_e32 v141, v59, v141
	v_exp_f32_e32 v63, v63
	v_sub_f32_e32 v64, v64, v125
	v_add_f32_e32 v141, v60, v141
	v_exp_f32_e32 v64, v64
	v_sub_f32_e32 v65, v65, v125
	v_add_f32_e32 v141, v61, v141
	v_exp_f32_e32 v65, v65
	v_sub_f32_e32 v34, v34, v125
	v_add_f32_e32 v141, v62, v141
	v_exp_f32_e32 v142, v34
	v_sub_f32_e32 v34, v35, v125
	v_add_f32_e32 v141, v63, v141
	v_exp_f32_e32 v143, v34
	v_sub_f32_e32 v34, v36, v125
	v_add_f32_e32 v141, v64, v141
	v_exp_f32_e32 v144, v34
	v_sub_f32_e32 v34, v37, v125
	v_add_f32_e32 v141, v65, v141
	v_exp_f32_e32 v145, v34
	v_sub_f32_e32 v35, v38, v125
	v_add_f32_e32 v34, v142, v141
	v_exp_f32_e32 v141, v35
	v_sub_f32_e32 v35, v39, v125
	v_add_f32_e32 v34, v143, v34
	v_exp_f32_e32 v146, v35
	v_sub_f32_e32 v35, v40, v125
	v_add_f32_e32 v34, v144, v34
	v_exp_f32_e32 v147, v35
	v_sub_f32_e32 v35, v41, v125
	v_add_f32_e32 v34, v145, v34
	v_exp_f32_e32 v148, v35
	v_sub_f32_e32 v35, v42, v125
	v_add_f32_e32 v34, v141, v34
	v_exp_f32_e32 v149, v35
	v_sub_f32_e32 v35, v43, v125
	v_add_f32_e32 v34, v146, v34
	v_exp_f32_e32 v150, v35
	v_sub_f32_e32 v35, v44, v125
	v_add_f32_e32 v34, v147, v34
	v_exp_f32_e32 v151, v35
	v_sub_f32_e32 v35, v45, v125
	v_add_f32_e32 v34, v148, v34
	v_exp_f32_e32 v152, v35
	v_sub_f32_e32 v35, v46, v125
	v_add_f32_e32 v34, v149, v34
	v_exp_f32_e32 v153, v35
	v_sub_f32_e32 v35, v47, v125
	v_add_f32_e32 v34, v150, v34
	v_exp_f32_e32 v154, v35
	v_sub_f32_e32 v35, v48, v125
	v_add_f32_e32 v34, v151, v34
	v_exp_f32_e32 v155, v35
	v_sub_f32_e32 v35, v49, v125
	v_add_f32_e32 v34, v152, v34
	v_exp_f32_e32 v49, v35
	v_add_f32_e32 v34, v153, v34
	v_add_f32_e32 v34, v154, v34
	v_add_f32_e32 v34, v155, v34
	v_add_f32_e32 v34, v49, v34
	v_add_f32_e32 v140, v140, v34
	v_cvt_pk_bf16_f32 v34, v50, v51
	v_cvt_pk_bf16_f32 v35, v52, v53
	v_cvt_pk_bf16_f32 v36, v54, v55
	v_cvt_pk_bf16_f32 v37, v56, v57
	v_cvt_pk_bf16_f32 v38, v58, v59
	v_cvt_pk_bf16_f32 v39, v60, v61
	v_cvt_pk_bf16_f32 v40, v62, v63
	v_cvt_pk_bf16_f32 v41, v64, v65
	v_cvt_pk_bf16_f32 v42, v142, v143
	v_cvt_pk_bf16_f32 v43, v144, v145
	v_cvt_pk_bf16_f32 v44, v141, v146
	v_cvt_pk_bf16_f32 v45, v147, v148
	v_cvt_pk_bf16_f32 v46, v149, v150
	v_cvt_pk_bf16_f32 v47, v151, v152
	v_cvt_pk_bf16_f32 v48, v153, v154
	v_cvt_pk_bf16_f32 v49, v155, v49
	v_mfma_f32_32x32x16_bf16 v[18:33], v[110:113], v[34:37], v[18:33]
	v_mfma_f32_32x32x16_bf16 v[2:17], v[106:109], v[34:37], v[2:17]
	v_mfma_f32_32x32x16_bf16 v[18:33], v[102:105], v[38:41], v[18:33]
	v_mfma_f32_32x32x16_bf16 v[2:17], v[98:101], v[38:41], v[2:17]
	v_mfma_f32_32x32x16_bf16 v[18:33], v[94:97], v[42:45], v[18:33]
	v_mfma_f32_32x32x16_bf16 v[2:17], v[90:93], v[42:45], v[2:17]
	v_mfma_f32_32x32x16_bf16 v[18:33], v[86:89], v[46:49], v[18:33]
	v_mfma_f32_32x32x16_bf16 v[2:17], v[82:85], v[46:49], v[2:17]
	ds_read_b128 v[34:37], v138 offset:18432
	ds_read_b128 v[38:41], v138 offset:18464
	ds_read_b128 v[42:45], v138 offset:18496
	ds_read_b128 v[46:49], v138 offset:18528
	ds_read_b128 v[82:85], v138 offset:23040
	ds_read_b128 v[86:89], v138 offset:23072
	ds_read_b128 v[90:93], v138 offset:23104
	ds_read_b128 v[94:97], v138 offset:23136
	s_waitcnt lgkmcnt(7)
	v_mfma_f32_32x32x16_bf16 v[50:65], v[34:37], v[78:81], 0
	s_waitcnt lgkmcnt(6)
	v_mfma_f32_32x32x16_bf16 v[50:65], v[38:41], v[74:77], v[50:65]
	s_waitcnt lgkmcnt(5)
	v_mfma_f32_32x32x16_bf16 v[50:65], v[42:45], v[66:69], v[50:65]
	s_waitcnt lgkmcnt(4)
	v_mfma_f32_32x32x16_bf16 v[50:65], v[46:49], v[70:73], v[50:65]
	s_waitcnt lgkmcnt(3)
	v_mfma_f32_32x32x16_bf16 v[34:49], v[82:85], v[78:81], 0
	s_waitcnt lgkmcnt(2)
	v_mfma_f32_32x32x16_bf16 v[34:49], v[86:89], v[74:77], v[34:49]
	s_waitcnt lgkmcnt(1)
	v_mfma_f32_32x32x16_bf16 v[34:49], v[90:93], v[66:69], v[34:49]
	s_waitcnt lgkmcnt(0)
	v_mfma_f32_32x32x16_bf16 v[34:49], v[94:97], v[70:73], v[34:49]
	ds_read2_b64 v[110:113], v127 offset0:32 offset1:34
	ds_read2_b64 v[102:105], v127 offset0:36 offset1:38
	ds_read2_b64 v[106:109], v129 offset0:64 offset1:66
	ds_read2_b64 v[98:101], v129 offset0:68 offset1:70
	ds_read2_b64 v[94:97], v127 offset0:40 offset1:42
	ds_read2_b64 v[90:93], v129 offset0:72 offset1:74
	ds_read2_b64 v[86:89], v127 offset0:44 offset1:46
	ds_read2_b64 v[82:85], v129 offset0:76 offset1:78
	v_max_f32_e32 v141, v51, v51
	v_max_f32_e32 v142, v50, v50
	v_max_f32_e32 v141, v142, v141
	v_max3_f32 v141, v141, v52, v53
	v_max3_f32 v141, v141, v54, v55
	v_max3_f32 v141, v141, v56, v57
	v_max3_f32 v141, v141, v58, v59
	v_max3_f32 v141, v141, v60, v61
	v_max3_f32 v141, v141, v62, v63
	v_max3_f32 v141, v141, v64, v65
	v_max3_f32 v141, v141, v34, v35
	v_max3_f32 v141, v141, v36, v37
	v_max3_f32 v141, v141, v38, v39
	v_max3_f32 v141, v141, v40, v41
	v_max3_f32 v141, v141, v42, v43
	v_max3_f32 v141, v141, v44, v45
	v_max3_f32 v141, v141, v46, v47
	v_max3_f32 v141, v141, v48, v49
	ds_bpermute_b32 v142, v131, v141
	s_waitcnt lgkmcnt(0)
	v_max_f32_e32 v142, v142, v142
	v_max_f32_e32 v141, v141, v142
	v_cmp_gt_f32_e32 vcc, v141, v125
	s_cbranch_vccz .LBB0_900
	v_max_f32_e32 v141, v141, v141
	v_max_f32_e32 v142, v125, v125
	v_max_f32_e32 v141, v142, v141
	v_sub_f32_e32 v125, v125, v141
	v_exp_f32_e32 v142, v125
	v_mov_b32_e32 v125, v141
	v_mul_f32_e32 v140, v140, v142
	v_mul_f32_e32 v16, v16, v142
	v_mul_f32_e32 v17, v17, v142
	v_mul_f32_e32 v14, v14, v142
	v_mul_f32_e32 v15, v15, v142
	v_mul_f32_e32 v12, v12, v142
	v_mul_f32_e32 v13, v13, v142
	v_mul_f32_e32 v10, v10, v142
	v_mul_f32_e32 v11, v11, v142
	v_mul_f32_e32 v8, v8, v142
	v_mul_f32_e32 v9, v9, v142
	v_mul_f32_e32 v6, v6, v142
	v_mul_f32_e32 v7, v7, v142
	v_mul_f32_e32 v4, v4, v142
	v_mul_f32_e32 v5, v5, v142
	v_mul_f32_e32 v2, v2, v142
	v_mul_f32_e32 v3, v3, v142
	v_mul_f32_e32 v32, v32, v142
	v_mul_f32_e32 v33, v33, v142
	v_mul_f32_e32 v30, v30, v142
	v_mul_f32_e32 v31, v31, v142
	v_mul_f32_e32 v28, v28, v142
	v_mul_f32_e32 v29, v29, v142
	v_mul_f32_e32 v26, v26, v142
	v_mul_f32_e32 v27, v27, v142
	v_mul_f32_e32 v24, v24, v142
	v_mul_f32_e32 v25, v25, v142
	v_mul_f32_e32 v22, v22, v142
	v_mul_f32_e32 v23, v23, v142
	v_mul_f32_e32 v20, v20, v142
	v_mul_f32_e32 v21, v21, v142
	v_mul_f32_e32 v18, v18, v142
	v_mul_f32_e32 v19, v19, v142
.LBB0_900:
	v_sub_f32_e32 v50, v50, v125
	v_exp_f32_e32 v50, v50
	v_sub_f32_e32 v51, v51, v125
	v_exp_f32_e32 v51, v51
	v_sub_f32_e32 v52, v52, v125
	v_exp_f32_e32 v52, v52
	v_sub_f32_e32 v53, v53, v125
	v_exp_f32_e32 v53, v53
	v_sub_f32_e32 v54, v54, v125
	v_add_f32_e32 v141, 0, v50
	v_exp_f32_e32 v54, v54
	v_sub_f32_e32 v55, v55, v125
	v_add_f32_e32 v141, v51, v141
	v_exp_f32_e32 v55, v55
	v_sub_f32_e32 v56, v56, v125
	v_add_f32_e32 v141, v52, v141
	v_exp_f32_e32 v56, v56
	v_sub_f32_e32 v57, v57, v125
	v_add_f32_e32 v141, v53, v141
	v_exp_f32_e32 v57, v57
	v_sub_f32_e32 v58, v58, v125
	v_add_f32_e32 v141, v54, v141
	v_exp_f32_e32 v58, v58
	v_sub_f32_e32 v59, v59, v125
	v_add_f32_e32 v141, v55, v141
	v_exp_f32_e32 v59, v59
	v_sub_f32_e32 v60, v60, v125
	v_add_f32_e32 v141, v56, v141
	v_exp_f32_e32 v60, v60
	v_sub_f32_e32 v61, v61, v125
	v_add_f32_e32 v141, v57, v141
	v_exp_f32_e32 v61, v61
	v_sub_f32_e32 v62, v62, v125
	v_add_f32_e32 v141, v58, v141
	v_exp_f32_e32 v62, v62
	v_sub_f32_e32 v63, v63, v125
	v_add_f32_e32 v141, v59, v141
	v_exp_f32_e32 v63, v63
	v_sub_f32_e32 v64, v64, v125
	v_add_f32_e32 v141, v60, v141
	v_exp_f32_e32 v64, v64
	v_sub_f32_e32 v65, v65, v125
	v_add_f32_e32 v141, v61, v141
	v_exp_f32_e32 v65, v65
	v_sub_f32_e32 v34, v34, v125
	v_add_f32_e32 v141, v62, v141
	v_exp_f32_e32 v142, v34
	v_sub_f32_e32 v34, v35, v125
	v_add_f32_e32 v141, v63, v141
	v_exp_f32_e32 v143, v34
	v_sub_f32_e32 v34, v36, v125
	v_add_f32_e32 v141, v64, v141
	v_exp_f32_e32 v144, v34
	v_sub_f32_e32 v34, v37, v125
	v_add_f32_e32 v141, v65, v141
	v_exp_f32_e32 v145, v34
	v_sub_f32_e32 v35, v38, v125
	v_add_f32_e32 v34, v142, v141
	v_exp_f32_e32 v141, v35
	v_sub_f32_e32 v35, v39, v125
	v_add_f32_e32 v34, v143, v34
	v_exp_f32_e32 v146, v35
	v_sub_f32_e32 v35, v40, v125
	v_add_f32_e32 v34, v144, v34
	v_exp_f32_e32 v147, v35
	v_sub_f32_e32 v35, v41, v125
	v_add_f32_e32 v34, v145, v34
	v_exp_f32_e32 v148, v35
	v_sub_f32_e32 v35, v42, v125
	v_add_f32_e32 v34, v141, v34
	v_exp_f32_e32 v149, v35
	v_sub_f32_e32 v35, v43, v125
	v_add_f32_e32 v34, v146, v34
	v_exp_f32_e32 v150, v35
	v_sub_f32_e32 v35, v44, v125
	v_add_f32_e32 v34, v147, v34
	v_exp_f32_e32 v151, v35
	v_sub_f32_e32 v35, v45, v125
	v_add_f32_e32 v34, v148, v34
	v_exp_f32_e32 v152, v35
	v_sub_f32_e32 v35, v46, v125
	v_add_f32_e32 v34, v149, v34
	v_exp_f32_e32 v153, v35
	v_sub_f32_e32 v35, v47, v125
	v_add_f32_e32 v34, v150, v34
	v_exp_f32_e32 v154, v35
	v_sub_f32_e32 v35, v48, v125
	v_add_f32_e32 v34, v151, v34
	v_exp_f32_e32 v155, v35
	v_sub_f32_e32 v35, v49, v125
	v_add_f32_e32 v34, v152, v34
	v_exp_f32_e32 v49, v35
	v_add_f32_e32 v34, v153, v34
	v_add_f32_e32 v34, v154, v34
	v_add_f32_e32 v34, v155, v34
	v_add_f32_e32 v34, v49, v34
	v_add_f32_e32 v140, v140, v34
	v_cvt_pk_bf16_f32 v34, v50, v51
	v_cvt_pk_bf16_f32 v35, v52, v53
	v_cvt_pk_bf16_f32 v36, v54, v55
	v_cvt_pk_bf16_f32 v37, v56, v57
	v_cvt_pk_bf16_f32 v38, v58, v59
	v_cvt_pk_bf16_f32 v39, v60, v61
	v_cvt_pk_bf16_f32 v40, v62, v63
	v_cvt_pk_bf16_f32 v41, v64, v65
	v_cvt_pk_bf16_f32 v42, v142, v143
	v_cvt_pk_bf16_f32 v43, v144, v145
	v_cvt_pk_bf16_f32 v44, v141, v146
	v_cvt_pk_bf16_f32 v45, v147, v148
	v_cvt_pk_bf16_f32 v46, v149, v150
	v_cvt_pk_bf16_f32 v47, v151, v152
	v_cvt_pk_bf16_f32 v48, v153, v154
	v_cvt_pk_bf16_f32 v49, v155, v49
	v_mfma_f32_32x32x16_bf16 v[18:33], v[110:113], v[34:37], v[18:33]
	v_mfma_f32_32x32x16_bf16 v[2:17], v[106:109], v[34:37], v[2:17]
	v_mfma_f32_32x32x16_bf16 v[18:33], v[102:105], v[38:41], v[18:33]
	v_mfma_f32_32x32x16_bf16 v[2:17], v[98:101], v[38:41], v[2:17]
	v_mfma_f32_32x32x16_bf16 v[18:33], v[94:97], v[42:45], v[18:33]
	v_mfma_f32_32x32x16_bf16 v[2:17], v[90:93], v[42:45], v[2:17]
	v_mfma_f32_32x32x16_bf16 v[18:33], v[86:89], v[46:49], v[18:33]
	v_mfma_f32_32x32x16_bf16 v[2:17], v[82:85], v[46:49], v[2:17]
	ds_read_b128 v[34:37], v138 offset:27648
	ds_read_b128 v[38:41], v138 offset:27680
	ds_read_b128 v[42:45], v138 offset:27712
	ds_read_b128 v[46:49], v138 offset:27744
	ds_read_b128 v[82:85], v138 offset:32256
	ds_read_b128 v[86:89], v138 offset:32288
	ds_read_b128 v[90:93], v138 offset:32320
	ds_read_b128 v[94:97], v138 offset:32352
	s_waitcnt lgkmcnt(7)
	v_mfma_f32_32x32x16_bf16 v[50:65], v[34:37], v[78:81], 0
	s_waitcnt lgkmcnt(6)
	v_mfma_f32_32x32x16_bf16 v[50:65], v[38:41], v[74:77], v[50:65]
	s_waitcnt lgkmcnt(5)
	v_mfma_f32_32x32x16_bf16 v[50:65], v[42:45], v[66:69], v[50:65]
	s_waitcnt lgkmcnt(4)
	v_mfma_f32_32x32x16_bf16 v[50:65], v[46:49], v[70:73], v[50:65]
	s_waitcnt lgkmcnt(3)
	v_mfma_f32_32x32x16_bf16 v[34:49], v[82:85], v[78:81], 0
	s_waitcnt lgkmcnt(2)
	v_mfma_f32_32x32x16_bf16 v[34:49], v[86:89], v[74:77], v[34:49]
	s_waitcnt lgkmcnt(1)
	v_mfma_f32_32x32x16_bf16 v[34:49], v[90:93], v[66:69], v[34:49]
	s_waitcnt lgkmcnt(0)
	v_mfma_f32_32x32x16_bf16 v[34:49], v[94:97], v[70:73], v[34:49]
	ds_read2_b64 v[94:97], v127 offset0:48 offset1:50
	ds_read2_b64 v[86:89], v127 offset0:52 offset1:54
	ds_read2_b64 v[90:93], v129 offset0:80 offset1:82
	ds_read2_b64 v[82:85], v129 offset0:84 offset1:86
	ds_read2_b64 v[78:81], v127 offset0:56 offset1:58
	ds_read2_b64 v[74:77], v129 offset0:88 offset1:90
	ds_read2_b64 v[70:73], v127 offset0:60 offset1:62
	ds_read2_b64 v[66:69], v129 offset0:92 offset1:94
	v_max_f32_e32 v98, v51, v51
	v_max_f32_e32 v99, v50, v50
	v_max_f32_e32 v98, v99, v98
	v_max3_f32 v98, v98, v52, v53
	v_max3_f32 v98, v98, v54, v55
	v_max3_f32 v98, v98, v56, v57
	v_max3_f32 v98, v98, v58, v59
	v_max3_f32 v98, v98, v60, v61
	v_max3_f32 v98, v98, v62, v63
	v_max3_f32 v98, v98, v64, v65
	v_max3_f32 v98, v98, v34, v35
	v_max3_f32 v98, v98, v36, v37
	v_max3_f32 v98, v98, v38, v39
	v_max3_f32 v98, v98, v40, v41
	v_max3_f32 v98, v98, v42, v43
	v_max3_f32 v98, v98, v44, v45
	v_max3_f32 v98, v98, v46, v47
	v_max3_f32 v98, v98, v48, v49
	ds_bpermute_b32 v99, v131, v98
	s_waitcnt lgkmcnt(0)
	v_max_f32_e32 v99, v99, v99
	v_max_f32_e32 v98, v98, v99
	v_cmp_gt_f32_e32 vcc, v98, v125
	s_cbranch_vccz .LBB0_895
	v_max_f32_e32 v98, v98, v98
	v_max_f32_e32 v99, v125, v125
	v_max_f32_e32 v99, v99, v98
	v_sub_f32_e32 v98, v125, v99
	v_exp_f32_e32 v98, v98
	v_mov_b32_e32 v125, v99
	v_mul_f32_e32 v140, v140, v98
	v_mul_f32_e32 v16, v16, v98
	v_mul_f32_e32 v17, v17, v98
	v_mul_f32_e32 v14, v14, v98
	v_mul_f32_e32 v15, v15, v98
	v_mul_f32_e32 v12, v12, v98
	v_mul_f32_e32 v13, v13, v98
	v_mul_f32_e32 v10, v10, v98
	v_mul_f32_e32 v11, v11, v98
	v_mul_f32_e32 v8, v8, v98
	v_mul_f32_e32 v9, v9, v98
	v_mul_f32_e32 v6, v6, v98
	v_mul_f32_e32 v7, v7, v98
	v_mul_f32_e32 v4, v4, v98
	v_mul_f32_e32 v5, v5, v98
	v_mul_f32_e32 v2, v2, v98
	v_mul_f32_e32 v3, v3, v98
	v_mul_f32_e32 v32, v32, v98
	v_mul_f32_e32 v33, v33, v98
	v_mul_f32_e32 v30, v30, v98
	v_mul_f32_e32 v31, v31, v98
	v_mul_f32_e32 v28, v28, v98
	v_mul_f32_e32 v29, v29, v98
	v_mul_f32_e32 v26, v26, v98
	v_mul_f32_e32 v27, v27, v98
	v_mul_f32_e32 v24, v24, v98
	v_mul_f32_e32 v25, v25, v98
	v_mul_f32_e32 v22, v22, v98
	v_mul_f32_e32 v23, v23, v98
	v_mul_f32_e32 v20, v20, v98
	v_mul_f32_e32 v21, v21, v98
	v_mul_f32_e32 v18, v18, v98
	v_mul_f32_e32 v19, v19, v98
	s_branch .LBB0_895

.LBB0_904:
	s_or_b64 exec, exec, s[14:15]
	v_max_i32_e32 v125, 1, v119
	v_min_i32_e32 v138, v136, v117
	v_sub_u32_e32 v125, v138, v125
	v_add_u32_e32 v125, 1, v125
	v_cvt_f32_i32_e32 v125, v125
	v_lshlrev_b32_e32 v140, 16, v134
	v_and_b32_e32 v141, 0xffff0000, v134
	v_lshlrev_b32_e32 v138, 16, v137
	v_div_scale_f32 v142, s[0:1], v125, v125, 1.0
	v_rcp_f32_e32 v143, v142
	v_and_b32_e32 v139, 0xffff0000, v137
	v_lshlrev_b64 v[6:7], 11, v[6:7]
	v_lshl_add_u64 v[6:7], v[4:5], 0, v[6:7]
	v_fma_f32 v134, -v142, v143, 1.0
	v_fmac_f32_e32 v143, v134, v143
	v_div_scale_f32 v134, vcc, 1.0, v125, 1.0
	v_mul_f32_e32 v137, v134, v143
	v_fma_f32 v144, -v142, v137, v134
	v_fmac_f32_e32 v137, v144, v143
	v_fma_f32 v134, -v142, v137, v134
	v_div_fmas_f32 v134, v134, v143, v137
	v_add_f32_e32 v142, 0, v138
	v_add_f32_e32 v143, 0, v139
	v_div_fixup_f32 v134, v134, v125, 1.0
	v_add_f32_e32 v142, v142, v140
	v_add_f32_e32 v143, v143, v141
	v_lshlrev_b64 v[68:69], 11, v[68:69]
	v_fma_f32 v144, v134, v142, -v140
	v_fma_f32 v145, v134, v143, -v141
	v_max_i32_e32 v134, 1, v136
	v_min_i32_e32 v136, v133, v117
	v_sub_u32_e32 v134, v136, v134
	v_add_u32_e32 v134, 1, v134
	v_cvt_f32_i32_e32 v134, v134
	v_cvt_pk_bf16_f32 v125, v144, v145
	global_store_dword v[6:7], v125, off
	v_lshlrev_b32_e32 v6, 16, v135
	v_div_scale_f32 v136, s[0:1], v134, v134, 1.0
	v_rcp_f32_e32 v137, v136
	v_and_b32_e32 v7, 0xffff0000, v135
	v_max_i32_e32 v133, 1, v133
	v_lshl_add_u64 v[68:69], v[4:5], 0, v[68:69]
	v_fma_f32 v125, -v136, v137, 1.0
	v_fmac_f32_e32 v137, v125, v137
	v_div_scale_f32 v125, vcc, 1.0, v134, 1.0
	v_mul_f32_e32 v135, v125, v137
	v_fma_f32 v144, -v136, v135, v125
	v_fmac_f32_e32 v135, v144, v137
	v_fma_f32 v125, -v136, v135, v125
	v_div_fmas_f32 v125, v125, v137, v135
	v_add_f32_e64 v136, v6, -v138
	v_add_f32_e64 v137, v7, -v139
	v_div_fixup_f32 v134, v125, v134, 1.0
	v_add_f32_e32 v136, v142, v136
	v_add_f32_e32 v137, v143, v137
	v_lshlrev_b64 v[66:67], 11, v[66:67]
	v_fma_f32 v135, v134, v137, -v7
	v_fma_f32 v134, v134, v136, -v6
	v_cvt_pk_bf16_f32 v125, v134, v135
	v_min_i32_e32 v134, v132, v117
	v_sub_u32_e32 v133, v134, v133
	v_add_u32_e32 v133, 1, v133
	v_cvt_f32_i32_e32 v133, v133
	global_store_dword v[68:69], v125, off
	v_lshlrev_b32_e32 v68, 16, v130
	v_and_b32_e32 v69, 0xffff0000, v130
	v_div_scale_f32 v134, s[0:1], v133, v133, 1.0
	v_rcp_f32_e32 v135, v134
	v_lshl_add_u64 v[66:67], v[4:5], 0, v[66:67]
	v_lshlrev_b64 v[64:65], 11, v[64:65]
	v_lshl_add_u64 v[64:65], v[4:5], 0, v[64:65]
	v_fma_f32 v125, -v134, v135, 1.0
	v_fmac_f32_e32 v135, v125, v135
	v_div_scale_f32 v125, vcc, 1.0, v133, 1.0
	v_mul_f32_e32 v130, v125, v135
	v_fma_f32 v138, -v134, v130, v125
	v_fmac_f32_e32 v130, v138, v135
	v_fma_f32 v125, -v134, v130, v125
	v_div_fmas_f32 v125, v125, v135, v130
	v_add_f32_e64 v134, v68, -v140
	v_add_f32_e64 v135, v69, -v141
	v_div_fixup_f32 v130, v125, v133, 1.0
	v_add_f32_e32 v134, v136, v134
	v_add_f32_e32 v135, v137, v135
	v_lshlrev_b64 v[62:63], 11, v[62:63]
	v_fma_f32 v136, v130, v134, -v68
	v_fma_f32 v137, v130, v135, -v69
	v_max_i32_e32 v130, 1, v132
	v_min_i32_e32 v132, v129, v117
	v_sub_u32_e32 v130, v132, v130
	v_add_u32_e32 v130, 1, v130
	v_cvt_f32_i32_e32 v130, v130
	v_cvt_pk_bf16_f32 v125, v136, v137
	global_store_dword v[66:67], v125, off
	v_lshlrev_b32_e32 v66, 16, v131
	v_div_scale_f32 v132, s[0:1], v130, v130, 1.0
	v_rcp_f32_e32 v133, v132
	v_and_b32_e32 v67, 0xffff0000, v131
	v_add_f32_e64 v6, v66, -v6
	v_add_f32_e64 v7, v67, -v7
	v_max_i32_e32 v129, 1, v129
	v_fma_f32 v125, -v132, v133, 1.0
	v_fmac_f32_e32 v133, v125, v133
	v_div_scale_f32 v125, vcc, 1.0, v130, 1.0
	v_mul_f32_e32 v131, v125, v133
	v_fma_f32 v136, -v132, v131, v125
	v_fmac_f32_e32 v131, v136, v133
	v_fma_f32 v125, -v132, v131, v125
	v_div_fmas_f32 v125, v125, v133, v131
	v_div_fixup_f32 v130, v125, v130, 1.0
	v_add_f32_e32 v6, v134, v6
	v_add_f32_e32 v7, v135, v7
	v_lshl_add_u64 v[62:63], v[4:5], 0, v[62:63]
	v_fma_f32 v131, v130, v7, -v67
	v_fma_f32 v130, v130, v6, -v66
	v_cvt_pk_bf16_f32 v125, v130, v131
	v_min_i32_e32 v130, v128, v117
	v_sub_u32_e32 v129, v130, v129
	v_add_u32_e32 v129, 1, v129
	v_cvt_f32_i32_e32 v129, v129
	global_store_dword v[64:65], v125, off
	v_lshlrev_b32_e32 v64, 16, v126
	v_and_b32_e32 v65, 0xffff0000, v126
	v_div_scale_f32 v130, s[0:1], v129, v129, 1.0
	v_rcp_f32_e32 v131, v130
	v_add_f32_e64 v68, v64, -v68
	v_add_f32_e64 v69, v65, -v69
	v_lshlrev_b64 v[60:61], 11, v[60:61]
	v_add_f32_e32 v6, v6, v68
	v_add_f32_e32 v7, v7, v69
	v_fma_f32 v125, -v130, v131, 1.0
	v_fmac_f32_e32 v131, v125, v131
	v_div_scale_f32 v125, vcc, 1.0, v129, 1.0
	v_mul_f32_e32 v126, v125, v131
	v_fma_f32 v132, -v130, v126, v125
	v_fmac_f32_e32 v126, v132, v131
	v_fma_f32 v125, -v130, v126, v125
	v_div_fmas_f32 v125, v125, v131, v126
	v_div_fixup_f32 v126, v125, v129, 1.0
	v_fma_f32 v68, v126, v6, -v64
	v_fma_f32 v69, v126, v7, -v65
	v_cvt_pk_bf16_f32 v68, v68, v69
	v_max_i32_e32 v69, 1, v128
	v_min_i32_e32 v125, v124, v117
	v_sub_u32_e32 v69, v125, v69
	v_add_u32_e32 v69, 1, v69
	v_cvt_f32_i32_e32 v69, v69
	global_store_dword v[62:63], v68, off
	v_lshlrev_b32_e32 v62, 16, v127
	v_and_b32_e32 v63, 0xffff0000, v127
	v_div_scale_f32 v125, s[0:1], v69, v69, 1.0
	v_rcp_f32_e32 v126, v125
	v_add_f32_e64 v66, v62, -v66
	v_add_f32_e64 v67, v63, -v67
	v_lshl_add_u64 v[60:61], v[4:5], 0, v[60:61]
	v_add_f32_e32 v6, v6, v66
	v_add_f32_e32 v7, v7, v67
	v_fma_f32 v68, -v125, v126, 1.0
	v_fmac_f32_e32 v126, v68, v126
	v_div_scale_f32 v68, vcc, 1.0, v69, 1.0
	v_mul_f32_e32 v127, v68, v126
	v_fma_f32 v128, -v125, v127, v68
	v_fmac_f32_e32 v127, v128, v126
	v_fma_f32 v68, -v125, v127, v68
	v_div_fmas_f32 v68, v68, v126, v127
	v_div_fixup_f32 v68, v68, v69, 1.0
	v_fma_f32 v66, v68, v6, -v62
	v_fma_f32 v67, v68, v7, -v63
	v_cvt_pk_bf16_f32 v66, v66, v67
	v_max_i32_e32 v67, 1, v124
	v_min_i32_e32 v68, v123, v117
	v_sub_u32_e32 v67, v68, v67
	v_add_u32_e32 v67, 1, v67
	v_cvt_f32_i32_e32 v67, v67
	global_store_dword v[60:61], v66, off
	v_lshlrev_b32_e32 v60, 16, v121
	v_and_b32_e32 v61, 0xffff0000, v121
	v_div_scale_f32 v68, s[0:1], v67, v67, 1.0
	v_rcp_f32_e32 v69, v68
	v_add_f32_e64 v64, v60, -v64
	v_add_f32_e64 v65, v61, -v65
	v_lshlrev_b64 v[58:59], 11, v[58:59]
	v_add_f32_e32 v6, v6, v64
	v_add_f32_e32 v7, v7, v65
	v_fma_f32 v66, -v68, v69, 1.0
	v_fmac_f32_e32 v69, v66, v69
	v_div_scale_f32 v66, vcc, 1.0, v67, 1.0
	v_mul_f32_e32 v121, v66, v69
	v_fma_f32 v124, -v68, v121, v66
	v_fmac_f32_e32 v121, v124, v69
	v_fma_f32 v66, -v68, v121, v66
	v_div_fmas_f32 v66, v66, v69, v121
	v_div_fixup_f32 v66, v66, v67, 1.0
	v_fma_f32 v64, v66, v6, -v60
	v_fma_f32 v65, v66, v7, -v61
	v_cvt_pk_bf16_f32 v64, v64, v65
	v_max_i32_e32 v65, 1, v123
	v_min_i32_e32 v66, v120, v117
	v_sub_u32_e32 v65, v66, v65
	v_add_u32_e32 v65, 1, v65
	v_cvt_f32_i32_e32 v65, v65
	v_lshl_add_u64 v[58:59], v[4:5], 0, v[58:59]
	global_store_dword v[58:59], v64, off
	v_lshlrev_b32_e32 v58, 16, v122
	v_div_scale_f32 v66, s[0:1], v65, v65, 1.0
	v_rcp_f32_e32 v67, v66
	v_and_b32_e32 v59, 0xffff0000, v122
	v_add_f32_e64 v62, v58, -v62
	v_add_f32_e64 v63, v59, -v63
	v_lshlrev_b64 v[56:57], 11, v[56:57]
	v_fma_f32 v64, -v66, v67, 1.0
	v_fmac_f32_e32 v67, v64, v67
	v_div_scale_f32 v64, vcc, 1.0, v65, 1.0
	v_mul_f32_e32 v68, v64, v67
	v_fma_f32 v69, -v66, v68, v64
	v_fmac_f32_e32 v68, v69, v67
	v_fma_f32 v64, -v66, v68, v64
	v_div_fmas_f32 v64, v64, v67, v68
	v_div_fixup_f32 v64, v64, v65, 1.0
	v_add_f32_e32 v6, v6, v62
	v_add_f32_e32 v7, v7, v63
	v_lshl_add_u64 v[56:57], v[4:5], 0, v[56:57]
	v_fma_f32 v62, v64, v6, -v58
	v_fma_f32 v63, v64, v7, -v59
	v_cvt_pk_bf16_f32 v62, v62, v63
	v_max_i32_e32 v63, 1, v120
	v_min_i32_e32 v64, v118, v117
	v_sub_u32_e32 v63, v64, v63
	v_add_u32_e32 v63, 1, v63
	v_cvt_f32_i32_e32 v63, v63
	global_store_dword v[56:57], v62, off
	v_lshlrev_b32_e32 v56, 16, v115
	v_and_b32_e32 v57, 0xffff0000, v115
	v_div_scale_f32 v64, s[0:1], v63, v63, 1.0
	v_rcp_f32_e32 v65, v64
	v_add_f32_e64 v60, v56, -v60
	v_add_f32_e64 v61, v57, -v61
	v_lshlrev_b64 v[54:55], 11, v[54:55]
	v_add_f32_e32 v6, v6, v60
	v_add_f32_e32 v7, v7, v61
	v_fma_f32 v62, -v64, v65, 1.0
	v_fmac_f32_e32 v65, v62, v65
	v_div_scale_f32 v62, vcc, 1.0, v63, 1.0
	v_mul_f32_e32 v66, v62, v65
	v_fma_f32 v67, -v64, v66, v62
	v_fmac_f32_e32 v66, v67, v65
	v_fma_f32 v62, -v64, v66, v62
	v_div_fmas_f32 v62, v62, v65, v66
	v_div_fixup_f32 v62, v62, v63, 1.0
	v_fma_f32 v60, v62, v6, -v56
	v_fma_f32 v61, v62, v7, -v57
	v_cvt_pk_bf16_f32 v60, v60, v61
	v_max_i32_e32 v61, 1, v118
	v_min_i32_e32 v62, v114, v117
	v_sub_u32_e32 v61, v62, v61
	v_add_u32_e32 v61, 1, v61
	v_cvt_f32_i32_e32 v61, v61
	v_lshl_add_u64 v[54:55], v[4:5], 0, v[54:55]
	global_store_dword v[54:55], v60, off
	v_lshlrev_b32_e32 v54, 16, v116
	v_div_scale_f32 v62, s[0:1], v61, v61, 1.0
	v_rcp_f32_e32 v63, v62
	v_and_b32_e32 v55, 0xffff0000, v116
	v_add_f32_e64 v58, v54, -v58
	v_add_f32_e64 v59, v55, -v59
	v_lshlrev_b64 v[52:53], 11, v[52:53]
	v_fma_f32 v60, -v62, v63, 1.0
	v_fmac_f32_e32 v63, v60, v63
	v_div_scale_f32 v60, vcc, 1.0, v61, 1.0
	v_mul_f32_e32 v64, v60, v63
	v_fma_f32 v65, -v62, v64, v60
	v_fmac_f32_e32 v64, v65, v63
	v_fma_f32 v60, -v62, v64, v60
	v_div_fmas_f32 v60, v60, v63, v64
	v_div_fixup_f32 v60, v60, v61, 1.0
	v_add_f32_e32 v6, v6, v58
	v_add_f32_e32 v7, v7, v59
	v_lshl_add_u64 v[52:53], v[4:5], 0, v[52:53]
	v_fma_f32 v58, v60, v6, -v54
	v_fma_f32 v59, v60, v7, -v55
	v_cvt_pk_bf16_f32 v58, v58, v59
	v_max_i32_e32 v59, 1, v114
	v_min_i32_e32 v60, v112, v117
	v_sub_u32_e32 v59, v60, v59
	v_add_u32_e32 v59, 1, v59
	v_cvt_f32_i32_e32 v59, v59
	global_store_dword v[52:53], v58, off
	v_lshlrev_b32_e32 v52, 16, v110
	v_and_b32_e32 v53, 0xffff0000, v110
	v_div_scale_f32 v60, s[0:1], v59, v59, 1.0
	v_rcp_f32_e32 v61, v60
	v_add_f32_e64 v56, v52, -v56
	v_add_f32_e64 v57, v53, -v57
	v_lshlrev_b64 v[50:51], 11, v[50:51]
	v_add_f32_e32 v6, v6, v56
	v_add_f32_e32 v7, v7, v57
	v_fma_f32 v58, -v60, v61, 1.0
	v_fmac_f32_e32 v61, v58, v61
	v_div_scale_f32 v58, vcc, 1.0, v59, 1.0
	v_mul_f32_e32 v62, v58, v61
	v_fma_f32 v63, -v60, v62, v58
	v_fmac_f32_e32 v62, v63, v61
	v_fma_f32 v58, -v60, v62, v58
	v_div_fmas_f32 v58, v58, v61, v62
	v_div_fixup_f32 v58, v58, v59, 1.0
	v_fma_f32 v56, v58, v6, -v52
	v_fma_f32 v57, v58, v7, -v53
	v_cvt_pk_bf16_f32 v56, v56, v57
	v_max_i32_e32 v57, 1, v112
	v_min_i32_e32 v58, v108, v117
	v_sub_u32_e32 v57, v58, v57
	v_add_u32_e32 v57, 1, v57
	v_cvt_f32_i32_e32 v57, v57
	v_lshl_add_u64 v[50:51], v[4:5], 0, v[50:51]
	global_store_dword v[50:51], v56, off
	v_lshlrev_b32_e32 v50, 16, v111
	v_div_scale_f32 v58, s[0:1], v57, v57, 1.0
	v_rcp_f32_e32 v59, v58
	v_and_b32_e32 v51, 0xffff0000, v111
	v_add_f32_e64 v54, v50, -v54
	v_add_f32_e64 v55, v51, -v55
	v_lshlrev_b64 v[48:49], 11, v[48:49]
	v_fma_f32 v56, -v58, v59, 1.0
	v_fmac_f32_e32 v59, v56, v59
	v_div_scale_f32 v56, vcc, 1.0, v57, 1.0
	v_mul_f32_e32 v60, v56, v59
	v_fma_f32 v61, -v58, v60, v56
	v_fmac_f32_e32 v60, v61, v59
	v_fma_f32 v56, -v58, v60, v56
	v_div_fmas_f32 v56, v56, v59, v60
	v_div_fixup_f32 v56, v56, v57, 1.0
	v_add_f32_e32 v6, v6, v54
	v_add_f32_e32 v7, v7, v55
	v_lshl_add_u64 v[48:49], v[4:5], 0, v[48:49]
	v_fma_f32 v54, v56, v6, -v50
	v_fma_f32 v55, v56, v7, -v51
	v_cvt_pk_bf16_f32 v54, v54, v55
	v_max_i32_e32 v55, 1, v108
	v_min_i32_e32 v56, v107, v117
	v_sub_u32_e32 v55, v56, v55
	v_add_u32_e32 v55, 1, v55
	v_cvt_f32_i32_e32 v55, v55
	global_store_dword v[48:49], v54, off
	v_lshlrev_b32_e32 v48, 16, v105
	v_and_b32_e32 v49, 0xffff0000, v105
	v_div_scale_f32 v56, s[0:1], v55, v55, 1.0
	v_rcp_f32_e32 v57, v56
	v_add_f32_e64 v52, v48, -v52
	v_add_f32_e64 v53, v49, -v53
	v_lshlrev_b64 v[46:47], 11, v[46:47]
	v_add_f32_e32 v6, v6, v52
	v_add_f32_e32 v7, v7, v53
	v_fma_f32 v54, -v56, v57, 1.0
	v_fmac_f32_e32 v57, v54, v57
	v_div_scale_f32 v54, vcc, 1.0, v55, 1.0
	v_mul_f32_e32 v58, v54, v57
	v_fma_f32 v59, -v56, v58, v54
	v_fmac_f32_e32 v58, v59, v57
	v_fma_f32 v54, -v56, v58, v54
	v_div_fmas_f32 v54, v54, v57, v58
	v_div_fixup_f32 v54, v54, v55, 1.0
	v_fma_f32 v52, v54, v6, -v48
	v_fma_f32 v53, v54, v7, -v49
	v_cvt_pk_bf16_f32 v52, v52, v53
	v_max_i32_e32 v53, 1, v107
	v_min_i32_e32 v54, v104, v117
	v_sub_u32_e32 v53, v54, v53
	v_add_u32_e32 v53, 1, v53
	v_cvt_f32_i32_e32 v53, v53
	v_lshl_add_u64 v[46:47], v[4:5], 0, v[46:47]
	global_store_dword v[46:47], v52, off
	v_lshlrev_b32_e32 v46, 16, v106
	v_div_scale_f32 v54, s[0:1], v53, v53, 1.0
	v_rcp_f32_e32 v55, v54
	v_and_b32_e32 v47, 0xffff0000, v106
	v_add_f32_e64 v50, v46, -v50
	v_add_f32_e64 v51, v47, -v51
	v_lshlrev_b64 v[44:45], 11, v[44:45]
	v_fma_f32 v52, -v54, v55, 1.0
	v_fmac_f32_e32 v55, v52, v55
	v_div_scale_f32 v52, vcc, 1.0, v53, 1.0
	v_mul_f32_e32 v56, v52, v55
	v_fma_f32 v57, -v54, v56, v52
	v_fmac_f32_e32 v56, v57, v55
	v_fma_f32 v52, -v54, v56, v52
	v_div_fmas_f32 v52, v52, v55, v56
	v_div_fixup_f32 v52, v52, v53, 1.0
	v_add_f32_e32 v6, v6, v50
	v_add_f32_e32 v7, v7, v51
	v_lshl_add_u64 v[44:45], v[4:5], 0, v[44:45]
	v_fma_f32 v50, v52, v6, -v46
	v_fma_f32 v51, v52, v7, -v47
	v_cvt_pk_bf16_f32 v50, v50, v51
	v_max_i32_e32 v51, 1, v104
	v_min_i32_e32 v52, v103, v117
	v_sub_u32_e32 v51, v52, v51
	v_add_u32_e32 v51, 1, v51
	v_cvt_f32_i32_e32 v51, v51
	global_store_dword v[44:45], v50, off
	v_lshlrev_b32_e32 v44, 16, v101
	v_and_b32_e32 v45, 0xffff0000, v101
	v_div_scale_f32 v52, s[0:1], v51, v51, 1.0
	v_rcp_f32_e32 v53, v52
	v_add_f32_e64 v48, v44, -v48
	v_add_f32_e64 v49, v45, -v49
	v_lshlrev_b64 v[42:43], 11, v[42:43]
	v_add_f32_e32 v6, v6, v48
	v_add_f32_e32 v7, v7, v49
	v_fma_f32 v50, -v52, v53, 1.0
	v_fmac_f32_e32 v53, v50, v53
	v_div_scale_f32 v50, vcc, 1.0, v51, 1.0
	v_mul_f32_e32 v54, v50, v53
	v_fma_f32 v55, -v52, v54, v50
	v_fmac_f32_e32 v54, v55, v53
	v_fma_f32 v50, -v52, v54, v50
	v_div_fmas_f32 v50, v50, v53, v54
	v_div_fixup_f32 v50, v50, v51, 1.0
	v_fma_f32 v48, v50, v6, -v44
	v_fma_f32 v49, v50, v7, -v45
	v_cvt_pk_bf16_f32 v48, v48, v49
	v_max_i32_e32 v49, 1, v103
	v_min_i32_e32 v50, v100, v117
	v_sub_u32_e32 v49, v50, v49
	v_add_u32_e32 v49, 1, v49
	v_cvt_f32_i32_e32 v49, v49
	v_lshl_add_u64 v[42:43], v[4:5], 0, v[42:43]
	global_store_dword v[42:43], v48, off
	s_waitcnt vmcnt(0)
	v_lshlrev_b32_e32 v42, 16, v102
	v_div_scale_f32 v50, s[0:1], v49, v49, 1.0
	v_rcp_f32_e32 v51, v50
	v_and_b32_e32 v43, 0xffff0000, v102
	v_add_f32_e64 v46, v42, -v46
	v_add_f32_e64 v47, v43, -v47
	v_lshlrev_b64 v[40:41], 11, v[40:41]
	v_fma_f32 v48, -v50, v51, 1.0
	v_fmac_f32_e32 v51, v48, v51
	v_div_scale_f32 v48, vcc, 1.0, v49, 1.0
	v_mul_f32_e32 v52, v48, v51
	v_fma_f32 v53, -v50, v52, v48
	v_fmac_f32_e32 v52, v53, v51
	v_fma_f32 v48, -v50, v52, v48
	v_div_fmas_f32 v48, v48, v51, v52
	v_div_fixup_f32 v48, v48, v49, 1.0
	v_add_f32_e32 v6, v6, v46
	v_add_f32_e32 v7, v7, v47
	v_lshl_add_u64 v[40:41], v[4:5], 0, v[40:41]
	v_fma_f32 v46, v48, v6, -v42
	v_fma_f32 v47, v48, v7, -v43
	v_cvt_pk_bf16_f32 v46, v46, v47
	v_max_i32_e32 v47, 1, v100
	v_min_i32_e32 v48, v99, v117
	v_sub_u32_e32 v47, v48, v47
	v_add_u32_e32 v47, 1, v47
	v_cvt_f32_i32_e32 v47, v47
	global_store_dword v[40:41], v46, off
	v_lshlrev_b32_e32 v40, 16, v97
	v_and_b32_e32 v41, 0xffff0000, v97
	v_div_scale_f32 v48, s[0:1], v47, v47, 1.0
	v_rcp_f32_e32 v49, v48
	v_add_f32_e64 v44, v40, -v44
	v_add_f32_e64 v45, v41, -v45
	v_lshlrev_b64 v[38:39], 11, v[38:39]
	v_add_f32_e32 v6, v6, v44
	v_add_f32_e32 v7, v7, v45
	v_fma_f32 v46, -v48, v49, 1.0
	v_fmac_f32_e32 v49, v46, v49
	v_div_scale_f32 v46, vcc, 1.0, v47, 1.0
	v_mul_f32_e32 v50, v46, v49
	v_fma_f32 v51, -v48, v50, v46
	v_fmac_f32_e32 v50, v51, v49
	v_fma_f32 v46, -v48, v50, v46
	v_div_fmas_f32 v46, v46, v49, v50
	v_div_fixup_f32 v46, v46, v47, 1.0
	v_fma_f32 v44, v46, v6, -v40
	v_fma_f32 v45, v46, v7, -v41
	v_cvt_pk_bf16_f32 v44, v44, v45
	v_max_i32_e32 v45, 1, v99
	v_min_i32_e32 v46, v96, v117
	v_sub_u32_e32 v45, v46, v45
	v_add_u32_e32 v45, 1, v45
	v_cvt_f32_i32_e32 v45, v45
	v_lshl_add_u64 v[38:39], v[4:5], 0, v[38:39]
	global_store_dword v[38:39], v44, off
	v_lshlrev_b32_e32 v38, 16, v98
	v_div_scale_f32 v46, s[0:1], v45, v45, 1.0
	v_rcp_f32_e32 v47, v46
	v_and_b32_e32 v39, 0xffff0000, v98
	v_add_f32_e64 v42, v38, -v42
	v_add_f32_e64 v43, v39, -v43
	v_lshlrev_b64 v[36:37], 11, v[36:37]
	v_fma_f32 v44, -v46, v47, 1.0
	v_fmac_f32_e32 v47, v44, v47
	v_div_scale_f32 v44, vcc, 1.0, v45, 1.0
	v_mul_f32_e32 v48, v44, v47
	v_fma_f32 v49, -v46, v48, v44
	v_fmac_f32_e32 v48, v49, v47
	v_fma_f32 v44, -v46, v48, v44
	v_div_fmas_f32 v44, v44, v47, v48
	v_div_fixup_f32 v44, v44, v45, 1.0
	v_add_f32_e32 v6, v6, v42
	v_add_f32_e32 v7, v7, v43
	v_lshl_add_u64 v[36:37], v[4:5], 0, v[36:37]
	v_fma_f32 v42, v44, v6, -v38
	v_fma_f32 v43, v44, v7, -v39
	v_cvt_pk_bf16_f32 v42, v42, v43
	v_max_i32_e32 v43, 1, v96
	v_min_i32_e32 v44, v95, v117
	v_sub_u32_e32 v43, v44, v43
	v_add_u32_e32 v43, 1, v43
	v_cvt_f32_i32_e32 v43, v43
	global_store_dword v[36:37], v42, off
	v_lshlrev_b32_e32 v36, 16, v93
	v_and_b32_e32 v37, 0xffff0000, v93
	v_div_scale_f32 v44, s[0:1], v43, v43, 1.0
	v_rcp_f32_e32 v45, v44
	v_add_f32_e64 v40, v36, -v40
	v_add_f32_e64 v41, v37, -v41
	v_lshlrev_b64 v[34:35], 11, v[34:35]
	v_add_f32_e32 v6, v6, v40
	v_add_f32_e32 v7, v7, v41
	v_fma_f32 v42, -v44, v45, 1.0
	v_fmac_f32_e32 v45, v42, v45
	v_div_scale_f32 v42, vcc, 1.0, v43, 1.0
	v_mul_f32_e32 v46, v42, v45
	v_fma_f32 v47, -v44, v46, v42
	v_fmac_f32_e32 v46, v47, v45
	v_fma_f32 v42, -v44, v46, v42
	v_div_fmas_f32 v42, v42, v45, v46
	v_div_fixup_f32 v42, v42, v43, 1.0
	v_fma_f32 v40, v42, v6, -v36
	v_fma_f32 v41, v42, v7, -v37
	v_cvt_pk_bf16_f32 v40, v40, v41
	v_max_i32_e32 v41, 1, v95
	v_min_i32_e32 v42, v92, v117
	v_sub_u32_e32 v41, v42, v41
	v_add_u32_e32 v41, 1, v41
	v_cvt_f32_i32_e32 v41, v41
	v_lshl_add_u64 v[34:35], v[4:5], 0, v[34:35]
	global_store_dword v[34:35], v40, off
	v_lshlrev_b32_e32 v34, 16, v94
	v_div_scale_f32 v42, s[0:1], v41, v41, 1.0
	v_rcp_f32_e32 v43, v42
	v_and_b32_e32 v35, 0xffff0000, v94
	v_add_f32_e64 v38, v34, -v38
	v_add_f32_e64 v39, v35, -v39
	v_lshlrev_b64 v[32:33], 11, v[32:33]
	v_fma_f32 v40, -v42, v43, 1.0
	v_fmac_f32_e32 v43, v40, v43
	v_div_scale_f32 v40, vcc, 1.0, v41, 1.0
	v_mul_f32_e32 v44, v40, v43
	v_fma_f32 v45, -v42, v44, v40
	v_fmac_f32_e32 v44, v45, v43
	v_fma_f32 v40, -v42, v44, v40
	v_div_fmas_f32 v40, v40, v43, v44
	v_div_fixup_f32 v40, v40, v41, 1.0
	v_add_f32_e32 v6, v6, v38
	v_add_f32_e32 v7, v7, v39
	v_lshl_add_u64 v[32:33], v[4:5], 0, v[32:33]
	v_fma_f32 v38, v40, v6, -v34
	v_fma_f32 v39, v40, v7, -v35
	v_cvt_pk_bf16_f32 v38, v38, v39
	v_max_i32_e32 v39, 1, v92
	v_min_i32_e32 v40, v91, v117
	v_sub_u32_e32 v39, v40, v39
	v_add_u32_e32 v39, 1, v39
	v_cvt_f32_i32_e32 v39, v39
	global_store_dword v[32:33], v38, off
	v_lshlrev_b32_e32 v32, 16, v89
	v_and_b32_e32 v33, 0xffff0000, v89
	v_div_scale_f32 v40, s[0:1], v39, v39, 1.0
	v_rcp_f32_e32 v41, v40
	v_add_f32_e64 v36, v32, -v36
	v_add_f32_e64 v37, v33, -v37
	v_lshlrev_b64 v[30:31], 11, v[30:31]
	v_add_f32_e32 v6, v6, v36
	v_add_f32_e32 v7, v7, v37
	v_fma_f32 v38, -v40, v41, 1.0
	v_fmac_f32_e32 v41, v38, v41
	v_div_scale_f32 v38, vcc, 1.0, v39, 1.0
	v_mul_f32_e32 v42, v38, v41
	v_fma_f32 v43, -v40, v42, v38
	v_fmac_f32_e32 v42, v43, v41
	v_fma_f32 v38, -v40, v42, v38
	v_div_fmas_f32 v38, v38, v41, v42
	v_div_fixup_f32 v38, v38, v39, 1.0
	v_fma_f32 v36, v38, v6, -v32
	v_fma_f32 v37, v38, v7, -v33
	v_cvt_pk_bf16_f32 v36, v36, v37
	v_max_i32_e32 v37, 1, v91
	v_min_i32_e32 v38, v88, v117
	v_sub_u32_e32 v37, v38, v37
	v_add_u32_e32 v37, 1, v37
	v_cvt_f32_i32_e32 v37, v37
	v_lshl_add_u64 v[30:31], v[4:5], 0, v[30:31]
	global_store_dword v[30:31], v36, off
	v_lshlrev_b32_e32 v30, 16, v90
	v_div_scale_f32 v38, s[0:1], v37, v37, 1.0
	v_rcp_f32_e32 v39, v38
	v_and_b32_e32 v31, 0xffff0000, v90
	v_add_f32_e64 v34, v30, -v34
	v_add_f32_e64 v35, v31, -v35
	v_lshlrev_b64 v[28:29], 11, v[28:29]
	v_fma_f32 v36, -v38, v39, 1.0
	v_fmac_f32_e32 v39, v36, v39
	v_div_scale_f32 v36, vcc, 1.0, v37, 1.0
	v_mul_f32_e32 v40, v36, v39
	v_fma_f32 v41, -v38, v40, v36
	v_fmac_f32_e32 v40, v41, v39
	v_fma_f32 v36, -v38, v40, v36
	v_div_fmas_f32 v36, v36, v39, v40
	v_div_fixup_f32 v36, v36, v37, 1.0
	v_add_f32_e32 v6, v6, v34
	v_add_f32_e32 v7, v7, v35
	v_lshl_add_u64 v[28:29], v[4:5], 0, v[28:29]
	v_fma_f32 v34, v36, v6, -v30
	v_fma_f32 v35, v36, v7, -v31
	v_cvt_pk_bf16_f32 v34, v34, v35
	v_max_i32_e32 v35, 1, v88
	v_min_i32_e32 v36, v87, v117
	v_sub_u32_e32 v35, v36, v35
	v_add_u32_e32 v35, 1, v35
	v_cvt_f32_i32_e32 v35, v35
	global_store_dword v[28:29], v34, off
	v_lshlrev_b32_e32 v28, 16, v84
	v_and_b32_e32 v29, 0xffff0000, v84
	v_div_scale_f32 v36, s[0:1], v35, v35, 1.0
	v_rcp_f32_e32 v37, v36
	v_add_f32_e64 v32, v28, -v32
	v_add_f32_e64 v33, v29, -v33
	v_lshlrev_b64 v[26:27], 11, v[26:27]
	v_add_f32_e32 v6, v6, v32
	v_add_f32_e32 v7, v7, v33
	v_fma_f32 v34, -v36, v37, 1.0
	v_fmac_f32_e32 v37, v34, v37
	v_div_scale_f32 v34, vcc, 1.0, v35, 1.0
	v_mul_f32_e32 v38, v34, v37
	v_fma_f32 v39, -v36, v38, v34
	v_fmac_f32_e32 v38, v39, v37
	v_fma_f32 v34, -v36, v38, v34
	v_div_fmas_f32 v34, v34, v37, v38
	v_div_fixup_f32 v34, v34, v35, 1.0
	v_fma_f32 v32, v34, v6, -v28
	v_fma_f32 v33, v34, v7, -v29
	v_cvt_pk_bf16_f32 v32, v32, v33
	v_max_i32_e32 v33, 1, v87
	v_min_i32_e32 v34, v83, v117
	v_sub_u32_e32 v33, v34, v33
	v_add_u32_e32 v33, 1, v33
	v_cvt_f32_i32_e32 v33, v33
	v_lshl_add_u64 v[26:27], v[4:5], 0, v[26:27]
	global_store_dword v[26:27], v32, off
	v_lshlrev_b32_e32 v26, 16, v86
	v_div_scale_f32 v34, s[0:1], v33, v33, 1.0
	v_rcp_f32_e32 v35, v34
	v_and_b32_e32 v27, 0xffff0000, v86
	v_add_f32_e64 v30, v26, -v30
	v_add_f32_e64 v31, v27, -v31
	v_lshlrev_b64 v[24:25], 11, v[24:25]
	v_fma_f32 v32, -v34, v35, 1.0
	v_fmac_f32_e32 v35, v32, v35
	v_div_scale_f32 v32, vcc, 1.0, v33, 1.0
	v_mul_f32_e32 v36, v32, v35
	v_fma_f32 v37, -v34, v36, v32
	v_fmac_f32_e32 v36, v37, v35
	v_fma_f32 v32, -v34, v36, v32
	v_div_fmas_f32 v32, v32, v35, v36
	v_div_fixup_f32 v32, v32, v33, 1.0
	v_add_f32_e32 v6, v6, v30
	v_add_f32_e32 v7, v7, v31
	v_lshl_add_u64 v[24:25], v[4:5], 0, v[24:25]
	v_fma_f32 v30, v32, v6, -v26
	v_fma_f32 v31, v32, v7, -v27
	v_cvt_pk_bf16_f32 v30, v30, v31
	v_max_i32_e32 v31, 1, v83
	v_min_i32_e32 v32, v81, v117
	v_sub_u32_e32 v31, v32, v31
	v_add_u32_e32 v31, 1, v31
	v_cvt_f32_i32_e32 v32, v31
	global_store_dword v[24:25], v30, off
	v_lshlrev_b32_e32 v24, 16, v80
	v_and_b32_e32 v25, 0xffff0000, v80
	v_div_scale_f32 v33, s[0:1], v32, v32, 1.0
	v_rcp_f32_e32 v34, v33
	v_add_f32_e64 v28, v24, -v28
	v_add_f32_e64 v29, v25, -v29
	v_lshlrev_b64 v[20:21], 11, v[20:21]
	v_add_f32_e32 v6, v6, v28
	v_add_f32_e32 v7, v7, v29
	v_fma_f32 v35, -v33, v34, 1.0
	v_fmac_f32_e32 v34, v35, v34
	v_div_scale_f32 v35, vcc, 1.0, v32, 1.0
	v_mul_f32_e32 v36, v35, v34
	v_fma_f32 v37, -v33, v36, v35
	v_fmac_f32_e32 v36, v37, v34
	v_fma_f32 v33, -v33, v36, v35
	v_div_fmas_f32 v33, v33, v34, v36
	v_div_fixup_f32 v32, v33, v32, 1.0
	v_max_i32_e32 v33, 1, v81
	v_min_i32_e32 v34, v78, v117
	v_sub_u32_e32 v33, v34, v33
	v_add_u32_e32 v33, 1, v33
	v_cvt_f32_i32_e32 v33, v33
	v_lshl_add_u64 v[20:21], v[4:5], 0, v[20:21]
	v_and_b32_e32 v37, 0xffff0000, v82
	v_lshlrev_b32_e32 v34, 16, v82
	v_div_scale_f32 v35, s[0:1], v33, v33, 1.0
	v_rcp_f32_e32 v38, v35
	v_lshlrev_b64 v[22:23], 11, v[22:23]
	v_lshl_add_u64 v[22:23], v[4:5], 0, v[22:23]
	v_lshlrev_b32_e32 v30, 16, v85
	v_fma_f32 v39, -v35, v38, 1.0
	v_fmac_f32_e32 v38, v39, v38
	v_div_scale_f32 v39, vcc, 1.0, v33, 1.0
	v_mul_f32_e32 v40, v39, v38
	v_fma_f32 v41, -v35, v40, v39
	v_fmac_f32_e32 v40, v41, v38
	v_fma_f32 v35, -v35, v40, v39
	v_div_fmas_f32 v35, v35, v38, v40
	v_div_fixup_f32 v38, v35, v33, 1.0
	v_max_i32_e32 v33, 1, v78
	v_min_i32_e32 v35, v76, v117
	v_sub_u32_e32 v33, v35, v33
	v_add_u32_e32 v33, 1, v33
	v_cvt_f32_i32_e32 v33, v33
	v_and_b32_e32 v31, 0xffff0000, v85
	v_lshlrev_b64 v[18:19], 11, v[18:19]
	v_lshl_add_u64 v[18:19], v[4:5], 0, v[18:19]
	v_div_scale_f32 v35, s[0:1], v33, v33, 1.0
	v_rcp_f32_e32 v39, v35
	v_fma_f32 v28, v32, v6, -v24
	v_fma_f32 v29, v32, v7, -v25
	v_cvt_pk_bf16_f32 v28, v28, v29
	global_store_dword v[20:21], v28, off
	v_fma_f32 v20, -v35, v39, 1.0
	v_fmac_f32_e32 v39, v20, v39
	v_div_scale_f32 v20, vcc, 1.0, v33, 1.0
	v_mul_f32_e32 v21, v20, v39
	v_fma_f32 v28, -v35, v21, v20
	v_fmac_f32_e32 v21, v28, v39
	v_fma_f32 v20, -v35, v21, v20
	v_mov_b32_e32 v35, v37
	v_add_f32_e64 v26, v34, -v26
	v_add_f32_e64 v27, v35, -v27
	v_div_fmas_f32 v20, v20, v39, v21
	v_add_f32_e32 v6, v6, v26
	v_add_f32_e32 v7, v7, v27
	v_div_fixup_f32 v20, v20, v33, 1.0
	v_fma_f32 v26, v38, v6, -v34
	v_fma_f32 v27, v38, v7, -v35
	v_cvt_pk_bf16_f32 v21, v26, v27
	global_store_dword v[22:23], v21, off
	v_max_i32_e32 v21, 1, v76
	v_min_i32_e32 v22, v75, v117
	v_sub_u32_e32 v21, v22, v21
	v_add_u32_e32 v21, 1, v21
	v_cvt_f32_i32_e32 v26, v21
	v_add_f32_e64 v22, v30, -v24
	v_add_f32_e64 v23, v31, -v25
	v_and_b32_e32 v36, 0xffff0000, v79
	v_add_f32_e32 v6, v6, v22
	v_add_f32_e32 v7, v7, v23
	v_div_scale_f32 v22, s[0:1], v26, v26, 1.0
	v_rcp_f32_e32 v23, v22
	v_fma_f32 v21, v20, v7, -v31
	v_fma_f32 v20, v20, v6, -v30
	v_cvt_pk_bf16_f32 v20, v20, v21
	global_store_dword v[18:19], v20, off
	v_fma_f32 v18, -v22, v23, 1.0
	v_fmac_f32_e32 v23, v18, v23
	v_div_scale_f32 v18, vcc, 1.0, v26, 1.0
	v_mul_f32_e32 v19, v18, v23
	v_fma_f32 v20, -v22, v19, v18
	v_fmac_f32_e32 v19, v20, v23
	v_fma_f32 v18, -v22, v19, v18
	v_div_fmas_f32 v18, v18, v23, v19
	v_max_i32_e32 v19, 1, v75
	v_min_i32_e32 v20, v73, v117
	v_sub_u32_e32 v19, v20, v19
	v_add_u32_e32 v19, 1, v19
	v_cvt_f32_i32_e32 v19, v19
	v_div_fixup_f32 v18, v18, v26, 1.0
	v_lshlrev_b32_e32 v29, 16, v79
	v_lshlrev_b32_e32 v28, 16, v74
	v_div_scale_f32 v24, s[0:1], v19, v19, 1.0
	v_rcp_f32_e32 v25, v24
	v_lshlrev_b64 v[16:17], 11, v[16:17]
	v_lshl_add_u64 v[16:17], v[4:5], 0, v[16:17]
	v_lshlrev_b32_e32 v20, 16, v72
	v_fma_f32 v26, -v24, v25, 1.0
	v_fmac_f32_e32 v25, v26, v25
	v_div_scale_f32 v26, vcc, 1.0, v19, 1.0
	v_mul_f32_e32 v27, v26, v25
	v_fma_f32 v32, -v24, v27, v26
	v_fmac_f32_e32 v27, v32, v25
	v_fma_f32 v24, -v24, v27, v26
	v_div_fmas_f32 v24, v24, v25, v27
	v_div_fixup_f32 v24, v24, v19, 1.0
	v_max_i32_e32 v19, 1, v73
	v_min_i32_e32 v25, v70, v117
	v_sub_u32_e32 v19, v25, v19
	v_add_u32_e32 v19, 1, v19
	v_pk_mov_b32 v[26:27], v[28:29], v[36:37] op_sel:[1,0]
	v_cvt_f32_i32_e32 v25, v19
	v_add_f32_e64 v32, v26, -v34
	v_add_f32_e64 v33, v27, -v35
	v_and_b32_e32 v21, 0xffff0000, v72
	v_add_f32_e32 v6, v6, v32
	v_add_f32_e32 v7, v7, v33
	v_add_f32_e64 v30, v20, -v30
	v_add_f32_e64 v31, v21, -v31
	v_fma_f32 v19, v18, v7, -v27
	v_fma_f32 v18, v18, v6, -v26
	v_cvt_pk_bf16_f32 v18, v18, v19
	v_div_scale_f32 v19, s[0:1], v25, v25, 1.0
	v_rcp_f32_e32 v32, v19
	global_store_dword v[16:17], v18, off
	v_add_f32_e32 v6, v6, v30
	v_add_f32_e32 v7, v7, v31
	v_lshlrev_b64 v[14:15], 11, v[14:15]
	v_fma_f32 v16, -v19, v32, 1.0
	v_fmac_f32_e32 v32, v16, v32
	v_div_scale_f32 v16, vcc, 1.0, v25, 1.0
	v_mul_f32_e32 v18, v16, v32
	v_fma_f32 v33, -v19, v18, v16
	v_fmac_f32_e32 v18, v33, v32
	v_fma_f32 v16, -v19, v18, v16
	v_div_fmas_f32 v16, v16, v32, v18
	v_div_fixup_f32 v18, v16, v25, 1.0
	v_max_i32_e32 v16, 1, v70
	v_min_i32_e32 v19, v0, v117
	v_sub_u32_e32 v16, v19, v16
	v_add_u32_e32 v16, 1, v16
	v_cvt_f32_i32_e32 v16, v16
	v_fma_f32 v25, v24, v7, -v21
	v_fma_f32 v24, v24, v6, -v20
	v_lshl_add_u64 v[14:15], v[4:5], 0, v[14:15]
	v_cvt_pk_bf16_f32 v24, v24, v25
	v_div_scale_f32 v19, s[0:1], v16, v16, 1.0
	v_rcp_f32_e32 v30, v19
	global_store_dword v[14:15], v24, off
	v_and_b32_e32 v29, 0xffff0000, v74
	v_lshlrev_b64 v[12:13], 11, v[12:13]
	v_fma_f32 v14, -v19, v30, 1.0
	v_fmac_f32_e32 v30, v14, v30
	v_div_scale_f32 v14, vcc, 1.0, v16, 1.0
	v_mul_f32_e32 v15, v14, v30
	v_fma_f32 v24, -v19, v15, v14
	v_fmac_f32_e32 v15, v24, v30
	v_add_f32_e64 v24, v28, -v26
	v_add_f32_e64 v25, v29, -v27
	v_fma_f32 v14, -v19, v15, v14
	v_add_f32_e32 v6, v6, v24
	v_add_f32_e32 v7, v7, v25
	v_lshl_add_u64 v[12:13], v[4:5], 0, v[12:13]
	v_fma_f32 v19, v18, v7, -v29
	v_fma_f32 v18, v18, v6, -v28
	v_div_fmas_f32 v14, v14, v30, v15
	v_cvt_pk_bf16_f32 v15, v18, v19
	global_store_dword v[12:13], v15, off
	v_add_u32_e32 v12, 32, v119
	v_max_i32_e32 v0, 1, v0
	v_min_i32_e32 v12, v12, v117
	v_sub_u32_e32 v0, v12, v0
	v_add_u32_e32 v0, 1, v0
	v_cvt_f32_i32_e32 v0, v0
	v_lshlrev_b32_e32 v22, 16, v77
	v_and_b32_e32 v23, 0xffff0000, v77
	v_add_f32_e64 v12, v22, -v20
	v_add_f32_e64 v13, v23, -v21
	v_div_scale_f32 v15, s[0:1], v0, v0, 1.0
	v_rcp_f32_e32 v18, v15
	v_div_fixup_f32 v14, v14, v16, 1.0
	v_add_f32_e32 v6, v6, v12
	v_add_f32_e32 v7, v7, v13
	v_lshlrev_b64 v[10:11], 11, v[10:11]
	v_fma_f32 v12, v14, v6, -v22
	v_fma_f32 v13, v14, v7, -v23
	v_lshl_add_u64 v[10:11], v[4:5], 0, v[10:11]
	v_cvt_pk_bf16_f32 v12, v12, v13
	global_store_dword v[10:11], v12, off
	v_fma_f32 v10, -v15, v18, 1.0
	v_fmac_f32_e32 v18, v10, v18
	v_div_scale_f32 v10, vcc, 1.0, v0, 1.0
	v_mul_f32_e32 v11, v10, v18
	v_fma_f32 v12, -v15, v11, v10
	v_fmac_f32_e32 v11, v12, v18
	v_fma_f32 v10, -v15, v11, v10
	v_and_b32_e32 v17, 0xffff0000, v71
	v_lshlrev_b32_e32 v16, 16, v71
	v_div_fmas_f32 v10, v10, v18, v11
	v_div_fixup_f32 v0, v10, v0, 1.0
	v_add_f32_e64 v10, v16, -v28
	v_add_f32_e64 v11, v17, -v29
	s_nop 0
	v_add_f32_e32 v6, v6, v10
	v_add_f32_e32 v7, v7, v11
	s_nop 0
	v_fma_f32 v10, v0, v6, -v16
	v_fma_f32 v11, v0, v7, -v17

.LBB0_987:
	s_or_b64 exec, exec, s[20:21]
	v_lshlrev_b32_e32 v150, 16, v70
	v_and_b32_e32 v151, 0xffff0000, v70
	v_lshlrev_b32_e32 v156, 16, v7
	v_and_b32_e32 v157, 0xffff0000, v7
	v_max_i32_e32 v7, 4, v119
	v_min_i32_e32 v70, v135, v117
	v_sub_u32_e32 v7, v70, v7
	v_add_u32_e32 v7, 4, v7
	v_cvt_f32_i32_e32 v7, v7
	v_lshlrev_b32_e32 v154, 16, v73
	v_and_b32_e32 v155, 0xffff0000, v73
	v_lshlrev_b32_e32 v148, 16, v71
	v_div_scale_f32 v73, s[0:1], v7, v7, 1.0
	v_rcp_f32_e32 v158, v73
	v_and_b32_e32 v149, 0xffff0000, v71
	v_lshlrev_b32_e32 v70, 16, v146
	v_and_b32_e32 v71, 0xffff0000, v146
	v_fma_f32 v146, -v73, v158, 1.0
	v_fmac_f32_e32 v158, v146, v158
	v_div_scale_f32 v146, vcc, 1.0, v7, 1.0
	v_lshlrev_b32_e32 v152, 16, v74
	v_and_b32_e32 v153, 0xffff0000, v74
	v_lshlrev_b32_e32 v76, 16, v75
	v_and_b32_e32 v77, 0xffff0000, v75
	v_lshlrev_b32_e32 v74, 16, v147
	v_and_b32_e32 v75, 0xffff0000, v147
	v_mul_f32_e32 v147, v146, v158
	v_fma_f32 v159, -v73, v147, v146
	v_fmac_f32_e32 v147, v159, v158
	v_fma_f32 v73, -v73, v147, v146
	v_div_fmas_f32 v73, v73, v158, v147
	v_add_f32_e32 v158, 0, v148
	v_add_f32_e32 v159, 0, v149
	v_div_fixup_f32 v146, v73, v7, 1.0
	v_add_f32_e32 v158, v158, v150
	v_add_f32_e32 v159, v159, v151
	v_max_i32_e32 v72, 4, v72
	v_add_f32_e32 v158, v158, v152
	v_add_f32_e32 v159, v159, v153
	v_min_i32_e32 v73, v133, v117
	v_add_f32_e32 v158, v158, v154
	v_add_f32_e32 v159, v159, v155
	v_sub_u32_e32 v72, v73, v72
	v_add_f32_e32 v158, v158, v156
	v_add_f32_e32 v159, v159, v157
	v_add_u32_e32 v72, 4, v72
	v_add_f32_e32 v158, v158, v76
	v_add_f32_e32 v159, v159, v77
	v_ashrrev_i32_e32 v7, 31, v6
	v_add_f32_e32 v158, v158, v74
	v_add_f32_e32 v159, v159, v75
	v_max_i32_e32 v140, 4, v140
	v_add_f32_e32 v158, v158, v70
	v_add_f32_e32 v159, v159, v71
	v_lshlrev_b64 v[68:69], 11, v[68:69]
	v_fma_f32 v147, v146, v159, -v157
	v_fma_f32 v146, v146, v158, -v156
	v_cvt_pk_bf16_f32 v146, v146, v147
	v_cvt_f32_i32_e32 v147, v72
	v_lshlrev_b64 v[72:73], 11, v[6:7]
	v_lshl_add_u64 v[72:73], v[4:5], 0, v[72:73]
	global_store_dword v[72:73], v146, off
	v_div_scale_f32 v7, s[0:1], v147, v147, 1.0
	v_rcp_f32_e32 v160, v7
	v_lshlrev_b32_e32 v72, 16, v145
	v_and_b32_e32 v73, 0xffff0000, v145
	v_add_f32_e64 v148, v72, -v148
	v_add_f32_e64 v149, v73, -v149
	v_fma_f32 v145, -v7, v160, 1.0
	v_fmac_f32_e32 v160, v145, v160
	v_div_scale_f32 v145, vcc, 1.0, v147, 1.0
	v_mul_f32_e32 v146, v145, v160
	v_fma_f32 v161, -v7, v146, v145
	v_fmac_f32_e32 v146, v161, v160
	v_fma_f32 v7, -v7, v146, v145
	v_min_i32_e32 v145, v128, v117
	v_sub_u32_e32 v140, v145, v140
	v_add_u32_e32 v140, 4, v140
	v_cvt_f32_i32_e32 v140, v140
	v_div_fmas_f32 v7, v7, v160, v146
	v_div_fixup_f32 v146, v7, v147, 1.0
	v_add_f32_e32 v148, v158, v148
	v_add_f32_e32 v149, v159, v149
	v_div_scale_f32 v145, s[0:1], v140, v140, 1.0
	v_fma_f32 v147, v146, v149, -v77
	v_fma_f32 v146, v146, v148, -v76
	v_cvt_pk_bf16_f32 v7, v146, v147
	v_rcp_f32_e32 v146, v145
	v_lshl_add_u64 v[68:69], v[4:5], 0, v[68:69]
	global_store_dword v[68:69], v7, off
	v_lshlrev_b32_e32 v68, 16, v143
	v_fma_f32 v7, -v145, v146, 1.0
	v_fmac_f32_e32 v146, v7, v146
	v_div_scale_f32 v7, vcc, 1.0, v140, 1.0
	v_and_b32_e32 v69, 0xffff0000, v143
	v_mul_f32_e32 v143, v7, v146
	v_fma_f32 v147, -v145, v143, v7
	v_fmac_f32_e32 v143, v147, v146
	v_fma_f32 v7, -v145, v143, v7
	v_div_fmas_f32 v7, v7, v146, v143
	v_add_f32_e64 v146, v68, -v150
	v_add_f32_e64 v147, v69, -v151
	v_div_fixup_f32 v140, v7, v140, 1.0
	v_add_f32_e32 v146, v148, v146
	v_add_f32_e32 v147, v149, v147
	v_max_i32_e32 v139, 4, v139
	v_fma_f32 v148, v140, v146, -v74
	v_fma_f32 v149, v140, v147, -v75
	v_min_i32_e32 v140, v126, v117
	v_sub_u32_e32 v139, v140, v139
	v_add_u32_e32 v139, 4, v139
	v_cvt_f32_i32_e32 v139, v139
	v_lshlrev_b64 v[66:67], 11, v[66:67]
	v_cvt_pk_bf16_f32 v7, v148, v149
	v_lshl_add_u64 v[66:67], v[4:5], 0, v[66:67]
	v_div_scale_f32 v140, s[0:1], v139, v139, 1.0
	v_rcp_f32_e32 v143, v140
	global_store_dword v[66:67], v7, off
	v_lshlrev_b32_e32 v66, 16, v144
	v_and_b32_e32 v67, 0xffff0000, v144
	v_fma_f32 v7, -v140, v143, 1.0
	v_fmac_f32_e32 v143, v7, v143
	v_div_scale_f32 v7, vcc, 1.0, v139, 1.0
	v_mul_f32_e32 v144, v7, v143
	v_fma_f32 v145, -v140, v144, v7
	v_fmac_f32_e32 v144, v145, v143
	v_fma_f32 v7, -v140, v144, v7
	v_div_fmas_f32 v7, v7, v143, v144
	v_div_fixup_f32 v140, v7, v139, 1.0
	v_max_i32_e32 v135, 4, v135
	v_min_i32_e32 v139, v121, v117
	v_sub_u32_e32 v135, v139, v135
	v_add_u32_e32 v135, 4, v135
	v_cvt_f32_i32_e32 v135, v135
	v_add_f32_e64 v144, v66, -v152
	v_add_f32_e64 v145, v67, -v153
	v_lshlrev_b64 v[64:65], 11, v[64:65]
	v_add_f32_e32 v144, v146, v144
	v_add_f32_e32 v145, v147, v145
	v_div_scale_f32 v139, s[0:1], v135, v135, 1.0
	v_fma_f32 v146, v140, v144, -v70
	v_fma_f32 v147, v140, v145, -v71
	v_rcp_f32_e32 v140, v139
	v_cvt_pk_bf16_f32 v7, v146, v147
	v_lshl_add_u64 v[64:65], v[4:5], 0, v[64:65]
	global_store_dword v[64:65], v7, off
	v_fma_f32 v7, -v139, v140, 1.0
	v_fmac_f32_e32 v140, v7, v140
	v_div_scale_f32 v7, vcc, 1.0, v135, 1.0
	v_lshlrev_b32_e32 v64, 16, v141
	v_and_b32_e32 v65, 0xffff0000, v141
	v_mul_f32_e32 v141, v7, v140
	v_fma_f32 v143, -v139, v141, v7
	v_fmac_f32_e32 v141, v143, v140
	v_fma_f32 v7, -v139, v141, v7
	v_div_fmas_f32 v7, v7, v140, v141
	v_div_fixup_f32 v140, v7, v135, 1.0
	v_max_i32_e32 v133, 4, v133
	v_min_i32_e32 v135, v118, v117
	v_sub_u32_e32 v133, v135, v133
	v_add_u32_e32 v133, 4, v133
	v_cvt_f32_i32_e32 v133, v133
	v_add_f32_e64 v146, v64, -v154
	v_add_f32_e64 v147, v65, -v155
	v_lshlrev_b64 v[62:63], 11, v[62:63]
	v_add_f32_e32 v144, v144, v146
	v_add_f32_e32 v145, v145, v147
	v_div_scale_f32 v135, s[0:1], v133, v133, 1.0
	v_rcp_f32_e32 v139, v135
	v_fma_f32 v141, v140, v145, -v73
	v_fma_f32 v140, v140, v144, -v72
	v_cvt_pk_bf16_f32 v7, v140, v141
	v_lshl_add_u64 v[62:63], v[4:5], 0, v[62:63]
	global_store_dword v[62:63], v7, off
	v_fma_f32 v7, -v135, v139, 1.0
	v_fmac_f32_e32 v139, v7, v139
	v_div_scale_f32 v7, vcc, 1.0, v133, 1.0
	v_mul_f32_e32 v140, v7, v139
	v_fma_f32 v141, -v135, v140, v7
	v_fmac_f32_e32 v140, v141, v139
	v_fma_f32 v7, -v135, v140, v7
	v_div_fmas_f32 v7, v7, v139, v140
	v_div_fixup_f32 v140, v7, v133, 1.0
	v_max_i32_e32 v128, 4, v128
	v_min_i32_e32 v133, v114, v117
	v_sub_u32_e32 v128, v133, v128
	v_add_u32_e32 v128, 4, v128
	v_cvt_f32_i32_e32 v128, v128
	v_lshlrev_b32_e32 v62, 16, v142
	v_and_b32_e32 v63, 0xffff0000, v142
	v_add_f32_e64 v142, v62, -v156
	v_add_f32_e64 v143, v63, -v157
	v_div_scale_f32 v133, s[0:1], v128, v128, 1.0
	v_rcp_f32_e32 v135, v133
	v_add_f32_e32 v142, v144, v142
	v_add_f32_e32 v143, v145, v143
	v_lshlrev_b64 v[60:61], 11, v[60:61]
	v_fma_f32 v141, v140, v143, -v69
	v_fma_f32 v140, v140, v142, -v68
	v_cvt_pk_bf16_f32 v7, v140, v141
	v_lshl_add_u64 v[60:61], v[4:5], 0, v[60:61]
	global_store_dword v[60:61], v7, off
	v_fma_f32 v7, -v133, v135, 1.0
	v_fmac_f32_e32 v135, v7, v135
	v_div_scale_f32 v7, vcc, 1.0, v128, 1.0
	v_lshlrev_b32_e32 v60, 16, v137
	v_and_b32_e32 v61, 0xffff0000, v137
	v_mul_f32_e32 v137, v7, v135
	v_fma_f32 v139, -v133, v137, v7
	v_fmac_f32_e32 v137, v139, v135
	v_fma_f32 v7, -v133, v137, v7
	v_div_fmas_f32 v7, v7, v135, v137
	v_add_f32_e64 v76, v60, -v76
	v_add_f32_e64 v77, v61, -v77
	v_div_fixup_f32 v128, v7, v128, 1.0
	v_add_f32_e32 v76, v142, v76
	v_add_f32_e32 v77, v143, v77
	v_max_i32_e32 v126, 4, v126
	s_waitcnt vmcnt(0)
	v_fma_f32 v140, v128, v76, -v66
	v_fma_f32 v141, v128, v77, -v67
	v_min_i32_e32 v128, v112, v117
	v_sub_u32_e32 v126, v128, v126
	v_add_u32_e32 v126, 4, v126
	v_cvt_f32_i32_e32 v126, v126
	v_lshlrev_b64 v[58:59], 11, v[58:59]
	v_cvt_pk_bf16_f32 v7, v140, v141
	v_lshl_add_u64 v[58:59], v[4:5], 0, v[58:59]
	v_div_scale_f32 v128, s[0:1], v126, v126, 1.0
	v_rcp_f32_e32 v133, v128
	global_store_dword v[58:59], v7, off
	v_lshlrev_b32_e32 v58, 16, v138
	v_and_b32_e32 v59, 0xffff0000, v138
	v_fma_f32 v7, -v128, v133, 1.0
	v_fmac_f32_e32 v133, v7, v133
	v_div_scale_f32 v7, vcc, 1.0, v126, 1.0
	v_mul_f32_e32 v135, v7, v133
	v_fma_f32 v137, -v128, v135, v7
	v_fmac_f32_e32 v135, v137, v133
	v_fma_f32 v7, -v128, v135, v7
	v_div_fmas_f32 v7, v7, v133, v135
	v_add_f32_e64 v74, v58, -v74
	v_add_f32_e64 v75, v59, -v75
	v_div_fixup_f32 v126, v7, v126, 1.0
	v_add_f32_e32 v74, v76, v74
	v_add_f32_e32 v75, v77, v75
	v_lshlrev_b64 v[56:57], 11, v[56:57]
	v_fma_f32 v76, v126, v74, -v64
	v_fma_f32 v77, v126, v75, -v65
	v_cvt_pk_bf16_f32 v7, v76, v77
	v_max_i32_e32 v76, 4, v121
	v_min_i32_e32 v77, v108, v117
	v_sub_u32_e32 v76, v77, v76
	v_add_u32_e32 v76, 4, v76
	v_cvt_f32_i32_e32 v76, v76
	v_lshl_add_u64 v[56:57], v[4:5], 0, v[56:57]
	global_store_dword v[56:57], v7, off
	v_lshlrev_b32_e32 v56, 16, v130
	v_div_scale_f32 v77, s[0:1], v76, v76, 1.0
	v_rcp_f32_e32 v121, v77
	v_and_b32_e32 v57, 0xffff0000, v130
	v_add_f32_e64 v70, v56, -v70
	v_add_f32_e64 v71, v57, -v71
	v_lshlrev_b64 v[54:55], 11, v[54:55]
	v_fma_f32 v7, -v77, v121, 1.0
	v_fmac_f32_e32 v121, v7, v121
	v_div_scale_f32 v7, vcc, 1.0, v76, 1.0
	v_mul_f32_e32 v126, v7, v121
	v_fma_f32 v128, -v77, v126, v7
	v_fmac_f32_e32 v126, v128, v121
	v_fma_f32 v7, -v77, v126, v7
	v_div_fmas_f32 v7, v7, v121, v126
	v_div_fixup_f32 v76, v7, v76, 1.0
	v_add_f32_e32 v70, v74, v70
	v_add_f32_e32 v71, v75, v71
	v_lshl_add_u64 v[54:55], v[4:5], 0, v[54:55]
	v_fma_f32 v74, v76, v70, -v62
	v_fma_f32 v75, v76, v71, -v63
	v_cvt_pk_bf16_f32 v7, v74, v75
	v_max_i32_e32 v74, 4, v118
	v_min_i32_e32 v75, v107, v117
	v_sub_u32_e32 v74, v75, v74
	v_add_u32_e32 v74, 4, v74
	v_cvt_f32_i32_e32 v74, v74
	global_store_dword v[54:55], v7, off
	v_lshlrev_b32_e32 v54, 16, v131
	v_and_b32_e32 v55, 0xffff0000, v131
	v_div_scale_f32 v75, s[0:1], v74, v74, 1.0
	v_rcp_f32_e32 v76, v75
	v_add_f32_e64 v72, v54, -v72
	v_add_f32_e64 v73, v55, -v73
	v_lshlrev_b64 v[52:53], 11, v[52:53]
	v_add_f32_e32 v70, v70, v72
	v_add_f32_e32 v71, v71, v73
	v_fma_f32 v7, -v75, v76, 1.0
	v_fmac_f32_e32 v76, v7, v76
	v_div_scale_f32 v7, vcc, 1.0, v74, 1.0
	v_mul_f32_e32 v77, v7, v76
	v_fma_f32 v118, -v75, v77, v7
	v_fmac_f32_e32 v77, v118, v76
	v_fma_f32 v7, -v75, v77, v7
	v_div_fmas_f32 v7, v7, v76, v77
	v_div_fixup_f32 v74, v7, v74, 1.0
	v_fma_f32 v72, v74, v70, -v60
	v_fma_f32 v73, v74, v71, -v61
	v_cvt_pk_bf16_f32 v7, v72, v73
	v_max_i32_e32 v72, 4, v114
	v_min_i32_e32 v73, v104, v117
	v_sub_u32_e32 v72, v73, v72
	v_add_u32_e32 v72, 4, v72
	v_cvt_f32_i32_e32 v72, v72
	v_lshl_add_u64 v[52:53], v[4:5], 0, v[52:53]
	global_store_dword v[52:53], v7, off
	v_lshlrev_b32_e32 v52, 16, v122
	v_div_scale_f32 v73, s[0:1], v72, v72, 1.0
	v_rcp_f32_e32 v74, v73
	v_and_b32_e32 v53, 0xffff0000, v122
	v_add_f32_e64 v68, v52, -v68
	v_add_f32_e64 v69, v53, -v69
	v_lshlrev_b64 v[50:51], 11, v[50:51]
	v_fma_f32 v7, -v73, v74, 1.0
	v_fmac_f32_e32 v74, v7, v74
	v_div_scale_f32 v7, vcc, 1.0, v72, 1.0
	v_mul_f32_e32 v75, v7, v74
	v_fma_f32 v76, -v73, v75, v7
	v_fmac_f32_e32 v75, v76, v74
	v_fma_f32 v7, -v73, v75, v7
	v_div_fmas_f32 v7, v7, v74, v75
	v_div_fixup_f32 v72, v7, v72, 1.0
	v_add_f32_e32 v68, v70, v68
	v_add_f32_e32 v69, v71, v69
	v_lshl_add_u64 v[50:51], v[4:5], 0, v[50:51]
	v_fma_f32 v70, v72, v68, -v58
	v_fma_f32 v71, v72, v69, -v59
	v_cvt_pk_bf16_f32 v7, v70, v71
	v_max_i32_e32 v70, 4, v112
	v_min_i32_e32 v71, v102, v117
	v_sub_u32_e32 v70, v71, v70
	v_add_u32_e32 v70, 4, v70
	v_cvt_f32_i32_e32 v70, v70
	global_store_dword v[50:51], v7, off
	v_lshlrev_b32_e32 v50, 16, v123
	v_and_b32_e32 v51, 0xffff0000, v123
	v_div_scale_f32 v71, s[0:1], v70, v70, 1.0
	v_rcp_f32_e32 v72, v71
	v_add_f32_e64 v66, v50, -v66
	v_add_f32_e64 v67, v51, -v67
	v_lshlrev_b64 v[48:49], 11, v[48:49]
	v_add_f32_e32 v66, v68, v66
	v_add_f32_e32 v67, v69, v67
	v_fma_f32 v7, -v71, v72, 1.0
	v_fmac_f32_e32 v72, v7, v72
	v_div_scale_f32 v7, vcc, 1.0, v70, 1.0
	v_mul_f32_e32 v73, v7, v72
	v_fma_f32 v74, -v71, v73, v7
	v_fmac_f32_e32 v73, v74, v72
	v_fma_f32 v7, -v71, v73, v7
	v_div_fmas_f32 v7, v7, v72, v73
	v_div_fixup_f32 v70, v7, v70, 1.0
	v_fma_f32 v68, v70, v66, -v56
	v_fma_f32 v69, v70, v67, -v57
	v_cvt_pk_bf16_f32 v7, v68, v69
	v_max_i32_e32 v68, 4, v108
	v_min_i32_e32 v69, v86, v117
	v_sub_u32_e32 v68, v69, v68
	v_add_u32_e32 v68, 4, v68
	v_cvt_f32_i32_e32 v68, v68
	v_lshl_add_u64 v[48:49], v[4:5], 0, v[48:49]
	global_store_dword v[48:49], v7, off
	v_lshlrev_b32_e32 v48, 16, v115
	v_div_scale_f32 v69, s[0:1], v68, v68, 1.0
	v_rcp_f32_e32 v70, v69
	v_and_b32_e32 v49, 0xffff0000, v115
	v_add_f32_e64 v64, v48, -v64
	v_add_f32_e64 v65, v49, -v65
	v_lshlrev_b64 v[46:47], 11, v[46:47]
	v_fma_f32 v7, -v69, v70, 1.0
	v_fmac_f32_e32 v70, v7, v70
	v_div_scale_f32 v7, vcc, 1.0, v68, 1.0
	v_mul_f32_e32 v71, v7, v70
	v_fma_f32 v72, -v69, v71, v7
	v_fmac_f32_e32 v71, v72, v70
	v_fma_f32 v7, -v69, v71, v7
	v_div_fmas_f32 v7, v7, v70, v71
	v_div_fixup_f32 v68, v7, v68, 1.0
	v_add_f32_e32 v64, v66, v64
	v_add_f32_e32 v65, v67, v65
	v_lshl_add_u64 v[46:47], v[4:5], 0, v[46:47]
	v_fma_f32 v66, v68, v64, -v54
	v_fma_f32 v67, v68, v65, -v55
	v_cvt_pk_bf16_f32 v7, v66, v67
	v_max_i32_e32 v66, 4, v107
	v_min_i32_e32 v67, v85, v117
	v_sub_u32_e32 v66, v67, v66
	v_add_u32_e32 v66, 4, v66
	v_cvt_f32_i32_e32 v66, v66
	global_store_dword v[46:47], v7, off
	v_lshlrev_b32_e32 v46, 16, v116
	v_and_b32_e32 v47, 0xffff0000, v116
	v_div_scale_f32 v67, s[0:1], v66, v66, 1.0
	v_rcp_f32_e32 v68, v67
	v_add_f32_e64 v62, v46, -v62
	v_add_f32_e64 v63, v47, -v63
	v_lshlrev_b64 v[44:45], 11, v[44:45]
	v_add_f32_e32 v62, v64, v62
	v_add_f32_e32 v63, v65, v63
	v_fma_f32 v7, -v67, v68, 1.0
	v_fmac_f32_e32 v68, v7, v68
	v_div_scale_f32 v7, vcc, 1.0, v66, 1.0
	v_mul_f32_e32 v69, v7, v68
	v_fma_f32 v70, -v67, v69, v7
	v_fmac_f32_e32 v69, v70, v68
	v_fma_f32 v7, -v67, v69, v7
	v_div_fmas_f32 v7, v7, v68, v69
	v_div_fixup_f32 v66, v7, v66, 1.0
	v_fma_f32 v64, v66, v62, -v52
	v_fma_f32 v65, v66, v63, -v53
	v_cvt_pk_bf16_f32 v7, v64, v65
	v_max_i32_e32 v64, 4, v104
	v_min_i32_e32 v65, v84, v117
	v_sub_u32_e32 v64, v65, v64
	v_add_u32_e32 v64, 4, v64
	v_cvt_f32_i32_e32 v64, v64
	v_lshl_add_u64 v[44:45], v[4:5], 0, v[44:45]
	global_store_dword v[44:45], v7, off
	v_lshlrev_b32_e32 v44, 16, v110
	v_div_scale_f32 v65, s[0:1], v64, v64, 1.0
	v_rcp_f32_e32 v66, v65
	v_and_b32_e32 v45, 0xffff0000, v110
	v_add_f32_e64 v60, v44, -v60
	v_add_f32_e64 v61, v45, -v61
	v_lshlrev_b64 v[42:43], 11, v[42:43]
	v_fma_f32 v7, -v65, v66, 1.0
	v_fmac_f32_e32 v66, v7, v66
	v_div_scale_f32 v7, vcc, 1.0, v64, 1.0
	v_mul_f32_e32 v67, v7, v66
	v_fma_f32 v68, -v65, v67, v7
	v_fmac_f32_e32 v67, v68, v66
	v_fma_f32 v7, -v65, v67, v7
	v_div_fmas_f32 v7, v7, v66, v67
	v_div_fixup_f32 v64, v7, v64, 1.0
	v_add_f32_e32 v60, v62, v60
	v_add_f32_e32 v61, v63, v61
	v_lshl_add_u64 v[42:43], v[4:5], 0, v[42:43]
	v_fma_f32 v62, v64, v60, -v50
	v_fma_f32 v63, v64, v61, -v51
	v_cvt_pk_bf16_f32 v7, v62, v63
	v_max_i32_e32 v62, 4, v102
	v_min_i32_e32 v63, v82, v117
	v_sub_u32_e32 v62, v63, v62
	v_add_u32_e32 v62, 4, v62
	v_cvt_f32_i32_e32 v62, v62
	global_store_dword v[42:43], v7, off
	v_lshlrev_b32_e32 v42, 16, v111
	v_and_b32_e32 v43, 0xffff0000, v111
	v_div_scale_f32 v63, s[0:1], v62, v62, 1.0
	v_rcp_f32_e32 v64, v63
	v_add_f32_e64 v58, v42, -v58
	v_add_f32_e64 v59, v43, -v59
	v_lshlrev_b64 v[40:41], 11, v[40:41]
	v_add_f32_e32 v74, v60, v58
	v_add_f32_e32 v75, v61, v59
	v_fma_f32 v7, -v63, v64, 1.0
	v_fmac_f32_e32 v64, v7, v64
	v_div_scale_f32 v7, vcc, 1.0, v62, 1.0
	v_mul_f32_e32 v65, v7, v64
	v_fma_f32 v66, -v63, v65, v7
	v_fmac_f32_e32 v65, v66, v64
	v_fma_f32 v7, -v63, v65, v7
	v_div_fmas_f32 v7, v7, v64, v65
	v_div_fixup_f32 v62, v7, v62, 1.0
	v_fma_f32 v58, v62, v74, -v48
	v_fma_f32 v59, v62, v75, -v49
	v_cvt_pk_bf16_f32 v7, v58, v59
	v_max_i32_e32 v58, 4, v86
	v_min_i32_e32 v59, v78, v117
	v_sub_u32_e32 v58, v59, v58
	v_add_u32_e32 v58, 4, v58
	v_cvt_f32_i32_e32 v60, v58
	v_lshl_add_u64 v[40:41], v[4:5], 0, v[40:41]
	global_store_dword v[40:41], v7, off
	v_lshlrev_b64 v[28:29], 11, v[28:29]
	v_div_scale_f32 v7, s[0:1], v60, v60, 1.0
	v_rcp_f32_e32 v61, v7
	v_lshlrev_b64 v[26:27], 11, v[26:27]
	v_lshlrev_b32_e32 v58, 16, v105
	v_and_b32_e32 v59, 0xffff0000, v105
	v_fma_f32 v62, -v7, v61, 1.0
	v_fmac_f32_e32 v61, v62, v61
	v_div_scale_f32 v62, vcc, 1.0, v60, 1.0
	v_mul_f32_e32 v63, v62, v61
	v_fma_f32 v64, -v7, v63, v62
	v_fmac_f32_e32 v63, v64, v61
	v_fma_f32 v7, -v7, v63, v62
	v_div_fmas_f32 v7, v7, v61, v63
	v_div_fixup_f32 v102, v7, v60, 1.0
	v_max_i32_e32 v7, 4, v85
	v_min_i32_e32 v60, v81, v117
	v_sub_u32_e32 v7, v60, v7
	v_add_u32_e32 v7, 4, v7
	v_cvt_f32_i32_e32 v7, v7
	v_lshlrev_b32_e32 v60, 16, v106
	v_and_b32_e32 v61, 0xffff0000, v106
	v_add_f32_e64 v56, v58, -v56
	v_add_f32_e64 v57, v59, -v57
	v_div_scale_f32 v62, s[0:1], v7, v7, 1.0
	v_rcp_f32_e32 v63, v62
	v_add_f32_e32 v56, v74, v56
	v_add_f32_e32 v57, v75, v57
	v_lshlrev_b64 v[38:39], 11, v[38:39]
	v_fma_f32 v74, v102, v56, -v46
	v_fma_f32 v75, v102, v57, -v47
	v_fma_f32 v64, -v62, v63, 1.0
	v_fmac_f32_e32 v63, v64, v63
	v_div_scale_f32 v64, vcc, 1.0, v7, 1.0
	v_mul_f32_e32 v65, v64, v63
	v_fma_f32 v66, -v62, v65, v64
	v_fmac_f32_e32 v65, v66, v63
	v_fma_f32 v62, -v62, v65, v64
	v_div_fmas_f32 v62, v62, v63, v65
	v_div_fixup_f32 v106, v62, v7, 1.0
	v_max_i32_e32 v7, 4, v84
	v_min_i32_e32 v62, v0, v117
	v_sub_u32_e32 v7, v62, v7
	v_add_u32_e32 v7, 4, v7
	v_cvt_f32_i32_e32 v7, v7
	v_max_i32_e32 v0, 4, v0
	v_lshl_add_u64 v[84:85], v[4:5], 0, v[28:29]
	v_lshlrev_b32_e32 v28, 16, v97
	v_div_scale_f32 v64, s[0:1], v7, v7, 1.0
	v_rcp_f32_e32 v65, v64
	v_and_b32_e32 v29, 0xffff0000, v97
	v_lshl_add_u64 v[104:105], v[4:5], 0, v[38:39]
	v_cvt_pk_bf16_f32 v74, v74, v75
	v_fma_f32 v66, -v64, v65, 1.0
	v_fmac_f32_e32 v65, v66, v65
	v_div_scale_f32 v66, vcc, 1.0, v7, 1.0
	v_mul_f32_e32 v67, v66, v65
	v_fma_f32 v68, -v64, v67, v66
	v_fmac_f32_e32 v67, v68, v65
	v_fma_f32 v64, -v64, v67, v66
	v_div_fmas_f32 v64, v64, v65, v67
	v_div_fixup_f32 v86, v64, v7, 1.0
	v_max_i32_e32 v7, 4, v82
	v_min_i32_e32 v64, v80, v117
	v_sub_u32_e32 v7, v64, v7
	v_add_u32_e32 v7, 4, v7
	v_cvt_f32_i32_e32 v7, v7
	global_store_dword v[104:105], v74, off
	v_add_f32_e64 v54, v60, -v54
	v_add_f32_e64 v55, v61, -v55
	v_lshlrev_b64 v[36:37], 11, v[36:37]
	v_div_scale_f32 v66, s[0:1], v7, v7, 1.0
	v_rcp_f32_e32 v67, v66
	v_add_f32_e32 v54, v56, v54
	v_add_f32_e32 v55, v57, v55
	v_lshl_add_u64 v[110:111], v[4:5], 0, v[36:37]
	v_fma_f32 v56, v106, v54, -v44
	v_fma_f32 v57, v106, v55, -v45
	v_fma_f32 v68, -v66, v67, 1.0
	v_fmac_f32_e32 v67, v68, v67
	v_div_scale_f32 v68, vcc, 1.0, v7, 1.0
	v_mul_f32_e32 v69, v68, v67
	v_fma_f32 v70, -v66, v69, v68
	v_fmac_f32_e32 v69, v70, v67
	v_fma_f32 v66, -v66, v69, v68
	v_div_fmas_f32 v66, v66, v67, v69
	v_div_fixup_f32 v82, v66, v7, 1.0
	v_max_i32_e32 v7, 4, v78
	v_min_i32_e32 v66, v94, v117
	v_sub_u32_e32 v7, v66, v7
	v_add_u32_e32 v7, 4, v7
	v_cvt_f32_i32_e32 v7, v7
	v_lshlrev_b32_e32 v66, 16, v99
	v_and_b32_e32 v67, 0xffff0000, v99
	v_cvt_pk_bf16_f32 v56, v56, v57
	v_div_scale_f32 v68, s[0:1], v7, v7, 1.0
	v_rcp_f32_e32 v69, v68
	global_store_dword v[110:111], v56, off
	v_lshlrev_b32_e32 v62, 16, v101
	v_and_b32_e32 v63, 0xffff0000, v101
	v_fma_f32 v70, -v68, v69, 1.0
	v_fmac_f32_e32 v69, v70, v69
	v_div_scale_f32 v70, vcc, 1.0, v7, 1.0
	v_mul_f32_e32 v71, v70, v69
	v_fma_f32 v72, -v68, v71, v70
	v_fmac_f32_e32 v71, v72, v69
	v_fma_f32 v68, -v68, v71, v70
	v_div_fmas_f32 v68, v68, v69, v71
	v_div_fixup_f32 v78, v68, v7, 1.0
	v_max_i32_e32 v7, 4, v81
	v_min_i32_e32 v68, v92, v117
	v_sub_u32_e32 v7, v68, v7
	v_add_u32_e32 v7, 4, v7
	v_cvt_f32_i32_e32 v7, v7
	v_add_f32_e64 v52, v62, -v52
	v_add_f32_e64 v53, v63, -v53
	v_lshlrev_b64 v[34:35], 11, v[34:35]
	v_add_f32_e32 v52, v54, v52
	v_add_f32_e32 v53, v55, v53
	v_div_scale_f32 v70, s[0:1], v7, v7, 1.0
	v_rcp_f32_e32 v71, v70
	v_fma_f32 v54, v86, v52, -v42
	v_fma_f32 v55, v86, v53, -v43
	v_lshl_add_u64 v[114:115], v[4:5], 0, v[34:35]
	v_cvt_pk_bf16_f32 v54, v54, v55
	v_fma_f32 v72, -v70, v71, 1.0
	v_fmac_f32_e32 v71, v72, v71
	v_div_scale_f32 v72, vcc, 1.0, v7, 1.0
	v_mul_f32_e32 v73, v72, v71
	v_fma_f32 v76, -v70, v73, v72
	v_fmac_f32_e32 v73, v76, v71
	v_fma_f32 v70, -v70, v73, v72
	v_div_fmas_f32 v70, v70, v71, v73
	v_div_fixup_f32 v72, v70, v7, 1.0
	v_min_i32_e32 v7, v90, v117
	v_sub_u32_e32 v0, v7, v0
	v_add_u32_e32 v0, 4, v0
	v_cvt_f32_i32_e32 v0, v0
	global_store_dword v[114:115], v54, off
	v_lshlrev_b32_e32 v64, 16, v103
	v_and_b32_e32 v65, 0xffff0000, v103
	v_div_scale_f32 v7, s[0:1], v0, v0, 1.0
	v_rcp_f32_e32 v73, v7
	v_add_f32_e64 v50, v64, -v50
	v_add_f32_e64 v51, v65, -v51
	v_lshlrev_b64 v[32:33], 11, v[32:33]
	v_add_f32_e32 v50, v52, v50
	v_add_f32_e32 v51, v53, v51
	v_fma_f32 v76, -v7, v73, 1.0
	v_fmac_f32_e32 v73, v76, v73
	v_div_scale_f32 v76, vcc, 1.0, v0, 1.0
	v_mul_f32_e32 v77, v76, v73
	v_fma_f32 v81, -v7, v77, v76
	v_fmac_f32_e32 v77, v81, v73
	v_fma_f32 v7, -v7, v77, v76
	v_div_fmas_f32 v7, v7, v73, v77
	v_div_fixup_f32 v0, v7, v0, 1.0
	v_max_i32_e32 v7, 4, v80
	v_min_i32_e32 v73, v89, v117
	v_sub_u32_e32 v7, v73, v7
	v_add_u32_e32 v7, 4, v7
	v_cvt_f32_i32_e32 v7, v7
	v_lshl_add_u64 v[80:81], v[4:5], 0, v[26:27]
	v_lshlrev_b32_e32 v26, 16, v98
	v_and_b32_e32 v27, 0xffff0000, v98
	v_div_scale_f32 v76, s[0:1], v7, v7, 1.0
	v_rcp_f32_e32 v77, v76
	v_fma_f32 v52, v82, v50, -v58
	v_fma_f32 v53, v82, v51, -v59
	v_lshl_add_u64 v[122:123], v[4:5], 0, v[32:33]
	v_cvt_pk_bf16_f32 v52, v52, v53
	v_fma_f32 v97, -v76, v77, 1.0
	v_fmac_f32_e32 v77, v97, v77
	v_div_scale_f32 v97, vcc, 1.0, v7, 1.0
	v_mul_f32_e32 v98, v97, v77
	v_fma_f32 v99, -v76, v98, v97
	v_fmac_f32_e32 v98, v99, v77
	v_fma_f32 v76, -v76, v98, v97
	v_div_fmas_f32 v76, v76, v77, v98
	v_div_fixup_f32 v76, v76, v7, 1.0
	v_max_i32_e32 v7, 4, v94
	v_min_i32_e32 v77, v88, v117
	v_sub_u32_e32 v7, v77, v7
	v_add_u32_e32 v7, 4, v7
	v_cvt_f32_i32_e32 v7, v7
	global_store_dword v[122:123], v52, off
	v_add_f32_e64 v48, v66, -v48
	v_add_f32_e64 v49, v67, -v49
	v_lshlrev_b64 v[30:31], 11, v[30:31]
	v_div_scale_f32 v77, s[0:1], v7, v7, 1.0
	v_rcp_f32_e32 v94, v77
	v_add_f32_e32 v48, v50, v48
	v_add_f32_e32 v49, v51, v49
	v_lshlrev_b32_e32 v36, 16, v129
	v_fma_f32 v50, v78, v48, -v60
	v_fma_f32 v51, v78, v49, -v61
	v_fma_f32 v74, -v77, v94, 1.0
	v_fmac_f32_e32 v94, v74, v94
	v_div_scale_f32 v74, vcc, 1.0, v7, 1.0
	v_mul_f32_e32 v75, v74, v94
	v_fma_f32 v97, -v77, v75, v74
	v_fmac_f32_e32 v75, v97, v94
	v_fma_f32 v74, -v77, v75, v74
	v_div_fmas_f32 v74, v74, v94, v75
	v_div_fixup_f32 v74, v74, v7, 1.0
	v_max_i32_e32 v7, 4, v92
	v_min_i32_e32 v75, v87, v117
	v_sub_u32_e32 v7, v75, v7
	v_add_u32_e32 v7, 4, v7
	v_cvt_f32_i32_e32 v7, v7
	v_and_b32_e32 v37, 0xffff0000, v129
	v_lshl_add_u64 v[128:129], v[4:5], 0, v[30:31]
	v_cvt_pk_bf16_f32 v50, v50, v51
	v_div_scale_f32 v75, s[0:1], v7, v7, 1.0
	v_rcp_f32_e32 v77, v75
	global_store_dword v[128:129], v50, off
	v_lshlrev_b32_e32 v30, 16, v100
	v_and_b32_e32 v31, 0xffff0000, v100
	v_fma_f32 v56, -v75, v77, 1.0
	v_fmac_f32_e32 v77, v56, v77
	v_div_scale_f32 v56, vcc, 1.0, v7, 1.0
	v_mul_f32_e32 v57, v56, v77
	v_fma_f32 v92, -v75, v57, v56
	v_fmac_f32_e32 v57, v92, v77
	v_fma_f32 v56, -v75, v57, v56
	v_div_fmas_f32 v56, v56, v77, v57
	v_div_fixup_f32 v56, v56, v7, 1.0
	v_max_i32_e32 v7, 4, v90
	v_min_i32_e32 v57, v83, v117
	v_sub_u32_e32 v7, v57, v7
	v_add_u32_e32 v7, 4, v7
	v_cvt_f32_i32_e32 v7, v7
	v_add_f32_e64 v46, v30, -v46
	v_add_f32_e64 v47, v31, -v47
	v_and_b32_e32 v73, 0xffff0000, v91
	v_add_f32_e32 v46, v48, v46
	v_add_f32_e32 v47, v49, v47
	v_div_scale_f32 v57, s[0:1], v7, v7, 1.0
	v_rcp_f32_e32 v75, v57
	v_fma_f32 v48, v72, v46, -v62
	v_fma_f32 v49, v72, v47, -v63
	v_cvt_pk_bf16_f32 v48, v48, v49
	global_store_dword v[84:85], v48, off
	v_fma_f32 v54, -v57, v75, 1.0
	v_fmac_f32_e32 v75, v54, v75
	v_div_scale_f32 v54, vcc, 1.0, v7, 1.0
	v_mul_f32_e32 v55, v54, v75
	v_fma_f32 v77, -v57, v55, v54
	v_fmac_f32_e32 v55, v77, v75
	v_fma_f32 v54, -v57, v55, v54
	v_div_fmas_f32 v54, v54, v75, v55
	v_div_fixup_f32 v54, v54, v7, 1.0
	v_max_i32_e32 v7, 4, v89
	v_min_i32_e32 v55, v79, v117
	v_sub_u32_e32 v7, v55, v7
	v_add_u32_e32 v7, 4, v7
	v_cvt_f32_i32_e32 v7, v7
	v_add_f32_e64 v44, v28, -v44
	v_add_f32_e64 v45, v29, -v45
	v_add_f32_e64 v42, v26, -v42
	v_add_f32_e64 v43, v27, -v43
	v_add_f32_e32 v44, v46, v44
	v_add_f32_e32 v45, v47, v45
	v_div_scale_f32 v55, s[0:1], v7, v7, 1.0
	v_rcp_f32_e32 v57, v55
	v_fma_f32 v46, v0, v44, -v64
	v_fma_f32 v47, v0, v45, -v65
	v_cvt_pk_bf16_f32 v0, v46, v47
	global_store_dword v[80:81], v0, off
	v_fma_f32 v52, -v55, v57, 1.0
	v_fmac_f32_e32 v57, v52, v57
	v_div_scale_f32 v52, vcc, 1.0, v7, 1.0
	v_mul_f32_e32 v53, v52, v57
	v_fma_f32 v75, -v55, v53, v52
	v_fmac_f32_e32 v53, v75, v57
	v_fma_f32 v52, -v55, v53, v52
	v_div_fmas_f32 v52, v52, v57, v53
	v_div_fixup_f32 v52, v52, v7, 1.0
	v_max_i32_e32 v7, 4, v88
	v_min_i32_e32 v53, v96, v117
	v_sub_u32_e32 v7, v53, v7
	v_add_u32_e32 v7, 4, v7
	v_cvt_f32_i32_e32 v7, v7
	v_add_f32_e32 v42, v44, v42
	v_add_f32_e32 v43, v45, v43
	v_lshlrev_b64 v[24:25], 11, v[24:25]
	v_fma_f32 v44, v76, v42, -v66
	v_fma_f32 v45, v76, v43, -v67
	v_div_scale_f32 v53, s[0:1], v7, v7, 1.0
	v_rcp_f32_e32 v55, v53
	v_lshlrev_b32_e32 v40, 16, v134
	v_and_b32_e32 v41, 0xffff0000, v134
	v_lshl_add_u64 v[24:25], v[4:5], 0, v[24:25]
	v_fma_f32 v50, -v53, v55, 1.0
	v_fmac_f32_e32 v55, v50, v55
	v_div_scale_f32 v50, vcc, 1.0, v7, 1.0
	v_mul_f32_e32 v51, v50, v55
	v_fma_f32 v57, -v53, v51, v50
	v_fmac_f32_e32 v51, v57, v55
	v_fma_f32 v50, -v53, v51, v50
	v_div_fmas_f32 v50, v50, v55, v51
	v_div_fixup_f32 v50, v50, v7, 1.0
	v_max_i32_e32 v7, 4, v87
	v_min_i32_e32 v51, v95, v117
	v_sub_u32_e32 v7, v51, v7
	v_add_u32_e32 v7, 4, v7
	v_cvt_f32_i32_e32 v7, v7
	v_lshlrev_b64 v[22:23], 11, v[22:23]
	v_lshlrev_b32_e32 v38, 16, v136
	v_and_b32_e32 v39, 0xffff0000, v136
	v_div_scale_f32 v51, s[0:1], v7, v7, 1.0
	v_rcp_f32_e32 v53, v51
	v_lshl_add_u64 v[22:23], v[4:5], 0, v[22:23]
	v_lshlrev_b64 v[20:21], 11, v[20:21]
	v_lshl_add_u64 v[20:21], v[4:5], 0, v[20:21]
	v_fma_f32 v48, -v51, v53, 1.0
	v_fmac_f32_e32 v53, v48, v53
	v_div_scale_f32 v48, vcc, 1.0, v7, 1.0
	v_mul_f32_e32 v49, v48, v53
	v_fma_f32 v55, -v51, v49, v48
	v_fmac_f32_e32 v49, v55, v53
	v_fma_f32 v48, -v51, v49, v48
	v_div_fmas_f32 v48, v48, v53, v49
	v_div_fixup_f32 v48, v48, v7, 1.0
	v_max_i32_e32 v7, 4, v83
	v_min_i32_e32 v49, v93, v117
	v_sub_u32_e32 v7, v49, v7
	v_add_u32_e32 v7, 4, v7
	v_cvt_f32_i32_e32 v7, v7
	v_lshlrev_b64 v[18:19], 11, v[18:19]
	v_lshlrev_b32_e32 v34, 16, v132
	v_and_b32_e32 v35, 0xffff0000, v132
	v_div_scale_f32 v49, s[0:1], v7, v7, 1.0
	v_rcp_f32_e32 v51, v49
	v_lshl_add_u64 v[18:19], v[4:5], 0, v[18:19]
	v_lshlrev_b64 v[16:17], 11, v[16:17]
	v_lshlrev_b32_e32 v32, 16, v124
	v_fma_f32 v0, -v49, v51, 1.0
	v_fmac_f32_e32 v51, v0, v51
	v_div_scale_f32 v0, vcc, 1.0, v7, 1.0
	v_mul_f32_e32 v46, v0, v51
	v_fma_f32 v47, -v49, v46, v0
	v_fmac_f32_e32 v46, v47, v51
	v_fma_f32 v0, -v49, v46, v0
	v_div_fmas_f32 v0, v0, v51, v46
	v_div_fixup_f32 v0, v0, v7, 1.0
	v_cvt_pk_bf16_f32 v7, v44, v45
	global_store_dword v[24:25], v7, off
	v_add_f32_e64 v24, v40, -v58
	v_add_f32_e64 v25, v41, -v59
	v_and_b32_e32 v33, 0xffff0000, v124
	v_add_f32_e32 v24, v42, v24
	v_add_f32_e32 v25, v43, v25
	v_lshl_add_u64 v[16:17], v[4:5], 0, v[16:17]
	v_fma_f32 v42, v74, v24, -v30
	v_fma_f32 v43, v74, v25, -v31
	v_cvt_pk_bf16_f32 v7, v42, v43
	global_store_dword v[22:23], v7, off
	v_add_f32_e64 v22, v38, -v60
	v_add_f32_e64 v23, v39, -v61
	v_lshlrev_b64 v[14:15], 11, v[14:15]
	v_add_f32_e32 v22, v24, v22
	v_add_f32_e32 v23, v25, v23
	v_lshlrev_b32_e32 v68, 16, v127
	v_fma_f32 v24, v56, v22, -v28
	v_fma_f32 v25, v56, v23, -v29
	v_cvt_pk_bf16_f32 v7, v24, v25
	global_store_dword v[20:21], v7, off
	v_add_f32_e64 v20, v36, -v62
	v_add_f32_e64 v21, v37, -v63
	v_and_b32_e32 v69, 0xffff0000, v127
	v_add_f32_e32 v20, v22, v20
	v_add_f32_e32 v21, v23, v21
	v_lshl_add_u64 v[14:15], v[4:5], 0, v[14:15]
	v_fma_f32 v22, v54, v20, -v26
	v_fma_f32 v23, v54, v21, -v27
	v_cvt_pk_bf16_f32 v7, v22, v23
	global_store_dword v[18:19], v7, off
	v_add_f32_e64 v18, v34, -v64
	v_add_f32_e64 v19, v35, -v65
	v_lshlrev_b64 v[12:13], 11, v[12:13]
	v_add_f32_e32 v18, v20, v18
	v_add_f32_e32 v19, v21, v19
	v_lshl_add_u64 v[12:13], v[4:5], 0, v[12:13]
	v_fma_f32 v20, v52, v18, -v40
	v_fma_f32 v21, v52, v19, -v41
	v_cvt_pk_bf16_f32 v7, v20, v21
	global_store_dword v[16:17], v7, off
	v_add_f32_e64 v16, v32, -v66
	v_add_f32_e64 v17, v33, -v67
	v_lshlrev_b32_e32 v70, 16, v120
	v_add_f32_e32 v16, v18, v16
	v_add_f32_e32 v17, v19, v17
	v_and_b32_e32 v71, 0xffff0000, v120
	v_fma_f32 v18, v50, v16, -v38
	v_fma_f32 v19, v50, v17, -v39
	v_cvt_pk_bf16_f32 v7, v18, v19
	global_store_dword v[14:15], v7, off
	v_add_f32_e64 v14, v68, -v30
	v_add_f32_e64 v15, v69, -v31
	v_lshlrev_b64 v[10:11], 11, v[10:11]
	v_add_f32_e32 v14, v16, v14
	v_add_f32_e32 v15, v17, v15
	v_lshl_add_u64 v[10:11], v[4:5], 0, v[10:11]
	v_fma_f32 v16, v48, v14, -v36
	v_fma_f32 v17, v48, v15, -v37
	v_cvt_pk_bf16_f32 v7, v16, v17
	global_store_dword v[12:13], v7, off
	v_add_u32_e32 v12, 35, v119
	v_max_i32_e32 v7, 4, v79
	v_min_i32_e32 v12, v12, v117
	v_sub_u32_e32 v7, v12, v7
	v_add_u32_e32 v7, 4, v7
	v_cvt_f32_i32_e32 v7, v7
	v_add_f32_e64 v12, v70, -v28
	v_add_f32_e64 v13, v71, -v29
	v_lshlrev_b32_e32 v72, 16, v91
	v_add_f32_e32 v12, v14, v12
	v_add_f32_e32 v13, v15, v13
	v_div_scale_f32 v16, s[0:1], v7, v7, 1.0
	v_rcp_f32_e32 v17, v16
	v_fma_f32 v14, v0, v12, -v34
	v_fma_f32 v15, v0, v13, -v35
	v_cvt_pk_bf16_f32 v0, v14, v15
	global_store_dword v[10:11], v0, off
	v_fma_f32 v0, -v16, v17, 1.0
	v_fmac_f32_e32 v17, v0, v17
	v_div_scale_f32 v0, vcc, 1.0, v7, 1.0
	v_mul_f32_e32 v10, v0, v17
	v_fma_f32 v11, -v16, v10, v0
	v_fmac_f32_e32 v10, v11, v17
	v_fma_f32 v0, -v16, v10, v0
	v_div_fmas_f32 v0, v0, v17, v10
	v_add_f32_e64 v10, v72, -v26
	v_add_f32_e64 v11, v73, -v27
	v_div_fixup_f32 v0, v0, v7, 1.0
	v_add_f32_e32 v10, v12, v10
	v_add_f32_e32 v11, v13, v11
	s_xor_b64 s[20:21], exec, -1
	v_fma_f32 v10, v0, v10, -v32
	v_fma_f32 v11, v0, v11, -v33

.LBB0_1084:
	s_or_b64 exec, exec, s[20:21]
	v_lshlrev_b32_e32 v174, 16, v51
	v_and_b32_e32 v175, 0xffff0000, v51
	v_lshlrev_b32_e32 v176, 16, v50
	v_and_b32_e32 v177, 0xffff0000, v50
	v_add_f32_e32 v50, 0, v174
	v_add_f32_e32 v51, 0, v175
	v_lshlrev_b32_e32 v178, 16, v53
	v_and_b32_e32 v179, 0xffff0000, v53
	v_add_f32_e32 v50, v50, v176
	v_add_f32_e32 v51, v51, v177
	v_lshlrev_b32_e32 v180, 16, v52
	v_and_b32_e32 v181, 0xffff0000, v52
	v_add_f32_e32 v50, v50, v178
	v_add_f32_e32 v51, v51, v179
	v_lshlrev_b32_e32 v94, 16, v59
	v_and_b32_e32 v95, 0xffff0000, v59
	v_add_f32_e32 v50, v50, v180
	v_add_f32_e32 v51, v51, v181
	v_lshlrev_b32_e32 v92, 16, v58
	v_and_b32_e32 v93, 0xffff0000, v58
	v_add_f32_e32 v50, v50, v94
	v_add_f32_e32 v51, v51, v95
	v_lshlrev_b32_e32 v90, 16, v68
	v_and_b32_e32 v91, 0xffff0000, v68
	v_add_f32_e32 v50, v50, v92
	v_add_f32_e32 v51, v51, v93
	v_lshlrev_b32_e32 v86, 16, v7
	v_add_f32_e32 v182, v50, v90
	v_add_f32_e32 v183, v51, v91
	v_and_b32_e32 v87, 0xffff0000, v7
	v_max_i32_e32 v7, 8, v119
	v_min_i32_e32 v50, v101, v117
	v_sub_u32_e32 v7, v50, v7
	v_add_u32_e32 v7, 8, v7
	v_cvt_f32_i32_e32 v7, v7
	v_lshlrev_b32_e32 v88, 16, v67
	v_and_b32_e32 v89, 0xffff0000, v67
	v_lshlrev_b32_e32 v58, 16, v130
	v_div_scale_f32 v67, s[0:1], v7, v7, 1.0
	v_and_b32_e32 v59, 0xffff0000, v130
	v_rcp_f32_e32 v130, v67
	v_lshlrev_b32_e32 v84, 16, v69
	v_and_b32_e32 v85, 0xffff0000, v69
	v_lshlrev_b32_e32 v68, 16, v131
	v_and_b32_e32 v69, 0xffff0000, v131
	v_fma_f32 v131, -v67, v130, 1.0
	v_add_f32_e32 v182, v182, v88
	v_add_f32_e32 v183, v183, v89
	v_fmac_f32_e32 v130, v131, v130
	v_div_scale_f32 v131, vcc, 1.0, v7, 1.0
	v_add_f32_e32 v182, v182, v86
	v_add_f32_e32 v183, v183, v87
	v_lshlrev_b32_e32 v82, 16, v76
	v_and_b32_e32 v83, 0xffff0000, v76
	v_lshlrev_b32_e32 v50, 16, v133
	v_and_b32_e32 v51, 0xffff0000, v133
	v_mul_f32_e32 v133, v131, v130
	v_add_f32_e32 v182, v182, v84
	v_add_f32_e32 v183, v183, v85
	v_lshlrev_b32_e32 v76, 16, v77
	v_and_b32_e32 v77, 0xffff0000, v77
	v_lshlrev_b32_e32 v52, 16, v134
	v_and_b32_e32 v53, 0xffff0000, v134
	v_fma_f32 v134, -v67, v133, v131
	v_add_f32_e32 v182, v182, v82
	v_add_f32_e32 v183, v183, v83
	v_fmac_f32_e32 v133, v134, v130
	v_add_f32_e32 v182, v182, v76
	v_add_f32_e32 v183, v183, v77
	v_fma_f32 v67, -v67, v133, v131
	v_add_f32_e32 v182, v182, v68
	v_add_f32_e32 v183, v183, v69
	v_div_fmas_f32 v67, v67, v130, v133
	v_add_f32_e32 v182, v182, v58
	v_add_f32_e32 v183, v183, v59
	v_div_fixup_f32 v130, v67, v7, 1.0
	v_add_f32_e32 v182, v182, v52
	v_add_f32_e32 v183, v183, v53
	v_max_i32_e32 v66, 8, v66
	v_min_i32_e32 v67, v99, v117
	v_add_f32_e32 v182, v182, v50
	v_add_f32_e32 v183, v183, v51
	v_sub_u32_e32 v66, v67, v66
	v_fma_f32 v131, v130, v183, -v87
	v_fma_f32 v130, v130, v182, -v86
	v_add_u32_e32 v66, 8, v66
	v_cvt_pk_bf16_f32 v130, v130, v131
	v_cvt_f32_i32_e32 v131, v66
	v_ashrrev_i32_e32 v7, 31, v6
	v_lshlrev_b64 v[66:67], 11, v[6:7]
	v_lshl_add_u64 v[66:67], v[4:5], 0, v[66:67]
	v_div_scale_f32 v7, s[0:1], v131, v131, 1.0
	v_rcp_f32_e32 v133, v7
	global_store_dword v[66:67], v130, off
	v_lshlrev_b32_e32 v66, 16, v132
	v_and_b32_e32 v67, 0xffff0000, v132
	v_fma_f32 v130, -v7, v133, 1.0
	v_fmac_f32_e32 v133, v130, v133
	v_div_scale_f32 v130, vcc, 1.0, v131, 1.0
	v_mul_f32_e32 v132, v130, v133
	v_fma_f32 v134, -v7, v132, v130
	v_fmac_f32_e32 v132, v134, v133
	v_fma_f32 v7, -v7, v132, v130
	v_div_fmas_f32 v7, v7, v133, v132
	v_add_f32_e64 v132, v66, -v174
	v_add_f32_e64 v133, v67, -v175
	v_div_fixup_f32 v130, v7, v131, 1.0
	v_add_f32_e32 v132, v182, v132
	v_add_f32_e32 v133, v183, v133
	v_max_i32_e32 v114, 8, v114
	v_fma_f32 v131, v130, v133, -v85
	v_fma_f32 v130, v130, v132, -v84
	v_cvt_pk_bf16_f32 v7, v130, v131
	v_min_i32_e32 v130, v97, v117
	v_sub_u32_e32 v114, v130, v114
	v_add_u32_e32 v114, 8, v114
	v_cvt_f32_i32_e32 v114, v114
	v_lshlrev_b64 v[72:73], 11, v[72:73]
	v_lshl_add_u64 v[72:73], v[4:5], 0, v[72:73]
	global_store_dword v[72:73], v7, off
	v_div_scale_f32 v130, s[0:1], v114, v114, 1.0
	v_rcp_f32_e32 v131, v130
	v_lshlrev_b32_e32 v72, 16, v127
	v_and_b32_e32 v73, 0xffff0000, v127
	v_max_i32_e32 v107, 8, v107
	v_fma_f32 v7, -v130, v131, 1.0
	v_fmac_f32_e32 v131, v7, v131
	v_div_scale_f32 v7, vcc, 1.0, v114, 1.0
	v_mul_f32_e32 v127, v7, v131
	v_fma_f32 v134, -v130, v127, v7
	v_fmac_f32_e32 v127, v134, v131
	v_fma_f32 v7, -v130, v127, v7
	v_div_fmas_f32 v7, v7, v131, v127
	v_add_f32_e64 v130, v72, -v176
	v_add_f32_e64 v131, v73, -v177
	v_div_fixup_f32 v114, v7, v114, 1.0
	v_add_f32_e32 v130, v132, v130
	v_add_f32_e32 v131, v133, v131
	v_lshlrev_b64 v[80:81], 11, v[80:81]
	s_waitcnt vmcnt(0)
	v_fma_f32 v132, v114, v130, -v82
	v_fma_f32 v133, v114, v131, -v83
	v_min_i32_e32 v114, v96, v117
	v_sub_u32_e32 v107, v114, v107
	v_add_u32_e32 v107, 8, v107
	v_cvt_f32_i32_e32 v107, v107
	v_cvt_pk_bf16_f32 v7, v132, v133
	v_lshl_add_u64 v[80:81], v[4:5], 0, v[80:81]
	global_store_dword v[80:81], v7, off
	v_div_scale_f32 v114, s[0:1], v107, v107, 1.0
	v_rcp_f32_e32 v127, v114
	v_lshlrev_b32_e32 v80, 16, v128
	v_and_b32_e32 v81, 0xffff0000, v128
	v_max_i32_e32 v106, 8, v106
	v_fma_f32 v7, -v114, v127, 1.0
	v_fmac_f32_e32 v127, v7, v127
	v_div_scale_f32 v7, vcc, 1.0, v107, 1.0
	v_mul_f32_e32 v128, v7, v127
	v_fma_f32 v132, -v114, v128, v7
	v_fmac_f32_e32 v128, v132, v127
	v_fma_f32 v7, -v114, v128, v7
	v_div_fmas_f32 v7, v7, v127, v128
	v_div_fixup_f32 v114, v7, v107, 1.0
	v_min_i32_e32 v107, v98, v117
	v_sub_u32_e32 v106, v107, v106
	v_add_u32_e32 v106, 8, v106
	v_cvt_f32_i32_e32 v106, v106
	v_add_f32_e64 v132, v80, -v178
	v_add_f32_e64 v133, v81, -v179
	v_lshlrev_b64 v[78:79], 11, v[78:79]
	v_add_f32_e32 v130, v130, v132
	v_add_f32_e32 v131, v131, v133
	v_div_scale_f32 v107, s[0:1], v106, v106, 1.0
	v_fma_f32 v132, v114, v130, -v76
	v_fma_f32 v133, v114, v131, -v77
	v_rcp_f32_e32 v114, v107
	v_cvt_pk_bf16_f32 v7, v132, v133
	v_lshl_add_u64 v[78:79], v[4:5], 0, v[78:79]
	global_store_dword v[78:79], v7, off
	v_fma_f32 v7, -v107, v114, 1.0
	v_fmac_f32_e32 v114, v7, v114
	v_div_scale_f32 v7, vcc, 1.0, v106, 1.0
	v_lshlrev_b32_e32 v78, 16, v124
	v_and_b32_e32 v79, 0xffff0000, v124
	v_mul_f32_e32 v124, v7, v114
	v_fma_f32 v127, -v107, v124, v7
	v_fmac_f32_e32 v124, v127, v114
	v_fma_f32 v7, -v107, v124, v7
	v_div_fmas_f32 v7, v7, v114, v124
	v_add_f32_e64 v132, v78, -v180
	v_add_f32_e64 v133, v79, -v181
	v_div_fixup_f32 v106, v7, v106, 1.0
	v_add_f32_e32 v130, v130, v132
	v_add_f32_e32 v131, v131, v133
	v_max_i32_e32 v104, 8, v104
	v_fma_f32 v107, v106, v131, -v69
	v_fma_f32 v106, v106, v130, -v68
	v_cvt_pk_bf16_f32 v7, v106, v107
	v_min_i32_e32 v106, v100, v117
	v_sub_u32_e32 v104, v106, v104
	v_add_u32_e32 v104, 8, v104
	v_cvt_f32_i32_e32 v104, v104
	v_lshlrev_b64 v[74:75], 11, v[74:75]
	v_lshl_add_u64 v[74:75], v[4:5], 0, v[74:75]
	global_store_dword v[74:75], v7, off
	v_div_scale_f32 v106, s[0:1], v104, v104, 1.0
	v_rcp_f32_e32 v107, v106
	v_lshlrev_b32_e32 v74, 16, v126
	v_and_b32_e32 v75, 0xffff0000, v126
	v_add_f32_e64 v94, v74, -v94
	v_add_f32_e64 v95, v75, -v95
	v_fma_f32 v7, -v106, v107, 1.0
	v_fmac_f32_e32 v107, v7, v107
	v_div_scale_f32 v7, vcc, 1.0, v104, 1.0
	v_mul_f32_e32 v114, v7, v107
	v_fma_f32 v124, -v106, v114, v7
	v_fmac_f32_e32 v114, v124, v107
	v_fma_f32 v7, -v106, v114, v7
	v_div_fmas_f32 v7, v7, v107, v114
	v_div_fixup_f32 v104, v7, v104, 1.0
	v_add_f32_e32 v94, v130, v94
	v_add_f32_e32 v95, v131, v95
	v_max_i32_e32 v103, 8, v103
	v_fma_f32 v106, v104, v94, -v58
	v_fma_f32 v107, v104, v95, -v59
	v_min_i32_e32 v104, v0, v117
	v_sub_u32_e32 v103, v104, v103
	v_add_u32_e32 v103, 8, v103
	v_cvt_f32_i32_e32 v103, v103
	v_cvt_pk_bf16_f32 v7, v106, v107
	v_lshlrev_b64 v[70:71], 11, v[70:71]
	v_lshl_add_u64 v[70:71], v[4:5], 0, v[70:71]
	v_div_scale_f32 v104, s[0:1], v103, v103, 1.0
	v_rcp_f32_e32 v106, v104
	global_store_dword v[70:71], v7, off
	v_lshlrev_b32_e32 v70, 16, v121
	v_and_b32_e32 v71, 0xffff0000, v121
	v_fma_f32 v7, -v104, v106, 1.0
	v_fmac_f32_e32 v106, v7, v106
	v_div_scale_f32 v7, vcc, 1.0, v103, 1.0
	v_mul_f32_e32 v107, v7, v106
	v_fma_f32 v114, -v104, v107, v7
	v_fmac_f32_e32 v107, v114, v106
	v_fma_f32 v7, -v104, v107, v7
	v_div_fmas_f32 v7, v7, v106, v107
	v_add_f32_e64 v92, v70, -v92
	v_add_f32_e64 v93, v71, -v93
	v_div_fixup_f32 v104, v7, v103, 1.0
	v_add_f32_e32 v92, v94, v92
	v_add_f32_e32 v93, v95, v93
	v_lshlrev_b64 v[64:65], 11, v[64:65]
	v_fma_f32 v94, v104, v92, -v52
	v_fma_f32 v95, v104, v93, -v53
	v_cvt_pk_bf16_f32 v7, v94, v95
	v_max_i32_e32 v94, 8, v102
	v_min_i32_e32 v95, v105, v117
	v_sub_u32_e32 v94, v95, v94
	v_add_u32_e32 v94, 8, v94
	v_cvt_f32_i32_e32 v94, v94
	v_lshl_add_u64 v[64:65], v[4:5], 0, v[64:65]
	global_store_dword v[64:65], v7, off
	v_lshlrev_b32_e32 v64, 16, v123
	v_div_scale_f32 v95, s[0:1], v94, v94, 1.0
	v_rcp_f32_e32 v102, v95
	v_and_b32_e32 v65, 0xffff0000, v123
	v_add_f32_e64 v90, v64, -v90
	v_add_f32_e64 v91, v65, -v91
	v_lshlrev_b64 v[62:63], 11, v[62:63]
	v_fma_f32 v7, -v95, v102, 1.0
	v_fmac_f32_e32 v102, v7, v102
	v_div_scale_f32 v7, vcc, 1.0, v94, 1.0
	v_mul_f32_e32 v103, v7, v102
	v_fma_f32 v104, -v95, v103, v7
	v_fmac_f32_e32 v103, v104, v102
	v_fma_f32 v7, -v95, v103, v7
	v_div_fmas_f32 v7, v7, v102, v103
	v_div_fixup_f32 v94, v7, v94, 1.0
	v_add_f32_e32 v106, v92, v90
	v_add_f32_e32 v107, v93, v91
	v_lshl_add_u64 v[62:63], v[4:5], 0, v[62:63]
	v_fma_f32 v90, v94, v106, -v50
	v_fma_f32 v91, v94, v107, -v51
	v_cvt_pk_bf16_f32 v7, v90, v91
	v_max_i32_e32 v90, 8, v101
	v_min_i32_e32 v91, v118, v117
	v_sub_u32_e32 v90, v91, v90
	v_add_u32_e32 v90, 8, v90
	v_cvt_f32_i32_e32 v92, v90
	global_store_dword v[62:63], v7, off
	v_lshlrev_b32_e32 v90, 16, v116
	v_and_b32_e32 v91, 0xffff0000, v116
	v_div_scale_f32 v7, s[0:1], v92, v92, 1.0
	v_rcp_f32_e32 v93, v7
	v_lshlrev_b64 v[56:57], 11, v[56:57]
	v_lshl_add_u64 v[132:133], v[4:5], 0, v[56:57]
	v_lshlrev_b32_e32 v56, 16, v112
	v_fma_f32 v94, -v7, v93, 1.0
	v_fmac_f32_e32 v93, v94, v93
	v_div_scale_f32 v94, vcc, 1.0, v92, 1.0
	v_mul_f32_e32 v95, v94, v93
	v_fma_f32 v101, -v7, v95, v94
	v_fmac_f32_e32 v95, v101, v93
	v_fma_f32 v7, -v7, v95, v94
	v_div_fmas_f32 v7, v7, v93, v95
	v_div_fixup_f32 v128, v7, v92, 1.0
	v_max_i32_e32 v7, 8, v99
	v_min_i32_e32 v92, v136, v117
	v_sub_u32_e32 v7, v92, v7
	v_add_u32_e32 v7, 8, v7
	v_cvt_f32_i32_e32 v7, v7
	v_and_b32_e32 v57, 0xffff0000, v112
	v_lshlrev_b64 v[48:49], 11, v[48:49]
	v_lshl_add_u64 v[126:127], v[4:5], 0, v[48:49]
	v_div_scale_f32 v94, s[0:1], v7, v7, 1.0
	v_rcp_f32_e32 v95, v94
	v_lshlrev_b32_e32 v48, 16, v108
	v_and_b32_e32 v49, 0xffff0000, v108
	v_lshlrev_b64 v[60:61], 11, v[60:61]
	v_fma_f32 v99, -v94, v95, 1.0
	v_fmac_f32_e32 v95, v99, v95
	v_div_scale_f32 v99, vcc, 1.0, v7, 1.0
	v_mul_f32_e32 v101, v99, v95
	v_fma_f32 v102, -v94, v101, v99
	v_fmac_f32_e32 v101, v102, v95
	v_fma_f32 v94, -v94, v101, v99
	v_div_fmas_f32 v94, v94, v95, v101
	v_div_fixup_f32 v124, v94, v7, 1.0
	v_max_i32_e32 v7, 8, v97
	v_min_i32_e32 v94, v140, v117
	v_sub_u32_e32 v7, v94, v7
	v_add_u32_e32 v7, 8, v7
	v_cvt_f32_i32_e32 v7, v7
	v_lshlrev_b64 v[46:47], 11, v[46:47]
	v_lshlrev_b32_e32 v62, 16, v135
	v_and_b32_e32 v63, 0xffff0000, v135
	v_div_scale_f32 v97, s[0:1], v7, v7, 1.0
	v_rcp_f32_e32 v99, v97
	v_lshl_add_u64 v[134:135], v[4:5], 0, v[60:61]
	v_lshlrev_b32_e32 v60, 16, v120
	v_and_b32_e32 v61, 0xffff0000, v120
	v_fma_f32 v101, -v97, v99, 1.0
	v_fmac_f32_e32 v99, v101, v99
	v_div_scale_f32 v101, vcc, 1.0, v7, 1.0
	v_mul_f32_e32 v102, v101, v99
	v_fma_f32 v103, -v97, v102, v101
	v_fmac_f32_e32 v102, v103, v99
	v_fma_f32 v97, -v97, v102, v101
	v_div_fmas_f32 v97, v97, v99, v102
	v_div_fixup_f32 v116, v97, v7, 1.0
	v_max_i32_e32 v7, 8, v96
	v_min_i32_e32 v96, v144, v117
	v_sub_u32_e32 v7, v96, v7
	v_add_u32_e32 v7, 8, v7
	v_cvt_f32_i32_e32 v7, v7
	v_lshl_add_u64 v[120:121], v[4:5], 0, v[46:47]
	v_lshlrev_b32_e32 v46, 16, v111
	v_and_b32_e32 v47, 0xffff0000, v111
	v_div_scale_f32 v99, s[0:1], v7, v7, 1.0
	v_rcp_f32_e32 v101, v99
	v_max_i32_e32 v0, 8, v0
	v_lshlrev_b64 v[54:55], 11, v[54:55]
	v_lshlrev_b64 v[44:45], 11, v[44:45]
	v_fma_f32 v102, -v99, v101, 1.0
	v_fmac_f32_e32 v101, v102, v101
	v_div_scale_f32 v102, vcc, 1.0, v7, 1.0
	v_mul_f32_e32 v103, v102, v101
	v_fma_f32 v104, -v99, v103, v102
	v_fmac_f32_e32 v103, v104, v101
	v_fma_f32 v99, -v99, v103, v102
	v_div_fmas_f32 v99, v99, v101, v103
	v_div_fixup_f32 v112, v99, v7, 1.0
	v_max_i32_e32 v7, 8, v98
	v_min_i32_e32 v98, v148, v117
	v_sub_u32_e32 v7, v98, v7
	v_add_u32_e32 v7, 8, v7
	v_cvt_f32_i32_e32 v7, v7
	v_lshl_add_u64 v[130:131], v[4:5], 0, v[54:55]
	v_lshlrev_b32_e32 v54, 16, v115
	v_and_b32_e32 v55, 0xffff0000, v115
	v_div_scale_f32 v101, s[0:1], v7, v7, 1.0
	v_rcp_f32_e32 v102, v101
	v_lshlrev_b64 v[42:43], 11, v[42:43]
	v_lshlrev_b32_e32 v98, 16, v143
	v_and_b32_e32 v99, 0xffff0000, v143
	v_fma_f32 v103, -v101, v102, 1.0
	v_fmac_f32_e32 v102, v103, v102
	v_div_scale_f32 v103, vcc, 1.0, v7, 1.0
	v_mul_f32_e32 v104, v103, v102
	v_fma_f32 v108, -v101, v104, v103
	v_fmac_f32_e32 v104, v108, v102
	v_fma_f32 v101, -v101, v104, v103
	v_div_fmas_f32 v101, v101, v102, v104
	v_div_fixup_f32 v108, v101, v7, 1.0
	v_max_i32_e32 v7, 8, v100
	v_min_i32_e32 v100, v152, v117
	v_sub_u32_e32 v7, v100, v7
	v_add_u32_e32 v7, 8, v7
	v_cvt_f32_i32_e32 v7, v7
	v_lshlrev_b32_e32 v100, 16, v147
	v_and_b32_e32 v101, 0xffff0000, v147
	v_max_i32_e32 v118, 8, v118
	v_div_scale_f32 v102, s[0:1], v7, v7, 1.0
	v_rcp_f32_e32 v103, v102
	v_lshlrev_b64 v[40:41], 11, v[40:41]
	v_lshlrev_b32_e32 v94, 16, v151
	v_and_b32_e32 v95, 0xffff0000, v151
	v_fma_f32 v104, -v102, v103, 1.0
	v_fmac_f32_e32 v103, v104, v103
	v_div_scale_f32 v104, vcc, 1.0, v7, 1.0
	v_mul_f32_e32 v111, v104, v103
	v_fma_f32 v114, -v102, v111, v104
	v_fmac_f32_e32 v111, v114, v103
	v_fma_f32 v102, -v102, v111, v104
	v_div_fmas_f32 v102, v102, v103, v111
	v_div_fixup_f32 v104, v102, v7, 1.0
	v_min_i32_e32 v7, v156, v117
	v_sub_u32_e32 v0, v7, v0
	v_add_u32_e32 v0, 8, v0
	v_cvt_f32_i32_e32 v0, v0
	v_lshl_add_u64 v[114:115], v[4:5], 0, v[44:45]
	v_lshlrev_b32_e32 v44, 16, v110
	v_and_b32_e32 v45, 0xffff0000, v110
	v_div_scale_f32 v7, s[0:1], v0, v0, 1.0
	v_rcp_f32_e32 v111, v7
	v_lshlrev_b32_e32 v102, 16, v139
	v_and_b32_e32 v103, 0xffff0000, v139
	v_max_i32_e32 v136, 8, v136
	v_fma_f32 v110, -v7, v111, 1.0
	v_fmac_f32_e32 v111, v110, v111
	v_div_scale_f32 v110, vcc, 1.0, v0, 1.0
	v_mul_f32_e32 v123, v110, v111
	v_fma_f32 v139, -v7, v123, v110
	v_fmac_f32_e32 v123, v139, v111
	v_fma_f32 v7, -v7, v123, v110
	v_div_fmas_f32 v7, v7, v111, v123
	v_div_fixup_f32 v0, v7, v0, 1.0
	v_max_i32_e32 v7, 8, v105
	v_min_i32_e32 v105, v160, v117
	v_sub_u32_e32 v7, v105, v7
	v_add_u32_e32 v7, 8, v7
	v_cvt_f32_i32_e32 v7, v7
	v_lshl_add_u64 v[110:111], v[4:5], 0, v[42:43]
	v_lshlrev_b32_e32 v42, 16, v122
	v_and_b32_e32 v43, 0xffff0000, v122
	v_div_scale_f32 v123, s[0:1], v7, v7, 1.0
	v_rcp_f32_e32 v139, v123
	v_lshlrev_b64 v[38:39], 11, v[38:39]
	v_lshlrev_b32_e32 v96, 16, v155
	v_and_b32_e32 v97, 0xffff0000, v155
	v_fma_f32 v122, -v123, v139, 1.0
	v_fmac_f32_e32 v139, v122, v139
	v_div_scale_f32 v122, vcc, 1.0, v7, 1.0
	v_mul_f32_e32 v143, v122, v139
	v_fma_f32 v147, -v123, v143, v122
	v_fmac_f32_e32 v143, v147, v139
	v_fma_f32 v122, -v123, v143, v122
	v_min_i32_e32 v123, v161, v117
	v_sub_u32_e32 v118, v123, v118
	v_add_u32_e32 v118, 8, v118
	v_div_fmas_f32 v122, v122, v139, v143
	v_cvt_f32_i32_e32 v139, v118
	v_div_fixup_f32 v118, v122, v7, 1.0
	v_lshl_add_u64 v[122:123], v[4:5], 0, v[40:41]
	v_lshlrev_b32_e32 v40, 16, v138
	v_div_scale_f32 v7, s[0:1], v139, v139, 1.0
	v_rcp_f32_e32 v143, v7
	v_and_b32_e32 v41, 0xffff0000, v138
	v_max_i32_e32 v140, 8, v140
	v_lshlrev_b64 v[36:37], 11, v[36:37]
	v_fma_f32 v138, -v7, v143, 1.0
	v_fmac_f32_e32 v143, v138, v143
	v_div_scale_f32 v138, vcc, 1.0, v139, 1.0
	v_mul_f32_e32 v147, v138, v143
	v_fma_f32 v151, -v7, v147, v138
	v_fmac_f32_e32 v147, v151, v143
	v_fma_f32 v7, -v7, v147, v138
	v_min_i32_e32 v138, v157, v117
	v_sub_u32_e32 v136, v138, v136
	v_add_u32_e32 v136, 8, v136
	v_div_fmas_f32 v7, v7, v143, v147
	v_cvt_f32_i32_e32 v143, v136
	v_div_fixup_f32 v136, v7, v139, 1.0
	v_lshl_add_u64 v[138:139], v[4:5], 0, v[38:39]
	v_lshlrev_b32_e32 v38, 16, v142
	v_div_scale_f32 v7, s[0:1], v143, v143, 1.0
	v_rcp_f32_e32 v147, v7
	v_and_b32_e32 v39, 0xffff0000, v142
	v_lshlrev_b32_e32 v92, 16, v159
	v_and_b32_e32 v93, 0xffff0000, v159
	v_fma_f32 v142, -v7, v147, 1.0
	v_fmac_f32_e32 v147, v142, v147
	v_div_scale_f32 v142, vcc, 1.0, v143, 1.0
	v_mul_f32_e32 v151, v142, v147
	v_fma_f32 v155, -v7, v151, v142
	v_fmac_f32_e32 v151, v155, v147
	v_fma_f32 v7, -v7, v151, v142
	v_min_i32_e32 v142, v153, v117
	v_sub_u32_e32 v140, v142, v140
	v_add_u32_e32 v140, 8, v140
	v_div_fmas_f32 v7, v7, v147, v151
	v_cvt_f32_i32_e32 v147, v140
	v_div_fixup_f32 v140, v7, v143, 1.0
	v_lshl_add_u64 v[142:143], v[4:5], 0, v[36:37]
	v_lshlrev_b32_e32 v36, 16, v146
	v_div_scale_f32 v7, s[0:1], v147, v147, 1.0
	v_rcp_f32_e32 v151, v7
	v_and_b32_e32 v37, 0xffff0000, v146
	v_max_i32_e32 v144, 8, v144
	v_lshlrev_b64 v[34:35], 11, v[34:35]
	v_fma_f32 v146, -v7, v151, 1.0
	v_fmac_f32_e32 v151, v146, v151
	v_div_scale_f32 v146, vcc, 1.0, v147, 1.0
	v_mul_f32_e32 v155, v146, v151
	v_fma_f32 v159, -v7, v155, v146
	v_fmac_f32_e32 v155, v159, v151
	v_fma_f32 v7, -v7, v155, v146
	v_min_i32_e32 v146, v149, v117
	v_sub_u32_e32 v144, v146, v144
	v_add_u32_e32 v144, 8, v144
	v_div_fmas_f32 v7, v7, v151, v155
	v_cvt_f32_i32_e32 v151, v144
	v_div_fixup_f32 v144, v7, v147, 1.0
	v_lshl_add_u64 v[146:147], v[4:5], 0, v[34:35]
	v_lshlrev_b32_e32 v34, 16, v150
	v_div_scale_f32 v7, s[0:1], v151, v151, 1.0
	v_rcp_f32_e32 v155, v7
	v_and_b32_e32 v35, 0xffff0000, v150
	v_max_i32_e32 v148, 8, v148
	v_lshlrev_b64 v[32:33], 11, v[32:33]
	v_fma_f32 v150, -v7, v155, 1.0
	v_fmac_f32_e32 v155, v150, v155
	v_div_scale_f32 v150, vcc, 1.0, v151, 1.0
	v_mul_f32_e32 v159, v150, v155
	v_fma_f32 v163, -v7, v159, v150
	v_fmac_f32_e32 v159, v163, v155
	v_fma_f32 v7, -v7, v159, v150
	v_min_i32_e32 v150, v145, v117
	v_sub_u32_e32 v148, v150, v148
	v_add_u32_e32 v148, 8, v148
	v_div_fmas_f32 v7, v7, v155, v159
	v_cvt_f32_i32_e32 v155, v148
	v_div_fixup_f32 v148, v7, v151, 1.0
	v_lshl_add_u64 v[150:151], v[4:5], 0, v[32:33]
	v_lshlrev_b32_e32 v32, 16, v154
	v_div_scale_f32 v7, s[0:1], v155, v155, 1.0
	v_rcp_f32_e32 v159, v7
	v_and_b32_e32 v33, 0xffff0000, v154
	v_max_i32_e32 v152, 8, v152
	v_lshlrev_b64 v[30:31], 11, v[30:31]
	v_fma_f32 v154, -v7, v159, 1.0
	v_fmac_f32_e32 v159, v154, v159
	v_div_scale_f32 v154, vcc, 1.0, v155, 1.0
	v_mul_f32_e32 v163, v154, v159
	v_fma_f32 v173, -v7, v163, v154
	v_fmac_f32_e32 v163, v173, v159
	v_fma_f32 v7, -v7, v163, v154
	v_min_i32_e32 v154, v141, v117
	v_sub_u32_e32 v152, v154, v152
	v_add_u32_e32 v152, 8, v152
	v_div_fmas_f32 v7, v7, v159, v163
	v_cvt_f32_i32_e32 v159, v152
	v_div_fixup_f32 v152, v7, v155, 1.0
	v_lshl_add_u64 v[154:155], v[4:5], 0, v[30:31]
	v_lshlrev_b32_e32 v30, 16, v158
	v_div_scale_f32 v7, s[0:1], v159, v159, 1.0
	v_rcp_f32_e32 v163, v7
	v_and_b32_e32 v31, 0xffff0000, v158
	v_max_i32_e32 v156, 8, v156
	v_lshlrev_b64 v[28:29], 11, v[28:29]
	v_fma_f32 v158, -v7, v163, 1.0
	v_fmac_f32_e32 v163, v158, v163
	v_div_scale_f32 v158, vcc, 1.0, v159, 1.0
	v_mul_f32_e32 v173, v158, v163
	v_fma_f32 v174, -v7, v173, v158
	v_fmac_f32_e32 v173, v174, v163
	v_fma_f32 v7, -v7, v173, v158
	v_min_i32_e32 v158, v137, v117
	v_sub_u32_e32 v156, v158, v156
	v_add_u32_e32 v156, 8, v156
	v_div_fmas_f32 v7, v7, v163, v173
	v_cvt_f32_i32_e32 v163, v156
	v_div_fixup_f32 v156, v7, v159, 1.0
	v_lshl_add_u64 v[158:159], v[4:5], 0, v[28:29]
	v_lshlrev_b32_e32 v28, 16, v162
	v_div_scale_f32 v7, s[0:1], v163, v163, 1.0
	v_rcp_f32_e32 v173, v7
	v_and_b32_e32 v29, 0xffff0000, v162
	v_max_i32_e32 v160, 8, v160
	v_lshlrev_b64 v[24:25], 11, v[24:25]
	v_fma_f32 v162, -v7, v173, 1.0
	v_fmac_f32_e32 v173, v162, v173
	v_div_scale_f32 v162, vcc, 1.0, v163, 1.0
	v_mul_f32_e32 v174, v162, v173
	v_fma_f32 v175, -v7, v174, v162
	v_fmac_f32_e32 v174, v175, v173
	v_fma_f32 v7, -v7, v174, v162
	v_min_i32_e32 v162, v129, v117
	v_sub_u32_e32 v160, v162, v160
	v_add_u32_e32 v160, 8, v160
	v_div_fmas_f32 v7, v7, v173, v174
	v_cvt_f32_i32_e32 v173, v160
	v_div_fixup_f32 v160, v7, v163, 1.0
	v_lshl_add_u64 v[162:163], v[4:5], 0, v[24:25]
	v_lshlrev_b32_e32 v24, 16, v164
	v_div_scale_f32 v7, s[0:1], v173, v173, 1.0
	v_rcp_f32_e32 v174, v7
	v_and_b32_e32 v25, 0xffff0000, v164
	v_add_f32_e64 v88, v90, -v88
	v_add_f32_e64 v89, v91, -v89
	v_add_f32_e64 v86, v60, -v86
	v_add_f32_e64 v87, v61, -v87
	v_fma_f32 v164, -v7, v174, 1.0
	v_fmac_f32_e32 v174, v164, v174
	v_div_scale_f32 v164, vcc, 1.0, v173, 1.0
	v_mul_f32_e32 v175, v164, v174
	v_fma_f32 v176, -v7, v175, v164
	v_fmac_f32_e32 v175, v176, v174
	v_fma_f32 v7, -v7, v175, v164
	v_div_fmas_f32 v7, v7, v174, v175
	v_div_fixup_f32 v164, v7, v173, 1.0
	v_max_i32_e32 v7, 8, v161
	v_min_i32_e32 v161, v172, v117
	v_sub_u32_e32 v7, v161, v7
	v_add_u32_e32 v7, 8, v7
	v_cvt_f32_i32_e32 v7, v7
	v_add_f32_e32 v106, v106, v88
	v_add_f32_e32 v107, v107, v89
	v_add_f32_e64 v84, v56, -v84
	v_add_f32_e64 v85, v57, -v85
	v_fma_f32 v88, v128, v106, -v66
	v_fma_f32 v89, v128, v107, -v67
	v_div_scale_f32 v161, s[0:1], v7, v7, 1.0
	v_rcp_f32_e32 v172, v161
	v_cvt_pk_bf16_f32 v88, v88, v89
	global_store_dword v[134:135], v88, off
	v_add_f32_e32 v106, v106, v86
	v_add_f32_e32 v107, v107, v87
	v_fma_f32 v88, -v161, v172, 1.0
	v_fmac_f32_e32 v172, v88, v172
	v_div_scale_f32 v88, vcc, 1.0, v7, 1.0
	v_mul_f32_e32 v89, v88, v172
	v_fma_f32 v128, -v161, v89, v88
	v_fmac_f32_e32 v89, v128, v172
	v_fma_f32 v88, -v161, v89, v88
	v_div_fmas_f32 v88, v88, v172, v89
	v_div_fixup_f32 v88, v88, v7, 1.0
	v_max_i32_e32 v7, 8, v157
	v_min_i32_e32 v89, v171, v117
	v_sub_u32_e32 v7, v89, v7
	v_add_u32_e32 v7, 8, v7
	v_cvt_f32_i32_e32 v7, v7
	v_fma_f32 v86, v124, v106, -v72
	v_fma_f32 v87, v124, v107, -v73
	v_cvt_pk_bf16_f32 v86, v86, v87
	global_store_dword v[132:133], v86, off
	v_div_scale_f32 v89, s[0:1], v7, v7, 1.0
	v_rcp_f32_e32 v128, v89
	v_add_f32_e32 v84, v106, v84
	v_add_f32_e32 v85, v107, v85
	v_add_f32_e64 v82, v54, -v82
	v_add_f32_e64 v83, v55, -v83
	v_fma_f32 v106, v116, v84, -v80
	v_fma_f32 v107, v116, v85, -v81
	v_fma_f32 v86, -v89, v128, 1.0
	v_fmac_f32_e32 v128, v86, v128
	v_div_scale_f32 v86, vcc, 1.0, v7, 1.0
	v_mul_f32_e32 v87, v86, v128
	v_fma_f32 v124, -v89, v87, v86
	v_fmac_f32_e32 v87, v124, v128
	v_fma_f32 v86, -v89, v87, v86
	v_div_fmas_f32 v86, v86, v128, v87
	v_div_fixup_f32 v86, v86, v7, 1.0
	v_max_i32_e32 v7, 8, v153
	v_min_i32_e32 v87, v170, v117
	v_sub_u32_e32 v7, v87, v7
	v_add_u32_e32 v7, 8, v7
	v_cvt_f32_i32_e32 v7, v7
	v_cvt_pk_bf16_f32 v106, v106, v107
	global_store_dword v[130:131], v106, off
	v_add_f32_e32 v82, v84, v82
	v_add_f32_e32 v83, v85, v83
	v_div_scale_f32 v87, s[0:1], v7, v7, 1.0
	v_rcp_f32_e32 v89, v87
	v_fma_f32 v84, v112, v82, -v78
	v_fma_f32 v85, v112, v83, -v79
	v_cvt_pk_bf16_f32 v84, v84, v85
	global_store_dword v[126:127], v84, off
	v_fma_f32 v106, -v87, v89, 1.0
	v_fmac_f32_e32 v89, v106, v89
	v_div_scale_f32 v106, vcc, 1.0, v7, 1.0
	v_mul_f32_e32 v107, v106, v89
	v_fma_f32 v116, -v87, v107, v106
	v_fmac_f32_e32 v107, v116, v89
	v_fma_f32 v87, -v87, v107, v106
	v_div_fmas_f32 v87, v87, v89, v107
	v_div_fixup_f32 v106, v87, v7, 1.0
	v_max_i32_e32 v7, 8, v149
	v_min_i32_e32 v87, v169, v117
	v_sub_u32_e32 v7, v87, v7
	v_add_u32_e32 v7, 8, v7
	v_cvt_f32_i32_e32 v7, v7
	v_add_f32_e64 v76, v48, -v76
	v_add_f32_e64 v77, v49, -v77
	v_add_f32_e64 v68, v46, -v68
	v_add_f32_e64 v69, v47, -v69
	v_add_f32_e32 v76, v82, v76
	v_add_f32_e32 v77, v83, v77
	v_div_scale_f32 v87, s[0:1], v7, v7, 1.0
	v_rcp_f32_e32 v89, v87
	v_fma_f32 v82, v108, v76, -v74
	v_fma_f32 v83, v108, v77, -v75
	v_cvt_pk_bf16_f32 v82, v82, v83
	global_store_dword v[120:121], v82, off
	v_fma_f32 v84, -v87, v89, 1.0
	v_fmac_f32_e32 v89, v84, v89
	v_div_scale_f32 v84, vcc, 1.0, v7, 1.0
	v_mul_f32_e32 v85, v84, v89
	v_fma_f32 v107, -v87, v85, v84
	v_fmac_f32_e32 v85, v107, v89
	v_fma_f32 v84, -v87, v85, v84
	v_div_fmas_f32 v84, v84, v89, v85
	v_div_fixup_f32 v84, v84, v7, 1.0
	v_max_i32_e32 v7, 8, v145
	v_min_i32_e32 v85, v168, v117
	v_sub_u32_e32 v7, v85, v7
	v_add_u32_e32 v7, 8, v7
	v_cvt_f32_i32_e32 v7, v7
	v_and_b32_e32 v105, 0xffff0000, v165
	v_add_f32_e32 v68, v76, v68
	v_add_f32_e32 v69, v77, v69
	v_add_f32_e64 v58, v44, -v58
	v_add_f32_e64 v59, v45, -v59
	v_div_scale_f32 v85, s[0:1], v7, v7, 1.0
	v_rcp_f32_e32 v87, v85
	v_fma_f32 v76, v104, v68, -v70
	v_fma_f32 v77, v104, v69, -v71
	v_cvt_pk_bf16_f32 v76, v76, v77
	global_store_dword v[114:115], v76, off
	v_fma_f32 v82, -v85, v87, 1.0
	v_fmac_f32_e32 v87, v82, v87
	v_div_scale_f32 v82, vcc, 1.0, v7, 1.0
	v_mul_f32_e32 v83, v82, v87
	v_fma_f32 v89, -v85, v83, v82
	v_fmac_f32_e32 v83, v89, v87
	v_fma_f32 v82, -v85, v83, v82
	v_div_fmas_f32 v82, v82, v87, v83
	v_div_fixup_f32 v82, v82, v7, 1.0
	v_max_i32_e32 v7, 8, v141
	v_min_i32_e32 v83, v167, v117
	v_sub_u32_e32 v7, v83, v7
	v_add_u32_e32 v7, 8, v7
	v_cvt_f32_i32_e32 v7, v7
	v_add_f32_e32 v58, v68, v58
	v_add_f32_e32 v59, v69, v59
	v_add_f32_e64 v52, v42, -v52
	v_add_f32_e64 v53, v43, -v53
	v_fma_f32 v68, v0, v58, -v64
	v_fma_f32 v69, v0, v59, -v65
	v_div_scale_f32 v83, s[0:1], v7, v7, 1.0
	v_rcp_f32_e32 v85, v83
	v_cvt_pk_bf16_f32 v0, v68, v69
	global_store_dword v[110:111], v0, off
	v_add_f32_e32 v52, v58, v52
	v_add_f32_e32 v53, v59, v53
	v_fma_f32 v76, -v83, v85, 1.0
	v_fmac_f32_e32 v85, v76, v85
	v_div_scale_f32 v76, vcc, 1.0, v7, 1.0
	v_mul_f32_e32 v77, v76, v85
	v_fma_f32 v87, -v83, v77, v76
	v_fmac_f32_e32 v77, v87, v85
	v_fma_f32 v76, -v83, v77, v76
	v_div_fmas_f32 v76, v76, v85, v77
	v_div_fixup_f32 v76, v76, v7, 1.0
	v_max_i32_e32 v7, 8, v137
	v_min_i32_e32 v77, v166, v117
	v_sub_u32_e32 v7, v77, v7
	v_add_u32_e32 v7, 8, v7
	v_cvt_f32_i32_e32 v7, v7
	v_add_f32_e64 v50, v40, -v50
	v_add_f32_e64 v51, v41, -v51
	v_fma_f32 v58, v118, v52, -v90
	v_fma_f32 v59, v118, v53, -v91
	v_add_f32_e32 v50, v52, v50
	v_add_f32_e32 v51, v53, v51
	v_div_scale_f32 v77, s[0:1], v7, v7, 1.0
	v_rcp_f32_e32 v83, v77
	v_fma_f32 v52, v136, v50, -v60
	v_fma_f32 v53, v136, v51, -v61
	v_lshlrev_b64 v[26:27], 11, v[26:27]
	v_lshl_add_u64 v[26:27], v[4:5], 0, v[26:27]
	v_fma_f32 v0, -v77, v83, 1.0
	v_fmac_f32_e32 v83, v0, v83
	v_div_scale_f32 v0, vcc, 1.0, v7, 1.0
	v_mul_f32_e32 v68, v0, v83
	v_fma_f32 v69, -v77, v68, v0
	v_fmac_f32_e32 v68, v69, v83
	v_fma_f32 v0, -v77, v68, v0
	v_div_fmas_f32 v0, v0, v83, v68
	v_div_fixup_f32 v0, v0, v7, 1.0
	v_cvt_pk_bf16_f32 v7, v58, v59
	global_store_dword v[122:123], v7, off
	v_cvt_pk_bf16_f32 v7, v52, v53
	v_add_f32_e64 v52, v38, -v66
	v_add_f32_e64 v53, v39, -v67
	global_store_dword v[138:139], v7, off
	v_add_f32_e32 v50, v50, v52
	v_add_f32_e32 v51, v51, v53
	v_lshlrev_b64 v[22:23], 11, v[22:23]
	v_fma_f32 v52, v140, v50, -v56
	v_fma_f32 v53, v140, v51, -v57
	v_cvt_pk_bf16_f32 v7, v52, v53
	v_add_f32_e64 v52, v36, -v72
	v_add_f32_e64 v53, v37, -v73
	global_store_dword v[142:143], v7, off
	v_add_f32_e32 v50, v50, v52
	v_add_f32_e32 v51, v51, v53
	v_lshl_add_u64 v[22:23], v[4:5], 0, v[22:23]
	v_fma_f32 v52, v144, v50, -v54
	v_fma_f32 v53, v144, v51, -v55
	v_cvt_pk_bf16_f32 v7, v52, v53
	v_add_f32_e64 v52, v34, -v80
	v_add_f32_e64 v53, v35, -v81
	global_store_dword v[146:147], v7, off
	v_add_f32_e32 v50, v50, v52
	v_add_f32_e32 v51, v51, v53
	v_lshlrev_b64 v[20:21], 11, v[20:21]
	v_fma_f32 v52, v148, v50, -v48
	v_fma_f32 v53, v148, v51, -v49
	v_cvt_pk_bf16_f32 v7, v52, v53
	v_add_f32_e64 v52, v32, -v78
	v_add_f32_e64 v53, v33, -v79
	global_store_dword v[150:151], v7, off
	v_add_f32_e32 v50, v50, v52
	v_add_f32_e32 v51, v51, v53
	v_lshl_add_u64 v[20:21], v[4:5], 0, v[20:21]
	v_fma_f32 v52, v152, v50, -v46
	v_fma_f32 v53, v152, v51, -v47
	v_cvt_pk_bf16_f32 v7, v52, v53
	v_add_f32_e64 v52, v30, -v74
	v_add_f32_e64 v53, v31, -v75
	global_store_dword v[154:155], v7, off
	v_add_f32_e32 v50, v50, v52
	v_add_f32_e32 v51, v51, v53
	v_lshlrev_b64 v[18:19], 11, v[18:19]
	v_fma_f32 v52, v156, v50, -v44
	v_fma_f32 v53, v156, v51, -v45
	v_cvt_pk_bf16_f32 v7, v52, v53
	v_add_f32_e64 v52, v28, -v70
	v_add_f32_e64 v53, v29, -v71
	global_store_dword v[158:159], v7, off
	v_add_f32_e32 v50, v50, v52
	v_add_f32_e32 v51, v51, v53
	v_lshl_add_u64 v[18:19], v[4:5], 0, v[18:19]
	v_fma_f32 v52, v160, v50, -v42
	v_fma_f32 v53, v160, v51, -v43
	v_cvt_pk_bf16_f32 v7, v52, v53
	v_add_f32_e64 v52, v24, -v64
	v_add_f32_e64 v53, v25, -v65
	global_store_dword v[162:163], v7, off
	v_add_f32_e32 v50, v50, v52
	v_add_f32_e32 v51, v51, v53
	v_lshlrev_b64 v[16:17], 11, v[16:17]
	v_fma_f32 v40, v164, v50, -v40
	v_fma_f32 v41, v164, v51, -v41
	v_cvt_pk_bf16_f32 v7, v40, v41
	global_store_dword v[26:27], v7, off
	v_add_f32_e64 v26, v62, -v90
	v_add_f32_e64 v27, v63, -v91
	v_lshl_add_u64 v[16:17], v[4:5], 0, v[16:17]
	v_add_f32_e32 v26, v50, v26
	v_add_f32_e32 v27, v51, v27
	v_lshlrev_b64 v[14:15], 11, v[14:15]
	v_fma_f32 v38, v88, v26, -v38
	v_fma_f32 v39, v88, v27, -v39
	v_cvt_pk_bf16_f32 v7, v38, v39
	global_store_dword v[22:23], v7, off
	v_add_f32_e64 v22, v92, -v60
	v_add_f32_e64 v23, v93, -v61
	v_lshl_add_u64 v[14:15], v[4:5], 0, v[14:15]
	v_add_f32_e32 v22, v26, v22
	v_add_f32_e32 v23, v27, v23
	v_lshlrev_b64 v[12:13], 11, v[12:13]
	v_fma_f32 v26, v86, v22, -v36
	v_fma_f32 v27, v86, v23, -v37
	v_cvt_pk_bf16_f32 v7, v26, v27
	global_store_dword v[20:21], v7, off
	v_add_f32_e64 v20, v94, -v56
	v_add_f32_e64 v21, v95, -v57
	v_lshl_add_u64 v[12:13], v[4:5], 0, v[12:13]
	v_add_f32_e32 v20, v22, v20
	v_add_f32_e32 v21, v23, v21
	v_lshlrev_b64 v[10:11], 11, v[10:11]
	v_fma_f32 v22, v106, v20, -v34
	v_fma_f32 v23, v106, v21, -v35
	v_cvt_pk_bf16_f32 v7, v22, v23
	global_store_dword v[18:19], v7, off
	v_add_f32_e64 v18, v96, -v54
	v_add_f32_e64 v19, v97, -v55
	v_lshl_add_u64 v[10:11], v[4:5], 0, v[10:11]
	v_add_f32_e32 v18, v20, v18
	v_add_f32_e32 v19, v21, v19
	v_lshlrev_b32_e32 v104, 16, v165
	v_fma_f32 v20, v84, v18, -v32
	v_fma_f32 v21, v84, v19, -v33
	v_cvt_pk_bf16_f32 v7, v20, v21
	global_store_dword v[16:17], v7, off
	v_add_f32_e64 v16, v98, -v48
	v_add_f32_e64 v17, v99, -v49
	s_andn2_b64 s[14:15], s[14:15], exec
	v_add_f32_e32 v16, v18, v16
	v_add_f32_e32 v17, v19, v17
	s_nop 0
	v_fma_f32 v18, v82, v16, -v30
	v_fma_f32 v19, v82, v17, -v31
	v_cvt_pk_bf16_f32 v7, v18, v19
	global_store_dword v[14:15], v7, off
	v_add_f32_e64 v14, v100, -v46
	v_add_f32_e64 v15, v101, -v47
	s_nop 0
	v_add_f32_e32 v14, v16, v14
	v_add_f32_e32 v15, v17, v15
	s_nop 0
	v_fma_f32 v16, v76, v14, -v28
	v_fma_f32 v17, v76, v15, -v29
	v_cvt_pk_bf16_f32 v7, v16, v17
	global_store_dword v[12:13], v7, off
	v_add_u32_e32 v12, 39, v119
	v_max_i32_e32 v7, 8, v129
	v_min_i32_e32 v12, v12, v117
	v_sub_u32_e32 v7, v12, v7
	v_add_u32_e32 v7, 8, v7
	v_cvt_f32_i32_e32 v7, v7
	v_add_f32_e64 v12, v102, -v44
	v_add_f32_e64 v13, v103, -v45
	v_div_scale_f32 v16, s[0:1], v7, v7, 1.0
	v_rcp_f32_e32 v17, v16
	v_add_f32_e32 v12, v14, v12
	v_add_f32_e32 v13, v15, v13
	s_nop 0
	v_fma_f32 v14, v0, v12, -v24
	v_fma_f32 v15, v0, v13, -v25
	v_cvt_pk_bf16_f32 v0, v14, v15
	global_store_dword v[10:11], v0, off
	v_fma_f32 v0, -v16, v17, 1.0
	v_fmac_f32_e32 v17, v0, v17
	v_div_scale_f32 v0, vcc, 1.0, v7, 1.0
	v_mul_f32_e32 v10, v0, v17
	v_fma_f32 v11, -v16, v10, v0
	v_fmac_f32_e32 v10, v11, v17
	v_fma_f32 v0, -v16, v10, v0
	v_div_fmas_f32 v0, v0, v17, v10
	v_add_f32_e64 v10, v104, -v42
	v_add_f32_e64 v11, v105, -v43
	v_div_fixup_f32 v0, v0, v7, 1.0
	v_add_f32_e32 v10, v12, v10
	v_add_f32_e32 v11, v13, v11
	s_nop 0
	v_fma_f32 v10, v0, v10, -v62
	v_fma_f32 v11, v0, v11, -v63
	s_or_b64 exec, exec, s[16:17]
	s_and_saveexec_b64 s[0:1], s[14:15]
	s_xor_b64 s[14:15], exec, s[0:1]
	s_cbranch_execz .LBB0_1159
	s_branch .LBB0_1088

.LBB0_1158:
	s_or_b64 exec, exec, s[16:17]
	v_lshlrev_b32_e32 v140, 16, v137
	v_and_b32_e32 v141, 0xffff0000, v137
	v_max_i32_e32 v125, 2, v119
	v_min_i32_e32 v137, v133, v117
	v_sub_u32_e32 v125, v137, v125
	v_add_u32_e32 v125, 2, v125
	v_cvt_f32_i32_e32 v125, v125
	v_lshlrev_b32_e32 v142, 16, v135
	v_and_b32_e32 v143, 0xffff0000, v135
	v_lshlrev_b32_e32 v144, 16, v7
	v_div_scale_f32 v135, s[0:1], v125, v125, 1.0
	v_rcp_f32_e32 v137, v135
	v_and_b32_e32 v145, 0xffff0000, v7
	v_lshlrev_b32_e32 v146, 16, v139
	v_and_b32_e32 v147, 0xffff0000, v139
	v_fma_f32 v7, -v135, v137, 1.0
	v_fmac_f32_e32 v137, v7, v137
	v_div_scale_f32 v7, vcc, 1.0, v125, 1.0
	v_mul_f32_e32 v139, v7, v137
	v_fma_f32 v148, -v135, v139, v7
	v_fmac_f32_e32 v139, v148, v137
	v_fma_f32 v7, -v135, v139, v7
	v_max_i32_e32 v135, 2, v136
	v_min_i32_e32 v136, v131, v117
	v_sub_u32_e32 v135, v136, v135
	v_add_u32_e32 v135, 2, v135
	v_cvt_f32_i32_e32 v135, v135
	v_add_f32_e32 v150, 0, v140
	v_add_f32_e32 v151, 0, v141
	v_div_fmas_f32 v7, v7, v137, v139
	v_add_f32_e32 v150, v150, v142
	v_add_f32_e32 v151, v151, v143
	v_div_scale_f32 v136, s[0:1], v135, v135, 1.0
	v_add_f32_e32 v150, v150, v144
	v_add_f32_e32 v151, v151, v145
	v_rcp_f32_e32 v137, v136
	v_div_fixup_f32 v148, v7, v125, 1.0
	v_add_f32_e32 v150, v150, v146
	v_add_f32_e32 v151, v151, v147
	v_ashrrev_i32_e32 v7, 31, v6
	v_fma_f32 v149, v148, v151, -v145
	v_fma_f32 v148, v148, v150, -v144
	v_lshlrev_b64 v[6:7], 11, v[6:7]
	v_cvt_pk_bf16_f32 v125, v148, v149
	v_lshl_add_u64 v[6:7], v[4:5], 0, v[6:7]
	global_store_dword v[6:7], v125, off
	v_fma_f32 v125, -v136, v137, 1.0
	v_fmac_f32_e32 v137, v125, v137
	v_div_scale_f32 v125, vcc, 1.0, v135, 1.0
	v_lshlrev_b32_e32 v6, 16, v138
	v_and_b32_e32 v7, 0xffff0000, v138
	v_mul_f32_e32 v138, v125, v137
	v_fma_f32 v139, -v136, v138, v125
	v_fmac_f32_e32 v138, v139, v137
	v_fma_f32 v125, -v136, v138, v125
	v_div_fmas_f32 v125, v125, v137, v138
	v_div_fixup_f32 v136, v125, v135, 1.0
	v_max_i32_e32 v133, 2, v133
	v_min_i32_e32 v135, v129, v117
	v_sub_u32_e32 v133, v135, v133
	v_add_u32_e32 v133, 2, v133
	v_cvt_f32_i32_e32 v133, v133
	v_add_f32_e64 v138, v6, -v140
	v_add_f32_e64 v139, v7, -v141
	v_lshlrev_b64 v[68:69], 11, v[68:69]
	v_add_f32_e32 v138, v150, v138
	v_add_f32_e32 v139, v151, v139
	v_div_scale_f32 v135, s[0:1], v133, v133, 1.0
	v_fma_f32 v137, v136, v139, -v147
	v_fma_f32 v136, v136, v138, -v146
	v_cvt_pk_bf16_f32 v125, v136, v137
	v_rcp_f32_e32 v136, v135
	v_lshl_add_u64 v[68:69], v[4:5], 0, v[68:69]
	global_store_dword v[68:69], v125, off
	v_lshlrev_b32_e32 v68, 16, v132
	v_fma_f32 v125, -v135, v136, 1.0
	v_fmac_f32_e32 v136, v125, v136
	v_div_scale_f32 v125, vcc, 1.0, v133, 1.0
	v_and_b32_e32 v69, 0xffff0000, v132
	v_mul_f32_e32 v132, v125, v136
	v_fma_f32 v137, -v135, v132, v125
	v_fmac_f32_e32 v132, v137, v136
	v_fma_f32 v125, -v135, v132, v125
	v_div_fmas_f32 v125, v125, v136, v132
	v_add_f32_e64 v136, v68, -v142
	v_add_f32_e64 v137, v69, -v143
	v_div_fixup_f32 v132, v125, v133, 1.0
	v_add_f32_e32 v136, v138, v136
	v_add_f32_e32 v137, v139, v137
	v_max_i32_e32 v131, 2, v131
	v_fma_f32 v133, v132, v137, -v7
	v_fma_f32 v132, v132, v136, -v6
	v_cvt_pk_bf16_f32 v125, v132, v133
	v_min_i32_e32 v132, v127, v117
	v_sub_u32_e32 v131, v132, v131
	v_add_u32_e32 v131, 2, v131
	v_cvt_f32_i32_e32 v131, v131
	v_lshlrev_b64 v[66:67], 11, v[66:67]
	v_lshl_add_u64 v[66:67], v[4:5], 0, v[66:67]
	global_store_dword v[66:67], v125, off
	v_div_scale_f32 v132, s[0:1], v131, v131, 1.0
	v_rcp_f32_e32 v133, v132
	v_lshlrev_b32_e32 v66, 16, v134
	v_and_b32_e32 v67, 0xffff0000, v134
	v_max_i32_e32 v129, 2, v129
	v_fma_f32 v125, -v132, v133, 1.0
	v_fmac_f32_e32 v133, v125, v133
	v_div_scale_f32 v125, vcc, 1.0, v131, 1.0
	v_mul_f32_e32 v134, v125, v133
	v_fma_f32 v135, -v132, v134, v125
	v_fmac_f32_e32 v134, v135, v133
	v_fma_f32 v125, -v132, v134, v125
	v_div_fmas_f32 v125, v125, v133, v134
	v_div_fixup_f32 v132, v125, v131, 1.0
	v_min_i32_e32 v131, v124, v117
	v_sub_u32_e32 v129, v131, v129
	v_add_u32_e32 v129, 2, v129
	v_cvt_f32_i32_e32 v129, v129
	v_add_f32_e64 v134, v66, -v144
	v_add_f32_e64 v135, v67, -v145
	v_lshlrev_b64 v[64:65], 11, v[64:65]
	v_add_f32_e32 v134, v136, v134
	v_add_f32_e32 v135, v137, v135
	v_div_scale_f32 v131, s[0:1], v129, v129, 1.0
	v_fma_f32 v133, v132, v135, -v69
	v_fma_f32 v132, v132, v134, -v68
	v_cvt_pk_bf16_f32 v125, v132, v133
	v_rcp_f32_e32 v132, v131
	v_lshl_add_u64 v[64:65], v[4:5], 0, v[64:65]
	global_store_dword v[64:65], v125, off
	v_lshlrev_b32_e32 v64, 16, v128
	v_fma_f32 v125, -v131, v132, 1.0
	v_fmac_f32_e32 v132, v125, v132
	v_div_scale_f32 v125, vcc, 1.0, v129, 1.0
	v_and_b32_e32 v65, 0xffff0000, v128
	v_mul_f32_e32 v128, v125, v132
	v_fma_f32 v133, -v131, v128, v125
	v_fmac_f32_e32 v128, v133, v132
	v_fma_f32 v125, -v131, v128, v125
	v_div_fmas_f32 v125, v125, v132, v128
	v_add_f32_e64 v132, v64, -v146
	v_add_f32_e64 v133, v65, -v147
	v_div_fixup_f32 v128, v125, v129, 1.0
	v_add_f32_e32 v132, v134, v132
	v_add_f32_e32 v133, v135, v133
	v_max_i32_e32 v127, 2, v127
	v_fma_f32 v129, v128, v133, -v67
	v_fma_f32 v128, v128, v132, -v66
	v_cvt_pk_bf16_f32 v125, v128, v129
	v_min_i32_e32 v128, v122, v117
	v_sub_u32_e32 v127, v128, v127
	v_add_u32_e32 v127, 2, v127
	v_cvt_f32_i32_e32 v127, v127
	v_lshlrev_b64 v[62:63], 11, v[62:63]
	v_lshl_add_u64 v[62:63], v[4:5], 0, v[62:63]
	global_store_dword v[62:63], v125, off
	v_div_scale_f32 v128, s[0:1], v127, v127, 1.0
	v_rcp_f32_e32 v129, v128
	v_lshlrev_b32_e32 v62, 16, v130
	v_and_b32_e32 v63, 0xffff0000, v130
	v_max_i32_e32 v124, 2, v124
	v_fma_f32 v125, -v128, v129, 1.0
	v_fmac_f32_e32 v129, v125, v129
	v_div_scale_f32 v125, vcc, 1.0, v127, 1.0
	v_mul_f32_e32 v130, v125, v129
	v_fma_f32 v131, -v128, v130, v125
	v_fmac_f32_e32 v130, v131, v129
	v_fma_f32 v125, -v128, v130, v125
	v_div_fmas_f32 v125, v125, v129, v130
	v_div_fixup_f32 v128, v125, v127, 1.0
	v_min_i32_e32 v127, v120, v117
	v_sub_u32_e32 v124, v127, v124
	v_add_u32_e32 v124, 2, v124
	v_cvt_f32_i32_e32 v124, v124
	v_add_f32_e64 v6, v62, -v6
	v_add_f32_e64 v7, v63, -v7
	v_lshlrev_b64 v[60:61], 11, v[60:61]
	v_add_f32_e32 v6, v132, v6
	v_add_f32_e32 v7, v133, v7
	v_div_scale_f32 v127, s[0:1], v124, v124, 1.0
	v_fma_f32 v129, v128, v7, -v65
	v_fma_f32 v128, v128, v6, -v64
	v_cvt_pk_bf16_f32 v125, v128, v129
	v_rcp_f32_e32 v128, v127
	v_lshl_add_u64 v[60:61], v[4:5], 0, v[60:61]
	global_store_dword v[60:61], v125, off
	v_lshlrev_b32_e32 v60, 16, v123
	v_and_b32_e32 v61, 0xffff0000, v123
	v_fma_f32 v123, -v127, v128, 1.0
	v_fmac_f32_e32 v128, v123, v128
	v_div_scale_f32 v123, vcc, 1.0, v124, 1.0
	v_mul_f32_e32 v125, v123, v128
	v_fma_f32 v129, -v127, v125, v123
	v_fmac_f32_e32 v125, v129, v128
	v_fma_f32 v123, -v127, v125, v123
	v_div_fmas_f32 v123, v123, v128, v125
	v_add_f32_e64 v68, v60, -v68
	v_add_f32_e64 v69, v61, -v69
	v_div_fixup_f32 v124, v123, v124, 1.0
	v_add_f32_e32 v6, v6, v68
	v_add_f32_e32 v7, v7, v69
	v_lshlrev_b64 v[58:59], 11, v[58:59]
	v_fma_f32 v68, v124, v6, -v62
	v_fma_f32 v69, v124, v7, -v63
	v_cvt_pk_bf16_f32 v68, v68, v69
	v_max_i32_e32 v69, 2, v122
	v_min_i32_e32 v122, v116, v117
	v_sub_u32_e32 v69, v122, v69
	v_add_u32_e32 v69, 2, v69
	v_cvt_f32_i32_e32 v69, v69
	v_lshl_add_u64 v[58:59], v[4:5], 0, v[58:59]
	global_store_dword v[58:59], v68, off
	v_lshlrev_b32_e32 v58, 16, v126
	v_div_scale_f32 v122, s[0:1], v69, v69, 1.0
	v_rcp_f32_e32 v123, v122
	v_and_b32_e32 v59, 0xffff0000, v126
	v_add_f32_e64 v66, v58, -v66
	v_add_f32_e64 v67, v59, -v67
	v_lshlrev_b64 v[56:57], 11, v[56:57]
	v_fma_f32 v68, -v122, v123, 1.0
	v_fmac_f32_e32 v123, v68, v123
	v_div_scale_f32 v68, vcc, 1.0, v69, 1.0
	v_mul_f32_e32 v124, v68, v123
	v_fma_f32 v125, -v122, v124, v68
	v_fmac_f32_e32 v124, v125, v123
	v_fma_f32 v68, -v122, v124, v68
	v_div_fmas_f32 v68, v68, v123, v124
	v_div_fixup_f32 v68, v68, v69, 1.0
	v_add_f32_e32 v6, v6, v66
	v_add_f32_e32 v7, v7, v67
	v_lshl_add_u64 v[56:57], v[4:5], 0, v[56:57]
	v_fma_f32 v66, v68, v6, -v60
	v_fma_f32 v67, v68, v7, -v61
	v_cvt_pk_bf16_f32 v66, v66, v67
	v_max_i32_e32 v67, 2, v120
	v_min_i32_e32 v68, v114, v117
	v_sub_u32_e32 v67, v68, v67
	v_add_u32_e32 v67, 2, v67
	v_cvt_f32_i32_e32 v67, v67
	global_store_dword v[56:57], v66, off
	v_lshlrev_b32_e32 v56, 16, v118
	v_and_b32_e32 v57, 0xffff0000, v118
	v_div_scale_f32 v68, s[0:1], v67, v67, 1.0
	v_rcp_f32_e32 v69, v68
	v_add_f32_e64 v64, v56, -v64
	v_add_f32_e64 v65, v57, -v65
	v_lshlrev_b64 v[54:55], 11, v[54:55]
	v_add_f32_e32 v6, v6, v64
	v_add_f32_e32 v7, v7, v65
	v_fma_f32 v66, -v68, v69, 1.0
	v_fmac_f32_e32 v69, v66, v69
	v_div_scale_f32 v66, vcc, 1.0, v67, 1.0
	v_mul_f32_e32 v118, v66, v69
	v_fma_f32 v120, -v68, v118, v66
	v_fmac_f32_e32 v118, v120, v69
	v_fma_f32 v66, -v68, v118, v66
	v_div_fmas_f32 v66, v66, v69, v118
	v_div_fixup_f32 v66, v66, v67, 1.0
	v_fma_f32 v64, v66, v6, -v58
	v_fma_f32 v65, v66, v7, -v59
	v_cvt_pk_bf16_f32 v64, v64, v65
	v_max_i32_e32 v65, 2, v116
	v_min_i32_e32 v66, v111, v117
	v_sub_u32_e32 v65, v66, v65
	v_add_u32_e32 v65, 2, v65
	v_cvt_f32_i32_e32 v65, v65
	v_lshl_add_u64 v[54:55], v[4:5], 0, v[54:55]
	global_store_dword v[54:55], v64, off
	v_lshlrev_b32_e32 v54, 16, v121
	v_div_scale_f32 v66, s[0:1], v65, v65, 1.0
	v_rcp_f32_e32 v67, v66
	v_and_b32_e32 v55, 0xffff0000, v121
	v_add_f32_e64 v62, v54, -v62
	v_add_f32_e64 v63, v55, -v63
	v_lshlrev_b64 v[52:53], 11, v[52:53]
	v_fma_f32 v64, -v66, v67, 1.0
	v_fmac_f32_e32 v67, v64, v67
	v_div_scale_f32 v64, vcc, 1.0, v65, 1.0
	v_mul_f32_e32 v68, v64, v67
	v_fma_f32 v69, -v66, v68, v64
	v_fmac_f32_e32 v68, v69, v67
	v_fma_f32 v64, -v66, v68, v64
	v_div_fmas_f32 v64, v64, v67, v68
	v_div_fixup_f32 v64, v64, v65, 1.0
	v_add_f32_e32 v6, v6, v62
	v_add_f32_e32 v7, v7, v63
	v_lshl_add_u64 v[52:53], v[4:5], 0, v[52:53]
	v_fma_f32 v62, v64, v6, -v56
	v_fma_f32 v63, v64, v7, -v57
	v_cvt_pk_bf16_f32 v62, v62, v63
	v_max_i32_e32 v63, 2, v114
	v_min_i32_e32 v64, v108, v117
	v_sub_u32_e32 v63, v64, v63
	v_add_u32_e32 v63, 2, v63
	v_cvt_f32_i32_e32 v63, v63
	global_store_dword v[52:53], v62, off
	v_lshlrev_b32_e32 v52, 16, v112
	v_and_b32_e32 v53, 0xffff0000, v112
	v_div_scale_f32 v64, s[0:1], v63, v63, 1.0
	v_rcp_f32_e32 v65, v64
	v_add_f32_e64 v60, v52, -v60
	v_add_f32_e64 v61, v53, -v61
	v_lshlrev_b64 v[50:51], 11, v[50:51]
	v_add_f32_e32 v6, v6, v60
	v_add_f32_e32 v7, v7, v61
	v_fma_f32 v62, -v64, v65, 1.0
	v_fmac_f32_e32 v65, v62, v65
	v_div_scale_f32 v62, vcc, 1.0, v63, 1.0
	v_mul_f32_e32 v66, v62, v65
	v_fma_f32 v67, -v64, v66, v62
	v_fmac_f32_e32 v66, v67, v65
	v_fma_f32 v62, -v64, v66, v62
	v_div_fmas_f32 v62, v62, v65, v66
	v_div_fixup_f32 v62, v62, v63, 1.0
	v_fma_f32 v60, v62, v6, -v54
	v_fma_f32 v61, v62, v7, -v55
	v_cvt_pk_bf16_f32 v60, v60, v61
	v_max_i32_e32 v61, 2, v111
	v_min_i32_e32 v62, v106, v117
	v_sub_u32_e32 v61, v62, v61
	v_add_u32_e32 v61, 2, v61
	v_cvt_f32_i32_e32 v61, v61
	v_lshl_add_u64 v[50:51], v[4:5], 0, v[50:51]
	global_store_dword v[50:51], v60, off
	v_lshlrev_b32_e32 v50, 16, v115
	v_div_scale_f32 v62, s[0:1], v61, v61, 1.0
	v_rcp_f32_e32 v63, v62
	v_and_b32_e32 v51, 0xffff0000, v115
	v_add_f32_e64 v58, v50, -v58
	v_add_f32_e64 v59, v51, -v59
	v_lshlrev_b64 v[48:49], 11, v[48:49]
	v_fma_f32 v60, -v62, v63, 1.0
	v_fmac_f32_e32 v63, v60, v63
	v_div_scale_f32 v60, vcc, 1.0, v61, 1.0
	v_mul_f32_e32 v64, v60, v63
	v_fma_f32 v65, -v62, v64, v60
	v_fmac_f32_e32 v64, v65, v63
	v_fma_f32 v60, -v62, v64, v60
	v_div_fmas_f32 v60, v60, v63, v64
	v_div_fixup_f32 v60, v60, v61, 1.0
	v_add_f32_e32 v6, v6, v58
	v_add_f32_e32 v7, v7, v59
	v_lshl_add_u64 v[48:49], v[4:5], 0, v[48:49]
	v_fma_f32 v58, v60, v6, -v52
	v_fma_f32 v59, v60, v7, -v53
	v_cvt_pk_bf16_f32 v58, v58, v59
	v_max_i32_e32 v59, 2, v108
	v_min_i32_e32 v60, v104, v117
	v_sub_u32_e32 v59, v60, v59
	v_add_u32_e32 v59, 2, v59
	v_cvt_f32_i32_e32 v59, v59
	global_store_dword v[48:49], v58, off
	v_lshlrev_b32_e32 v48, 16, v107
	v_and_b32_e32 v49, 0xffff0000, v107
	v_div_scale_f32 v60, s[0:1], v59, v59, 1.0
	v_rcp_f32_e32 v61, v60
	v_add_f32_e64 v56, v48, -v56
	v_add_f32_e64 v57, v49, -v57
	v_lshlrev_b64 v[46:47], 11, v[46:47]
	v_add_f32_e32 v6, v6, v56
	v_add_f32_e32 v7, v7, v57
	v_fma_f32 v58, -v60, v61, 1.0
	v_fmac_f32_e32 v61, v58, v61
	v_div_scale_f32 v58, vcc, 1.0, v59, 1.0
	v_mul_f32_e32 v62, v58, v61
	v_fma_f32 v63, -v60, v62, v58
	v_fmac_f32_e32 v62, v63, v61
	v_fma_f32 v58, -v60, v62, v58
	v_div_fmas_f32 v58, v58, v61, v62
	v_div_fixup_f32 v58, v58, v59, 1.0
	v_fma_f32 v56, v58, v6, -v50
	v_fma_f32 v57, v58, v7, -v51
	v_cvt_pk_bf16_f32 v56, v56, v57
	v_max_i32_e32 v57, 2, v106
	v_min_i32_e32 v58, v102, v117
	v_sub_u32_e32 v57, v58, v57
	v_add_u32_e32 v57, 2, v57
	v_cvt_f32_i32_e32 v57, v57
	v_lshl_add_u64 v[46:47], v[4:5], 0, v[46:47]
	global_store_dword v[46:47], v56, off
	v_lshlrev_b32_e32 v46, 16, v110
	v_div_scale_f32 v58, s[0:1], v57, v57, 1.0
	v_rcp_f32_e32 v59, v58
	v_and_b32_e32 v47, 0xffff0000, v110
	v_add_f32_e64 v54, v46, -v54
	v_add_f32_e64 v55, v47, -v55
	v_lshlrev_b64 v[44:45], 11, v[44:45]
	v_fma_f32 v56, -v58, v59, 1.0
	v_fmac_f32_e32 v59, v56, v59
	v_div_scale_f32 v56, vcc, 1.0, v57, 1.0
	v_mul_f32_e32 v60, v56, v59
	v_fma_f32 v61, -v58, v60, v56
	v_fmac_f32_e32 v60, v61, v59
	v_fma_f32 v56, -v58, v60, v56
	v_div_fmas_f32 v56, v56, v59, v60
	v_div_fixup_f32 v56, v56, v57, 1.0
	v_add_f32_e32 v6, v6, v54
	v_add_f32_e32 v7, v7, v55
	v_lshl_add_u64 v[44:45], v[4:5], 0, v[44:45]
	v_fma_f32 v54, v56, v6, -v48
	v_fma_f32 v55, v56, v7, -v49
	v_cvt_pk_bf16_f32 v54, v54, v55
	v_max_i32_e32 v55, 2, v104
	v_min_i32_e32 v56, v100, v117
	v_sub_u32_e32 v55, v56, v55
	v_add_u32_e32 v55, 2, v55
	v_cvt_f32_i32_e32 v55, v55
	global_store_dword v[44:45], v54, off
	v_lshlrev_b32_e32 v44, 16, v103
	v_and_b32_e32 v45, 0xffff0000, v103
	v_div_scale_f32 v56, s[0:1], v55, v55, 1.0
	v_rcp_f32_e32 v57, v56
	v_add_f32_e64 v52, v44, -v52
	v_add_f32_e64 v53, v45, -v53
	v_lshlrev_b64 v[42:43], 11, v[42:43]
	v_add_f32_e32 v6, v6, v52
	v_add_f32_e32 v7, v7, v53
	v_fma_f32 v54, -v56, v57, 1.0
	v_fmac_f32_e32 v57, v54, v57
	v_div_scale_f32 v54, vcc, 1.0, v55, 1.0
	v_mul_f32_e32 v58, v54, v57
	v_fma_f32 v59, -v56, v58, v54
	v_fmac_f32_e32 v58, v59, v57
	v_fma_f32 v54, -v56, v58, v54
	v_div_fmas_f32 v54, v54, v57, v58
	v_div_fixup_f32 v54, v54, v55, 1.0
	v_fma_f32 v52, v54, v6, -v46
	v_fma_f32 v53, v54, v7, -v47
	v_cvt_pk_bf16_f32 v52, v52, v53
	v_max_i32_e32 v53, 2, v102
	v_min_i32_e32 v54, v98, v117
	v_sub_u32_e32 v53, v54, v53
	v_add_u32_e32 v53, 2, v53
	v_cvt_f32_i32_e32 v53, v53
	v_lshl_add_u64 v[42:43], v[4:5], 0, v[42:43]
	global_store_dword v[42:43], v52, off
	v_lshlrev_b32_e32 v42, 16, v105
	v_div_scale_f32 v54, s[0:1], v53, v53, 1.0
	v_rcp_f32_e32 v55, v54
	v_and_b32_e32 v43, 0xffff0000, v105
	v_add_f32_e64 v50, v42, -v50
	v_add_f32_e64 v51, v43, -v51
	v_lshlrev_b64 v[40:41], 11, v[40:41]
	v_fma_f32 v52, -v54, v55, 1.0
	v_fmac_f32_e32 v55, v52, v55
	v_div_scale_f32 v52, vcc, 1.0, v53, 1.0
	v_mul_f32_e32 v56, v52, v55
	v_fma_f32 v57, -v54, v56, v52
	v_fmac_f32_e32 v56, v57, v55
	v_fma_f32 v52, -v54, v56, v52
	v_div_fmas_f32 v52, v52, v55, v56
	v_div_fixup_f32 v52, v52, v53, 1.0
	v_add_f32_e32 v6, v6, v50
	v_add_f32_e32 v7, v7, v51
	v_lshl_add_u64 v[40:41], v[4:5], 0, v[40:41]
	v_fma_f32 v50, v52, v6, -v44
	v_fma_f32 v51, v52, v7, -v45
	v_cvt_pk_bf16_f32 v50, v50, v51
	v_max_i32_e32 v51, 2, v100
	v_min_i32_e32 v52, v96, v117
	v_sub_u32_e32 v51, v52, v51
	v_add_u32_e32 v51, 2, v51
	v_cvt_f32_i32_e32 v51, v51
	global_store_dword v[40:41], v50, off
	v_lshlrev_b32_e32 v40, 16, v99
	v_and_b32_e32 v41, 0xffff0000, v99
	v_div_scale_f32 v52, s[0:1], v51, v51, 1.0
	v_rcp_f32_e32 v53, v52
	v_add_f32_e64 v48, v40, -v48
	v_add_f32_e64 v49, v41, -v49
	v_lshlrev_b64 v[38:39], 11, v[38:39]
	v_add_f32_e32 v6, v6, v48
	v_add_f32_e32 v7, v7, v49
	v_fma_f32 v50, -v52, v53, 1.0
	v_fmac_f32_e32 v53, v50, v53
	v_div_scale_f32 v50, vcc, 1.0, v51, 1.0
	v_mul_f32_e32 v54, v50, v53
	v_fma_f32 v55, -v52, v54, v50
	v_fmac_f32_e32 v54, v55, v53
	v_fma_f32 v50, -v52, v54, v50
	v_div_fmas_f32 v50, v50, v53, v54
	v_div_fixup_f32 v50, v50, v51, 1.0
	v_fma_f32 v48, v50, v6, -v42
	v_fma_f32 v49, v50, v7, -v43
	v_cvt_pk_bf16_f32 v48, v48, v49
	v_max_i32_e32 v49, 2, v98
	v_min_i32_e32 v50, v93, v117
	v_sub_u32_e32 v49, v50, v49
	v_add_u32_e32 v49, 2, v49
	v_cvt_f32_i32_e32 v49, v49
	v_lshl_add_u64 v[38:39], v[4:5], 0, v[38:39]
	global_store_dword v[38:39], v48, off
	s_waitcnt vmcnt(0)
	v_lshlrev_b32_e32 v38, 16, v101
	v_div_scale_f32 v50, s[0:1], v49, v49, 1.0
	v_rcp_f32_e32 v51, v50
	v_and_b32_e32 v39, 0xffff0000, v101
	v_add_f32_e64 v46, v38, -v46
	v_add_f32_e64 v47, v39, -v47
	v_lshlrev_b64 v[36:37], 11, v[36:37]
	v_fma_f32 v48, -v50, v51, 1.0
	v_fmac_f32_e32 v51, v48, v51
	v_div_scale_f32 v48, vcc, 1.0, v49, 1.0
	v_mul_f32_e32 v52, v48, v51
	v_fma_f32 v53, -v50, v52, v48
	v_fmac_f32_e32 v52, v53, v51
	v_fma_f32 v48, -v50, v52, v48
	v_div_fmas_f32 v48, v48, v51, v52
	v_div_fixup_f32 v48, v48, v49, 1.0
	v_add_f32_e32 v6, v6, v46
	v_add_f32_e32 v7, v7, v47
	v_lshl_add_u64 v[36:37], v[4:5], 0, v[36:37]
	v_fma_f32 v46, v48, v6, -v40
	v_fma_f32 v47, v48, v7, -v41
	v_cvt_pk_bf16_f32 v46, v46, v47
	v_max_i32_e32 v47, 2, v96
	v_min_i32_e32 v48, v90, v117
	v_sub_u32_e32 v47, v48, v47
	v_add_u32_e32 v47, 2, v47
	v_cvt_f32_i32_e32 v47, v47
	global_store_dword v[36:37], v46, off
	v_lshlrev_b32_e32 v36, 16, v95
	v_and_b32_e32 v37, 0xffff0000, v95
	v_div_scale_f32 v48, s[0:1], v47, v47, 1.0
	v_rcp_f32_e32 v49, v48
	v_add_f32_e64 v44, v36, -v44
	v_add_f32_e64 v45, v37, -v45
	v_lshlrev_b64 v[34:35], 11, v[34:35]
	v_add_f32_e32 v6, v6, v44
	v_add_f32_e32 v7, v7, v45
	v_fma_f32 v46, -v48, v49, 1.0
	v_fmac_f32_e32 v49, v46, v49
	v_div_scale_f32 v46, vcc, 1.0, v47, 1.0
	v_mul_f32_e32 v50, v46, v49
	v_fma_f32 v51, -v48, v50, v46
	v_fmac_f32_e32 v50, v51, v49
	v_fma_f32 v46, -v48, v50, v46
	v_div_fmas_f32 v46, v46, v49, v50
	v_div_fixup_f32 v46, v46, v47, 1.0
	v_fma_f32 v44, v46, v6, -v38
	v_fma_f32 v45, v46, v7, -v39
	v_cvt_pk_bf16_f32 v44, v44, v45
	v_max_i32_e32 v45, 2, v93
	v_min_i32_e32 v46, v87, v117
	v_sub_u32_e32 v45, v46, v45
	v_add_u32_e32 v45, 2, v45
	v_cvt_f32_i32_e32 v45, v45
	v_lshl_add_u64 v[34:35], v[4:5], 0, v[34:35]
	global_store_dword v[34:35], v44, off
	v_lshlrev_b32_e32 v34, 16, v97
	v_div_scale_f32 v46, s[0:1], v45, v45, 1.0
	v_rcp_f32_e32 v47, v46
	v_and_b32_e32 v35, 0xffff0000, v97
	v_add_f32_e64 v42, v34, -v42
	v_add_f32_e64 v43, v35, -v43
	v_lshlrev_b64 v[30:31], 11, v[30:31]
	v_fma_f32 v44, -v46, v47, 1.0
	v_fmac_f32_e32 v47, v44, v47
	v_div_scale_f32 v44, vcc, 1.0, v45, 1.0
	v_mul_f32_e32 v48, v44, v47
	v_fma_f32 v49, -v46, v48, v44
	v_fmac_f32_e32 v48, v49, v47
	v_fma_f32 v44, -v46, v48, v44
	v_div_fmas_f32 v44, v44, v47, v48
	v_div_fixup_f32 v44, v44, v45, 1.0
	v_add_f32_e32 v42, v6, v42
	v_add_f32_e32 v43, v7, v43
	v_lshl_add_u64 v[30:31], v[4:5], 0, v[30:31]
	v_fma_f32 v6, v44, v42, -v36
	v_fma_f32 v7, v44, v43, -v37
	v_cvt_pk_bf16_f32 v44, v6, v7
	v_max_i32_e32 v6, 2, v90
	v_min_i32_e32 v7, v85, v117
	v_sub_u32_e32 v6, v7, v6
	v_add_u32_e32 v6, 2, v6
	v_cvt_f32_i32_e32 v45, v6
	v_lshlrev_b64 v[6:7], 11, v[32:33]
	v_lshl_add_u64 v[6:7], v[4:5], 0, v[6:7]
	global_store_dword v[6:7], v44, off
	v_div_scale_f32 v32, s[0:1], v45, v45, 1.0
	v_rcp_f32_e32 v33, v32
	v_lshlrev_b32_e32 v6, 16, v89
	v_and_b32_e32 v7, 0xffff0000, v89
	v_add_f32_e64 v40, v6, -v40
	v_add_f32_e64 v41, v7, -v41
	v_fma_f32 v44, -v32, v33, 1.0
	v_fmac_f32_e32 v33, v44, v33
	v_div_scale_f32 v44, vcc, 1.0, v45, 1.0
	v_mul_f32_e32 v46, v44, v33
	v_fma_f32 v47, -v32, v46, v44
	v_fmac_f32_e32 v46, v47, v33
	v_fma_f32 v32, -v32, v46, v44
	v_div_fmas_f32 v32, v32, v33, v46
	v_div_fixup_f32 v32, v32, v45, 1.0
	v_add_f32_e32 v40, v42, v40
	v_add_f32_e32 v41, v43, v41
	v_min_i32_e32 v42, v83, v117
	v_fma_f32 v33, v32, v41, -v35
	v_fma_f32 v32, v32, v40, -v34
	v_cvt_pk_bf16_f32 v32, v32, v33
	v_max_i32_e32 v33, 2, v87
	v_sub_u32_e32 v33, v42, v33
	v_add_u32_e32 v33, 2, v33
	v_cvt_f32_i32_e32 v33, v33
	global_store_dword v[30:31], v32, off
	v_lshlrev_b32_e32 v30, 16, v91
	v_and_b32_e32 v31, 0xffff0000, v91
	v_div_scale_f32 v42, s[0:1], v33, v33, 1.0
	v_rcp_f32_e32 v43, v42
	v_add_f32_e64 v38, v30, -v38
	v_add_f32_e64 v39, v31, -v39
	v_lshlrev_b64 v[28:29], 11, v[28:29]
	v_add_f32_e32 v38, v40, v38
	v_add_f32_e32 v39, v41, v39
	v_fma_f32 v32, -v42, v43, 1.0
	v_fmac_f32_e32 v43, v32, v43
	v_div_scale_f32 v32, vcc, 1.0, v33, 1.0
	v_mul_f32_e32 v44, v32, v43
	v_fma_f32 v45, -v42, v44, v32
	v_fmac_f32_e32 v44, v45, v43
	v_fma_f32 v32, -v42, v44, v32
	v_div_fmas_f32 v32, v32, v43, v44
	v_div_fixup_f32 v32, v32, v33, 1.0
	v_fma_f32 v33, v32, v39, -v7
	v_fma_f32 v32, v32, v38, -v6
	v_cvt_pk_bf16_f32 v32, v32, v33
	v_max_i32_e32 v33, 2, v85
	v_min_i32_e32 v40, v81, v117
	v_sub_u32_e32 v33, v40, v33
	v_add_u32_e32 v33, 2, v33
	v_cvt_f32_i32_e32 v33, v33
	v_lshl_add_u64 v[28:29], v[4:5], 0, v[28:29]
	global_store_dword v[28:29], v32, off
	v_lshlrev_b32_e32 v28, 16, v84
	v_div_scale_f32 v40, s[0:1], v33, v33, 1.0
	v_rcp_f32_e32 v41, v40
	v_and_b32_e32 v29, 0xffff0000, v84
	v_add_f32_e64 v36, v28, -v36
	v_add_f32_e64 v37, v29, -v37
	v_lshlrev_b64 v[26:27], 11, v[26:27]
	v_fma_f32 v32, -v40, v41, 1.0
	v_fmac_f32_e32 v41, v32, v41
	v_div_scale_f32 v32, vcc, 1.0, v33, 1.0
	v_mul_f32_e32 v42, v32, v41
	v_fma_f32 v43, -v40, v42, v32
	v_fmac_f32_e32 v42, v43, v41
	v_fma_f32 v32, -v40, v42, v32
	v_div_fmas_f32 v32, v32, v41, v42
	v_div_fixup_f32 v32, v32, v33, 1.0
	v_add_f32_e32 v36, v38, v36
	v_add_f32_e32 v37, v39, v37
	v_min_i32_e32 v38, v79, v117
	v_fma_f32 v33, v32, v37, -v31
	v_fma_f32 v32, v32, v36, -v30
	v_cvt_pk_bf16_f32 v32, v32, v33
	v_max_i32_e32 v33, 2, v83
	v_sub_u32_e32 v33, v38, v33
	v_add_u32_e32 v33, 2, v33
	v_cvt_f32_i32_e32 v33, v33
	v_lshl_add_u64 v[26:27], v[4:5], 0, v[26:27]
	global_store_dword v[26:27], v32, off
	v_lshlrev_b32_e32 v26, 16, v86
	v_div_scale_f32 v38, s[0:1], v33, v33, 1.0
	v_rcp_f32_e32 v39, v38
	v_and_b32_e32 v27, 0xffff0000, v86
	v_add_f32_e64 v34, v26, -v34
	v_add_f32_e64 v35, v27, -v35
	v_lshlrev_b64 v[24:25], 11, v[24:25]
	v_fma_f32 v32, -v38, v39, 1.0
	v_fmac_f32_e32 v39, v32, v39
	v_div_scale_f32 v32, vcc, 1.0, v33, 1.0
	v_mul_f32_e32 v40, v32, v39
	v_fma_f32 v41, -v38, v40, v32
	v_fmac_f32_e32 v40, v41, v39
	v_fma_f32 v32, -v38, v40, v32
	v_div_fmas_f32 v32, v32, v39, v40
	v_div_fixup_f32 v32, v32, v33, 1.0
	v_add_f32_e32 v34, v36, v34
	v_add_f32_e32 v35, v37, v35
	v_min_i32_e32 v36, v77, v117
	v_fma_f32 v33, v32, v35, -v29
	v_fma_f32 v32, v32, v34, -v28
	v_cvt_pk_bf16_f32 v32, v32, v33
	v_max_i32_e32 v33, 2, v81
	v_sub_u32_e32 v33, v36, v33
	v_add_u32_e32 v33, 2, v33
	v_cvt_f32_i32_e32 v36, v33
	v_lshl_add_u64 v[24:25], v[4:5], 0, v[24:25]
	global_store_dword v[24:25], v32, off
	v_lshlrev_b32_e32 v24, 16, v80
	v_div_scale_f32 v37, s[0:1], v36, v36, 1.0
	v_rcp_f32_e32 v38, v37
	v_and_b32_e32 v25, 0xffff0000, v80
	v_add_f32_e64 v6, v24, -v6
	v_add_f32_e64 v7, v25, -v7
	v_lshlrev_b64 v[22:23], 11, v[22:23]
	v_fma_f32 v39, -v37, v38, 1.0
	v_fmac_f32_e32 v38, v39, v38
	v_div_scale_f32 v39, vcc, 1.0, v36, 1.0
	v_mul_f32_e32 v40, v39, v38
	v_fma_f32 v41, -v37, v40, v39
	v_fmac_f32_e32 v40, v41, v38
	v_fma_f32 v37, -v37, v40, v39
	v_div_fmas_f32 v37, v37, v38, v40
	v_div_fixup_f32 v36, v37, v36, 1.0
	v_max_i32_e32 v37, 2, v79
	v_min_i32_e32 v38, v75, v117
	v_sub_u32_e32 v37, v38, v37
	v_add_u32_e32 v37, 2, v37
	v_cvt_f32_i32_e32 v37, v37
	v_add_f32_e32 v6, v34, v6
	v_add_f32_e32 v7, v35, v7
	v_lshl_add_u64 v[22:23], v[4:5], 0, v[22:23]
	v_lshlrev_b32_e32 v38, 16, v82
	v_div_scale_f32 v42, s[0:1], v37, v37, 1.0
	v_rcp_f32_e32 v43, v42
	v_and_b32_e32 v39, 0xffff0000, v82
	v_add_f32_e64 v30, v38, -v30
	v_add_f32_e64 v31, v39, -v31
	v_lshlrev_b64 v[20:21], 11, v[20:21]
	v_fma_f32 v44, -v42, v43, 1.0
	v_fmac_f32_e32 v43, v44, v43
	v_div_scale_f32 v44, vcc, 1.0, v37, 1.0
	v_mul_f32_e32 v45, v44, v43
	v_fma_f32 v46, -v42, v45, v44
	v_fmac_f32_e32 v45, v46, v43
	v_fma_f32 v42, -v42, v45, v44
	v_div_fmas_f32 v42, v42, v43, v45
	v_div_fixup_f32 v42, v42, v37, 1.0
	v_max_i32_e32 v37, 2, v77
	v_min_i32_e32 v43, v73, v117
	v_sub_u32_e32 v37, v43, v37
	v_add_u32_e32 v37, 2, v37
	v_cvt_f32_i32_e32 v37, v37
	v_lshl_add_u64 v[20:21], v[4:5], 0, v[20:21]
	v_lshlrev_b32_e32 v44, 16, v76
	v_and_b32_e32 v45, 0xffff0000, v76
	v_div_scale_f32 v43, s[0:1], v37, v37, 1.0
	v_rcp_f32_e32 v48, v43
	v_add_f32_e64 v28, v44, -v28
	v_add_f32_e64 v29, v45, -v29
	v_lshlrev_b64 v[18:19], 11, v[18:19]
	v_lshl_add_u64 v[18:19], v[4:5], 0, v[18:19]
	v_fma_f32 v49, -v43, v48, 1.0
	v_fmac_f32_e32 v48, v49, v48
	v_div_scale_f32 v49, vcc, 1.0, v37, 1.0
	v_mul_f32_e32 v50, v49, v48
	v_fma_f32 v51, -v43, v50, v49
	v_fmac_f32_e32 v50, v51, v48
	v_fma_f32 v43, -v43, v50, v49
	v_div_fmas_f32 v43, v43, v48, v50
	v_div_fixup_f32 v48, v43, v37, 1.0
	v_max_i32_e32 v37, 2, v75
	v_min_i32_e32 v43, v71, v117
	v_sub_u32_e32 v37, v43, v37
	v_add_u32_e32 v37, 2, v37
	v_cvt_f32_i32_e32 v43, v37
	v_and_b32_e32 v37, 0xffff0000, v72
	v_fma_f32 v34, v36, v6, -v26
	v_fma_f32 v35, v36, v7, -v27
	v_cvt_pk_bf16_f32 v34, v34, v35
	v_div_scale_f32 v49, s[0:1], v43, v43, 1.0
	v_rcp_f32_e32 v52, v49
	global_store_dword v[22:23], v34, off
	v_add_f32_e32 v6, v6, v30
	v_add_f32_e32 v7, v7, v31
	v_lshlrev_b32_e32 v50, 16, v78
	v_fma_f32 v53, -v49, v52, 1.0
	v_fmac_f32_e32 v52, v53, v52
	v_div_scale_f32 v53, vcc, 1.0, v43, 1.0
	v_mul_f32_e32 v54, v53, v52
	v_fma_f32 v55, -v49, v54, v53
	v_fmac_f32_e32 v54, v55, v52
	v_fma_f32 v49, -v49, v54, v53
	v_div_fmas_f32 v49, v49, v52, v54
	v_div_fixup_f32 v52, v49, v43, 1.0
	v_max_i32_e32 v43, 2, v73
	v_min_i32_e32 v49, v70, v117
	v_sub_u32_e32 v43, v49, v43
	v_add_u32_e32 v43, 2, v43
	v_cvt_f32_i32_e32 v43, v43
	v_and_b32_e32 v51, 0xffff0000, v78
	v_add_f32_e64 v26, v50, -v26
	v_add_f32_e64 v27, v51, -v27
	v_lshlrev_b64 v[16:17], 11, v[16:17]
	v_div_scale_f32 v49, s[0:1], v43, v43, 1.0
	v_rcp_f32_e32 v53, v49
	v_fma_f32 v30, v42, v6, -v24
	v_fma_f32 v31, v42, v7, -v25
	v_cvt_pk_bf16_f32 v30, v30, v31
	global_store_dword v[20:21], v30, off
	v_fma_f32 v22, -v49, v53, 1.0
	v_fmac_f32_e32 v53, v22, v53
	v_div_scale_f32 v22, vcc, 1.0, v43, 1.0
	v_mul_f32_e32 v23, v22, v53
	v_fma_f32 v34, -v49, v23, v22
	v_fmac_f32_e32 v23, v34, v53
	v_fma_f32 v22, -v49, v23, v22
	v_div_fmas_f32 v22, v22, v53, v23
	v_max_i32_e32 v23, 2, v71
	v_min_i32_e32 v34, v0, v117
	v_sub_u32_e32 v23, v34, v23
	v_add_u32_e32 v23, 2, v23
	v_cvt_f32_i32_e32 v23, v23
	v_add_f32_e32 v6, v6, v28
	v_add_f32_e32 v7, v7, v29
	v_lshlrev_b32_e32 v32, 16, v92
	v_fma_f32 v28, v48, v6, -v38
	v_fma_f32 v29, v48, v7, -v39
	v_div_scale_f32 v34, s[0:1], v23, v23, 1.0
	v_rcp_f32_e32 v35, v34
	v_cvt_pk_bf16_f32 v28, v28, v29
	global_store_dword v[18:19], v28, off
	v_add_f32_e32 v6, v6, v26
	v_add_f32_e32 v7, v7, v27
	v_fma_f32 v20, -v34, v35, 1.0
	v_fmac_f32_e32 v35, v20, v35
	v_div_scale_f32 v20, vcc, 1.0, v23, 1.0
	v_mul_f32_e32 v21, v20, v35
	v_fma_f32 v30, -v34, v21, v20
	v_fmac_f32_e32 v21, v30, v35
	v_fma_f32 v20, -v34, v21, v20
	v_div_fmas_f32 v20, v20, v35, v21
	v_div_fixup_f32 v20, v20, v23, 1.0
	v_max_i32_e32 v21, 2, v70
	v_min_i32_e32 v23, v74, v117
	v_sub_u32_e32 v21, v23, v21
	v_add_u32_e32 v21, 2, v21
	v_cvt_f32_i32_e32 v21, v21
	v_fma_f32 v26, v52, v6, -v44
	v_fma_f32 v27, v52, v7, -v45
	v_and_b32_e32 v33, 0xffff0000, v92
	v_lshl_add_u64 v[16:17], v[4:5], 0, v[16:17]
	v_div_scale_f32 v23, s[0:1], v21, v21, 1.0
	v_rcp_f32_e32 v30, v23
	v_div_fixup_f32 v22, v22, v43, 1.0
	v_lshlrev_b64 v[14:15], 11, v[14:15]
	v_lshlrev_b32_e32 v40, 16, v94
	v_fma_f32 v18, -v23, v30, 1.0
	v_fmac_f32_e32 v30, v18, v30
	v_div_scale_f32 v18, vcc, 1.0, v21, 1.0
	v_mul_f32_e32 v19, v18, v30
	v_fma_f32 v28, -v23, v19, v18
	v_fmac_f32_e32 v19, v28, v30
	v_fma_f32 v18, -v23, v19, v18
	v_div_fmas_f32 v18, v18, v30, v19
	v_cvt_pk_bf16_f32 v19, v26, v27
	global_store_dword v[16:17], v19, off
	v_add_f32_e64 v16, v32, -v24
	v_add_f32_e64 v17, v33, -v25
	v_and_b32_e32 v41, 0xffff0000, v94
	v_add_f32_e32 v6, v6, v16
	v_add_f32_e32 v7, v7, v17
	v_lshl_add_u64 v[14:15], v[4:5], 0, v[14:15]
	v_fma_f32 v16, v22, v6, -v50
	v_fma_f32 v17, v22, v7, -v51
	v_cvt_pk_bf16_f32 v16, v16, v17
	global_store_dword v[14:15], v16, off
	v_add_f32_e64 v14, v40, -v38
	v_add_f32_e64 v15, v41, -v39
	v_lshlrev_b64 v[12:13], 11, v[12:13]
	v_add_f32_e32 v6, v6, v14
	v_add_f32_e32 v7, v7, v15
	v_lshl_add_u64 v[12:13], v[4:5], 0, v[12:13]
	v_fma_f32 v14, v20, v6, -v32
	v_fma_f32 v15, v20, v7, -v33
	v_cvt_pk_bf16_f32 v14, v14, v15
	global_store_dword v[12:13], v14, off
	v_add_u32_e32 v12, 33, v119
	v_max_i32_e32 v0, 2, v0
	v_min_i32_e32 v12, v12, v117
	v_sub_u32_e32 v0, v12, v0
	v_add_u32_e32 v0, 2, v0
	v_cvt_f32_i32_e32 v0, v0
	v_lshlrev_b32_e32 v46, 16, v88
	v_and_b32_e32 v47, 0xffff0000, v88
	v_add_f32_e64 v12, v46, -v44
	v_add_f32_e64 v13, v47, -v45
	v_div_scale_f32 v14, s[0:1], v0, v0, 1.0
	v_rcp_f32_e32 v15, v14
	v_div_fixup_f32 v18, v18, v21, 1.0
	v_add_f32_e32 v6, v6, v12
	v_add_f32_e32 v7, v7, v13
	v_lshlrev_b64 v[10:11], 11, v[10:11]
	v_fma_f32 v12, v18, v6, -v40
	v_fma_f32 v13, v18, v7, -v41
	v_lshl_add_u64 v[10:11], v[4:5], 0, v[10:11]
	v_cvt_pk_bf16_f32 v12, v12, v13
	global_store_dword v[10:11], v12, off
	v_fma_f32 v10, -v14, v15, 1.0
	v_fmac_f32_e32 v15, v10, v15
	v_div_scale_f32 v10, vcc, 1.0, v0, 1.0
	v_mul_f32_e32 v11, v10, v15
	v_fma_f32 v12, -v14, v11, v10
	v_fmac_f32_e32 v11, v12, v15
	v_fma_f32 v10, -v14, v11, v10
	v_lshlrev_b32_e32 v36, 16, v72
	v_div_fmas_f32 v10, v10, v15, v11
	v_div_fixup_f32 v0, v10, v0, 1.0
	v_add_f32_e64 v10, v36, -v50
	v_add_f32_e64 v11, v37, -v51
	s_nop 0
	v_add_f32_e32 v6, v6, v10
	v_add_f32_e32 v7, v7, v11
	s_nop 0
	v_fma_f32 v10, v0, v6, -v46
	v_fma_f32 v11, v0, v7, -v47

.LBB0_1252:
	s_lshl_b32 s50, s42, 7
	s_ashr_i32 s51, s50, 31
	s_andn2_b64 vcc, exec, s[44:45]
	v_lshlrev_b32_e32 v140, 1, v134
	s_cbranch_vccnz .LBB0_1254
	v_readlane_b32 s0, v254, 21
	v_readlane_b32 s1, v254, 22
	v_mov_b32_e32 v141, v1
	v_mul_f32_e32 v120, v120, v128
	v_mul_f32_e32 v121, v121, v129
	v_mov_b64_e32 v[142:143], s[0:1]
	s_movk_i32 s0, 0x600
	v_mad_i64_i32 v[142:143], s[0:1], v150, s0, v[142:143]
	v_lshl_add_u64 v[142:143], s[50:51], 1, v[142:143]
	s_lshl_b32 s0, s75, 1
	s_mov_b32 s1, s87
	v_lshl_add_u64 v[142:143], v[142:143], 0, s[0:1]
	v_mul_f32_e32 v118, v118, v126
	v_mul_f32_e32 v119, v119, v127
	v_mul_f32_e32 v116, v116, v124
	v_mul_f32_e32 v117, v117, v125
	v_mul_f32_e32 v114, v114, v122
	v_mul_f32_e32 v115, v115, v123
	v_lshl_add_u64 v[142:143], v[142:143], 0, v[140:141]
	v_cvt_pk_bf16_f32 v118, v118, v119
	v_cvt_pk_bf16_f32 v119, v120, v121
	v_cvt_pk_bf16_f32 v120, v114, v115
	v_cvt_pk_bf16_f32 v121, v116, v117
	global_store_dwordx4 v[142:143], v[118:121], off

.LBB0_1285:
	v_readlane_b32 s0, v254, 21
	v_readlane_b32 s1, v254, 22
	v_mov_b32_e32 v141, v1
	v_mul_f32_e32 v104, v104, v112
	v_mul_f32_e32 v105, v105, v113
	v_mov_b64_e32 v[114:115], s[0:1]
	s_movk_i32 s0, 0x600
	v_mad_i64_i32 v[114:115], s[0:1], v118, s0, v[114:115]
	v_lshl_add_u64 v[114:115], s[50:51], 1, v[114:115]
	s_lshl_b32 s0, s75, 1
	s_mov_b32 s1, s87
	v_lshl_add_u64 v[114:115], v[114:115], 0, s[0:1]
	v_mul_f32_e32 v102, v102, v110
	v_mul_f32_e32 v103, v103, v111
	v_mul_f32_e32 v100, v100, v108
	v_mul_f32_e32 v101, v101, v109
	v_mul_f32_e32 v98, v98, v106
	v_mul_f32_e32 v99, v99, v107
	v_lshl_add_u64 v[114:115], v[114:115], 0, v[140:141]
	v_cvt_pk_bf16_f32 v102, v102, v103
	v_cvt_pk_bf16_f32 v103, v104, v105
	v_cvt_pk_bf16_f32 v104, v98, v99
	v_cvt_pk_bf16_f32 v105, v100, v101
	global_store_dwordx4 v[114:115], v[102:105], off
	s_nop 1
	v_or_b32_e32 v102, 32, v150
	s_and_b64 vcc, exec, s[44:45]
	s_mov_b64 s[52:53], -1
	s_cbranch_vccz .LBB0_1265

.LBB0_1287:
	v_readlane_b32 s0, v254, 21
	v_readlane_b32 s1, v254, 22
	v_mov_b32_e32 v141, v1
	v_mul_f32_e32 v88, v88, v96
	v_mul_f32_e32 v89, v89, v97
	v_mov_b64_e32 v[98:99], s[0:1]
	s_movk_i32 s0, 0x600
	v_mad_i64_i32 v[98:99], s[0:1], v102, s0, v[98:99]
	v_lshl_add_u64 v[98:99], s[50:51], 1, v[98:99]
	s_lshl_b32 s0, s75, 1
	s_mov_b32 s1, s87
	v_lshl_add_u64 v[98:99], v[98:99], 0, s[0:1]
	v_mul_f32_e32 v86, v86, v94
	v_mul_f32_e32 v87, v87, v95
	v_mul_f32_e32 v84, v84, v92
	v_mul_f32_e32 v85, v85, v93
	v_mul_f32_e32 v82, v82, v90
	v_mul_f32_e32 v83, v83, v91
	v_lshl_add_u64 v[98:99], v[98:99], 0, v[140:141]
	v_cvt_pk_bf16_f32 v86, v86, v87
	v_cvt_pk_bf16_f32 v87, v88, v89
	v_cvt_pk_bf16_f32 v88, v82, v83
	v_cvt_pk_bf16_f32 v89, v84, v85
	global_store_dwordx4 v[98:99], v[86:89], off
	s_nop 1
	v_or_b32_e32 v86, 48, v150
	s_and_b64 vcc, exec, s[44:45]
	s_mov_b64 s[52:53], -1
	s_cbranch_vccz .LBB0_1275

.LBB0_1289:
	v_readlane_b32 s0, v254, 21
	v_readlane_b32 s1, v254, 22
	v_mov_b32_e32 v141, v1
	v_mul_f32_e32 v72, v72, v80
	v_mul_f32_e32 v73, v73, v81
	v_mov_b64_e32 v[82:83], s[0:1]
	s_movk_i32 s0, 0x600
	v_mad_i64_i32 v[82:83], s[0:1], v86, s0, v[82:83]
	v_lshl_add_u64 v[82:83], s[50:51], 1, v[82:83]
	s_lshl_b32 s0, s75, 1
	s_mov_b32 s1, s87
	v_lshl_add_u64 v[82:83], v[82:83], 0, s[0:1]
	v_mul_f32_e32 v70, v70, v78
	v_mul_f32_e32 v71, v71, v79
	v_mul_f32_e32 v68, v68, v76
	v_mul_f32_e32 v69, v69, v77
	v_mul_f32_e32 v66, v66, v74
	v_mul_f32_e32 v67, v67, v75
	v_lshl_add_u64 v[82:83], v[82:83], 0, v[140:141]
	v_cvt_pk_bf16_f32 v70, v70, v71
	v_cvt_pk_bf16_f32 v71, v72, v73
	v_cvt_pk_bf16_f32 v72, v66, v67
	v_cvt_pk_bf16_f32 v73, v68, v69
	global_store_dwordx4 v[82:83], v[70:73], off

.LBB0_1331:
	v_readlane_b32 s0, v254, 21
	v_readlane_b32 s1, v254, 22
	v_mov_b32_e32 v141, v1
	v_mul_f32_e32 v56, v56, v64
	v_mul_f32_e32 v57, v57, v65
	v_mov_b64_e32 v[66:67], s[0:1]
	s_movk_i32 s0, 0x600
	v_mad_i64_i32 v[66:67], s[0:1], v70, s0, v[66:67]
	v_lshl_add_u64 v[66:67], s[50:51], 1, v[66:67]
	s_lshl_b32 s0, s75, 1
	s_mov_b32 s1, s87
	v_lshl_add_u64 v[66:67], v[66:67], 0, s[0:1]
	v_mul_f32_e32 v54, v54, v62
	v_mul_f32_e32 v55, v55, v63
	v_mul_f32_e32 v52, v52, v60
	v_mul_f32_e32 v53, v53, v61
	v_mul_f32_e32 v50, v50, v58
	v_mul_f32_e32 v51, v51, v59
	v_lshl_add_u64 v[66:67], v[66:67], 0, v[140:141]
	v_cvt_pk_bf16_f32 v54, v54, v55
	v_cvt_pk_bf16_f32 v55, v56, v57
	v_cvt_pk_bf16_f32 v56, v50, v51
	v_cvt_pk_bf16_f32 v57, v52, v53
	global_store_dwordx4 v[66:67], v[54:57], off
	s_nop 1
	v_or_b32_e32 v54, 16, v70
	s_and_b64 vcc, exec, s[44:45]
	s_mov_b64 s[52:53], -1
	s_cbranch_vccz .LBB0_1301

.LBB0_1333:
	v_readlane_b32 s0, v254, 21
	v_readlane_b32 s1, v254, 22
	v_mov_b32_e32 v141, v1
	v_mul_f32_e32 v40, v40, v48
	v_mul_f32_e32 v41, v41, v49
	v_mov_b64_e32 v[50:51], s[0:1]
	s_movk_i32 s0, 0x600
	v_mad_i64_i32 v[50:51], s[0:1], v54, s0, v[50:51]
	v_lshl_add_u64 v[50:51], s[50:51], 1, v[50:51]
	s_lshl_b32 s0, s75, 1
	s_mov_b32 s1, s87
	v_lshl_add_u64 v[50:51], v[50:51], 0, s[0:1]
	v_mul_f32_e32 v38, v38, v46
	v_mul_f32_e32 v39, v39, v47
	v_mul_f32_e32 v36, v36, v44
	v_mul_f32_e32 v37, v37, v45
	v_mul_f32_e32 v34, v34, v42
	v_mul_f32_e32 v35, v35, v43
	v_lshl_add_u64 v[50:51], v[50:51], 0, v[140:141]
	v_cvt_pk_bf16_f32 v38, v38, v39
	v_cvt_pk_bf16_f32 v39, v40, v41
	v_cvt_pk_bf16_f32 v40, v34, v35
	v_cvt_pk_bf16_f32 v41, v36, v37
	global_store_dwordx4 v[50:51], v[38:41], off
	s_nop 1
	v_or_b32_e32 v38, 32, v70
	s_and_b64 vcc, exec, s[44:45]
	s_mov_b64 s[52:53], -1
	s_cbranch_vccz .LBB0_1311

.LBB0_1335:
	v_readlane_b32 s0, v254, 21
	v_readlane_b32 s1, v254, 22
	v_mov_b32_e32 v141, v1
	v_mul_f32_e32 v24, v24, v32
	v_mul_f32_e32 v25, v25, v33
	v_mov_b64_e32 v[34:35], s[0:1]
	s_movk_i32 s0, 0x600
	v_mad_i64_i32 v[34:35], s[0:1], v38, s0, v[34:35]
	v_lshl_add_u64 v[34:35], s[50:51], 1, v[34:35]
	s_lshl_b32 s0, s75, 1
	s_mov_b32 s1, s87
	v_lshl_add_u64 v[34:35], v[34:35], 0, s[0:1]
	v_mul_f32_e32 v22, v22, v30
	v_mul_f32_e32 v23, v23, v31
	v_mul_f32_e32 v20, v20, v28
	v_mul_f32_e32 v21, v21, v29
	v_mul_f32_e32 v18, v18, v26
	v_mul_f32_e32 v19, v19, v27
	v_lshl_add_u64 v[34:35], v[34:35], 0, v[140:141]
	v_cvt_pk_bf16_f32 v22, v22, v23
	v_cvt_pk_bf16_f32 v23, v24, v25
	v_cvt_pk_bf16_f32 v24, v18, v19
	v_cvt_pk_bf16_f32 v25, v20, v21
	global_store_dwordx4 v[34:35], v[22:25], off
	s_nop 1
	v_or_b32_e32 v22, 48, v70
	s_and_b64 vcc, exec, s[44:45]
	s_mov_b64 s[44:45], -1
	s_cbranch_vccz .LBB0_1321

.LBB0_1337:
	v_readlane_b32 s0, v254, 21
	v_readlane_b32 s1, v254, 22
	s_lshl_b32 s86, s75, 1
	v_mov_b32_e32 v141, v1
	v_mov_b64_e32 v[18:19], s[0:1]
	s_movk_i32 s0, 0x600
	v_mad_i64_i32 v[18:19], s[0:1], v22, s0, v[18:19]
	v_lshl_add_u64 v[18:19], s[50:51], 1, v[18:19]
	v_lshl_add_u64 v[18:19], v[18:19], 0, s[86:87]
	v_mul_f32_e32 v8, v8, v16
	v_mul_f32_e32 v9, v9, v17
	v_mul_f32_e32 v6, v6, v14
	v_mul_f32_e32 v7, v7, v15
	v_mul_f32_e32 v4, v4, v12
	v_mul_f32_e32 v5, v5, v13
	v_mul_f32_e32 v2, v2, v10
	v_mul_f32_e32 v3, v3, v11
	v_lshl_add_u64 v[18:19], v[18:19], 0, v[140:141]
	v_cvt_pk_bf16_f32 v6, v6, v7
	v_cvt_pk_bf16_f32 v7, v8, v9
	v_cvt_pk_bf16_f32 v8, v2, v3
	v_cvt_pk_bf16_f32 v9, v4, v5
	global_store_dwordx4 v[18:19], v[6:9], off
	s_branch .LBB0_1237

.Lrope_skip_0:
	s_or_b64 exec, exec, vcc
	v_mul_f32_e32 v0, v127, v127
	v_fmac_f32_e32 v0, v126, v126
	v_fmac_f32_e32 v0, v128, v128
	v_fmac_f32_e32 v0, v129, v129
	v_fmac_f32_e32 v0, v122, v122
	v_fmac_f32_e32 v0, v123, v123
	v_fmac_f32_e32 v0, v124, v124
	v_fmac_f32_e32 v0, v125, v125
	v_mul_f32_e32 v148, v110, v110
	v_mul_f32_e32 v149, v111, v111
	v_mul_f32_e32 v146, v112, v112
	v_mul_f32_e32 v147, v113, v113
	v_add_f32_e32 v0, v148, v0
	v_add_f32_e32 v0, v149, v0
	v_add_f32_e32 v0, v146, v0
	v_add_f32_e32 v0, v147, v0
	v_mul_f32_e32 v148, v106, v106
	v_mul_f32_e32 v149, v107, v107
	v_mul_f32_e32 v146, v108, v108
	v_mul_f32_e32 v147, v109, v109
	v_add_f32_e32 v0, v148, v0
	v_add_f32_e32 v0, v149, v0
	v_cmp_lt_i32_e32 vcc, v205, v203
	v_add_f32_e32 v0, v146, v0
	v_add_f32_e32 v0, v147, v0
	v_cndmask_b32_e32 v146, v224, v205, vcc
	v_lshlrev_b32_e32 v146, 2, v146
	ds_bpermute_b32 v146, v146, v0
	v_cmp_lt_i32_e32 vcc, v204, v203
	s_waitcnt lgkmcnt(0)
	v_add_f32_e32 v0, v0, v146
	v_cndmask_b32_e32 v146, v224, v204, vcc
	v_lshlrev_b32_e32 v146, 2, v146
	ds_bpermute_b32 v146, v146, v0
	s_waitcnt lgkmcnt(0)
	v_add_f32_e32 v0, v0, v146
	v_fmamk_f32 v0, v0, 0x3c800000, v226
	v_mul_f32_e32 v146, 0x4b800000, v0
	v_cmp_gt_f32_e32 vcc, s58, v0
	s_nop 1
	v_cndmask_b32_e32 v0, v0, v146, vcc
	v_rsq_f32_e32 v0, v0
	s_nop 0
	v_mul_f32_e32 v146, 0x45800000, v0
	v_cndmask_b32_e32 v158, v0, v146, vcc
	v_lshl_or_b32 v0, v182, 6, v166
	v_mul_f32_e32 v146, v126, v158
	v_mul_f32_e32 v147, v127, v158
	v_mul_f32_e32 v148, v128, v158
	v_mul_f32_e32 v149, v129, v158
	s_waitcnt vmcnt(0)
	v_mul_f32_e32 v146, v142, v146
	v_mul_f32_e32 v147, v143, v147
	v_mul_f32_e32 v148, v144, v148
	v_mul_f32_e32 v149, v145, v149
	v_lshlrev_b32_e32 v0, 2, v0
	s_and_saveexec_b64 s[44:45], s[42:43]
	s_cbranch_execz .LBB0_1358
	v_mul_f32_e32 v156, v147, v215
	v_mul_f32_e32 v157, v147, v214
	s_nop 0
	v_fma_f32 v154, v146, v214, -v156
	v_fma_f32 v155, v146, v215, -v157
	v_fma_f32 v147, v146, v215, v157
	v_fma_f32 v146, v146, v214, v156
	v_mul_f32_e32 v146, v149, v217
	v_fma_f32 v156, v148, v216, -v146
	v_fma_f32 v157, v149, v217, -v146
	v_mul_f32_e32 v146, v149, v216
	v_fma_f32 v148, v148, v217, v146
	v_fma_f32 v149, v149, v216, v146
	v_mov_b32_e32 v155, v147
	v_mov_b32_e32 v157, v148
	v_mov_b64_e32 v[146:147], v[154:155]
	v_mov_b64_e32 v[148:149], v[156:157]
.LBB0_1358:
	s_or_b64 exec, exec, s[44:45]
	v_mov_b32_e32 v159, v158
	v_mov_b32_e32 v154, v158
	v_mov_b32_e32 v155, v158
	v_mul_f32_e32 v150, v124, v154
	v_mul_f32_e32 v151, v125, v155
	v_mul_f32_e32 v156, v122, v158
	v_mul_f32_e32 v157, v123, v159
	v_mul_f32_e32 v152, v140, v150
	v_mul_f32_e32 v153, v141, v151
	v_mul_f32_e32 v150, v138, v156
	v_mul_f32_e32 v151, v139, v157
	s_and_saveexec_b64 s[44:45], s[42:43]
	s_cbranch_execz .LBB0_1360
	v_mul_f32_e32 v156, v151, v219
	v_mul_f32_e32 v157, v151, v218
	s_nop 0
	v_fma_f32 v210, v150, v218, -v156
	v_fma_f32 v211, v150, v219, -v157
	v_fma_f32 v151, v150, v219, v157
	v_fma_f32 v150, v150, v218, v156
	v_mul_f32_e32 v150, v153, v221
	v_fma_f32 v212, v152, v220, -v150
	v_fma_f32 v213, v153, v221, -v150
	v_mul_f32_e32 v150, v153, v220
	v_fma_f32 v152, v152, v221, v150
	v_fma_f32 v153, v153, v220, v150
	v_mov_b32_e32 v211, v151
	v_mov_b32_e32 v213, v152
	v_mov_b64_e32 v[150:151], v[210:211]
	v_mov_b64_e32 v[152:153], v[212:213]
.LBB0_1360:
	s_or_b64 exec, exec, s[44:45]
	v_mul_f32_e32 v154, v112, v154
	v_mul_f32_e32 v155, v113, v155
	v_mul_f32_e32 v160, v110, v158
	v_mul_f32_e32 v161, v111, v159
	v_mul_f32_e32 v156, v136, v154
	v_mul_f32_e32 v157, v137, v155
	v_mul_f32_e32 v154, v134, v160
	v_mul_f32_e32 v155, v135, v161
	s_and_saveexec_b64 s[44:45], s[42:43]
	s_cbranch_execz .LBB0_1362
	v_mul_f32_e32 v160, v155, v243
	v_mul_f32_e32 v161, v155, v242
	s_nop 0
	v_fma_f32 v210, v154, v242, -v160
	v_fma_f32 v211, v154, v243, -v161
	v_fma_f32 v155, v154, v243, v161
	v_fma_f32 v154, v154, v242, v160
	v_mul_f32_e32 v154, v157, v245
	v_fma_f32 v212, v156, v244, -v154
	v_fma_f32 v213, v157, v245, -v154
	v_mul_f32_e32 v154, v157, v244
	v_fma_f32 v156, v156, v245, v154
	v_fma_f32 v157, v157, v244, v154
	v_mov_b32_e32 v211, v155
	v_mov_b32_e32 v213, v156
	v_mov_b64_e32 v[154:155], v[210:211]
	v_mov_b64_e32 v[156:157], v[212:213]
.LBB0_1362:
	s_or_b64 exec, exec, s[44:45]
	v_mov_b32_e32 v160, v158
	v_mov_b32_e32 v161, v158
	v_mul_f32_e32 v160, v108, v160
	v_mul_f32_e32 v161, v109, v161
	v_mul_f32_e32 v158, v106, v158
	v_mul_f32_e32 v159, v107, v159
	v_mul_f32_e32 v160, v132, v160
	v_mul_f32_e32 v161, v133, v161
	v_mul_f32_e32 v158, v130, v158
	v_mul_f32_e32 v159, v131, v159
	s_and_saveexec_b64 s[44:45], s[42:43]
	s_cbranch_execz .LBB0_1364
	v_mul_f32_e32 v0, v161, v249
	v_mul_f32_e32 v194, v159, v247
	v_mul_f32_e32 v195, v159, v246
	v_fma_f32 v196, v160, v248, -v0
	v_fma_f32 v197, v161, v249, -v0
	v_mul_f32_e32 v0, v161, v248
	v_mul_f32_e32 v184, v158, v246
	v_mul_f32_e32 v185, v159, v247
	v_fma_f32 v159, v158, v247, v195
	v_fma_f32 v158, v158, v246, v194
	v_fma_f32 v160, v160, v249, v0
	v_fma_f32 v161, v161, v248, v0
	v_sub_f32_e32 v158, v184, v194
	v_mov_b32_e32 v161, v160
	v_mov_b32_e32 v160, v196

.LBB0_1365:
	s_lshl_b32 s0, s66, 8
	s_or_b32 s54, s0, s71
	v_cndmask_b32_e64 v0, 0, 1, s[34:35]
	s_xor_b64 s[20:21], s[20:21], -1
	s_ashr_i32 s55, s54, 31
	v_cmp_ne_u32_e64 s[42:43], 1, v0
	s_andn2_b64 vcc, exec, s[34:35]
	s_mov_b64 s[34:35], -1
	s_cbranch_vccnz .LBB0_1367
	v_ashrrev_i32_e32 v181, 31, v180
	v_readlane_b32 s0, v254, 21
	v_lshlrev_b64 v[184:185], 10, v[180:181]
	v_readlane_b32 s1, v254, 22
	v_lshlrev_b32_e32 v0, 1, v166
	s_mov_b64 s[34:35], 0
	v_lshl_add_u64 v[184:185], s[0:1], 0, v[184:185]
	s_mov_b32 s0, 0x3e38aa3b
	v_mul_f32_e32 v194, s0, v148
	v_mul_f32_e32 v195, s0, v149
	v_mul_f32_e32 v196, s0, v146
	v_mul_f32_e32 v197, s0, v147
	v_lshl_add_u64 v[184:185], s[54:55], 1, v[184:185]
	v_cvt_pk_bf16_f32 v206, v196, v197
	v_cvt_pk_bf16_f32 v207, v194, v195
	v_mul_f32_e32 v194, s0, v152
	v_mul_f32_e32 v195, s0, v153
	v_mul_f32_e32 v196, s0, v150
	v_mul_f32_e32 v197, s0, v151
	v_lshl_add_u64 v[184:185], v[184:185], 0, v[0:1]
	v_cvt_pk_bf16_f32 v208, v196, v197
	v_cvt_pk_bf16_f32 v209, v194, v195
	v_mul_f32_e32 v194, s0, v156
	v_mul_f32_e32 v195, s0, v157
	v_mul_f32_e32 v196, s0, v154
	v_mul_f32_e32 v197, s0, v155
	global_store_dwordx4 v[184:185], v[206:209], off
	s_nop 1
	v_cvt_pk_bf16_f32 v206, v196, v197
	v_cvt_pk_bf16_f32 v207, v194, v195
	v_mul_f32_e32 v194, s0, v160
	v_mul_f32_e32 v195, s0, v161
	v_mul_f32_e32 v196, s0, v158
	v_mul_f32_e32 v197, s0, v159
	v_cvt_pk_bf16_f32 v209, v194, v195
	v_cvt_pk_bf16_f32 v208, v196, v197
	global_store_dwordx4 v[184:185], v[206:209], off offset:64

.Lrope_skip_1:
	s_or_b64 exec, exec, vcc
	v_mul_f32_e32 v0, v119, v119
	v_fmac_f32_e32 v0, v118, v118
	v_fmac_f32_e32 v0, v120, v120
	v_fmac_f32_e32 v0, v121, v121
	v_fmac_f32_e32 v0, v114, v114
	v_fmac_f32_e32 v0, v115, v115
	v_fmac_f32_e32 v0, v116, v116
	v_fmac_f32_e32 v0, v117, v117
	v_mul_f32_e32 v148, v94, v94
	v_mul_f32_e32 v149, v95, v95
	v_mul_f32_e32 v146, v96, v96
	v_mul_f32_e32 v147, v97, v97
	v_add_f32_e32 v0, v148, v0
	v_add_f32_e32 v0, v149, v0
	v_add_f32_e32 v0, v146, v0
	v_add_f32_e32 v0, v147, v0
	v_mul_f32_e32 v148, v90, v90
	v_mul_f32_e32 v149, v91, v91
	v_mul_f32_e32 v146, v92, v92
	v_mul_f32_e32 v147, v93, v93
	v_add_f32_e32 v0, v148, v0
	v_add_f32_e32 v0, v149, v0
	v_cmp_lt_i32_e32 vcc, v205, v203
	v_add_f32_e32 v0, v146, v0
	v_add_f32_e32 v0, v147, v0
	v_cndmask_b32_e32 v146, v224, v205, vcc
	v_lshlrev_b32_e32 v146, 2, v146
	ds_bpermute_b32 v146, v146, v0
	v_cmp_lt_i32_e32 vcc, v204, v203
	s_waitcnt lgkmcnt(0)
	v_add_f32_e32 v0, v0, v146
	v_cndmask_b32_e32 v146, v224, v204, vcc
	v_lshlrev_b32_e32 v146, 2, v146
	ds_bpermute_b32 v146, v146, v0
	s_waitcnt lgkmcnt(0)
	v_add_f32_e32 v0, v0, v146
	v_fmamk_f32 v0, v0, 0x3c800000, v226
	v_mul_f32_e32 v146, 0x4b800000, v0
	v_cmp_gt_f32_e32 vcc, s58, v0
	s_nop 1
	v_cndmask_b32_e32 v0, v0, v146, vcc
	v_rsq_f32_e32 v0, v0
	s_nop 0
	v_mul_f32_e32 v146, 0x45800000, v0
	v_cndmask_b32_e32 v158, v0, v146, vcc
	v_lshl_or_b32 v0, v182, 6, v166
	v_mul_f32_e32 v146, v118, v158
	v_mul_f32_e32 v147, v119, v158
	v_mul_f32_e32 v148, v120, v158
	v_mul_f32_e32 v149, v121, v158
	s_waitcnt vmcnt(0)
	v_mul_f32_e32 v146, v142, v146
	v_mul_f32_e32 v147, v143, v147
	v_mul_f32_e32 v148, v144, v148
	v_mul_f32_e32 v149, v145, v149
	v_lshlrev_b32_e32 v0, 2, v0
	s_and_saveexec_b64 s[20:21], s[50:51]
	s_cbranch_execz .LBB0_1383
	v_mul_f32_e32 v156, v147, v215
	v_mul_f32_e32 v157, v147, v214
	s_nop 0
	v_fma_f32 v154, v146, v214, -v156
	v_fma_f32 v155, v146, v215, -v157
	v_fma_f32 v147, v146, v215, v157
	v_fma_f32 v146, v146, v214, v156
	v_mul_f32_e32 v146, v149, v217
	v_fma_f32 v156, v148, v216, -v146
	v_fma_f32 v157, v149, v217, -v146
	v_mul_f32_e32 v146, v149, v216
	v_fma_f32 v148, v148, v217, v146
	v_fma_f32 v149, v149, v216, v146
	v_mov_b32_e32 v155, v147
	v_mov_b32_e32 v157, v148
	v_mov_b64_e32 v[146:147], v[154:155]
	v_mov_b64_e32 v[148:149], v[156:157]
.LBB0_1383:
	s_or_b64 exec, exec, s[20:21]
	v_mov_b32_e32 v159, v158
	v_mov_b32_e32 v154, v158
	v_mov_b32_e32 v155, v158
	v_mul_f32_e32 v150, v116, v154
	v_mul_f32_e32 v151, v117, v155
	v_mul_f32_e32 v156, v114, v158
	v_mul_f32_e32 v157, v115, v159
	v_mul_f32_e32 v152, v140, v150
	v_mul_f32_e32 v153, v141, v151
	v_mul_f32_e32 v150, v138, v156
	v_mul_f32_e32 v151, v139, v157
	s_and_saveexec_b64 s[20:21], s[50:51]
	s_cbranch_execz .LBB0_1385
	v_mul_f32_e32 v156, v151, v219
	v_mul_f32_e32 v157, v151, v218
	s_nop 0
	v_fma_f32 v210, v150, v218, -v156
	v_fma_f32 v211, v150, v219, -v157
	v_fma_f32 v151, v150, v219, v157
	v_fma_f32 v150, v150, v218, v156
	v_mul_f32_e32 v150, v153, v221
	v_fma_f32 v212, v152, v220, -v150
	v_fma_f32 v213, v153, v221, -v150
	v_mul_f32_e32 v150, v153, v220
	v_fma_f32 v152, v152, v221, v150
	v_fma_f32 v153, v153, v220, v150
	v_mov_b32_e32 v211, v151
	v_mov_b32_e32 v213, v152
	v_mov_b64_e32 v[150:151], v[210:211]
	v_mov_b64_e32 v[152:153], v[212:213]
.LBB0_1385:
	s_or_b64 exec, exec, s[20:21]
	v_mul_f32_e32 v154, v96, v154
	v_mul_f32_e32 v155, v97, v155
	v_mul_f32_e32 v160, v94, v158
	v_mul_f32_e32 v161, v95, v159
	v_mul_f32_e32 v156, v136, v154
	v_mul_f32_e32 v157, v137, v155
	v_mul_f32_e32 v154, v134, v160
	v_mul_f32_e32 v155, v135, v161
	s_and_saveexec_b64 s[20:21], s[50:51]
	s_cbranch_execz .LBB0_1387
	v_mul_f32_e32 v160, v155, v243
	v_mul_f32_e32 v161, v155, v242
	s_nop 0
	v_fma_f32 v210, v154, v242, -v160
	v_fma_f32 v211, v154, v243, -v161
	v_fma_f32 v155, v154, v243, v161
	v_fma_f32 v154, v154, v242, v160
	v_mul_f32_e32 v154, v157, v245
	v_fma_f32 v212, v156, v244, -v154
	v_fma_f32 v213, v157, v245, -v154
	v_mul_f32_e32 v154, v157, v244
	v_fma_f32 v156, v156, v245, v154
	v_fma_f32 v157, v157, v244, v154
	v_mov_b32_e32 v211, v155
	v_mov_b32_e32 v213, v156
	v_mov_b64_e32 v[154:155], v[210:211]
	v_mov_b64_e32 v[156:157], v[212:213]
.LBB0_1387:
	s_or_b64 exec, exec, s[20:21]
	v_mov_b32_e32 v160, v158
	v_mov_b32_e32 v161, v158
	v_mul_f32_e32 v160, v92, v160
	v_mul_f32_e32 v161, v93, v161
	v_mul_f32_e32 v158, v90, v158
	v_mul_f32_e32 v159, v91, v159
	v_mul_f32_e32 v160, v132, v160
	v_mul_f32_e32 v161, v133, v161
	v_mul_f32_e32 v158, v130, v158
	v_mul_f32_e32 v159, v131, v159
	s_and_saveexec_b64 s[20:21], s[50:51]
	s_cbranch_execz .LBB0_1389
	v_mul_f32_e32 v196, v159, v247
	v_mul_f32_e32 v197, v159, v246
	v_mul_f32_e32 v0, v161, v249
	v_mul_f32_e32 v194, v158, v246
	v_mul_f32_e32 v195, v159, v247
	v_fma_f32 v159, v158, v247, v197
	v_fma_f32 v158, v158, v246, v196
	v_fma_f32 v206, v160, v248, -v0
	v_fma_f32 v207, v161, v249, -v0
	v_mul_f32_e32 v0, v161, v248
	v_fma_f32 v160, v160, v249, v0
	v_fma_f32 v161, v161, v248, v0
	v_sub_f32_e32 v158, v194, v196
	v_mov_b32_e32 v161, v160
	v_mov_b32_e32 v160, v206

.LBB0_1392:
	v_ashrrev_i32_e32 v185, 31, v184
	v_readlane_b32 s0, v254, 21
	v_lshlrev_b64 v[194:195], 10, v[184:185]
	v_readlane_b32 s1, v254, 22
	v_lshlrev_b32_e32 v0, 1, v166
	s_nop 0
	v_lshl_add_u64 v[194:195], s[0:1], 0, v[194:195]
	s_mov_b32 s0, 0x3e38aa3b
	v_mul_f32_e32 v196, s0, v148
	v_mul_f32_e32 v197, s0, v149
	v_mul_f32_e32 v206, s0, v146
	v_mul_f32_e32 v207, s0, v147
	v_lshl_add_u64 v[194:195], s[54:55], 1, v[194:195]
	v_cvt_pk_bf16_f32 v206, v206, v207
	v_cvt_pk_bf16_f32 v207, v196, v197
	v_mul_f32_e32 v196, s0, v152
	v_mul_f32_e32 v197, s0, v153
	v_mul_f32_e32 v208, s0, v150
	v_mul_f32_e32 v209, s0, v151
	v_lshl_add_u64 v[194:195], v[194:195], 0, v[0:1]
	v_cvt_pk_bf16_f32 v208, v208, v209
	v_cvt_pk_bf16_f32 v209, v196, v197
	global_store_dwordx4 v[194:195], v[206:209], off
	v_mul_f32_e32 v196, s0, v156
	v_mul_f32_e32 v197, s0, v157
	s_nop 0
	v_mul_f32_e32 v206, s0, v154
	v_mul_f32_e32 v207, s0, v155
	v_mul_f32_e32 v208, s0, v158
	v_mul_f32_e32 v209, s0, v159
	v_cvt_pk_bf16_f32 v206, v206, v207
	v_cvt_pk_bf16_f32 v207, v196, v197
	v_mul_f32_e32 v196, s0, v160
	v_mul_f32_e32 v197, s0, v161
	v_cvt_pk_bf16_f32 v208, v208, v209
	v_cvt_pk_bf16_f32 v209, v196, v197
	global_store_dwordx4 v[194:195], v[206:209], off offset:64
	s_cbranch_execnz .LBB0_1405

.Lrope_skip_2:
	s_or_b64 exec, exec, vcc
	v_mul_f32_e32 v0, v103, v103
	v_fmac_f32_e32 v0, v102, v102
	v_fmac_f32_e32 v0, v104, v104
	v_fmac_f32_e32 v0, v105, v105
	v_fmac_f32_e32 v0, v98, v98
	v_fmac_f32_e32 v0, v99, v99
	v_fmac_f32_e32 v0, v100, v100
	v_fmac_f32_e32 v0, v101, v101
	v_mul_f32_e32 v148, v78, v78
	v_mul_f32_e32 v149, v79, v79
	v_mul_f32_e32 v146, v80, v80
	v_mul_f32_e32 v147, v81, v81
	v_add_f32_e32 v0, v148, v0
	v_add_f32_e32 v0, v149, v0
	v_add_f32_e32 v0, v146, v0
	v_add_f32_e32 v0, v147, v0
	v_mul_f32_e32 v148, v74, v74
	v_mul_f32_e32 v149, v75, v75
	v_mul_f32_e32 v146, v76, v76
	v_mul_f32_e32 v147, v77, v77
	v_add_f32_e32 v0, v148, v0
	v_add_f32_e32 v0, v149, v0
	v_cmp_lt_i32_e32 vcc, v205, v203
	v_add_f32_e32 v0, v146, v0
	v_add_f32_e32 v0, v147, v0
	v_cndmask_b32_e32 v146, v224, v205, vcc
	v_lshlrev_b32_e32 v146, 2, v146
	ds_bpermute_b32 v146, v146, v0
	v_cmp_lt_i32_e32 vcc, v204, v203
	s_waitcnt lgkmcnt(0)
	v_add_f32_e32 v0, v0, v146
	v_cndmask_b32_e32 v146, v224, v204, vcc
	v_lshlrev_b32_e32 v146, 2, v146
	ds_bpermute_b32 v146, v146, v0
	s_waitcnt lgkmcnt(0)
	v_add_f32_e32 v0, v0, v146
	v_fmamk_f32 v0, v0, 0x3c800000, v226
	v_mul_f32_e32 v146, 0x4b800000, v0
	v_cmp_gt_f32_e32 vcc, s58, v0
	s_nop 1
	v_cndmask_b32_e32 v0, v0, v146, vcc
	v_rsq_f32_e32 v0, v0
	s_nop 0
	v_mul_f32_e32 v146, 0x45800000, v0
	v_cndmask_b32_e32 v158, v0, v146, vcc
	v_lshl_or_b32 v0, v182, 6, v166
	v_mul_f32_e32 v146, v102, v158
	v_mul_f32_e32 v147, v103, v158
	v_mul_f32_e32 v148, v104, v158
	v_mul_f32_e32 v149, v105, v158
	s_waitcnt vmcnt(0)
	v_mul_f32_e32 v146, v142, v146
	v_mul_f32_e32 v147, v143, v147
	v_mul_f32_e32 v148, v144, v148
	v_mul_f32_e32 v149, v145, v149
	v_lshlrev_b32_e32 v0, 2, v0
	s_and_saveexec_b64 s[20:21], s[50:51]
	s_cbranch_execz .LBB0_1408
	v_mul_f32_e32 v156, v147, v215
	v_mul_f32_e32 v157, v147, v214
	s_nop 0
	v_fma_f32 v154, v146, v214, -v156
	v_fma_f32 v155, v146, v215, -v157
	v_fma_f32 v147, v146, v215, v157
	v_fma_f32 v146, v146, v214, v156
	v_mul_f32_e32 v146, v149, v217
	v_fma_f32 v156, v148, v216, -v146
	v_fma_f32 v157, v149, v217, -v146
	v_mul_f32_e32 v146, v149, v216
	v_fma_f32 v148, v148, v217, v146
	v_fma_f32 v149, v149, v216, v146
	v_mov_b32_e32 v155, v147
	v_mov_b32_e32 v157, v148
	v_mov_b64_e32 v[146:147], v[154:155]
	v_mov_b64_e32 v[148:149], v[156:157]
.LBB0_1408:
	s_or_b64 exec, exec, s[20:21]
	v_mov_b32_e32 v159, v158
	v_mov_b32_e32 v154, v158
	v_mov_b32_e32 v155, v158
	v_mul_f32_e32 v150, v100, v154
	v_mul_f32_e32 v151, v101, v155
	v_mul_f32_e32 v156, v98, v158
	v_mul_f32_e32 v157, v99, v159
	v_mul_f32_e32 v152, v140, v150
	v_mul_f32_e32 v153, v141, v151
	v_mul_f32_e32 v150, v138, v156
	v_mul_f32_e32 v151, v139, v157
	s_and_saveexec_b64 s[20:21], s[50:51]
	s_cbranch_execz .LBB0_1410
	v_mul_f32_e32 v156, v151, v219
	v_mul_f32_e32 v157, v151, v218
	s_nop 0
	v_fma_f32 v210, v150, v218, -v156
	v_fma_f32 v211, v150, v219, -v157
	v_fma_f32 v151, v150, v219, v157
	v_fma_f32 v150, v150, v218, v156
	v_mul_f32_e32 v150, v153, v221
	v_fma_f32 v212, v152, v220, -v150
	v_fma_f32 v213, v153, v221, -v150
	v_mul_f32_e32 v150, v153, v220
	v_fma_f32 v152, v152, v221, v150
	v_fma_f32 v153, v153, v220, v150
	v_mov_b32_e32 v211, v151
	v_mov_b32_e32 v213, v152
	v_mov_b64_e32 v[150:151], v[210:211]
	v_mov_b64_e32 v[152:153], v[212:213]
.LBB0_1410:
	s_or_b64 exec, exec, s[20:21]
	v_mul_f32_e32 v154, v80, v154
	v_mul_f32_e32 v155, v81, v155
	v_mul_f32_e32 v160, v78, v158
	v_mul_f32_e32 v161, v79, v159
	v_mul_f32_e32 v156, v136, v154
	v_mul_f32_e32 v157, v137, v155
	v_mul_f32_e32 v154, v134, v160
	v_mul_f32_e32 v155, v135, v161
	s_and_saveexec_b64 s[20:21], s[50:51]
	s_cbranch_execz .LBB0_1412
	v_mul_f32_e32 v160, v155, v243
	v_mul_f32_e32 v161, v155, v242
	s_nop 0
	v_fma_f32 v210, v154, v242, -v160
	v_fma_f32 v211, v154, v243, -v161
	v_fma_f32 v155, v154, v243, v161
	v_fma_f32 v154, v154, v242, v160
	v_mul_f32_e32 v154, v157, v245
	v_fma_f32 v212, v156, v244, -v154
	v_fma_f32 v213, v157, v245, -v154
	v_mul_f32_e32 v154, v157, v244
	v_fma_f32 v156, v156, v245, v154
	v_fma_f32 v157, v157, v244, v154
	v_mov_b32_e32 v211, v155
	v_mov_b32_e32 v213, v156
	v_mov_b64_e32 v[154:155], v[210:211]
	v_mov_b64_e32 v[156:157], v[212:213]
.LBB0_1412:
	s_or_b64 exec, exec, s[20:21]
	v_mov_b32_e32 v160, v158
	v_mov_b32_e32 v161, v158
	v_mul_f32_e32 v160, v76, v160
	v_mul_f32_e32 v161, v77, v161
	v_mul_f32_e32 v158, v74, v158
	v_mul_f32_e32 v159, v75, v159
	v_mul_f32_e32 v160, v132, v160
	v_mul_f32_e32 v161, v133, v161
	v_mul_f32_e32 v158, v130, v158
	v_mul_f32_e32 v159, v131, v159
	s_and_saveexec_b64 s[20:21], s[50:51]
	s_cbranch_execz .LBB0_1414
	v_mul_f32_e32 v196, v159, v247
	v_mul_f32_e32 v197, v159, v246
	v_mul_f32_e32 v0, v161, v249
	v_mul_f32_e32 v194, v158, v246
	v_mul_f32_e32 v195, v159, v247
	v_fma_f32 v159, v158, v247, v197
	v_fma_f32 v158, v158, v246, v196
	v_fma_f32 v206, v160, v248, -v0
	v_fma_f32 v207, v161, v249, -v0
	v_mul_f32_e32 v0, v161, v248
	v_fma_f32 v160, v160, v249, v0
	v_fma_f32 v161, v161, v248, v0
	v_sub_f32_e32 v158, v194, v196
	v_mov_b32_e32 v161, v160
	v_mov_b32_e32 v160, v206

.Lrope_skip_3:
	s_or_b64 exec, exec, vcc
	v_mul_f32_e32 v0, v87, v87
	v_fmac_f32_e32 v0, v86, v86
	v_fmac_f32_e32 v0, v88, v88
	v_fmac_f32_e32 v0, v89, v89
	v_fmac_f32_e32 v0, v82, v82
	v_fmac_f32_e32 v0, v83, v83
	v_fmac_f32_e32 v0, v84, v84
	v_fmac_f32_e32 v0, v85, v85
	v_mul_f32_e32 v148, v70, v70
	v_mul_f32_e32 v149, v71, v71
	v_mul_f32_e32 v146, v72, v72
	v_mul_f32_e32 v147, v73, v73
	v_add_f32_e32 v0, v148, v0
	v_add_f32_e32 v0, v149, v0
	v_add_f32_e32 v0, v146, v0
	v_add_f32_e32 v0, v147, v0
	v_mul_f32_e32 v148, v66, v66
	v_mul_f32_e32 v149, v67, v67
	v_mul_f32_e32 v146, v68, v68
	v_mul_f32_e32 v147, v69, v69
	v_add_f32_e32 v0, v148, v0
	v_add_f32_e32 v0, v149, v0
	v_cmp_lt_i32_e32 vcc, v205, v203
	v_add_f32_e32 v0, v146, v0
	v_add_f32_e32 v0, v147, v0
	v_cndmask_b32_e32 v146, v224, v205, vcc
	v_lshlrev_b32_e32 v146, 2, v146
	ds_bpermute_b32 v146, v146, v0
	v_cmp_lt_i32_e32 vcc, v204, v203
	s_waitcnt lgkmcnt(0)
	v_add_f32_e32 v0, v0, v146
	v_cndmask_b32_e32 v146, v224, v204, vcc
	v_lshlrev_b32_e32 v146, 2, v146
	ds_bpermute_b32 v146, v146, v0
	s_waitcnt lgkmcnt(0)
	v_add_f32_e32 v0, v0, v146
	v_fmamk_f32 v0, v0, 0x3c800000, v226
	v_mul_f32_e32 v146, 0x4b800000, v0
	v_cmp_gt_f32_e32 vcc, s58, v0
	s_nop 1
	v_cndmask_b32_e32 v0, v0, v146, vcc
	v_rsq_f32_e32 v0, v0
	s_nop 0
	v_mul_f32_e32 v146, 0x45800000, v0
	v_cndmask_b32_e32 v158, v0, v146, vcc
	v_lshl_or_b32 v0, v180, 6, v166
	v_mul_f32_e32 v146, v86, v158
	v_mul_f32_e32 v147, v87, v158
	v_mul_f32_e32 v148, v88, v158
	v_mul_f32_e32 v149, v89, v158
	s_waitcnt vmcnt(0)
	v_mul_f32_e32 v146, v142, v146
	v_mul_f32_e32 v147, v143, v147
	v_mul_f32_e32 v148, v144, v148
	v_mul_f32_e32 v149, v145, v149
	v_lshlrev_b32_e32 v0, 2, v0
	s_and_saveexec_b64 s[20:21], s[50:51]
	s_cbranch_execz .LBB0_1433
	v_mul_f32_e32 v156, v147, v215
	v_mul_f32_e32 v157, v147, v214
	s_nop 0
	v_fma_f32 v154, v146, v214, -v156
	v_fma_f32 v155, v146, v215, -v157
	v_fma_f32 v147, v146, v215, v157
	v_fma_f32 v146, v146, v214, v156
	v_mul_f32_e32 v146, v149, v217
	v_fma_f32 v156, v148, v216, -v146
	v_fma_f32 v157, v149, v217, -v146
	v_mul_f32_e32 v146, v149, v216
	v_fma_f32 v148, v148, v217, v146
	v_fma_f32 v149, v149, v216, v146
	v_mov_b32_e32 v155, v147
	v_mov_b32_e32 v157, v148
	v_mov_b64_e32 v[146:147], v[154:155]
	v_mov_b64_e32 v[148:149], v[156:157]
.LBB0_1433:
	s_or_b64 exec, exec, s[20:21]
	v_mov_b32_e32 v159, v158
	v_mov_b32_e32 v154, v158
	v_mov_b32_e32 v155, v158
	v_mul_f32_e32 v150, v84, v154
	v_mul_f32_e32 v151, v85, v155
	v_mul_f32_e32 v156, v82, v158
	v_mul_f32_e32 v157, v83, v159
	v_mul_f32_e32 v152, v140, v150
	v_mul_f32_e32 v153, v141, v151
	v_mul_f32_e32 v150, v138, v156
	v_mul_f32_e32 v151, v139, v157
	s_and_saveexec_b64 s[20:21], s[50:51]
	s_cbranch_execz .LBB0_1435
	v_mul_f32_e32 v156, v151, v219
	v_mul_f32_e32 v157, v151, v218
	s_nop 0
	v_fma_f32 v210, v150, v218, -v156
	v_fma_f32 v211, v150, v219, -v157
	v_fma_f32 v151, v150, v219, v157
	v_fma_f32 v150, v150, v218, v156
	v_mul_f32_e32 v150, v153, v221
	v_fma_f32 v212, v152, v220, -v150
	v_fma_f32 v213, v153, v221, -v150
	v_mul_f32_e32 v150, v153, v220
	v_fma_f32 v152, v152, v221, v150
	v_fma_f32 v153, v153, v220, v150
	v_mov_b32_e32 v211, v151
	v_mov_b32_e32 v213, v152
	v_mov_b64_e32 v[150:151], v[210:211]
	v_mov_b64_e32 v[152:153], v[212:213]
.LBB0_1435:
	s_or_b64 exec, exec, s[20:21]
	v_mul_f32_e32 v154, v72, v154
	v_mul_f32_e32 v155, v73, v155
	v_mul_f32_e32 v160, v70, v158
	v_mul_f32_e32 v161, v71, v159
	v_mul_f32_e32 v156, v136, v154
	v_mul_f32_e32 v157, v137, v155
	v_mul_f32_e32 v154, v134, v160
	v_mul_f32_e32 v155, v135, v161
	s_and_saveexec_b64 s[20:21], s[50:51]
	s_cbranch_execz .LBB0_1437
	v_mul_f32_e32 v160, v155, v243
	v_mul_f32_e32 v161, v155, v242
	s_nop 0
	v_fma_f32 v210, v154, v242, -v160
	v_fma_f32 v211, v154, v243, -v161
	v_fma_f32 v155, v154, v243, v161
	v_fma_f32 v154, v154, v242, v160
	v_mul_f32_e32 v154, v157, v245
	v_fma_f32 v212, v156, v244, -v154
	v_fma_f32 v213, v157, v245, -v154
	v_mul_f32_e32 v154, v157, v244
	v_fma_f32 v156, v156, v245, v154
	v_fma_f32 v157, v157, v244, v154
	v_mov_b32_e32 v211, v155
	v_mov_b32_e32 v213, v156
	v_mov_b64_e32 v[154:155], v[210:211]
	v_mov_b64_e32 v[156:157], v[212:213]
.LBB0_1437:
	s_or_b64 exec, exec, s[20:21]
	v_mov_b32_e32 v160, v158
	v_mov_b32_e32 v161, v158
	v_mul_f32_e32 v160, v68, v160
	v_mul_f32_e32 v161, v69, v161
	v_mul_f32_e32 v158, v66, v158
	v_mul_f32_e32 v159, v67, v159
	v_mul_f32_e32 v160, v132, v160
	v_mul_f32_e32 v161, v133, v161
	v_mul_f32_e32 v158, v130, v158
	v_mul_f32_e32 v159, v131, v159
	s_and_saveexec_b64 s[20:21], s[50:51]
	s_cbranch_execz .LBB0_1439
	v_mul_f32_e32 v0, v161, v249
	v_mul_f32_e32 v194, v159, v247
	v_mul_f32_e32 v195, v159, v246
	v_fma_f32 v196, v160, v248, -v0
	v_fma_f32 v197, v161, v249, -v0
	v_mul_f32_e32 v0, v161, v248
	v_mul_f32_e32 v184, v158, v246
	v_mul_f32_e32 v185, v159, v247
	v_fma_f32 v159, v158, v247, v195
	v_fma_f32 v158, v158, v246, v194
	v_fma_f32 v160, v160, v249, v0
	v_fma_f32 v161, v161, v248, v0
	v_sub_f32_e32 v158, v184, v194
	v_mov_b32_e32 v161, v160
	v_mov_b32_e32 v160, v196

.LBB0_1442:
	v_ashrrev_i32_e32 v183, 31, v182
	v_readlane_b32 s0, v254, 21
	v_lshlrev_b64 v[184:185], 10, v[182:183]
	v_readlane_b32 s1, v254, 22
	v_lshlrev_b32_e32 v0, 1, v166
	s_nop 0
	v_lshl_add_u64 v[184:185], s[0:1], 0, v[184:185]
	s_mov_b32 s0, 0x3e38aa3b
	v_mul_f32_e32 v194, s0, v148
	v_mul_f32_e32 v195, s0, v149
	v_mul_f32_e32 v196, s0, v146
	v_mul_f32_e32 v197, s0, v147
	v_lshl_add_u64 v[184:185], s[54:55], 1, v[184:185]
	v_cvt_pk_bf16_f32 v206, v196, v197
	v_cvt_pk_bf16_f32 v207, v194, v195
	v_mul_f32_e32 v194, s0, v152
	v_mul_f32_e32 v195, s0, v153
	v_mul_f32_e32 v196, s0, v150
	v_mul_f32_e32 v197, s0, v151
	v_lshl_add_u64 v[184:185], v[184:185], 0, v[0:1]
	v_cvt_pk_bf16_f32 v208, v196, v197
	v_cvt_pk_bf16_f32 v209, v194, v195
	v_mul_f32_e32 v194, s0, v156
	v_mul_f32_e32 v195, s0, v157
	v_mul_f32_e32 v196, s0, v154
	v_mul_f32_e32 v197, s0, v155
	global_store_dwordx4 v[184:185], v[206:209], off
	s_nop 1
	v_cvt_pk_bf16_f32 v206, v196, v197
	v_cvt_pk_bf16_f32 v207, v194, v195
	v_mul_f32_e32 v194, s0, v160
	v_mul_f32_e32 v195, s0, v161
	v_mul_f32_e32 v196, s0, v158
	v_mul_f32_e32 v197, s0, v159
	v_cvt_pk_bf16_f32 v209, v194, v195
	v_cvt_pk_bf16_f32 v208, v196, v197
	global_store_dwordx4 v[184:185], v[206:209], off offset:64
	s_cbranch_execnz .LBB0_1455

.Lrope_skip_4:
	s_or_b64 exec, exec, vcc
	v_mul_f32_e32 v0, v63, v63
	v_fmac_f32_e32 v0, v62, v62
	v_fmac_f32_e32 v0, v64, v64
	v_fmac_f32_e32 v0, v65, v65
	v_fmac_f32_e32 v0, v58, v58
	v_fmac_f32_e32 v0, v59, v59
	v_fmac_f32_e32 v0, v60, v60
	v_fmac_f32_e32 v0, v61, v61
	v_mul_f32_e32 v148, v46, v46
	v_mul_f32_e32 v149, v47, v47
	v_mul_f32_e32 v146, v48, v48
	v_mul_f32_e32 v147, v49, v49
	v_add_f32_e32 v0, v148, v0
	v_add_f32_e32 v0, v149, v0
	v_add_f32_e32 v0, v146, v0
	v_add_f32_e32 v0, v147, v0
	v_mul_f32_e32 v148, v42, v42
	v_mul_f32_e32 v149, v43, v43
	v_mul_f32_e32 v146, v44, v44
	v_mul_f32_e32 v147, v45, v45
	v_add_f32_e32 v0, v148, v0
	v_add_f32_e32 v0, v149, v0
	v_cmp_lt_i32_e32 vcc, v205, v203
	v_add_f32_e32 v0, v146, v0
	v_add_f32_e32 v0, v147, v0
	v_cndmask_b32_e32 v146, v224, v205, vcc
	v_lshlrev_b32_e32 v146, 2, v146
	ds_bpermute_b32 v146, v146, v0
	v_cmp_lt_i32_e32 vcc, v204, v203
	s_waitcnt lgkmcnt(0)
	v_add_f32_e32 v0, v0, v146
	v_cndmask_b32_e32 v146, v224, v204, vcc
	v_lshlrev_b32_e32 v146, 2, v146
	ds_bpermute_b32 v146, v146, v0
	s_waitcnt lgkmcnt(0)
	v_add_f32_e32 v0, v0, v146
	v_fmamk_f32 v0, v0, 0x3c800000, v226
	v_mul_f32_e32 v146, 0x4b800000, v0
	v_cmp_gt_f32_e32 vcc, s58, v0
	s_nop 1
	v_cndmask_b32_e32 v0, v0, v146, vcc
	v_rsq_f32_e32 v0, v0
	s_nop 0
	v_mul_f32_e32 v146, 0x45800000, v0
	v_cndmask_b32_e32 v158, v0, v146, vcc
	v_lshl_or_b32 v0, v182, 6, v166
	v_mul_f32_e32 v146, v62, v158
	v_mul_f32_e32 v147, v63, v158
	v_mul_f32_e32 v148, v64, v158
	v_mul_f32_e32 v149, v65, v158
	s_waitcnt vmcnt(0)
	v_mul_f32_e32 v146, v142, v146
	v_mul_f32_e32 v147, v143, v147
	v_mul_f32_e32 v148, v144, v148
	v_mul_f32_e32 v149, v145, v149
	v_lshlrev_b32_e32 v0, 2, v0
	s_and_saveexec_b64 s[20:21], s[50:51]
	s_cbranch_execz .LBB0_1458
	v_mul_f32_e32 v156, v147, v215
	v_mul_f32_e32 v157, v147, v214
	s_nop 0
	v_fma_f32 v154, v146, v214, -v156
	v_fma_f32 v155, v146, v215, -v157
	v_fma_f32 v147, v146, v215, v157
	v_fma_f32 v146, v146, v214, v156
	v_mul_f32_e32 v146, v149, v217
	v_fma_f32 v156, v148, v216, -v146
	v_fma_f32 v157, v149, v217, -v146
	v_mul_f32_e32 v146, v149, v216
	v_fma_f32 v148, v148, v217, v146
	v_fma_f32 v149, v149, v216, v146
	v_mov_b32_e32 v155, v147
	v_mov_b32_e32 v157, v148
	v_mov_b64_e32 v[146:147], v[154:155]
	v_mov_b64_e32 v[148:149], v[156:157]
.LBB0_1458:
	s_or_b64 exec, exec, s[20:21]
	v_mov_b32_e32 v159, v158
	v_mov_b32_e32 v154, v158
	v_mov_b32_e32 v155, v158
	v_mul_f32_e32 v150, v60, v154
	v_mul_f32_e32 v151, v61, v155
	v_mul_f32_e32 v156, v58, v158
	v_mul_f32_e32 v157, v59, v159
	v_mul_f32_e32 v152, v140, v150
	v_mul_f32_e32 v153, v141, v151
	v_mul_f32_e32 v150, v138, v156
	v_mul_f32_e32 v151, v139, v157
	s_and_saveexec_b64 s[20:21], s[50:51]
	s_cbranch_execz .LBB0_1460
	v_mul_f32_e32 v156, v151, v219
	v_mul_f32_e32 v157, v151, v218
	s_nop 0
	v_fma_f32 v210, v150, v218, -v156
	v_fma_f32 v211, v150, v219, -v157
	v_fma_f32 v151, v150, v219, v157
	v_fma_f32 v150, v150, v218, v156
	v_mul_f32_e32 v150, v153, v221
	v_fma_f32 v212, v152, v220, -v150
	v_fma_f32 v213, v153, v221, -v150
	v_mul_f32_e32 v150, v153, v220
	v_fma_f32 v152, v152, v221, v150
	v_fma_f32 v153, v153, v220, v150
	v_mov_b32_e32 v211, v151
	v_mov_b32_e32 v213, v152
	v_mov_b64_e32 v[150:151], v[210:211]
	v_mov_b64_e32 v[152:153], v[212:213]
.LBB0_1460:
	s_or_b64 exec, exec, s[20:21]
	v_mul_f32_e32 v154, v48, v154
	v_mul_f32_e32 v155, v49, v155
	v_mul_f32_e32 v160, v46, v158
	v_mul_f32_e32 v161, v47, v159
	v_mul_f32_e32 v156, v136, v154
	v_mul_f32_e32 v157, v137, v155
	v_mul_f32_e32 v154, v134, v160
	v_mul_f32_e32 v155, v135, v161
	s_and_saveexec_b64 s[20:21], s[50:51]
	s_cbranch_execz .LBB0_1462
	v_mul_f32_e32 v160, v155, v243
	v_mul_f32_e32 v161, v155, v242
	s_nop 0
	v_fma_f32 v210, v154, v242, -v160
	v_fma_f32 v211, v154, v243, -v161
	v_fma_f32 v155, v154, v243, v161
	v_fma_f32 v154, v154, v242, v160
	v_mul_f32_e32 v154, v157, v245
	v_fma_f32 v212, v156, v244, -v154
	v_fma_f32 v213, v157, v245, -v154
	v_mul_f32_e32 v154, v157, v244
	v_fma_f32 v156, v156, v245, v154
	v_fma_f32 v157, v157, v244, v154
	v_mov_b32_e32 v211, v155
	v_mov_b32_e32 v213, v156
	v_mov_b64_e32 v[154:155], v[210:211]
	v_mov_b64_e32 v[156:157], v[212:213]
.LBB0_1462:
	s_or_b64 exec, exec, s[20:21]
	v_mov_b32_e32 v160, v158
	v_mov_b32_e32 v161, v158
	v_mul_f32_e32 v160, v44, v160
	v_mul_f32_e32 v161, v45, v161
	v_mul_f32_e32 v158, v42, v158
	v_mul_f32_e32 v159, v43, v159
	v_mul_f32_e32 v160, v132, v160
	v_mul_f32_e32 v161, v133, v161
	v_mul_f32_e32 v158, v130, v158
	v_mul_f32_e32 v159, v131, v159
	s_and_saveexec_b64 s[20:21], s[50:51]
	s_cbranch_execz .LBB0_1464
	v_mul_f32_e32 v0, v161, v249
	v_mul_f32_e32 v194, v159, v247
	v_mul_f32_e32 v195, v159, v246
	v_fma_f32 v196, v160, v248, -v0
	v_fma_f32 v197, v161, v249, -v0
	v_mul_f32_e32 v0, v161, v248
	v_mul_f32_e32 v184, v158, v246
	v_mul_f32_e32 v185, v159, v247
	v_fma_f32 v159, v158, v247, v195
	v_fma_f32 v158, v158, v246, v194
	v_fma_f32 v160, v160, v249, v0
	v_fma_f32 v161, v161, v248, v0
	v_sub_f32_e32 v158, v184, v194
	v_mov_b32_e32 v161, v160
	v_mov_b32_e32 v160, v196

.LBB0_1467:
	v_ashrrev_i32_e32 v181, 31, v180
	v_readlane_b32 s0, v254, 21
	v_lshlrev_b64 v[184:185], 10, v[180:181]
	v_readlane_b32 s1, v254, 22
	v_lshlrev_b32_e32 v0, 1, v166
	s_nop 0
	v_lshl_add_u64 v[184:185], s[0:1], 0, v[184:185]
	s_mov_b32 s0, 0x3e38aa3b
	v_mul_f32_e32 v194, s0, v148
	v_mul_f32_e32 v195, s0, v149
	v_mul_f32_e32 v196, s0, v146
	v_mul_f32_e32 v197, s0, v147
	v_lshl_add_u64 v[184:185], s[54:55], 1, v[184:185]
	v_cvt_pk_bf16_f32 v206, v196, v197
	v_cvt_pk_bf16_f32 v207, v194, v195
	v_mul_f32_e32 v194, s0, v152
	v_mul_f32_e32 v195, s0, v153
	v_mul_f32_e32 v196, s0, v150
	v_mul_f32_e32 v197, s0, v151
	v_lshl_add_u64 v[184:185], v[184:185], 0, v[0:1]
	v_cvt_pk_bf16_f32 v208, v196, v197
	v_cvt_pk_bf16_f32 v209, v194, v195
	v_mul_f32_e32 v194, s0, v156
	v_mul_f32_e32 v195, s0, v157
	v_mul_f32_e32 v196, s0, v154
	v_mul_f32_e32 v197, s0, v155
	global_store_dwordx4 v[184:185], v[206:209], off
	s_nop 1
	v_cvt_pk_bf16_f32 v206, v196, v197
	v_cvt_pk_bf16_f32 v207, v194, v195
	v_mul_f32_e32 v194, s0, v160
	v_mul_f32_e32 v195, s0, v161
	v_mul_f32_e32 v196, s0, v158
	v_mul_f32_e32 v197, s0, v159
	v_cvt_pk_bf16_f32 v209, v194, v195
	v_cvt_pk_bf16_f32 v208, v196, v197
	global_store_dwordx4 v[184:185], v[206:209], off offset:64
	s_add_i32 s0, s4, 0xfffff000
	s_ashr_i32 s8, s0, 11
	s_cbranch_execnz .LBB0_1480

.Lrope_skip_5:
	s_or_b64 exec, exec, vcc
	v_mul_f32_e32 v0, v55, v55
	v_fmac_f32_e32 v0, v54, v54
	v_fmac_f32_e32 v0, v56, v56
	v_fmac_f32_e32 v0, v57, v57
	v_fmac_f32_e32 v0, v50, v50
	v_fmac_f32_e32 v0, v51, v51
	v_fmac_f32_e32 v0, v52, v52
	v_fmac_f32_e32 v0, v53, v53
	v_mul_f32_e32 v148, v30, v30
	v_mul_f32_e32 v149, v31, v31
	v_mul_f32_e32 v146, v32, v32
	v_mul_f32_e32 v147, v33, v33
	v_add_f32_e32 v0, v148, v0
	v_add_f32_e32 v0, v149, v0
	v_add_f32_e32 v0, v146, v0
	v_add_f32_e32 v0, v147, v0
	v_mul_f32_e32 v148, v26, v26
	v_mul_f32_e32 v149, v27, v27
	v_mul_f32_e32 v146, v28, v28
	v_mul_f32_e32 v147, v29, v29
	v_add_f32_e32 v0, v148, v0
	v_add_f32_e32 v0, v149, v0
	v_cmp_lt_i32_e32 vcc, v205, v203
	v_add_f32_e32 v0, v146, v0
	v_add_f32_e32 v0, v147, v0
	v_cndmask_b32_e32 v146, v224, v205, vcc
	v_lshlrev_b32_e32 v146, 2, v146
	ds_bpermute_b32 v146, v146, v0
	v_cmp_lt_i32_e32 vcc, v204, v203
	s_waitcnt lgkmcnt(0)
	v_add_f32_e32 v0, v0, v146
	v_cndmask_b32_e32 v146, v224, v204, vcc
	v_lshlrev_b32_e32 v146, 2, v146
	ds_bpermute_b32 v146, v146, v0
	s_waitcnt lgkmcnt(0)
	v_add_f32_e32 v0, v0, v146
	v_fmamk_f32 v0, v0, 0x3c800000, v226
	v_mul_f32_e32 v146, 0x4b800000, v0
	v_cmp_gt_f32_e32 vcc, s58, v0
	s_nop 1
	v_cndmask_b32_e32 v0, v0, v146, vcc
	v_rsq_f32_e32 v0, v0
	s_nop 0
	v_mul_f32_e32 v146, 0x45800000, v0
	v_cndmask_b32_e32 v158, v0, v146, vcc
	v_lshl_or_b32 v0, v182, 6, v166
	v_mul_f32_e32 v146, v54, v158
	v_mul_f32_e32 v147, v55, v158
	v_mul_f32_e32 v148, v56, v158
	v_mul_f32_e32 v149, v57, v158
	s_waitcnt vmcnt(0)
	v_mul_f32_e32 v146, v142, v146
	v_mul_f32_e32 v147, v143, v147
	v_mul_f32_e32 v148, v144, v148
	v_mul_f32_e32 v149, v145, v149
	v_lshlrev_b32_e32 v0, 2, v0
	s_and_saveexec_b64 s[20:21], s[50:51]
	s_cbranch_execz .LBB0_1483
	v_mul_f32_e32 v156, v147, v215
	v_mul_f32_e32 v157, v147, v214
	s_nop 0
	v_fma_f32 v154, v146, v214, -v156
	v_fma_f32 v155, v146, v215, -v157
	v_fma_f32 v147, v146, v215, v157
	v_fma_f32 v146, v146, v214, v156
	v_mul_f32_e32 v146, v149, v217
	v_fma_f32 v156, v148, v216, -v146
	v_fma_f32 v157, v149, v217, -v146
	v_mul_f32_e32 v146, v149, v216
	v_fma_f32 v148, v148, v217, v146
	v_fma_f32 v149, v149, v216, v146
	v_mov_b32_e32 v155, v147
	v_mov_b32_e32 v157, v148
	v_mov_b64_e32 v[146:147], v[154:155]
	v_mov_b64_e32 v[148:149], v[156:157]
.LBB0_1483:
	s_or_b64 exec, exec, s[20:21]
	v_mov_b32_e32 v159, v158
	v_mov_b32_e32 v154, v158
	v_mov_b32_e32 v155, v158
	v_mul_f32_e32 v150, v52, v154
	v_mul_f32_e32 v151, v53, v155
	v_mul_f32_e32 v156, v50, v158
	v_mul_f32_e32 v157, v51, v159
	v_mul_f32_e32 v152, v140, v150
	v_mul_f32_e32 v153, v141, v151
	v_mul_f32_e32 v150, v138, v156
	v_mul_f32_e32 v151, v139, v157
	s_and_saveexec_b64 s[20:21], s[50:51]
	s_cbranch_execz .LBB0_1485
	v_mul_f32_e32 v156, v151, v219
	v_mul_f32_e32 v157, v151, v218
	s_nop 0
	v_fma_f32 v210, v150, v218, -v156
	v_fma_f32 v211, v150, v219, -v157
	v_fma_f32 v151, v150, v219, v157
	v_fma_f32 v150, v150, v218, v156
	v_mul_f32_e32 v150, v153, v221
	v_fma_f32 v212, v152, v220, -v150
	v_fma_f32 v213, v153, v221, -v150
	v_mul_f32_e32 v150, v153, v220
	v_fma_f32 v152, v152, v221, v150
	v_fma_f32 v153, v153, v220, v150
	v_mov_b32_e32 v211, v151
	v_mov_b32_e32 v213, v152
	v_mov_b64_e32 v[150:151], v[210:211]
	v_mov_b64_e32 v[152:153], v[212:213]
.LBB0_1485:
	s_or_b64 exec, exec, s[20:21]
	v_mul_f32_e32 v154, v32, v154
	v_mul_f32_e32 v155, v33, v155
	v_mul_f32_e32 v160, v30, v158
	v_mul_f32_e32 v161, v31, v159
	v_mul_f32_e32 v156, v136, v154
	v_mul_f32_e32 v157, v137, v155
	v_mul_f32_e32 v154, v134, v160
	v_mul_f32_e32 v155, v135, v161
	s_and_saveexec_b64 s[20:21], s[50:51]
	s_cbranch_execz .LBB0_1487
	v_mul_f32_e32 v160, v155, v243
	v_mul_f32_e32 v161, v155, v242
	s_nop 0
	v_fma_f32 v210, v154, v242, -v160
	v_fma_f32 v211, v154, v243, -v161
	v_fma_f32 v155, v154, v243, v161
	v_fma_f32 v154, v154, v242, v160
	v_mul_f32_e32 v154, v157, v245
	v_fma_f32 v212, v156, v244, -v154
	v_fma_f32 v213, v157, v245, -v154
	v_mul_f32_e32 v154, v157, v244
	v_fma_f32 v156, v156, v245, v154
	v_fma_f32 v157, v157, v244, v154
	v_mov_b32_e32 v211, v155
	v_mov_b32_e32 v213, v156
	v_mov_b64_e32 v[154:155], v[210:211]
	v_mov_b64_e32 v[156:157], v[212:213]
.LBB0_1487:
	s_or_b64 exec, exec, s[20:21]
	v_mov_b32_e32 v160, v158
	v_mov_b32_e32 v161, v158
	v_mul_f32_e32 v160, v28, v160
	v_mul_f32_e32 v161, v29, v161
	v_mul_f32_e32 v158, v26, v158
	v_mul_f32_e32 v159, v27, v159
	v_mul_f32_e32 v160, v132, v160
	v_mul_f32_e32 v161, v133, v161
	v_mul_f32_e32 v158, v130, v158
	v_mul_f32_e32 v159, v131, v159
	s_and_saveexec_b64 s[20:21], s[50:51]
	s_cbranch_execz .LBB0_1489
	v_mul_f32_e32 v196, v159, v247
	v_mul_f32_e32 v197, v159, v246
	v_mul_f32_e32 v0, v161, v249
	v_mul_f32_e32 v194, v158, v246
	v_mul_f32_e32 v195, v159, v247
	v_fma_f32 v159, v158, v247, v197
	v_fma_f32 v158, v158, v246, v196
	v_fma_f32 v206, v160, v248, -v0
	v_fma_f32 v207, v161, v249, -v0
	v_mul_f32_e32 v0, v161, v248
	v_fma_f32 v160, v160, v249, v0
	v_fma_f32 v161, v161, v248, v0
	v_sub_f32_e32 v158, v194, v196
	v_mov_b32_e32 v161, v160
	v_mov_b32_e32 v160, v206

.Lrope_skip_6:
	s_or_b64 exec, exec, vcc
	v_mul_f32_e32 v0, v39, v39
	v_fmac_f32_e32 v0, v38, v38
	v_fmac_f32_e32 v0, v40, v40
	v_fmac_f32_e32 v0, v41, v41
	v_fmac_f32_e32 v0, v34, v34
	v_fmac_f32_e32 v0, v35, v35
	v_fmac_f32_e32 v0, v36, v36
	v_fmac_f32_e32 v0, v37, v37
	v_mul_f32_e32 v148, v18, v18
	v_mul_f32_e32 v149, v19, v19
	v_mul_f32_e32 v146, v20, v20
	v_mul_f32_e32 v147, v21, v21
	v_add_f32_e32 v0, v148, v0
	v_add_f32_e32 v0, v149, v0
	v_add_f32_e32 v0, v146, v0
	v_add_f32_e32 v0, v147, v0
	v_mul_f32_e32 v148, v10, v10
	v_mul_f32_e32 v149, v11, v11
	v_mul_f32_e32 v146, v12, v12
	v_mul_f32_e32 v147, v13, v13
	v_add_f32_e32 v0, v148, v0
	v_add_f32_e32 v0, v149, v0
	v_cmp_lt_i32_e32 vcc, v205, v203
	v_add_f32_e32 v0, v146, v0
	v_add_f32_e32 v0, v147, v0
	v_cndmask_b32_e32 v146, v224, v205, vcc
	v_lshlrev_b32_e32 v146, 2, v146
	ds_bpermute_b32 v146, v146, v0
	v_cmp_lt_i32_e32 vcc, v204, v203
	s_waitcnt lgkmcnt(0)
	v_add_f32_e32 v0, v0, v146
	v_cndmask_b32_e32 v146, v224, v204, vcc
	v_lshlrev_b32_e32 v146, 2, v146
	ds_bpermute_b32 v146, v146, v0
	s_waitcnt lgkmcnt(0)
	v_add_f32_e32 v0, v0, v146
	v_fmamk_f32 v0, v0, 0x3c800000, v226
	v_mul_f32_e32 v146, 0x4b800000, v0
	v_cmp_gt_f32_e32 vcc, s58, v0
	s_nop 1
	v_cndmask_b32_e32 v0, v0, v146, vcc
	v_rsq_f32_e32 v0, v0
	s_nop 0
	v_mul_f32_e32 v146, 0x45800000, v0
	v_cndmask_b32_e32 v158, v0, v146, vcc
	v_lshl_or_b32 v0, v182, 6, v166
	v_mul_f32_e32 v146, v38, v158
	v_mul_f32_e32 v147, v39, v158
	v_mul_f32_e32 v148, v40, v158
	v_mul_f32_e32 v149, v41, v158
	s_waitcnt vmcnt(0)
	v_mul_f32_e32 v146, v142, v146
	v_mul_f32_e32 v147, v143, v147
	v_mul_f32_e32 v148, v144, v148
	v_mul_f32_e32 v149, v145, v149
	v_lshlrev_b32_e32 v0, 2, v0
	s_and_saveexec_b64 s[20:21], s[50:51]
	s_cbranch_execz .LBB0_1508
	v_mul_f32_e32 v156, v147, v215
	v_mul_f32_e32 v157, v147, v214
	s_nop 0
	v_fma_f32 v154, v146, v214, -v156
	v_fma_f32 v155, v146, v215, -v157
	v_fma_f32 v147, v146, v215, v157
	v_fma_f32 v146, v146, v214, v156
	v_mul_f32_e32 v146, v149, v217
	v_fma_f32 v156, v148, v216, -v146
	v_fma_f32 v157, v149, v217, -v146
	v_mul_f32_e32 v146, v149, v216
	v_fma_f32 v148, v148, v217, v146
	v_fma_f32 v149, v149, v216, v146
	v_mov_b32_e32 v155, v147
	v_mov_b32_e32 v157, v148
	v_mov_b64_e32 v[146:147], v[154:155]
	v_mov_b64_e32 v[148:149], v[156:157]
.LBB0_1508:
	s_or_b64 exec, exec, s[20:21]
	v_mov_b32_e32 v159, v158
	v_mov_b32_e32 v154, v158
	v_mov_b32_e32 v155, v158
	v_mul_f32_e32 v150, v36, v154
	v_mul_f32_e32 v151, v37, v155
	v_mul_f32_e32 v156, v34, v158
	v_mul_f32_e32 v157, v35, v159
	v_mul_f32_e32 v152, v140, v150
	v_mul_f32_e32 v153, v141, v151
	v_mul_f32_e32 v150, v138, v156
	v_mul_f32_e32 v151, v139, v157
	s_and_saveexec_b64 s[20:21], s[50:51]
	s_cbranch_execz .LBB0_1510
	v_mul_f32_e32 v156, v151, v219
	v_mul_f32_e32 v157, v151, v218
	s_nop 0
	v_fma_f32 v210, v150, v218, -v156
	v_fma_f32 v211, v150, v219, -v157
	v_fma_f32 v151, v150, v219, v157
	v_fma_f32 v150, v150, v218, v156
	v_mul_f32_e32 v150, v153, v221
	v_fma_f32 v212, v152, v220, -v150
	v_fma_f32 v213, v153, v221, -v150
	v_mul_f32_e32 v150, v153, v220
	v_fma_f32 v152, v152, v221, v150
	v_fma_f32 v153, v153, v220, v150
	v_mov_b32_e32 v211, v151
	v_mov_b32_e32 v213, v152
	v_mov_b64_e32 v[150:151], v[210:211]
	v_mov_b64_e32 v[152:153], v[212:213]
.LBB0_1510:
	s_or_b64 exec, exec, s[20:21]
	v_mul_f32_e32 v154, v20, v154
	v_mul_f32_e32 v155, v21, v155
	v_mul_f32_e32 v160, v18, v158
	v_mul_f32_e32 v161, v19, v159
	v_mul_f32_e32 v156, v136, v154
	v_mul_f32_e32 v157, v137, v155
	v_mul_f32_e32 v154, v134, v160
	v_mul_f32_e32 v155, v135, v161
	s_and_saveexec_b64 s[20:21], s[50:51]
	s_cbranch_execz .LBB0_1512
	v_mul_f32_e32 v160, v155, v243
	v_mul_f32_e32 v161, v155, v242
	s_nop 0
	v_fma_f32 v210, v154, v242, -v160
	v_fma_f32 v211, v154, v243, -v161
	v_fma_f32 v155, v154, v243, v161
	v_fma_f32 v154, v154, v242, v160
	v_mul_f32_e32 v154, v157, v245
	v_fma_f32 v212, v156, v244, -v154
	v_fma_f32 v213, v157, v245, -v154
	v_mul_f32_e32 v154, v157, v244
	v_fma_f32 v156, v156, v245, v154
	v_fma_f32 v157, v157, v244, v154
	v_mov_b32_e32 v211, v155
	v_mov_b32_e32 v213, v156
	v_mov_b64_e32 v[154:155], v[210:211]
	v_mov_b64_e32 v[156:157], v[212:213]
.LBB0_1512:
	s_or_b64 exec, exec, s[20:21]
	v_mov_b32_e32 v160, v158
	v_mov_b32_e32 v161, v158
	v_mul_f32_e32 v160, v12, v160
	v_mul_f32_e32 v161, v13, v161
	v_mul_f32_e32 v158, v10, v158
	v_mul_f32_e32 v159, v11, v159
	v_mul_f32_e32 v160, v132, v160
	v_mul_f32_e32 v161, v133, v161
	v_mul_f32_e32 v158, v130, v158
	v_mul_f32_e32 v159, v131, v159
	s_and_saveexec_b64 s[20:21], s[50:51]
	s_cbranch_execz .LBB0_1514
	v_mul_f32_e32 v196, v159, v247
	v_mul_f32_e32 v197, v159, v246
	v_mul_f32_e32 v0, v161, v249
	v_mul_f32_e32 v194, v158, v246
	v_mul_f32_e32 v195, v159, v247
	v_fma_f32 v159, v158, v247, v197
	v_fma_f32 v158, v158, v246, v196
	v_fma_f32 v206, v160, v248, -v0
	v_fma_f32 v207, v161, v249, -v0
	v_mul_f32_e32 v0, v161, v248
	v_fma_f32 v160, v160, v249, v0
	v_fma_f32 v161, v161, v248, v0
	v_sub_f32_e32 v158, v194, v196
	v_mov_b32_e32 v161, v160
	v_mov_b32_e32 v160, v206

.Lrope_skip_7:
	s_or_b64 exec, exec, vcc
	v_mul_f32_e32 v0, v23, v23
	v_fmac_f32_e32 v0, v22, v22
	v_fmac_f32_e32 v0, v24, v24
	v_fmac_f32_e32 v0, v25, v25
	v_fmac_f32_e32 v0, v14, v14
	v_fmac_f32_e32 v0, v15, v15
	v_fmac_f32_e32 v0, v16, v16
	v_fmac_f32_e32 v0, v17, v17
	v_mul_f32_e32 v148, v6, v6
	v_mul_f32_e32 v149, v7, v7
	v_mul_f32_e32 v146, v8, v8
	v_mul_f32_e32 v147, v9, v9
	v_add_f32_e32 v0, v148, v0
	v_add_f32_e32 v0, v149, v0
	v_add_f32_e32 v0, v146, v0
	v_add_f32_e32 v0, v147, v0
	v_mul_f32_e32 v148, v2, v2
	v_mul_f32_e32 v149, v3, v3
	v_mul_f32_e32 v146, v4, v4
	v_mul_f32_e32 v147, v5, v5
	v_add_f32_e32 v0, v148, v0
	v_add_f32_e32 v0, v149, v0
	v_cmp_lt_i32_e32 vcc, v205, v203
	v_add_f32_e32 v0, v146, v0
	v_add_f32_e32 v0, v147, v0
	v_cndmask_b32_e32 v146, v224, v205, vcc
	v_lshlrev_b32_e32 v146, 2, v146
	ds_bpermute_b32 v146, v146, v0
	v_cmp_lt_i32_e32 vcc, v204, v203
	s_waitcnt lgkmcnt(0)
	v_add_f32_e32 v0, v0, v146
	v_cndmask_b32_e32 v146, v224, v204, vcc
	v_lshlrev_b32_e32 v146, 2, v146
	ds_bpermute_b32 v146, v146, v0
	s_waitcnt lgkmcnt(0)
	v_add_f32_e32 v0, v0, v146
	v_fmamk_f32 v0, v0, 0x3c800000, v226
	v_mul_f32_e32 v146, 0x4b800000, v0
	v_cmp_gt_f32_e32 vcc, s58, v0
	s_nop 1
	v_cndmask_b32_e32 v0, v0, v146, vcc
	v_rsq_f32_e32 v0, v0
	s_nop 0
	v_mul_f32_e32 v146, 0x45800000, v0
	v_cndmask_b32_e32 v158, v0, v146, vcc
	v_lshl_or_b32 v0, v180, 6, v166
	v_mul_f32_e32 v146, v22, v158
	v_mul_f32_e32 v147, v23, v158
	v_mul_f32_e32 v148, v24, v158
	v_mul_f32_e32 v149, v25, v158
	s_waitcnt vmcnt(0)
	v_mul_f32_e32 v146, v142, v146
	v_mul_f32_e32 v147, v143, v147
	v_mul_f32_e32 v148, v144, v148
	v_mul_f32_e32 v149, v145, v149
	v_lshlrev_b32_e32 v0, 2, v0
	s_and_saveexec_b64 s[20:21], s[50:51]
	s_cbranch_execz .LBB0_1533
	v_mul_f32_e32 v152, v147, v215
	v_mul_f32_e32 v153, v147, v214
	s_nop 0
	v_fma_f32 v150, v146, v214, -v152
	v_fma_f32 v151, v146, v215, -v153
	v_fma_f32 v142, v146, v214, v152
	v_fma_f32 v143, v146, v215, v153
	v_mul_f32_e32 v142, v149, v217
	v_fma_f32 v152, v148, v216, -v142
	v_fma_f32 v153, v149, v217, -v142
	v_mul_f32_e32 v142, v149, v216
	v_fma_f32 v144, v148, v217, v142
	v_fma_f32 v145, v149, v216, v142
	v_mov_b32_e32 v151, v143
	v_mov_b32_e32 v153, v144
	v_mov_b64_e32 v[146:147], v[150:151]
	v_mov_b64_e32 v[148:149], v[152:153]
.LBB0_1533:
	s_or_b64 exec, exec, s[20:21]
	v_mov_b32_e32 v159, v158
	v_mov_b32_e32 v142, v158
	v_mov_b32_e32 v143, v158
	v_mul_f32_e32 v144, v16, v142
	v_mul_f32_e32 v145, v17, v143
	v_mul_f32_e32 v150, v14, v158
	v_mul_f32_e32 v151, v15, v159
	v_mul_f32_e32 v152, v140, v144
	v_mul_f32_e32 v153, v141, v145
	v_mul_f32_e32 v150, v138, v150
	v_mul_f32_e32 v151, v139, v151
	s_and_saveexec_b64 s[20:21], s[50:51]
	s_cbranch_execz .LBB0_1535
	v_mul_f32_e32 v144, v151, v219
	v_mul_f32_e32 v145, v151, v218
	s_nop 0
	v_fma_f32 v154, v150, v218, -v144
	v_fma_f32 v155, v150, v219, -v145
	v_fma_f32 v138, v150, v218, v144
	v_fma_f32 v139, v150, v219, v145
	v_mul_f32_e32 v138, v153, v221
	v_fma_f32 v156, v152, v220, -v138
	v_fma_f32 v157, v153, v221, -v138
	v_mul_f32_e32 v138, v153, v220
	v_fma_f32 v140, v152, v221, v138
	v_fma_f32 v141, v153, v220, v138
	v_mov_b32_e32 v155, v139
	v_mov_b32_e32 v157, v140
	v_mov_b64_e32 v[150:151], v[154:155]
	v_mov_b64_e32 v[152:153], v[156:157]
.LBB0_1535:
	s_or_b64 exec, exec, s[20:21]
	v_mul_f32_e32 v138, v8, v142
	v_mul_f32_e32 v139, v9, v143
	v_mul_f32_e32 v140, v6, v158
	v_mul_f32_e32 v141, v7, v159
	v_mul_f32_e32 v156, v136, v138
	v_mul_f32_e32 v157, v137, v139
	v_mul_f32_e32 v154, v134, v140
	v_mul_f32_e32 v155, v135, v141
	s_and_saveexec_b64 s[20:21], s[50:51]
	s_cbranch_execz .LBB0_1537
	v_mul_f32_e32 v140, v155, v243
	v_mul_f32_e32 v141, v155, v242
	s_nop 0
	v_fma_f32 v138, v154, v242, -v140
	v_fma_f32 v139, v154, v243, -v141
	v_fma_f32 v134, v154, v242, v140
	v_fma_f32 v135, v154, v243, v141
	v_mul_f32_e32 v134, v157, v245
	v_fma_f32 v140, v156, v244, -v134
	v_fma_f32 v141, v157, v245, -v134
	v_mul_f32_e32 v134, v157, v244
	v_fma_f32 v136, v156, v245, v134
	v_fma_f32 v137, v157, v244, v134
	v_mov_b32_e32 v139, v135
	v_mov_b32_e32 v141, v136
	v_mov_b64_e32 v[156:157], v[140:141]
	v_mov_b64_e32 v[154:155], v[138:139]
.LBB0_1537:
	s_or_b64 exec, exec, s[20:21]
	v_mov_b32_e32 v134, v158
	v_mov_b32_e32 v135, v158
	v_mul_f32_e32 v134, v4, v134
	v_mul_f32_e32 v135, v5, v135
	v_mul_f32_e32 v136, v2, v158
	v_mul_f32_e32 v137, v3, v159
	v_mul_f32_e32 v160, v132, v134
	v_mul_f32_e32 v161, v133, v135
	v_mul_f32_e32 v158, v130, v136
	v_mul_f32_e32 v159, v131, v137
	s_and_saveexec_b64 s[20:21], s[50:51]
	s_cbranch_execz .LBB0_1539
	v_mul_f32_e32 v136, v159, v247
	v_mul_f32_e32 v137, v159, v246
	v_mul_f32_e32 v0, v161, v249
	v_mul_f32_e32 v134, v158, v246
	v_mul_f32_e32 v135, v159, v247
	v_fma_f32 v159, v158, v247, v137
	v_fma_f32 v158, v158, v246, v136
	v_fma_f32 v130, v160, v248, -v0
	v_fma_f32 v131, v161, v249, -v0
	v_mul_f32_e32 v0, v161, v248
	v_fma_f32 v132, v160, v249, v0
	v_fma_f32 v133, v161, v248, v0
	v_sub_f32_e32 v158, v134, v136
	v_mov_b32_e32 v161, v132
	v_mov_b32_e32 v160, v130

.LBB0_1542:
	v_ashrrev_i32_e32 v183, 31, v182
	v_readlane_b32 s0, v254, 21
	s_waitcnt vmcnt(0)
	v_lshlrev_b64 v[130:131], 10, v[182:183]
	v_readlane_b32 s1, v254, 22
	v_lshlrev_b32_e32 v0, 1, v166
	s_nop 0
	v_lshl_add_u64 v[130:131], s[0:1], 0, v[130:131]
	v_lshl_add_u64 v[130:131], s[54:55], 1, v[130:131]
	s_mov_b32 s0, 0x3e38aa3b
	v_lshl_add_u64 v[134:135], v[130:131], 0, v[0:1]
	v_mul_f32_e32 v132, s0, v148
	v_mul_f32_e32 v133, s0, v149
	v_mul_f32_e32 v130, s0, v146
	v_mul_f32_e32 v131, s0, v147
	v_mul_f32_e32 v136, s0, v152
	v_mul_f32_e32 v137, s0, v153
	v_cvt_pk_bf16_f32 v130, v130, v131
	v_cvt_pk_bf16_f32 v131, v132, v133
	v_mul_f32_e32 v132, s0, v150
	v_mul_f32_e32 v133, s0, v151
	s_nop 0
	v_cvt_pk_bf16_f32 v132, v132, v133
	v_cvt_pk_bf16_f32 v133, v136, v137
	global_store_dwordx4 v[134:135], v[130:133], off
	v_mul_f32_e32 v136, s0, v160
	v_mul_f32_e32 v137, s0, v161
	s_nop 0
	v_mul_f32_e32 v132, s0, v156
	v_mul_f32_e32 v133, s0, v157
	v_mul_f32_e32 v130, s0, v154
	v_mul_f32_e32 v131, s0, v155
	s_nop 0
	v_cvt_pk_bf16_f32 v130, v130, v131
	v_cvt_pk_bf16_f32 v131, v132, v133
	v_mul_f32_e32 v132, s0, v158
	v_mul_f32_e32 v133, s0, v159
	s_nop 0
	v_cvt_pk_bf16_f32 v132, v132, v133
	v_cvt_pk_bf16_f32 v133, v136, v137
	global_store_dwordx4 v[134:135], v[130:133], off offset:64
	s_cbranch_execnz .LBB0_1555
